# GEMM tiles staged with a full-cache-line LDS-DMA layout: each wave-instruction fetches 8 rows x 128 B instead of 16 rows x 64 B; new conflict-free LDS image and fragment read addressing
# speedup vs baseline: 1.0028x; 1.0028x over previous
.LBB0_66:
	s_or_b64 exec, exec, s[4:5]
	s_mov_b64 s[4:5], s[0:1]
	v_mov_b32_e32 v8, v157
	s_cmpk_lt_i32 s2, 0xb00
	s_cselect_b64 s[24:25], -1, 0
	s_cmpk_gt_i32 s2, 0xaff
	v_readfirstlane_b32 s20, v8
	s_cbranch_scc1 .LBB0_84
	v_lshlrev_b32_e32 v0, 4, v8
	v_add_u32_e32 v1, 0x2000, v0
	v_ashrrev_i32_e32 v2, 31, v1
	v_lshrrev_b32_e32 v2, 22, v2
	v_add_u32_e32 v2, v1, v2
	v_ashrrev_i32_e32 v9, 10, v2
	v_mul_i32_i24_e32 v2, 0x400, v9
	v_sub_u32_e32 v1, v1, v2
	v_lshrrev_b32_e32 v2, 4, v1
	v_bitop3_b32 v1, v2, v1, 32 bitop3:0x6c
	v_ashrrev_i32_e32 v2, 31, v1
	v_lshrrev_b32_e32 v2, 26, v2
	v_add_u32_e32 v2, v1, v2
	v_lshlrev_b32_e32 v3, 3, v9
	v_ashrrev_i32_e32 v10, 6, v2
	v_and_b32_e32 v3, -16, v3
	v_add_u32_e32 v3, v10, v3
	v_and_b32_e32 v4, 3, v10
	s_mov_b32 s8, 0x1fffe0
	v_lshrrev_b32_e32 v5, 2, v3
	v_lshlrev_b32_e32 v6, 1, v3
	v_and_b32_e32 v2, 0xc0, v2
	v_and_or_b32 v4, v3, s8, v4
	v_and_b32_e32 v5, 4, v5
	v_and_b32_e32 v6, 24, v6
	v_sub_u32_e32 v1, v1, v2
	v_mov_b32_e32 v2, 1
	v_or3_b32 v4, v4, v5, v6
	v_lshlrev_b32_e32 v5, 5, v9
	v_ashrrev_i16_sdwa v1, v2, sext(v1) dst_sel:DWORD dst_unused:UNUSED_PAD src0_sel:DWORD src1_sel:BYTE_0
	v_and_b32_e32 v5, 32, v5
	v_bfe_i32 v11, v1, 0, 16
	v_add_lshl_u32 v1, v5, v11, 1
	v_lshl_add_u32 v128, v4, 11, v1
	v_lshrrev_b32_e32 v250, 3, v157
	v_and_b32_e32 v251, 6, v250
	v_and_b32_e32 v252, 7, v157
	v_xor_b32_e32 v251, v251, v252
	v_lshlrev_b32_e32 v251, 4, v251
	v_and_b32_e32 v252, 12, v250
	v_lshlrev_b32_e32 v252, 1, v252
	v_and_b32_e32 v253, 16, v250
	v_lshrrev_b32_e32 v253, 2, v253
	v_or_b32_e32 v252, v252, v253
	v_and_b32_e32 v253, 35, v250
	v_or_b32_e32 v250, v252, v253
	v_mul_u32_u24_e32 v250, 0x800, v250
	v_add_u32_e32 v128, v250, v251
	v_add_u32_e32 v128, 0x20000, v128
	v_lshl_add_u32 v130, v3, 11, v1
	v_lshrrev_b32_e32 v250, 3, v157
	v_and_b32_e32 v251, 6, v250
	v_and_b32_e32 v252, 7, v157
	v_xor_b32_e32 v251, v251, v252
	v_lshlrev_b32_e32 v251, 4, v251
	v_mul_u32_u24_e32 v250, 0x800, v250
	v_add_u32_e32 v130, v250, v251
	v_add_u32_e32 v130, 0x20000, v130
	v_bfe_i32 v1, v8, 27, 1
	v_lshrrev_b32_e32 v1, 22, v1
	v_add_u32_e32 v1, v0, v1
	s_load_dwordx2 s[4:5], s[4:5], 0x80
	v_and_b32_e32 v1, 0xfffffc00, v1
	v_sub_u32_e32 v0, v0, v1
	v_lshrrev_b32_e32 v1, 4, v0
	v_ashrrev_i32_e32 v3, 31, v8
	v_bitop3_b32 v0, v1, v0, 32 bitop3:0x6c
	v_lshrrev_b32_e32 v3, 26, v3
	v_ashrrev_i32_e32 v1, 31, v0
	v_add_u32_e32 v3, v8, v3
	s_waitcnt lgkmcnt(0)
	s_add_u32 s3, s4, 0x6000000
	v_lshrrev_b32_e32 v1, 26, v1
	v_ashrrev_i32_e32 v13, 6, v3
	s_addc_u32 s35, s5, 0
	v_add_u32_e32 v1, v0, v1
	v_lshlrev_b32_e32 v3, 3, v13
	s_add_u32 s50, s4, 0x400000
	v_ashrrev_i32_e32 v12, 6, v1
	v_and_b32_e32 v3, -16, v3
	s_addc_u32 s51, s5, 0
	v_add_u32_e32 v3, v12, v3
	v_and_b32_e32 v4, 3, v12
	s_ashr_i32 s53, s2, 31
	v_and_or_b32 v4, v3, s8, v4
	s_lshr_b32 s8, s53, 29
	s_add_i32 s8, s2, s8
	s_ashr_i32 s17, s20, 6
	s_ashr_i32 s9, s8, 3
	s_and_b32 s8, s8, -8
	s_ashr_i32 s21, s20, 8
	s_lshl_b32 s52, s17, 10
	s_sub_i32 s8, s2, s8
	s_cmp_lt_i32 s8, 0
	s_movk_i32 s54, 0x161
	s_cselect_b32 s10, s54, 0x160
	s_mul_i32 s8, s10, s8
	s_add_i32 s8, s8, s9
	s_mul_hi_i32 s9, s8, 0x2e8ba2e9
	s_lshr_b32 s10, s9, 31
	s_ashr_i32 s9, s9, 3
	s_add_i32 s9, s9, s10
	s_lshl_b32 s10, s9, 1
	s_mul_i32 s9, s9, 44
	s_sub_i32 s8, s8, s9
	s_bfe_u32 s9, s8, 0x10007
	s_add_i32 s9, s8, s9
	s_bfe_i32 s11, s9, 0x80000
	s_and_b32 s9, s9, 0xfe
	s_sub_i32 s8, s8, s9
	s_sext_i32_i16 s11, s11
	s_sext_i32_i8 s8, s8
	v_lshrrev_b32_e32 v5, 2, v3
	v_lshlrev_b32_e32 v6, 1, v3
	v_and_b32_e32 v1, 0xc0, v1
	s_lshr_b32 s16, s11, 1
	s_add_i32 s44, s10, s8
	v_and_b32_e32 v5, 4, v5
	v_and_b32_e32 v6, 24, v6
	v_sub_u32_e32 v0, v0, v1
	s_ashr_i32 s45, s44, 31
	s_bfe_i64 s[10:11], s[16:17], 0x100000
	v_or3_b32 v4, v4, v5, v6
	v_lshlrev_b32_e32 v5, 5, v13
	v_ashrrev_i16_sdwa v0, v2, sext(v0) dst_sel:DWORD dst_unused:UNUSED_PAD src0_sel:DWORD src1_sel:BYTE_0
	s_lshl_b64 s[8:9], s[44:45], 19
	s_lshl_b64 s[10:11], s[10:11], 19
	v_and_b32_e32 v5, 32, v5
	v_bfe_i32 v14, v0, 0, 16
	s_add_u32 s46, s50, s10
	v_add_lshl_u32 v0, v5, v14, 1
	s_addc_u32 s47, s51, s11
	s_add_i32 s55, s52, 0
	v_lshl_add_u32 v132, v4, 11, v0
	v_lshrrev_b32_e32 v250, 3, v157
	v_and_b32_e32 v251, 6, v250
	v_and_b32_e32 v252, 7, v157
	v_xor_b32_e32 v251, v251, v252
	v_lshlrev_b32_e32 v251, 4, v251
	v_and_b32_e32 v252, 12, v250
	v_lshlrev_b32_e32 v252, 1, v252
	v_and_b32_e32 v253, 16, v250
	v_lshrrev_b32_e32 v253, 2, v253
	v_or_b32_e32 v252, v252, v253
	v_and_b32_e32 v253, 35, v250
	v_or_b32_e32 v250, v252, v253
	v_mul_u32_u24_e32 v250, 0x800, v250
	v_add_u32_e32 v132, v250, v251
	s_add_i32 m0, s55, 0x10000
	v_lshl_add_u32 v134, v3, 11, v0
	v_lshrrev_b32_e32 v250, 3, v157
	v_and_b32_e32 v251, 6, v250
	v_and_b32_e32 v252, 7, v157
	v_xor_b32_e32 v251, v251, v252
	v_lshlrev_b32_e32 v251, 4, v251
	v_mul_u32_u24_e32 v250, 0x800, v250
	v_add_u32_e32 v134, v250, v251
	global_load_lds_dwordx4 v132, s[46:47]
	s_add_i32 m0, s55, 0x12000
	s_add_u32 s10, s46, 0x40000
	global_load_lds_dwordx4 v128, s[46:47]
	s_addc_u32 s11, s47, 0
	s_add_i32 m0, s55, 0x14000
	v_mov_b32_e32 v133, 0
	global_load_lds_dwordx4 v132, s[10:11]
	s_add_i32 m0, s55, 0x16000
	s_add_u32 s48, s3, s8
	s_addc_u32 s49, s35, s9
	s_add_i32 s56, s55, 0x2000
	global_load_lds_dwordx4 v128, s[10:11]
	s_mov_b32 m0, s55
	s_add_u32 s8, s48, 0x40000
	global_load_lds_dwordx4 v134, s[48:49]
	s_mov_b32 m0, s56
	s_addc_u32 s9, s49, 0
	s_add_i32 s57, s55, 0x4000
	global_load_lds_dwordx4 v130, s[48:49]
	s_mov_b32 m0, s57
	s_add_i32 s58, s55, 0x6000
	global_load_lds_dwordx4 v134, s[8:9]
	s_mov_b32 m0, s58
	v_mov_b32_e32 v129, v133
	global_load_lds_dwordx4 v130, s[8:9]
	v_mov_b32_e32 v135, v133
	v_mov_b32_e32 v131, v133
	s_cmp_eq_u32 s21, 1
	s_mov_b32 s59, 0
	v_lshl_add_u64 v[6:7], s[46:47], 0, v[132:133]
	v_lshl_add_u64 v[4:5], s[46:47], 0, v[128:129]
	v_lshl_add_u64 v[0:1], s[48:49], 0, v[134:135]
	s_cselect_b64 s[8:9], -1, 0
	s_cmp_lg_u32 s21, 1
	v_lshl_add_u64 v[2:3], s[48:49], 0, v[130:131]
	s_cbranch_scc1 .LBB0_69
	s_barrier
.LBB0_69:
	s_add_u32 s10, s4, 0xa000000
	s_addc_u32 s11, s5, 0
	s_add_u32 s12, s4, 0x100000
	s_addc_u32 s13, s5, 0
	s_lshl_b32 s4, s17, 5
	s_mov_b64 s[14:15], 0x80
	s_and_b32 s23, s4, 0x60
	s_add_i32 m0, s55, 0x18000
	v_lshl_add_u64 v[6:7], v[6:7], 0, s[14:15]
	s_lshl_b32 s22, s21, 13
	s_lshl_b32 s26, s23, 7
	s_waitcnt vmcnt(2)
	s_barrier
	global_load_lds_dwordx4 v[6:7], off
	v_lshl_add_u64 v[4:5], v[4:5], 0, s[14:15]
	s_add_i32 m0, s55, 0x1a000
	s_add_i32 s60, s55, 0x8000
	s_add_i32 s61, s55, 0xa000
	global_load_lds_dwordx4 v[4:5], off
	v_lshl_add_u64 v[0:1], v[0:1], 0, s[14:15]
	s_mov_b32 m0, s60
	s_add_u32 s4, s46, 0x40080
	global_load_lds_dwordx4 v[0:1], off
	v_lshl_add_u64 v[0:1], v[2:3], 0, s[14:15]
	s_mov_b32 m0, s61
	s_addc_u32 s5, s47, 0
	global_load_lds_dwordx4 v[0:1], off
	s_add_i32 m0, s55, 0x1c000
	v_lshl_add_u64 v[0:1], s[4:5], 0, v[132:133]
	global_load_lds_dwordx4 v[0:1], off
	v_lshl_add_u64 v[0:1], s[4:5], 0, v[128:129]
	s_add_i32 m0, s55, 0x1e000
	s_cmp_lt_i32 s17, 4
	global_load_lds_dwordx4 v[0:1], off
	v_lshrrev_b32_e32 v1, 1, v8
	v_and_b32_e32 v1, 24, v1
	v_and_b32_e32 v0, 15, v8
	v_lshlrev_b32_e32 v2, 1, v1
	v_lshl_or_b32 v146, s21, 6, v0
	v_lshl_or_b32 v0, v0, 6, v2
	v_lshlrev_b32_e32 v2, 2, v8
	v_or_b32_e32 v149, s23, v1
	v_lshlrev_b32_e32 v1, 14, v9
	v_and_b32_e32 v2, 32, v2
	v_and_b32_e32 v1, 0xffff8000, v1
	v_bitop3_b32 v3, v0, s22, v2 bitop3:0xde
	v_bitop3_b32 v147, v0, s26, v2 bitop3:0xde
	v_and_b32_e32 v250, 15, v157
	v_bfe_u32 v251, v157, 4, 2
	v_and_b32_e32 v252, 2, v250
	v_xor_b32_e32 v251, v251, v252
	v_and_b32_e32 v252, 4, v250
	v_lshlrev_b32_e32 v252, 4, v252
	v_lshl_or_b32 v251, v251, 4, v252
	v_lshl_or_b32 v250, v250, 7, v251
	v_bfe_u32 v253, v157, 6, 2
	v_lshl_or_b32 v147, v253, 12, v250
	v_lshl_add_u32 v1, v10, 11, v1
	v_and_b32_e32 v2, 1, v9
	v_lshl_or_b32 v1, v2, 6, v1
	v_lshl_add_u32 v136, v11, 1, v1
	v_lshrrev_b32_e32 v250, 3, v157
	v_and_b32_e32 v251, 6, v250
	v_and_b32_e32 v252, 7, v157
	v_xor_b32_e32 v251, v251, v252
	v_lshlrev_b32_e32 v251, 4, v251
	v_mul_u32_u24_e32 v250, 0x800, v250
	v_add_u32_e32 v136, v250, v251
	v_add_u32_e32 v136, 0x20000, v136
	v_lshlrev_b32_e32 v1, 14, v13
	v_and_b32_e32 v1, 0xffff8000, v1
	s_waitcnt vmcnt(6)
	s_movk_i32 s4, 0xffc0
	v_mov_b32_e32 v0, s20
	v_lshl_add_u32 v1, v12, 11, v1
	v_and_b32_e32 v2, 1, v13
	s_sext_i32_i8 s67, s16
	s_cselect_b64 s[16:17], -1, 0
	v_bfi_b32 v148, s4, v0, v8
	s_cmpk_lt_u32 s20, 0x100
	v_lshlrev_b32_e32 v0, 4, v146
	v_lshl_or_b32 v1, v2, 6, v1
	s_cselect_b64 s[20:21], -1, 0
	s_ashr_i32 s62, s42, 31
	s_mov_b32 s63, s42
	v_mov_b32_e32 v137, v133
	v_lshl_add_u32 v138, v14, 1, v1
	v_lshrrev_b32_e32 v250, 3, v157
	v_and_b32_e32 v251, 6, v250
	v_and_b32_e32 v252, 7, v157
	v_xor_b32_e32 v251, v251, v252
	v_lshlrev_b32_e32 v251, 4, v251
	v_mul_u32_u24_e32 v250, 0x800, v250
	v_add_u32_e32 v138, v250, v251
	v_mov_b32_e32 v139, v133
	v_mov_b64_e32 v[140:141], 0xb00
	v_mov_b64_e32 v[142:143], 0xaff
	s_add_i32 s64, 0, 0x10000
	s_add_i32 s65, 0, 0x14000
	v_add_u32_e32 v150, 0, v3
	v_and_b32_e32 v250, 15, v157
	v_bfe_u32 v251, v157, 4, 2
	v_and_b32_e32 v252, 2, v250
	v_xor_b32_e32 v251, v251, v252
	v_and_b32_e32 v252, 4, v250
	v_lshlrev_b32_e32 v252, 4, v252
	v_lshl_or_b32 v251, v251, 4, v252
	v_lshl_or_b32 v250, v250, 7, v251
	v_lshrrev_b32_e32 v253, 8, v157
	v_lshl_or_b32 v150, v253, 13, v250
	v_add_u32_e32 v151, 0, v0
	v_mov_b32_e32 v152, 0x358637bd
	s_movk_i32 s66, 0x1600
	s_barrier
	s_branch .LBB0_72

.LBB0_74:
	s_ashr_i32 s27, s26, 31
	s_lshl_b64 s[28:29], s[26:27], 19
	s_add_u32 s28, s3, s28
	s_addc_u32 s29, s35, s29
	s_and_b64 s[30:31], s[4:5], exec
	s_cselect_b32 s27, s29, s49
	s_cselect_b32 s68, s28, s48
	s_ashr_i32 s23, s22, 31
	s_lshl_b64 s[30:31], s[22:23], 19
	s_add_u32 s30, s50, s30
	s_addc_u32 s31, s51, s31
	s_and_b64 s[70:71], s[4:5], exec
	s_cselect_b32 s69, s31, s47
	s_cselect_b32 s70, s30, s46
	s_lshl_b32 s23, s44, 8
	v_add_u32_e32 v0, s23, v148
	s_add_u32 s71, s46, 0x100
	v_ashrrev_i32_e32 v1, 31, v0
	s_addc_u32 s74, s47, 0
	v_lshl_add_u64 v[144:145], v[0:1], 4, s[12:13]
	s_add_u32 s44, s48, 0x40080
	s_addc_u32 s45, s49, 0
	s_mov_b32 s75, -2
	s_mov_b64 s[46:47], 0
	s_cmp_eq_u32 s59, 1
	s_cbranch_scc1 .Lfa_0
	v_add_u32_e32 v153, s64, v147
	ds_read_b128 v[160:163], v153
	v_xor_b32_e32 v253, 64, v153
	ds_read_b128 v[164:167], v253
	ds_read_b128 v[168:171], v153 offset:2048
	ds_read_b128 v[172:175], v253 offset:2048
	v_add_u32_e32 v153, s65, v147
	ds_read_b128 v[176:179], v153
	v_xor_b32_e32 v253, 64, v153
	ds_read_b128 v[180:183], v253
	ds_read_b128 v[186:189], v153 offset:2048
	ds_read_b128 v[190:193], v253 offset:2048
	s_add_u32 s48, s44, 0xfffc0080
	s_addc_u32 s49, s45, -1
	s_and_b64 s[46:47], s[46:47], exec
	s_cselect_b32 s49, s27, s49
	s_cselect_b32 s48, s68, s48
	s_cselect_b32 s47, s69, s74
	s_cselect_b32 s46, s70, s71
	v_lshl_add_u64 v[154:155], s[44:45], 0, v[138:139]
	s_add_i32 m0, s55, 0xc000
	ds_read_b128 v[194:197], v150
	v_xor_b32_e32 v253, 64, v150
	ds_read_b128 v[198:201], v253
	ds_read_b128 v[202:205], v150 offset:2048
	ds_read_b128 v[206:209], v253 offset:2048
	ds_read_b128 v[210:213], v150 offset:4096
	ds_read_b128 v[214:217], v253 offset:4096
	ds_read_b128 v[218:221], v150 offset:6144
	ds_read_b128 v[222:225], v253 offset:6144
	global_load_lds_dwordx4 v[154:155], off
	v_lshl_add_u64 v[154:155], s[44:45], 0, v[136:137]
	s_add_i32 m0, s55, 0xe000
	s_nop 0
	global_load_lds_dwordx4 v[154:155], off
	s_waitcnt vmcnt(16)
	s_waitcnt lgkmcnt(0)
	s_barrier
	s_setprio 1
	s_waitcnt lgkmcnt(0)
	v_mfma_f32_16x16x32_bf16 v[124:127], v[160:163], v[194:197], 0
	v_mfma_f32_16x16x32_bf16 v[116:119], v[168:171], v[194:197], 0
	v_mfma_f32_16x16x32_bf16 v[108:111], v[160:163], v[202:205], 0
	v_mfma_f32_16x16x32_bf16 v[100:103], v[168:171], v[202:205], 0
	v_mfma_f32_16x16x32_bf16 v[92:95], v[160:163], v[210:213], 0
	v_mfma_f32_16x16x32_bf16 v[84:87], v[168:171], v[210:213], 0
	v_mfma_f32_16x16x32_bf16 v[76:79], v[160:163], v[218:221], 0
	v_mfma_f32_16x16x32_bf16 v[68:71], v[168:171], v[218:221], 0
	v_mfma_f32_16x16x32_bf16 v[124:127], v[164:167], v[198:201], v[124:127]
	v_mfma_f32_16x16x32_bf16 v[116:119], v[172:175], v[198:201], v[116:119]
	v_mfma_f32_16x16x32_bf16 v[108:111], v[164:167], v[206:209], v[108:111]
	v_mfma_f32_16x16x32_bf16 v[100:103], v[172:175], v[206:209], v[100:103]
	v_mfma_f32_16x16x32_bf16 v[92:95], v[164:167], v[214:217], v[92:95]
	v_mfma_f32_16x16x32_bf16 v[84:87], v[172:175], v[214:217], v[84:87]
	v_mfma_f32_16x16x32_bf16 v[76:79], v[164:167], v[222:225], v[76:79]
	v_mfma_f32_16x16x32_bf16 v[68:71], v[172:175], v[222:225], v[68:71]
	s_setprio 0
	s_setprio 1
	v_mfma_f32_16x16x32_bf16 v[120:123], v[176:179], v[194:197], 0
	v_mfma_f32_16x16x32_bf16 v[112:115], v[186:189], v[194:197], 0
	v_mfma_f32_16x16x32_bf16 v[104:107], v[176:179], v[202:205], 0
	v_mfma_f32_16x16x32_bf16 v[96:99], v[186:189], v[202:205], 0
	v_mfma_f32_16x16x32_bf16 v[88:91], v[176:179], v[210:213], 0
	v_mfma_f32_16x16x32_bf16 v[80:83], v[186:189], v[210:213], 0
	v_mfma_f32_16x16x32_bf16 v[72:75], v[176:179], v[218:221], 0
	v_mfma_f32_16x16x32_bf16 v[64:67], v[186:189], v[218:221], 0
	v_mfma_f32_16x16x32_bf16 v[120:123], v[180:183], v[198:201], v[120:123]
	v_mfma_f32_16x16x32_bf16 v[112:115], v[190:193], v[198:201], v[112:115]
	v_mfma_f32_16x16x32_bf16 v[104:107], v[180:183], v[206:209], v[104:107]
	v_mfma_f32_16x16x32_bf16 v[96:99], v[190:193], v[206:209], v[96:99]
	v_mfma_f32_16x16x32_bf16 v[88:91], v[180:183], v[214:217], v[88:91]
	v_mfma_f32_16x16x32_bf16 v[80:83], v[190:193], v[214:217], v[80:83]
	v_mfma_f32_16x16x32_bf16 v[72:75], v[180:183], v[222:225], v[72:75]
	v_mfma_f32_16x16x32_bf16 v[64:67], v[190:193], v[222:225], v[64:67]
	s_setprio 0
	s_barrier
	s_add_i32 s76, s64, s52
	v_lshl_add_u64 v[154:155], s[46:47], 0, v[132:133]
	s_mov_b32 m0, s76
	ds_read_b128 v[194:197], v150 offset:16384
	v_xor_b32_e32 v253, 64, v150
	ds_read_b128 v[198:201], v253 offset:16384
	ds_read_b128 v[202:205], v150 offset:18432
	ds_read_b128 v[206:209], v253 offset:18432
	ds_read_b128 v[210:213], v150 offset:20480
	ds_read_b128 v[214:217], v253 offset:20480
	ds_read_b128 v[218:221], v150 offset:22528
	ds_read_b128 v[222:225], v253 offset:22528
	global_load_lds_dwordx4 v[154:155], off
	s_add_i32 m0, s76, 0x2000
	s_add_u32 s76, s46, 0x40000
	v_lshl_add_u64 v[226:227], s[46:47], 0, v[128:129]
	s_addc_u32 s77, s47, 0
	s_add_i32 s78, s65, s52
	global_load_lds_dwordx4 v[226:227], off
	v_lshl_add_u64 v[228:229], s[76:77], 0, v[132:133]
	s_mov_b32 m0, s78
	v_lshl_add_u64 v[230:231], s[48:49], 0, v[130:131]
	global_load_lds_dwordx4 v[228:229], off
	v_lshl_add_u64 v[228:229], s[76:77], 0, v[128:129]
	s_add_i32 m0, s78, 0x2000
	s_nop 0
	global_load_lds_dwordx4 v[228:229], off
	v_lshl_add_u64 v[228:229], s[48:49], 0, v[134:135]
	s_mov_b32 m0, s55
	s_nop 0
	global_load_lds_dwordx4 v[228:229], off
	s_mov_b32 m0, s56
	s_nop 0
	global_load_lds_dwordx4 v[230:231], off
	s_waitcnt vmcnt(16)
	s_waitcnt lgkmcnt(0)
	s_barrier
	s_setprio 1
	s_waitcnt lgkmcnt(0)
	v_mfma_f32_16x16x32_bf16 v[60:63], v[160:163], v[194:197], 0
	v_mfma_f32_16x16x32_bf16 v[52:55], v[168:171], v[194:197], 0
	v_mfma_f32_16x16x32_bf16 v[44:47], v[160:163], v[202:205], 0
	v_mfma_f32_16x16x32_bf16 v[36:39], v[168:171], v[202:205], 0
	v_mfma_f32_16x16x32_bf16 v[28:31], v[160:163], v[210:213], 0
	v_mfma_f32_16x16x32_bf16 v[20:23], v[168:171], v[210:213], 0
	v_mfma_f32_16x16x32_bf16 v[12:15], v[160:163], v[218:221], 0
	v_mfma_f32_16x16x32_bf16 v[4:7], v[168:171], v[218:221], 0
	v_mfma_f32_16x16x32_bf16 v[60:63], v[164:167], v[198:201], v[60:63]
	v_mfma_f32_16x16x32_bf16 v[52:55], v[172:175], v[198:201], v[52:55]
	v_mfma_f32_16x16x32_bf16 v[44:47], v[164:167], v[206:209], v[44:47]
	v_mfma_f32_16x16x32_bf16 v[36:39], v[172:175], v[206:209], v[36:39]
	v_mfma_f32_16x16x32_bf16 v[28:31], v[164:167], v[214:217], v[28:31]
	v_mfma_f32_16x16x32_bf16 v[20:23], v[172:175], v[214:217], v[20:23]
	v_mfma_f32_16x16x32_bf16 v[12:15], v[164:167], v[222:225], v[12:15]
	v_mfma_f32_16x16x32_bf16 v[4:7], v[172:175], v[222:225], v[4:7]
	s_setprio 0
	s_setprio 1
	v_mfma_f32_16x16x32_bf16 v[56:59], v[176:179], v[194:197], 0
	v_mfma_f32_16x16x32_bf16 v[48:51], v[186:189], v[194:197], 0
	v_mfma_f32_16x16x32_bf16 v[40:43], v[176:179], v[202:205], 0
	v_mfma_f32_16x16x32_bf16 v[32:35], v[186:189], v[202:205], 0
	v_mfma_f32_16x16x32_bf16 v[24:27], v[176:179], v[210:213], 0
	v_mfma_f32_16x16x32_bf16 v[16:19], v[186:189], v[210:213], 0
	v_mfma_f32_16x16x32_bf16 v[8:11], v[176:179], v[218:221], 0
	v_mfma_f32_16x16x32_bf16 v[0:3], v[186:189], v[218:221], 0
	v_mfma_f32_16x16x32_bf16 v[56:59], v[180:183], v[198:201], v[56:59]
	v_mfma_f32_16x16x32_bf16 v[48:51], v[190:193], v[198:201], v[48:51]
	v_mfma_f32_16x16x32_bf16 v[40:43], v[180:183], v[206:209], v[40:43]
	v_mfma_f32_16x16x32_bf16 v[32:35], v[190:193], v[206:209], v[32:35]
	v_mfma_f32_16x16x32_bf16 v[24:27], v[180:183], v[214:217], v[24:27]
	v_mfma_f32_16x16x32_bf16 v[16:19], v[190:193], v[214:217], v[16:19]
	v_mfma_f32_16x16x32_bf16 v[8:11], v[180:183], v[222:225], v[8:11]
	v_mfma_f32_16x16x32_bf16 v[0:3], v[190:193], v[222:225], v[0:3]
	s_setprio 0
	s_barrier
	s_add_i32 s76, 0, 0x18000
	v_add_u32_e32 v153, s76, v147
	s_add_i32 s77, 0, 0x1c000
	ds_read_b128 v[160:163], v153
	v_xor_b32_e32 v253, 64, v153
	ds_read_b128 v[164:167], v253
	ds_read_b128 v[168:171], v153 offset:2048
	ds_read_b128 v[172:175], v253 offset:2048
	v_add_u32_e32 v153, s77, v147
	ds_read_b128 v[176:179], v153
	v_xor_b32_e32 v253, 64, v153
	ds_read_b128 v[180:183], v253
	ds_read_b128 v[186:189], v153 offset:2048
	ds_read_b128 v[190:193], v253 offset:2048
	s_add_u32 s48, s48, 0x40000
	s_addc_u32 s49, s49, 0
	s_mov_b32 m0, s57
	v_lshl_add_u64 v[232:233], s[48:49], 0, v[134:135]
	ds_read_b128 v[194:197], v150 offset:32768
	v_xor_b32_e32 v253, 64, v150
	ds_read_b128 v[198:201], v253 offset:32768
	ds_read_b128 v[202:205], v150 offset:34816
	ds_read_b128 v[206:209], v253 offset:34816
	ds_read_b128 v[210:213], v150 offset:36864
	ds_read_b128 v[214:217], v253 offset:36864
	ds_read_b128 v[218:221], v150 offset:38912
	ds_read_b128 v[222:225], v253 offset:38912
	global_load_lds_dwordx4 v[232:233], off
	v_lshl_add_u64 v[232:233], s[48:49], 0, v[130:131]
	s_mov_b32 m0, s58
	s_nop 0
	global_load_lds_dwordx4 v[232:233], off
	s_waitcnt vmcnt(8)
	s_waitcnt lgkmcnt(0)
	s_barrier
	s_setprio 1
	s_waitcnt lgkmcnt(0)
	v_mfma_f32_16x16x32_bf16 v[124:127], v[160:163], v[194:197], v[124:127]
	v_mfma_f32_16x16x32_bf16 v[116:119], v[168:171], v[194:197], v[116:119]
	v_mfma_f32_16x16x32_bf16 v[108:111], v[160:163], v[202:205], v[108:111]
	v_mfma_f32_16x16x32_bf16 v[100:103], v[168:171], v[202:205], v[100:103]
	v_mfma_f32_16x16x32_bf16 v[92:95], v[160:163], v[210:213], v[92:95]
	v_mfma_f32_16x16x32_bf16 v[84:87], v[168:171], v[210:213], v[84:87]
	v_mfma_f32_16x16x32_bf16 v[76:79], v[160:163], v[218:221], v[76:79]
	v_mfma_f32_16x16x32_bf16 v[68:71], v[168:171], v[218:221], v[68:71]
	v_mfma_f32_16x16x32_bf16 v[124:127], v[164:167], v[198:201], v[124:127]
	v_mfma_f32_16x16x32_bf16 v[116:119], v[172:175], v[198:201], v[116:119]
	v_mfma_f32_16x16x32_bf16 v[108:111], v[164:167], v[206:209], v[108:111]
	v_mfma_f32_16x16x32_bf16 v[100:103], v[172:175], v[206:209], v[100:103]
	v_mfma_f32_16x16x32_bf16 v[92:95], v[164:167], v[214:217], v[92:95]
	v_mfma_f32_16x16x32_bf16 v[84:87], v[172:175], v[214:217], v[84:87]
	v_mfma_f32_16x16x32_bf16 v[76:79], v[164:167], v[222:225], v[76:79]
	v_mfma_f32_16x16x32_bf16 v[68:71], v[172:175], v[222:225], v[68:71]
	s_setprio 0
	s_setprio 1
	v_mfma_f32_16x16x32_bf16 v[120:123], v[176:179], v[194:197], v[120:123]
	v_mfma_f32_16x16x32_bf16 v[112:115], v[186:189], v[194:197], v[112:115]
	v_mfma_f32_16x16x32_bf16 v[104:107], v[176:179], v[202:205], v[104:107]
	v_mfma_f32_16x16x32_bf16 v[96:99], v[186:189], v[202:205], v[96:99]
	v_mfma_f32_16x16x32_bf16 v[88:91], v[176:179], v[210:213], v[88:91]
	v_mfma_f32_16x16x32_bf16 v[80:83], v[186:189], v[210:213], v[80:83]
	v_mfma_f32_16x16x32_bf16 v[72:75], v[176:179], v[218:221], v[72:75]
	v_mfma_f32_16x16x32_bf16 v[64:67], v[186:189], v[218:221], v[64:67]
	v_mfma_f32_16x16x32_bf16 v[120:123], v[180:183], v[198:201], v[120:123]
	v_mfma_f32_16x16x32_bf16 v[112:115], v[190:193], v[198:201], v[112:115]
	v_mfma_f32_16x16x32_bf16 v[104:107], v[180:183], v[206:209], v[104:107]
	v_mfma_f32_16x16x32_bf16 v[96:99], v[190:193], v[206:209], v[96:99]
	v_mfma_f32_16x16x32_bf16 v[88:91], v[180:183], v[214:217], v[88:91]
	v_mfma_f32_16x16x32_bf16 v[80:83], v[190:193], v[214:217], v[80:83]
	v_mfma_f32_16x16x32_bf16 v[72:75], v[180:183], v[222:225], v[72:75]
	v_mfma_f32_16x16x32_bf16 v[64:67], v[190:193], v[222:225], v[64:67]
	s_setprio 0
	s_barrier
	s_add_i32 s48, s76, s52
	v_lshl_add_u64 v[154:155], v[154:155], 0, s[14:15]
	s_mov_b32 m0, s48
	ds_read_b128 v[194:197], v150 offset:49152
	v_xor_b32_e32 v253, 64, v150
	ds_read_b128 v[198:201], v253 offset:49152
	ds_read_b128 v[202:205], v150 offset:51200
	ds_read_b128 v[206:209], v253 offset:51200
	ds_read_b128 v[210:213], v150 offset:53248
	ds_read_b128 v[214:217], v253 offset:53248
	ds_read_b128 v[218:221], v150 offset:55296
	ds_read_b128 v[222:225], v253 offset:55296
	global_load_lds_dwordx4 v[154:155], off
	s_add_i32 m0, s48, 0x2000
	s_add_u32 s46, s46, 0x40080
	v_lshl_add_u64 v[154:155], v[226:227], 0, s[14:15]
	s_addc_u32 s47, s47, 0
	s_add_i32 s48, s77, s52
	global_load_lds_dwordx4 v[154:155], off
	v_lshl_add_u64 v[154:155], s[46:47], 0, v[132:133]
	s_mov_b32 m0, s48
	s_nop 0
	global_load_lds_dwordx4 v[154:155], off
	v_lshl_add_u64 v[154:155], s[46:47], 0, v[128:129]
	s_add_i32 m0, s48, 0x2000
	s_nop 0
	global_load_lds_dwordx4 v[154:155], off
	v_lshl_add_u64 v[154:155], v[228:229], 0, s[14:15]
	s_mov_b32 m0, s60
	s_nop 0
	global_load_lds_dwordx4 v[154:155], off
	v_lshl_add_u64 v[154:155], v[230:231], 0, s[14:15]
	s_mov_b32 m0, s61
	s_nop 0
	global_load_lds_dwordx4 v[154:155], off
	s_waitcnt vmcnt(8)
	s_waitcnt lgkmcnt(0)
	s_barrier
	s_setprio 1
	s_waitcnt lgkmcnt(0)
	v_mfma_f32_16x16x32_bf16 v[60:63], v[160:163], v[194:197], v[60:63]
	v_mfma_f32_16x16x32_bf16 v[52:55], v[168:171], v[194:197], v[52:55]
	v_mfma_f32_16x16x32_bf16 v[44:47], v[160:163], v[202:205], v[44:47]
	v_mfma_f32_16x16x32_bf16 v[36:39], v[168:171], v[202:205], v[36:39]
	v_mfma_f32_16x16x32_bf16 v[28:31], v[160:163], v[210:213], v[28:31]
	v_mfma_f32_16x16x32_bf16 v[20:23], v[168:171], v[210:213], v[20:23]
	v_mfma_f32_16x16x32_bf16 v[12:15], v[160:163], v[218:221], v[12:15]
	v_mfma_f32_16x16x32_bf16 v[4:7], v[168:171], v[218:221], v[4:7]
	v_mfma_f32_16x16x32_bf16 v[60:63], v[164:167], v[198:201], v[60:63]
	v_mfma_f32_16x16x32_bf16 v[52:55], v[172:175], v[198:201], v[52:55]
	v_mfma_f32_16x16x32_bf16 v[44:47], v[164:167], v[206:209], v[44:47]
	v_mfma_f32_16x16x32_bf16 v[36:39], v[172:175], v[206:209], v[36:39]
	v_mfma_f32_16x16x32_bf16 v[28:31], v[164:167], v[214:217], v[28:31]
	v_mfma_f32_16x16x32_bf16 v[20:23], v[172:175], v[214:217], v[20:23]
	v_mfma_f32_16x16x32_bf16 v[12:15], v[164:167], v[222:225], v[12:15]
	v_mfma_f32_16x16x32_bf16 v[4:7], v[172:175], v[222:225], v[4:7]
	s_setprio 0
	s_setprio 1
	v_mfma_f32_16x16x32_bf16 v[56:59], v[176:179], v[194:197], v[56:59]
	v_mfma_f32_16x16x32_bf16 v[48:51], v[186:189], v[194:197], v[48:51]
	v_mfma_f32_16x16x32_bf16 v[40:43], v[176:179], v[202:205], v[40:43]
	v_mfma_f32_16x16x32_bf16 v[32:35], v[186:189], v[202:205], v[32:35]
	v_mfma_f32_16x16x32_bf16 v[24:27], v[176:179], v[210:213], v[24:27]
	v_mfma_f32_16x16x32_bf16 v[16:19], v[186:189], v[210:213], v[16:19]
	v_mfma_f32_16x16x32_bf16 v[8:11], v[176:179], v[218:221], v[8:11]
	v_mfma_f32_16x16x32_bf16 v[0:3], v[186:189], v[218:221], v[0:3]
	v_mfma_f32_16x16x32_bf16 v[56:59], v[180:183], v[198:201], v[56:59]
	v_mfma_f32_16x16x32_bf16 v[48:51], v[190:193], v[198:201], v[48:51]
	v_mfma_f32_16x16x32_bf16 v[40:43], v[180:183], v[206:209], v[40:43]
	v_mfma_f32_16x16x32_bf16 v[32:35], v[190:193], v[206:209], v[32:35]
	v_mfma_f32_16x16x32_bf16 v[24:27], v[180:183], v[214:217], v[24:27]
	v_mfma_f32_16x16x32_bf16 v[16:19], v[190:193], v[214:217], v[16:19]
	v_mfma_f32_16x16x32_bf16 v[8:11], v[180:183], v[222:225], v[8:11]
	v_mfma_f32_16x16x32_bf16 v[0:3], v[190:193], v[222:225], v[0:3]
	s_setprio 0
	s_barrier
	s_add_i32 s75, s75, 2
	s_add_u32 s71, s71, 0x100
	s_addc_u32 s74, s74, 0
	s_add_u32 s44, s44, 0x100
	s_addc_u32 s45, s45, 0
	s_branch .LBB0_76
.Lfa_0:
	v_add_u32_e32 v153, s64, v147
	ds_read_b128 v[160:163], v153
	v_xor_b32_e32 v253, 64, v153
	ds_read_b128 v[164:167], v253
	ds_read_b128 v[168:171], v153 offset:2048
	ds_read_b128 v[172:175], v253 offset:2048
	v_add_u32_e32 v153, s65, v147
	ds_read_b128 v[176:179], v153
	v_xor_b32_e32 v253, 64, v153
	ds_read_b128 v[180:183], v253
	ds_read_b128 v[186:189], v153 offset:2048
	ds_read_b128 v[190:193], v253 offset:2048
	s_add_u32 s48, s44, 0xfffc0080
	s_addc_u32 s49, s45, -1
	s_and_b64 s[46:47], s[46:47], exec
	s_cselect_b32 s49, s27, s49
	s_cselect_b32 s48, s68, s48
	s_cselect_b32 s47, s69, s74
	s_cselect_b32 s46, s70, s71
	v_lshl_add_u64 v[154:155], s[44:45], 0, v[138:139]
	s_add_i32 m0, s55, 0xc000
	ds_read_b128 v[194:197], v150
	v_xor_b32_e32 v253, 64, v150
	ds_read_b128 v[198:201], v253
	ds_read_b128 v[202:205], v150 offset:2048
	ds_read_b128 v[206:209], v253 offset:2048
	ds_read_b128 v[210:213], v150 offset:4096
	ds_read_b128 v[214:217], v253 offset:4096
	ds_read_b128 v[218:221], v150 offset:6144
	ds_read_b128 v[222:225], v253 offset:6144
	global_load_lds_dwordx4 v[154:155], off
	v_lshl_add_u64 v[154:155], s[44:45], 0, v[136:137]
	s_add_i32 m0, s55, 0xe000
	s_nop 0
	global_load_lds_dwordx4 v[154:155], off
	s_waitcnt vmcnt(8)
	s_waitcnt lgkmcnt(0)
	s_barrier
	s_setprio 1
	s_waitcnt lgkmcnt(0)
	v_mfma_f32_16x16x32_bf16 v[124:127], v[160:163], v[194:197], 0
	v_mfma_f32_16x16x32_bf16 v[116:119], v[168:171], v[194:197], 0
	v_mfma_f32_16x16x32_bf16 v[108:111], v[160:163], v[202:205], 0
	v_mfma_f32_16x16x32_bf16 v[100:103], v[168:171], v[202:205], 0
	v_mfma_f32_16x16x32_bf16 v[92:95], v[160:163], v[210:213], 0
	v_mfma_f32_16x16x32_bf16 v[84:87], v[168:171], v[210:213], 0
	v_mfma_f32_16x16x32_bf16 v[76:79], v[160:163], v[218:221], 0
	v_mfma_f32_16x16x32_bf16 v[68:71], v[168:171], v[218:221], 0
	v_mfma_f32_16x16x32_bf16 v[124:127], v[164:167], v[198:201], v[124:127]
	v_mfma_f32_16x16x32_bf16 v[116:119], v[172:175], v[198:201], v[116:119]
	v_mfma_f32_16x16x32_bf16 v[108:111], v[164:167], v[206:209], v[108:111]
	v_mfma_f32_16x16x32_bf16 v[100:103], v[172:175], v[206:209], v[100:103]
	v_mfma_f32_16x16x32_bf16 v[92:95], v[164:167], v[214:217], v[92:95]
	v_mfma_f32_16x16x32_bf16 v[84:87], v[172:175], v[214:217], v[84:87]
	v_mfma_f32_16x16x32_bf16 v[76:79], v[164:167], v[222:225], v[76:79]
	v_mfma_f32_16x16x32_bf16 v[68:71], v[172:175], v[222:225], v[68:71]
	s_setprio 0
	s_setprio 1
	v_mfma_f32_16x16x32_bf16 v[120:123], v[176:179], v[194:197], 0
	v_mfma_f32_16x16x32_bf16 v[112:115], v[186:189], v[194:197], 0
	v_mfma_f32_16x16x32_bf16 v[104:107], v[176:179], v[202:205], 0
	v_mfma_f32_16x16x32_bf16 v[96:99], v[186:189], v[202:205], 0
	v_mfma_f32_16x16x32_bf16 v[88:91], v[176:179], v[210:213], 0
	v_mfma_f32_16x16x32_bf16 v[80:83], v[186:189], v[210:213], 0
	v_mfma_f32_16x16x32_bf16 v[72:75], v[176:179], v[218:221], 0
	v_mfma_f32_16x16x32_bf16 v[64:67], v[186:189], v[218:221], 0
	v_mfma_f32_16x16x32_bf16 v[120:123], v[180:183], v[198:201], v[120:123]
	v_mfma_f32_16x16x32_bf16 v[112:115], v[190:193], v[198:201], v[112:115]
	v_mfma_f32_16x16x32_bf16 v[104:107], v[180:183], v[206:209], v[104:107]
	v_mfma_f32_16x16x32_bf16 v[96:99], v[190:193], v[206:209], v[96:99]
	v_mfma_f32_16x16x32_bf16 v[88:91], v[180:183], v[214:217], v[88:91]
	v_mfma_f32_16x16x32_bf16 v[80:83], v[190:193], v[214:217], v[80:83]
	v_mfma_f32_16x16x32_bf16 v[72:75], v[180:183], v[222:225], v[72:75]
	v_mfma_f32_16x16x32_bf16 v[64:67], v[190:193], v[222:225], v[64:67]
	s_setprio 0
	s_barrier
	s_add_i32 s76, s64, s52
	v_lshl_add_u64 v[154:155], s[46:47], 0, v[132:133]
	s_mov_b32 m0, s76
	ds_read_b128 v[194:197], v150 offset:16384
	v_xor_b32_e32 v253, 64, v150
	ds_read_b128 v[198:201], v253 offset:16384
	ds_read_b128 v[202:205], v150 offset:18432
	ds_read_b128 v[206:209], v253 offset:18432
	ds_read_b128 v[210:213], v150 offset:20480
	ds_read_b128 v[214:217], v253 offset:20480
	ds_read_b128 v[218:221], v150 offset:22528
	ds_read_b128 v[222:225], v253 offset:22528
	global_load_lds_dwordx4 v[154:155], off
	s_add_i32 m0, s76, 0x2000
	s_add_u32 s76, s46, 0x40000
	v_lshl_add_u64 v[226:227], s[46:47], 0, v[128:129]
	s_addc_u32 s77, s47, 0
	s_add_i32 s78, s65, s52
	global_load_lds_dwordx4 v[226:227], off
	v_lshl_add_u64 v[228:229], s[76:77], 0, v[132:133]
	s_mov_b32 m0, s78
	v_lshl_add_u64 v[230:231], s[48:49], 0, v[130:131]
	global_load_lds_dwordx4 v[228:229], off
	v_lshl_add_u64 v[228:229], s[76:77], 0, v[128:129]
	s_add_i32 m0, s78, 0x2000
	s_nop 0
	global_load_lds_dwordx4 v[228:229], off
	v_lshl_add_u64 v[228:229], s[48:49], 0, v[134:135]
	s_mov_b32 m0, s55
	s_nop 0
	global_load_lds_dwordx4 v[228:229], off
	s_mov_b32 m0, s56
	s_nop 0
	global_load_lds_dwordx4 v[230:231], off
	s_waitcnt vmcnt(8)
	s_waitcnt lgkmcnt(0)
	s_barrier
	s_setprio 1
	s_waitcnt lgkmcnt(0)
	v_mfma_f32_16x16x32_bf16 v[60:63], v[160:163], v[194:197], 0
	v_mfma_f32_16x16x32_bf16 v[52:55], v[168:171], v[194:197], 0
	v_mfma_f32_16x16x32_bf16 v[44:47], v[160:163], v[202:205], 0
	v_mfma_f32_16x16x32_bf16 v[36:39], v[168:171], v[202:205], 0
	v_mfma_f32_16x16x32_bf16 v[28:31], v[160:163], v[210:213], 0
	v_mfma_f32_16x16x32_bf16 v[20:23], v[168:171], v[210:213], 0
	v_mfma_f32_16x16x32_bf16 v[12:15], v[160:163], v[218:221], 0
	v_mfma_f32_16x16x32_bf16 v[4:7], v[168:171], v[218:221], 0
	v_mfma_f32_16x16x32_bf16 v[60:63], v[164:167], v[198:201], v[60:63]
	v_mfma_f32_16x16x32_bf16 v[52:55], v[172:175], v[198:201], v[52:55]
	v_mfma_f32_16x16x32_bf16 v[44:47], v[164:167], v[206:209], v[44:47]
	v_mfma_f32_16x16x32_bf16 v[36:39], v[172:175], v[206:209], v[36:39]
	v_mfma_f32_16x16x32_bf16 v[28:31], v[164:167], v[214:217], v[28:31]
	v_mfma_f32_16x16x32_bf16 v[20:23], v[172:175], v[214:217], v[20:23]
	v_mfma_f32_16x16x32_bf16 v[12:15], v[164:167], v[222:225], v[12:15]
	v_mfma_f32_16x16x32_bf16 v[4:7], v[172:175], v[222:225], v[4:7]
	s_setprio 0
	s_setprio 1
	v_mfma_f32_16x16x32_bf16 v[56:59], v[176:179], v[194:197], 0
	v_mfma_f32_16x16x32_bf16 v[48:51], v[186:189], v[194:197], 0
	v_mfma_f32_16x16x32_bf16 v[40:43], v[176:179], v[202:205], 0
	v_mfma_f32_16x16x32_bf16 v[32:35], v[186:189], v[202:205], 0
	v_mfma_f32_16x16x32_bf16 v[24:27], v[176:179], v[210:213], 0
	v_mfma_f32_16x16x32_bf16 v[16:19], v[186:189], v[210:213], 0
	v_mfma_f32_16x16x32_bf16 v[8:11], v[176:179], v[218:221], 0
	v_mfma_f32_16x16x32_bf16 v[0:3], v[186:189], v[218:221], 0
	v_mfma_f32_16x16x32_bf16 v[56:59], v[180:183], v[198:201], v[56:59]
	v_mfma_f32_16x16x32_bf16 v[48:51], v[190:193], v[198:201], v[48:51]
	v_mfma_f32_16x16x32_bf16 v[40:43], v[180:183], v[206:209], v[40:43]
	v_mfma_f32_16x16x32_bf16 v[32:35], v[190:193], v[206:209], v[32:35]
	v_mfma_f32_16x16x32_bf16 v[24:27], v[180:183], v[214:217], v[24:27]
	v_mfma_f32_16x16x32_bf16 v[16:19], v[190:193], v[214:217], v[16:19]
	v_mfma_f32_16x16x32_bf16 v[8:11], v[180:183], v[222:225], v[8:11]
	v_mfma_f32_16x16x32_bf16 v[0:3], v[190:193], v[222:225], v[0:3]
	s_setprio 0
	s_barrier
	s_add_i32 s76, 0, 0x18000
	v_add_u32_e32 v153, s76, v147
	s_add_i32 s77, 0, 0x1c000
	ds_read_b128 v[160:163], v153
	v_xor_b32_e32 v253, 64, v153
	ds_read_b128 v[164:167], v253
	ds_read_b128 v[168:171], v153 offset:2048
	ds_read_b128 v[172:175], v253 offset:2048
	v_add_u32_e32 v153, s77, v147
	ds_read_b128 v[176:179], v153
	v_xor_b32_e32 v253, 64, v153
	ds_read_b128 v[180:183], v253
	ds_read_b128 v[186:189], v153 offset:2048
	ds_read_b128 v[190:193], v253 offset:2048
	s_add_u32 s48, s48, 0x40000
	s_addc_u32 s49, s49, 0
	s_mov_b32 m0, s57
	v_lshl_add_u64 v[232:233], s[48:49], 0, v[134:135]
	ds_read_b128 v[194:197], v150 offset:32768
	v_xor_b32_e32 v253, 64, v150
	ds_read_b128 v[198:201], v253 offset:32768
	ds_read_b128 v[202:205], v150 offset:34816
	ds_read_b128 v[206:209], v253 offset:34816
	ds_read_b128 v[210:213], v150 offset:36864
	ds_read_b128 v[214:217], v253 offset:36864
	ds_read_b128 v[218:221], v150 offset:38912
	ds_read_b128 v[222:225], v253 offset:38912
	global_load_lds_dwordx4 v[232:233], off
	v_lshl_add_u64 v[232:233], s[48:49], 0, v[130:131]
	s_mov_b32 m0, s58
	s_nop 0
	global_load_lds_dwordx4 v[232:233], off
	s_waitcnt vmcnt(8)
	s_waitcnt lgkmcnt(0)
	s_barrier
	s_setprio 1
	s_waitcnt lgkmcnt(0)
	v_mfma_f32_16x16x32_bf16 v[124:127], v[160:163], v[194:197], v[124:127]
	v_mfma_f32_16x16x32_bf16 v[116:119], v[168:171], v[194:197], v[116:119]
	v_mfma_f32_16x16x32_bf16 v[108:111], v[160:163], v[202:205], v[108:111]
	v_mfma_f32_16x16x32_bf16 v[100:103], v[168:171], v[202:205], v[100:103]
	v_mfma_f32_16x16x32_bf16 v[92:95], v[160:163], v[210:213], v[92:95]
	v_mfma_f32_16x16x32_bf16 v[84:87], v[168:171], v[210:213], v[84:87]
	v_mfma_f32_16x16x32_bf16 v[76:79], v[160:163], v[218:221], v[76:79]
	v_mfma_f32_16x16x32_bf16 v[68:71], v[168:171], v[218:221], v[68:71]
	v_mfma_f32_16x16x32_bf16 v[124:127], v[164:167], v[198:201], v[124:127]
	v_mfma_f32_16x16x32_bf16 v[116:119], v[172:175], v[198:201], v[116:119]
	v_mfma_f32_16x16x32_bf16 v[108:111], v[164:167], v[206:209], v[108:111]
	v_mfma_f32_16x16x32_bf16 v[100:103], v[172:175], v[206:209], v[100:103]
	v_mfma_f32_16x16x32_bf16 v[92:95], v[164:167], v[214:217], v[92:95]
	v_mfma_f32_16x16x32_bf16 v[84:87], v[172:175], v[214:217], v[84:87]
	v_mfma_f32_16x16x32_bf16 v[76:79], v[164:167], v[222:225], v[76:79]
	v_mfma_f32_16x16x32_bf16 v[68:71], v[172:175], v[222:225], v[68:71]
	s_setprio 0
	s_setprio 1
	v_mfma_f32_16x16x32_bf16 v[120:123], v[176:179], v[194:197], v[120:123]
	v_mfma_f32_16x16x32_bf16 v[112:115], v[186:189], v[194:197], v[112:115]
	v_mfma_f32_16x16x32_bf16 v[104:107], v[176:179], v[202:205], v[104:107]
	v_mfma_f32_16x16x32_bf16 v[96:99], v[186:189], v[202:205], v[96:99]
	v_mfma_f32_16x16x32_bf16 v[88:91], v[176:179], v[210:213], v[88:91]
	v_mfma_f32_16x16x32_bf16 v[80:83], v[186:189], v[210:213], v[80:83]
	v_mfma_f32_16x16x32_bf16 v[72:75], v[176:179], v[218:221], v[72:75]
	v_mfma_f32_16x16x32_bf16 v[64:67], v[186:189], v[218:221], v[64:67]
	v_mfma_f32_16x16x32_bf16 v[120:123], v[180:183], v[198:201], v[120:123]
	v_mfma_f32_16x16x32_bf16 v[112:115], v[190:193], v[198:201], v[112:115]
	v_mfma_f32_16x16x32_bf16 v[104:107], v[180:183], v[206:209], v[104:107]
	v_mfma_f32_16x16x32_bf16 v[96:99], v[190:193], v[206:209], v[96:99]
	v_mfma_f32_16x16x32_bf16 v[88:91], v[180:183], v[214:217], v[88:91]
	v_mfma_f32_16x16x32_bf16 v[80:83], v[190:193], v[214:217], v[80:83]
	v_mfma_f32_16x16x32_bf16 v[72:75], v[180:183], v[222:225], v[72:75]
	v_mfma_f32_16x16x32_bf16 v[64:67], v[190:193], v[222:225], v[64:67]
	s_setprio 0
	s_barrier
	s_add_i32 s48, s76, s52
	v_lshl_add_u64 v[154:155], v[154:155], 0, s[14:15]
	s_mov_b32 m0, s48
	ds_read_b128 v[194:197], v150 offset:49152
	v_xor_b32_e32 v253, 64, v150
	ds_read_b128 v[198:201], v253 offset:49152
	ds_read_b128 v[202:205], v150 offset:51200
	ds_read_b128 v[206:209], v253 offset:51200
	ds_read_b128 v[210:213], v150 offset:53248
	ds_read_b128 v[214:217], v253 offset:53248
	ds_read_b128 v[218:221], v150 offset:55296
	ds_read_b128 v[222:225], v253 offset:55296
	global_load_lds_dwordx4 v[154:155], off
	s_add_i32 m0, s48, 0x2000
	s_add_u32 s46, s46, 0x40080
	v_lshl_add_u64 v[154:155], v[226:227], 0, s[14:15]
	s_addc_u32 s47, s47, 0
	s_add_i32 s48, s77, s52
	global_load_lds_dwordx4 v[154:155], off
	v_lshl_add_u64 v[154:155], s[46:47], 0, v[132:133]
	s_mov_b32 m0, s48
	s_nop 0
	global_load_lds_dwordx4 v[154:155], off
	v_lshl_add_u64 v[154:155], s[46:47], 0, v[128:129]
	s_add_i32 m0, s48, 0x2000
	s_nop 0
	global_load_lds_dwordx4 v[154:155], off
	v_lshl_add_u64 v[154:155], v[228:229], 0, s[14:15]
	s_mov_b32 m0, s60
	s_nop 0
	global_load_lds_dwordx4 v[154:155], off
	v_lshl_add_u64 v[154:155], v[230:231], 0, s[14:15]
	s_mov_b32 m0, s61
	s_nop 0
	global_load_lds_dwordx4 v[154:155], off
	s_waitcnt vmcnt(8)
	s_waitcnt lgkmcnt(0)
	s_barrier
	s_setprio 1
	s_waitcnt lgkmcnt(0)
	v_mfma_f32_16x16x32_bf16 v[60:63], v[160:163], v[194:197], v[60:63]
	v_mfma_f32_16x16x32_bf16 v[52:55], v[168:171], v[194:197], v[52:55]
	v_mfma_f32_16x16x32_bf16 v[44:47], v[160:163], v[202:205], v[44:47]
	v_mfma_f32_16x16x32_bf16 v[36:39], v[168:171], v[202:205], v[36:39]
	v_mfma_f32_16x16x32_bf16 v[28:31], v[160:163], v[210:213], v[28:31]
	v_mfma_f32_16x16x32_bf16 v[20:23], v[168:171], v[210:213], v[20:23]
	v_mfma_f32_16x16x32_bf16 v[12:15], v[160:163], v[218:221], v[12:15]
	v_mfma_f32_16x16x32_bf16 v[4:7], v[168:171], v[218:221], v[4:7]
	v_mfma_f32_16x16x32_bf16 v[60:63], v[164:167], v[198:201], v[60:63]
	v_mfma_f32_16x16x32_bf16 v[52:55], v[172:175], v[198:201], v[52:55]
	v_mfma_f32_16x16x32_bf16 v[44:47], v[164:167], v[206:209], v[44:47]
	v_mfma_f32_16x16x32_bf16 v[36:39], v[172:175], v[206:209], v[36:39]
	v_mfma_f32_16x16x32_bf16 v[28:31], v[164:167], v[214:217], v[28:31]
	v_mfma_f32_16x16x32_bf16 v[20:23], v[172:175], v[214:217], v[20:23]
	v_mfma_f32_16x16x32_bf16 v[12:15], v[164:167], v[222:225], v[12:15]
	v_mfma_f32_16x16x32_bf16 v[4:7], v[172:175], v[222:225], v[4:7]
	s_setprio 0
	s_setprio 1
	v_mfma_f32_16x16x32_bf16 v[56:59], v[176:179], v[194:197], v[56:59]
	v_mfma_f32_16x16x32_bf16 v[48:51], v[186:189], v[194:197], v[48:51]
	v_mfma_f32_16x16x32_bf16 v[40:43], v[176:179], v[202:205], v[40:43]
	v_mfma_f32_16x16x32_bf16 v[32:35], v[186:189], v[202:205], v[32:35]
	v_mfma_f32_16x16x32_bf16 v[24:27], v[176:179], v[210:213], v[24:27]
	v_mfma_f32_16x16x32_bf16 v[16:19], v[186:189], v[210:213], v[16:19]
	v_mfma_f32_16x16x32_bf16 v[8:11], v[176:179], v[218:221], v[8:11]
	v_mfma_f32_16x16x32_bf16 v[0:3], v[186:189], v[218:221], v[0:3]
	v_mfma_f32_16x16x32_bf16 v[56:59], v[180:183], v[198:201], v[56:59]
	v_mfma_f32_16x16x32_bf16 v[48:51], v[190:193], v[198:201], v[48:51]
	v_mfma_f32_16x16x32_bf16 v[40:43], v[180:183], v[206:209], v[40:43]
	v_mfma_f32_16x16x32_bf16 v[32:35], v[190:193], v[206:209], v[32:35]
	v_mfma_f32_16x16x32_bf16 v[24:27], v[180:183], v[214:217], v[24:27]
	v_mfma_f32_16x16x32_bf16 v[16:19], v[190:193], v[214:217], v[16:19]
	v_mfma_f32_16x16x32_bf16 v[8:11], v[180:183], v[222:225], v[8:11]
	v_mfma_f32_16x16x32_bf16 v[0:3], v[190:193], v[222:225], v[0:3]
	s_setprio 0
	s_barrier
	s_add_i32 s75, s75, 2
	s_add_u32 s71, s71, 0x100
	s_addc_u32 s74, s74, 0
	s_add_u32 s44, s44, 0x100
	s_addc_u32 s45, s45, 0
	s_branch .LBB0_76
.LBB0_75:
	v_add_u32_e32 v153, s64, v147
	ds_read_b128 v[160:163], v153
	v_xor_b32_e32 v253, 64, v153
	ds_read_b128 v[164:167], v253
	ds_read_b128 v[168:171], v153 offset:2048
	ds_read_b128 v[172:175], v253 offset:2048
	v_add_u32_e32 v153, s65, v147
	ds_read_b128 v[176:179], v153
	v_xor_b32_e32 v253, 64, v153
	ds_read_b128 v[180:183], v253
	ds_read_b128 v[186:189], v153 offset:2048
	ds_read_b128 v[190:193], v253 offset:2048
	s_add_u32 s48, s44, 0xfffc0080
	s_addc_u32 s49, s45, -1
	s_and_b64 s[46:47], s[46:47], exec
	s_cselect_b32 s49, s27, s49
	s_cselect_b32 s48, s68, s48
	s_cselect_b32 s47, s69, s74
	s_cselect_b32 s46, s70, s71
	v_lshl_add_u64 v[154:155], s[44:45], 0, v[138:139]
	s_add_i32 m0, s55, 0xc000
	ds_read_b128 v[194:197], v150
	v_xor_b32_e32 v253, 64, v150
	ds_read_b128 v[198:201], v253
	ds_read_b128 v[202:205], v150 offset:2048
	ds_read_b128 v[206:209], v253 offset:2048
	ds_read_b128 v[210:213], v150 offset:4096
	ds_read_b128 v[214:217], v253 offset:4096
	ds_read_b128 v[218:221], v150 offset:6144
	ds_read_b128 v[222:225], v253 offset:6144
	global_load_lds_dwordx4 v[154:155], off
	v_lshl_add_u64 v[154:155], s[44:45], 0, v[136:137]
	s_add_i32 m0, s55, 0xe000
	s_nop 0
	global_load_lds_dwordx4 v[154:155], off
	s_waitcnt vmcnt(8)
	s_waitcnt lgkmcnt(0)
	s_barrier
	s_setprio 1
	s_waitcnt lgkmcnt(0)
	v_mfma_f32_16x16x32_bf16 v[124:127], v[160:163], v[194:197], v[124:127]
	v_mfma_f32_16x16x32_bf16 v[116:119], v[168:171], v[194:197], v[116:119]
	v_mfma_f32_16x16x32_bf16 v[108:111], v[160:163], v[202:205], v[108:111]
	v_mfma_f32_16x16x32_bf16 v[100:103], v[168:171], v[202:205], v[100:103]
	v_mfma_f32_16x16x32_bf16 v[92:95], v[160:163], v[210:213], v[92:95]
	v_mfma_f32_16x16x32_bf16 v[84:87], v[168:171], v[210:213], v[84:87]
	v_mfma_f32_16x16x32_bf16 v[76:79], v[160:163], v[218:221], v[76:79]
	v_mfma_f32_16x16x32_bf16 v[68:71], v[168:171], v[218:221], v[68:71]
	v_mfma_f32_16x16x32_bf16 v[124:127], v[164:167], v[198:201], v[124:127]
	v_mfma_f32_16x16x32_bf16 v[116:119], v[172:175], v[198:201], v[116:119]
	v_mfma_f32_16x16x32_bf16 v[108:111], v[164:167], v[206:209], v[108:111]
	v_mfma_f32_16x16x32_bf16 v[100:103], v[172:175], v[206:209], v[100:103]
	v_mfma_f32_16x16x32_bf16 v[92:95], v[164:167], v[214:217], v[92:95]
	v_mfma_f32_16x16x32_bf16 v[84:87], v[172:175], v[214:217], v[84:87]
	v_mfma_f32_16x16x32_bf16 v[76:79], v[164:167], v[222:225], v[76:79]
	v_mfma_f32_16x16x32_bf16 v[68:71], v[172:175], v[222:225], v[68:71]
	s_setprio 0
	s_setprio 1
	v_mfma_f32_16x16x32_bf16 v[120:123], v[176:179], v[194:197], v[120:123]
	v_mfma_f32_16x16x32_bf16 v[112:115], v[186:189], v[194:197], v[112:115]
	v_mfma_f32_16x16x32_bf16 v[104:107], v[176:179], v[202:205], v[104:107]
	v_mfma_f32_16x16x32_bf16 v[96:99], v[186:189], v[202:205], v[96:99]
	v_mfma_f32_16x16x32_bf16 v[88:91], v[176:179], v[210:213], v[88:91]
	v_mfma_f32_16x16x32_bf16 v[80:83], v[186:189], v[210:213], v[80:83]
	v_mfma_f32_16x16x32_bf16 v[72:75], v[176:179], v[218:221], v[72:75]
	v_mfma_f32_16x16x32_bf16 v[64:67], v[186:189], v[218:221], v[64:67]
	v_mfma_f32_16x16x32_bf16 v[120:123], v[180:183], v[198:201], v[120:123]
	v_mfma_f32_16x16x32_bf16 v[112:115], v[190:193], v[198:201], v[112:115]
	v_mfma_f32_16x16x32_bf16 v[104:107], v[180:183], v[206:209], v[104:107]
	v_mfma_f32_16x16x32_bf16 v[96:99], v[190:193], v[206:209], v[96:99]
	v_mfma_f32_16x16x32_bf16 v[88:91], v[180:183], v[214:217], v[88:91]
	v_mfma_f32_16x16x32_bf16 v[80:83], v[190:193], v[214:217], v[80:83]
	v_mfma_f32_16x16x32_bf16 v[72:75], v[180:183], v[222:225], v[72:75]
	v_mfma_f32_16x16x32_bf16 v[64:67], v[190:193], v[222:225], v[64:67]
	s_setprio 0
	s_barrier
	s_add_i32 s76, s64, s52
	v_lshl_add_u64 v[154:155], s[46:47], 0, v[132:133]
	s_mov_b32 m0, s76
	ds_read_b128 v[194:197], v150 offset:16384
	v_xor_b32_e32 v253, 64, v150
	ds_read_b128 v[198:201], v253 offset:16384
	ds_read_b128 v[202:205], v150 offset:18432
	ds_read_b128 v[206:209], v253 offset:18432
	ds_read_b128 v[210:213], v150 offset:20480
	ds_read_b128 v[214:217], v253 offset:20480
	ds_read_b128 v[218:221], v150 offset:22528
	ds_read_b128 v[222:225], v253 offset:22528
	global_load_lds_dwordx4 v[154:155], off
	s_add_i32 m0, s76, 0x2000
	s_add_u32 s76, s46, 0x40000
	v_lshl_add_u64 v[226:227], s[46:47], 0, v[128:129]
	s_addc_u32 s77, s47, 0
	s_add_i32 s78, s65, s52
	global_load_lds_dwordx4 v[226:227], off
	v_lshl_add_u64 v[228:229], s[76:77], 0, v[132:133]
	s_mov_b32 m0, s78
	v_lshl_add_u64 v[230:231], s[48:49], 0, v[130:131]
	global_load_lds_dwordx4 v[228:229], off
	v_lshl_add_u64 v[228:229], s[76:77], 0, v[128:129]
	s_add_i32 m0, s78, 0x2000
	s_nop 0
	global_load_lds_dwordx4 v[228:229], off
	v_lshl_add_u64 v[228:229], s[48:49], 0, v[134:135]
	s_mov_b32 m0, s55
	s_nop 0
	global_load_lds_dwordx4 v[228:229], off
	s_mov_b32 m0, s56
	s_nop 0
	global_load_lds_dwordx4 v[230:231], off
	s_waitcnt vmcnt(8)
	s_waitcnt lgkmcnt(0)
	s_barrier
	s_setprio 1
	s_waitcnt lgkmcnt(0)
	v_mfma_f32_16x16x32_bf16 v[60:63], v[160:163], v[194:197], v[60:63]
	v_mfma_f32_16x16x32_bf16 v[52:55], v[168:171], v[194:197], v[52:55]
	v_mfma_f32_16x16x32_bf16 v[44:47], v[160:163], v[202:205], v[44:47]
	v_mfma_f32_16x16x32_bf16 v[36:39], v[168:171], v[202:205], v[36:39]
	v_mfma_f32_16x16x32_bf16 v[28:31], v[160:163], v[210:213], v[28:31]
	v_mfma_f32_16x16x32_bf16 v[20:23], v[168:171], v[210:213], v[20:23]
	v_mfma_f32_16x16x32_bf16 v[12:15], v[160:163], v[218:221], v[12:15]
	v_mfma_f32_16x16x32_bf16 v[4:7], v[168:171], v[218:221], v[4:7]
	v_mfma_f32_16x16x32_bf16 v[60:63], v[164:167], v[198:201], v[60:63]
	v_mfma_f32_16x16x32_bf16 v[52:55], v[172:175], v[198:201], v[52:55]
	v_mfma_f32_16x16x32_bf16 v[44:47], v[164:167], v[206:209], v[44:47]
	v_mfma_f32_16x16x32_bf16 v[36:39], v[172:175], v[206:209], v[36:39]
	v_mfma_f32_16x16x32_bf16 v[28:31], v[164:167], v[214:217], v[28:31]
	v_mfma_f32_16x16x32_bf16 v[20:23], v[172:175], v[214:217], v[20:23]
	v_mfma_f32_16x16x32_bf16 v[12:15], v[164:167], v[222:225], v[12:15]
	v_mfma_f32_16x16x32_bf16 v[4:7], v[172:175], v[222:225], v[4:7]
	s_setprio 0
	s_setprio 1
	v_mfma_f32_16x16x32_bf16 v[56:59], v[176:179], v[194:197], v[56:59]
	v_mfma_f32_16x16x32_bf16 v[48:51], v[186:189], v[194:197], v[48:51]
	v_mfma_f32_16x16x32_bf16 v[40:43], v[176:179], v[202:205], v[40:43]
	v_mfma_f32_16x16x32_bf16 v[32:35], v[186:189], v[202:205], v[32:35]
	v_mfma_f32_16x16x32_bf16 v[24:27], v[176:179], v[210:213], v[24:27]
	v_mfma_f32_16x16x32_bf16 v[16:19], v[186:189], v[210:213], v[16:19]
	v_mfma_f32_16x16x32_bf16 v[8:11], v[176:179], v[218:221], v[8:11]
	v_mfma_f32_16x16x32_bf16 v[0:3], v[186:189], v[218:221], v[0:3]
	v_mfma_f32_16x16x32_bf16 v[56:59], v[180:183], v[198:201], v[56:59]
	v_mfma_f32_16x16x32_bf16 v[48:51], v[190:193], v[198:201], v[48:51]
	v_mfma_f32_16x16x32_bf16 v[40:43], v[180:183], v[206:209], v[40:43]
	v_mfma_f32_16x16x32_bf16 v[32:35], v[190:193], v[206:209], v[32:35]
	v_mfma_f32_16x16x32_bf16 v[24:27], v[180:183], v[214:217], v[24:27]
	v_mfma_f32_16x16x32_bf16 v[16:19], v[190:193], v[214:217], v[16:19]
	v_mfma_f32_16x16x32_bf16 v[8:11], v[180:183], v[222:225], v[8:11]
	v_mfma_f32_16x16x32_bf16 v[0:3], v[190:193], v[222:225], v[0:3]
	s_setprio 0
	s_barrier
	s_add_i32 s76, 0, 0x18000
	v_add_u32_e32 v153, s76, v147
	s_add_i32 s77, 0, 0x1c000
	ds_read_b128 v[160:163], v153
	v_xor_b32_e32 v253, 64, v153
	ds_read_b128 v[164:167], v253
	ds_read_b128 v[168:171], v153 offset:2048
	ds_read_b128 v[172:175], v253 offset:2048
	v_add_u32_e32 v153, s77, v147
	ds_read_b128 v[176:179], v153
	v_xor_b32_e32 v253, 64, v153
	ds_read_b128 v[180:183], v253
	ds_read_b128 v[186:189], v153 offset:2048
	ds_read_b128 v[190:193], v253 offset:2048
	s_add_u32 s48, s48, 0x40000
	s_addc_u32 s49, s49, 0
	s_mov_b32 m0, s57
	v_lshl_add_u64 v[232:233], s[48:49], 0, v[134:135]
	ds_read_b128 v[194:197], v150 offset:32768
	v_xor_b32_e32 v253, 64, v150
	ds_read_b128 v[198:201], v253 offset:32768
	ds_read_b128 v[202:205], v150 offset:34816
	ds_read_b128 v[206:209], v253 offset:34816
	ds_read_b128 v[210:213], v150 offset:36864
	ds_read_b128 v[214:217], v253 offset:36864
	ds_read_b128 v[218:221], v150 offset:38912
	ds_read_b128 v[222:225], v253 offset:38912
	global_load_lds_dwordx4 v[232:233], off
	v_lshl_add_u64 v[232:233], s[48:49], 0, v[130:131]
	s_mov_b32 m0, s58
	s_nop 0
	global_load_lds_dwordx4 v[232:233], off
	s_waitcnt vmcnt(8)
	s_waitcnt lgkmcnt(0)
	s_barrier
	s_setprio 1
	s_waitcnt lgkmcnt(0)
	v_mfma_f32_16x16x32_bf16 v[124:127], v[160:163], v[194:197], v[124:127]
	v_mfma_f32_16x16x32_bf16 v[116:119], v[168:171], v[194:197], v[116:119]
	v_mfma_f32_16x16x32_bf16 v[108:111], v[160:163], v[202:205], v[108:111]
	v_mfma_f32_16x16x32_bf16 v[100:103], v[168:171], v[202:205], v[100:103]
	v_mfma_f32_16x16x32_bf16 v[92:95], v[160:163], v[210:213], v[92:95]
	v_mfma_f32_16x16x32_bf16 v[84:87], v[168:171], v[210:213], v[84:87]
	v_mfma_f32_16x16x32_bf16 v[76:79], v[160:163], v[218:221], v[76:79]
	v_mfma_f32_16x16x32_bf16 v[68:71], v[168:171], v[218:221], v[68:71]
	v_mfma_f32_16x16x32_bf16 v[124:127], v[164:167], v[198:201], v[124:127]
	v_mfma_f32_16x16x32_bf16 v[116:119], v[172:175], v[198:201], v[116:119]
	v_mfma_f32_16x16x32_bf16 v[108:111], v[164:167], v[206:209], v[108:111]
	v_mfma_f32_16x16x32_bf16 v[100:103], v[172:175], v[206:209], v[100:103]
	v_mfma_f32_16x16x32_bf16 v[92:95], v[164:167], v[214:217], v[92:95]
	v_mfma_f32_16x16x32_bf16 v[84:87], v[172:175], v[214:217], v[84:87]
	v_mfma_f32_16x16x32_bf16 v[76:79], v[164:167], v[222:225], v[76:79]
	v_mfma_f32_16x16x32_bf16 v[68:71], v[172:175], v[222:225], v[68:71]
	s_setprio 0
	s_setprio 1
	v_mfma_f32_16x16x32_bf16 v[120:123], v[176:179], v[194:197], v[120:123]
	v_mfma_f32_16x16x32_bf16 v[112:115], v[186:189], v[194:197], v[112:115]
	v_mfma_f32_16x16x32_bf16 v[104:107], v[176:179], v[202:205], v[104:107]
	v_mfma_f32_16x16x32_bf16 v[96:99], v[186:189], v[202:205], v[96:99]
	v_mfma_f32_16x16x32_bf16 v[88:91], v[176:179], v[210:213], v[88:91]
	v_mfma_f32_16x16x32_bf16 v[80:83], v[186:189], v[210:213], v[80:83]
	v_mfma_f32_16x16x32_bf16 v[72:75], v[176:179], v[218:221], v[72:75]
	v_mfma_f32_16x16x32_bf16 v[64:67], v[186:189], v[218:221], v[64:67]
	v_mfma_f32_16x16x32_bf16 v[120:123], v[180:183], v[198:201], v[120:123]
	v_mfma_f32_16x16x32_bf16 v[112:115], v[190:193], v[198:201], v[112:115]
	v_mfma_f32_16x16x32_bf16 v[104:107], v[180:183], v[206:209], v[104:107]
	v_mfma_f32_16x16x32_bf16 v[96:99], v[190:193], v[206:209], v[96:99]
	v_mfma_f32_16x16x32_bf16 v[88:91], v[180:183], v[214:217], v[88:91]
	v_mfma_f32_16x16x32_bf16 v[80:83], v[190:193], v[214:217], v[80:83]
	v_mfma_f32_16x16x32_bf16 v[72:75], v[180:183], v[222:225], v[72:75]
	v_mfma_f32_16x16x32_bf16 v[64:67], v[190:193], v[222:225], v[64:67]
	s_setprio 0
	s_barrier
	s_add_i32 s48, s76, s52
	v_lshl_add_u64 v[154:155], v[154:155], 0, s[14:15]
	s_mov_b32 m0, s48
	ds_read_b128 v[194:197], v150 offset:49152
	v_xor_b32_e32 v253, 64, v150
	ds_read_b128 v[198:201], v253 offset:49152
	ds_read_b128 v[202:205], v150 offset:51200
	ds_read_b128 v[206:209], v253 offset:51200
	ds_read_b128 v[210:213], v150 offset:53248
	ds_read_b128 v[214:217], v253 offset:53248
	ds_read_b128 v[218:221], v150 offset:55296
	ds_read_b128 v[222:225], v253 offset:55296
	global_load_lds_dwordx4 v[154:155], off
	s_add_i32 m0, s48, 0x2000
	s_add_u32 s46, s46, 0x40080
	v_lshl_add_u64 v[154:155], v[226:227], 0, s[14:15]
	s_addc_u32 s47, s47, 0
	s_add_i32 s48, s77, s52
	global_load_lds_dwordx4 v[154:155], off
	v_lshl_add_u64 v[154:155], s[46:47], 0, v[132:133]
	s_mov_b32 m0, s48
	s_nop 0
	global_load_lds_dwordx4 v[154:155], off
	v_lshl_add_u64 v[154:155], s[46:47], 0, v[128:129]
	s_add_i32 m0, s48, 0x2000
	s_nop 0
	global_load_lds_dwordx4 v[154:155], off
	v_lshl_add_u64 v[154:155], v[228:229], 0, s[14:15]
	s_mov_b32 m0, s60
	s_nop 0
	global_load_lds_dwordx4 v[154:155], off
	v_lshl_add_u64 v[154:155], v[230:231], 0, s[14:15]
	s_mov_b32 m0, s61
	s_nop 0
	global_load_lds_dwordx4 v[154:155], off
	s_waitcnt vmcnt(8)
	s_waitcnt lgkmcnt(0)
	s_barrier
	s_setprio 1
	s_waitcnt lgkmcnt(0)
	v_mfma_f32_16x16x32_bf16 v[60:63], v[160:163], v[194:197], v[60:63]
	v_mfma_f32_16x16x32_bf16 v[52:55], v[168:171], v[194:197], v[52:55]
	v_mfma_f32_16x16x32_bf16 v[44:47], v[160:163], v[202:205], v[44:47]
	v_mfma_f32_16x16x32_bf16 v[36:39], v[168:171], v[202:205], v[36:39]
	v_mfma_f32_16x16x32_bf16 v[28:31], v[160:163], v[210:213], v[28:31]
	v_mfma_f32_16x16x32_bf16 v[20:23], v[168:171], v[210:213], v[20:23]
	v_mfma_f32_16x16x32_bf16 v[12:15], v[160:163], v[218:221], v[12:15]
	v_mfma_f32_16x16x32_bf16 v[4:7], v[168:171], v[218:221], v[4:7]
	v_mfma_f32_16x16x32_bf16 v[60:63], v[164:167], v[198:201], v[60:63]
	v_mfma_f32_16x16x32_bf16 v[52:55], v[172:175], v[198:201], v[52:55]
	v_mfma_f32_16x16x32_bf16 v[44:47], v[164:167], v[206:209], v[44:47]
	v_mfma_f32_16x16x32_bf16 v[36:39], v[172:175], v[206:209], v[36:39]
	v_mfma_f32_16x16x32_bf16 v[28:31], v[164:167], v[214:217], v[28:31]
	v_mfma_f32_16x16x32_bf16 v[20:23], v[172:175], v[214:217], v[20:23]
	v_mfma_f32_16x16x32_bf16 v[12:15], v[164:167], v[222:225], v[12:15]
	v_mfma_f32_16x16x32_bf16 v[4:7], v[172:175], v[222:225], v[4:7]
	s_setprio 0
	s_setprio 1
	v_mfma_f32_16x16x32_bf16 v[56:59], v[176:179], v[194:197], v[56:59]
	v_mfma_f32_16x16x32_bf16 v[48:51], v[186:189], v[194:197], v[48:51]
	v_mfma_f32_16x16x32_bf16 v[40:43], v[176:179], v[202:205], v[40:43]
	v_mfma_f32_16x16x32_bf16 v[32:35], v[186:189], v[202:205], v[32:35]
	v_mfma_f32_16x16x32_bf16 v[24:27], v[176:179], v[210:213], v[24:27]
	v_mfma_f32_16x16x32_bf16 v[16:19], v[186:189], v[210:213], v[16:19]
	v_mfma_f32_16x16x32_bf16 v[8:11], v[176:179], v[218:221], v[8:11]
	v_mfma_f32_16x16x32_bf16 v[0:3], v[186:189], v[218:221], v[0:3]
	v_mfma_f32_16x16x32_bf16 v[56:59], v[180:183], v[198:201], v[56:59]
	v_mfma_f32_16x16x32_bf16 v[48:51], v[190:193], v[198:201], v[48:51]
	v_mfma_f32_16x16x32_bf16 v[40:43], v[180:183], v[206:209], v[40:43]
	v_mfma_f32_16x16x32_bf16 v[32:35], v[190:193], v[206:209], v[32:35]
	v_mfma_f32_16x16x32_bf16 v[24:27], v[180:183], v[214:217], v[24:27]
	v_mfma_f32_16x16x32_bf16 v[16:19], v[190:193], v[214:217], v[16:19]
	v_mfma_f32_16x16x32_bf16 v[8:11], v[180:183], v[222:225], v[8:11]
	v_mfma_f32_16x16x32_bf16 v[0:3], v[190:193], v[222:225], v[0:3]
	s_setprio 0
	s_barrier
	s_add_i32 s75, s75, 2
	s_add_u32 s71, s71, 0x100
	s_addc_u32 s74, s74, 0
	s_add_u32 s44, s44, 0x100
	s_addc_u32 s45, s45, 0
	s_cmp_gt_u32 s75, 13
	s_cbranch_scc1 .LBB0_78

.Llast_0:
	v_add_u32_e32 v153, s64, v147
	ds_read_b128 v[160:163], v153
	v_xor_b32_e32 v253, 64, v153
	ds_read_b128 v[164:167], v253
	ds_read_b128 v[168:171], v153 offset:2048
	ds_read_b128 v[172:175], v253 offset:2048
	v_add_u32_e32 v153, s65, v147
	ds_read_b128 v[176:179], v153
	v_xor_b32_e32 v253, 64, v153
	ds_read_b128 v[180:183], v253
	ds_read_b128 v[186:189], v153 offset:2048
	ds_read_b128 v[190:193], v253 offset:2048
	s_add_u32 s48, s44, 0xfffc0080
	s_addc_u32 s49, s45, -1
	s_and_b64 s[46:47], s[46:47], exec
	s_cselect_b32 s49, s27, s49
	s_cselect_b32 s48, s68, s48
	s_cselect_b32 s47, s69, s74
	s_cselect_b32 s46, s70, s71
	v_lshl_add_u64 v[154:155], s[44:45], 0, v[138:139]
	s_add_i32 m0, s55, 0xc000
	ds_read_b128 v[194:197], v150
	v_xor_b32_e32 v253, 64, v150
	ds_read_b128 v[198:201], v253
	ds_read_b128 v[202:205], v150 offset:2048
	ds_read_b128 v[206:209], v253 offset:2048
	ds_read_b128 v[210:213], v150 offset:4096
	ds_read_b128 v[214:217], v253 offset:4096
	ds_read_b128 v[218:221], v150 offset:6144
	ds_read_b128 v[222:225], v253 offset:6144
	global_load_lds_dwordx4 v[154:155], off
	v_lshl_add_u64 v[154:155], s[44:45], 0, v[136:137]
	s_add_i32 m0, s55, 0xe000
	s_nop 0
	global_load_lds_dwordx4 v[154:155], off
	s_waitcnt vmcnt(8)
	s_waitcnt lgkmcnt(0)
	s_barrier
	s_setprio 1
	s_waitcnt lgkmcnt(0)
	v_mfma_f32_16x16x32_bf16 v[124:127], v[160:163], v[194:197], v[124:127]
	v_mfma_f32_16x16x32_bf16 v[116:119], v[168:171], v[194:197], v[116:119]
	v_mfma_f32_16x16x32_bf16 v[108:111], v[160:163], v[202:205], v[108:111]
	v_mfma_f32_16x16x32_bf16 v[100:103], v[168:171], v[202:205], v[100:103]
	v_mfma_f32_16x16x32_bf16 v[92:95], v[160:163], v[210:213], v[92:95]
	v_mfma_f32_16x16x32_bf16 v[84:87], v[168:171], v[210:213], v[84:87]
	v_mfma_f32_16x16x32_bf16 v[76:79], v[160:163], v[218:221], v[76:79]
	v_mfma_f32_16x16x32_bf16 v[68:71], v[168:171], v[218:221], v[68:71]
	v_mfma_f32_16x16x32_bf16 v[124:127], v[164:167], v[198:201], v[124:127]
	v_mfma_f32_16x16x32_bf16 v[116:119], v[172:175], v[198:201], v[116:119]
	v_mfma_f32_16x16x32_bf16 v[108:111], v[164:167], v[206:209], v[108:111]
	v_mfma_f32_16x16x32_bf16 v[100:103], v[172:175], v[206:209], v[100:103]
	v_mfma_f32_16x16x32_bf16 v[92:95], v[164:167], v[214:217], v[92:95]
	v_mfma_f32_16x16x32_bf16 v[84:87], v[172:175], v[214:217], v[84:87]
	v_mfma_f32_16x16x32_bf16 v[76:79], v[164:167], v[222:225], v[76:79]
	v_mfma_f32_16x16x32_bf16 v[68:71], v[172:175], v[222:225], v[68:71]
	s_setprio 0
	s_setprio 1
	v_mfma_f32_16x16x32_bf16 v[120:123], v[176:179], v[194:197], v[120:123]
	v_mfma_f32_16x16x32_bf16 v[112:115], v[186:189], v[194:197], v[112:115]
	v_mfma_f32_16x16x32_bf16 v[104:107], v[176:179], v[202:205], v[104:107]
	v_mfma_f32_16x16x32_bf16 v[96:99], v[186:189], v[202:205], v[96:99]
	v_mfma_f32_16x16x32_bf16 v[88:91], v[176:179], v[210:213], v[88:91]
	v_mfma_f32_16x16x32_bf16 v[80:83], v[186:189], v[210:213], v[80:83]
	v_mfma_f32_16x16x32_bf16 v[72:75], v[176:179], v[218:221], v[72:75]
	v_mfma_f32_16x16x32_bf16 v[64:67], v[186:189], v[218:221], v[64:67]
	v_mfma_f32_16x16x32_bf16 v[120:123], v[180:183], v[198:201], v[120:123]
	v_mfma_f32_16x16x32_bf16 v[112:115], v[190:193], v[198:201], v[112:115]
	v_mfma_f32_16x16x32_bf16 v[104:107], v[180:183], v[206:209], v[104:107]
	v_mfma_f32_16x16x32_bf16 v[96:99], v[190:193], v[206:209], v[96:99]
	v_mfma_f32_16x16x32_bf16 v[88:91], v[180:183], v[214:217], v[88:91]
	v_mfma_f32_16x16x32_bf16 v[80:83], v[190:193], v[214:217], v[80:83]
	v_mfma_f32_16x16x32_bf16 v[72:75], v[180:183], v[222:225], v[72:75]
	v_mfma_f32_16x16x32_bf16 v[64:67], v[190:193], v[222:225], v[64:67]
	s_setprio 0
	s_barrier
	s_add_i32 s76, s64, s52
	v_lshl_add_u64 v[154:155], s[46:47], 0, v[132:133]
	s_mov_b32 m0, s76
	ds_read_b128 v[194:197], v150 offset:16384
	v_xor_b32_e32 v253, 64, v150
	ds_read_b128 v[198:201], v253 offset:16384
	ds_read_b128 v[202:205], v150 offset:18432
	ds_read_b128 v[206:209], v253 offset:18432
	ds_read_b128 v[210:213], v150 offset:20480
	ds_read_b128 v[214:217], v253 offset:20480
	ds_read_b128 v[218:221], v150 offset:22528
	ds_read_b128 v[222:225], v253 offset:22528
	global_load_lds_dwordx4 v[154:155], off
	s_add_i32 m0, s76, 0x2000
	s_add_u32 s76, s46, 0x40000
	v_lshl_add_u64 v[226:227], s[46:47], 0, v[128:129]
	s_addc_u32 s77, s47, 0
	s_add_i32 s78, s65, s52
	global_load_lds_dwordx4 v[226:227], off
	v_lshl_add_u64 v[228:229], s[76:77], 0, v[132:133]
	s_mov_b32 m0, s78
	v_lshl_add_u64 v[230:231], s[48:49], 0, v[130:131]
	global_load_lds_dwordx4 v[228:229], off
	v_lshl_add_u64 v[228:229], s[76:77], 0, v[128:129]
	s_add_i32 m0, s78, 0x2000
	s_nop 0
	global_load_lds_dwordx4 v[228:229], off
	v_lshl_add_u64 v[228:229], s[48:49], 0, v[134:135]
	s_mov_b32 m0, s55
	s_nop 0
	global_load_lds_dwordx4 v[228:229], off
	s_mov_b32 m0, s56
	s_nop 0
	global_load_lds_dwordx4 v[230:231], off
	s_waitcnt vmcnt(8)
	s_waitcnt lgkmcnt(0)
	s_barrier
	s_setprio 1
	s_waitcnt lgkmcnt(0)
	v_mfma_f32_16x16x32_bf16 v[60:63], v[160:163], v[194:197], v[60:63]
	v_mfma_f32_16x16x32_bf16 v[52:55], v[168:171], v[194:197], v[52:55]
	v_mfma_f32_16x16x32_bf16 v[44:47], v[160:163], v[202:205], v[44:47]
	v_mfma_f32_16x16x32_bf16 v[36:39], v[168:171], v[202:205], v[36:39]
	v_mfma_f32_16x16x32_bf16 v[28:31], v[160:163], v[210:213], v[28:31]
	v_mfma_f32_16x16x32_bf16 v[20:23], v[168:171], v[210:213], v[20:23]
	v_mfma_f32_16x16x32_bf16 v[12:15], v[160:163], v[218:221], v[12:15]
	v_mfma_f32_16x16x32_bf16 v[4:7], v[168:171], v[218:221], v[4:7]
	v_mfma_f32_16x16x32_bf16 v[60:63], v[164:167], v[198:201], v[60:63]
	v_mfma_f32_16x16x32_bf16 v[52:55], v[172:175], v[198:201], v[52:55]
	v_mfma_f32_16x16x32_bf16 v[44:47], v[164:167], v[206:209], v[44:47]
	v_mfma_f32_16x16x32_bf16 v[36:39], v[172:175], v[206:209], v[36:39]
	v_mfma_f32_16x16x32_bf16 v[28:31], v[164:167], v[214:217], v[28:31]
	v_mfma_f32_16x16x32_bf16 v[20:23], v[172:175], v[214:217], v[20:23]
	v_mfma_f32_16x16x32_bf16 v[12:15], v[164:167], v[222:225], v[12:15]
	v_mfma_f32_16x16x32_bf16 v[4:7], v[172:175], v[222:225], v[4:7]
	s_setprio 0
	s_setprio 1
	v_mfma_f32_16x16x32_bf16 v[56:59], v[176:179], v[194:197], v[56:59]
	v_mfma_f32_16x16x32_bf16 v[48:51], v[186:189], v[194:197], v[48:51]
	v_mfma_f32_16x16x32_bf16 v[40:43], v[176:179], v[202:205], v[40:43]
	v_mfma_f32_16x16x32_bf16 v[32:35], v[186:189], v[202:205], v[32:35]
	v_mfma_f32_16x16x32_bf16 v[24:27], v[176:179], v[210:213], v[24:27]
	v_mfma_f32_16x16x32_bf16 v[16:19], v[186:189], v[210:213], v[16:19]
	v_mfma_f32_16x16x32_bf16 v[8:11], v[176:179], v[218:221], v[8:11]
	v_mfma_f32_16x16x32_bf16 v[0:3], v[186:189], v[218:221], v[0:3]
	v_mfma_f32_16x16x32_bf16 v[56:59], v[180:183], v[198:201], v[56:59]
	v_mfma_f32_16x16x32_bf16 v[48:51], v[190:193], v[198:201], v[48:51]
	v_mfma_f32_16x16x32_bf16 v[40:43], v[180:183], v[206:209], v[40:43]
	v_mfma_f32_16x16x32_bf16 v[32:35], v[190:193], v[206:209], v[32:35]
	v_mfma_f32_16x16x32_bf16 v[24:27], v[180:183], v[214:217], v[24:27]
	v_mfma_f32_16x16x32_bf16 v[16:19], v[190:193], v[214:217], v[16:19]
	v_mfma_f32_16x16x32_bf16 v[8:11], v[180:183], v[222:225], v[8:11]
	v_mfma_f32_16x16x32_bf16 v[0:3], v[190:193], v[222:225], v[0:3]
	s_setprio 0
	s_barrier
	s_add_i32 s76, 0, 0x18000
	v_add_u32_e32 v153, s76, v147
	s_add_i32 s77, 0, 0x1c000
	ds_read_b128 v[160:163], v153
	v_xor_b32_e32 v253, 64, v153
	ds_read_b128 v[164:167], v253
	ds_read_b128 v[168:171], v153 offset:2048
	ds_read_b128 v[172:175], v253 offset:2048
	v_add_u32_e32 v153, s77, v147
	ds_read_b128 v[176:179], v153
	v_xor_b32_e32 v253, 64, v153
	ds_read_b128 v[180:183], v253
	ds_read_b128 v[186:189], v153 offset:2048
	ds_read_b128 v[190:193], v253 offset:2048
	s_add_u32 s48, s48, 0x40000
	s_addc_u32 s49, s49, 0
	s_mov_b32 m0, s57
	v_lshl_add_u64 v[232:233], s[48:49], 0, v[134:135]
	ds_read_b128 v[194:197], v150 offset:32768
	v_xor_b32_e32 v253, 64, v150
	ds_read_b128 v[198:201], v253 offset:32768
	ds_read_b128 v[202:205], v150 offset:34816
	ds_read_b128 v[206:209], v253 offset:34816
	ds_read_b128 v[210:213], v150 offset:36864
	ds_read_b128 v[214:217], v253 offset:36864
	ds_read_b128 v[218:221], v150 offset:38912
	ds_read_b128 v[222:225], v253 offset:38912
	global_load_lds_dwordx4 v[232:233], off
	v_lshl_add_u64 v[232:233], s[48:49], 0, v[130:131]
	s_mov_b32 m0, s58
	s_nop 0
	global_load_lds_dwordx4 v[232:233], off
	s_waitcnt vmcnt(8)
	s_waitcnt lgkmcnt(0)
	s_barrier
	s_setprio 1
	s_waitcnt lgkmcnt(0)
	v_mfma_f32_16x16x32_bf16 v[124:127], v[160:163], v[194:197], v[124:127]
	v_mfma_f32_16x16x32_bf16 v[116:119], v[168:171], v[194:197], v[116:119]
	v_mfma_f32_16x16x32_bf16 v[108:111], v[160:163], v[202:205], v[108:111]
	v_mfma_f32_16x16x32_bf16 v[100:103], v[168:171], v[202:205], v[100:103]
	v_mfma_f32_16x16x32_bf16 v[92:95], v[160:163], v[210:213], v[92:95]
	v_mfma_f32_16x16x32_bf16 v[84:87], v[168:171], v[210:213], v[84:87]
	v_mfma_f32_16x16x32_bf16 v[76:79], v[160:163], v[218:221], v[76:79]
	v_mfma_f32_16x16x32_bf16 v[68:71], v[168:171], v[218:221], v[68:71]
	v_mfma_f32_16x16x32_bf16 v[124:127], v[164:167], v[198:201], v[124:127]
	v_mfma_f32_16x16x32_bf16 v[116:119], v[172:175], v[198:201], v[116:119]
	v_mfma_f32_16x16x32_bf16 v[108:111], v[164:167], v[206:209], v[108:111]
	v_mfma_f32_16x16x32_bf16 v[100:103], v[172:175], v[206:209], v[100:103]
	v_mfma_f32_16x16x32_bf16 v[92:95], v[164:167], v[214:217], v[92:95]
	v_mfma_f32_16x16x32_bf16 v[84:87], v[172:175], v[214:217], v[84:87]
	v_mfma_f32_16x16x32_bf16 v[76:79], v[164:167], v[222:225], v[76:79]
	v_mfma_f32_16x16x32_bf16 v[68:71], v[172:175], v[222:225], v[68:71]
	s_setprio 0
	s_setprio 1
	v_mfma_f32_16x16x32_bf16 v[120:123], v[176:179], v[194:197], v[120:123]
	v_mfma_f32_16x16x32_bf16 v[112:115], v[186:189], v[194:197], v[112:115]
	v_mfma_f32_16x16x32_bf16 v[104:107], v[176:179], v[202:205], v[104:107]
	v_mfma_f32_16x16x32_bf16 v[96:99], v[186:189], v[202:205], v[96:99]
	v_mfma_f32_16x16x32_bf16 v[88:91], v[176:179], v[210:213], v[88:91]
	v_mfma_f32_16x16x32_bf16 v[80:83], v[186:189], v[210:213], v[80:83]
	v_mfma_f32_16x16x32_bf16 v[72:75], v[176:179], v[218:221], v[72:75]
	v_mfma_f32_16x16x32_bf16 v[64:67], v[186:189], v[218:221], v[64:67]
	v_mfma_f32_16x16x32_bf16 v[120:123], v[180:183], v[198:201], v[120:123]
	v_mfma_f32_16x16x32_bf16 v[112:115], v[190:193], v[198:201], v[112:115]
	v_mfma_f32_16x16x32_bf16 v[104:107], v[180:183], v[206:209], v[104:107]
	v_mfma_f32_16x16x32_bf16 v[96:99], v[190:193], v[206:209], v[96:99]
	v_mfma_f32_16x16x32_bf16 v[88:91], v[180:183], v[214:217], v[88:91]
	v_mfma_f32_16x16x32_bf16 v[80:83], v[190:193], v[214:217], v[80:83]
	v_mfma_f32_16x16x32_bf16 v[72:75], v[180:183], v[222:225], v[72:75]
	v_mfma_f32_16x16x32_bf16 v[64:67], v[190:193], v[222:225], v[64:67]
	s_setprio 0
	s_barrier
	v_add_u32_e32 v234, 0x21000, v151
	ds_read_b128 v[236:239], v234
	ds_read_b128 v[240:243], v234 offset:256
	ds_read_b128 v[244:247], v234 offset:512
	ds_read_b128 v[248:251], v234 offset:768
	v_add_u32_e32 v235, s23, v146
	v_mul_u32_u24_e32 v235, 0x1600, v235
	v_lshl_or_b32 v234, s67, 7, v149
	v_lshl_add_u32 v235, v234, 1, v235
	s_add_i32 s48, s76, s52
	v_lshl_add_u64 v[154:155], v[154:155], 0, s[14:15]
	s_mov_b32 m0, s48
	ds_read_b128 v[194:197], v150 offset:49152
	v_xor_b32_e32 v253, 64, v150
	ds_read_b128 v[198:201], v253 offset:49152
	ds_read_b128 v[202:205], v150 offset:51200
	ds_read_b128 v[206:209], v253 offset:51200
	ds_read_b128 v[210:213], v150 offset:53248
	ds_read_b128 v[214:217], v253 offset:53248
	ds_read_b128 v[218:221], v150 offset:55296
	ds_read_b128 v[222:225], v253 offset:55296
	global_load_lds_dwordx4 v[154:155], off
	s_add_i32 m0, s48, 0x2000
	s_add_u32 s46, s46, 0x40080
	v_lshl_add_u64 v[154:155], v[226:227], 0, s[14:15]
	s_addc_u32 s47, s47, 0
	s_add_i32 s48, s77, s52
	global_load_lds_dwordx4 v[154:155], off
	v_lshl_add_u64 v[154:155], s[46:47], 0, v[132:133]
	s_mov_b32 m0, s48
	s_nop 0
	global_load_lds_dwordx4 v[154:155], off
	v_lshl_add_u64 v[154:155], s[46:47], 0, v[128:129]
	s_add_i32 m0, s48, 0x2000
	s_nop 0
	global_load_lds_dwordx4 v[154:155], off
	v_lshl_add_u64 v[154:155], v[228:229], 0, s[14:15]
	s_mov_b32 m0, s60
	s_nop 0
	global_load_lds_dwordx4 v[154:155], off
	v_lshl_add_u64 v[154:155], v[230:231], 0, s[14:15]
	s_mov_b32 m0, s61
	s_nop 0
	global_load_lds_dwordx4 v[154:155], off
	s_waitcnt lgkmcnt(8)
	v_add_f32_e32 v236, v236, v237
	v_add_f32_e32 v238, v238, v239
	v_add_f32_e32 v240, v240, v241
	v_add_f32_e32 v242, v242, v243
	v_add_f32_e32 v244, v244, v245
	v_add_f32_e32 v246, v246, v247
	v_add_f32_e32 v248, v248, v249
	v_add_f32_e32 v250, v250, v251
	v_add_f32_e32 v236, v236, v238
	v_add_f32_e32 v240, v240, v242
	v_add_f32_e32 v244, v244, v246
	v_add_f32_e32 v248, v248, v250
	v_fmamk_f32 v236, v236, 0x3a800000, v152
	v_fmamk_f32 v240, v240, 0x3a800000, v152
	v_fmamk_f32 v244, v244, 0x3a800000, v152
	v_fmamk_f32 v248, v248, 0x3a800000, v152
	v_rsq_f32_e32 v236, v236
	v_rsq_f32_e32 v240, v240
	v_rsq_f32_e32 v244, v244
	v_rsq_f32_e32 v248, v248
	v_mul_f32_e32 v252, 0xbfb8aa3b, v236
	v_mul_f32_e32 v254, v236, v236
	v_pk_mul_f32 v[120:121], v[124:125], v[120:121]
	v_pk_mul_f32 v[122:123], v[126:127], v[122:123]
	v_pk_mul_f32 v[112:113], v[116:117], v[112:113]
	v_pk_mul_f32 v[114:115], v[118:119], v[114:115]
	v_pk_mul_f32 v[124:125], v[124:125], v[252:253] op_sel_hi:[1,0]
	v_pk_mul_f32 v[126:127], v[126:127], v[252:253] op_sel_hi:[1,0]
	v_pk_mul_f32 v[116:117], v[116:117], v[252:253] op_sel_hi:[1,0]
	v_pk_mul_f32 v[118:119], v[118:119], v[252:253] op_sel_hi:[1,0]
	v_exp_f32_e32 v124, v124
	v_exp_f32_e32 v125, v125
	v_exp_f32_e32 v126, v126
	v_exp_f32_e32 v127, v127
	v_exp_f32_e32 v116, v116
	v_exp_f32_e32 v117, v117
	v_exp_f32_e32 v118, v118
	v_exp_f32_e32 v119, v119
	v_pk_add_f32 v[124:125], v[124:125], 1.0 op_sel_hi:[1,0]
	v_pk_add_f32 v[126:127], v[126:127], 1.0 op_sel_hi:[1,0]
	v_pk_add_f32 v[116:117], v[116:117], 1.0 op_sel_hi:[1,0]
	v_pk_add_f32 v[118:119], v[118:119], 1.0 op_sel_hi:[1,0]
	v_rcp_f32_e32 v124, v124
	v_rcp_f32_e32 v125, v125
	v_rcp_f32_e32 v126, v126
	v_rcp_f32_e32 v127, v127
	v_rcp_f32_e32 v116, v116
	v_rcp_f32_e32 v117, v117
	v_rcp_f32_e32 v118, v118
	v_rcp_f32_e32 v119, v119
	v_pk_mul_f32 v[120:121], v[120:121], v[254:255] op_sel_hi:[1,0]
	v_pk_mul_f32 v[122:123], v[122:123], v[254:255] op_sel_hi:[1,0]
	v_pk_mul_f32 v[112:113], v[112:113], v[254:255] op_sel_hi:[1,0]
	v_pk_mul_f32 v[114:115], v[114:115], v[254:255] op_sel_hi:[1,0]
	v_pk_mul_f32 v[120:121], v[120:121], v[124:125]
	v_pk_mul_f32 v[122:123], v[122:123], v[126:127]
	v_pk_mul_f32 v[112:113], v[112:113], v[116:117]
	v_pk_mul_f32 v[114:115], v[114:115], v[118:119]
	v_cvt_pk_bf16_f32 v120, v120, v121
	v_cvt_pk_bf16_f32 v121, v122, v123
	v_cvt_pk_bf16_f32 v122, v112, v113
	v_cvt_pk_bf16_f32 v123, v114, v115
	global_store_dwordx4 v235, v[120:123], s[10:11]
	v_add_u32_e32 v234, 0x16000, v235
	v_mul_f32_e32 v252, 0xbfb8aa3b, v240
	v_mul_f32_e32 v254, v240, v240
	v_pk_mul_f32 v[104:105], v[108:109], v[104:105]
	v_pk_mul_f32 v[106:107], v[110:111], v[106:107]
	v_pk_mul_f32 v[96:97], v[100:101], v[96:97]
	v_pk_mul_f32 v[98:99], v[102:103], v[98:99]
	v_pk_mul_f32 v[108:109], v[108:109], v[252:253] op_sel_hi:[1,0]
	v_pk_mul_f32 v[110:111], v[110:111], v[252:253] op_sel_hi:[1,0]
	v_pk_mul_f32 v[100:101], v[100:101], v[252:253] op_sel_hi:[1,0]
	v_pk_mul_f32 v[102:103], v[102:103], v[252:253] op_sel_hi:[1,0]
	v_exp_f32_e32 v108, v108
	v_exp_f32_e32 v109, v109
	v_exp_f32_e32 v110, v110
	v_exp_f32_e32 v111, v111
	v_exp_f32_e32 v100, v100
	v_exp_f32_e32 v101, v101
	v_exp_f32_e32 v102, v102
	v_exp_f32_e32 v103, v103
	v_pk_add_f32 v[108:109], v[108:109], 1.0 op_sel_hi:[1,0]
	v_pk_add_f32 v[110:111], v[110:111], 1.0 op_sel_hi:[1,0]
	v_pk_add_f32 v[100:101], v[100:101], 1.0 op_sel_hi:[1,0]
	v_pk_add_f32 v[102:103], v[102:103], 1.0 op_sel_hi:[1,0]
	v_rcp_f32_e32 v108, v108
	v_rcp_f32_e32 v109, v109
	v_rcp_f32_e32 v110, v110
	v_rcp_f32_e32 v111, v111
	v_rcp_f32_e32 v100, v100
	v_rcp_f32_e32 v101, v101
	v_rcp_f32_e32 v102, v102
	v_rcp_f32_e32 v103, v103
	v_pk_mul_f32 v[104:105], v[104:105], v[254:255] op_sel_hi:[1,0]
	v_pk_mul_f32 v[106:107], v[106:107], v[254:255] op_sel_hi:[1,0]
	v_pk_mul_f32 v[96:97], v[96:97], v[254:255] op_sel_hi:[1,0]
	v_pk_mul_f32 v[98:99], v[98:99], v[254:255] op_sel_hi:[1,0]
	v_pk_mul_f32 v[104:105], v[104:105], v[108:109]
	v_pk_mul_f32 v[106:107], v[106:107], v[110:111]
	v_pk_mul_f32 v[96:97], v[96:97], v[100:101]
	v_pk_mul_f32 v[98:99], v[98:99], v[102:103]
	v_cvt_pk_bf16_f32 v104, v104, v105
	v_cvt_pk_bf16_f32 v105, v106, v107
	v_cvt_pk_bf16_f32 v106, v96, v97
	v_cvt_pk_bf16_f32 v107, v98, v99
	global_store_dwordx4 v234, v[104:107], s[10:11]
	v_add_u32_e32 v235, 0x16000, v234
	v_mul_f32_e32 v252, 0xbfb8aa3b, v244
	v_mul_f32_e32 v254, v244, v244
	v_pk_mul_f32 v[88:89], v[92:93], v[88:89]
	v_pk_mul_f32 v[90:91], v[94:95], v[90:91]
	v_pk_mul_f32 v[80:81], v[84:85], v[80:81]
	v_pk_mul_f32 v[82:83], v[86:87], v[82:83]
	v_pk_mul_f32 v[92:93], v[92:93], v[252:253] op_sel_hi:[1,0]
	v_pk_mul_f32 v[94:95], v[94:95], v[252:253] op_sel_hi:[1,0]
	v_pk_mul_f32 v[84:85], v[84:85], v[252:253] op_sel_hi:[1,0]
	v_pk_mul_f32 v[86:87], v[86:87], v[252:253] op_sel_hi:[1,0]
	v_exp_f32_e32 v92, v92
	v_exp_f32_e32 v93, v93
	v_exp_f32_e32 v94, v94
	v_exp_f32_e32 v95, v95
	v_exp_f32_e32 v84, v84
	v_exp_f32_e32 v85, v85
	v_exp_f32_e32 v86, v86
	v_exp_f32_e32 v87, v87
	v_pk_add_f32 v[92:93], v[92:93], 1.0 op_sel_hi:[1,0]
	v_pk_add_f32 v[94:95], v[94:95], 1.0 op_sel_hi:[1,0]
	v_pk_add_f32 v[84:85], v[84:85], 1.0 op_sel_hi:[1,0]
	v_pk_add_f32 v[86:87], v[86:87], 1.0 op_sel_hi:[1,0]
	v_rcp_f32_e32 v92, v92
	v_rcp_f32_e32 v93, v93
	v_rcp_f32_e32 v94, v94
	v_rcp_f32_e32 v95, v95
	v_rcp_f32_e32 v84, v84
	v_rcp_f32_e32 v85, v85
	v_rcp_f32_e32 v86, v86
	v_rcp_f32_e32 v87, v87
	v_pk_mul_f32 v[88:89], v[88:89], v[254:255] op_sel_hi:[1,0]
	v_pk_mul_f32 v[90:91], v[90:91], v[254:255] op_sel_hi:[1,0]
	v_pk_mul_f32 v[80:81], v[80:81], v[254:255] op_sel_hi:[1,0]
	v_pk_mul_f32 v[82:83], v[82:83], v[254:255] op_sel_hi:[1,0]
	v_pk_mul_f32 v[88:89], v[88:89], v[92:93]
	v_pk_mul_f32 v[90:91], v[90:91], v[94:95]
	v_pk_mul_f32 v[80:81], v[80:81], v[84:85]
	v_pk_mul_f32 v[82:83], v[82:83], v[86:87]
	v_cvt_pk_bf16_f32 v88, v88, v89
	v_cvt_pk_bf16_f32 v89, v90, v91
	v_cvt_pk_bf16_f32 v90, v80, v81
	v_cvt_pk_bf16_f32 v91, v82, v83
	global_store_dwordx4 v235, v[88:91], s[10:11]
	v_add_u32_e32 v234, 0x16000, v235
	v_mul_f32_e32 v252, 0xbfb8aa3b, v248
	v_mul_f32_e32 v254, v248, v248
	v_pk_mul_f32 v[72:73], v[76:77], v[72:73]
	v_pk_mul_f32 v[74:75], v[78:79], v[74:75]
	v_pk_mul_f32 v[64:65], v[68:69], v[64:65]
	v_pk_mul_f32 v[66:67], v[70:71], v[66:67]
	v_pk_mul_f32 v[76:77], v[76:77], v[252:253] op_sel_hi:[1,0]
	v_pk_mul_f32 v[78:79], v[78:79], v[252:253] op_sel_hi:[1,0]
	v_pk_mul_f32 v[68:69], v[68:69], v[252:253] op_sel_hi:[1,0]
	v_pk_mul_f32 v[70:71], v[70:71], v[252:253] op_sel_hi:[1,0]
	v_exp_f32_e32 v76, v76
	v_exp_f32_e32 v77, v77
	v_exp_f32_e32 v78, v78
	v_exp_f32_e32 v79, v79
	v_exp_f32_e32 v68, v68
	v_exp_f32_e32 v69, v69
	v_exp_f32_e32 v70, v70
	v_exp_f32_e32 v71, v71
	v_pk_add_f32 v[76:77], v[76:77], 1.0 op_sel_hi:[1,0]
	v_pk_add_f32 v[78:79], v[78:79], 1.0 op_sel_hi:[1,0]
	v_pk_add_f32 v[68:69], v[68:69], 1.0 op_sel_hi:[1,0]
	v_pk_add_f32 v[70:71], v[70:71], 1.0 op_sel_hi:[1,0]
	v_rcp_f32_e32 v76, v76
	v_rcp_f32_e32 v77, v77
	v_rcp_f32_e32 v78, v78
	v_rcp_f32_e32 v79, v79
	v_rcp_f32_e32 v68, v68
	v_rcp_f32_e32 v69, v69
	v_rcp_f32_e32 v70, v70
	v_rcp_f32_e32 v71, v71
	v_pk_mul_f32 v[72:73], v[72:73], v[254:255] op_sel_hi:[1,0]
	v_pk_mul_f32 v[74:75], v[74:75], v[254:255] op_sel_hi:[1,0]
	v_pk_mul_f32 v[64:65], v[64:65], v[254:255] op_sel_hi:[1,0]
	v_pk_mul_f32 v[66:67], v[66:67], v[254:255] op_sel_hi:[1,0]
	v_pk_mul_f32 v[72:73], v[72:73], v[76:77]
	v_pk_mul_f32 v[74:75], v[74:75], v[78:79]
	v_pk_mul_f32 v[64:65], v[64:65], v[68:69]
	v_pk_mul_f32 v[66:67], v[66:67], v[70:71]
	v_cvt_pk_bf16_f32 v72, v72, v73
	v_cvt_pk_bf16_f32 v73, v74, v75
	v_cvt_pk_bf16_f32 v74, v64, v65
	v_cvt_pk_bf16_f32 v75, v66, v67
	global_store_dwordx4 v234, v[72:75], s[10:11]
	s_waitcnt vmcnt(12)
	s_waitcnt lgkmcnt(0)
	s_barrier
	s_setprio 1
	s_waitcnt lgkmcnt(0)
	v_mfma_f32_16x16x32_bf16 v[60:63], v[160:163], v[194:197], v[60:63]
	v_mfma_f32_16x16x32_bf16 v[52:55], v[168:171], v[194:197], v[52:55]
	v_mfma_f32_16x16x32_bf16 v[44:47], v[160:163], v[202:205], v[44:47]
	v_mfma_f32_16x16x32_bf16 v[36:39], v[168:171], v[202:205], v[36:39]
	v_mfma_f32_16x16x32_bf16 v[28:31], v[160:163], v[210:213], v[28:31]
	v_mfma_f32_16x16x32_bf16 v[20:23], v[168:171], v[210:213], v[20:23]
	v_mfma_f32_16x16x32_bf16 v[12:15], v[160:163], v[218:221], v[12:15]
	v_mfma_f32_16x16x32_bf16 v[4:7], v[168:171], v[218:221], v[4:7]
	v_mfma_f32_16x16x32_bf16 v[60:63], v[164:167], v[198:201], v[60:63]
	v_mfma_f32_16x16x32_bf16 v[52:55], v[172:175], v[198:201], v[52:55]
	v_mfma_f32_16x16x32_bf16 v[44:47], v[164:167], v[206:209], v[44:47]
	v_mfma_f32_16x16x32_bf16 v[36:39], v[172:175], v[206:209], v[36:39]
	v_mfma_f32_16x16x32_bf16 v[28:31], v[164:167], v[214:217], v[28:31]
	v_mfma_f32_16x16x32_bf16 v[20:23], v[172:175], v[214:217], v[20:23]
	v_mfma_f32_16x16x32_bf16 v[12:15], v[164:167], v[222:225], v[12:15]
	v_mfma_f32_16x16x32_bf16 v[4:7], v[172:175], v[222:225], v[4:7]
	s_setprio 0
	s_setprio 1
	v_mfma_f32_16x16x32_bf16 v[56:59], v[176:179], v[194:197], v[56:59]
	v_mfma_f32_16x16x32_bf16 v[48:51], v[186:189], v[194:197], v[48:51]
	v_mfma_f32_16x16x32_bf16 v[40:43], v[176:179], v[202:205], v[40:43]
	v_mfma_f32_16x16x32_bf16 v[32:35], v[186:189], v[202:205], v[32:35]
	v_mfma_f32_16x16x32_bf16 v[24:27], v[176:179], v[210:213], v[24:27]
	v_mfma_f32_16x16x32_bf16 v[16:19], v[186:189], v[210:213], v[16:19]
	v_mfma_f32_16x16x32_bf16 v[8:11], v[176:179], v[218:221], v[8:11]
	v_mfma_f32_16x16x32_bf16 v[0:3], v[186:189], v[218:221], v[0:3]
	v_mfma_f32_16x16x32_bf16 v[56:59], v[180:183], v[198:201], v[56:59]
	v_mfma_f32_16x16x32_bf16 v[48:51], v[190:193], v[198:201], v[48:51]
	v_mfma_f32_16x16x32_bf16 v[40:43], v[180:183], v[206:209], v[40:43]
	v_mfma_f32_16x16x32_bf16 v[32:35], v[190:193], v[206:209], v[32:35]
	v_mfma_f32_16x16x32_bf16 v[24:27], v[180:183], v[214:217], v[24:27]
	v_mfma_f32_16x16x32_bf16 v[16:19], v[190:193], v[214:217], v[16:19]
	v_mfma_f32_16x16x32_bf16 v[8:11], v[180:183], v[222:225], v[8:11]
	v_mfma_f32_16x16x32_bf16 v[0:3], v[190:193], v[222:225], v[0:3]
	s_setprio 0
	s_barrier
	s_add_i32 s75, s75, 2
	s_add_u32 s71, s71, 0x100
	s_addc_u32 s74, s74, 0
	s_add_u32 s44, s44, 0x100
	s_addc_u32 s45, s45, 0

.LBB0_142:
	v_cndmask_b32_e64 v0, 0, 1, s[10:11]
	v_cmp_ne_u32_e64 s[4:5], 1, v0
	s_andn2_b64 vcc, exec, s[10:11]
	s_cbranch_vccnz .LBB0_184
	v_ashrrev_i32_e32 v1, 31, v8
	v_lshrrev_b32_e32 v1, 26, v1
	v_add_u32_e32 v1, v8, v1
	v_ashrrev_i32_e32 v9, 6, v1
	v_bfe_i32 v1, v8, 27, 1
	v_lshlrev_b32_e32 v0, 4, v8
	v_lshrrev_b32_e32 v1, 22, v1
	v_add_u32_e32 v1, v0, v1
	v_and_b32_e32 v1, 0xfffffc00, v1
	v_sub_u32_e32 v1, v0, v1
	v_lshrrev_b32_e32 v2, 4, v1
	v_bitop3_b32 v1, v2, v1, 32 bitop3:0x6c
	v_ashrrev_i32_e32 v3, 31, v1
	v_lshrrev_b32_e32 v3, 26, v3
	v_lshlrev_b32_e32 v2, 3, v9
	v_add_u32_e32 v3, v1, v3
	v_and_b32_e32 v2, -16, v2
	v_ashrrev_i32_e32 v10, 6, v3
	v_and_b32_e32 v3, 0xc0, v3
	v_add_u32_e32 v2, v10, v2
	v_lshlrev_b32_e32 v4, 5, v9
	v_sub_u32_e32 v1, v1, v3
	v_mov_b32_e32 v3, 1
	v_and_b32_e32 v11, 32, v4
	v_ashrrev_i16_sdwa v1, v3, sext(v1) dst_sel:DWORD dst_unused:UNUSED_PAD src0_sel:DWORD src1_sel:BYTE_0
	v_lshlrev_b32_e32 v4, 1, v2
	v_lshrrev_b32_e32 v5, 2, v2
	v_and_b32_e32 v6, 3, v10
	s_mov_b32 s10, 0xffffe0
	v_bfe_i32 v12, v1, 0, 16
	v_and_b32_e32 v4, 24, v4
	v_and_b32_e32 v5, 4, v5
	v_and_or_b32 v6, v2, s10, v6
	s_movk_i32 s13, 0xb00
	v_add_u32_e32 v1, v11, v12
	v_or3_b32 v4, v6, v5, v4
	v_mul_lo_u32 v2, v2, s13
	v_add_lshl_u32 v152, v1, v2, 1
	v_lshrrev_b32_e32 v250, 3, v157
	v_and_b32_e32 v251, 6, v250
	v_and_b32_e32 v252, 7, v157
	v_xor_b32_e32 v251, v251, v252
	v_lshlrev_b32_e32 v251, 4, v251
	v_mul_u32_u24_e32 v250, 0x1600, v250
	v_add_u32_e32 v152, v250, v251
	v_mul_u32_u24_e32 v2, 0xb00, v4
	v_add_u32_e32 v0, 0x2000, v0
	v_add_lshl_u32 v154, v2, v1, 1
	v_lshrrev_b32_e32 v250, 3, v157
	v_and_b32_e32 v251, 6, v250
	v_and_b32_e32 v252, 7, v157
	v_xor_b32_e32 v251, v251, v252
	v_lshlrev_b32_e32 v251, 4, v251
	v_and_b32_e32 v252, 12, v250
	v_lshlrev_b32_e32 v252, 1, v252
	v_and_b32_e32 v253, 16, v250
	v_lshrrev_b32_e32 v253, 2, v253
	v_or_b32_e32 v252, v252, v253
	v_and_b32_e32 v253, 35, v250
	v_or_b32_e32 v250, v252, v253
	v_mul_u32_u24_e32 v250, 0x1600, v250
	v_add_u32_e32 v154, v250, v251
	v_ashrrev_i32_e32 v1, 31, v0
	v_lshrrev_b32_e32 v1, 22, v1
	v_add_u32_e32 v1, v0, v1
	v_ashrrev_i32_e32 v13, 10, v1
	v_mul_i32_i24_e32 v1, 0x400, v13
	v_sub_u32_e32 v0, v0, v1
	v_lshrrev_b32_e32 v1, 4, v0
	v_bitop3_b32 v0, v1, v0, 32 bitop3:0x6c
	v_ashrrev_i32_e32 v2, 31, v0
	s_waitcnt lgkmcnt(0)
	s_add_u32 s35, s8, 0xa000000
	v_lshrrev_b32_e32 v2, 26, v2
	s_addc_u32 s62, s9, 0
	v_lshlrev_b32_e32 v1, 3, v13
	v_add_u32_e32 v2, v0, v2
	s_add_u32 s63, s8, 0x3000000
	v_and_b32_e32 v1, -16, v1
	v_ashrrev_i32_e32 v15, 6, v2
	v_lshlrev_b32_e32 v4, 5, v13
	s_addc_u32 s64, s9, 0
	s_ashr_i32 s3, s12, 6
	v_add_u32_e32 v1, v15, v1
	v_and_b32_e32 v14, 32, v4
	v_and_b32_e32 v2, 0xc0, v2
	v_and_b32_e32 v4, 3, v15
	v_sub_u32_e32 v0, v0, v2
	v_and_or_b32 v4, v1, s10, v4
	s_ashr_i32 s10, s12, 8
	s_lshl_b32 s65, s3, 10
	s_mul_i32 s15, s16, 0x160000
	v_ashrrev_i16_sdwa v0, v3, sext(v0) dst_sel:DWORD dst_unused:UNUSED_PAD src0_sel:DWORD src1_sel:BYTE_0
	v_lshlrev_b32_e32 v2, 1, v1
	v_lshrrev_b32_e32 v3, 2, v1
	s_mul_hi_i32 s14, s16, 0x160000
	s_add_u32 s56, s63, s15
	v_bfe_i32 v16, v0, 0, 16
	v_and_b32_e32 v2, 24, v2
	v_and_b32_e32 v3, 4, v3
	s_addc_u32 s57, s64, s14
	s_add_i32 s66, s65, 0
	v_add_u32_e32 v0, v14, v16
	v_or3_b32 v2, v4, v3, v2
	v_mul_lo_u32 v1, v1, s13
	s_add_i32 m0, s66, 0x10000
	v_add_lshl_u32 v160, v0, v1, 1
	v_lshrrev_b32_e32 v250, 3, v157
	v_and_b32_e32 v251, 6, v250
	v_and_b32_e32 v252, 7, v157
	v_xor_b32_e32 v251, v251, v252
	v_lshlrev_b32_e32 v251, 4, v251
	v_mul_u32_u24_e32 v250, 0x1600, v250
	v_add_u32_e32 v160, v250, v251
	v_add_u32_e32 v160, 0x58000, v160
	v_mul_u32_u24_e32 v1, 0xb00, v2
	global_load_lds_dwordx4 v154, s[56:57]
	s_add_i32 m0, s66, 0x12000
	v_add_lshl_u32 v162, v1, v0, 1
	v_lshrrev_b32_e32 v250, 3, v157
	v_and_b32_e32 v251, 6, v250
	v_and_b32_e32 v252, 7, v157
	v_xor_b32_e32 v251, v251, v252
	v_lshlrev_b32_e32 v251, 4, v251
	v_and_b32_e32 v252, 12, v250
	v_lshlrev_b32_e32 v252, 1, v252
	v_and_b32_e32 v253, 16, v250
	v_lshrrev_b32_e32 v253, 2, v253
	v_or_b32_e32 v252, v252, v253
	v_and_b32_e32 v253, 35, v250
	v_or_b32_e32 v250, v252, v253
	v_mul_u32_u24_e32 v250, 0x1600, v250
	v_add_u32_e32 v162, v250, v251
	v_add_u32_e32 v162, 0x58000, v162
	s_add_u32 s14, s56, 0xb0000
	global_load_lds_dwordx4 v162, s[56:57]
	s_addc_u32 s15, s57, 0
	s_add_i32 m0, s66, 0x14000
	s_mul_i32 s20, s17, 0x160000
	global_load_lds_dwordx4 v154, s[14:15]
	s_add_i32 m0, s66, 0x16000
	s_mul_hi_i32 s11, s17, 0x160000
	s_add_u32 s54, s35, s20
	s_addc_u32 s55, s62, s11
	s_add_i32 s67, s66, 0x2000
	global_load_lds_dwordx4 v162, s[14:15]
	s_mov_b32 m0, s66
	s_add_u32 s14, s54, 0xb0000
	global_load_lds_dwordx4 v152, s[54:55]
	s_mov_b32 m0, s67
	s_addc_u32 s15, s55, 0
	s_add_i32 s68, s66, 0x4000
	global_load_lds_dwordx4 v160, s[54:55]
	s_mov_b32 m0, s68
	s_add_i32 s69, s66, 0x6000
	global_load_lds_dwordx4 v152, s[14:15]
	s_mov_b32 m0, s69
	v_mov_b32_e32 v155, 0
	global_load_lds_dwordx4 v160, s[14:15]
	v_mov_b32_e32 v163, v155
	v_mov_b32_e32 v153, v155
	v_mov_b32_e32 v161, v155
	s_cmp_eq_u32 s10, 1
	s_mov_b32 s70, 0
	v_lshl_add_u64 v[6:7], s[56:57], 0, v[154:155]
	v_lshl_add_u64 v[4:5], s[56:57], 0, v[162:163]
	v_lshl_add_u64 v[0:1], s[54:55], 0, v[152:153]
	s_cselect_b64 s[20:21], -1, 0
	s_cmp_lg_u32 s10, 1
	v_lshl_add_u64 v[2:3], s[54:55], 0, v[160:161]
	s_cbranch_scc1 .LBB0_145
	s_barrier
.LBB0_145:
	s_add_u32 s22, s8, 0x6000000
	s_addc_u32 s23, s9, 0
	s_add_u32 s26, s8, 0x100000
	s_mov_b64 s[28:29], 0x80
	s_addc_u32 s27, s9, 0
	s_and_b32 s44, s3, 3
	s_add_i32 m0, s66, 0x18000
	v_lshl_add_u64 v[6:7], v[6:7], 0, s[28:29]
	s_lshl_b32 s11, s10, 13
	s_lshl_b32 s14, s44, 12
	s_waitcnt vmcnt(2)
	s_barrier
	global_load_lds_dwordx4 v[6:7], off
	v_lshl_add_u64 v[4:5], v[4:5], 0, s[28:29]
	s_add_i32 m0, s66, 0x1a000
	s_add_i32 s3, s66, 0x8000
	s_add_i32 s71, s66, 0xa000
	global_load_lds_dwordx4 v[4:5], off
	v_lshl_add_u64 v[0:1], v[0:1], 0, s[28:29]
	s_mov_b32 m0, s3
	s_add_u32 s8, s56, 0xb0080
	global_load_lds_dwordx4 v[0:1], off
	v_lshl_add_u64 v[0:1], v[2:3], 0, s[28:29]
	s_mov_b32 m0, s71
	s_addc_u32 s9, s57, 0
	global_load_lds_dwordx4 v[0:1], off
	s_add_i32 m0, s66, 0x1c000
	v_lshl_add_u64 v[0:1], s[8:9], 0, v[154:155]
	global_load_lds_dwordx4 v[0:1], off
	v_lshl_add_u64 v[0:1], s[8:9], 0, v[162:163]
	s_add_i32 m0, s66, 0x1e000
	s_cmpk_lt_u32 s12, 0x100
	global_load_lds_dwordx4 v[0:1], off
	v_bfe_u32 v0, v8, 4, 2
	v_and_b32_e32 v1, 15, v8
	v_lshlrev_b32_e32 v3, 4, v0
	s_cselect_b64 s[30:31], -1, 0
	s_lshl_b32 s12, s44, 2
	v_lshl_or_b32 v185, s10, 6, v1
	v_lshl_or_b32 v1, v1, 6, v3
	v_lshlrev_b32_e32 v3, 2, v8
	s_add_i32 s12, s12, 0
	v_and_b32_e32 v3, 32, v3
	s_add_i32 s12, s12, 0x20000
	v_lshlrev_b32_e32 v2, 3, v0
	v_bitop3_b32 v4, v1, s11, v3 bitop3:0xde
	v_bitop3_b32 v186, v1, s14, v3 bitop3:0xde
	v_and_b32_e32 v250, 15, v157
	v_bfe_u32 v251, v157, 4, 2
	v_and_b32_e32 v252, 2, v250
	v_xor_b32_e32 v251, v251, v252
	v_and_b32_e32 v252, 4, v250
	v_lshlrev_b32_e32 v252, 4, v252
	v_lshl_or_b32 v251, v251, 4, v252
	v_lshl_or_b32 v250, v250, 7, v251
	v_bfe_u32 v253, v157, 6, 2
	v_lshl_or_b32 v186, v253, 12, v250
	v_cmp_eq_u32_e64 s[8:9], 0, v0
	v_lshl_add_u32 v188, v185, 4, s12
	v_lshrrev_b32_e32 v1, 1, v13
	v_mul_lo_u32 v0, v15, s13
	s_mov_b32 s12, 0xb000
	v_lshl_or_b32 v187, s44, 5, v2
	v_mad_u64_u32 v[0:1], s[44:45], v1, s12, v[0:1]
	v_or_b32_e32 v0, v0, v14
	s_mov_b64 s[14:15], 0xb0080
	v_add_lshl_u32 v0, v0, v16, 1
	v_mov_b32_e32 v1, v155
	v_lshrrev_b32_e32 v250, 3, v157
	v_and_b32_e32 v251, 6, v250
	v_and_b32_e32 v252, 7, v157
	v_xor_b32_e32 v251, v251, v252
	v_lshlrev_b32_e32 v251, 4, v251
	v_mul_u32_u24_e32 v250, 0x1600, v250
	v_add_u32_e32 v0, v250, v251
	v_add_u32_e32 v0, 0x58000, v0
	v_lshl_add_u64 v[164:165], v[0:1], 0, s[14:15]
	v_lshrrev_b32_e32 v1, 1, v9
	v_mul_lo_u32 v0, v10, s13
	v_mad_u64_u32 v[0:1], s[12:13], v1, s12, v[0:1]
	v_or_b32_e32 v0, v0, v11
	s_waitcnt vmcnt(6)
	v_lshlrev_b32_e32 v2, 4, v157
	v_add_lshl_u32 v0, v0, v12, 1
	v_mov_b32_e32 v1, v155
	s_movk_i32 s10, 0x100
	v_lshrrev_b32_e32 v250, 3, v157
	v_and_b32_e32 v251, 6, v250
	v_and_b32_e32 v252, 7, v157
	v_xor_b32_e32 v251, v251, v252
	v_lshlrev_b32_e32 v251, 4, v251
	v_mul_u32_u24_e32 v250, 0x1600, v250
	v_add_u32_e32 v0, v250, v251
	v_lshl_add_u64 v[166:167], v[0:1], 0, s[14:15]
	s_add_i32 s77, 0, 0x10000
	s_add_i32 s78, 0, 0x14000
	v_add_u32_e32 v0, 0, v2
	v_cmp_gt_u32_e64 s[10:11], s10, v157
	s_ashr_i32 s74, s42, 31
	s_mov_b32 s75, s42
	s_ashr_i32 s76, s2, 31
	v_mov_b64_e32 v[168:169], 0x200
	v_mov_b64_e32 v[170:171], 0x1ff
	v_add_u32_e32 v189, s77, v186
	v_add_u32_e32 v190, s78, v186
	v_add_u32_e32 v191, 0, v4
	v_and_b32_e32 v250, 15, v157
	v_bfe_u32 v251, v157, 4, 2
	v_and_b32_e32 v252, 2, v250
	v_xor_b32_e32 v251, v251, v252
	v_and_b32_e32 v252, 4, v250
	v_lshlrev_b32_e32 v252, 4, v252
	v_lshl_or_b32 v251, v251, 4, v252
	v_lshl_or_b32 v250, v250, 7, v251
	v_lshrrev_b32_e32 v253, 8, v157
	v_lshl_or_b32 v191, v253, 13, v250
	s_mov_b64 s[44:45], 0x40000
	s_mov_b64 s[46:47], 0x48000
	s_mov_b64 s[48:49], 0x50000
	s_mov_b64 s[50:51], 0x58000
	v_add_u32_e32 v192, 0x20000, v0
	s_barrier
	s_branch .LBB0_148

.LBB0_158:
	s_add_u32 s81, s56, 0x100
	s_addc_u32 s82, s57, 0
	s_mov_b32 s83, -2
	s_waitcnt lgkmcnt(0)
	s_cmp_eq_u32 s70, 1
	s_cbranch_scc1 .Lfa_1
	ds_read_b128 v[128:131], v189
	v_xor_b32_e32 v253, 64, v189
	ds_read_b128 v[132:135], v253
	ds_read_b128 v[136:139], v189 offset:2048
	ds_read_b128 v[140:143], v253 offset:2048
	ds_read_b128 v[144:147], v190
	v_xor_b32_e32 v253, 64, v190
	ds_read_b128 v[148:151], v253
	ds_read_b128 v[172:175], v190 offset:2048
	ds_read_b128 v[176:179], v253 offset:2048
	s_add_u32 s56, s54, 0x100
	s_addc_u32 s57, s55, 0
	s_cmp_eq_u32 s83, 40
	s_cselect_b32 s61, s15, s57
	s_cselect_b32 s60, s14, s56
	s_cselect_b32 s59, s53, s82
	s_cselect_b32 s58, s52, s81
	v_lshl_add_u64 v[222:223], s[54:55], 0, v[166:167]
	s_add_i32 m0, s66, 0xc000
	ds_read_b128 v[180:183], v191
	v_xor_b32_e32 v253, 64, v191
	ds_read_b128 v[194:197], v253
	ds_read_b128 v[198:201], v191 offset:2048
	ds_read_b128 v[202:205], v253 offset:2048
	ds_read_b128 v[206:209], v191 offset:4096
	ds_read_b128 v[210:213], v253 offset:4096
	ds_read_b128 v[214:217], v191 offset:6144
	ds_read_b128 v[218:221], v253 offset:6144
	global_load_lds_dwordx4 v[222:223], off
	v_lshl_add_u64 v[222:223], s[54:55], 0, v[164:165]
	s_add_i32 m0, s66, 0xe000
	s_nop 0
	global_load_lds_dwordx4 v[222:223], off
	s_waitcnt vmcnt(24)
	s_waitcnt lgkmcnt(0)
	s_barrier
	s_setprio 1
	s_waitcnt lgkmcnt(0)
	v_mfma_f32_16x16x32_bf16 v[124:127], v[128:131], v[180:183], 0
	v_mfma_f32_16x16x32_bf16 v[120:123], v[136:139], v[180:183], 0
	v_mfma_f32_16x16x32_bf16 v[108:111], v[128:131], v[198:201], 0
	v_mfma_f32_16x16x32_bf16 v[104:107], v[136:139], v[198:201], 0
	v_mfma_f32_16x16x32_bf16 v[92:95], v[128:131], v[206:209], 0
	v_mfma_f32_16x16x32_bf16 v[88:91], v[136:139], v[206:209], 0
	v_mfma_f32_16x16x32_bf16 v[76:79], v[128:131], v[214:217], 0
	v_mfma_f32_16x16x32_bf16 v[72:75], v[136:139], v[214:217], 0
	v_mfma_f32_16x16x32_bf16 v[124:127], v[132:135], v[194:197], v[124:127]
	v_mfma_f32_16x16x32_bf16 v[120:123], v[140:143], v[194:197], v[120:123]
	v_mfma_f32_16x16x32_bf16 v[108:111], v[132:135], v[202:205], v[108:111]
	v_mfma_f32_16x16x32_bf16 v[104:107], v[140:143], v[202:205], v[104:107]
	v_mfma_f32_16x16x32_bf16 v[92:95], v[132:135], v[210:213], v[92:95]
	v_mfma_f32_16x16x32_bf16 v[88:91], v[140:143], v[210:213], v[88:91]
	v_mfma_f32_16x16x32_bf16 v[76:79], v[132:135], v[218:221], v[76:79]
	v_mfma_f32_16x16x32_bf16 v[72:75], v[140:143], v[218:221], v[72:75]
	s_setprio 0
	s_setprio 1
	v_mfma_f32_16x16x32_bf16 v[116:119], v[144:147], v[180:183], 0
	v_mfma_f32_16x16x32_bf16 v[112:115], v[172:175], v[180:183], 0
	v_mfma_f32_16x16x32_bf16 v[100:103], v[144:147], v[198:201], 0
	v_mfma_f32_16x16x32_bf16 v[96:99], v[172:175], v[198:201], 0
	v_mfma_f32_16x16x32_bf16 v[84:87], v[144:147], v[206:209], 0
	v_mfma_f32_16x16x32_bf16 v[80:83], v[172:175], v[206:209], 0
	v_mfma_f32_16x16x32_bf16 v[68:71], v[144:147], v[214:217], 0
	v_mfma_f32_16x16x32_bf16 v[64:67], v[172:175], v[214:217], 0
	v_mfma_f32_16x16x32_bf16 v[116:119], v[148:151], v[194:197], v[116:119]
	v_mfma_f32_16x16x32_bf16 v[112:115], v[176:179], v[194:197], v[112:115]
	v_mfma_f32_16x16x32_bf16 v[100:103], v[148:151], v[202:205], v[100:103]
	v_mfma_f32_16x16x32_bf16 v[96:99], v[176:179], v[202:205], v[96:99]
	v_mfma_f32_16x16x32_bf16 v[84:87], v[148:151], v[210:213], v[84:87]
	v_mfma_f32_16x16x32_bf16 v[80:83], v[176:179], v[210:213], v[80:83]
	v_mfma_f32_16x16x32_bf16 v[68:71], v[148:151], v[218:221], v[68:71]
	v_mfma_f32_16x16x32_bf16 v[64:67], v[176:179], v[218:221], v[64:67]
	s_setprio 0
	s_barrier
	s_add_i32 s54, s77, s65
	v_lshl_add_u64 v[222:223], s[58:59], 0, v[154:155]
	s_mov_b32 m0, s54
	ds_read_b128 v[180:183], v191 offset:16384
	v_xor_b32_e32 v253, 64, v191
	ds_read_b128 v[194:197], v253 offset:16384
	ds_read_b128 v[198:201], v191 offset:18432
	ds_read_b128 v[202:205], v253 offset:18432
	ds_read_b128 v[206:209], v191 offset:20480
	ds_read_b128 v[210:213], v253 offset:20480
	ds_read_b128 v[214:217], v191 offset:22528
	ds_read_b128 v[218:221], v253 offset:22528
	global_load_lds_dwordx4 v[222:223], off
	s_add_i32 m0, s54, 0x2000
	s_add_u32 s54, s58, 0xb0000
	v_lshl_add_u64 v[224:225], s[58:59], 0, v[162:163]
	s_addc_u32 s55, s59, 0
	s_add_i32 s84, s78, s65
	global_load_lds_dwordx4 v[224:225], off
	v_lshl_add_u64 v[226:227], s[54:55], 0, v[154:155]
	s_mov_b32 m0, s84
	v_lshl_add_u64 v[228:229], s[60:61], 0, v[160:161]
	global_load_lds_dwordx4 v[226:227], off
	v_lshl_add_u64 v[226:227], s[54:55], 0, v[162:163]
	s_add_i32 m0, s84, 0x2000
	s_nop 0
	global_load_lds_dwordx4 v[226:227], off
	v_lshl_add_u64 v[226:227], s[60:61], 0, v[152:153]
	s_mov_b32 m0, s66
	s_nop 0
	global_load_lds_dwordx4 v[226:227], off
	s_mov_b32 m0, s67
	s_nop 0
	global_load_lds_dwordx4 v[228:229], off
	s_waitcnt vmcnt(24)
	s_waitcnt lgkmcnt(0)
	s_barrier
	s_setprio 1
	s_waitcnt lgkmcnt(0)
	v_mfma_f32_16x16x32_bf16 v[60:63], v[128:131], v[180:183], 0
	v_mfma_f32_16x16x32_bf16 v[56:59], v[136:139], v[180:183], 0
	v_mfma_f32_16x16x32_bf16 v[44:47], v[128:131], v[198:201], 0
	v_mfma_f32_16x16x32_bf16 v[40:43], v[136:139], v[198:201], 0
	v_mfma_f32_16x16x32_bf16 v[28:31], v[128:131], v[206:209], 0
	v_mfma_f32_16x16x32_bf16 v[24:27], v[136:139], v[206:209], 0
	v_mfma_f32_16x16x32_bf16 v[12:15], v[128:131], v[214:217], 0
	v_mfma_f32_16x16x32_bf16 v[8:11], v[136:139], v[214:217], 0
	v_mfma_f32_16x16x32_bf16 v[60:63], v[132:135], v[194:197], v[60:63]
	v_mfma_f32_16x16x32_bf16 v[56:59], v[140:143], v[194:197], v[56:59]
	v_mfma_f32_16x16x32_bf16 v[44:47], v[132:135], v[202:205], v[44:47]
	v_mfma_f32_16x16x32_bf16 v[40:43], v[140:143], v[202:205], v[40:43]
	v_mfma_f32_16x16x32_bf16 v[28:31], v[132:135], v[210:213], v[28:31]
	v_mfma_f32_16x16x32_bf16 v[24:27], v[140:143], v[210:213], v[24:27]
	v_mfma_f32_16x16x32_bf16 v[12:15], v[132:135], v[218:221], v[12:15]
	v_mfma_f32_16x16x32_bf16 v[8:11], v[140:143], v[218:221], v[8:11]
	s_setprio 0
	s_setprio 1
	v_mfma_f32_16x16x32_bf16 v[52:55], v[144:147], v[180:183], 0
	v_mfma_f32_16x16x32_bf16 v[48:51], v[172:175], v[180:183], 0
	v_mfma_f32_16x16x32_bf16 v[36:39], v[144:147], v[198:201], 0
	v_mfma_f32_16x16x32_bf16 v[32:35], v[172:175], v[198:201], 0
	v_mfma_f32_16x16x32_bf16 v[20:23], v[144:147], v[206:209], 0
	v_mfma_f32_16x16x32_bf16 v[16:19], v[172:175], v[206:209], 0
	v_mfma_f32_16x16x32_bf16 v[4:7], v[144:147], v[214:217], 0
	v_mfma_f32_16x16x32_bf16 v[0:3], v[172:175], v[214:217], 0
	v_mfma_f32_16x16x32_bf16 v[52:55], v[148:151], v[194:197], v[52:55]
	v_mfma_f32_16x16x32_bf16 v[48:51], v[176:179], v[194:197], v[48:51]
	v_mfma_f32_16x16x32_bf16 v[36:39], v[148:151], v[202:205], v[36:39]
	v_mfma_f32_16x16x32_bf16 v[32:35], v[176:179], v[202:205], v[32:35]
	v_mfma_f32_16x16x32_bf16 v[20:23], v[148:151], v[210:213], v[20:23]
	v_mfma_f32_16x16x32_bf16 v[16:19], v[176:179], v[210:213], v[16:19]
	v_mfma_f32_16x16x32_bf16 v[4:7], v[148:151], v[218:221], v[4:7]
	v_mfma_f32_16x16x32_bf16 v[0:3], v[176:179], v[218:221], v[0:3]
	s_setprio 0
	s_barrier
	s_add_i32 s84, 0, 0x18000
	s_add_i32 s85, 0, 0x1c000
	v_add_u32_e32 v140, s84, v186
	v_add_u32_e32 v176, s85, v186
	ds_read_b128 v[128:131], v140
	v_xor_b32_e32 v253, 64, v140
	ds_read_b128 v[132:135], v253
	ds_read_b128 v[136:139], v140 offset:2048
	ds_read_b128 v[140:143], v253 offset:2048
	ds_read_b128 v[144:147], v176
	v_xor_b32_e32 v253, 64, v176
	ds_read_b128 v[148:151], v253
	ds_read_b128 v[172:175], v176 offset:2048
	ds_read_b128 v[176:179], v253 offset:2048
	s_add_u32 s54, s60, 0xb0000
	s_addc_u32 s55, s61, 0
	s_mov_b32 m0, s68
	v_lshl_add_u64 v[230:231], s[54:55], 0, v[152:153]
	ds_read_b128 v[180:183], v191 offset:32768
	v_xor_b32_e32 v253, 64, v191
	ds_read_b128 v[194:197], v253 offset:32768
	ds_read_b128 v[198:201], v191 offset:34816
	ds_read_b128 v[202:205], v253 offset:34816
	ds_read_b128 v[206:209], v191 offset:36864
	ds_read_b128 v[210:213], v253 offset:36864
	ds_read_b128 v[214:217], v191 offset:38912
	ds_read_b128 v[218:221], v253 offset:38912
	global_load_lds_dwordx4 v[230:231], off
	v_lshl_add_u64 v[230:231], s[54:55], 0, v[160:161]
	s_mov_b32 m0, s69
	s_nop 0
	global_load_lds_dwordx4 v[230:231], off
	s_waitcnt vmcnt(8)
	s_waitcnt lgkmcnt(0)
	s_barrier
	s_setprio 1
	s_waitcnt lgkmcnt(0)
	v_mfma_f32_16x16x32_bf16 v[124:127], v[128:131], v[180:183], v[124:127]
	v_mfma_f32_16x16x32_bf16 v[120:123], v[136:139], v[180:183], v[120:123]
	v_mfma_f32_16x16x32_bf16 v[108:111], v[128:131], v[198:201], v[108:111]
	v_mfma_f32_16x16x32_bf16 v[104:107], v[136:139], v[198:201], v[104:107]
	v_mfma_f32_16x16x32_bf16 v[92:95], v[128:131], v[206:209], v[92:95]
	v_mfma_f32_16x16x32_bf16 v[88:91], v[136:139], v[206:209], v[88:91]
	v_mfma_f32_16x16x32_bf16 v[76:79], v[128:131], v[214:217], v[76:79]
	v_mfma_f32_16x16x32_bf16 v[72:75], v[136:139], v[214:217], v[72:75]
	v_mfma_f32_16x16x32_bf16 v[124:127], v[132:135], v[194:197], v[124:127]
	v_mfma_f32_16x16x32_bf16 v[120:123], v[140:143], v[194:197], v[120:123]
	v_mfma_f32_16x16x32_bf16 v[108:111], v[132:135], v[202:205], v[108:111]
	v_mfma_f32_16x16x32_bf16 v[104:107], v[140:143], v[202:205], v[104:107]
	v_mfma_f32_16x16x32_bf16 v[92:95], v[132:135], v[210:213], v[92:95]
	v_mfma_f32_16x16x32_bf16 v[88:91], v[140:143], v[210:213], v[88:91]
	v_mfma_f32_16x16x32_bf16 v[76:79], v[132:135], v[218:221], v[76:79]
	v_mfma_f32_16x16x32_bf16 v[72:75], v[140:143], v[218:221], v[72:75]
	s_setprio 0
	s_setprio 1
	v_mfma_f32_16x16x32_bf16 v[116:119], v[144:147], v[180:183], v[116:119]
	v_mfma_f32_16x16x32_bf16 v[112:115], v[172:175], v[180:183], v[112:115]
	v_mfma_f32_16x16x32_bf16 v[100:103], v[144:147], v[198:201], v[100:103]
	v_mfma_f32_16x16x32_bf16 v[96:99], v[172:175], v[198:201], v[96:99]
	v_mfma_f32_16x16x32_bf16 v[84:87], v[144:147], v[206:209], v[84:87]
	v_mfma_f32_16x16x32_bf16 v[80:83], v[172:175], v[206:209], v[80:83]
	v_mfma_f32_16x16x32_bf16 v[68:71], v[144:147], v[214:217], v[68:71]
	v_mfma_f32_16x16x32_bf16 v[64:67], v[172:175], v[214:217], v[64:67]
	v_mfma_f32_16x16x32_bf16 v[116:119], v[148:151], v[194:197], v[116:119]
	v_mfma_f32_16x16x32_bf16 v[112:115], v[176:179], v[194:197], v[112:115]
	v_mfma_f32_16x16x32_bf16 v[100:103], v[148:151], v[202:205], v[100:103]
	v_mfma_f32_16x16x32_bf16 v[96:99], v[176:179], v[202:205], v[96:99]
	v_mfma_f32_16x16x32_bf16 v[84:87], v[148:151], v[210:213], v[84:87]
	v_mfma_f32_16x16x32_bf16 v[80:83], v[176:179], v[210:213], v[80:83]
	v_mfma_f32_16x16x32_bf16 v[68:71], v[148:151], v[218:221], v[68:71]
	v_mfma_f32_16x16x32_bf16 v[64:67], v[176:179], v[218:221], v[64:67]
	s_setprio 0
	s_barrier
	s_add_i32 s54, s84, s65
	v_lshl_add_u64 v[222:223], v[222:223], 0, s[28:29]
	s_mov_b32 m0, s54
	ds_read_b128 v[180:183], v191 offset:49152
	v_xor_b32_e32 v253, 64, v191
	ds_read_b128 v[194:197], v253 offset:49152
	ds_read_b128 v[198:201], v191 offset:51200
	ds_read_b128 v[202:205], v253 offset:51200
	ds_read_b128 v[206:209], v191 offset:53248
	ds_read_b128 v[210:213], v253 offset:53248
	ds_read_b128 v[214:217], v191 offset:55296
	ds_read_b128 v[218:221], v253 offset:55296
	global_load_lds_dwordx4 v[222:223], off
	s_add_i32 m0, s54, 0x2000
	s_add_u32 s54, s58, 0xb0080
	v_lshl_add_u64 v[222:223], v[224:225], 0, s[28:29]
	s_addc_u32 s55, s59, 0
	s_add_i32 s58, s85, s65
	global_load_lds_dwordx4 v[222:223], off
	v_lshl_add_u64 v[222:223], s[54:55], 0, v[154:155]
	s_mov_b32 m0, s58
	s_nop 0
	global_load_lds_dwordx4 v[222:223], off
	v_lshl_add_u64 v[222:223], s[54:55], 0, v[162:163]
	s_add_i32 m0, s58, 0x2000
	s_nop 0
	global_load_lds_dwordx4 v[222:223], off
	v_lshl_add_u64 v[222:223], v[226:227], 0, s[28:29]
	s_mov_b32 m0, s3
	s_nop 0
	global_load_lds_dwordx4 v[222:223], off
	v_lshl_add_u64 v[222:223], v[228:229], 0, s[28:29]
	s_mov_b32 m0, s71
	s_nop 0
	global_load_lds_dwordx4 v[222:223], off
	s_waitcnt vmcnt(8)
	s_waitcnt lgkmcnt(0)
	s_barrier
	s_setprio 1
	s_waitcnt lgkmcnt(0)
	v_mfma_f32_16x16x32_bf16 v[60:63], v[128:131], v[180:183], v[60:63]
	v_mfma_f32_16x16x32_bf16 v[56:59], v[136:139], v[180:183], v[56:59]
	v_mfma_f32_16x16x32_bf16 v[44:47], v[128:131], v[198:201], v[44:47]
	v_mfma_f32_16x16x32_bf16 v[40:43], v[136:139], v[198:201], v[40:43]
	v_mfma_f32_16x16x32_bf16 v[28:31], v[128:131], v[206:209], v[28:31]
	v_mfma_f32_16x16x32_bf16 v[24:27], v[136:139], v[206:209], v[24:27]
	v_mfma_f32_16x16x32_bf16 v[12:15], v[128:131], v[214:217], v[12:15]
	v_mfma_f32_16x16x32_bf16 v[8:11], v[136:139], v[214:217], v[8:11]
	v_mfma_f32_16x16x32_bf16 v[60:63], v[132:135], v[194:197], v[60:63]
	v_mfma_f32_16x16x32_bf16 v[56:59], v[140:143], v[194:197], v[56:59]
	v_mfma_f32_16x16x32_bf16 v[44:47], v[132:135], v[202:205], v[44:47]
	v_mfma_f32_16x16x32_bf16 v[40:43], v[140:143], v[202:205], v[40:43]
	v_mfma_f32_16x16x32_bf16 v[28:31], v[132:135], v[210:213], v[28:31]
	v_mfma_f32_16x16x32_bf16 v[24:27], v[140:143], v[210:213], v[24:27]
	v_mfma_f32_16x16x32_bf16 v[12:15], v[132:135], v[218:221], v[12:15]
	v_mfma_f32_16x16x32_bf16 v[8:11], v[140:143], v[218:221], v[8:11]
	s_setprio 0
	s_setprio 1
	v_mfma_f32_16x16x32_bf16 v[52:55], v[144:147], v[180:183], v[52:55]
	v_mfma_f32_16x16x32_bf16 v[48:51], v[172:175], v[180:183], v[48:51]
	v_mfma_f32_16x16x32_bf16 v[36:39], v[144:147], v[198:201], v[36:39]
	v_mfma_f32_16x16x32_bf16 v[32:35], v[172:175], v[198:201], v[32:35]
	v_mfma_f32_16x16x32_bf16 v[20:23], v[144:147], v[206:209], v[20:23]
	v_mfma_f32_16x16x32_bf16 v[16:19], v[172:175], v[206:209], v[16:19]
	v_mfma_f32_16x16x32_bf16 v[4:7], v[144:147], v[214:217], v[4:7]
	v_mfma_f32_16x16x32_bf16 v[0:3], v[172:175], v[214:217], v[0:3]
	v_mfma_f32_16x16x32_bf16 v[52:55], v[148:151], v[194:197], v[52:55]
	v_mfma_f32_16x16x32_bf16 v[48:51], v[176:179], v[194:197], v[48:51]
	v_mfma_f32_16x16x32_bf16 v[36:39], v[148:151], v[202:205], v[36:39]
	v_mfma_f32_16x16x32_bf16 v[32:35], v[176:179], v[202:205], v[32:35]
	v_mfma_f32_16x16x32_bf16 v[20:23], v[148:151], v[210:213], v[20:23]
	v_mfma_f32_16x16x32_bf16 v[16:19], v[176:179], v[210:213], v[16:19]
	v_mfma_f32_16x16x32_bf16 v[4:7], v[148:151], v[218:221], v[4:7]
	v_mfma_f32_16x16x32_bf16 v[0:3], v[176:179], v[218:221], v[0:3]
	s_setprio 0
	s_barrier
	s_add_i32 s83, s83, 2
	s_add_u32 s81, s81, 0x100
	s_addc_u32 s82, s82, 0
	s_cmp_gt_u32 s83, 41
	s_mov_b64 s[54:55], s[56:57]
	s_branch .LBB0_159
.Lfa_1:
	ds_read_b128 v[128:131], v189
	v_xor_b32_e32 v253, 64, v189
	ds_read_b128 v[132:135], v253
	ds_read_b128 v[136:139], v189 offset:2048
	ds_read_b128 v[140:143], v253 offset:2048
	ds_read_b128 v[144:147], v190
	v_xor_b32_e32 v253, 64, v190
	ds_read_b128 v[148:151], v253
	ds_read_b128 v[172:175], v190 offset:2048
	ds_read_b128 v[176:179], v253 offset:2048
	s_add_u32 s56, s54, 0x100
	s_addc_u32 s57, s55, 0
	s_cmp_eq_u32 s83, 40
	s_cselect_b32 s61, s15, s57
	s_cselect_b32 s60, s14, s56
	s_cselect_b32 s59, s53, s82
	s_cselect_b32 s58, s52, s81
	v_lshl_add_u64 v[222:223], s[54:55], 0, v[166:167]
	s_add_i32 m0, s66, 0xc000
	ds_read_b128 v[180:183], v191
	v_xor_b32_e32 v253, 64, v191
	ds_read_b128 v[194:197], v253
	ds_read_b128 v[198:201], v191 offset:2048
	ds_read_b128 v[202:205], v253 offset:2048
	ds_read_b128 v[206:209], v191 offset:4096
	ds_read_b128 v[210:213], v253 offset:4096
	ds_read_b128 v[214:217], v191 offset:6144
	ds_read_b128 v[218:221], v253 offset:6144
	global_load_lds_dwordx4 v[222:223], off
	v_lshl_add_u64 v[222:223], s[54:55], 0, v[164:165]
	s_add_i32 m0, s66, 0xe000
	s_nop 0
	global_load_lds_dwordx4 v[222:223], off
	s_waitcnt vmcnt(8)
	s_waitcnt lgkmcnt(0)
	s_barrier
	s_setprio 1
	s_waitcnt lgkmcnt(0)
	v_mfma_f32_16x16x32_bf16 v[124:127], v[128:131], v[180:183], 0
	v_mfma_f32_16x16x32_bf16 v[120:123], v[136:139], v[180:183], 0
	v_mfma_f32_16x16x32_bf16 v[108:111], v[128:131], v[198:201], 0
	v_mfma_f32_16x16x32_bf16 v[104:107], v[136:139], v[198:201], 0
	v_mfma_f32_16x16x32_bf16 v[92:95], v[128:131], v[206:209], 0
	v_mfma_f32_16x16x32_bf16 v[88:91], v[136:139], v[206:209], 0
	v_mfma_f32_16x16x32_bf16 v[76:79], v[128:131], v[214:217], 0
	v_mfma_f32_16x16x32_bf16 v[72:75], v[136:139], v[214:217], 0
	v_mfma_f32_16x16x32_bf16 v[124:127], v[132:135], v[194:197], v[124:127]
	v_mfma_f32_16x16x32_bf16 v[120:123], v[140:143], v[194:197], v[120:123]
	v_mfma_f32_16x16x32_bf16 v[108:111], v[132:135], v[202:205], v[108:111]
	v_mfma_f32_16x16x32_bf16 v[104:107], v[140:143], v[202:205], v[104:107]
	v_mfma_f32_16x16x32_bf16 v[92:95], v[132:135], v[210:213], v[92:95]
	v_mfma_f32_16x16x32_bf16 v[88:91], v[140:143], v[210:213], v[88:91]
	v_mfma_f32_16x16x32_bf16 v[76:79], v[132:135], v[218:221], v[76:79]
	v_mfma_f32_16x16x32_bf16 v[72:75], v[140:143], v[218:221], v[72:75]
	s_setprio 0
	s_setprio 1
	v_mfma_f32_16x16x32_bf16 v[116:119], v[144:147], v[180:183], 0
	v_mfma_f32_16x16x32_bf16 v[112:115], v[172:175], v[180:183], 0
	v_mfma_f32_16x16x32_bf16 v[100:103], v[144:147], v[198:201], 0
	v_mfma_f32_16x16x32_bf16 v[96:99], v[172:175], v[198:201], 0
	v_mfma_f32_16x16x32_bf16 v[84:87], v[144:147], v[206:209], 0
	v_mfma_f32_16x16x32_bf16 v[80:83], v[172:175], v[206:209], 0
	v_mfma_f32_16x16x32_bf16 v[68:71], v[144:147], v[214:217], 0
	v_mfma_f32_16x16x32_bf16 v[64:67], v[172:175], v[214:217], 0
	v_mfma_f32_16x16x32_bf16 v[116:119], v[148:151], v[194:197], v[116:119]
	v_mfma_f32_16x16x32_bf16 v[112:115], v[176:179], v[194:197], v[112:115]
	v_mfma_f32_16x16x32_bf16 v[100:103], v[148:151], v[202:205], v[100:103]
	v_mfma_f32_16x16x32_bf16 v[96:99], v[176:179], v[202:205], v[96:99]
	v_mfma_f32_16x16x32_bf16 v[84:87], v[148:151], v[210:213], v[84:87]
	v_mfma_f32_16x16x32_bf16 v[80:83], v[176:179], v[210:213], v[80:83]
	v_mfma_f32_16x16x32_bf16 v[68:71], v[148:151], v[218:221], v[68:71]
	v_mfma_f32_16x16x32_bf16 v[64:67], v[176:179], v[218:221], v[64:67]
	s_setprio 0
	s_barrier
	s_add_i32 s54, s77, s65
	v_lshl_add_u64 v[222:223], s[58:59], 0, v[154:155]
	s_mov_b32 m0, s54
	ds_read_b128 v[180:183], v191 offset:16384
	v_xor_b32_e32 v253, 64, v191
	ds_read_b128 v[194:197], v253 offset:16384
	ds_read_b128 v[198:201], v191 offset:18432
	ds_read_b128 v[202:205], v253 offset:18432
	ds_read_b128 v[206:209], v191 offset:20480
	ds_read_b128 v[210:213], v253 offset:20480
	ds_read_b128 v[214:217], v191 offset:22528
	ds_read_b128 v[218:221], v253 offset:22528
	global_load_lds_dwordx4 v[222:223], off
	s_add_i32 m0, s54, 0x2000
	s_add_u32 s54, s58, 0xb0000
	v_lshl_add_u64 v[224:225], s[58:59], 0, v[162:163]
	s_addc_u32 s55, s59, 0
	s_add_i32 s84, s78, s65
	global_load_lds_dwordx4 v[224:225], off
	v_lshl_add_u64 v[226:227], s[54:55], 0, v[154:155]
	s_mov_b32 m0, s84
	v_lshl_add_u64 v[228:229], s[60:61], 0, v[160:161]
	global_load_lds_dwordx4 v[226:227], off
	v_lshl_add_u64 v[226:227], s[54:55], 0, v[162:163]
	s_add_i32 m0, s84, 0x2000
	s_nop 0
	global_load_lds_dwordx4 v[226:227], off
	v_lshl_add_u64 v[226:227], s[60:61], 0, v[152:153]
	s_mov_b32 m0, s66
	s_nop 0
	global_load_lds_dwordx4 v[226:227], off
	s_mov_b32 m0, s67
	s_nop 0
	global_load_lds_dwordx4 v[228:229], off
	s_waitcnt vmcnt(8)
	s_waitcnt lgkmcnt(0)
	s_barrier
	s_setprio 1
	s_waitcnt lgkmcnt(0)
	v_mfma_f32_16x16x32_bf16 v[60:63], v[128:131], v[180:183], 0
	v_mfma_f32_16x16x32_bf16 v[56:59], v[136:139], v[180:183], 0
	v_mfma_f32_16x16x32_bf16 v[44:47], v[128:131], v[198:201], 0
	v_mfma_f32_16x16x32_bf16 v[40:43], v[136:139], v[198:201], 0
	v_mfma_f32_16x16x32_bf16 v[28:31], v[128:131], v[206:209], 0
	v_mfma_f32_16x16x32_bf16 v[24:27], v[136:139], v[206:209], 0
	v_mfma_f32_16x16x32_bf16 v[12:15], v[128:131], v[214:217], 0
	v_mfma_f32_16x16x32_bf16 v[8:11], v[136:139], v[214:217], 0
	v_mfma_f32_16x16x32_bf16 v[60:63], v[132:135], v[194:197], v[60:63]
	v_mfma_f32_16x16x32_bf16 v[56:59], v[140:143], v[194:197], v[56:59]
	v_mfma_f32_16x16x32_bf16 v[44:47], v[132:135], v[202:205], v[44:47]
	v_mfma_f32_16x16x32_bf16 v[40:43], v[140:143], v[202:205], v[40:43]
	v_mfma_f32_16x16x32_bf16 v[28:31], v[132:135], v[210:213], v[28:31]
	v_mfma_f32_16x16x32_bf16 v[24:27], v[140:143], v[210:213], v[24:27]
	v_mfma_f32_16x16x32_bf16 v[12:15], v[132:135], v[218:221], v[12:15]
	v_mfma_f32_16x16x32_bf16 v[8:11], v[140:143], v[218:221], v[8:11]
	s_setprio 0
	s_setprio 1
	v_mfma_f32_16x16x32_bf16 v[52:55], v[144:147], v[180:183], 0
	v_mfma_f32_16x16x32_bf16 v[48:51], v[172:175], v[180:183], 0
	v_mfma_f32_16x16x32_bf16 v[36:39], v[144:147], v[198:201], 0
	v_mfma_f32_16x16x32_bf16 v[32:35], v[172:175], v[198:201], 0
	v_mfma_f32_16x16x32_bf16 v[20:23], v[144:147], v[206:209], 0
	v_mfma_f32_16x16x32_bf16 v[16:19], v[172:175], v[206:209], 0
	v_mfma_f32_16x16x32_bf16 v[4:7], v[144:147], v[214:217], 0
	v_mfma_f32_16x16x32_bf16 v[0:3], v[172:175], v[214:217], 0
	v_mfma_f32_16x16x32_bf16 v[52:55], v[148:151], v[194:197], v[52:55]
	v_mfma_f32_16x16x32_bf16 v[48:51], v[176:179], v[194:197], v[48:51]
	v_mfma_f32_16x16x32_bf16 v[36:39], v[148:151], v[202:205], v[36:39]
	v_mfma_f32_16x16x32_bf16 v[32:35], v[176:179], v[202:205], v[32:35]
	v_mfma_f32_16x16x32_bf16 v[20:23], v[148:151], v[210:213], v[20:23]
	v_mfma_f32_16x16x32_bf16 v[16:19], v[176:179], v[210:213], v[16:19]
	v_mfma_f32_16x16x32_bf16 v[4:7], v[148:151], v[218:221], v[4:7]
	v_mfma_f32_16x16x32_bf16 v[0:3], v[176:179], v[218:221], v[0:3]
	s_setprio 0
	s_barrier
	s_add_i32 s84, 0, 0x18000
	s_add_i32 s85, 0, 0x1c000
	v_add_u32_e32 v140, s84, v186
	v_add_u32_e32 v176, s85, v186
	ds_read_b128 v[128:131], v140
	v_xor_b32_e32 v253, 64, v140
	ds_read_b128 v[132:135], v253
	ds_read_b128 v[136:139], v140 offset:2048
	ds_read_b128 v[140:143], v253 offset:2048
	ds_read_b128 v[144:147], v176
	v_xor_b32_e32 v253, 64, v176
	ds_read_b128 v[148:151], v253
	ds_read_b128 v[172:175], v176 offset:2048
	ds_read_b128 v[176:179], v253 offset:2048
	s_add_u32 s54, s60, 0xb0000
	s_addc_u32 s55, s61, 0
	s_mov_b32 m0, s68
	v_lshl_add_u64 v[230:231], s[54:55], 0, v[152:153]
	ds_read_b128 v[180:183], v191 offset:32768
	v_xor_b32_e32 v253, 64, v191
	ds_read_b128 v[194:197], v253 offset:32768
	ds_read_b128 v[198:201], v191 offset:34816
	ds_read_b128 v[202:205], v253 offset:34816
	ds_read_b128 v[206:209], v191 offset:36864
	ds_read_b128 v[210:213], v253 offset:36864
	ds_read_b128 v[214:217], v191 offset:38912
	ds_read_b128 v[218:221], v253 offset:38912
	global_load_lds_dwordx4 v[230:231], off
	v_lshl_add_u64 v[230:231], s[54:55], 0, v[160:161]
	s_mov_b32 m0, s69
	s_nop 0
	global_load_lds_dwordx4 v[230:231], off
	s_waitcnt vmcnt(8)
	s_waitcnt lgkmcnt(0)
	s_barrier
	s_setprio 1
	s_waitcnt lgkmcnt(0)
	v_mfma_f32_16x16x32_bf16 v[124:127], v[128:131], v[180:183], v[124:127]
	v_mfma_f32_16x16x32_bf16 v[120:123], v[136:139], v[180:183], v[120:123]
	v_mfma_f32_16x16x32_bf16 v[108:111], v[128:131], v[198:201], v[108:111]
	v_mfma_f32_16x16x32_bf16 v[104:107], v[136:139], v[198:201], v[104:107]
	v_mfma_f32_16x16x32_bf16 v[92:95], v[128:131], v[206:209], v[92:95]
	v_mfma_f32_16x16x32_bf16 v[88:91], v[136:139], v[206:209], v[88:91]
	v_mfma_f32_16x16x32_bf16 v[76:79], v[128:131], v[214:217], v[76:79]
	v_mfma_f32_16x16x32_bf16 v[72:75], v[136:139], v[214:217], v[72:75]
	v_mfma_f32_16x16x32_bf16 v[124:127], v[132:135], v[194:197], v[124:127]
	v_mfma_f32_16x16x32_bf16 v[120:123], v[140:143], v[194:197], v[120:123]
	v_mfma_f32_16x16x32_bf16 v[108:111], v[132:135], v[202:205], v[108:111]
	v_mfma_f32_16x16x32_bf16 v[104:107], v[140:143], v[202:205], v[104:107]
	v_mfma_f32_16x16x32_bf16 v[92:95], v[132:135], v[210:213], v[92:95]
	v_mfma_f32_16x16x32_bf16 v[88:91], v[140:143], v[210:213], v[88:91]
	v_mfma_f32_16x16x32_bf16 v[76:79], v[132:135], v[218:221], v[76:79]
	v_mfma_f32_16x16x32_bf16 v[72:75], v[140:143], v[218:221], v[72:75]
	s_setprio 0
	s_setprio 1
	v_mfma_f32_16x16x32_bf16 v[116:119], v[144:147], v[180:183], v[116:119]
	v_mfma_f32_16x16x32_bf16 v[112:115], v[172:175], v[180:183], v[112:115]
	v_mfma_f32_16x16x32_bf16 v[100:103], v[144:147], v[198:201], v[100:103]
	v_mfma_f32_16x16x32_bf16 v[96:99], v[172:175], v[198:201], v[96:99]
	v_mfma_f32_16x16x32_bf16 v[84:87], v[144:147], v[206:209], v[84:87]
	v_mfma_f32_16x16x32_bf16 v[80:83], v[172:175], v[206:209], v[80:83]
	v_mfma_f32_16x16x32_bf16 v[68:71], v[144:147], v[214:217], v[68:71]
	v_mfma_f32_16x16x32_bf16 v[64:67], v[172:175], v[214:217], v[64:67]
	v_mfma_f32_16x16x32_bf16 v[116:119], v[148:151], v[194:197], v[116:119]
	v_mfma_f32_16x16x32_bf16 v[112:115], v[176:179], v[194:197], v[112:115]
	v_mfma_f32_16x16x32_bf16 v[100:103], v[148:151], v[202:205], v[100:103]
	v_mfma_f32_16x16x32_bf16 v[96:99], v[176:179], v[202:205], v[96:99]
	v_mfma_f32_16x16x32_bf16 v[84:87], v[148:151], v[210:213], v[84:87]
	v_mfma_f32_16x16x32_bf16 v[80:83], v[176:179], v[210:213], v[80:83]
	v_mfma_f32_16x16x32_bf16 v[68:71], v[148:151], v[218:221], v[68:71]
	v_mfma_f32_16x16x32_bf16 v[64:67], v[176:179], v[218:221], v[64:67]
	s_setprio 0
	s_barrier
	s_add_i32 s54, s84, s65
	v_lshl_add_u64 v[222:223], v[222:223], 0, s[28:29]
	s_mov_b32 m0, s54
	ds_read_b128 v[180:183], v191 offset:49152
	v_xor_b32_e32 v253, 64, v191
	ds_read_b128 v[194:197], v253 offset:49152
	ds_read_b128 v[198:201], v191 offset:51200
	ds_read_b128 v[202:205], v253 offset:51200
	ds_read_b128 v[206:209], v191 offset:53248
	ds_read_b128 v[210:213], v253 offset:53248
	ds_read_b128 v[214:217], v191 offset:55296
	ds_read_b128 v[218:221], v253 offset:55296
	global_load_lds_dwordx4 v[222:223], off
	s_add_i32 m0, s54, 0x2000
	s_add_u32 s54, s58, 0xb0080
	v_lshl_add_u64 v[222:223], v[224:225], 0, s[28:29]
	s_addc_u32 s55, s59, 0
	s_add_i32 s58, s85, s65
	global_load_lds_dwordx4 v[222:223], off
	v_lshl_add_u64 v[222:223], s[54:55], 0, v[154:155]
	s_mov_b32 m0, s58
	s_nop 0
	global_load_lds_dwordx4 v[222:223], off
	v_lshl_add_u64 v[222:223], s[54:55], 0, v[162:163]
	s_add_i32 m0, s58, 0x2000
	s_nop 0
	global_load_lds_dwordx4 v[222:223], off
	v_lshl_add_u64 v[222:223], v[226:227], 0, s[28:29]
	s_mov_b32 m0, s3
	s_nop 0
	global_load_lds_dwordx4 v[222:223], off
	v_lshl_add_u64 v[222:223], v[228:229], 0, s[28:29]
	s_mov_b32 m0, s71
	s_nop 0
	global_load_lds_dwordx4 v[222:223], off
	s_waitcnt vmcnt(8)
	s_waitcnt lgkmcnt(0)
	s_barrier
	s_setprio 1
	s_waitcnt lgkmcnt(0)
	v_mfma_f32_16x16x32_bf16 v[60:63], v[128:131], v[180:183], v[60:63]
	v_mfma_f32_16x16x32_bf16 v[56:59], v[136:139], v[180:183], v[56:59]
	v_mfma_f32_16x16x32_bf16 v[44:47], v[128:131], v[198:201], v[44:47]
	v_mfma_f32_16x16x32_bf16 v[40:43], v[136:139], v[198:201], v[40:43]
	v_mfma_f32_16x16x32_bf16 v[28:31], v[128:131], v[206:209], v[28:31]
	v_mfma_f32_16x16x32_bf16 v[24:27], v[136:139], v[206:209], v[24:27]
	v_mfma_f32_16x16x32_bf16 v[12:15], v[128:131], v[214:217], v[12:15]
	v_mfma_f32_16x16x32_bf16 v[8:11], v[136:139], v[214:217], v[8:11]
	v_mfma_f32_16x16x32_bf16 v[60:63], v[132:135], v[194:197], v[60:63]
	v_mfma_f32_16x16x32_bf16 v[56:59], v[140:143], v[194:197], v[56:59]
	v_mfma_f32_16x16x32_bf16 v[44:47], v[132:135], v[202:205], v[44:47]
	v_mfma_f32_16x16x32_bf16 v[40:43], v[140:143], v[202:205], v[40:43]
	v_mfma_f32_16x16x32_bf16 v[28:31], v[132:135], v[210:213], v[28:31]
	v_mfma_f32_16x16x32_bf16 v[24:27], v[140:143], v[210:213], v[24:27]
	v_mfma_f32_16x16x32_bf16 v[12:15], v[132:135], v[218:221], v[12:15]
	v_mfma_f32_16x16x32_bf16 v[8:11], v[140:143], v[218:221], v[8:11]
	s_setprio 0
	s_setprio 1
	v_mfma_f32_16x16x32_bf16 v[52:55], v[144:147], v[180:183], v[52:55]
	v_mfma_f32_16x16x32_bf16 v[48:51], v[172:175], v[180:183], v[48:51]
	v_mfma_f32_16x16x32_bf16 v[36:39], v[144:147], v[198:201], v[36:39]
	v_mfma_f32_16x16x32_bf16 v[32:35], v[172:175], v[198:201], v[32:35]
	v_mfma_f32_16x16x32_bf16 v[20:23], v[144:147], v[206:209], v[20:23]
	v_mfma_f32_16x16x32_bf16 v[16:19], v[172:175], v[206:209], v[16:19]
	v_mfma_f32_16x16x32_bf16 v[4:7], v[144:147], v[214:217], v[4:7]
	v_mfma_f32_16x16x32_bf16 v[0:3], v[172:175], v[214:217], v[0:3]
	v_mfma_f32_16x16x32_bf16 v[52:55], v[148:151], v[194:197], v[52:55]
	v_mfma_f32_16x16x32_bf16 v[48:51], v[176:179], v[194:197], v[48:51]
	v_mfma_f32_16x16x32_bf16 v[36:39], v[148:151], v[202:205], v[36:39]
	v_mfma_f32_16x16x32_bf16 v[32:35], v[176:179], v[202:205], v[32:35]
	v_mfma_f32_16x16x32_bf16 v[20:23], v[148:151], v[210:213], v[20:23]
	v_mfma_f32_16x16x32_bf16 v[16:19], v[176:179], v[210:213], v[16:19]
	v_mfma_f32_16x16x32_bf16 v[4:7], v[148:151], v[218:221], v[4:7]
	v_mfma_f32_16x16x32_bf16 v[0:3], v[176:179], v[218:221], v[0:3]
	s_setprio 0
	s_barrier
	s_add_i32 s83, s83, 2
	s_add_u32 s81, s81, 0x100
	s_addc_u32 s82, s82, 0
	s_cmp_gt_u32 s83, 41
	s_mov_b64 s[54:55], s[56:57]
.LBB0_159:
	ds_read_b128 v[128:131], v189
	v_xor_b32_e32 v253, 64, v189
	ds_read_b128 v[132:135], v253
	ds_read_b128 v[136:139], v189 offset:2048
	ds_read_b128 v[140:143], v253 offset:2048
	ds_read_b128 v[144:147], v190
	v_xor_b32_e32 v253, 64, v190
	ds_read_b128 v[148:151], v253
	ds_read_b128 v[172:175], v190 offset:2048
	ds_read_b128 v[176:179], v253 offset:2048
	s_add_u32 s56, s54, 0x100
	s_addc_u32 s57, s55, 0
	s_cmp_eq_u32 s83, 40
	s_cselect_b32 s61, s15, s57
	s_cselect_b32 s60, s14, s56
	s_cselect_b32 s59, s53, s82
	s_cselect_b32 s58, s52, s81
	v_lshl_add_u64 v[222:223], s[54:55], 0, v[166:167]
	s_add_i32 m0, s66, 0xc000
	ds_read_b128 v[180:183], v191
	v_xor_b32_e32 v253, 64, v191
	ds_read_b128 v[194:197], v253
	ds_read_b128 v[198:201], v191 offset:2048
	ds_read_b128 v[202:205], v253 offset:2048
	ds_read_b128 v[206:209], v191 offset:4096
	ds_read_b128 v[210:213], v253 offset:4096
	ds_read_b128 v[214:217], v191 offset:6144
	ds_read_b128 v[218:221], v253 offset:6144
	global_load_lds_dwordx4 v[222:223], off
	v_lshl_add_u64 v[222:223], s[54:55], 0, v[164:165]
	s_add_i32 m0, s66, 0xe000
	s_nop 0
	global_load_lds_dwordx4 v[222:223], off
	s_waitcnt vmcnt(8)
	s_waitcnt lgkmcnt(0)
	s_barrier
	s_setprio 1
	s_waitcnt lgkmcnt(0)
	v_mfma_f32_16x16x32_bf16 v[124:127], v[128:131], v[180:183], v[124:127]
	v_mfma_f32_16x16x32_bf16 v[120:123], v[136:139], v[180:183], v[120:123]
	v_mfma_f32_16x16x32_bf16 v[108:111], v[128:131], v[198:201], v[108:111]
	v_mfma_f32_16x16x32_bf16 v[104:107], v[136:139], v[198:201], v[104:107]
	v_mfma_f32_16x16x32_bf16 v[92:95], v[128:131], v[206:209], v[92:95]
	v_mfma_f32_16x16x32_bf16 v[88:91], v[136:139], v[206:209], v[88:91]
	v_mfma_f32_16x16x32_bf16 v[76:79], v[128:131], v[214:217], v[76:79]
	v_mfma_f32_16x16x32_bf16 v[72:75], v[136:139], v[214:217], v[72:75]
	v_mfma_f32_16x16x32_bf16 v[124:127], v[132:135], v[194:197], v[124:127]
	v_mfma_f32_16x16x32_bf16 v[120:123], v[140:143], v[194:197], v[120:123]
	v_mfma_f32_16x16x32_bf16 v[108:111], v[132:135], v[202:205], v[108:111]
	v_mfma_f32_16x16x32_bf16 v[104:107], v[140:143], v[202:205], v[104:107]
	v_mfma_f32_16x16x32_bf16 v[92:95], v[132:135], v[210:213], v[92:95]
	v_mfma_f32_16x16x32_bf16 v[88:91], v[140:143], v[210:213], v[88:91]
	v_mfma_f32_16x16x32_bf16 v[76:79], v[132:135], v[218:221], v[76:79]
	v_mfma_f32_16x16x32_bf16 v[72:75], v[140:143], v[218:221], v[72:75]
	s_setprio 0
	s_setprio 1
	v_mfma_f32_16x16x32_bf16 v[116:119], v[144:147], v[180:183], v[116:119]
	v_mfma_f32_16x16x32_bf16 v[112:115], v[172:175], v[180:183], v[112:115]
	v_mfma_f32_16x16x32_bf16 v[100:103], v[144:147], v[198:201], v[100:103]
	v_mfma_f32_16x16x32_bf16 v[96:99], v[172:175], v[198:201], v[96:99]
	v_mfma_f32_16x16x32_bf16 v[84:87], v[144:147], v[206:209], v[84:87]
	v_mfma_f32_16x16x32_bf16 v[80:83], v[172:175], v[206:209], v[80:83]
	v_mfma_f32_16x16x32_bf16 v[68:71], v[144:147], v[214:217], v[68:71]
	v_mfma_f32_16x16x32_bf16 v[64:67], v[172:175], v[214:217], v[64:67]
	v_mfma_f32_16x16x32_bf16 v[116:119], v[148:151], v[194:197], v[116:119]
	v_mfma_f32_16x16x32_bf16 v[112:115], v[176:179], v[194:197], v[112:115]
	v_mfma_f32_16x16x32_bf16 v[100:103], v[148:151], v[202:205], v[100:103]
	v_mfma_f32_16x16x32_bf16 v[96:99], v[176:179], v[202:205], v[96:99]
	v_mfma_f32_16x16x32_bf16 v[84:87], v[148:151], v[210:213], v[84:87]
	v_mfma_f32_16x16x32_bf16 v[80:83], v[176:179], v[210:213], v[80:83]
	v_mfma_f32_16x16x32_bf16 v[68:71], v[148:151], v[218:221], v[68:71]
	v_mfma_f32_16x16x32_bf16 v[64:67], v[176:179], v[218:221], v[64:67]
	s_setprio 0
	s_barrier
	s_add_i32 s54, s77, s65
	v_lshl_add_u64 v[222:223], s[58:59], 0, v[154:155]
	s_mov_b32 m0, s54
	ds_read_b128 v[180:183], v191 offset:16384
	v_xor_b32_e32 v253, 64, v191
	ds_read_b128 v[194:197], v253 offset:16384
	ds_read_b128 v[198:201], v191 offset:18432
	ds_read_b128 v[202:205], v253 offset:18432
	ds_read_b128 v[206:209], v191 offset:20480
	ds_read_b128 v[210:213], v253 offset:20480
	ds_read_b128 v[214:217], v191 offset:22528
	ds_read_b128 v[218:221], v253 offset:22528
	global_load_lds_dwordx4 v[222:223], off
	s_add_i32 m0, s54, 0x2000
	s_add_u32 s54, s58, 0xb0000
	v_lshl_add_u64 v[224:225], s[58:59], 0, v[162:163]
	s_addc_u32 s55, s59, 0
	s_add_i32 s84, s78, s65
	global_load_lds_dwordx4 v[224:225], off
	v_lshl_add_u64 v[226:227], s[54:55], 0, v[154:155]
	s_mov_b32 m0, s84
	v_lshl_add_u64 v[228:229], s[60:61], 0, v[160:161]
	global_load_lds_dwordx4 v[226:227], off
	v_lshl_add_u64 v[226:227], s[54:55], 0, v[162:163]
	s_add_i32 m0, s84, 0x2000
	s_nop 0
	global_load_lds_dwordx4 v[226:227], off
	v_lshl_add_u64 v[226:227], s[60:61], 0, v[152:153]
	s_mov_b32 m0, s66
	s_nop 0
	global_load_lds_dwordx4 v[226:227], off
	s_mov_b32 m0, s67
	s_nop 0
	global_load_lds_dwordx4 v[228:229], off
	s_waitcnt vmcnt(8)
	s_waitcnt lgkmcnt(0)
	s_barrier
	s_setprio 1
	s_waitcnt lgkmcnt(0)
	v_mfma_f32_16x16x32_bf16 v[60:63], v[128:131], v[180:183], v[60:63]
	v_mfma_f32_16x16x32_bf16 v[56:59], v[136:139], v[180:183], v[56:59]
	v_mfma_f32_16x16x32_bf16 v[44:47], v[128:131], v[198:201], v[44:47]
	v_mfma_f32_16x16x32_bf16 v[40:43], v[136:139], v[198:201], v[40:43]
	v_mfma_f32_16x16x32_bf16 v[28:31], v[128:131], v[206:209], v[28:31]
	v_mfma_f32_16x16x32_bf16 v[24:27], v[136:139], v[206:209], v[24:27]
	v_mfma_f32_16x16x32_bf16 v[12:15], v[128:131], v[214:217], v[12:15]
	v_mfma_f32_16x16x32_bf16 v[8:11], v[136:139], v[214:217], v[8:11]
	v_mfma_f32_16x16x32_bf16 v[60:63], v[132:135], v[194:197], v[60:63]
	v_mfma_f32_16x16x32_bf16 v[56:59], v[140:143], v[194:197], v[56:59]
	v_mfma_f32_16x16x32_bf16 v[44:47], v[132:135], v[202:205], v[44:47]
	v_mfma_f32_16x16x32_bf16 v[40:43], v[140:143], v[202:205], v[40:43]
	v_mfma_f32_16x16x32_bf16 v[28:31], v[132:135], v[210:213], v[28:31]
	v_mfma_f32_16x16x32_bf16 v[24:27], v[140:143], v[210:213], v[24:27]
	v_mfma_f32_16x16x32_bf16 v[12:15], v[132:135], v[218:221], v[12:15]
	v_mfma_f32_16x16x32_bf16 v[8:11], v[140:143], v[218:221], v[8:11]
	s_setprio 0
	s_setprio 1
	v_mfma_f32_16x16x32_bf16 v[52:55], v[144:147], v[180:183], v[52:55]
	v_mfma_f32_16x16x32_bf16 v[48:51], v[172:175], v[180:183], v[48:51]
	v_mfma_f32_16x16x32_bf16 v[36:39], v[144:147], v[198:201], v[36:39]
	v_mfma_f32_16x16x32_bf16 v[32:35], v[172:175], v[198:201], v[32:35]
	v_mfma_f32_16x16x32_bf16 v[20:23], v[144:147], v[206:209], v[20:23]
	v_mfma_f32_16x16x32_bf16 v[16:19], v[172:175], v[206:209], v[16:19]
	v_mfma_f32_16x16x32_bf16 v[4:7], v[144:147], v[214:217], v[4:7]
	v_mfma_f32_16x16x32_bf16 v[0:3], v[172:175], v[214:217], v[0:3]
	v_mfma_f32_16x16x32_bf16 v[52:55], v[148:151], v[194:197], v[52:55]
	v_mfma_f32_16x16x32_bf16 v[48:51], v[176:179], v[194:197], v[48:51]
	v_mfma_f32_16x16x32_bf16 v[36:39], v[148:151], v[202:205], v[36:39]
	v_mfma_f32_16x16x32_bf16 v[32:35], v[176:179], v[202:205], v[32:35]
	v_mfma_f32_16x16x32_bf16 v[20:23], v[148:151], v[210:213], v[20:23]
	v_mfma_f32_16x16x32_bf16 v[16:19], v[176:179], v[210:213], v[16:19]
	v_mfma_f32_16x16x32_bf16 v[4:7], v[148:151], v[218:221], v[4:7]
	v_mfma_f32_16x16x32_bf16 v[0:3], v[176:179], v[218:221], v[0:3]
	s_setprio 0
	s_barrier
	s_add_i32 s84, 0, 0x18000
	s_add_i32 s85, 0, 0x1c000
	v_add_u32_e32 v140, s84, v186
	v_add_u32_e32 v176, s85, v186
	ds_read_b128 v[128:131], v140
	v_xor_b32_e32 v253, 64, v140
	ds_read_b128 v[132:135], v253
	ds_read_b128 v[136:139], v140 offset:2048
	ds_read_b128 v[140:143], v253 offset:2048
	ds_read_b128 v[144:147], v176
	v_xor_b32_e32 v253, 64, v176
	ds_read_b128 v[148:151], v253
	ds_read_b128 v[172:175], v176 offset:2048
	ds_read_b128 v[176:179], v253 offset:2048
	s_add_u32 s54, s60, 0xb0000
	s_addc_u32 s55, s61, 0
	s_mov_b32 m0, s68
	v_lshl_add_u64 v[230:231], s[54:55], 0, v[152:153]
	ds_read_b128 v[180:183], v191 offset:32768
	v_xor_b32_e32 v253, 64, v191
	ds_read_b128 v[194:197], v253 offset:32768
	ds_read_b128 v[198:201], v191 offset:34816
	ds_read_b128 v[202:205], v253 offset:34816
	ds_read_b128 v[206:209], v191 offset:36864
	ds_read_b128 v[210:213], v253 offset:36864
	ds_read_b128 v[214:217], v191 offset:38912
	ds_read_b128 v[218:221], v253 offset:38912
	global_load_lds_dwordx4 v[230:231], off
	v_lshl_add_u64 v[230:231], s[54:55], 0, v[160:161]
	s_mov_b32 m0, s69
	s_nop 0
	global_load_lds_dwordx4 v[230:231], off
	s_waitcnt vmcnt(8)
	s_waitcnt lgkmcnt(0)
	s_barrier
	s_setprio 1
	s_waitcnt lgkmcnt(0)
	v_mfma_f32_16x16x32_bf16 v[124:127], v[128:131], v[180:183], v[124:127]
	v_mfma_f32_16x16x32_bf16 v[120:123], v[136:139], v[180:183], v[120:123]
	v_mfma_f32_16x16x32_bf16 v[108:111], v[128:131], v[198:201], v[108:111]
	v_mfma_f32_16x16x32_bf16 v[104:107], v[136:139], v[198:201], v[104:107]
	v_mfma_f32_16x16x32_bf16 v[92:95], v[128:131], v[206:209], v[92:95]
	v_mfma_f32_16x16x32_bf16 v[88:91], v[136:139], v[206:209], v[88:91]
	v_mfma_f32_16x16x32_bf16 v[76:79], v[128:131], v[214:217], v[76:79]
	v_mfma_f32_16x16x32_bf16 v[72:75], v[136:139], v[214:217], v[72:75]
	v_mfma_f32_16x16x32_bf16 v[124:127], v[132:135], v[194:197], v[124:127]
	v_mfma_f32_16x16x32_bf16 v[120:123], v[140:143], v[194:197], v[120:123]
	v_mfma_f32_16x16x32_bf16 v[108:111], v[132:135], v[202:205], v[108:111]
	v_mfma_f32_16x16x32_bf16 v[104:107], v[140:143], v[202:205], v[104:107]
	v_mfma_f32_16x16x32_bf16 v[92:95], v[132:135], v[210:213], v[92:95]
	v_mfma_f32_16x16x32_bf16 v[88:91], v[140:143], v[210:213], v[88:91]
	v_mfma_f32_16x16x32_bf16 v[76:79], v[132:135], v[218:221], v[76:79]
	v_mfma_f32_16x16x32_bf16 v[72:75], v[140:143], v[218:221], v[72:75]
	s_setprio 0
	s_setprio 1
	v_mfma_f32_16x16x32_bf16 v[116:119], v[144:147], v[180:183], v[116:119]
	v_mfma_f32_16x16x32_bf16 v[112:115], v[172:175], v[180:183], v[112:115]
	v_mfma_f32_16x16x32_bf16 v[100:103], v[144:147], v[198:201], v[100:103]
	v_mfma_f32_16x16x32_bf16 v[96:99], v[172:175], v[198:201], v[96:99]
	v_mfma_f32_16x16x32_bf16 v[84:87], v[144:147], v[206:209], v[84:87]
	v_mfma_f32_16x16x32_bf16 v[80:83], v[172:175], v[206:209], v[80:83]
	v_mfma_f32_16x16x32_bf16 v[68:71], v[144:147], v[214:217], v[68:71]
	v_mfma_f32_16x16x32_bf16 v[64:67], v[172:175], v[214:217], v[64:67]
	v_mfma_f32_16x16x32_bf16 v[116:119], v[148:151], v[194:197], v[116:119]
	v_mfma_f32_16x16x32_bf16 v[112:115], v[176:179], v[194:197], v[112:115]
	v_mfma_f32_16x16x32_bf16 v[100:103], v[148:151], v[202:205], v[100:103]
	v_mfma_f32_16x16x32_bf16 v[96:99], v[176:179], v[202:205], v[96:99]
	v_mfma_f32_16x16x32_bf16 v[84:87], v[148:151], v[210:213], v[84:87]
	v_mfma_f32_16x16x32_bf16 v[80:83], v[176:179], v[210:213], v[80:83]
	v_mfma_f32_16x16x32_bf16 v[68:71], v[148:151], v[218:221], v[68:71]
	v_mfma_f32_16x16x32_bf16 v[64:67], v[176:179], v[218:221], v[64:67]
	s_setprio 0
	s_barrier
	s_add_i32 s54, s84, s65
	v_lshl_add_u64 v[222:223], v[222:223], 0, s[28:29]
	s_mov_b32 m0, s54
	ds_read_b128 v[180:183], v191 offset:49152
	v_xor_b32_e32 v253, 64, v191
	ds_read_b128 v[194:197], v253 offset:49152
	ds_read_b128 v[198:201], v191 offset:51200
	ds_read_b128 v[202:205], v253 offset:51200
	ds_read_b128 v[206:209], v191 offset:53248
	ds_read_b128 v[210:213], v253 offset:53248
	ds_read_b128 v[214:217], v191 offset:55296
	ds_read_b128 v[218:221], v253 offset:55296
	global_load_lds_dwordx4 v[222:223], off
	s_add_i32 m0, s54, 0x2000
	s_add_u32 s54, s58, 0xb0080
	v_lshl_add_u64 v[222:223], v[224:225], 0, s[28:29]
	s_addc_u32 s55, s59, 0
	s_add_i32 s58, s85, s65
	global_load_lds_dwordx4 v[222:223], off
	v_lshl_add_u64 v[222:223], s[54:55], 0, v[154:155]
	s_mov_b32 m0, s58
	s_nop 0
	global_load_lds_dwordx4 v[222:223], off
	v_lshl_add_u64 v[222:223], s[54:55], 0, v[162:163]
	s_add_i32 m0, s58, 0x2000
	s_nop 0
	global_load_lds_dwordx4 v[222:223], off
	v_lshl_add_u64 v[222:223], v[226:227], 0, s[28:29]
	s_mov_b32 m0, s3
	s_nop 0
	global_load_lds_dwordx4 v[222:223], off
	v_lshl_add_u64 v[222:223], v[228:229], 0, s[28:29]
	s_mov_b32 m0, s71
	s_nop 0
	global_load_lds_dwordx4 v[222:223], off
	s_waitcnt vmcnt(8)
	s_waitcnt lgkmcnt(0)
	s_barrier
	s_setprio 1
	s_waitcnt lgkmcnt(0)
	v_mfma_f32_16x16x32_bf16 v[60:63], v[128:131], v[180:183], v[60:63]
	v_mfma_f32_16x16x32_bf16 v[56:59], v[136:139], v[180:183], v[56:59]
	v_mfma_f32_16x16x32_bf16 v[44:47], v[128:131], v[198:201], v[44:47]
	v_mfma_f32_16x16x32_bf16 v[40:43], v[136:139], v[198:201], v[40:43]
	v_mfma_f32_16x16x32_bf16 v[28:31], v[128:131], v[206:209], v[28:31]
	v_mfma_f32_16x16x32_bf16 v[24:27], v[136:139], v[206:209], v[24:27]
	v_mfma_f32_16x16x32_bf16 v[12:15], v[128:131], v[214:217], v[12:15]
	v_mfma_f32_16x16x32_bf16 v[8:11], v[136:139], v[214:217], v[8:11]
	v_mfma_f32_16x16x32_bf16 v[60:63], v[132:135], v[194:197], v[60:63]
	v_mfma_f32_16x16x32_bf16 v[56:59], v[140:143], v[194:197], v[56:59]
	v_mfma_f32_16x16x32_bf16 v[44:47], v[132:135], v[202:205], v[44:47]
	v_mfma_f32_16x16x32_bf16 v[40:43], v[140:143], v[202:205], v[40:43]
	v_mfma_f32_16x16x32_bf16 v[28:31], v[132:135], v[210:213], v[28:31]
	v_mfma_f32_16x16x32_bf16 v[24:27], v[140:143], v[210:213], v[24:27]
	v_mfma_f32_16x16x32_bf16 v[12:15], v[132:135], v[218:221], v[12:15]
	v_mfma_f32_16x16x32_bf16 v[8:11], v[140:143], v[218:221], v[8:11]
	s_setprio 0
	s_setprio 1
	v_mfma_f32_16x16x32_bf16 v[52:55], v[144:147], v[180:183], v[52:55]
	v_mfma_f32_16x16x32_bf16 v[48:51], v[172:175], v[180:183], v[48:51]
	v_mfma_f32_16x16x32_bf16 v[36:39], v[144:147], v[198:201], v[36:39]
	v_mfma_f32_16x16x32_bf16 v[32:35], v[172:175], v[198:201], v[32:35]
	v_mfma_f32_16x16x32_bf16 v[20:23], v[144:147], v[206:209], v[20:23]
	v_mfma_f32_16x16x32_bf16 v[16:19], v[172:175], v[206:209], v[16:19]
	v_mfma_f32_16x16x32_bf16 v[4:7], v[144:147], v[214:217], v[4:7]
	v_mfma_f32_16x16x32_bf16 v[0:3], v[172:175], v[214:217], v[0:3]
	v_mfma_f32_16x16x32_bf16 v[52:55], v[148:151], v[194:197], v[52:55]
	v_mfma_f32_16x16x32_bf16 v[48:51], v[176:179], v[194:197], v[48:51]
	v_mfma_f32_16x16x32_bf16 v[36:39], v[148:151], v[202:205], v[36:39]
	v_mfma_f32_16x16x32_bf16 v[32:35], v[176:179], v[202:205], v[32:35]
	v_mfma_f32_16x16x32_bf16 v[20:23], v[148:151], v[210:213], v[20:23]
	v_mfma_f32_16x16x32_bf16 v[16:19], v[176:179], v[210:213], v[16:19]
	v_mfma_f32_16x16x32_bf16 v[4:7], v[148:151], v[218:221], v[4:7]
	v_mfma_f32_16x16x32_bf16 v[0:3], v[176:179], v[218:221], v[0:3]
	s_setprio 0
	s_barrier
	s_add_i32 s83, s83, 2
	s_add_u32 s81, s81, 0x100
	s_addc_u32 s82, s82, 0
	s_cmp_gt_u32 s83, 41
	s_mov_b64 s[54:55], s[56:57]
	s_cbranch_scc0 .LBB0_159
	s_and_b64 vcc, exec, s[30:31]
	s_cbranch_vccz .LBB0_162
	s_barrier

.LBB0_242:
	s_andn2_b64 vcc, exec, s[8:9]
	s_cbranch_vccnz .LBB0_298
	v_ashrrev_i32_e32 v1, 31, v8
	v_lshrrev_b32_e32 v1, 26, v1
	v_add_u32_e32 v1, v8, v1
	v_ashrrev_i32_e32 v9, 6, v1
	v_bfe_i32 v1, v8, 27, 1
	v_lshlrev_b32_e32 v0, 4, v8
	v_lshrrev_b32_e32 v1, 22, v1
	v_add_u32_e32 v1, v0, v1
	v_and_b32_e32 v1, 0xfffffc00, v1
	v_sub_u32_e32 v1, v0, v1
	v_lshrrev_b32_e32 v2, 4, v1
	v_bitop3_b32 v1, v2, v1, 32 bitop3:0x6c
	v_ashrrev_i32_e32 v3, 31, v1
	v_lshrrev_b32_e32 v3, 26, v3
	v_add_u32_e32 v3, v1, v3
	v_lshlrev_b32_e32 v2, 3, v9
	v_ashrrev_i32_e32 v10, 6, v3
	v_and_b32_e32 v3, 0xc0, v3
	v_and_b32_e32 v2, -16, v2
	v_sub_u32_e32 v1, v1, v3
	v_mov_b32_e32 v3, 1
	v_add_u32_e32 v2, v10, v2
	v_ashrrev_i16_sdwa v1, v3, sext(v1) dst_sel:DWORD dst_unused:UNUSED_PAD src0_sel:DWORD src1_sel:BYTE_0
	v_lshlrev_b32_e32 v4, 5, v9
	v_bfe_i32 v11, v1, 0, 16
	v_lshlrev_b32_e32 v1, 1, v2
	v_lshrrev_b32_e32 v5, 2, v2
	v_and_b32_e32 v6, 3, v10
	s_mov_b32 s9, 0x1fffe0
	v_and_b32_e32 v4, 32, v4
	v_and_b32_e32 v1, 24, v1
	v_and_b32_e32 v5, 4, v5
	v_and_or_b32 v6, v2, s9, v6
	v_or3_b32 v1, v6, v5, v1
	v_add_lshl_u32 v4, v4, v11, 1
	v_add_u32_e32 v0, 0x2000, v0
	v_lshl_add_u32 v162, v1, 11, v4
	v_lshrrev_b32_e32 v250, 3, v157
	v_and_b32_e32 v251, 6, v250
	v_and_b32_e32 v252, 7, v157
	v_xor_b32_e32 v251, v251, v252
	v_lshlrev_b32_e32 v251, 4, v251
	v_and_b32_e32 v252, 12, v250
	v_lshlrev_b32_e32 v252, 1, v252
	v_and_b32_e32 v253, 16, v250
	v_lshrrev_b32_e32 v253, 2, v253
	v_or_b32_e32 v252, v252, v253
	v_and_b32_e32 v253, 35, v250
	v_or_b32_e32 v250, v252, v253
	v_mul_u32_u24_e32 v250, 0x800, v250
	v_add_u32_e32 v162, v250, v251
	v_ashrrev_i32_e32 v1, 31, v0
	v_lshrrev_b32_e32 v1, 22, v1
	v_add_u32_e32 v1, v0, v1
	v_ashrrev_i32_e32 v12, 10, v1
	v_mul_i32_i24_e32 v1, 0x400, v12
	v_sub_u32_e32 v0, v0, v1
	v_lshrrev_b32_e32 v1, 4, v0
	v_bitop3_b32 v0, v1, v0, 32 bitop3:0x6c
	v_lshl_add_u32 v160, v2, 11, v4
	v_lshrrev_b32_e32 v250, 3, v157
	v_and_b32_e32 v251, 6, v250
	v_and_b32_e32 v252, 7, v157
	v_xor_b32_e32 v251, v251, v252
	v_lshlrev_b32_e32 v251, 4, v251
	v_mul_u32_u24_e32 v250, 0x800, v250
	v_add_u32_e32 v160, v250, v251
	v_ashrrev_i32_e32 v2, 31, v0
	v_lshrrev_b32_e32 v2, 26, v2
	s_waitcnt lgkmcnt(0)
	s_add_u32 s35, s16, 0x6000000
	v_add_u32_e32 v2, v0, v2
	s_addc_u32 s47, s17, 0
	v_lshlrev_b32_e32 v1, 3, v12
	v_ashrrev_i32_e32 v13, 6, v2
	v_and_b32_e32 v2, 0xc0, v2
	s_add_u32 s49, s16, 0x4600000
	v_and_b32_e32 v1, -16, v1
	v_sub_u32_e32 v0, v0, v2
	s_addc_u32 s70, s17, 0
	s_ashr_i32 s8, s3, 6
	v_add_u32_e32 v1, v13, v1
	v_ashrrev_i16_sdwa v0, v3, sext(v0) dst_sel:DWORD dst_unused:UNUSED_PAD src0_sel:DWORD src1_sel:BYTE_0
	v_and_b32_e32 v3, 3, v13
	s_ashr_i32 s15, s14, 31
	s_ashr_i32 s21, s20, 31
	v_and_or_b32 v3, v1, s9, v3
	s_ashr_i32 s9, s3, 8
	s_lshl_b32 s71, s8, 10
	s_lshl_b64 s[10:11], s[14:15], 19
	s_lshl_b64 s[12:13], s[20:21], 19
	s_add_u32 s66, s49, s12
	v_lshlrev_b32_e32 v4, 5, v12
	v_bfe_i32 v14, v0, 0, 16
	v_lshlrev_b32_e32 v0, 1, v1
	v_lshrrev_b32_e32 v2, 2, v1
	s_addc_u32 s67, s70, s13
	s_add_i32 s74, s71, 0
	v_and_b32_e32 v4, 32, v4
	v_and_b32_e32 v0, 24, v0
	v_and_b32_e32 v2, 4, v2
	s_add_i32 m0, s74, 0x10000
	v_or3_b32 v0, v3, v2, v0
	v_add_lshl_u32 v2, v4, v14, 1
	global_load_lds_dwordx4 v162, s[66:67]
	s_add_i32 m0, s74, 0x12000
	v_lshl_add_u32 v166, v0, 11, v2
	v_lshrrev_b32_e32 v250, 3, v157
	v_and_b32_e32 v251, 6, v250
	v_and_b32_e32 v252, 7, v157
	v_xor_b32_e32 v251, v251, v252
	v_lshlrev_b32_e32 v251, 4, v251
	v_and_b32_e32 v252, 12, v250
	v_lshlrev_b32_e32 v252, 1, v252
	v_and_b32_e32 v253, 16, v250
	v_lshrrev_b32_e32 v253, 2, v253
	v_or_b32_e32 v252, v252, v253
	v_and_b32_e32 v253, 35, v250
	v_or_b32_e32 v250, v252, v253
	v_mul_u32_u24_e32 v250, 0x800, v250
	v_add_u32_e32 v166, v250, v251
	v_add_u32_e32 v166, 0x20000, v166
	s_add_u32 s12, s66, 0x40000
	global_load_lds_dwordx4 v166, s[66:67]
	s_addc_u32 s13, s67, 0
	s_add_i32 m0, s74, 0x14000
	v_lshl_add_u32 v164, v1, 11, v2
	v_lshrrev_b32_e32 v250, 3, v157
	v_and_b32_e32 v251, 6, v250
	v_and_b32_e32 v252, 7, v157
	v_xor_b32_e32 v251, v251, v252
	v_lshlrev_b32_e32 v251, 4, v251
	v_mul_u32_u24_e32 v250, 0x800, v250
	v_add_u32_e32 v164, v250, v251
	v_add_u32_e32 v164, 0x20000, v164
	global_load_lds_dwordx4 v162, s[12:13]
	s_add_i32 m0, s74, 0x16000
	s_add_u32 s68, s35, s10
	s_addc_u32 s69, s47, s11
	s_add_i32 s75, s74, 0x2000
	global_load_lds_dwordx4 v166, s[12:13]
	s_mov_b32 m0, s74
	s_add_u32 s10, s68, 0x40000
	global_load_lds_dwordx4 v160, s[68:69]
	s_mov_b32 m0, s75
	s_addc_u32 s11, s69, 0
	s_add_i32 s76, s74, 0x4000
	global_load_lds_dwordx4 v164, s[68:69]
	s_mov_b32 m0, s76
	s_add_i32 s77, s74, 0x6000
	global_load_lds_dwordx4 v160, s[10:11]
	s_mov_b32 m0, s77
	v_mov_b32_e32 v163, 0
	global_load_lds_dwordx4 v164, s[10:11]
	v_mov_b32_e32 v167, v163
	v_mov_b32_e32 v161, v163
	v_mov_b32_e32 v165, v163
	s_cmp_eq_u32 s9, 1
	s_mov_b32 s21, 0
	v_lshl_add_u64 v[6:7], s[66:67], 0, v[162:163]
	v_lshl_add_u64 v[4:5], s[66:67], 0, v[166:167]
	v_lshl_add_u64 v[0:1], s[68:69], 0, v[160:161]
	s_cselect_b64 s[22:23], -1, 0
	s_cmp_lg_u32 s9, 1
	v_lshl_add_u64 v[2:3], s[68:69], 0, v[164:165]
	s_cbranch_scc1 .LBB0_245
	s_barrier
.LBB0_245:
	s_add_u32 s26, s16, 0x100000
	s_mov_b64 s[28:29], 0x80
	s_addc_u32 s27, s17, 0
	s_and_b32 s12, s8, 3
	s_add_i32 m0, s74, 0x18000
	v_lshl_add_u64 v[6:7], v[6:7], 0, s[28:29]
	s_lshl_b32 s13, s9, 13
	s_lshl_b32 s15, s12, 12
	s_waitcnt vmcnt(2)
	s_barrier
	global_load_lds_dwordx4 v[6:7], off
	v_lshl_add_u64 v[4:5], v[4:5], 0, s[28:29]
	s_add_i32 m0, s74, 0x1a000
	s_add_i32 s78, s74, 0x8000
	s_add_i32 s79, s74, 0xa000
	global_load_lds_dwordx4 v[4:5], off
	v_lshl_add_u64 v[0:1], v[0:1], 0, s[28:29]
	s_mov_b32 m0, s78
	s_add_u32 s10, s66, 0x40080
	global_load_lds_dwordx4 v[0:1], off
	v_lshl_add_u64 v[0:1], v[2:3], 0, s[28:29]
	s_mov_b32 m0, s79
	s_addc_u32 s11, s67, 0
	global_load_lds_dwordx4 v[0:1], off
	s_add_i32 m0, s74, 0x1c000
	v_lshl_add_u64 v[0:1], s[10:11], 0, v[162:163]
	global_load_lds_dwordx4 v[0:1], off
	v_lshl_add_u64 v[0:1], s[10:11], 0, v[166:167]
	s_add_i32 m0, s74, 0x1e000
	v_and_b32_e32 v3, 48, v8
	global_load_lds_dwordx4 v[0:1], off
	v_and_b32_e32 v1, 15, v8
	v_lshl_or_b32 v180, s9, 6, v1
	v_lshl_or_b32 v1, v1, 6, v3
	v_lshlrev_b32_e32 v3, 2, v8
	v_and_b32_e32 v3, 32, v3
	v_bitop3_b32 v4, v1, s13, v3 bitop3:0xde
	v_bitop3_b32 v181, v1, s15, v3 bitop3:0xde
	v_and_b32_e32 v250, 15, v157
	v_bfe_u32 v251, v157, 4, 2
	v_and_b32_e32 v252, 2, v250
	v_xor_b32_e32 v251, v251, v252
	v_and_b32_e32 v252, 4, v250
	v_lshlrev_b32_e32 v252, 4, v252
	v_lshl_or_b32 v251, v251, 4, v252
	v_lshl_or_b32 v250, v250, 7, v251
	v_bfe_u32 v253, v157, 6, 2
	v_lshl_or_b32 v181, v253, 12, v250
	s_cmp_lt_i32 s8, 4
	s_movk_i32 s8, 0xffc0
	v_mov_b32_e32 v1, s3
	v_lshrrev_b32_e32 v2, 1, v8
	v_bfi_b32 v182, s8, v1, v8
	v_lshlrev_b32_e32 v1, 14, v12
	v_and_b32_e32 v2, 24, v2
	v_and_b32_e32 v1, 0xffff8000, v1
	v_lshl_or_b32 v183, s12, 5, v2
	v_lshl_add_u32 v1, v13, 11, v1
	v_and_b32_e32 v2, 1, v12
	v_lshl_or_b32 v1, v2, 6, v1
	s_cselect_b64 s[30:31], -1, 0
	s_cmpk_lt_u32 s3, 0x100
	v_lshl_add_u32 v168, v14, 1, v1
	v_lshrrev_b32_e32 v250, 3, v157
	v_and_b32_e32 v251, 6, v250
	v_and_b32_e32 v252, 7, v157
	v_xor_b32_e32 v251, v251, v252
	v_lshlrev_b32_e32 v251, 4, v251
	v_mul_u32_u24_e32 v250, 0x800, v250
	v_add_u32_e32 v168, v250, v251
	v_add_u32_e32 v168, 0x20000, v168
	v_lshlrev_b32_e32 v1, 14, v9
	v_and_b32_e32 v0, 63, v8
	s_cselect_b64 s[44:45], -1, 0
	s_lshl_b32 s3, s12, 2
	v_and_b32_e32 v1, 0xffff8000, v1
	s_waitcnt vmcnt(6)
	v_cmp_gt_u32_e64 s[8:9], 16, v0
	v_lshlrev_b32_e32 v0, 4, v157
	s_add_i32 s3, s3, 0
	v_lshl_add_u32 v1, v10, 11, v1
	v_and_b32_e32 v2, 1, v9
	s_movk_i32 s10, 0x100
	v_lshlrev_b32_e32 v185, 4, v180
	s_add_i32 s3, s3, 0x20000
	v_lshl_or_b32 v1, v2, 6, v1
	v_add_u32_e32 v0, 0, v0
	v_cmp_gt_u32_e64 s[10:11], s10, v157
	s_ashr_i32 s80, s42, 31
	s_mov_b32 s81, s42
	s_ashr_i32 s82, s2, 31
	v_add_u32_e32 v186, s3, v185
	v_mov_b32_e32 v169, v163
	v_lshl_add_u32 v170, v11, 1, v1
	v_lshrrev_b32_e32 v250, 3, v157
	v_and_b32_e32 v251, 6, v250
	v_and_b32_e32 v252, 7, v157
	v_xor_b32_e32 v251, v251, v252
	v_lshlrev_b32_e32 v251, 4, v251
	v_mul_u32_u24_e32 v250, 0x800, v250
	v_add_u32_e32 v170, v250, v251
	v_mov_b32_e32 v171, v163
	v_mov_b64_e32 v[172:173], 0x800
	v_mov_b64_e32 v[174:175], 0x7ff
	s_add_i32 s83, 0, 0x10000
	s_add_i32 s84, 0, 0x14000
	v_add_u32_e32 v187, 0, v4
	v_and_b32_e32 v250, 15, v157
	v_bfe_u32 v251, v157, 4, 2
	v_and_b32_e32 v252, 2, v250
	v_xor_b32_e32 v251, v251, v252
	v_and_b32_e32 v252, 4, v250
	v_lshlrev_b32_e32 v252, 4, v252
	v_lshl_or_b32 v251, v251, 4, v252
	v_lshl_or_b32 v250, v250, 7, v251
	v_lshrrev_b32_e32 v253, 8, v157
	v_lshl_or_b32 v187, v253, 13, v250
	s_mov_b32 s85, 0xa000000
	v_mov_b32_e32 v188, 0x358637bd
	s_mov_b32 s46, 0x3dd2d3e7
	s_mov_b32 s48, 0xc0135761
	s_mov_b64 s[50:51], 0x80000
	s_mov_b32 s86, 0x80000
	s_mov_b64 s[52:53], 0x90000
	s_mov_b32 s87, 0x90000
	s_mov_b64 s[54:55], 0xa0000
	s_mov_b32 s88, 0xa0000
	s_mov_b64 s[56:57], 0xb0000
	s_mov_b32 s89, 0xb0000
	v_add_u32_e32 v189, 0x20000, v0
	s_mov_b32 s90, s21
	s_barrier
	s_branch .LBB0_248

.LBB0_254:
	s_ashr_i32 s61, s60, 31
	s_lshl_b64 s[62:63], s[60:61], 19
	s_add_u32 s62, s35, s62
	s_addc_u32 s63, s47, s63
	s_and_b64 s[64:65], s[12:13], exec
	s_cselect_b32 s3, s63, s69
	s_cselect_b32 s61, s62, s68
	s_ashr_i32 s59, s58, 31
	s_lshl_b64 s[64:65], s[58:59], 19
	s_add_u32 s64, s49, s64
	s_addc_u32 s65, s70, s65
	s_and_b64 s[92:93], s[12:13], exec
	s_cselect_b32 s91, s65, s67
	s_cselect_b32 s92, s64, s66
	s_lshl_b32 s59, s14, 8
	v_add_u32_e32 v0, s59, v182
	s_add_u32 s93, s66, 0x100
	s_waitcnt lgkmcnt(0)
	v_ashrrev_i32_e32 v1, 31, v0
	s_addc_u32 s94, s67, 0
	v_lshl_add_u64 v[72:73], v[0:1], 4, s[26:27]
	s_add_u32 s14, s68, 0x40080
	s_addc_u32 s15, s69, 0
	s_mov_b32 s95, -2
	s_mov_b64 s[66:67], 0
	s_cmp_eq_u32 s90, 1
	s_cbranch_scc1 .Lfa_2
	v_add_u32_e32 v74, s83, v181
	ds_read_b128 v[88:91], v74
	v_xor_b32_e32 v253, 64, v74
	ds_read_b128 v[108:111], v253
	ds_read_b128 v[128:131], v74 offset:2048
	ds_read_b128 v[144:147], v253 offset:2048
	v_add_u32_e32 v74, s84, v181
	ds_read_b128 v[148:151], v74
	v_xor_b32_e32 v253, 64, v74
	ds_read_b128 v[152:155], v253
	ds_read_b128 v[176:179], v74 offset:2048
	ds_read_b128 v[190:193], v253 offset:2048
	s_add_u32 s68, s14, 0xfffc0080
	s_addc_u32 s69, s15, -1
	s_and_b64 s[66:67], s[66:67], exec
	s_cselect_b32 s69, s3, s69
	s_cselect_b32 s68, s61, s68
	s_cselect_b32 s67, s91, s94
	s_cselect_b32 s66, s92, s93
	v_lshl_add_u64 v[74:75], s[14:15], 0, v[170:171]
	s_add_i32 m0, s74, 0xc000
	ds_read_b128 v[194:197], v187
	v_xor_b32_e32 v253, 64, v187
	ds_read_b128 v[198:201], v253
	ds_read_b128 v[202:205], v187 offset:2048
	ds_read_b128 v[206:209], v253 offset:2048
	ds_read_b128 v[210:213], v187 offset:4096
	ds_read_b128 v[214:217], v253 offset:4096
	ds_read_b128 v[218:221], v187 offset:6144
	ds_read_b128 v[222:225], v253 offset:6144
	global_load_lds_dwordx4 v[74:75], off
	v_lshl_add_u64 v[74:75], s[14:15], 0, v[168:169]
	s_add_i32 m0, s74, 0xe000
	s_nop 0
	global_load_lds_dwordx4 v[74:75], off
	s_waitcnt vmcnt(24)
	s_waitcnt lgkmcnt(0)
	s_barrier
	s_setprio 1
	s_waitcnt lgkmcnt(0)
	v_mfma_f32_16x16x32_bf16 v[140:143], v[88:91], v[194:197], 0
	v_mfma_f32_16x16x32_bf16 v[136:139], v[128:131], v[194:197], 0
	v_mfma_f32_16x16x32_bf16 v[120:123], v[88:91], v[202:205], 0
	v_mfma_f32_16x16x32_bf16 v[116:119], v[128:131], v[202:205], 0
	v_mfma_f32_16x16x32_bf16 v[100:103], v[88:91], v[210:213], 0
	v_mfma_f32_16x16x32_bf16 v[96:99], v[128:131], v[210:213], 0
	v_mfma_f32_16x16x32_bf16 v[80:83], v[88:91], v[218:221], 0
	v_mfma_f32_16x16x32_bf16 v[74:77], v[128:131], v[218:221], 0
	v_mfma_f32_16x16x32_bf16 v[140:143], v[108:111], v[198:201], v[140:143]
	v_mfma_f32_16x16x32_bf16 v[136:139], v[144:147], v[198:201], v[136:139]
	v_mfma_f32_16x16x32_bf16 v[120:123], v[108:111], v[206:209], v[120:123]
	v_mfma_f32_16x16x32_bf16 v[116:119], v[144:147], v[206:209], v[116:119]
	v_mfma_f32_16x16x32_bf16 v[100:103], v[108:111], v[214:217], v[100:103]
	v_mfma_f32_16x16x32_bf16 v[96:99], v[144:147], v[214:217], v[96:99]
	v_mfma_f32_16x16x32_bf16 v[80:83], v[108:111], v[222:225], v[80:83]
	v_mfma_f32_16x16x32_bf16 v[74:77], v[144:147], v[222:225], v[74:77]
	s_setprio 0
	s_setprio 1
	v_mfma_f32_16x16x32_bf16 v[132:135], v[148:151], v[194:197], 0
	v_mfma_f32_16x16x32_bf16 v[124:127], v[176:179], v[194:197], 0
	v_mfma_f32_16x16x32_bf16 v[112:115], v[148:151], v[202:205], 0
	v_mfma_f32_16x16x32_bf16 v[104:107], v[176:179], v[202:205], 0
	v_mfma_f32_16x16x32_bf16 v[92:95], v[148:151], v[210:213], 0
	v_mfma_f32_16x16x32_bf16 v[84:87], v[176:179], v[210:213], 0
	v_mfma_f32_16x16x32_bf16 v[68:71], v[148:151], v[218:221], 0
	v_mfma_f32_16x16x32_bf16 v[64:67], v[176:179], v[218:221], 0
	v_mfma_f32_16x16x32_bf16 v[132:135], v[152:155], v[198:201], v[132:135]
	v_mfma_f32_16x16x32_bf16 v[124:127], v[190:193], v[198:201], v[124:127]
	v_mfma_f32_16x16x32_bf16 v[112:115], v[152:155], v[206:209], v[112:115]
	v_mfma_f32_16x16x32_bf16 v[104:107], v[190:193], v[206:209], v[104:107]
	v_mfma_f32_16x16x32_bf16 v[92:95], v[152:155], v[214:217], v[92:95]
	v_mfma_f32_16x16x32_bf16 v[84:87], v[190:193], v[214:217], v[84:87]
	v_mfma_f32_16x16x32_bf16 v[68:71], v[152:155], v[222:225], v[68:71]
	v_mfma_f32_16x16x32_bf16 v[64:67], v[190:193], v[222:225], v[64:67]
	s_setprio 0
	s_barrier
	s_add_i32 s96, s83, s71
	v_lshl_add_u64 v[226:227], s[66:67], 0, v[162:163]
	s_mov_b32 m0, s96
	ds_read_b128 v[194:197], v187 offset:16384
	v_xor_b32_e32 v253, 64, v187
	ds_read_b128 v[198:201], v253 offset:16384
	ds_read_b128 v[202:205], v187 offset:18432
	ds_read_b128 v[206:209], v253 offset:18432
	ds_read_b128 v[210:213], v187 offset:20480
	ds_read_b128 v[214:217], v253 offset:20480
	ds_read_b128 v[218:221], v187 offset:22528
	ds_read_b128 v[222:225], v253 offset:22528
	global_load_lds_dwordx4 v[226:227], off
	s_add_i32 m0, s96, 0x2000
	s_add_u32 s96, s66, 0x40000
	v_lshl_add_u64 v[228:229], s[66:67], 0, v[166:167]
	s_addc_u32 s97, s67, 0
	s_add_i32 vcc_lo, s84, s71
	global_load_lds_dwordx4 v[228:229], off
	v_lshl_add_u64 v[78:79], s[96:97], 0, v[162:163]
	s_mov_b32 m0, vcc_lo
	v_lshl_add_u64 v[230:231], s[68:69], 0, v[160:161]
	global_load_lds_dwordx4 v[78:79], off
	v_lshl_add_u64 v[78:79], s[96:97], 0, v[166:167]
	s_add_i32 m0, vcc_lo, 0x2000
	v_lshl_add_u64 v[232:233], s[68:69], 0, v[164:165]
	global_load_lds_dwordx4 v[78:79], off
	s_mov_b32 m0, s74
	s_nop 0
	global_load_lds_dwordx4 v[230:231], off
	s_mov_b32 m0, s75
	s_nop 0
	global_load_lds_dwordx4 v[232:233], off
	s_waitcnt vmcnt(24)
	s_waitcnt lgkmcnt(0)
	s_barrier
	s_setprio 1
	s_waitcnt lgkmcnt(0)
	v_mfma_f32_16x16x32_bf16 v[60:63], v[88:91], v[194:197], 0
	v_mfma_f32_16x16x32_bf16 v[56:59], v[128:131], v[194:197], 0
	v_mfma_f32_16x16x32_bf16 v[44:47], v[88:91], v[202:205], 0
	v_mfma_f32_16x16x32_bf16 v[40:43], v[128:131], v[202:205], 0
	v_mfma_f32_16x16x32_bf16 v[28:31], v[88:91], v[210:213], 0
	v_mfma_f32_16x16x32_bf16 v[24:27], v[128:131], v[210:213], 0
	v_mfma_f32_16x16x32_bf16 v[12:15], v[88:91], v[218:221], 0
	v_mfma_f32_16x16x32_bf16 v[8:11], v[128:131], v[218:221], 0
	v_mfma_f32_16x16x32_bf16 v[60:63], v[108:111], v[198:201], v[60:63]
	v_mfma_f32_16x16x32_bf16 v[56:59], v[144:147], v[198:201], v[56:59]
	v_mfma_f32_16x16x32_bf16 v[44:47], v[108:111], v[206:209], v[44:47]
	v_mfma_f32_16x16x32_bf16 v[40:43], v[144:147], v[206:209], v[40:43]
	v_mfma_f32_16x16x32_bf16 v[28:31], v[108:111], v[214:217], v[28:31]
	v_mfma_f32_16x16x32_bf16 v[24:27], v[144:147], v[214:217], v[24:27]
	v_mfma_f32_16x16x32_bf16 v[12:15], v[108:111], v[222:225], v[12:15]
	v_mfma_f32_16x16x32_bf16 v[8:11], v[144:147], v[222:225], v[8:11]
	s_setprio 0
	s_setprio 1
	v_mfma_f32_16x16x32_bf16 v[52:55], v[148:151], v[194:197], 0
	v_mfma_f32_16x16x32_bf16 v[48:51], v[176:179], v[194:197], 0
	v_mfma_f32_16x16x32_bf16 v[36:39], v[148:151], v[202:205], 0
	v_mfma_f32_16x16x32_bf16 v[32:35], v[176:179], v[202:205], 0
	v_mfma_f32_16x16x32_bf16 v[20:23], v[148:151], v[210:213], 0
	v_mfma_f32_16x16x32_bf16 v[16:19], v[176:179], v[210:213], 0
	v_mfma_f32_16x16x32_bf16 v[4:7], v[148:151], v[218:221], 0
	v_mfma_f32_16x16x32_bf16 v[0:3], v[176:179], v[218:221], 0
	v_mfma_f32_16x16x32_bf16 v[52:55], v[152:155], v[198:201], v[52:55]
	v_mfma_f32_16x16x32_bf16 v[48:51], v[190:193], v[198:201], v[48:51]
	v_mfma_f32_16x16x32_bf16 v[36:39], v[152:155], v[206:209], v[36:39]
	v_mfma_f32_16x16x32_bf16 v[32:35], v[190:193], v[206:209], v[32:35]
	v_mfma_f32_16x16x32_bf16 v[20:23], v[152:155], v[214:217], v[20:23]
	v_mfma_f32_16x16x32_bf16 v[16:19], v[190:193], v[214:217], v[16:19]
	v_mfma_f32_16x16x32_bf16 v[4:7], v[152:155], v[222:225], v[4:7]
	v_mfma_f32_16x16x32_bf16 v[0:3], v[190:193], v[222:225], v[0:3]
	s_setprio 0
	s_barrier
	s_add_i32 s96, 0, 0x18000
	v_add_u32_e32 v78, s96, v181
	s_add_i32 s97, 0, 0x1c000
	ds_read_b128 v[88:91], v78
	v_xor_b32_e32 v253, 64, v78
	ds_read_b128 v[108:111], v253
	ds_read_b128 v[128:131], v78 offset:2048
	ds_read_b128 v[144:147], v253 offset:2048
	v_add_u32_e32 v78, s97, v181
	ds_read_b128 v[148:151], v78
	v_xor_b32_e32 v253, 64, v78
	ds_read_b128 v[152:155], v253
	ds_read_b128 v[176:179], v78 offset:2048
	ds_read_b128 v[190:193], v253 offset:2048
	s_add_u32 s68, s68, 0x40000
	s_addc_u32 s69, s69, 0
	s_mov_b32 m0, s76
	v_lshl_add_u64 v[78:79], s[68:69], 0, v[160:161]
	ds_read_b128 v[194:197], v187 offset:32768
	v_xor_b32_e32 v253, 64, v187
	ds_read_b128 v[198:201], v253 offset:32768
	ds_read_b128 v[202:205], v187 offset:34816
	ds_read_b128 v[206:209], v253 offset:34816
	ds_read_b128 v[210:213], v187 offset:36864
	ds_read_b128 v[214:217], v253 offset:36864
	ds_read_b128 v[218:221], v187 offset:38912
	ds_read_b128 v[222:225], v253 offset:38912
	global_load_lds_dwordx4 v[78:79], off
	v_lshl_add_u64 v[78:79], s[68:69], 0, v[164:165]
	s_mov_b32 m0, s77
	s_nop 0
	global_load_lds_dwordx4 v[78:79], off
	s_waitcnt vmcnt(8)
	s_waitcnt lgkmcnt(0)
	s_barrier
	s_setprio 1
	s_waitcnt lgkmcnt(0)
	v_mfma_f32_16x16x32_bf16 v[140:143], v[88:91], v[194:197], v[140:143]
	v_mfma_f32_16x16x32_bf16 v[136:139], v[128:131], v[194:197], v[136:139]
	v_mfma_f32_16x16x32_bf16 v[120:123], v[88:91], v[202:205], v[120:123]
	v_mfma_f32_16x16x32_bf16 v[116:119], v[128:131], v[202:205], v[116:119]
	v_mfma_f32_16x16x32_bf16 v[100:103], v[88:91], v[210:213], v[100:103]
	v_mfma_f32_16x16x32_bf16 v[96:99], v[128:131], v[210:213], v[96:99]
	v_mfma_f32_16x16x32_bf16 v[78:81], v[88:91], v[218:221], v[80:83]
	v_mfma_f32_16x16x32_bf16 v[74:77], v[128:131], v[218:221], v[74:77]
	v_mfma_f32_16x16x32_bf16 v[140:143], v[108:111], v[198:201], v[140:143]
	v_mfma_f32_16x16x32_bf16 v[136:139], v[144:147], v[198:201], v[136:139]
	v_mfma_f32_16x16x32_bf16 v[120:123], v[108:111], v[206:209], v[120:123]
	v_mfma_f32_16x16x32_bf16 v[116:119], v[144:147], v[206:209], v[116:119]
	v_mfma_f32_16x16x32_bf16 v[100:103], v[108:111], v[214:217], v[100:103]
	v_mfma_f32_16x16x32_bf16 v[96:99], v[144:147], v[214:217], v[96:99]
	v_mfma_f32_16x16x32_bf16 v[80:83], v[108:111], v[222:225], v[78:81]
	v_mfma_f32_16x16x32_bf16 v[76:79], v[144:147], v[222:225], v[74:77]
	s_setprio 0
	s_setprio 1
	v_mfma_f32_16x16x32_bf16 v[132:135], v[148:151], v[194:197], v[132:135]
	v_mfma_f32_16x16x32_bf16 v[124:127], v[176:179], v[194:197], v[124:127]
	v_mfma_f32_16x16x32_bf16 v[112:115], v[148:151], v[202:205], v[112:115]
	v_mfma_f32_16x16x32_bf16 v[104:107], v[176:179], v[202:205], v[104:107]
	v_mfma_f32_16x16x32_bf16 v[92:95], v[148:151], v[210:213], v[92:95]
	v_mfma_f32_16x16x32_bf16 v[84:87], v[176:179], v[210:213], v[84:87]
	v_mfma_f32_16x16x32_bf16 v[68:71], v[148:151], v[218:221], v[68:71]
	v_mfma_f32_16x16x32_bf16 v[64:67], v[176:179], v[218:221], v[64:67]
	v_mfma_f32_16x16x32_bf16 v[132:135], v[152:155], v[198:201], v[132:135]
	v_mfma_f32_16x16x32_bf16 v[124:127], v[190:193], v[198:201], v[124:127]
	v_mfma_f32_16x16x32_bf16 v[112:115], v[152:155], v[206:209], v[112:115]
	v_mfma_f32_16x16x32_bf16 v[104:107], v[190:193], v[206:209], v[104:107]
	v_mfma_f32_16x16x32_bf16 v[92:95], v[152:155], v[214:217], v[92:95]
	v_mfma_f32_16x16x32_bf16 v[84:87], v[190:193], v[214:217], v[84:87]
	v_mfma_f32_16x16x32_bf16 v[68:71], v[152:155], v[222:225], v[68:71]
	v_mfma_f32_16x16x32_bf16 v[64:67], v[190:193], v[222:225], v[64:67]
	s_setprio 0
	s_barrier
	s_add_i32 s68, s96, s71
	v_lshl_add_u64 v[74:75], v[226:227], 0, s[28:29]
	s_mov_b32 m0, s68
	ds_read_b128 v[194:197], v187 offset:49152
	v_xor_b32_e32 v253, 64, v187
	ds_read_b128 v[198:201], v253 offset:49152
	ds_read_b128 v[202:205], v187 offset:51200
	ds_read_b128 v[206:209], v253 offset:51200
	ds_read_b128 v[210:213], v187 offset:53248
	ds_read_b128 v[214:217], v253 offset:53248
	ds_read_b128 v[218:221], v187 offset:55296
	ds_read_b128 v[222:225], v253 offset:55296
	global_load_lds_dwordx4 v[74:75], off
	s_add_i32 m0, s68, 0x2000
	s_add_u32 s66, s66, 0x40080
	v_lshl_add_u64 v[74:75], v[228:229], 0, s[28:29]
	s_addc_u32 s67, s67, 0
	s_add_i32 s68, s97, s71
	global_load_lds_dwordx4 v[74:75], off
	v_lshl_add_u64 v[74:75], s[66:67], 0, v[162:163]
	s_mov_b32 m0, s68
	s_nop 0
	global_load_lds_dwordx4 v[74:75], off
	v_lshl_add_u64 v[74:75], s[66:67], 0, v[166:167]
	s_add_i32 m0, s68, 0x2000
	s_nop 0
	global_load_lds_dwordx4 v[74:75], off
	v_lshl_add_u64 v[74:75], v[230:231], 0, s[28:29]
	s_mov_b32 m0, s78
	s_nop 0
	global_load_lds_dwordx4 v[74:75], off
	v_lshl_add_u64 v[74:75], v[232:233], 0, s[28:29]
	s_mov_b32 m0, s79
	s_nop 0
	global_load_lds_dwordx4 v[74:75], off
	s_waitcnt vmcnt(8)
	s_waitcnt lgkmcnt(0)
	s_barrier
	s_setprio 1
	s_waitcnt lgkmcnt(0)
	v_mfma_f32_16x16x32_bf16 v[60:63], v[88:91], v[194:197], v[60:63]
	v_mfma_f32_16x16x32_bf16 v[56:59], v[128:131], v[194:197], v[56:59]
	v_mfma_f32_16x16x32_bf16 v[44:47], v[88:91], v[202:205], v[44:47]
	v_mfma_f32_16x16x32_bf16 v[40:43], v[128:131], v[202:205], v[40:43]
	v_mfma_f32_16x16x32_bf16 v[28:31], v[88:91], v[210:213], v[28:31]
	v_mfma_f32_16x16x32_bf16 v[24:27], v[128:131], v[210:213], v[24:27]
	v_mfma_f32_16x16x32_bf16 v[12:15], v[88:91], v[218:221], v[12:15]
	v_mfma_f32_16x16x32_bf16 v[8:11], v[128:131], v[218:221], v[8:11]
	v_mfma_f32_16x16x32_bf16 v[60:63], v[108:111], v[198:201], v[60:63]
	v_mfma_f32_16x16x32_bf16 v[56:59], v[144:147], v[198:201], v[56:59]
	v_mfma_f32_16x16x32_bf16 v[44:47], v[108:111], v[206:209], v[44:47]
	v_mfma_f32_16x16x32_bf16 v[40:43], v[144:147], v[206:209], v[40:43]
	v_mfma_f32_16x16x32_bf16 v[28:31], v[108:111], v[214:217], v[28:31]
	v_mfma_f32_16x16x32_bf16 v[24:27], v[144:147], v[214:217], v[24:27]
	v_mfma_f32_16x16x32_bf16 v[12:15], v[108:111], v[222:225], v[12:15]
	v_mfma_f32_16x16x32_bf16 v[8:11], v[144:147], v[222:225], v[8:11]
	s_setprio 0
	s_setprio 1
	v_mfma_f32_16x16x32_bf16 v[52:55], v[148:151], v[194:197], v[52:55]
	v_mfma_f32_16x16x32_bf16 v[48:51], v[176:179], v[194:197], v[48:51]
	v_mfma_f32_16x16x32_bf16 v[36:39], v[148:151], v[202:205], v[36:39]
	v_mfma_f32_16x16x32_bf16 v[32:35], v[176:179], v[202:205], v[32:35]
	v_mfma_f32_16x16x32_bf16 v[20:23], v[148:151], v[210:213], v[20:23]
	v_mfma_f32_16x16x32_bf16 v[16:19], v[176:179], v[210:213], v[16:19]
	v_mfma_f32_16x16x32_bf16 v[4:7], v[148:151], v[218:221], v[4:7]
	v_mfma_f32_16x16x32_bf16 v[0:3], v[176:179], v[218:221], v[0:3]
	v_mfma_f32_16x16x32_bf16 v[52:55], v[152:155], v[198:201], v[52:55]
	v_mfma_f32_16x16x32_bf16 v[48:51], v[190:193], v[198:201], v[48:51]
	v_mfma_f32_16x16x32_bf16 v[36:39], v[152:155], v[206:209], v[36:39]
	v_mfma_f32_16x16x32_bf16 v[32:35], v[190:193], v[206:209], v[32:35]
	v_mfma_f32_16x16x32_bf16 v[20:23], v[152:155], v[214:217], v[20:23]
	v_mfma_f32_16x16x32_bf16 v[16:19], v[190:193], v[214:217], v[16:19]
	v_mfma_f32_16x16x32_bf16 v[4:7], v[152:155], v[222:225], v[4:7]
	v_mfma_f32_16x16x32_bf16 v[0:3], v[190:193], v[222:225], v[0:3]
	s_setprio 0
	s_barrier
	s_add_i32 s95, s95, 2
	s_add_u32 s93, s93, 0x100
	s_addc_u32 s94, s94, 0
	s_add_u32 s14, s14, 0x100
	s_addc_u32 s15, s15, 0
	s_branch .LBB0_256
.Lfa_2:
	v_add_u32_e32 v74, s83, v181
	ds_read_b128 v[88:91], v74
	v_xor_b32_e32 v253, 64, v74
	ds_read_b128 v[108:111], v253
	ds_read_b128 v[128:131], v74 offset:2048
	ds_read_b128 v[144:147], v253 offset:2048
	v_add_u32_e32 v74, s84, v181
	ds_read_b128 v[148:151], v74
	v_xor_b32_e32 v253, 64, v74
	ds_read_b128 v[152:155], v253
	ds_read_b128 v[176:179], v74 offset:2048
	ds_read_b128 v[190:193], v253 offset:2048
	s_add_u32 s68, s14, 0xfffc0080
	s_addc_u32 s69, s15, -1
	s_and_b64 s[66:67], s[66:67], exec
	s_cselect_b32 s69, s3, s69
	s_cselect_b32 s68, s61, s68
	s_cselect_b32 s67, s91, s94
	s_cselect_b32 s66, s92, s93
	v_lshl_add_u64 v[74:75], s[14:15], 0, v[170:171]
	s_add_i32 m0, s74, 0xc000
	ds_read_b128 v[194:197], v187
	v_xor_b32_e32 v253, 64, v187
	ds_read_b128 v[198:201], v253
	ds_read_b128 v[202:205], v187 offset:2048
	ds_read_b128 v[206:209], v253 offset:2048
	ds_read_b128 v[210:213], v187 offset:4096
	ds_read_b128 v[214:217], v253 offset:4096
	ds_read_b128 v[218:221], v187 offset:6144
	ds_read_b128 v[222:225], v253 offset:6144
	global_load_lds_dwordx4 v[74:75], off
	v_lshl_add_u64 v[74:75], s[14:15], 0, v[168:169]
	s_add_i32 m0, s74, 0xe000
	s_nop 0
	global_load_lds_dwordx4 v[74:75], off
	s_waitcnt vmcnt(8)
	s_waitcnt lgkmcnt(0)
	s_barrier
	s_setprio 1
	s_waitcnt lgkmcnt(0)
	v_mfma_f32_16x16x32_bf16 v[140:143], v[88:91], v[194:197], 0
	v_mfma_f32_16x16x32_bf16 v[136:139], v[128:131], v[194:197], 0
	v_mfma_f32_16x16x32_bf16 v[120:123], v[88:91], v[202:205], 0
	v_mfma_f32_16x16x32_bf16 v[116:119], v[128:131], v[202:205], 0
	v_mfma_f32_16x16x32_bf16 v[100:103], v[88:91], v[210:213], 0
	v_mfma_f32_16x16x32_bf16 v[96:99], v[128:131], v[210:213], 0
	v_mfma_f32_16x16x32_bf16 v[80:83], v[88:91], v[218:221], 0
	v_mfma_f32_16x16x32_bf16 v[74:77], v[128:131], v[218:221], 0
	v_mfma_f32_16x16x32_bf16 v[140:143], v[108:111], v[198:201], v[140:143]
	v_mfma_f32_16x16x32_bf16 v[136:139], v[144:147], v[198:201], v[136:139]
	v_mfma_f32_16x16x32_bf16 v[120:123], v[108:111], v[206:209], v[120:123]
	v_mfma_f32_16x16x32_bf16 v[116:119], v[144:147], v[206:209], v[116:119]
	v_mfma_f32_16x16x32_bf16 v[100:103], v[108:111], v[214:217], v[100:103]
	v_mfma_f32_16x16x32_bf16 v[96:99], v[144:147], v[214:217], v[96:99]
	v_mfma_f32_16x16x32_bf16 v[80:83], v[108:111], v[222:225], v[80:83]
	v_mfma_f32_16x16x32_bf16 v[74:77], v[144:147], v[222:225], v[74:77]
	s_setprio 0
	s_setprio 1
	v_mfma_f32_16x16x32_bf16 v[132:135], v[148:151], v[194:197], 0
	v_mfma_f32_16x16x32_bf16 v[124:127], v[176:179], v[194:197], 0
	v_mfma_f32_16x16x32_bf16 v[112:115], v[148:151], v[202:205], 0
	v_mfma_f32_16x16x32_bf16 v[104:107], v[176:179], v[202:205], 0
	v_mfma_f32_16x16x32_bf16 v[92:95], v[148:151], v[210:213], 0
	v_mfma_f32_16x16x32_bf16 v[84:87], v[176:179], v[210:213], 0
	v_mfma_f32_16x16x32_bf16 v[68:71], v[148:151], v[218:221], 0
	v_mfma_f32_16x16x32_bf16 v[64:67], v[176:179], v[218:221], 0
	v_mfma_f32_16x16x32_bf16 v[132:135], v[152:155], v[198:201], v[132:135]
	v_mfma_f32_16x16x32_bf16 v[124:127], v[190:193], v[198:201], v[124:127]
	v_mfma_f32_16x16x32_bf16 v[112:115], v[152:155], v[206:209], v[112:115]
	v_mfma_f32_16x16x32_bf16 v[104:107], v[190:193], v[206:209], v[104:107]
	v_mfma_f32_16x16x32_bf16 v[92:95], v[152:155], v[214:217], v[92:95]
	v_mfma_f32_16x16x32_bf16 v[84:87], v[190:193], v[214:217], v[84:87]
	v_mfma_f32_16x16x32_bf16 v[68:71], v[152:155], v[222:225], v[68:71]
	v_mfma_f32_16x16x32_bf16 v[64:67], v[190:193], v[222:225], v[64:67]
	s_setprio 0
	s_barrier
	s_add_i32 s96, s83, s71
	v_lshl_add_u64 v[226:227], s[66:67], 0, v[162:163]
	s_mov_b32 m0, s96
	ds_read_b128 v[194:197], v187 offset:16384
	v_xor_b32_e32 v253, 64, v187
	ds_read_b128 v[198:201], v253 offset:16384
	ds_read_b128 v[202:205], v187 offset:18432
	ds_read_b128 v[206:209], v253 offset:18432
	ds_read_b128 v[210:213], v187 offset:20480
	ds_read_b128 v[214:217], v253 offset:20480
	ds_read_b128 v[218:221], v187 offset:22528
	ds_read_b128 v[222:225], v253 offset:22528
	global_load_lds_dwordx4 v[226:227], off
	s_add_i32 m0, s96, 0x2000
	s_add_u32 s96, s66, 0x40000
	v_lshl_add_u64 v[228:229], s[66:67], 0, v[166:167]
	s_addc_u32 s97, s67, 0
	s_add_i32 vcc_lo, s84, s71
	global_load_lds_dwordx4 v[228:229], off
	v_lshl_add_u64 v[78:79], s[96:97], 0, v[162:163]
	s_mov_b32 m0, vcc_lo
	v_lshl_add_u64 v[230:231], s[68:69], 0, v[160:161]
	global_load_lds_dwordx4 v[78:79], off
	v_lshl_add_u64 v[78:79], s[96:97], 0, v[166:167]
	s_add_i32 m0, vcc_lo, 0x2000
	v_lshl_add_u64 v[232:233], s[68:69], 0, v[164:165]
	global_load_lds_dwordx4 v[78:79], off
	s_mov_b32 m0, s74
	s_nop 0
	global_load_lds_dwordx4 v[230:231], off
	s_mov_b32 m0, s75
	s_nop 0
	global_load_lds_dwordx4 v[232:233], off
	s_waitcnt vmcnt(8)
	s_waitcnt lgkmcnt(0)
	s_barrier
	s_setprio 1
	s_waitcnt lgkmcnt(0)
	v_mfma_f32_16x16x32_bf16 v[60:63], v[88:91], v[194:197], 0
	v_mfma_f32_16x16x32_bf16 v[56:59], v[128:131], v[194:197], 0
	v_mfma_f32_16x16x32_bf16 v[44:47], v[88:91], v[202:205], 0
	v_mfma_f32_16x16x32_bf16 v[40:43], v[128:131], v[202:205], 0
	v_mfma_f32_16x16x32_bf16 v[28:31], v[88:91], v[210:213], 0
	v_mfma_f32_16x16x32_bf16 v[24:27], v[128:131], v[210:213], 0
	v_mfma_f32_16x16x32_bf16 v[12:15], v[88:91], v[218:221], 0
	v_mfma_f32_16x16x32_bf16 v[8:11], v[128:131], v[218:221], 0
	v_mfma_f32_16x16x32_bf16 v[60:63], v[108:111], v[198:201], v[60:63]
	v_mfma_f32_16x16x32_bf16 v[56:59], v[144:147], v[198:201], v[56:59]
	v_mfma_f32_16x16x32_bf16 v[44:47], v[108:111], v[206:209], v[44:47]
	v_mfma_f32_16x16x32_bf16 v[40:43], v[144:147], v[206:209], v[40:43]
	v_mfma_f32_16x16x32_bf16 v[28:31], v[108:111], v[214:217], v[28:31]
	v_mfma_f32_16x16x32_bf16 v[24:27], v[144:147], v[214:217], v[24:27]
	v_mfma_f32_16x16x32_bf16 v[12:15], v[108:111], v[222:225], v[12:15]
	v_mfma_f32_16x16x32_bf16 v[8:11], v[144:147], v[222:225], v[8:11]
	s_setprio 0
	s_setprio 1
	v_mfma_f32_16x16x32_bf16 v[52:55], v[148:151], v[194:197], 0
	v_mfma_f32_16x16x32_bf16 v[48:51], v[176:179], v[194:197], 0
	v_mfma_f32_16x16x32_bf16 v[36:39], v[148:151], v[202:205], 0
	v_mfma_f32_16x16x32_bf16 v[32:35], v[176:179], v[202:205], 0
	v_mfma_f32_16x16x32_bf16 v[20:23], v[148:151], v[210:213], 0
	v_mfma_f32_16x16x32_bf16 v[16:19], v[176:179], v[210:213], 0
	v_mfma_f32_16x16x32_bf16 v[4:7], v[148:151], v[218:221], 0
	v_mfma_f32_16x16x32_bf16 v[0:3], v[176:179], v[218:221], 0
	v_mfma_f32_16x16x32_bf16 v[52:55], v[152:155], v[198:201], v[52:55]
	v_mfma_f32_16x16x32_bf16 v[48:51], v[190:193], v[198:201], v[48:51]
	v_mfma_f32_16x16x32_bf16 v[36:39], v[152:155], v[206:209], v[36:39]
	v_mfma_f32_16x16x32_bf16 v[32:35], v[190:193], v[206:209], v[32:35]
	v_mfma_f32_16x16x32_bf16 v[20:23], v[152:155], v[214:217], v[20:23]
	v_mfma_f32_16x16x32_bf16 v[16:19], v[190:193], v[214:217], v[16:19]
	v_mfma_f32_16x16x32_bf16 v[4:7], v[152:155], v[222:225], v[4:7]
	v_mfma_f32_16x16x32_bf16 v[0:3], v[190:193], v[222:225], v[0:3]
	s_setprio 0
	s_barrier
	s_add_i32 s96, 0, 0x18000
	v_add_u32_e32 v78, s96, v181
	s_add_i32 s97, 0, 0x1c000
	ds_read_b128 v[88:91], v78
	v_xor_b32_e32 v253, 64, v78
	ds_read_b128 v[108:111], v253
	ds_read_b128 v[128:131], v78 offset:2048
	ds_read_b128 v[144:147], v253 offset:2048
	v_add_u32_e32 v78, s97, v181
	ds_read_b128 v[148:151], v78
	v_xor_b32_e32 v253, 64, v78
	ds_read_b128 v[152:155], v253
	ds_read_b128 v[176:179], v78 offset:2048
	ds_read_b128 v[190:193], v253 offset:2048
	s_add_u32 s68, s68, 0x40000
	s_addc_u32 s69, s69, 0
	s_mov_b32 m0, s76
	v_lshl_add_u64 v[78:79], s[68:69], 0, v[160:161]
	ds_read_b128 v[194:197], v187 offset:32768
	v_xor_b32_e32 v253, 64, v187
	ds_read_b128 v[198:201], v253 offset:32768
	ds_read_b128 v[202:205], v187 offset:34816
	ds_read_b128 v[206:209], v253 offset:34816
	ds_read_b128 v[210:213], v187 offset:36864
	ds_read_b128 v[214:217], v253 offset:36864
	ds_read_b128 v[218:221], v187 offset:38912
	ds_read_b128 v[222:225], v253 offset:38912
	global_load_lds_dwordx4 v[78:79], off
	v_lshl_add_u64 v[78:79], s[68:69], 0, v[164:165]
	s_mov_b32 m0, s77
	s_nop 0
	global_load_lds_dwordx4 v[78:79], off
	s_waitcnt vmcnt(8)
	s_waitcnt lgkmcnt(0)
	s_barrier
	s_setprio 1
	s_waitcnt lgkmcnt(0)
	v_mfma_f32_16x16x32_bf16 v[140:143], v[88:91], v[194:197], v[140:143]
	v_mfma_f32_16x16x32_bf16 v[136:139], v[128:131], v[194:197], v[136:139]
	v_mfma_f32_16x16x32_bf16 v[120:123], v[88:91], v[202:205], v[120:123]
	v_mfma_f32_16x16x32_bf16 v[116:119], v[128:131], v[202:205], v[116:119]
	v_mfma_f32_16x16x32_bf16 v[100:103], v[88:91], v[210:213], v[100:103]
	v_mfma_f32_16x16x32_bf16 v[96:99], v[128:131], v[210:213], v[96:99]
	v_mfma_f32_16x16x32_bf16 v[78:81], v[88:91], v[218:221], v[80:83]
	v_mfma_f32_16x16x32_bf16 v[74:77], v[128:131], v[218:221], v[74:77]
	v_mfma_f32_16x16x32_bf16 v[140:143], v[108:111], v[198:201], v[140:143]
	v_mfma_f32_16x16x32_bf16 v[136:139], v[144:147], v[198:201], v[136:139]
	v_mfma_f32_16x16x32_bf16 v[120:123], v[108:111], v[206:209], v[120:123]
	v_mfma_f32_16x16x32_bf16 v[116:119], v[144:147], v[206:209], v[116:119]
	v_mfma_f32_16x16x32_bf16 v[100:103], v[108:111], v[214:217], v[100:103]
	v_mfma_f32_16x16x32_bf16 v[96:99], v[144:147], v[214:217], v[96:99]
	v_mfma_f32_16x16x32_bf16 v[80:83], v[108:111], v[222:225], v[78:81]
	v_mfma_f32_16x16x32_bf16 v[76:79], v[144:147], v[222:225], v[74:77]
	s_setprio 0
	s_setprio 1
	v_mfma_f32_16x16x32_bf16 v[132:135], v[148:151], v[194:197], v[132:135]
	v_mfma_f32_16x16x32_bf16 v[124:127], v[176:179], v[194:197], v[124:127]
	v_mfma_f32_16x16x32_bf16 v[112:115], v[148:151], v[202:205], v[112:115]
	v_mfma_f32_16x16x32_bf16 v[104:107], v[176:179], v[202:205], v[104:107]
	v_mfma_f32_16x16x32_bf16 v[92:95], v[148:151], v[210:213], v[92:95]
	v_mfma_f32_16x16x32_bf16 v[84:87], v[176:179], v[210:213], v[84:87]
	v_mfma_f32_16x16x32_bf16 v[68:71], v[148:151], v[218:221], v[68:71]
	v_mfma_f32_16x16x32_bf16 v[64:67], v[176:179], v[218:221], v[64:67]
	v_mfma_f32_16x16x32_bf16 v[132:135], v[152:155], v[198:201], v[132:135]
	v_mfma_f32_16x16x32_bf16 v[124:127], v[190:193], v[198:201], v[124:127]
	v_mfma_f32_16x16x32_bf16 v[112:115], v[152:155], v[206:209], v[112:115]
	v_mfma_f32_16x16x32_bf16 v[104:107], v[190:193], v[206:209], v[104:107]
	v_mfma_f32_16x16x32_bf16 v[92:95], v[152:155], v[214:217], v[92:95]
	v_mfma_f32_16x16x32_bf16 v[84:87], v[190:193], v[214:217], v[84:87]
	v_mfma_f32_16x16x32_bf16 v[68:71], v[152:155], v[222:225], v[68:71]
	v_mfma_f32_16x16x32_bf16 v[64:67], v[190:193], v[222:225], v[64:67]
	s_setprio 0
	s_barrier
	s_add_i32 s68, s96, s71
	v_lshl_add_u64 v[74:75], v[226:227], 0, s[28:29]
	s_mov_b32 m0, s68
	ds_read_b128 v[194:197], v187 offset:49152
	v_xor_b32_e32 v253, 64, v187
	ds_read_b128 v[198:201], v253 offset:49152
	ds_read_b128 v[202:205], v187 offset:51200
	ds_read_b128 v[206:209], v253 offset:51200
	ds_read_b128 v[210:213], v187 offset:53248
	ds_read_b128 v[214:217], v253 offset:53248
	ds_read_b128 v[218:221], v187 offset:55296
	ds_read_b128 v[222:225], v253 offset:55296
	global_load_lds_dwordx4 v[74:75], off
	s_add_i32 m0, s68, 0x2000
	s_add_u32 s66, s66, 0x40080
	v_lshl_add_u64 v[74:75], v[228:229], 0, s[28:29]
	s_addc_u32 s67, s67, 0
	s_add_i32 s68, s97, s71
	global_load_lds_dwordx4 v[74:75], off
	v_lshl_add_u64 v[74:75], s[66:67], 0, v[162:163]
	s_mov_b32 m0, s68
	s_nop 0
	global_load_lds_dwordx4 v[74:75], off
	v_lshl_add_u64 v[74:75], s[66:67], 0, v[166:167]
	s_add_i32 m0, s68, 0x2000
	s_nop 0
	global_load_lds_dwordx4 v[74:75], off
	v_lshl_add_u64 v[74:75], v[230:231], 0, s[28:29]
	s_mov_b32 m0, s78
	s_nop 0
	global_load_lds_dwordx4 v[74:75], off
	v_lshl_add_u64 v[74:75], v[232:233], 0, s[28:29]
	s_mov_b32 m0, s79
	s_nop 0
	global_load_lds_dwordx4 v[74:75], off
	s_waitcnt vmcnt(8)
	s_waitcnt lgkmcnt(0)
	s_barrier
	s_setprio 1
	s_waitcnt lgkmcnt(0)
	v_mfma_f32_16x16x32_bf16 v[60:63], v[88:91], v[194:197], v[60:63]
	v_mfma_f32_16x16x32_bf16 v[56:59], v[128:131], v[194:197], v[56:59]
	v_mfma_f32_16x16x32_bf16 v[44:47], v[88:91], v[202:205], v[44:47]
	v_mfma_f32_16x16x32_bf16 v[40:43], v[128:131], v[202:205], v[40:43]
	v_mfma_f32_16x16x32_bf16 v[28:31], v[88:91], v[210:213], v[28:31]
	v_mfma_f32_16x16x32_bf16 v[24:27], v[128:131], v[210:213], v[24:27]
	v_mfma_f32_16x16x32_bf16 v[12:15], v[88:91], v[218:221], v[12:15]
	v_mfma_f32_16x16x32_bf16 v[8:11], v[128:131], v[218:221], v[8:11]
	v_mfma_f32_16x16x32_bf16 v[60:63], v[108:111], v[198:201], v[60:63]
	v_mfma_f32_16x16x32_bf16 v[56:59], v[144:147], v[198:201], v[56:59]
	v_mfma_f32_16x16x32_bf16 v[44:47], v[108:111], v[206:209], v[44:47]
	v_mfma_f32_16x16x32_bf16 v[40:43], v[144:147], v[206:209], v[40:43]
	v_mfma_f32_16x16x32_bf16 v[28:31], v[108:111], v[214:217], v[28:31]
	v_mfma_f32_16x16x32_bf16 v[24:27], v[144:147], v[214:217], v[24:27]
	v_mfma_f32_16x16x32_bf16 v[12:15], v[108:111], v[222:225], v[12:15]
	v_mfma_f32_16x16x32_bf16 v[8:11], v[144:147], v[222:225], v[8:11]
	s_setprio 0
	s_setprio 1
	v_mfma_f32_16x16x32_bf16 v[52:55], v[148:151], v[194:197], v[52:55]
	v_mfma_f32_16x16x32_bf16 v[48:51], v[176:179], v[194:197], v[48:51]
	v_mfma_f32_16x16x32_bf16 v[36:39], v[148:151], v[202:205], v[36:39]
	v_mfma_f32_16x16x32_bf16 v[32:35], v[176:179], v[202:205], v[32:35]
	v_mfma_f32_16x16x32_bf16 v[20:23], v[148:151], v[210:213], v[20:23]
	v_mfma_f32_16x16x32_bf16 v[16:19], v[176:179], v[210:213], v[16:19]
	v_mfma_f32_16x16x32_bf16 v[4:7], v[148:151], v[218:221], v[4:7]
	v_mfma_f32_16x16x32_bf16 v[0:3], v[176:179], v[218:221], v[0:3]
	v_mfma_f32_16x16x32_bf16 v[52:55], v[152:155], v[198:201], v[52:55]
	v_mfma_f32_16x16x32_bf16 v[48:51], v[190:193], v[198:201], v[48:51]
	v_mfma_f32_16x16x32_bf16 v[36:39], v[152:155], v[206:209], v[36:39]
	v_mfma_f32_16x16x32_bf16 v[32:35], v[190:193], v[206:209], v[32:35]
	v_mfma_f32_16x16x32_bf16 v[20:23], v[152:155], v[214:217], v[20:23]
	v_mfma_f32_16x16x32_bf16 v[16:19], v[190:193], v[214:217], v[16:19]
	v_mfma_f32_16x16x32_bf16 v[4:7], v[152:155], v[222:225], v[4:7]
	v_mfma_f32_16x16x32_bf16 v[0:3], v[190:193], v[222:225], v[0:3]
	s_setprio 0
	s_barrier
	s_add_i32 s95, s95, 2
	s_add_u32 s93, s93, 0x100
	s_addc_u32 s94, s94, 0
	s_add_u32 s14, s14, 0x100
	s_addc_u32 s15, s15, 0
	s_branch .LBB0_256
.LBB0_255:
	v_add_u32_e32 v74, s83, v181
	ds_read_b128 v[88:91], v74
	v_xor_b32_e32 v253, 64, v74
	ds_read_b128 v[108:111], v253
	ds_read_b128 v[128:131], v74 offset:2048
	ds_read_b128 v[144:147], v253 offset:2048
	v_add_u32_e32 v74, s84, v181
	ds_read_b128 v[148:151], v74
	v_xor_b32_e32 v253, 64, v74
	ds_read_b128 v[152:155], v253
	ds_read_b128 v[176:179], v74 offset:2048
	ds_read_b128 v[190:193], v253 offset:2048
	s_add_u32 s68, s14, 0xfffc0080
	s_addc_u32 s69, s15, -1
	s_and_b64 s[66:67], s[66:67], exec
	s_cselect_b32 s69, s3, s69
	s_cselect_b32 s68, s61, s68
	s_cselect_b32 s67, s91, s94
	s_cselect_b32 s66, s92, s93
	v_lshl_add_u64 v[74:75], s[14:15], 0, v[170:171]
	s_add_i32 m0, s74, 0xc000
	ds_read_b128 v[194:197], v187
	v_xor_b32_e32 v253, 64, v187
	ds_read_b128 v[198:201], v253
	ds_read_b128 v[202:205], v187 offset:2048
	ds_read_b128 v[206:209], v253 offset:2048
	ds_read_b128 v[210:213], v187 offset:4096
	ds_read_b128 v[214:217], v253 offset:4096
	ds_read_b128 v[218:221], v187 offset:6144
	ds_read_b128 v[222:225], v253 offset:6144
	global_load_lds_dwordx4 v[74:75], off
	v_lshl_add_u64 v[74:75], s[14:15], 0, v[168:169]
	s_add_i32 m0, s74, 0xe000
	s_nop 0
	global_load_lds_dwordx4 v[74:75], off
	s_waitcnt vmcnt(8)
	s_waitcnt lgkmcnt(0)
	s_barrier
	s_setprio 1
	s_waitcnt lgkmcnt(0)
	v_mfma_f32_16x16x32_bf16 v[140:143], v[88:91], v[194:197], v[140:143]
	v_mfma_f32_16x16x32_bf16 v[136:139], v[128:131], v[194:197], v[136:139]
	v_mfma_f32_16x16x32_bf16 v[120:123], v[88:91], v[202:205], v[120:123]
	v_mfma_f32_16x16x32_bf16 v[116:119], v[128:131], v[202:205], v[116:119]
	v_mfma_f32_16x16x32_bf16 v[100:103], v[88:91], v[210:213], v[100:103]
	v_mfma_f32_16x16x32_bf16 v[96:99], v[128:131], v[210:213], v[96:99]
	v_mfma_f32_16x16x32_bf16 v[80:83], v[88:91], v[218:221], v[80:83]
	v_mfma_f32_16x16x32_bf16 v[74:77], v[128:131], v[218:221], v[76:79]
	v_mfma_f32_16x16x32_bf16 v[140:143], v[108:111], v[198:201], v[140:143]
	v_mfma_f32_16x16x32_bf16 v[136:139], v[144:147], v[198:201], v[136:139]
	v_mfma_f32_16x16x32_bf16 v[120:123], v[108:111], v[206:209], v[120:123]
	v_mfma_f32_16x16x32_bf16 v[116:119], v[144:147], v[206:209], v[116:119]
	v_mfma_f32_16x16x32_bf16 v[100:103], v[108:111], v[214:217], v[100:103]
	v_mfma_f32_16x16x32_bf16 v[96:99], v[144:147], v[214:217], v[96:99]
	v_mfma_f32_16x16x32_bf16 v[80:83], v[108:111], v[222:225], v[80:83]
	v_mfma_f32_16x16x32_bf16 v[74:77], v[144:147], v[222:225], v[74:77]
	s_setprio 0
	s_setprio 1
	v_mfma_f32_16x16x32_bf16 v[132:135], v[148:151], v[194:197], v[132:135]
	v_mfma_f32_16x16x32_bf16 v[124:127], v[176:179], v[194:197], v[124:127]
	v_mfma_f32_16x16x32_bf16 v[112:115], v[148:151], v[202:205], v[112:115]
	v_mfma_f32_16x16x32_bf16 v[104:107], v[176:179], v[202:205], v[104:107]
	v_mfma_f32_16x16x32_bf16 v[92:95], v[148:151], v[210:213], v[92:95]
	v_mfma_f32_16x16x32_bf16 v[84:87], v[176:179], v[210:213], v[84:87]
	v_mfma_f32_16x16x32_bf16 v[68:71], v[148:151], v[218:221], v[68:71]
	v_mfma_f32_16x16x32_bf16 v[64:67], v[176:179], v[218:221], v[64:67]
	v_mfma_f32_16x16x32_bf16 v[132:135], v[152:155], v[198:201], v[132:135]
	v_mfma_f32_16x16x32_bf16 v[124:127], v[190:193], v[198:201], v[124:127]
	v_mfma_f32_16x16x32_bf16 v[112:115], v[152:155], v[206:209], v[112:115]
	v_mfma_f32_16x16x32_bf16 v[104:107], v[190:193], v[206:209], v[104:107]
	v_mfma_f32_16x16x32_bf16 v[92:95], v[152:155], v[214:217], v[92:95]
	v_mfma_f32_16x16x32_bf16 v[84:87], v[190:193], v[214:217], v[84:87]
	v_mfma_f32_16x16x32_bf16 v[68:71], v[152:155], v[222:225], v[68:71]
	v_mfma_f32_16x16x32_bf16 v[64:67], v[190:193], v[222:225], v[64:67]
	s_setprio 0
	s_barrier
	s_add_i32 s96, s83, s71
	v_lshl_add_u64 v[226:227], s[66:67], 0, v[162:163]
	s_mov_b32 m0, s96
	ds_read_b128 v[194:197], v187 offset:16384
	v_xor_b32_e32 v253, 64, v187
	ds_read_b128 v[198:201], v253 offset:16384
	ds_read_b128 v[202:205], v187 offset:18432
	ds_read_b128 v[206:209], v253 offset:18432
	ds_read_b128 v[210:213], v187 offset:20480
	ds_read_b128 v[214:217], v253 offset:20480
	ds_read_b128 v[218:221], v187 offset:22528
	ds_read_b128 v[222:225], v253 offset:22528
	global_load_lds_dwordx4 v[226:227], off
	s_add_i32 m0, s96, 0x2000
	s_add_u32 s96, s66, 0x40000
	v_lshl_add_u64 v[228:229], s[66:67], 0, v[166:167]
	s_addc_u32 s97, s67, 0
	s_add_i32 vcc_lo, s84, s71
	global_load_lds_dwordx4 v[228:229], off
	v_lshl_add_u64 v[78:79], s[96:97], 0, v[162:163]
	s_mov_b32 m0, vcc_lo
	v_lshl_add_u64 v[230:231], s[68:69], 0, v[160:161]
	global_load_lds_dwordx4 v[78:79], off
	v_lshl_add_u64 v[78:79], s[96:97], 0, v[166:167]
	s_add_i32 m0, vcc_lo, 0x2000
	v_lshl_add_u64 v[232:233], s[68:69], 0, v[164:165]
	global_load_lds_dwordx4 v[78:79], off
	s_mov_b32 m0, s74
	s_nop 0
	global_load_lds_dwordx4 v[230:231], off
	s_mov_b32 m0, s75
	s_nop 0
	global_load_lds_dwordx4 v[232:233], off
	s_waitcnt vmcnt(8)
	s_waitcnt lgkmcnt(0)
	s_barrier
	s_setprio 1
	s_waitcnt lgkmcnt(0)
	v_mfma_f32_16x16x32_bf16 v[60:63], v[88:91], v[194:197], v[60:63]
	v_mfma_f32_16x16x32_bf16 v[56:59], v[128:131], v[194:197], v[56:59]
	v_mfma_f32_16x16x32_bf16 v[44:47], v[88:91], v[202:205], v[44:47]
	v_mfma_f32_16x16x32_bf16 v[40:43], v[128:131], v[202:205], v[40:43]
	v_mfma_f32_16x16x32_bf16 v[28:31], v[88:91], v[210:213], v[28:31]
	v_mfma_f32_16x16x32_bf16 v[24:27], v[128:131], v[210:213], v[24:27]
	v_mfma_f32_16x16x32_bf16 v[12:15], v[88:91], v[218:221], v[12:15]
	v_mfma_f32_16x16x32_bf16 v[8:11], v[128:131], v[218:221], v[8:11]
	v_mfma_f32_16x16x32_bf16 v[60:63], v[108:111], v[198:201], v[60:63]
	v_mfma_f32_16x16x32_bf16 v[56:59], v[144:147], v[198:201], v[56:59]
	v_mfma_f32_16x16x32_bf16 v[44:47], v[108:111], v[206:209], v[44:47]
	v_mfma_f32_16x16x32_bf16 v[40:43], v[144:147], v[206:209], v[40:43]
	v_mfma_f32_16x16x32_bf16 v[28:31], v[108:111], v[214:217], v[28:31]
	v_mfma_f32_16x16x32_bf16 v[24:27], v[144:147], v[214:217], v[24:27]
	v_mfma_f32_16x16x32_bf16 v[12:15], v[108:111], v[222:225], v[12:15]
	v_mfma_f32_16x16x32_bf16 v[8:11], v[144:147], v[222:225], v[8:11]
	s_setprio 0
	s_setprio 1
	v_mfma_f32_16x16x32_bf16 v[52:55], v[148:151], v[194:197], v[52:55]
	v_mfma_f32_16x16x32_bf16 v[48:51], v[176:179], v[194:197], v[48:51]
	v_mfma_f32_16x16x32_bf16 v[36:39], v[148:151], v[202:205], v[36:39]
	v_mfma_f32_16x16x32_bf16 v[32:35], v[176:179], v[202:205], v[32:35]
	v_mfma_f32_16x16x32_bf16 v[20:23], v[148:151], v[210:213], v[20:23]
	v_mfma_f32_16x16x32_bf16 v[16:19], v[176:179], v[210:213], v[16:19]
	v_mfma_f32_16x16x32_bf16 v[4:7], v[148:151], v[218:221], v[4:7]
	v_mfma_f32_16x16x32_bf16 v[0:3], v[176:179], v[218:221], v[0:3]
	v_mfma_f32_16x16x32_bf16 v[52:55], v[152:155], v[198:201], v[52:55]
	v_mfma_f32_16x16x32_bf16 v[48:51], v[190:193], v[198:201], v[48:51]
	v_mfma_f32_16x16x32_bf16 v[36:39], v[152:155], v[206:209], v[36:39]
	v_mfma_f32_16x16x32_bf16 v[32:35], v[190:193], v[206:209], v[32:35]
	v_mfma_f32_16x16x32_bf16 v[20:23], v[152:155], v[214:217], v[20:23]
	v_mfma_f32_16x16x32_bf16 v[16:19], v[190:193], v[214:217], v[16:19]
	v_mfma_f32_16x16x32_bf16 v[4:7], v[152:155], v[222:225], v[4:7]
	v_mfma_f32_16x16x32_bf16 v[0:3], v[190:193], v[222:225], v[0:3]
	s_setprio 0
	s_barrier
	s_add_i32 s96, 0, 0x18000
	v_add_u32_e32 v78, s96, v181
	s_add_i32 s97, 0, 0x1c000
	ds_read_b128 v[88:91], v78
	v_xor_b32_e32 v253, 64, v78
	ds_read_b128 v[108:111], v253
	ds_read_b128 v[128:131], v78 offset:2048
	ds_read_b128 v[144:147], v253 offset:2048
	v_add_u32_e32 v78, s97, v181
	ds_read_b128 v[148:151], v78
	v_xor_b32_e32 v253, 64, v78
	ds_read_b128 v[152:155], v253
	ds_read_b128 v[176:179], v78 offset:2048
	ds_read_b128 v[190:193], v253 offset:2048
	s_add_u32 s68, s68, 0x40000
	s_addc_u32 s69, s69, 0
	s_mov_b32 m0, s76
	v_lshl_add_u64 v[78:79], s[68:69], 0, v[160:161]
	ds_read_b128 v[194:197], v187 offset:32768
	v_xor_b32_e32 v253, 64, v187
	ds_read_b128 v[198:201], v253 offset:32768
	ds_read_b128 v[202:205], v187 offset:34816
	ds_read_b128 v[206:209], v253 offset:34816
	ds_read_b128 v[210:213], v187 offset:36864
	ds_read_b128 v[214:217], v253 offset:36864
	ds_read_b128 v[218:221], v187 offset:38912
	ds_read_b128 v[222:225], v253 offset:38912
	global_load_lds_dwordx4 v[78:79], off
	v_lshl_add_u64 v[78:79], s[68:69], 0, v[164:165]
	s_mov_b32 m0, s77
	s_nop 0
	global_load_lds_dwordx4 v[78:79], off
	s_waitcnt vmcnt(8)
	s_waitcnt lgkmcnt(0)
	s_barrier
	s_setprio 1
	s_waitcnt lgkmcnt(0)
	v_mfma_f32_16x16x32_bf16 v[140:143], v[88:91], v[194:197], v[140:143]
	v_mfma_f32_16x16x32_bf16 v[136:139], v[128:131], v[194:197], v[136:139]
	v_mfma_f32_16x16x32_bf16 v[120:123], v[88:91], v[202:205], v[120:123]
	v_mfma_f32_16x16x32_bf16 v[116:119], v[128:131], v[202:205], v[116:119]
	v_mfma_f32_16x16x32_bf16 v[100:103], v[88:91], v[210:213], v[100:103]
	v_mfma_f32_16x16x32_bf16 v[96:99], v[128:131], v[210:213], v[96:99]
	v_mfma_f32_16x16x32_bf16 v[78:81], v[88:91], v[218:221], v[80:83]
	v_mfma_f32_16x16x32_bf16 v[74:77], v[128:131], v[218:221], v[74:77]
	v_mfma_f32_16x16x32_bf16 v[140:143], v[108:111], v[198:201], v[140:143]
	v_mfma_f32_16x16x32_bf16 v[136:139], v[144:147], v[198:201], v[136:139]
	v_mfma_f32_16x16x32_bf16 v[120:123], v[108:111], v[206:209], v[120:123]
	v_mfma_f32_16x16x32_bf16 v[116:119], v[144:147], v[206:209], v[116:119]
	v_mfma_f32_16x16x32_bf16 v[100:103], v[108:111], v[214:217], v[100:103]
	v_mfma_f32_16x16x32_bf16 v[96:99], v[144:147], v[214:217], v[96:99]
	v_mfma_f32_16x16x32_bf16 v[80:83], v[108:111], v[222:225], v[78:81]
	v_mfma_f32_16x16x32_bf16 v[76:79], v[144:147], v[222:225], v[74:77]
	s_setprio 0
	s_setprio 1
	v_mfma_f32_16x16x32_bf16 v[132:135], v[148:151], v[194:197], v[132:135]
	v_mfma_f32_16x16x32_bf16 v[124:127], v[176:179], v[194:197], v[124:127]
	v_mfma_f32_16x16x32_bf16 v[112:115], v[148:151], v[202:205], v[112:115]
	v_mfma_f32_16x16x32_bf16 v[104:107], v[176:179], v[202:205], v[104:107]
	v_mfma_f32_16x16x32_bf16 v[92:95], v[148:151], v[210:213], v[92:95]
	v_mfma_f32_16x16x32_bf16 v[84:87], v[176:179], v[210:213], v[84:87]
	v_mfma_f32_16x16x32_bf16 v[68:71], v[148:151], v[218:221], v[68:71]
	v_mfma_f32_16x16x32_bf16 v[64:67], v[176:179], v[218:221], v[64:67]
	v_mfma_f32_16x16x32_bf16 v[132:135], v[152:155], v[198:201], v[132:135]
	v_mfma_f32_16x16x32_bf16 v[124:127], v[190:193], v[198:201], v[124:127]
	v_mfma_f32_16x16x32_bf16 v[112:115], v[152:155], v[206:209], v[112:115]
	v_mfma_f32_16x16x32_bf16 v[104:107], v[190:193], v[206:209], v[104:107]
	v_mfma_f32_16x16x32_bf16 v[92:95], v[152:155], v[214:217], v[92:95]
	v_mfma_f32_16x16x32_bf16 v[84:87], v[190:193], v[214:217], v[84:87]
	v_mfma_f32_16x16x32_bf16 v[68:71], v[152:155], v[222:225], v[68:71]
	v_mfma_f32_16x16x32_bf16 v[64:67], v[190:193], v[222:225], v[64:67]
	s_setprio 0
	s_barrier
	s_add_i32 s68, s96, s71
	v_lshl_add_u64 v[74:75], v[226:227], 0, s[28:29]
	s_mov_b32 m0, s68
	ds_read_b128 v[194:197], v187 offset:49152
	v_xor_b32_e32 v253, 64, v187
	ds_read_b128 v[198:201], v253 offset:49152
	ds_read_b128 v[202:205], v187 offset:51200
	ds_read_b128 v[206:209], v253 offset:51200
	ds_read_b128 v[210:213], v187 offset:53248
	ds_read_b128 v[214:217], v253 offset:53248
	ds_read_b128 v[218:221], v187 offset:55296
	ds_read_b128 v[222:225], v253 offset:55296
	global_load_lds_dwordx4 v[74:75], off
	s_add_i32 m0, s68, 0x2000
	s_add_u32 s66, s66, 0x40080
	v_lshl_add_u64 v[74:75], v[228:229], 0, s[28:29]
	s_addc_u32 s67, s67, 0
	s_add_i32 s68, s97, s71
	global_load_lds_dwordx4 v[74:75], off
	v_lshl_add_u64 v[74:75], s[66:67], 0, v[162:163]
	s_mov_b32 m0, s68
	s_nop 0
	global_load_lds_dwordx4 v[74:75], off
	v_lshl_add_u64 v[74:75], s[66:67], 0, v[166:167]
	s_add_i32 m0, s68, 0x2000
	s_nop 0
	global_load_lds_dwordx4 v[74:75], off
	v_lshl_add_u64 v[74:75], v[230:231], 0, s[28:29]
	s_mov_b32 m0, s78
	s_nop 0
	global_load_lds_dwordx4 v[74:75], off
	v_lshl_add_u64 v[74:75], v[232:233], 0, s[28:29]
	s_mov_b32 m0, s79
	s_nop 0
	global_load_lds_dwordx4 v[74:75], off
	s_waitcnt vmcnt(8)
	s_waitcnt lgkmcnt(0)
	s_barrier
	s_setprio 1
	s_waitcnt lgkmcnt(0)
	v_mfma_f32_16x16x32_bf16 v[60:63], v[88:91], v[194:197], v[60:63]
	v_mfma_f32_16x16x32_bf16 v[56:59], v[128:131], v[194:197], v[56:59]
	v_mfma_f32_16x16x32_bf16 v[44:47], v[88:91], v[202:205], v[44:47]
	v_mfma_f32_16x16x32_bf16 v[40:43], v[128:131], v[202:205], v[40:43]
	v_mfma_f32_16x16x32_bf16 v[28:31], v[88:91], v[210:213], v[28:31]
	v_mfma_f32_16x16x32_bf16 v[24:27], v[128:131], v[210:213], v[24:27]
	v_mfma_f32_16x16x32_bf16 v[12:15], v[88:91], v[218:221], v[12:15]
	v_mfma_f32_16x16x32_bf16 v[8:11], v[128:131], v[218:221], v[8:11]
	v_mfma_f32_16x16x32_bf16 v[60:63], v[108:111], v[198:201], v[60:63]
	v_mfma_f32_16x16x32_bf16 v[56:59], v[144:147], v[198:201], v[56:59]
	v_mfma_f32_16x16x32_bf16 v[44:47], v[108:111], v[206:209], v[44:47]
	v_mfma_f32_16x16x32_bf16 v[40:43], v[144:147], v[206:209], v[40:43]
	v_mfma_f32_16x16x32_bf16 v[28:31], v[108:111], v[214:217], v[28:31]
	v_mfma_f32_16x16x32_bf16 v[24:27], v[144:147], v[214:217], v[24:27]
	v_mfma_f32_16x16x32_bf16 v[12:15], v[108:111], v[222:225], v[12:15]
	v_mfma_f32_16x16x32_bf16 v[8:11], v[144:147], v[222:225], v[8:11]
	s_setprio 0
	s_setprio 1
	v_mfma_f32_16x16x32_bf16 v[52:55], v[148:151], v[194:197], v[52:55]
	v_mfma_f32_16x16x32_bf16 v[48:51], v[176:179], v[194:197], v[48:51]
	v_mfma_f32_16x16x32_bf16 v[36:39], v[148:151], v[202:205], v[36:39]
	v_mfma_f32_16x16x32_bf16 v[32:35], v[176:179], v[202:205], v[32:35]
	v_mfma_f32_16x16x32_bf16 v[20:23], v[148:151], v[210:213], v[20:23]
	v_mfma_f32_16x16x32_bf16 v[16:19], v[176:179], v[210:213], v[16:19]
	v_mfma_f32_16x16x32_bf16 v[4:7], v[148:151], v[218:221], v[4:7]
	v_mfma_f32_16x16x32_bf16 v[0:3], v[176:179], v[218:221], v[0:3]
	v_mfma_f32_16x16x32_bf16 v[52:55], v[152:155], v[198:201], v[52:55]
	v_mfma_f32_16x16x32_bf16 v[48:51], v[190:193], v[198:201], v[48:51]
	v_mfma_f32_16x16x32_bf16 v[36:39], v[152:155], v[206:209], v[36:39]
	v_mfma_f32_16x16x32_bf16 v[32:35], v[190:193], v[206:209], v[32:35]
	v_mfma_f32_16x16x32_bf16 v[20:23], v[152:155], v[214:217], v[20:23]
	v_mfma_f32_16x16x32_bf16 v[16:19], v[190:193], v[214:217], v[16:19]
	v_mfma_f32_16x16x32_bf16 v[4:7], v[152:155], v[222:225], v[4:7]
	v_mfma_f32_16x16x32_bf16 v[0:3], v[190:193], v[222:225], v[0:3]
	s_setprio 0
	s_barrier
	s_add_i32 s95, s95, 2
	s_add_u32 s93, s93, 0x100
	s_addc_u32 s94, s94, 0
	s_add_u32 s14, s14, 0x100
	s_addc_u32 s15, s15, 0
	s_cmp_gt_u32 s95, 13
	s_cbranch_scc1 .LBB0_258

.LBB0_427:
	s_and_b64 vcc, exec, s[4:5]
	s_cbranch_vccnz .LBB0_465
	v_ashrrev_i32_e32 v1, 31, v8
	v_lshrrev_b32_e32 v1, 26, v1
	v_add_u32_e32 v1, v8, v1
	v_ashrrev_i32_e32 v9, 6, v1
	v_bfe_i32 v1, v8, 27, 1
	v_lshlrev_b32_e32 v0, 4, v8
	v_lshrrev_b32_e32 v1, 22, v1
	v_add_u32_e32 v1, v0, v1
	v_and_b32_e32 v1, 0xfffffc00, v1
	v_sub_u32_e32 v1, v0, v1
	v_lshrrev_b32_e32 v2, 4, v1
	v_bitop3_b32 v1, v2, v1, 32 bitop3:0x6c
	v_ashrrev_i32_e32 v3, 31, v1
	v_lshrrev_b32_e32 v3, 26, v3
	v_add_u32_e32 v3, v1, v3
	v_lshlrev_b32_e32 v2, 3, v9
	v_ashrrev_i32_e32 v10, 6, v3
	v_and_b32_e32 v3, 0xc0, v3
	v_and_b32_e32 v2, -16, v2
	v_sub_u32_e32 v1, v1, v3
	v_mov_b32_e32 v3, 1
	v_add_u32_e32 v2, v10, v2
	v_ashrrev_i16_sdwa v1, v3, sext(v1) dst_sel:DWORD dst_unused:UNUSED_PAD src0_sel:DWORD src1_sel:BYTE_0
	v_lshlrev_b32_e32 v4, 5, v9
	v_bfe_i32 v11, v1, 0, 16
	v_lshlrev_b32_e32 v1, 1, v2
	v_lshrrev_b32_e32 v5, 2, v2
	v_and_b32_e32 v6, 3, v10
	s_mov_b32 s10, 0xfffe0
	v_and_b32_e32 v4, 32, v4
	v_and_b32_e32 v1, 24, v1
	v_and_b32_e32 v5, 4, v5
	v_and_or_b32 v6, v2, s10, v6
	v_or3_b32 v1, v6, v5, v1
	v_add_lshl_u32 v4, v4, v11, 1
	v_add_u32_e32 v0, 0x2000, v0
	v_lshl_add_u32 v154, v1, 12, v4
	v_lshrrev_b32_e32 v250, 3, v157
	v_and_b32_e32 v251, 6, v250
	v_and_b32_e32 v252, 7, v157
	v_xor_b32_e32 v251, v251, v252
	v_lshlrev_b32_e32 v251, 4, v251
	v_and_b32_e32 v252, 12, v250
	v_lshlrev_b32_e32 v252, 1, v252
	v_and_b32_e32 v253, 16, v250
	v_lshrrev_b32_e32 v253, 2, v253
	v_or_b32_e32 v252, v252, v253
	v_and_b32_e32 v253, 35, v250
	v_or_b32_e32 v250, v252, v253
	v_mul_u32_u24_e32 v250, 0x1000, v250
	v_add_u32_e32 v154, v250, v251
	v_ashrrev_i32_e32 v1, 31, v0
	v_lshrrev_b32_e32 v1, 22, v1
	v_add_u32_e32 v1, v0, v1
	v_ashrrev_i32_e32 v12, 10, v1
	v_mul_i32_i24_e32 v1, 0x400, v12
	v_sub_u32_e32 v0, v0, v1
	v_lshrrev_b32_e32 v1, 4, v0
	v_bitop3_b32 v0, v1, v0, 32 bitop3:0x6c
	v_lshl_add_u32 v152, v2, 12, v4
	v_lshrrev_b32_e32 v250, 3, v157
	v_and_b32_e32 v251, 6, v250
	v_and_b32_e32 v252, 7, v157
	v_xor_b32_e32 v251, v251, v252
	v_lshlrev_b32_e32 v251, 4, v251
	v_mul_u32_u24_e32 v250, 0x1000, v250
	v_add_u32_e32 v152, v250, v251
	v_ashrrev_i32_e32 v2, 31, v0
	v_lshrrev_b32_e32 v2, 26, v2
	s_waitcnt lgkmcnt(0)
	s_add_u32 s35, s8, 0xa000000
	v_add_u32_e32 v2, v0, v2
	s_addc_u32 s66, s9, 0
	v_lshlrev_b32_e32 v1, 3, v12
	v_ashrrev_i32_e32 v13, 6, v2
	v_and_b32_e32 v2, 0xc0, v2
	s_add_u32 s67, s8, 0x4e00000
	v_and_b32_e32 v1, -16, v1
	v_sub_u32_e32 v0, v0, v2
	s_addc_u32 s68, s9, 0
	s_ashr_i32 s3, s12, 6
	v_add_u32_e32 v1, v13, v1
	v_ashrrev_i16_sdwa v0, v3, sext(v0) dst_sel:DWORD dst_unused:UNUSED_PAD src0_sel:DWORD src1_sel:BYTE_0
	v_and_b32_e32 v3, 3, v13
	s_ashr_i32 s59, s58, 31
	s_ashr_i32 s15, s14, 31
	v_and_or_b32 v3, v1, s10, v3
	s_ashr_i32 s10, s12, 8
	s_lshl_b32 s69, s3, 10
	s_lshl_b64 s[16:17], s[58:59], 20
	s_lshl_b64 s[20:21], s[14:15], 20
	s_add_u32 s60, s67, s20
	v_lshlrev_b32_e32 v4, 5, v12
	v_bfe_i32 v14, v0, 0, 16
	v_lshlrev_b32_e32 v0, 1, v1
	v_lshrrev_b32_e32 v2, 2, v1
	s_addc_u32 s61, s68, s21
	s_add_i32 s70, s69, 0
	v_and_b32_e32 v4, 32, v4
	v_and_b32_e32 v0, 24, v0
	v_and_b32_e32 v2, 4, v2
	s_add_i32 m0, s70, 0x10000
	v_or3_b32 v0, v3, v2, v0
	v_add_lshl_u32 v2, v4, v14, 1
	global_load_lds_dwordx4 v154, s[60:61]
	s_add_i32 m0, s70, 0x12000
	v_lshl_add_u32 v162, v0, 12, v2
	v_lshrrev_b32_e32 v250, 3, v157
	v_and_b32_e32 v251, 6, v250
	v_and_b32_e32 v252, 7, v157
	v_xor_b32_e32 v251, v251, v252
	v_lshlrev_b32_e32 v251, 4, v251
	v_and_b32_e32 v252, 12, v250
	v_lshlrev_b32_e32 v252, 1, v252
	v_and_b32_e32 v253, 16, v250
	v_lshrrev_b32_e32 v253, 2, v253
	v_or_b32_e32 v252, v252, v253
	v_and_b32_e32 v253, 35, v250
	v_or_b32_e32 v250, v252, v253
	v_mul_u32_u24_e32 v250, 0x1000, v250
	v_add_u32_e32 v162, v250, v251
	v_add_u32_e32 v162, 0x40000, v162
	s_add_u32 s20, s60, 0x80000
	global_load_lds_dwordx4 v162, s[60:61]
	s_addc_u32 s21, s61, 0
	s_add_i32 m0, s70, 0x14000
	v_lshl_add_u32 v160, v1, 12, v2
	v_lshrrev_b32_e32 v250, 3, v157
	v_and_b32_e32 v251, 6, v250
	v_and_b32_e32 v252, 7, v157
	v_xor_b32_e32 v251, v251, v252
	v_lshlrev_b32_e32 v251, 4, v251
	v_mul_u32_u24_e32 v250, 0x1000, v250
	v_add_u32_e32 v160, v250, v251
	v_add_u32_e32 v160, 0x40000, v160
	global_load_lds_dwordx4 v154, s[20:21]
	s_add_i32 m0, s70, 0x16000
	s_add_u32 s62, s35, s16
	s_addc_u32 s63, s66, s17
	s_add_i32 s71, s70, 0x2000
	global_load_lds_dwordx4 v162, s[20:21]
	s_mov_b32 m0, s70
	s_add_u32 s16, s62, 0x80000
	global_load_lds_dwordx4 v152, s[62:63]
	s_mov_b32 m0, s71
	s_addc_u32 s17, s63, 0
	s_add_i32 s72, s70, 0x4000
	global_load_lds_dwordx4 v160, s[62:63]
	s_mov_b32 m0, s72
	s_add_i32 s73, s70, 0x6000
	global_load_lds_dwordx4 v152, s[16:17]
	s_mov_b32 m0, s73
	v_mov_b32_e32 v155, 0
	global_load_lds_dwordx4 v160, s[16:17]
	v_mov_b32_e32 v163, v155
	v_mov_b32_e32 v153, v155
	v_mov_b32_e32 v161, v155
	s_cmp_eq_u32 s10, 1
	s_mov_b32 s74, 0
	v_lshl_add_u64 v[6:7], s[60:61], 0, v[154:155]
	v_lshl_add_u64 v[4:5], s[60:61], 0, v[162:163]
	v_lshl_add_u64 v[0:1], s[62:63], 0, v[152:153]
	s_cselect_b64 s[16:17], -1, 0
	s_cmp_lg_u32 s10, 1
	v_lshl_add_u64 v[2:3], s[62:63], 0, v[160:161]
	s_cbranch_scc1 .LBB0_430
	s_barrier
.LBB0_430:
	s_add_u32 s20, s8, 0x6000000
	s_addc_u32 s21, s9, 0
	s_add_u32 s22, s8, 0x100000
	s_mov_b64 s[26:27], 0x80
	s_addc_u32 s23, s9, 0
	s_and_b32 s13, s3, 3
	s_add_i32 m0, s70, 0x18000
	v_lshl_add_u64 v[6:7], v[6:7], 0, s[26:27]
	s_lshl_b32 s11, s10, 13
	s_lshl_b32 s15, s13, 12
	s_waitcnt vmcnt(2)
	s_barrier
	global_load_lds_dwordx4 v[6:7], off
	v_lshl_add_u64 v[4:5], v[4:5], 0, s[26:27]
	s_add_i32 m0, s70, 0x1a000
	s_add_i32 s3, s70, 0x8000
	s_add_i32 s75, s70, 0xa000
	global_load_lds_dwordx4 v[4:5], off
	v_lshl_add_u64 v[0:1], v[0:1], 0, s[26:27]
	s_mov_b32 m0, s3
	s_add_u32 s8, s60, 0x80080
	global_load_lds_dwordx4 v[0:1], off
	v_lshl_add_u64 v[0:1], v[2:3], 0, s[26:27]
	s_mov_b32 m0, s75
	s_addc_u32 s9, s61, 0
	global_load_lds_dwordx4 v[0:1], off
	s_add_i32 m0, s70, 0x1c000
	v_lshl_add_u64 v[0:1], s[8:9], 0, v[154:155]
	global_load_lds_dwordx4 v[0:1], off
	v_lshl_add_u64 v[0:1], s[8:9], 0, v[162:163]
	s_add_i32 m0, s70, 0x1e000
	s_cmpk_lt_u32 s12, 0x100
	global_load_lds_dwordx4 v[0:1], off
	v_bfe_u32 v0, v8, 4, 2
	v_and_b32_e32 v1, 15, v8
	v_lshlrev_b32_e32 v3, 4, v0
	v_lshl_or_b32 v185, s10, 6, v1
	v_lshl_or_b32 v1, v1, 6, v3
	v_lshlrev_b32_e32 v3, 2, v8
	v_and_b32_e32 v3, 32, v3
	v_bitop3_b32 v4, v1, s11, v3 bitop3:0xde
	v_bitop3_b32 v186, v1, s15, v3 bitop3:0xde
	v_and_b32_e32 v250, 15, v157
	v_bfe_u32 v251, v157, 4, 2
	v_and_b32_e32 v252, 2, v250
	v_xor_b32_e32 v251, v251, v252
	v_and_b32_e32 v252, 4, v250
	v_lshlrev_b32_e32 v252, 4, v252
	v_lshl_or_b32 v251, v251, 4, v252
	v_lshl_or_b32 v250, v250, 7, v251
	v_bfe_u32 v253, v157, 6, 2
	v_lshl_or_b32 v186, v253, 12, v250
	v_lshlrev_b32_e32 v1, 15, v12
	v_lshlrev_b32_e32 v2, 3, v0
	v_and_b32_e32 v1, 0xffff0000, v1
	v_lshl_or_b32 v187, s13, 5, v2
	v_lshl_add_u32 v1, v13, 12, v1
	v_and_b32_e32 v2, 1, v12
	v_lshl_or_b32 v1, v2, 6, v1
	v_lshl_add_u32 v164, v14, 1, v1
	v_lshrrev_b32_e32 v250, 3, v157
	v_and_b32_e32 v251, 6, v250
	v_and_b32_e32 v252, 7, v157
	v_xor_b32_e32 v251, v251, v252
	v_lshlrev_b32_e32 v251, 4, v251
	v_mul_u32_u24_e32 v250, 0x1000, v250
	v_add_u32_e32 v164, v250, v251
	v_add_u32_e32 v164, 0x40000, v164
	v_lshlrev_b32_e32 v1, 15, v9
	s_cselect_b64 s[28:29], -1, 0
	s_lshl_b32 s12, s13, 2
	v_and_b32_e32 v1, 0xffff0000, v1
	s_waitcnt vmcnt(6)
	v_cmp_eq_u32_e64 s[8:9], 0, v0
	v_lshlrev_b32_e32 v0, 4, v157
	s_add_i32 s12, s12, 0
	v_lshl_add_u32 v1, v10, 12, v1
	v_and_b32_e32 v2, 1, v9
	s_movk_i32 s10, 0x100
	s_add_i32 s12, s12, 0x20000
	v_lshl_or_b32 v1, v2, 6, v1
	s_add_i32 s79, 0, 0x10000
	s_add_i32 s80, 0, 0x14000
	v_add_u32_e32 v0, 0, v0
	v_cmp_gt_u32_e64 s[10:11], s10, v157
	s_ashr_i32 s76, s42, 31
	s_mov_b32 s77, s42
	s_ashr_i32 s78, s2, 31
	v_lshl_add_u32 v188, v185, 4, s12
	v_mov_b32_e32 v165, v155
	v_lshl_add_u32 v166, v11, 1, v1
	v_lshrrev_b32_e32 v250, 3, v157
	v_and_b32_e32 v251, 6, v250
	v_and_b32_e32 v252, 7, v157
	v_xor_b32_e32 v251, v251, v252
	v_lshlrev_b32_e32 v251, 4, v251
	v_mul_u32_u24_e32 v250, 0x1000, v250
	v_add_u32_e32 v166, v250, v251
	v_mov_b32_e32 v167, v155
	v_mov_b64_e32 v[168:169], 0x200
	v_mov_b64_e32 v[170:171], 0x1ff
	v_add_u32_e32 v189, s79, v186
	v_add_u32_e32 v190, s80, v186
	v_add_u32_e32 v191, 0, v4
	v_and_b32_e32 v250, 15, v157
	v_bfe_u32 v251, v157, 4, 2
	v_and_b32_e32 v252, 2, v250
	v_xor_b32_e32 v251, v251, v252
	v_and_b32_e32 v252, 4, v250
	v_lshlrev_b32_e32 v252, 4, v252
	v_lshl_or_b32 v251, v251, 4, v252
	v_lshl_or_b32 v250, v250, 7, v251
	v_lshrrev_b32_e32 v253, 8, v157
	v_lshl_or_b32 v191, v253, 13, v250
	s_mov_b64 s[30:31], 0x40000
	s_mov_b64 s[44:45], 0x48000
	s_mov_b64 s[46:47], 0x50000
	s_mov_b64 s[48:49], 0x58000
	v_add_u32_e32 v192, 0x20000, v0
	s_barrier
	s_branch .LBB0_433

.LBB0_439:
	s_ashr_i32 s53, s52, 31
	s_lshl_b64 s[54:55], s[52:53], 20
	s_add_u32 s54, s35, s54
	s_addc_u32 s55, s66, s55
	s_and_b64 s[56:57], s[12:13], exec
	s_cselect_b32 s15, s55, s63
	s_cselect_b32 s53, s54, s62
	s_ashr_i32 s51, s50, 31
	s_lshl_b64 s[56:57], s[50:51], 20
	s_add_u32 s56, s67, s56
	s_addc_u32 s57, s68, s57
	s_and_b64 s[64:65], s[12:13], exec
	s_cselect_b32 s51, s57, s61
	s_cselect_b32 s59, s56, s60
	s_add_u32 s81, s60, 0x100
	s_addc_u32 s82, s61, 0
	s_add_u32 s60, s62, 0x80080
	s_addc_u32 s61, s63, 0
	s_mov_b32 s83, -2
	s_waitcnt lgkmcnt(0)
	s_cmp_eq_u32 s74, 1
	s_cbranch_scc1 .Lfa_3
	ds_read_b128 v[128:131], v189
	v_xor_b32_e32 v253, 64, v189
	ds_read_b128 v[132:135], v253
	ds_read_b128 v[136:139], v189 offset:2048
	ds_read_b128 v[140:143], v253 offset:2048
	ds_read_b128 v[144:147], v190
	v_xor_b32_e32 v253, 64, v190
	ds_read_b128 v[148:151], v253
	ds_read_b128 v[172:175], v190 offset:2048
	ds_read_b128 v[176:179], v253 offset:2048
	s_add_u32 s62, s60, 0xfff80080
	s_addc_u32 s63, s61, -1
	s_cmp_eq_u32 s83, 28
	s_cselect_b32 s65, s15, s63
	s_cselect_b32 s64, s53, s62
	s_cselect_b32 s63, s51, s82
	s_cselect_b32 s62, s59, s81
	v_lshl_add_u64 v[222:223], s[60:61], 0, v[166:167]
	s_add_i32 m0, s70, 0xc000
	ds_read_b128 v[180:183], v191
	v_xor_b32_e32 v253, 64, v191
	ds_read_b128 v[194:197], v253
	ds_read_b128 v[198:201], v191 offset:2048
	ds_read_b128 v[202:205], v253 offset:2048
	ds_read_b128 v[206:209], v191 offset:4096
	ds_read_b128 v[210:213], v253 offset:4096
	ds_read_b128 v[214:217], v191 offset:6144
	ds_read_b128 v[218:221], v253 offset:6144
	global_load_lds_dwordx4 v[222:223], off
	v_lshl_add_u64 v[222:223], s[60:61], 0, v[164:165]
	s_add_i32 m0, s70, 0xe000
	s_nop 0
	global_load_lds_dwordx4 v[222:223], off
	s_waitcnt vmcnt(24)
	s_waitcnt lgkmcnt(0)
	s_barrier
	s_setprio 1
	s_waitcnt lgkmcnt(0)
	v_mfma_f32_16x16x32_bf16 v[124:127], v[128:131], v[180:183], 0
	v_mfma_f32_16x16x32_bf16 v[120:123], v[136:139], v[180:183], 0
	v_mfma_f32_16x16x32_bf16 v[108:111], v[128:131], v[198:201], 0
	v_mfma_f32_16x16x32_bf16 v[104:107], v[136:139], v[198:201], 0
	v_mfma_f32_16x16x32_bf16 v[92:95], v[128:131], v[206:209], 0
	v_mfma_f32_16x16x32_bf16 v[88:91], v[136:139], v[206:209], 0
	v_mfma_f32_16x16x32_bf16 v[76:79], v[128:131], v[214:217], 0
	v_mfma_f32_16x16x32_bf16 v[72:75], v[136:139], v[214:217], 0
	v_mfma_f32_16x16x32_bf16 v[124:127], v[132:135], v[194:197], v[124:127]
	v_mfma_f32_16x16x32_bf16 v[120:123], v[140:143], v[194:197], v[120:123]
	v_mfma_f32_16x16x32_bf16 v[108:111], v[132:135], v[202:205], v[108:111]
	v_mfma_f32_16x16x32_bf16 v[104:107], v[140:143], v[202:205], v[104:107]
	v_mfma_f32_16x16x32_bf16 v[92:95], v[132:135], v[210:213], v[92:95]
	v_mfma_f32_16x16x32_bf16 v[88:91], v[140:143], v[210:213], v[88:91]
	v_mfma_f32_16x16x32_bf16 v[76:79], v[132:135], v[218:221], v[76:79]
	v_mfma_f32_16x16x32_bf16 v[72:75], v[140:143], v[218:221], v[72:75]
	s_setprio 0
	s_setprio 1
	v_mfma_f32_16x16x32_bf16 v[116:119], v[144:147], v[180:183], 0
	v_mfma_f32_16x16x32_bf16 v[112:115], v[172:175], v[180:183], 0
	v_mfma_f32_16x16x32_bf16 v[100:103], v[144:147], v[198:201], 0
	v_mfma_f32_16x16x32_bf16 v[96:99], v[172:175], v[198:201], 0
	v_mfma_f32_16x16x32_bf16 v[84:87], v[144:147], v[206:209], 0
	v_mfma_f32_16x16x32_bf16 v[80:83], v[172:175], v[206:209], 0
	v_mfma_f32_16x16x32_bf16 v[68:71], v[144:147], v[214:217], 0
	v_mfma_f32_16x16x32_bf16 v[64:67], v[172:175], v[214:217], 0
	v_mfma_f32_16x16x32_bf16 v[116:119], v[148:151], v[194:197], v[116:119]
	v_mfma_f32_16x16x32_bf16 v[112:115], v[176:179], v[194:197], v[112:115]
	v_mfma_f32_16x16x32_bf16 v[100:103], v[148:151], v[202:205], v[100:103]
	v_mfma_f32_16x16x32_bf16 v[96:99], v[176:179], v[202:205], v[96:99]
	v_mfma_f32_16x16x32_bf16 v[84:87], v[148:151], v[210:213], v[84:87]
	v_mfma_f32_16x16x32_bf16 v[80:83], v[176:179], v[210:213], v[80:83]
	v_mfma_f32_16x16x32_bf16 v[68:71], v[148:151], v[218:221], v[68:71]
	v_mfma_f32_16x16x32_bf16 v[64:67], v[176:179], v[218:221], v[64:67]
	s_setprio 0
	s_barrier
	s_add_i32 s84, s79, s69
	v_lshl_add_u64 v[222:223], s[62:63], 0, v[154:155]
	s_mov_b32 m0, s84
	ds_read_b128 v[180:183], v191 offset:16384
	v_xor_b32_e32 v253, 64, v191
	ds_read_b128 v[194:197], v253 offset:16384
	ds_read_b128 v[198:201], v191 offset:18432
	ds_read_b128 v[202:205], v253 offset:18432
	ds_read_b128 v[206:209], v191 offset:20480
	ds_read_b128 v[210:213], v253 offset:20480
	ds_read_b128 v[214:217], v191 offset:22528
	ds_read_b128 v[218:221], v253 offset:22528
	global_load_lds_dwordx4 v[222:223], off
	s_add_i32 m0, s84, 0x2000
	s_add_u32 s84, s62, 0x80000
	v_lshl_add_u64 v[224:225], s[62:63], 0, v[162:163]
	s_addc_u32 s85, s63, 0
	s_add_i32 s86, s80, s69
	global_load_lds_dwordx4 v[224:225], off
	v_lshl_add_u64 v[226:227], s[84:85], 0, v[154:155]
	s_mov_b32 m0, s86
	v_lshl_add_u64 v[228:229], s[64:65], 0, v[160:161]
	global_load_lds_dwordx4 v[226:227], off
	v_lshl_add_u64 v[226:227], s[84:85], 0, v[162:163]
	s_add_i32 m0, s86, 0x2000
	s_nop 0
	global_load_lds_dwordx4 v[226:227], off
	v_lshl_add_u64 v[226:227], s[64:65], 0, v[152:153]
	s_mov_b32 m0, s70
	s_nop 0
	global_load_lds_dwordx4 v[226:227], off
	s_mov_b32 m0, s71
	s_nop 0
	global_load_lds_dwordx4 v[228:229], off
	s_waitcnt vmcnt(24)
	s_waitcnt lgkmcnt(0)
	s_barrier
	s_setprio 1
	s_waitcnt lgkmcnt(0)
	v_mfma_f32_16x16x32_bf16 v[60:63], v[128:131], v[180:183], 0
	v_mfma_f32_16x16x32_bf16 v[56:59], v[136:139], v[180:183], 0
	v_mfma_f32_16x16x32_bf16 v[44:47], v[128:131], v[198:201], 0
	v_mfma_f32_16x16x32_bf16 v[40:43], v[136:139], v[198:201], 0
	v_mfma_f32_16x16x32_bf16 v[28:31], v[128:131], v[206:209], 0
	v_mfma_f32_16x16x32_bf16 v[24:27], v[136:139], v[206:209], 0
	v_mfma_f32_16x16x32_bf16 v[12:15], v[128:131], v[214:217], 0
	v_mfma_f32_16x16x32_bf16 v[8:11], v[136:139], v[214:217], 0
	v_mfma_f32_16x16x32_bf16 v[60:63], v[132:135], v[194:197], v[60:63]
	v_mfma_f32_16x16x32_bf16 v[56:59], v[140:143], v[194:197], v[56:59]
	v_mfma_f32_16x16x32_bf16 v[44:47], v[132:135], v[202:205], v[44:47]
	v_mfma_f32_16x16x32_bf16 v[40:43], v[140:143], v[202:205], v[40:43]
	v_mfma_f32_16x16x32_bf16 v[28:31], v[132:135], v[210:213], v[28:31]
	v_mfma_f32_16x16x32_bf16 v[24:27], v[140:143], v[210:213], v[24:27]
	v_mfma_f32_16x16x32_bf16 v[12:15], v[132:135], v[218:221], v[12:15]
	v_mfma_f32_16x16x32_bf16 v[8:11], v[140:143], v[218:221], v[8:11]
	s_setprio 0
	s_setprio 1
	v_mfma_f32_16x16x32_bf16 v[52:55], v[144:147], v[180:183], 0
	v_mfma_f32_16x16x32_bf16 v[48:51], v[172:175], v[180:183], 0
	v_mfma_f32_16x16x32_bf16 v[36:39], v[144:147], v[198:201], 0
	v_mfma_f32_16x16x32_bf16 v[32:35], v[172:175], v[198:201], 0
	v_mfma_f32_16x16x32_bf16 v[20:23], v[144:147], v[206:209], 0
	v_mfma_f32_16x16x32_bf16 v[16:19], v[172:175], v[206:209], 0
	v_mfma_f32_16x16x32_bf16 v[4:7], v[144:147], v[214:217], 0
	v_mfma_f32_16x16x32_bf16 v[0:3], v[172:175], v[214:217], 0
	v_mfma_f32_16x16x32_bf16 v[52:55], v[148:151], v[194:197], v[52:55]
	v_mfma_f32_16x16x32_bf16 v[48:51], v[176:179], v[194:197], v[48:51]
	v_mfma_f32_16x16x32_bf16 v[36:39], v[148:151], v[202:205], v[36:39]
	v_mfma_f32_16x16x32_bf16 v[32:35], v[176:179], v[202:205], v[32:35]
	v_mfma_f32_16x16x32_bf16 v[20:23], v[148:151], v[210:213], v[20:23]
	v_mfma_f32_16x16x32_bf16 v[16:19], v[176:179], v[210:213], v[16:19]
	v_mfma_f32_16x16x32_bf16 v[4:7], v[148:151], v[218:221], v[4:7]
	v_mfma_f32_16x16x32_bf16 v[0:3], v[176:179], v[218:221], v[0:3]
	s_setprio 0
	s_barrier
	s_add_i32 s84, 0, 0x18000
	s_add_i32 s85, 0, 0x1c000
	v_add_u32_e32 v140, s84, v186
	v_add_u32_e32 v176, s85, v186
	ds_read_b128 v[128:131], v140
	v_xor_b32_e32 v253, 64, v140
	ds_read_b128 v[132:135], v253
	ds_read_b128 v[136:139], v140 offset:2048
	ds_read_b128 v[140:143], v253 offset:2048
	ds_read_b128 v[144:147], v176
	v_xor_b32_e32 v253, 64, v176
	ds_read_b128 v[148:151], v253
	ds_read_b128 v[172:175], v176 offset:2048
	ds_read_b128 v[176:179], v253 offset:2048
	s_add_u32 s64, s64, 0x80000
	s_addc_u32 s65, s65, 0
	s_mov_b32 m0, s72
	v_lshl_add_u64 v[230:231], s[64:65], 0, v[152:153]
	ds_read_b128 v[180:183], v191 offset:32768
	v_xor_b32_e32 v253, 64, v191
	ds_read_b128 v[194:197], v253 offset:32768
	ds_read_b128 v[198:201], v191 offset:34816
	ds_read_b128 v[202:205], v253 offset:34816
	ds_read_b128 v[206:209], v191 offset:36864
	ds_read_b128 v[210:213], v253 offset:36864
	ds_read_b128 v[214:217], v191 offset:38912
	ds_read_b128 v[218:221], v253 offset:38912
	global_load_lds_dwordx4 v[230:231], off
	v_lshl_add_u64 v[230:231], s[64:65], 0, v[160:161]
	s_mov_b32 m0, s73
	s_nop 0
	global_load_lds_dwordx4 v[230:231], off
	s_waitcnt vmcnt(8)
	s_waitcnt lgkmcnt(0)
	s_barrier
	s_setprio 1
	s_waitcnt lgkmcnt(0)
	v_mfma_f32_16x16x32_bf16 v[124:127], v[128:131], v[180:183], v[124:127]
	v_mfma_f32_16x16x32_bf16 v[120:123], v[136:139], v[180:183], v[120:123]
	v_mfma_f32_16x16x32_bf16 v[108:111], v[128:131], v[198:201], v[108:111]
	v_mfma_f32_16x16x32_bf16 v[104:107], v[136:139], v[198:201], v[104:107]
	v_mfma_f32_16x16x32_bf16 v[92:95], v[128:131], v[206:209], v[92:95]
	v_mfma_f32_16x16x32_bf16 v[88:91], v[136:139], v[206:209], v[88:91]
	v_mfma_f32_16x16x32_bf16 v[76:79], v[128:131], v[214:217], v[76:79]
	v_mfma_f32_16x16x32_bf16 v[72:75], v[136:139], v[214:217], v[72:75]
	v_mfma_f32_16x16x32_bf16 v[124:127], v[132:135], v[194:197], v[124:127]
	v_mfma_f32_16x16x32_bf16 v[120:123], v[140:143], v[194:197], v[120:123]
	v_mfma_f32_16x16x32_bf16 v[108:111], v[132:135], v[202:205], v[108:111]
	v_mfma_f32_16x16x32_bf16 v[104:107], v[140:143], v[202:205], v[104:107]
	v_mfma_f32_16x16x32_bf16 v[92:95], v[132:135], v[210:213], v[92:95]
	v_mfma_f32_16x16x32_bf16 v[88:91], v[140:143], v[210:213], v[88:91]
	v_mfma_f32_16x16x32_bf16 v[76:79], v[132:135], v[218:221], v[76:79]
	v_mfma_f32_16x16x32_bf16 v[72:75], v[140:143], v[218:221], v[72:75]
	s_setprio 0
	s_setprio 1
	v_mfma_f32_16x16x32_bf16 v[116:119], v[144:147], v[180:183], v[116:119]
	v_mfma_f32_16x16x32_bf16 v[112:115], v[172:175], v[180:183], v[112:115]
	v_mfma_f32_16x16x32_bf16 v[100:103], v[144:147], v[198:201], v[100:103]
	v_mfma_f32_16x16x32_bf16 v[96:99], v[172:175], v[198:201], v[96:99]
	v_mfma_f32_16x16x32_bf16 v[84:87], v[144:147], v[206:209], v[84:87]
	v_mfma_f32_16x16x32_bf16 v[80:83], v[172:175], v[206:209], v[80:83]
	v_mfma_f32_16x16x32_bf16 v[68:71], v[144:147], v[214:217], v[68:71]
	v_mfma_f32_16x16x32_bf16 v[64:67], v[172:175], v[214:217], v[64:67]
	v_mfma_f32_16x16x32_bf16 v[116:119], v[148:151], v[194:197], v[116:119]
	v_mfma_f32_16x16x32_bf16 v[112:115], v[176:179], v[194:197], v[112:115]
	v_mfma_f32_16x16x32_bf16 v[100:103], v[148:151], v[202:205], v[100:103]
	v_mfma_f32_16x16x32_bf16 v[96:99], v[176:179], v[202:205], v[96:99]
	v_mfma_f32_16x16x32_bf16 v[84:87], v[148:151], v[210:213], v[84:87]
	v_mfma_f32_16x16x32_bf16 v[80:83], v[176:179], v[210:213], v[80:83]
	v_mfma_f32_16x16x32_bf16 v[68:71], v[148:151], v[218:221], v[68:71]
	v_mfma_f32_16x16x32_bf16 v[64:67], v[176:179], v[218:221], v[64:67]
	s_setprio 0
	s_barrier
	s_add_i32 s64, s84, s69
	v_lshl_add_u64 v[222:223], v[222:223], 0, s[26:27]
	s_mov_b32 m0, s64
	ds_read_b128 v[180:183], v191 offset:49152
	v_xor_b32_e32 v253, 64, v191
	ds_read_b128 v[194:197], v253 offset:49152
	ds_read_b128 v[198:201], v191 offset:51200
	ds_read_b128 v[202:205], v253 offset:51200
	ds_read_b128 v[206:209], v191 offset:53248
	ds_read_b128 v[210:213], v253 offset:53248
	ds_read_b128 v[214:217], v191 offset:55296
	ds_read_b128 v[218:221], v253 offset:55296
	global_load_lds_dwordx4 v[222:223], off
	s_add_i32 m0, s64, 0x2000
	s_add_u32 s62, s62, 0x80080
	v_lshl_add_u64 v[222:223], v[224:225], 0, s[26:27]
	s_addc_u32 s63, s63, 0
	s_add_i32 s64, s85, s69
	global_load_lds_dwordx4 v[222:223], off
	v_lshl_add_u64 v[222:223], s[62:63], 0, v[154:155]
	s_mov_b32 m0, s64
	s_nop 0
	global_load_lds_dwordx4 v[222:223], off
	v_lshl_add_u64 v[222:223], s[62:63], 0, v[162:163]
	s_add_i32 m0, s64, 0x2000
	s_nop 0
	global_load_lds_dwordx4 v[222:223], off
	v_lshl_add_u64 v[222:223], v[226:227], 0, s[26:27]
	s_mov_b32 m0, s3
	s_nop 0
	global_load_lds_dwordx4 v[222:223], off
	v_lshl_add_u64 v[222:223], v[228:229], 0, s[26:27]
	s_mov_b32 m0, s75
	s_nop 0
	global_load_lds_dwordx4 v[222:223], off
	s_waitcnt vmcnt(8)
	s_waitcnt lgkmcnt(0)
	s_barrier
	s_setprio 1
	s_waitcnt lgkmcnt(0)
	v_mfma_f32_16x16x32_bf16 v[60:63], v[128:131], v[180:183], v[60:63]
	v_mfma_f32_16x16x32_bf16 v[56:59], v[136:139], v[180:183], v[56:59]
	v_mfma_f32_16x16x32_bf16 v[44:47], v[128:131], v[198:201], v[44:47]
	v_mfma_f32_16x16x32_bf16 v[40:43], v[136:139], v[198:201], v[40:43]
	v_mfma_f32_16x16x32_bf16 v[28:31], v[128:131], v[206:209], v[28:31]
	v_mfma_f32_16x16x32_bf16 v[24:27], v[136:139], v[206:209], v[24:27]
	v_mfma_f32_16x16x32_bf16 v[12:15], v[128:131], v[214:217], v[12:15]
	v_mfma_f32_16x16x32_bf16 v[8:11], v[136:139], v[214:217], v[8:11]
	v_mfma_f32_16x16x32_bf16 v[60:63], v[132:135], v[194:197], v[60:63]
	v_mfma_f32_16x16x32_bf16 v[56:59], v[140:143], v[194:197], v[56:59]
	v_mfma_f32_16x16x32_bf16 v[44:47], v[132:135], v[202:205], v[44:47]
	v_mfma_f32_16x16x32_bf16 v[40:43], v[140:143], v[202:205], v[40:43]
	v_mfma_f32_16x16x32_bf16 v[28:31], v[132:135], v[210:213], v[28:31]
	v_mfma_f32_16x16x32_bf16 v[24:27], v[140:143], v[210:213], v[24:27]
	v_mfma_f32_16x16x32_bf16 v[12:15], v[132:135], v[218:221], v[12:15]
	v_mfma_f32_16x16x32_bf16 v[8:11], v[140:143], v[218:221], v[8:11]
	s_setprio 0
	s_setprio 1
	v_mfma_f32_16x16x32_bf16 v[52:55], v[144:147], v[180:183], v[52:55]
	v_mfma_f32_16x16x32_bf16 v[48:51], v[172:175], v[180:183], v[48:51]
	v_mfma_f32_16x16x32_bf16 v[36:39], v[144:147], v[198:201], v[36:39]
	v_mfma_f32_16x16x32_bf16 v[32:35], v[172:175], v[198:201], v[32:35]
	v_mfma_f32_16x16x32_bf16 v[20:23], v[144:147], v[206:209], v[20:23]
	v_mfma_f32_16x16x32_bf16 v[16:19], v[172:175], v[206:209], v[16:19]
	v_mfma_f32_16x16x32_bf16 v[4:7], v[144:147], v[214:217], v[4:7]
	v_mfma_f32_16x16x32_bf16 v[0:3], v[172:175], v[214:217], v[0:3]
	v_mfma_f32_16x16x32_bf16 v[52:55], v[148:151], v[194:197], v[52:55]
	v_mfma_f32_16x16x32_bf16 v[48:51], v[176:179], v[194:197], v[48:51]
	v_mfma_f32_16x16x32_bf16 v[36:39], v[148:151], v[202:205], v[36:39]
	v_mfma_f32_16x16x32_bf16 v[32:35], v[176:179], v[202:205], v[32:35]
	v_mfma_f32_16x16x32_bf16 v[20:23], v[148:151], v[210:213], v[20:23]
	v_mfma_f32_16x16x32_bf16 v[16:19], v[176:179], v[210:213], v[16:19]
	v_mfma_f32_16x16x32_bf16 v[4:7], v[148:151], v[218:221], v[4:7]
	v_mfma_f32_16x16x32_bf16 v[0:3], v[176:179], v[218:221], v[0:3]
	s_setprio 0
	s_barrier
	s_add_i32 s83, s83, 2
	s_add_u32 s81, s81, 0x100
	s_addc_u32 s82, s82, 0
	s_add_u32 s60, s60, 0x100
	s_addc_u32 s61, s61, 0
	s_cmp_gt_u32 s83, 29
	s_branch .LBB0_440
.Lfa_3:
	ds_read_b128 v[128:131], v189
	v_xor_b32_e32 v253, 64, v189
	ds_read_b128 v[132:135], v253
	ds_read_b128 v[136:139], v189 offset:2048
	ds_read_b128 v[140:143], v253 offset:2048
	ds_read_b128 v[144:147], v190
	v_xor_b32_e32 v253, 64, v190
	ds_read_b128 v[148:151], v253
	ds_read_b128 v[172:175], v190 offset:2048
	ds_read_b128 v[176:179], v253 offset:2048
	s_add_u32 s62, s60, 0xfff80080
	s_addc_u32 s63, s61, -1
	s_cmp_eq_u32 s83, 28
	s_cselect_b32 s65, s15, s63
	s_cselect_b32 s64, s53, s62
	s_cselect_b32 s63, s51, s82
	s_cselect_b32 s62, s59, s81
	v_lshl_add_u64 v[222:223], s[60:61], 0, v[166:167]
	s_add_i32 m0, s70, 0xc000
	ds_read_b128 v[180:183], v191
	v_xor_b32_e32 v253, 64, v191
	ds_read_b128 v[194:197], v253
	ds_read_b128 v[198:201], v191 offset:2048
	ds_read_b128 v[202:205], v253 offset:2048
	ds_read_b128 v[206:209], v191 offset:4096
	ds_read_b128 v[210:213], v253 offset:4096
	ds_read_b128 v[214:217], v191 offset:6144
	ds_read_b128 v[218:221], v253 offset:6144
	global_load_lds_dwordx4 v[222:223], off
	v_lshl_add_u64 v[222:223], s[60:61], 0, v[164:165]
	s_add_i32 m0, s70, 0xe000
	s_nop 0
	global_load_lds_dwordx4 v[222:223], off
	s_waitcnt vmcnt(8)
	s_waitcnt lgkmcnt(0)
	s_barrier
	s_setprio 1
	s_waitcnt lgkmcnt(0)
	v_mfma_f32_16x16x32_bf16 v[124:127], v[128:131], v[180:183], 0
	v_mfma_f32_16x16x32_bf16 v[120:123], v[136:139], v[180:183], 0
	v_mfma_f32_16x16x32_bf16 v[108:111], v[128:131], v[198:201], 0
	v_mfma_f32_16x16x32_bf16 v[104:107], v[136:139], v[198:201], 0
	v_mfma_f32_16x16x32_bf16 v[92:95], v[128:131], v[206:209], 0
	v_mfma_f32_16x16x32_bf16 v[88:91], v[136:139], v[206:209], 0
	v_mfma_f32_16x16x32_bf16 v[76:79], v[128:131], v[214:217], 0
	v_mfma_f32_16x16x32_bf16 v[72:75], v[136:139], v[214:217], 0
	v_mfma_f32_16x16x32_bf16 v[124:127], v[132:135], v[194:197], v[124:127]
	v_mfma_f32_16x16x32_bf16 v[120:123], v[140:143], v[194:197], v[120:123]
	v_mfma_f32_16x16x32_bf16 v[108:111], v[132:135], v[202:205], v[108:111]
	v_mfma_f32_16x16x32_bf16 v[104:107], v[140:143], v[202:205], v[104:107]
	v_mfma_f32_16x16x32_bf16 v[92:95], v[132:135], v[210:213], v[92:95]
	v_mfma_f32_16x16x32_bf16 v[88:91], v[140:143], v[210:213], v[88:91]
	v_mfma_f32_16x16x32_bf16 v[76:79], v[132:135], v[218:221], v[76:79]
	v_mfma_f32_16x16x32_bf16 v[72:75], v[140:143], v[218:221], v[72:75]
	s_setprio 0
	s_setprio 1
	v_mfma_f32_16x16x32_bf16 v[116:119], v[144:147], v[180:183], 0
	v_mfma_f32_16x16x32_bf16 v[112:115], v[172:175], v[180:183], 0
	v_mfma_f32_16x16x32_bf16 v[100:103], v[144:147], v[198:201], 0
	v_mfma_f32_16x16x32_bf16 v[96:99], v[172:175], v[198:201], 0
	v_mfma_f32_16x16x32_bf16 v[84:87], v[144:147], v[206:209], 0
	v_mfma_f32_16x16x32_bf16 v[80:83], v[172:175], v[206:209], 0
	v_mfma_f32_16x16x32_bf16 v[68:71], v[144:147], v[214:217], 0
	v_mfma_f32_16x16x32_bf16 v[64:67], v[172:175], v[214:217], 0
	v_mfma_f32_16x16x32_bf16 v[116:119], v[148:151], v[194:197], v[116:119]
	v_mfma_f32_16x16x32_bf16 v[112:115], v[176:179], v[194:197], v[112:115]
	v_mfma_f32_16x16x32_bf16 v[100:103], v[148:151], v[202:205], v[100:103]
	v_mfma_f32_16x16x32_bf16 v[96:99], v[176:179], v[202:205], v[96:99]
	v_mfma_f32_16x16x32_bf16 v[84:87], v[148:151], v[210:213], v[84:87]
	v_mfma_f32_16x16x32_bf16 v[80:83], v[176:179], v[210:213], v[80:83]
	v_mfma_f32_16x16x32_bf16 v[68:71], v[148:151], v[218:221], v[68:71]
	v_mfma_f32_16x16x32_bf16 v[64:67], v[176:179], v[218:221], v[64:67]
	s_setprio 0
	s_barrier
	s_add_i32 s84, s79, s69
	v_lshl_add_u64 v[222:223], s[62:63], 0, v[154:155]
	s_mov_b32 m0, s84
	ds_read_b128 v[180:183], v191 offset:16384
	v_xor_b32_e32 v253, 64, v191
	ds_read_b128 v[194:197], v253 offset:16384
	ds_read_b128 v[198:201], v191 offset:18432
	ds_read_b128 v[202:205], v253 offset:18432
	ds_read_b128 v[206:209], v191 offset:20480
	ds_read_b128 v[210:213], v253 offset:20480
	ds_read_b128 v[214:217], v191 offset:22528
	ds_read_b128 v[218:221], v253 offset:22528
	global_load_lds_dwordx4 v[222:223], off
	s_add_i32 m0, s84, 0x2000
	s_add_u32 s84, s62, 0x80000
	v_lshl_add_u64 v[224:225], s[62:63], 0, v[162:163]
	s_addc_u32 s85, s63, 0
	s_add_i32 s86, s80, s69
	global_load_lds_dwordx4 v[224:225], off
	v_lshl_add_u64 v[226:227], s[84:85], 0, v[154:155]
	s_mov_b32 m0, s86
	v_lshl_add_u64 v[228:229], s[64:65], 0, v[160:161]
	global_load_lds_dwordx4 v[226:227], off
	v_lshl_add_u64 v[226:227], s[84:85], 0, v[162:163]
	s_add_i32 m0, s86, 0x2000
	s_nop 0
	global_load_lds_dwordx4 v[226:227], off
	v_lshl_add_u64 v[226:227], s[64:65], 0, v[152:153]
	s_mov_b32 m0, s70
	s_nop 0
	global_load_lds_dwordx4 v[226:227], off
	s_mov_b32 m0, s71
	s_nop 0
	global_load_lds_dwordx4 v[228:229], off
	s_waitcnt vmcnt(8)
	s_waitcnt lgkmcnt(0)
	s_barrier
	s_setprio 1
	s_waitcnt lgkmcnt(0)
	v_mfma_f32_16x16x32_bf16 v[60:63], v[128:131], v[180:183], 0
	v_mfma_f32_16x16x32_bf16 v[56:59], v[136:139], v[180:183], 0
	v_mfma_f32_16x16x32_bf16 v[44:47], v[128:131], v[198:201], 0
	v_mfma_f32_16x16x32_bf16 v[40:43], v[136:139], v[198:201], 0
	v_mfma_f32_16x16x32_bf16 v[28:31], v[128:131], v[206:209], 0
	v_mfma_f32_16x16x32_bf16 v[24:27], v[136:139], v[206:209], 0
	v_mfma_f32_16x16x32_bf16 v[12:15], v[128:131], v[214:217], 0
	v_mfma_f32_16x16x32_bf16 v[8:11], v[136:139], v[214:217], 0
	v_mfma_f32_16x16x32_bf16 v[60:63], v[132:135], v[194:197], v[60:63]
	v_mfma_f32_16x16x32_bf16 v[56:59], v[140:143], v[194:197], v[56:59]
	v_mfma_f32_16x16x32_bf16 v[44:47], v[132:135], v[202:205], v[44:47]
	v_mfma_f32_16x16x32_bf16 v[40:43], v[140:143], v[202:205], v[40:43]
	v_mfma_f32_16x16x32_bf16 v[28:31], v[132:135], v[210:213], v[28:31]
	v_mfma_f32_16x16x32_bf16 v[24:27], v[140:143], v[210:213], v[24:27]
	v_mfma_f32_16x16x32_bf16 v[12:15], v[132:135], v[218:221], v[12:15]
	v_mfma_f32_16x16x32_bf16 v[8:11], v[140:143], v[218:221], v[8:11]
	s_setprio 0
	s_setprio 1
	v_mfma_f32_16x16x32_bf16 v[52:55], v[144:147], v[180:183], 0
	v_mfma_f32_16x16x32_bf16 v[48:51], v[172:175], v[180:183], 0
	v_mfma_f32_16x16x32_bf16 v[36:39], v[144:147], v[198:201], 0
	v_mfma_f32_16x16x32_bf16 v[32:35], v[172:175], v[198:201], 0
	v_mfma_f32_16x16x32_bf16 v[20:23], v[144:147], v[206:209], 0
	v_mfma_f32_16x16x32_bf16 v[16:19], v[172:175], v[206:209], 0
	v_mfma_f32_16x16x32_bf16 v[4:7], v[144:147], v[214:217], 0
	v_mfma_f32_16x16x32_bf16 v[0:3], v[172:175], v[214:217], 0
	v_mfma_f32_16x16x32_bf16 v[52:55], v[148:151], v[194:197], v[52:55]
	v_mfma_f32_16x16x32_bf16 v[48:51], v[176:179], v[194:197], v[48:51]
	v_mfma_f32_16x16x32_bf16 v[36:39], v[148:151], v[202:205], v[36:39]
	v_mfma_f32_16x16x32_bf16 v[32:35], v[176:179], v[202:205], v[32:35]
	v_mfma_f32_16x16x32_bf16 v[20:23], v[148:151], v[210:213], v[20:23]
	v_mfma_f32_16x16x32_bf16 v[16:19], v[176:179], v[210:213], v[16:19]
	v_mfma_f32_16x16x32_bf16 v[4:7], v[148:151], v[218:221], v[4:7]
	v_mfma_f32_16x16x32_bf16 v[0:3], v[176:179], v[218:221], v[0:3]
	s_setprio 0
	s_barrier
	s_add_i32 s84, 0, 0x18000
	s_add_i32 s85, 0, 0x1c000
	v_add_u32_e32 v140, s84, v186
	v_add_u32_e32 v176, s85, v186
	ds_read_b128 v[128:131], v140
	v_xor_b32_e32 v253, 64, v140
	ds_read_b128 v[132:135], v253
	ds_read_b128 v[136:139], v140 offset:2048
	ds_read_b128 v[140:143], v253 offset:2048
	ds_read_b128 v[144:147], v176
	v_xor_b32_e32 v253, 64, v176
	ds_read_b128 v[148:151], v253
	ds_read_b128 v[172:175], v176 offset:2048
	ds_read_b128 v[176:179], v253 offset:2048
	s_add_u32 s64, s64, 0x80000
	s_addc_u32 s65, s65, 0
	s_mov_b32 m0, s72
	v_lshl_add_u64 v[230:231], s[64:65], 0, v[152:153]
	ds_read_b128 v[180:183], v191 offset:32768
	v_xor_b32_e32 v253, 64, v191
	ds_read_b128 v[194:197], v253 offset:32768
	ds_read_b128 v[198:201], v191 offset:34816
	ds_read_b128 v[202:205], v253 offset:34816
	ds_read_b128 v[206:209], v191 offset:36864
	ds_read_b128 v[210:213], v253 offset:36864
	ds_read_b128 v[214:217], v191 offset:38912
	ds_read_b128 v[218:221], v253 offset:38912
	global_load_lds_dwordx4 v[230:231], off
	v_lshl_add_u64 v[230:231], s[64:65], 0, v[160:161]
	s_mov_b32 m0, s73
	s_nop 0
	global_load_lds_dwordx4 v[230:231], off
	s_waitcnt vmcnt(8)
	s_waitcnt lgkmcnt(0)
	s_barrier
	s_setprio 1
	s_waitcnt lgkmcnt(0)
	v_mfma_f32_16x16x32_bf16 v[124:127], v[128:131], v[180:183], v[124:127]
	v_mfma_f32_16x16x32_bf16 v[120:123], v[136:139], v[180:183], v[120:123]
	v_mfma_f32_16x16x32_bf16 v[108:111], v[128:131], v[198:201], v[108:111]
	v_mfma_f32_16x16x32_bf16 v[104:107], v[136:139], v[198:201], v[104:107]
	v_mfma_f32_16x16x32_bf16 v[92:95], v[128:131], v[206:209], v[92:95]
	v_mfma_f32_16x16x32_bf16 v[88:91], v[136:139], v[206:209], v[88:91]
	v_mfma_f32_16x16x32_bf16 v[76:79], v[128:131], v[214:217], v[76:79]
	v_mfma_f32_16x16x32_bf16 v[72:75], v[136:139], v[214:217], v[72:75]
	v_mfma_f32_16x16x32_bf16 v[124:127], v[132:135], v[194:197], v[124:127]
	v_mfma_f32_16x16x32_bf16 v[120:123], v[140:143], v[194:197], v[120:123]
	v_mfma_f32_16x16x32_bf16 v[108:111], v[132:135], v[202:205], v[108:111]
	v_mfma_f32_16x16x32_bf16 v[104:107], v[140:143], v[202:205], v[104:107]
	v_mfma_f32_16x16x32_bf16 v[92:95], v[132:135], v[210:213], v[92:95]
	v_mfma_f32_16x16x32_bf16 v[88:91], v[140:143], v[210:213], v[88:91]
	v_mfma_f32_16x16x32_bf16 v[76:79], v[132:135], v[218:221], v[76:79]
	v_mfma_f32_16x16x32_bf16 v[72:75], v[140:143], v[218:221], v[72:75]
	s_setprio 0
	s_setprio 1
	v_mfma_f32_16x16x32_bf16 v[116:119], v[144:147], v[180:183], v[116:119]
	v_mfma_f32_16x16x32_bf16 v[112:115], v[172:175], v[180:183], v[112:115]
	v_mfma_f32_16x16x32_bf16 v[100:103], v[144:147], v[198:201], v[100:103]
	v_mfma_f32_16x16x32_bf16 v[96:99], v[172:175], v[198:201], v[96:99]
	v_mfma_f32_16x16x32_bf16 v[84:87], v[144:147], v[206:209], v[84:87]
	v_mfma_f32_16x16x32_bf16 v[80:83], v[172:175], v[206:209], v[80:83]
	v_mfma_f32_16x16x32_bf16 v[68:71], v[144:147], v[214:217], v[68:71]
	v_mfma_f32_16x16x32_bf16 v[64:67], v[172:175], v[214:217], v[64:67]
	v_mfma_f32_16x16x32_bf16 v[116:119], v[148:151], v[194:197], v[116:119]
	v_mfma_f32_16x16x32_bf16 v[112:115], v[176:179], v[194:197], v[112:115]
	v_mfma_f32_16x16x32_bf16 v[100:103], v[148:151], v[202:205], v[100:103]
	v_mfma_f32_16x16x32_bf16 v[96:99], v[176:179], v[202:205], v[96:99]
	v_mfma_f32_16x16x32_bf16 v[84:87], v[148:151], v[210:213], v[84:87]
	v_mfma_f32_16x16x32_bf16 v[80:83], v[176:179], v[210:213], v[80:83]
	v_mfma_f32_16x16x32_bf16 v[68:71], v[148:151], v[218:221], v[68:71]
	v_mfma_f32_16x16x32_bf16 v[64:67], v[176:179], v[218:221], v[64:67]
	s_setprio 0
	s_barrier
	s_add_i32 s64, s84, s69
	v_lshl_add_u64 v[222:223], v[222:223], 0, s[26:27]
	s_mov_b32 m0, s64
	ds_read_b128 v[180:183], v191 offset:49152
	v_xor_b32_e32 v253, 64, v191
	ds_read_b128 v[194:197], v253 offset:49152
	ds_read_b128 v[198:201], v191 offset:51200
	ds_read_b128 v[202:205], v253 offset:51200
	ds_read_b128 v[206:209], v191 offset:53248
	ds_read_b128 v[210:213], v253 offset:53248
	ds_read_b128 v[214:217], v191 offset:55296
	ds_read_b128 v[218:221], v253 offset:55296
	global_load_lds_dwordx4 v[222:223], off
	s_add_i32 m0, s64, 0x2000
	s_add_u32 s62, s62, 0x80080
	v_lshl_add_u64 v[222:223], v[224:225], 0, s[26:27]
	s_addc_u32 s63, s63, 0
	s_add_i32 s64, s85, s69
	global_load_lds_dwordx4 v[222:223], off
	v_lshl_add_u64 v[222:223], s[62:63], 0, v[154:155]
	s_mov_b32 m0, s64
	s_nop 0
	global_load_lds_dwordx4 v[222:223], off
	v_lshl_add_u64 v[222:223], s[62:63], 0, v[162:163]
	s_add_i32 m0, s64, 0x2000
	s_nop 0
	global_load_lds_dwordx4 v[222:223], off
	v_lshl_add_u64 v[222:223], v[226:227], 0, s[26:27]
	s_mov_b32 m0, s3
	s_nop 0
	global_load_lds_dwordx4 v[222:223], off
	v_lshl_add_u64 v[222:223], v[228:229], 0, s[26:27]
	s_mov_b32 m0, s75
	s_nop 0
	global_load_lds_dwordx4 v[222:223], off
	s_waitcnt vmcnt(8)
	s_waitcnt lgkmcnt(0)
	s_barrier
	s_setprio 1
	s_waitcnt lgkmcnt(0)
	v_mfma_f32_16x16x32_bf16 v[60:63], v[128:131], v[180:183], v[60:63]
	v_mfma_f32_16x16x32_bf16 v[56:59], v[136:139], v[180:183], v[56:59]
	v_mfma_f32_16x16x32_bf16 v[44:47], v[128:131], v[198:201], v[44:47]
	v_mfma_f32_16x16x32_bf16 v[40:43], v[136:139], v[198:201], v[40:43]
	v_mfma_f32_16x16x32_bf16 v[28:31], v[128:131], v[206:209], v[28:31]
	v_mfma_f32_16x16x32_bf16 v[24:27], v[136:139], v[206:209], v[24:27]
	v_mfma_f32_16x16x32_bf16 v[12:15], v[128:131], v[214:217], v[12:15]
	v_mfma_f32_16x16x32_bf16 v[8:11], v[136:139], v[214:217], v[8:11]
	v_mfma_f32_16x16x32_bf16 v[60:63], v[132:135], v[194:197], v[60:63]
	v_mfma_f32_16x16x32_bf16 v[56:59], v[140:143], v[194:197], v[56:59]
	v_mfma_f32_16x16x32_bf16 v[44:47], v[132:135], v[202:205], v[44:47]
	v_mfma_f32_16x16x32_bf16 v[40:43], v[140:143], v[202:205], v[40:43]
	v_mfma_f32_16x16x32_bf16 v[28:31], v[132:135], v[210:213], v[28:31]
	v_mfma_f32_16x16x32_bf16 v[24:27], v[140:143], v[210:213], v[24:27]
	v_mfma_f32_16x16x32_bf16 v[12:15], v[132:135], v[218:221], v[12:15]
	v_mfma_f32_16x16x32_bf16 v[8:11], v[140:143], v[218:221], v[8:11]
	s_setprio 0
	s_setprio 1
	v_mfma_f32_16x16x32_bf16 v[52:55], v[144:147], v[180:183], v[52:55]
	v_mfma_f32_16x16x32_bf16 v[48:51], v[172:175], v[180:183], v[48:51]
	v_mfma_f32_16x16x32_bf16 v[36:39], v[144:147], v[198:201], v[36:39]
	v_mfma_f32_16x16x32_bf16 v[32:35], v[172:175], v[198:201], v[32:35]
	v_mfma_f32_16x16x32_bf16 v[20:23], v[144:147], v[206:209], v[20:23]
	v_mfma_f32_16x16x32_bf16 v[16:19], v[172:175], v[206:209], v[16:19]
	v_mfma_f32_16x16x32_bf16 v[4:7], v[144:147], v[214:217], v[4:7]
	v_mfma_f32_16x16x32_bf16 v[0:3], v[172:175], v[214:217], v[0:3]
	v_mfma_f32_16x16x32_bf16 v[52:55], v[148:151], v[194:197], v[52:55]
	v_mfma_f32_16x16x32_bf16 v[48:51], v[176:179], v[194:197], v[48:51]
	v_mfma_f32_16x16x32_bf16 v[36:39], v[148:151], v[202:205], v[36:39]
	v_mfma_f32_16x16x32_bf16 v[32:35], v[176:179], v[202:205], v[32:35]
	v_mfma_f32_16x16x32_bf16 v[20:23], v[148:151], v[210:213], v[20:23]
	v_mfma_f32_16x16x32_bf16 v[16:19], v[176:179], v[210:213], v[16:19]
	v_mfma_f32_16x16x32_bf16 v[4:7], v[148:151], v[218:221], v[4:7]
	v_mfma_f32_16x16x32_bf16 v[0:3], v[176:179], v[218:221], v[0:3]
	s_setprio 0
	s_barrier
	s_add_i32 s83, s83, 2
	s_add_u32 s81, s81, 0x100
	s_addc_u32 s82, s82, 0
	s_add_u32 s60, s60, 0x100
	s_addc_u32 s61, s61, 0
	s_cmp_gt_u32 s83, 29
.LBB0_440:
	ds_read_b128 v[128:131], v189
	v_xor_b32_e32 v253, 64, v189
	ds_read_b128 v[132:135], v253
	ds_read_b128 v[136:139], v189 offset:2048
	ds_read_b128 v[140:143], v253 offset:2048
	ds_read_b128 v[144:147], v190
	v_xor_b32_e32 v253, 64, v190
	ds_read_b128 v[148:151], v253
	ds_read_b128 v[172:175], v190 offset:2048
	ds_read_b128 v[176:179], v253 offset:2048
	s_add_u32 s62, s60, 0xfff80080
	s_addc_u32 s63, s61, -1
	s_cmp_eq_u32 s83, 28
	s_cselect_b32 s65, s15, s63
	s_cselect_b32 s64, s53, s62
	s_cselect_b32 s63, s51, s82
	s_cselect_b32 s62, s59, s81
	v_lshl_add_u64 v[222:223], s[60:61], 0, v[166:167]
	s_add_i32 m0, s70, 0xc000
	ds_read_b128 v[180:183], v191
	v_xor_b32_e32 v253, 64, v191
	ds_read_b128 v[194:197], v253
	ds_read_b128 v[198:201], v191 offset:2048
	ds_read_b128 v[202:205], v253 offset:2048
	ds_read_b128 v[206:209], v191 offset:4096
	ds_read_b128 v[210:213], v253 offset:4096
	ds_read_b128 v[214:217], v191 offset:6144
	ds_read_b128 v[218:221], v253 offset:6144
	global_load_lds_dwordx4 v[222:223], off
	v_lshl_add_u64 v[222:223], s[60:61], 0, v[164:165]
	s_add_i32 m0, s70, 0xe000
	s_nop 0
	global_load_lds_dwordx4 v[222:223], off
	s_waitcnt vmcnt(8)
	s_waitcnt lgkmcnt(0)
	s_barrier
	s_setprio 1
	s_waitcnt lgkmcnt(0)
	v_mfma_f32_16x16x32_bf16 v[124:127], v[128:131], v[180:183], v[124:127]
	v_mfma_f32_16x16x32_bf16 v[120:123], v[136:139], v[180:183], v[120:123]
	v_mfma_f32_16x16x32_bf16 v[108:111], v[128:131], v[198:201], v[108:111]
	v_mfma_f32_16x16x32_bf16 v[104:107], v[136:139], v[198:201], v[104:107]
	v_mfma_f32_16x16x32_bf16 v[92:95], v[128:131], v[206:209], v[92:95]
	v_mfma_f32_16x16x32_bf16 v[88:91], v[136:139], v[206:209], v[88:91]
	v_mfma_f32_16x16x32_bf16 v[76:79], v[128:131], v[214:217], v[76:79]
	v_mfma_f32_16x16x32_bf16 v[72:75], v[136:139], v[214:217], v[72:75]
	v_mfma_f32_16x16x32_bf16 v[124:127], v[132:135], v[194:197], v[124:127]
	v_mfma_f32_16x16x32_bf16 v[120:123], v[140:143], v[194:197], v[120:123]
	v_mfma_f32_16x16x32_bf16 v[108:111], v[132:135], v[202:205], v[108:111]
	v_mfma_f32_16x16x32_bf16 v[104:107], v[140:143], v[202:205], v[104:107]
	v_mfma_f32_16x16x32_bf16 v[92:95], v[132:135], v[210:213], v[92:95]
	v_mfma_f32_16x16x32_bf16 v[88:91], v[140:143], v[210:213], v[88:91]
	v_mfma_f32_16x16x32_bf16 v[76:79], v[132:135], v[218:221], v[76:79]
	v_mfma_f32_16x16x32_bf16 v[72:75], v[140:143], v[218:221], v[72:75]
	s_setprio 0
	s_setprio 1
	v_mfma_f32_16x16x32_bf16 v[116:119], v[144:147], v[180:183], v[116:119]
	v_mfma_f32_16x16x32_bf16 v[112:115], v[172:175], v[180:183], v[112:115]
	v_mfma_f32_16x16x32_bf16 v[100:103], v[144:147], v[198:201], v[100:103]
	v_mfma_f32_16x16x32_bf16 v[96:99], v[172:175], v[198:201], v[96:99]
	v_mfma_f32_16x16x32_bf16 v[84:87], v[144:147], v[206:209], v[84:87]
	v_mfma_f32_16x16x32_bf16 v[80:83], v[172:175], v[206:209], v[80:83]
	v_mfma_f32_16x16x32_bf16 v[68:71], v[144:147], v[214:217], v[68:71]
	v_mfma_f32_16x16x32_bf16 v[64:67], v[172:175], v[214:217], v[64:67]
	v_mfma_f32_16x16x32_bf16 v[116:119], v[148:151], v[194:197], v[116:119]
	v_mfma_f32_16x16x32_bf16 v[112:115], v[176:179], v[194:197], v[112:115]
	v_mfma_f32_16x16x32_bf16 v[100:103], v[148:151], v[202:205], v[100:103]
	v_mfma_f32_16x16x32_bf16 v[96:99], v[176:179], v[202:205], v[96:99]
	v_mfma_f32_16x16x32_bf16 v[84:87], v[148:151], v[210:213], v[84:87]
	v_mfma_f32_16x16x32_bf16 v[80:83], v[176:179], v[210:213], v[80:83]
	v_mfma_f32_16x16x32_bf16 v[68:71], v[148:151], v[218:221], v[68:71]
	v_mfma_f32_16x16x32_bf16 v[64:67], v[176:179], v[218:221], v[64:67]
	s_setprio 0
	s_barrier
	s_add_i32 s84, s79, s69
	v_lshl_add_u64 v[222:223], s[62:63], 0, v[154:155]
	s_mov_b32 m0, s84
	ds_read_b128 v[180:183], v191 offset:16384
	v_xor_b32_e32 v253, 64, v191
	ds_read_b128 v[194:197], v253 offset:16384
	ds_read_b128 v[198:201], v191 offset:18432
	ds_read_b128 v[202:205], v253 offset:18432
	ds_read_b128 v[206:209], v191 offset:20480
	ds_read_b128 v[210:213], v253 offset:20480
	ds_read_b128 v[214:217], v191 offset:22528
	ds_read_b128 v[218:221], v253 offset:22528
	global_load_lds_dwordx4 v[222:223], off
	s_add_i32 m0, s84, 0x2000
	s_add_u32 s84, s62, 0x80000
	v_lshl_add_u64 v[224:225], s[62:63], 0, v[162:163]
	s_addc_u32 s85, s63, 0
	s_add_i32 s86, s80, s69
	global_load_lds_dwordx4 v[224:225], off
	v_lshl_add_u64 v[226:227], s[84:85], 0, v[154:155]
	s_mov_b32 m0, s86
	v_lshl_add_u64 v[228:229], s[64:65], 0, v[160:161]
	global_load_lds_dwordx4 v[226:227], off
	v_lshl_add_u64 v[226:227], s[84:85], 0, v[162:163]
	s_add_i32 m0, s86, 0x2000
	s_nop 0
	global_load_lds_dwordx4 v[226:227], off
	v_lshl_add_u64 v[226:227], s[64:65], 0, v[152:153]
	s_mov_b32 m0, s70
	s_nop 0
	global_load_lds_dwordx4 v[226:227], off
	s_mov_b32 m0, s71
	s_nop 0
	global_load_lds_dwordx4 v[228:229], off
	s_waitcnt vmcnt(8)
	s_waitcnt lgkmcnt(0)
	s_barrier
	s_setprio 1
	s_waitcnt lgkmcnt(0)
	v_mfma_f32_16x16x32_bf16 v[60:63], v[128:131], v[180:183], v[60:63]
	v_mfma_f32_16x16x32_bf16 v[56:59], v[136:139], v[180:183], v[56:59]
	v_mfma_f32_16x16x32_bf16 v[44:47], v[128:131], v[198:201], v[44:47]
	v_mfma_f32_16x16x32_bf16 v[40:43], v[136:139], v[198:201], v[40:43]
	v_mfma_f32_16x16x32_bf16 v[28:31], v[128:131], v[206:209], v[28:31]
	v_mfma_f32_16x16x32_bf16 v[24:27], v[136:139], v[206:209], v[24:27]
	v_mfma_f32_16x16x32_bf16 v[12:15], v[128:131], v[214:217], v[12:15]
	v_mfma_f32_16x16x32_bf16 v[8:11], v[136:139], v[214:217], v[8:11]
	v_mfma_f32_16x16x32_bf16 v[60:63], v[132:135], v[194:197], v[60:63]
	v_mfma_f32_16x16x32_bf16 v[56:59], v[140:143], v[194:197], v[56:59]
	v_mfma_f32_16x16x32_bf16 v[44:47], v[132:135], v[202:205], v[44:47]
	v_mfma_f32_16x16x32_bf16 v[40:43], v[140:143], v[202:205], v[40:43]
	v_mfma_f32_16x16x32_bf16 v[28:31], v[132:135], v[210:213], v[28:31]
	v_mfma_f32_16x16x32_bf16 v[24:27], v[140:143], v[210:213], v[24:27]
	v_mfma_f32_16x16x32_bf16 v[12:15], v[132:135], v[218:221], v[12:15]
	v_mfma_f32_16x16x32_bf16 v[8:11], v[140:143], v[218:221], v[8:11]
	s_setprio 0
	s_setprio 1
	v_mfma_f32_16x16x32_bf16 v[52:55], v[144:147], v[180:183], v[52:55]
	v_mfma_f32_16x16x32_bf16 v[48:51], v[172:175], v[180:183], v[48:51]
	v_mfma_f32_16x16x32_bf16 v[36:39], v[144:147], v[198:201], v[36:39]
	v_mfma_f32_16x16x32_bf16 v[32:35], v[172:175], v[198:201], v[32:35]
	v_mfma_f32_16x16x32_bf16 v[20:23], v[144:147], v[206:209], v[20:23]
	v_mfma_f32_16x16x32_bf16 v[16:19], v[172:175], v[206:209], v[16:19]
	v_mfma_f32_16x16x32_bf16 v[4:7], v[144:147], v[214:217], v[4:7]
	v_mfma_f32_16x16x32_bf16 v[0:3], v[172:175], v[214:217], v[0:3]
	v_mfma_f32_16x16x32_bf16 v[52:55], v[148:151], v[194:197], v[52:55]
	v_mfma_f32_16x16x32_bf16 v[48:51], v[176:179], v[194:197], v[48:51]
	v_mfma_f32_16x16x32_bf16 v[36:39], v[148:151], v[202:205], v[36:39]
	v_mfma_f32_16x16x32_bf16 v[32:35], v[176:179], v[202:205], v[32:35]
	v_mfma_f32_16x16x32_bf16 v[20:23], v[148:151], v[210:213], v[20:23]
	v_mfma_f32_16x16x32_bf16 v[16:19], v[176:179], v[210:213], v[16:19]
	v_mfma_f32_16x16x32_bf16 v[4:7], v[148:151], v[218:221], v[4:7]
	v_mfma_f32_16x16x32_bf16 v[0:3], v[176:179], v[218:221], v[0:3]
	s_setprio 0
	s_barrier
	s_add_i32 s84, 0, 0x18000
	s_add_i32 s85, 0, 0x1c000
	v_add_u32_e32 v140, s84, v186
	v_add_u32_e32 v176, s85, v186
	ds_read_b128 v[128:131], v140
	v_xor_b32_e32 v253, 64, v140
	ds_read_b128 v[132:135], v253
	ds_read_b128 v[136:139], v140 offset:2048
	ds_read_b128 v[140:143], v253 offset:2048
	ds_read_b128 v[144:147], v176
	v_xor_b32_e32 v253, 64, v176
	ds_read_b128 v[148:151], v253
	ds_read_b128 v[172:175], v176 offset:2048
	ds_read_b128 v[176:179], v253 offset:2048
	s_add_u32 s64, s64, 0x80000
	s_addc_u32 s65, s65, 0
	s_mov_b32 m0, s72
	v_lshl_add_u64 v[230:231], s[64:65], 0, v[152:153]
	ds_read_b128 v[180:183], v191 offset:32768
	v_xor_b32_e32 v253, 64, v191
	ds_read_b128 v[194:197], v253 offset:32768
	ds_read_b128 v[198:201], v191 offset:34816
	ds_read_b128 v[202:205], v253 offset:34816
	ds_read_b128 v[206:209], v191 offset:36864
	ds_read_b128 v[210:213], v253 offset:36864
	ds_read_b128 v[214:217], v191 offset:38912
	ds_read_b128 v[218:221], v253 offset:38912
	global_load_lds_dwordx4 v[230:231], off
	v_lshl_add_u64 v[230:231], s[64:65], 0, v[160:161]
	s_mov_b32 m0, s73
	s_nop 0
	global_load_lds_dwordx4 v[230:231], off
	s_waitcnt vmcnt(8)
	s_waitcnt lgkmcnt(0)
	s_barrier
	s_setprio 1
	s_waitcnt lgkmcnt(0)
	v_mfma_f32_16x16x32_bf16 v[124:127], v[128:131], v[180:183], v[124:127]
	v_mfma_f32_16x16x32_bf16 v[120:123], v[136:139], v[180:183], v[120:123]
	v_mfma_f32_16x16x32_bf16 v[108:111], v[128:131], v[198:201], v[108:111]
	v_mfma_f32_16x16x32_bf16 v[104:107], v[136:139], v[198:201], v[104:107]
	v_mfma_f32_16x16x32_bf16 v[92:95], v[128:131], v[206:209], v[92:95]
	v_mfma_f32_16x16x32_bf16 v[88:91], v[136:139], v[206:209], v[88:91]
	v_mfma_f32_16x16x32_bf16 v[76:79], v[128:131], v[214:217], v[76:79]
	v_mfma_f32_16x16x32_bf16 v[72:75], v[136:139], v[214:217], v[72:75]
	v_mfma_f32_16x16x32_bf16 v[124:127], v[132:135], v[194:197], v[124:127]
	v_mfma_f32_16x16x32_bf16 v[120:123], v[140:143], v[194:197], v[120:123]
	v_mfma_f32_16x16x32_bf16 v[108:111], v[132:135], v[202:205], v[108:111]
	v_mfma_f32_16x16x32_bf16 v[104:107], v[140:143], v[202:205], v[104:107]
	v_mfma_f32_16x16x32_bf16 v[92:95], v[132:135], v[210:213], v[92:95]
	v_mfma_f32_16x16x32_bf16 v[88:91], v[140:143], v[210:213], v[88:91]
	v_mfma_f32_16x16x32_bf16 v[76:79], v[132:135], v[218:221], v[76:79]
	v_mfma_f32_16x16x32_bf16 v[72:75], v[140:143], v[218:221], v[72:75]
	s_setprio 0
	s_setprio 1
	v_mfma_f32_16x16x32_bf16 v[116:119], v[144:147], v[180:183], v[116:119]
	v_mfma_f32_16x16x32_bf16 v[112:115], v[172:175], v[180:183], v[112:115]
	v_mfma_f32_16x16x32_bf16 v[100:103], v[144:147], v[198:201], v[100:103]
	v_mfma_f32_16x16x32_bf16 v[96:99], v[172:175], v[198:201], v[96:99]
	v_mfma_f32_16x16x32_bf16 v[84:87], v[144:147], v[206:209], v[84:87]
	v_mfma_f32_16x16x32_bf16 v[80:83], v[172:175], v[206:209], v[80:83]
	v_mfma_f32_16x16x32_bf16 v[68:71], v[144:147], v[214:217], v[68:71]
	v_mfma_f32_16x16x32_bf16 v[64:67], v[172:175], v[214:217], v[64:67]
	v_mfma_f32_16x16x32_bf16 v[116:119], v[148:151], v[194:197], v[116:119]
	v_mfma_f32_16x16x32_bf16 v[112:115], v[176:179], v[194:197], v[112:115]
	v_mfma_f32_16x16x32_bf16 v[100:103], v[148:151], v[202:205], v[100:103]
	v_mfma_f32_16x16x32_bf16 v[96:99], v[176:179], v[202:205], v[96:99]
	v_mfma_f32_16x16x32_bf16 v[84:87], v[148:151], v[210:213], v[84:87]
	v_mfma_f32_16x16x32_bf16 v[80:83], v[176:179], v[210:213], v[80:83]
	v_mfma_f32_16x16x32_bf16 v[68:71], v[148:151], v[218:221], v[68:71]
	v_mfma_f32_16x16x32_bf16 v[64:67], v[176:179], v[218:221], v[64:67]
	s_setprio 0
	s_barrier
	s_add_i32 s64, s84, s69
	v_lshl_add_u64 v[222:223], v[222:223], 0, s[26:27]
	s_mov_b32 m0, s64
	ds_read_b128 v[180:183], v191 offset:49152
	v_xor_b32_e32 v253, 64, v191
	ds_read_b128 v[194:197], v253 offset:49152
	ds_read_b128 v[198:201], v191 offset:51200
	ds_read_b128 v[202:205], v253 offset:51200
	ds_read_b128 v[206:209], v191 offset:53248
	ds_read_b128 v[210:213], v253 offset:53248
	ds_read_b128 v[214:217], v191 offset:55296
	ds_read_b128 v[218:221], v253 offset:55296
	global_load_lds_dwordx4 v[222:223], off
	s_add_i32 m0, s64, 0x2000
	s_add_u32 s62, s62, 0x80080
	v_lshl_add_u64 v[222:223], v[224:225], 0, s[26:27]
	s_addc_u32 s63, s63, 0
	s_add_i32 s64, s85, s69
	global_load_lds_dwordx4 v[222:223], off
	v_lshl_add_u64 v[222:223], s[62:63], 0, v[154:155]
	s_mov_b32 m0, s64
	s_nop 0
	global_load_lds_dwordx4 v[222:223], off
	v_lshl_add_u64 v[222:223], s[62:63], 0, v[162:163]
	s_add_i32 m0, s64, 0x2000
	s_nop 0
	global_load_lds_dwordx4 v[222:223], off
	v_lshl_add_u64 v[222:223], v[226:227], 0, s[26:27]
	s_mov_b32 m0, s3
	s_nop 0
	global_load_lds_dwordx4 v[222:223], off
	v_lshl_add_u64 v[222:223], v[228:229], 0, s[26:27]
	s_mov_b32 m0, s75
	s_nop 0
	global_load_lds_dwordx4 v[222:223], off
	s_waitcnt vmcnt(8)
	s_waitcnt lgkmcnt(0)
	s_barrier
	s_setprio 1
	s_waitcnt lgkmcnt(0)
	v_mfma_f32_16x16x32_bf16 v[60:63], v[128:131], v[180:183], v[60:63]
	v_mfma_f32_16x16x32_bf16 v[56:59], v[136:139], v[180:183], v[56:59]
	v_mfma_f32_16x16x32_bf16 v[44:47], v[128:131], v[198:201], v[44:47]
	v_mfma_f32_16x16x32_bf16 v[40:43], v[136:139], v[198:201], v[40:43]
	v_mfma_f32_16x16x32_bf16 v[28:31], v[128:131], v[206:209], v[28:31]
	v_mfma_f32_16x16x32_bf16 v[24:27], v[136:139], v[206:209], v[24:27]
	v_mfma_f32_16x16x32_bf16 v[12:15], v[128:131], v[214:217], v[12:15]
	v_mfma_f32_16x16x32_bf16 v[8:11], v[136:139], v[214:217], v[8:11]
	v_mfma_f32_16x16x32_bf16 v[60:63], v[132:135], v[194:197], v[60:63]
	v_mfma_f32_16x16x32_bf16 v[56:59], v[140:143], v[194:197], v[56:59]
	v_mfma_f32_16x16x32_bf16 v[44:47], v[132:135], v[202:205], v[44:47]
	v_mfma_f32_16x16x32_bf16 v[40:43], v[140:143], v[202:205], v[40:43]
	v_mfma_f32_16x16x32_bf16 v[28:31], v[132:135], v[210:213], v[28:31]
	v_mfma_f32_16x16x32_bf16 v[24:27], v[140:143], v[210:213], v[24:27]
	v_mfma_f32_16x16x32_bf16 v[12:15], v[132:135], v[218:221], v[12:15]
	v_mfma_f32_16x16x32_bf16 v[8:11], v[140:143], v[218:221], v[8:11]
	s_setprio 0
	s_setprio 1
	v_mfma_f32_16x16x32_bf16 v[52:55], v[144:147], v[180:183], v[52:55]
	v_mfma_f32_16x16x32_bf16 v[48:51], v[172:175], v[180:183], v[48:51]
	v_mfma_f32_16x16x32_bf16 v[36:39], v[144:147], v[198:201], v[36:39]
	v_mfma_f32_16x16x32_bf16 v[32:35], v[172:175], v[198:201], v[32:35]
	v_mfma_f32_16x16x32_bf16 v[20:23], v[144:147], v[206:209], v[20:23]
	v_mfma_f32_16x16x32_bf16 v[16:19], v[172:175], v[206:209], v[16:19]
	v_mfma_f32_16x16x32_bf16 v[4:7], v[144:147], v[214:217], v[4:7]
	v_mfma_f32_16x16x32_bf16 v[0:3], v[172:175], v[214:217], v[0:3]
	v_mfma_f32_16x16x32_bf16 v[52:55], v[148:151], v[194:197], v[52:55]
	v_mfma_f32_16x16x32_bf16 v[48:51], v[176:179], v[194:197], v[48:51]
	v_mfma_f32_16x16x32_bf16 v[36:39], v[148:151], v[202:205], v[36:39]
	v_mfma_f32_16x16x32_bf16 v[32:35], v[176:179], v[202:205], v[32:35]
	v_mfma_f32_16x16x32_bf16 v[20:23], v[148:151], v[210:213], v[20:23]
	v_mfma_f32_16x16x32_bf16 v[16:19], v[176:179], v[210:213], v[16:19]
	v_mfma_f32_16x16x32_bf16 v[4:7], v[148:151], v[218:221], v[4:7]
	v_mfma_f32_16x16x32_bf16 v[0:3], v[176:179], v[218:221], v[0:3]
	s_setprio 0
	s_barrier
	s_add_i32 s83, s83, 2
	s_add_u32 s81, s81, 0x100
	s_addc_u32 s82, s82, 0
	s_add_u32 s60, s60, 0x100
	s_addc_u32 s61, s61, 0
	s_cmp_gt_u32 s83, 29
	s_cbranch_scc0 .LBB0_440
	s_and_b64 vcc, exec, s[28:29]
	s_cbranch_vccz .LBB0_443
	s_barrier

.LBB0_517:
	s_or_b64 exec, exec, s[8:9]
	s_mov_b64 s[10:11], s[0:1]
	v_mov_b32_e32 v8, v157
	s_waitcnt lgkmcnt(0)
	v_cndmask_b32_e64 v0, 0, 1, s[24:25]
	s_barrier
	v_cmp_ne_u32_e64 s[8:9], 1, v0
	s_andn2_b64 vcc, exec, s[24:25]
	v_readfirstlane_b32 s24, v8
	s_cbranch_vccnz .LBB0_535
	v_lshlrev_b32_e32 v0, 4, v8
	v_add_u32_e32 v1, 0x2000, v0
	v_ashrrev_i32_e32 v2, 31, v1
	v_lshrrev_b32_e32 v2, 22, v2
	v_add_u32_e32 v2, v1, v2
	v_ashrrev_i32_e32 v9, 10, v2
	v_mul_i32_i24_e32 v2, 0x400, v9
	v_sub_u32_e32 v1, v1, v2
	v_lshrrev_b32_e32 v2, 4, v1
	v_bitop3_b32 v1, v2, v1, 32 bitop3:0x6c
	v_ashrrev_i32_e32 v2, 31, v1
	v_lshrrev_b32_e32 v2, 26, v2
	v_add_u32_e32 v2, v1, v2
	v_lshlrev_b32_e32 v3, 3, v9
	v_ashrrev_i32_e32 v10, 6, v2
	v_and_b32_e32 v3, -16, v3
	v_add_u32_e32 v3, v10, v3
	v_and_b32_e32 v4, 3, v10
	s_mov_b32 s12, 0x1fffe0
	v_lshrrev_b32_e32 v5, 2, v3
	v_lshlrev_b32_e32 v6, 1, v3
	v_and_b32_e32 v2, 0xc0, v2
	v_and_or_b32 v4, v3, s12, v4
	v_and_b32_e32 v5, 4, v5
	v_and_b32_e32 v6, 24, v6
	v_sub_u32_e32 v1, v1, v2
	v_mov_b32_e32 v2, 1
	v_or3_b32 v4, v4, v5, v6
	v_lshlrev_b32_e32 v5, 5, v9
	v_ashrrev_i16_sdwa v1, v2, sext(v1) dst_sel:DWORD dst_unused:UNUSED_PAD src0_sel:DWORD src1_sel:BYTE_0
	v_and_b32_e32 v5, 32, v5
	v_bfe_i32 v11, v1, 0, 16
	v_add_lshl_u32 v1, v5, v11, 1
	v_lshl_add_u32 v128, v4, 11, v1
	v_lshrrev_b32_e32 v250, 3, v157
	v_and_b32_e32 v251, 6, v250
	v_and_b32_e32 v252, 7, v157
	v_xor_b32_e32 v251, v251, v252
	v_lshlrev_b32_e32 v251, 4, v251
	v_and_b32_e32 v252, 12, v250
	v_lshlrev_b32_e32 v252, 1, v252
	v_and_b32_e32 v253, 16, v250
	v_lshrrev_b32_e32 v253, 2, v253
	v_or_b32_e32 v252, v252, v253
	v_and_b32_e32 v253, 35, v250
	v_or_b32_e32 v250, v252, v253
	v_mul_u32_u24_e32 v250, 0x800, v250
	v_add_u32_e32 v128, v250, v251
	v_add_u32_e32 v128, 0x20000, v128
	v_lshl_add_u32 v130, v3, 11, v1
	v_lshrrev_b32_e32 v250, 3, v157
	v_and_b32_e32 v251, 6, v250
	v_and_b32_e32 v252, 7, v157
	v_xor_b32_e32 v251, v251, v252
	v_lshlrev_b32_e32 v251, 4, v251
	v_mul_u32_u24_e32 v250, 0x800, v250
	v_add_u32_e32 v130, v250, v251
	v_add_u32_e32 v130, 0x20000, v130
	v_bfe_i32 v1, v8, 27, 1
	v_lshrrev_b32_e32 v1, 22, v1
	v_add_u32_e32 v1, v0, v1
	s_load_dwordx2 s[10:11], s[10:11], 0x80
	v_and_b32_e32 v1, 0xfffffc00, v1
	v_sub_u32_e32 v0, v0, v1
	v_lshrrev_b32_e32 v1, 4, v0
	v_ashrrev_i32_e32 v3, 31, v8
	v_bitop3_b32 v0, v1, v0, 32 bitop3:0x6c
	v_lshrrev_b32_e32 v3, 26, v3
	v_ashrrev_i32_e32 v1, 31, v0
	v_add_u32_e32 v3, v8, v3
	s_waitcnt lgkmcnt(0)
	s_add_u32 s3, s10, 0x6000000
	v_lshrrev_b32_e32 v1, 26, v1
	v_ashrrev_i32_e32 v13, 6, v3
	s_addc_u32 s35, s11, 0
	v_add_u32_e32 v1, v0, v1
	v_lshlrev_b32_e32 v3, 3, v13
	s_add_u32 s52, s10, 0xf00000
	v_ashrrev_i32_e32 v12, 6, v1
	v_and_b32_e32 v3, -16, v3
	s_addc_u32 s53, s11, 0
	v_add_u32_e32 v3, v12, v3
	v_and_b32_e32 v4, 3, v12
	s_ashr_i32 s55, s2, 31
	v_and_or_b32 v4, v3, s12, v4
	s_lshr_b32 s12, s55, 29
	s_add_i32 s12, s2, s12
	s_ashr_i32 s23, s24, 6
	s_ashr_i32 s13, s12, 3
	s_and_b32 s12, s12, -8
	s_ashr_i32 s25, s24, 8
	s_lshl_b32 s54, s23, 10
	s_sub_i32 s12, s2, s12
	s_cmp_lt_i32 s12, 0
	s_movk_i32 s56, 0x161
	s_cselect_b32 s14, s56, 0x160
	s_mul_i32 s12, s14, s12
	s_add_i32 s12, s12, s13
	s_mul_hi_i32 s13, s12, 0x2e8ba2e9
	s_lshr_b32 s14, s13, 31
	s_ashr_i32 s13, s13, 3
	s_add_i32 s13, s13, s14
	s_lshl_b32 s14, s13, 1
	s_mul_i32 s13, s13, 44
	s_sub_i32 s12, s12, s13
	s_bfe_u32 s13, s12, 0x10007
	s_add_i32 s13, s12, s13
	s_bfe_i32 s15, s13, 0x80000
	s_and_b32 s13, s13, 0xfe
	s_sub_i32 s12, s12, s13
	s_sext_i32_i16 s15, s15
	s_sext_i32_i8 s12, s12
	v_lshrrev_b32_e32 v5, 2, v3
	v_lshlrev_b32_e32 v6, 1, v3
	v_and_b32_e32 v1, 0xc0, v1
	s_lshr_b32 s22, s15, 1
	s_add_i32 s46, s14, s12
	v_and_b32_e32 v5, 4, v5
	v_and_b32_e32 v6, 24, v6
	v_sub_u32_e32 v0, v0, v1
	s_ashr_i32 s47, s46, 31
	s_bfe_i64 s[14:15], s[22:23], 0x100000
	v_or3_b32 v4, v4, v5, v6
	v_lshlrev_b32_e32 v5, 5, v13
	v_ashrrev_i16_sdwa v0, v2, sext(v0) dst_sel:DWORD dst_unused:UNUSED_PAD src0_sel:DWORD src1_sel:BYTE_0
	s_lshl_b64 s[12:13], s[46:47], 19
	s_lshl_b64 s[14:15], s[14:15], 19
	v_and_b32_e32 v5, 32, v5
	v_bfe_i32 v14, v0, 0, 16
	s_add_u32 s48, s52, s14
	v_add_lshl_u32 v0, v5, v14, 1
	s_addc_u32 s49, s53, s15
	s_add_i32 s57, s54, 0
	v_lshl_add_u32 v132, v4, 11, v0
	v_lshrrev_b32_e32 v250, 3, v157
	v_and_b32_e32 v251, 6, v250
	v_and_b32_e32 v252, 7, v157
	v_xor_b32_e32 v251, v251, v252
	v_lshlrev_b32_e32 v251, 4, v251
	v_and_b32_e32 v252, 12, v250
	v_lshlrev_b32_e32 v252, 1, v252
	v_and_b32_e32 v253, 16, v250
	v_lshrrev_b32_e32 v253, 2, v253
	v_or_b32_e32 v252, v252, v253
	v_and_b32_e32 v253, 35, v250
	v_or_b32_e32 v250, v252, v253
	v_mul_u32_u24_e32 v250, 0x800, v250
	v_add_u32_e32 v132, v250, v251
	s_add_i32 m0, s57, 0x10000
	v_lshl_add_u32 v134, v3, 11, v0
	v_lshrrev_b32_e32 v250, 3, v157
	v_and_b32_e32 v251, 6, v250
	v_and_b32_e32 v252, 7, v157
	v_xor_b32_e32 v251, v251, v252
	v_lshlrev_b32_e32 v251, 4, v251
	v_mul_u32_u24_e32 v250, 0x800, v250
	v_add_u32_e32 v134, v250, v251
	global_load_lds_dwordx4 v132, s[48:49]
	s_add_i32 m0, s57, 0x12000
	s_add_u32 s14, s48, 0x40000
	global_load_lds_dwordx4 v128, s[48:49]
	s_addc_u32 s15, s49, 0
	s_add_i32 m0, s57, 0x14000
	v_mov_b32_e32 v133, 0
	global_load_lds_dwordx4 v132, s[14:15]
	s_add_i32 m0, s57, 0x16000
	s_add_u32 s50, s3, s12
	s_addc_u32 s51, s35, s13
	s_add_i32 s58, s57, 0x2000
	global_load_lds_dwordx4 v128, s[14:15]
	s_mov_b32 m0, s57
	s_add_u32 s12, s50, 0x40000
	global_load_lds_dwordx4 v134, s[50:51]
	s_mov_b32 m0, s58
	s_addc_u32 s13, s51, 0
	s_add_i32 s59, s57, 0x4000
	global_load_lds_dwordx4 v130, s[50:51]
	s_mov_b32 m0, s59
	s_add_i32 s60, s57, 0x6000
	global_load_lds_dwordx4 v134, s[12:13]
	s_mov_b32 m0, s60
	v_mov_b32_e32 v129, v133
	global_load_lds_dwordx4 v130, s[12:13]
	v_mov_b32_e32 v135, v133
	v_mov_b32_e32 v131, v133
	s_cmp_eq_u32 s25, 1
	s_mov_b32 s61, 0
	v_lshl_add_u64 v[6:7], s[48:49], 0, v[132:133]
	v_lshl_add_u64 v[4:5], s[48:49], 0, v[128:129]
	v_lshl_add_u64 v[0:1], s[50:51], 0, v[134:135]
	s_cselect_b64 s[12:13], -1, 0
	s_cmp_lg_u32 s25, 1
	v_lshl_add_u64 v[2:3], s[50:51], 0, v[130:131]
	s_cbranch_scc1 .LBB0_520
	s_barrier
.LBB0_520:
	s_add_u32 s14, s10, 0xa000000
	s_addc_u32 s15, s11, 0
	s_add_u32 s16, s10, 0x100000
	s_addc_u32 s17, s11, 0
	s_lshl_b32 s10, s23, 5
	s_mov_b64 s[20:21], 0x80
	s_and_b32 s27, s10, 0x60
	s_add_i32 m0, s57, 0x18000
	v_lshl_add_u64 v[6:7], v[6:7], 0, s[20:21]
	s_lshl_b32 s26, s25, 13
	s_lshl_b32 s28, s27, 7
	s_waitcnt vmcnt(2)
	s_barrier
	global_load_lds_dwordx4 v[6:7], off
	v_lshl_add_u64 v[4:5], v[4:5], 0, s[20:21]
	s_add_i32 m0, s57, 0x1a000
	s_add_i32 s62, s57, 0x8000
	s_add_i32 s63, s57, 0xa000
	global_load_lds_dwordx4 v[4:5], off
	v_lshl_add_u64 v[0:1], v[0:1], 0, s[20:21]
	s_mov_b32 m0, s62
	s_add_u32 s10, s48, 0x40080
	global_load_lds_dwordx4 v[0:1], off
	v_lshl_add_u64 v[0:1], v[2:3], 0, s[20:21]
	s_mov_b32 m0, s63
	s_addc_u32 s11, s49, 0
	global_load_lds_dwordx4 v[0:1], off
	s_add_i32 m0, s57, 0x1c000
	v_lshl_add_u64 v[0:1], s[10:11], 0, v[132:133]
	global_load_lds_dwordx4 v[0:1], off
	v_lshl_add_u64 v[0:1], s[10:11], 0, v[128:129]
	s_add_i32 m0, s57, 0x1e000
	s_cmp_lt_i32 s23, 4
	global_load_lds_dwordx4 v[0:1], off
	v_lshrrev_b32_e32 v1, 1, v8
	v_and_b32_e32 v1, 24, v1
	v_and_b32_e32 v0, 15, v8
	v_lshlrev_b32_e32 v2, 1, v1
	v_lshl_or_b32 v146, s25, 6, v0
	v_lshl_or_b32 v0, v0, 6, v2
	v_lshlrev_b32_e32 v2, 2, v8
	v_or_b32_e32 v149, s27, v1
	v_lshlrev_b32_e32 v1, 14, v9
	v_and_b32_e32 v2, 32, v2
	v_and_b32_e32 v1, 0xffff8000, v1
	v_bitop3_b32 v3, v0, s26, v2 bitop3:0xde
	v_bitop3_b32 v147, v0, s28, v2 bitop3:0xde
	v_and_b32_e32 v250, 15, v157
	v_bfe_u32 v251, v157, 4, 2
	v_and_b32_e32 v252, 2, v250
	v_xor_b32_e32 v251, v251, v252
	v_and_b32_e32 v252, 4, v250
	v_lshlrev_b32_e32 v252, 4, v252
	v_lshl_or_b32 v251, v251, 4, v252
	v_lshl_or_b32 v250, v250, 7, v251
	v_bfe_u32 v253, v157, 6, 2
	v_lshl_or_b32 v147, v253, 12, v250
	v_lshl_add_u32 v1, v10, 11, v1
	v_and_b32_e32 v2, 1, v9
	v_lshl_or_b32 v1, v2, 6, v1
	v_lshl_add_u32 v136, v11, 1, v1
	v_lshrrev_b32_e32 v250, 3, v157
	v_and_b32_e32 v251, 6, v250
	v_and_b32_e32 v252, 7, v157
	v_xor_b32_e32 v251, v251, v252
	v_lshlrev_b32_e32 v251, 4, v251
	v_mul_u32_u24_e32 v250, 0x800, v250
	v_add_u32_e32 v136, v250, v251
	v_add_u32_e32 v136, 0x20000, v136
	v_lshlrev_b32_e32 v1, 14, v13
	v_and_b32_e32 v1, 0xffff8000, v1
	s_waitcnt vmcnt(6)
	s_movk_i32 s10, 0xffc0
	v_mov_b32_e32 v0, s24
	v_lshl_add_u32 v1, v12, 11, v1
	v_and_b32_e32 v2, 1, v13
	s_sext_i32_i8 s69, s22
	s_cselect_b64 s[22:23], -1, 0
	v_bfi_b32 v148, s10, v0, v8
	s_cmpk_lt_u32 s24, 0x100
	v_lshlrev_b32_e32 v0, 4, v146
	v_lshl_or_b32 v1, v2, 6, v1
	s_cselect_b64 s[24:25], -1, 0
	s_ashr_i32 s64, s42, 31
	s_mov_b32 s65, s42
	v_mov_b32_e32 v137, v133
	v_lshl_add_u32 v138, v14, 1, v1
	v_lshrrev_b32_e32 v250, 3, v157
	v_and_b32_e32 v251, 6, v250
	v_and_b32_e32 v252, 7, v157
	v_xor_b32_e32 v251, v251, v252
	v_lshlrev_b32_e32 v251, 4, v251
	v_mul_u32_u24_e32 v250, 0x800, v250
	v_add_u32_e32 v138, v250, v251
	v_mov_b32_e32 v139, v133
	v_mov_b64_e32 v[140:141], 0xb00
	v_mov_b64_e32 v[142:143], 0xaff
	s_add_i32 s66, 0, 0x10000
	s_add_i32 s67, 0, 0x14000
	v_add_u32_e32 v150, 0, v3
	v_and_b32_e32 v250, 15, v157
	v_bfe_u32 v251, v157, 4, 2
	v_and_b32_e32 v252, 2, v250
	v_xor_b32_e32 v251, v251, v252
	v_and_b32_e32 v252, 4, v250
	v_lshlrev_b32_e32 v252, 4, v252
	v_lshl_or_b32 v251, v251, 4, v252
	v_lshl_or_b32 v250, v250, 7, v251
	v_lshrrev_b32_e32 v253, 8, v157
	v_lshl_or_b32 v150, v253, 13, v250
	v_add_u32_e32 v151, 0, v0
	v_mov_b32_e32 v152, 0x358637bd
	s_movk_i32 s68, 0x1600
	s_barrier
	s_branch .LBB0_523

.LBB0_525:
	s_ashr_i32 s29, s28, 31
	s_lshl_b64 s[30:31], s[28:29], 19
	s_add_u32 s30, s3, s30
	s_addc_u32 s31, s35, s31
	s_and_b64 s[44:45], s[10:11], exec
	s_cselect_b32 s29, s31, s51
	s_cselect_b32 s70, s30, s50
	s_ashr_i32 s27, s26, 31
	s_lshl_b64 s[44:45], s[26:27], 19
	s_add_u32 s44, s52, s44
	s_addc_u32 s45, s53, s45
	s_and_b64 s[72:73], s[10:11], exec
	s_cselect_b32 s71, s45, s49
	s_cselect_b32 s72, s44, s48
	s_lshl_b32 s27, s46, 8
	v_add_u32_e32 v0, s27, v148
	s_add_u32 s73, s48, 0x100
	v_ashrrev_i32_e32 v1, 31, v0
	s_addc_u32 s74, s49, 0
	v_lshl_add_u64 v[144:145], v[0:1], 4, s[16:17]
	s_add_u32 s46, s50, 0x40080
	s_addc_u32 s47, s51, 0
	s_mov_b32 s75, -2
	s_mov_b64 s[48:49], 0
	s_cmp_eq_u32 s61, 1
	s_cbranch_scc1 .Lfa_4
	v_add_u32_e32 v153, s66, v147
	ds_read_b128 v[160:163], v153
	v_xor_b32_e32 v253, 64, v153
	ds_read_b128 v[164:167], v253
	ds_read_b128 v[168:171], v153 offset:2048
	ds_read_b128 v[172:175], v253 offset:2048
	v_add_u32_e32 v153, s67, v147
	ds_read_b128 v[176:179], v153
	v_xor_b32_e32 v253, 64, v153
	ds_read_b128 v[180:183], v253
	ds_read_b128 v[186:189], v153 offset:2048
	ds_read_b128 v[190:193], v253 offset:2048
	s_add_u32 s50, s46, 0xfffc0080
	s_addc_u32 s51, s47, -1
	s_and_b64 s[48:49], s[48:49], exec
	s_cselect_b32 s51, s29, s51
	s_cselect_b32 s50, s70, s50
	s_cselect_b32 s49, s71, s74
	s_cselect_b32 s48, s72, s73
	v_lshl_add_u64 v[154:155], s[46:47], 0, v[138:139]
	s_add_i32 m0, s57, 0xc000
	ds_read_b128 v[194:197], v150
	v_xor_b32_e32 v253, 64, v150
	ds_read_b128 v[198:201], v253
	ds_read_b128 v[202:205], v150 offset:2048
	ds_read_b128 v[206:209], v253 offset:2048
	ds_read_b128 v[210:213], v150 offset:4096
	ds_read_b128 v[214:217], v253 offset:4096
	ds_read_b128 v[218:221], v150 offset:6144
	ds_read_b128 v[222:225], v253 offset:6144
	global_load_lds_dwordx4 v[154:155], off
	v_lshl_add_u64 v[154:155], s[46:47], 0, v[136:137]
	s_add_i32 m0, s57, 0xe000
	s_nop 0
	global_load_lds_dwordx4 v[154:155], off
	s_waitcnt vmcnt(16)
	s_waitcnt lgkmcnt(0)
	s_barrier
	s_setprio 1
	s_waitcnt lgkmcnt(0)
	v_mfma_f32_16x16x32_bf16 v[124:127], v[160:163], v[194:197], 0
	v_mfma_f32_16x16x32_bf16 v[116:119], v[168:171], v[194:197], 0
	v_mfma_f32_16x16x32_bf16 v[108:111], v[160:163], v[202:205], 0
	v_mfma_f32_16x16x32_bf16 v[100:103], v[168:171], v[202:205], 0
	v_mfma_f32_16x16x32_bf16 v[92:95], v[160:163], v[210:213], 0
	v_mfma_f32_16x16x32_bf16 v[84:87], v[168:171], v[210:213], 0
	v_mfma_f32_16x16x32_bf16 v[76:79], v[160:163], v[218:221], 0
	v_mfma_f32_16x16x32_bf16 v[68:71], v[168:171], v[218:221], 0
	v_mfma_f32_16x16x32_bf16 v[124:127], v[164:167], v[198:201], v[124:127]
	v_mfma_f32_16x16x32_bf16 v[116:119], v[172:175], v[198:201], v[116:119]
	v_mfma_f32_16x16x32_bf16 v[108:111], v[164:167], v[206:209], v[108:111]
	v_mfma_f32_16x16x32_bf16 v[100:103], v[172:175], v[206:209], v[100:103]
	v_mfma_f32_16x16x32_bf16 v[92:95], v[164:167], v[214:217], v[92:95]
	v_mfma_f32_16x16x32_bf16 v[84:87], v[172:175], v[214:217], v[84:87]
	v_mfma_f32_16x16x32_bf16 v[76:79], v[164:167], v[222:225], v[76:79]
	v_mfma_f32_16x16x32_bf16 v[68:71], v[172:175], v[222:225], v[68:71]
	s_setprio 0
	s_setprio 1
	v_mfma_f32_16x16x32_bf16 v[120:123], v[176:179], v[194:197], 0
	v_mfma_f32_16x16x32_bf16 v[112:115], v[186:189], v[194:197], 0
	v_mfma_f32_16x16x32_bf16 v[104:107], v[176:179], v[202:205], 0
	v_mfma_f32_16x16x32_bf16 v[96:99], v[186:189], v[202:205], 0
	v_mfma_f32_16x16x32_bf16 v[88:91], v[176:179], v[210:213], 0
	v_mfma_f32_16x16x32_bf16 v[80:83], v[186:189], v[210:213], 0
	v_mfma_f32_16x16x32_bf16 v[72:75], v[176:179], v[218:221], 0
	v_mfma_f32_16x16x32_bf16 v[64:67], v[186:189], v[218:221], 0
	v_mfma_f32_16x16x32_bf16 v[120:123], v[180:183], v[198:201], v[120:123]
	v_mfma_f32_16x16x32_bf16 v[112:115], v[190:193], v[198:201], v[112:115]
	v_mfma_f32_16x16x32_bf16 v[104:107], v[180:183], v[206:209], v[104:107]
	v_mfma_f32_16x16x32_bf16 v[96:99], v[190:193], v[206:209], v[96:99]
	v_mfma_f32_16x16x32_bf16 v[88:91], v[180:183], v[214:217], v[88:91]
	v_mfma_f32_16x16x32_bf16 v[80:83], v[190:193], v[214:217], v[80:83]
	v_mfma_f32_16x16x32_bf16 v[72:75], v[180:183], v[222:225], v[72:75]
	v_mfma_f32_16x16x32_bf16 v[64:67], v[190:193], v[222:225], v[64:67]
	s_setprio 0
	s_barrier
	s_add_i32 s76, s66, s54
	v_lshl_add_u64 v[154:155], s[48:49], 0, v[132:133]
	s_mov_b32 m0, s76
	ds_read_b128 v[194:197], v150 offset:16384
	v_xor_b32_e32 v253, 64, v150
	ds_read_b128 v[198:201], v253 offset:16384
	ds_read_b128 v[202:205], v150 offset:18432
	ds_read_b128 v[206:209], v253 offset:18432
	ds_read_b128 v[210:213], v150 offset:20480
	ds_read_b128 v[214:217], v253 offset:20480
	ds_read_b128 v[218:221], v150 offset:22528
	ds_read_b128 v[222:225], v253 offset:22528
	global_load_lds_dwordx4 v[154:155], off
	s_add_i32 m0, s76, 0x2000
	s_add_u32 s76, s48, 0x40000
	v_lshl_add_u64 v[226:227], s[48:49], 0, v[128:129]
	s_addc_u32 s77, s49, 0
	s_add_i32 s78, s67, s54
	global_load_lds_dwordx4 v[226:227], off
	v_lshl_add_u64 v[228:229], s[76:77], 0, v[132:133]
	s_mov_b32 m0, s78
	v_lshl_add_u64 v[230:231], s[50:51], 0, v[130:131]
	global_load_lds_dwordx4 v[228:229], off
	v_lshl_add_u64 v[228:229], s[76:77], 0, v[128:129]
	s_add_i32 m0, s78, 0x2000
	s_nop 0
	global_load_lds_dwordx4 v[228:229], off
	v_lshl_add_u64 v[228:229], s[50:51], 0, v[134:135]
	s_mov_b32 m0, s57
	s_nop 0
	global_load_lds_dwordx4 v[228:229], off
	s_mov_b32 m0, s58
	s_nop 0
	global_load_lds_dwordx4 v[230:231], off
	s_waitcnt vmcnt(16)
	s_waitcnt lgkmcnt(0)
	s_barrier
	s_setprio 1
	s_waitcnt lgkmcnt(0)
	v_mfma_f32_16x16x32_bf16 v[60:63], v[160:163], v[194:197], 0
	v_mfma_f32_16x16x32_bf16 v[52:55], v[168:171], v[194:197], 0
	v_mfma_f32_16x16x32_bf16 v[44:47], v[160:163], v[202:205], 0
	v_mfma_f32_16x16x32_bf16 v[36:39], v[168:171], v[202:205], 0
	v_mfma_f32_16x16x32_bf16 v[28:31], v[160:163], v[210:213], 0
	v_mfma_f32_16x16x32_bf16 v[20:23], v[168:171], v[210:213], 0
	v_mfma_f32_16x16x32_bf16 v[12:15], v[160:163], v[218:221], 0
	v_mfma_f32_16x16x32_bf16 v[4:7], v[168:171], v[218:221], 0
	v_mfma_f32_16x16x32_bf16 v[60:63], v[164:167], v[198:201], v[60:63]
	v_mfma_f32_16x16x32_bf16 v[52:55], v[172:175], v[198:201], v[52:55]
	v_mfma_f32_16x16x32_bf16 v[44:47], v[164:167], v[206:209], v[44:47]
	v_mfma_f32_16x16x32_bf16 v[36:39], v[172:175], v[206:209], v[36:39]
	v_mfma_f32_16x16x32_bf16 v[28:31], v[164:167], v[214:217], v[28:31]
	v_mfma_f32_16x16x32_bf16 v[20:23], v[172:175], v[214:217], v[20:23]
	v_mfma_f32_16x16x32_bf16 v[12:15], v[164:167], v[222:225], v[12:15]
	v_mfma_f32_16x16x32_bf16 v[4:7], v[172:175], v[222:225], v[4:7]
	s_setprio 0
	s_setprio 1
	v_mfma_f32_16x16x32_bf16 v[56:59], v[176:179], v[194:197], 0
	v_mfma_f32_16x16x32_bf16 v[48:51], v[186:189], v[194:197], 0
	v_mfma_f32_16x16x32_bf16 v[40:43], v[176:179], v[202:205], 0
	v_mfma_f32_16x16x32_bf16 v[32:35], v[186:189], v[202:205], 0
	v_mfma_f32_16x16x32_bf16 v[24:27], v[176:179], v[210:213], 0
	v_mfma_f32_16x16x32_bf16 v[16:19], v[186:189], v[210:213], 0
	v_mfma_f32_16x16x32_bf16 v[8:11], v[176:179], v[218:221], 0
	v_mfma_f32_16x16x32_bf16 v[0:3], v[186:189], v[218:221], 0
	v_mfma_f32_16x16x32_bf16 v[56:59], v[180:183], v[198:201], v[56:59]
	v_mfma_f32_16x16x32_bf16 v[48:51], v[190:193], v[198:201], v[48:51]
	v_mfma_f32_16x16x32_bf16 v[40:43], v[180:183], v[206:209], v[40:43]
	v_mfma_f32_16x16x32_bf16 v[32:35], v[190:193], v[206:209], v[32:35]
	v_mfma_f32_16x16x32_bf16 v[24:27], v[180:183], v[214:217], v[24:27]
	v_mfma_f32_16x16x32_bf16 v[16:19], v[190:193], v[214:217], v[16:19]
	v_mfma_f32_16x16x32_bf16 v[8:11], v[180:183], v[222:225], v[8:11]
	v_mfma_f32_16x16x32_bf16 v[0:3], v[190:193], v[222:225], v[0:3]
	s_setprio 0
	s_barrier
	s_add_i32 s76, 0, 0x18000
	v_add_u32_e32 v153, s76, v147
	s_add_i32 s77, 0, 0x1c000
	ds_read_b128 v[160:163], v153
	v_xor_b32_e32 v253, 64, v153
	ds_read_b128 v[164:167], v253
	ds_read_b128 v[168:171], v153 offset:2048
	ds_read_b128 v[172:175], v253 offset:2048
	v_add_u32_e32 v153, s77, v147
	ds_read_b128 v[176:179], v153
	v_xor_b32_e32 v253, 64, v153
	ds_read_b128 v[180:183], v253
	ds_read_b128 v[186:189], v153 offset:2048
	ds_read_b128 v[190:193], v253 offset:2048
	s_add_u32 s50, s50, 0x40000
	s_addc_u32 s51, s51, 0
	s_mov_b32 m0, s59
	v_lshl_add_u64 v[232:233], s[50:51], 0, v[134:135]
	ds_read_b128 v[194:197], v150 offset:32768
	v_xor_b32_e32 v253, 64, v150
	ds_read_b128 v[198:201], v253 offset:32768
	ds_read_b128 v[202:205], v150 offset:34816
	ds_read_b128 v[206:209], v253 offset:34816
	ds_read_b128 v[210:213], v150 offset:36864
	ds_read_b128 v[214:217], v253 offset:36864
	ds_read_b128 v[218:221], v150 offset:38912
	ds_read_b128 v[222:225], v253 offset:38912
	global_load_lds_dwordx4 v[232:233], off
	v_lshl_add_u64 v[232:233], s[50:51], 0, v[130:131]
	s_mov_b32 m0, s60
	s_nop 0
	global_load_lds_dwordx4 v[232:233], off
	s_waitcnt vmcnt(8)
	s_waitcnt lgkmcnt(0)
	s_barrier
	s_setprio 1
	s_waitcnt lgkmcnt(0)
	v_mfma_f32_16x16x32_bf16 v[124:127], v[160:163], v[194:197], v[124:127]
	v_mfma_f32_16x16x32_bf16 v[116:119], v[168:171], v[194:197], v[116:119]
	v_mfma_f32_16x16x32_bf16 v[108:111], v[160:163], v[202:205], v[108:111]
	v_mfma_f32_16x16x32_bf16 v[100:103], v[168:171], v[202:205], v[100:103]
	v_mfma_f32_16x16x32_bf16 v[92:95], v[160:163], v[210:213], v[92:95]
	v_mfma_f32_16x16x32_bf16 v[84:87], v[168:171], v[210:213], v[84:87]
	v_mfma_f32_16x16x32_bf16 v[76:79], v[160:163], v[218:221], v[76:79]
	v_mfma_f32_16x16x32_bf16 v[68:71], v[168:171], v[218:221], v[68:71]
	v_mfma_f32_16x16x32_bf16 v[124:127], v[164:167], v[198:201], v[124:127]
	v_mfma_f32_16x16x32_bf16 v[116:119], v[172:175], v[198:201], v[116:119]
	v_mfma_f32_16x16x32_bf16 v[108:111], v[164:167], v[206:209], v[108:111]
	v_mfma_f32_16x16x32_bf16 v[100:103], v[172:175], v[206:209], v[100:103]
	v_mfma_f32_16x16x32_bf16 v[92:95], v[164:167], v[214:217], v[92:95]
	v_mfma_f32_16x16x32_bf16 v[84:87], v[172:175], v[214:217], v[84:87]
	v_mfma_f32_16x16x32_bf16 v[76:79], v[164:167], v[222:225], v[76:79]
	v_mfma_f32_16x16x32_bf16 v[68:71], v[172:175], v[222:225], v[68:71]
	s_setprio 0
	s_setprio 1
	v_mfma_f32_16x16x32_bf16 v[120:123], v[176:179], v[194:197], v[120:123]
	v_mfma_f32_16x16x32_bf16 v[112:115], v[186:189], v[194:197], v[112:115]
	v_mfma_f32_16x16x32_bf16 v[104:107], v[176:179], v[202:205], v[104:107]
	v_mfma_f32_16x16x32_bf16 v[96:99], v[186:189], v[202:205], v[96:99]
	v_mfma_f32_16x16x32_bf16 v[88:91], v[176:179], v[210:213], v[88:91]
	v_mfma_f32_16x16x32_bf16 v[80:83], v[186:189], v[210:213], v[80:83]
	v_mfma_f32_16x16x32_bf16 v[72:75], v[176:179], v[218:221], v[72:75]
	v_mfma_f32_16x16x32_bf16 v[64:67], v[186:189], v[218:221], v[64:67]
	v_mfma_f32_16x16x32_bf16 v[120:123], v[180:183], v[198:201], v[120:123]
	v_mfma_f32_16x16x32_bf16 v[112:115], v[190:193], v[198:201], v[112:115]
	v_mfma_f32_16x16x32_bf16 v[104:107], v[180:183], v[206:209], v[104:107]
	v_mfma_f32_16x16x32_bf16 v[96:99], v[190:193], v[206:209], v[96:99]
	v_mfma_f32_16x16x32_bf16 v[88:91], v[180:183], v[214:217], v[88:91]
	v_mfma_f32_16x16x32_bf16 v[80:83], v[190:193], v[214:217], v[80:83]
	v_mfma_f32_16x16x32_bf16 v[72:75], v[180:183], v[222:225], v[72:75]
	v_mfma_f32_16x16x32_bf16 v[64:67], v[190:193], v[222:225], v[64:67]
	s_setprio 0
	s_barrier
	s_add_i32 s50, s76, s54
	v_lshl_add_u64 v[154:155], v[154:155], 0, s[20:21]
	s_mov_b32 m0, s50
	ds_read_b128 v[194:197], v150 offset:49152
	v_xor_b32_e32 v253, 64, v150
	ds_read_b128 v[198:201], v253 offset:49152
	ds_read_b128 v[202:205], v150 offset:51200
	ds_read_b128 v[206:209], v253 offset:51200
	ds_read_b128 v[210:213], v150 offset:53248
	ds_read_b128 v[214:217], v253 offset:53248
	ds_read_b128 v[218:221], v150 offset:55296
	ds_read_b128 v[222:225], v253 offset:55296
	global_load_lds_dwordx4 v[154:155], off
	s_add_i32 m0, s50, 0x2000
	s_add_u32 s48, s48, 0x40080
	v_lshl_add_u64 v[154:155], v[226:227], 0, s[20:21]
	s_addc_u32 s49, s49, 0
	s_add_i32 s50, s77, s54
	global_load_lds_dwordx4 v[154:155], off
	v_lshl_add_u64 v[154:155], s[48:49], 0, v[132:133]
	s_mov_b32 m0, s50
	s_nop 0
	global_load_lds_dwordx4 v[154:155], off
	v_lshl_add_u64 v[154:155], s[48:49], 0, v[128:129]
	s_add_i32 m0, s50, 0x2000
	s_nop 0
	global_load_lds_dwordx4 v[154:155], off
	v_lshl_add_u64 v[154:155], v[228:229], 0, s[20:21]
	s_mov_b32 m0, s62
	s_nop 0
	global_load_lds_dwordx4 v[154:155], off
	v_lshl_add_u64 v[154:155], v[230:231], 0, s[20:21]
	s_mov_b32 m0, s63
	s_nop 0
	global_load_lds_dwordx4 v[154:155], off
	s_waitcnt vmcnt(8)
	s_waitcnt lgkmcnt(0)
	s_barrier
	s_setprio 1
	s_waitcnt lgkmcnt(0)
	v_mfma_f32_16x16x32_bf16 v[60:63], v[160:163], v[194:197], v[60:63]
	v_mfma_f32_16x16x32_bf16 v[52:55], v[168:171], v[194:197], v[52:55]
	v_mfma_f32_16x16x32_bf16 v[44:47], v[160:163], v[202:205], v[44:47]
	v_mfma_f32_16x16x32_bf16 v[36:39], v[168:171], v[202:205], v[36:39]
	v_mfma_f32_16x16x32_bf16 v[28:31], v[160:163], v[210:213], v[28:31]
	v_mfma_f32_16x16x32_bf16 v[20:23], v[168:171], v[210:213], v[20:23]
	v_mfma_f32_16x16x32_bf16 v[12:15], v[160:163], v[218:221], v[12:15]
	v_mfma_f32_16x16x32_bf16 v[4:7], v[168:171], v[218:221], v[4:7]
	v_mfma_f32_16x16x32_bf16 v[60:63], v[164:167], v[198:201], v[60:63]
	v_mfma_f32_16x16x32_bf16 v[52:55], v[172:175], v[198:201], v[52:55]
	v_mfma_f32_16x16x32_bf16 v[44:47], v[164:167], v[206:209], v[44:47]
	v_mfma_f32_16x16x32_bf16 v[36:39], v[172:175], v[206:209], v[36:39]
	v_mfma_f32_16x16x32_bf16 v[28:31], v[164:167], v[214:217], v[28:31]
	v_mfma_f32_16x16x32_bf16 v[20:23], v[172:175], v[214:217], v[20:23]
	v_mfma_f32_16x16x32_bf16 v[12:15], v[164:167], v[222:225], v[12:15]
	v_mfma_f32_16x16x32_bf16 v[4:7], v[172:175], v[222:225], v[4:7]
	s_setprio 0
	s_setprio 1
	v_mfma_f32_16x16x32_bf16 v[56:59], v[176:179], v[194:197], v[56:59]
	v_mfma_f32_16x16x32_bf16 v[48:51], v[186:189], v[194:197], v[48:51]
	v_mfma_f32_16x16x32_bf16 v[40:43], v[176:179], v[202:205], v[40:43]
	v_mfma_f32_16x16x32_bf16 v[32:35], v[186:189], v[202:205], v[32:35]
	v_mfma_f32_16x16x32_bf16 v[24:27], v[176:179], v[210:213], v[24:27]
	v_mfma_f32_16x16x32_bf16 v[16:19], v[186:189], v[210:213], v[16:19]
	v_mfma_f32_16x16x32_bf16 v[8:11], v[176:179], v[218:221], v[8:11]
	v_mfma_f32_16x16x32_bf16 v[0:3], v[186:189], v[218:221], v[0:3]
	v_mfma_f32_16x16x32_bf16 v[56:59], v[180:183], v[198:201], v[56:59]
	v_mfma_f32_16x16x32_bf16 v[48:51], v[190:193], v[198:201], v[48:51]
	v_mfma_f32_16x16x32_bf16 v[40:43], v[180:183], v[206:209], v[40:43]
	v_mfma_f32_16x16x32_bf16 v[32:35], v[190:193], v[206:209], v[32:35]
	v_mfma_f32_16x16x32_bf16 v[24:27], v[180:183], v[214:217], v[24:27]
	v_mfma_f32_16x16x32_bf16 v[16:19], v[190:193], v[214:217], v[16:19]
	v_mfma_f32_16x16x32_bf16 v[8:11], v[180:183], v[222:225], v[8:11]
	v_mfma_f32_16x16x32_bf16 v[0:3], v[190:193], v[222:225], v[0:3]
	s_setprio 0
	s_barrier
	s_add_i32 s75, s75, 2
	s_add_u32 s73, s73, 0x100
	s_addc_u32 s74, s74, 0
	s_add_u32 s46, s46, 0x100
	s_addc_u32 s47, s47, 0
	s_branch .LBB0_527
.Lfa_4:
	v_add_u32_e32 v153, s66, v147
	ds_read_b128 v[160:163], v153
	v_xor_b32_e32 v253, 64, v153
	ds_read_b128 v[164:167], v253
	ds_read_b128 v[168:171], v153 offset:2048
	ds_read_b128 v[172:175], v253 offset:2048
	v_add_u32_e32 v153, s67, v147
	ds_read_b128 v[176:179], v153
	v_xor_b32_e32 v253, 64, v153
	ds_read_b128 v[180:183], v253
	ds_read_b128 v[186:189], v153 offset:2048
	ds_read_b128 v[190:193], v253 offset:2048
	s_add_u32 s50, s46, 0xfffc0080
	s_addc_u32 s51, s47, -1
	s_and_b64 s[48:49], s[48:49], exec
	s_cselect_b32 s51, s29, s51
	s_cselect_b32 s50, s70, s50
	s_cselect_b32 s49, s71, s74
	s_cselect_b32 s48, s72, s73
	v_lshl_add_u64 v[154:155], s[46:47], 0, v[138:139]
	s_add_i32 m0, s57, 0xc000
	ds_read_b128 v[194:197], v150
	v_xor_b32_e32 v253, 64, v150
	ds_read_b128 v[198:201], v253
	ds_read_b128 v[202:205], v150 offset:2048
	ds_read_b128 v[206:209], v253 offset:2048
	ds_read_b128 v[210:213], v150 offset:4096
	ds_read_b128 v[214:217], v253 offset:4096
	ds_read_b128 v[218:221], v150 offset:6144
	ds_read_b128 v[222:225], v253 offset:6144
	global_load_lds_dwordx4 v[154:155], off
	v_lshl_add_u64 v[154:155], s[46:47], 0, v[136:137]
	s_add_i32 m0, s57, 0xe000
	s_nop 0
	global_load_lds_dwordx4 v[154:155], off
	s_waitcnt vmcnt(8)
	s_waitcnt lgkmcnt(0)
	s_barrier
	s_setprio 1
	s_waitcnt lgkmcnt(0)
	v_mfma_f32_16x16x32_bf16 v[124:127], v[160:163], v[194:197], 0
	v_mfma_f32_16x16x32_bf16 v[116:119], v[168:171], v[194:197], 0
	v_mfma_f32_16x16x32_bf16 v[108:111], v[160:163], v[202:205], 0
	v_mfma_f32_16x16x32_bf16 v[100:103], v[168:171], v[202:205], 0
	v_mfma_f32_16x16x32_bf16 v[92:95], v[160:163], v[210:213], 0
	v_mfma_f32_16x16x32_bf16 v[84:87], v[168:171], v[210:213], 0
	v_mfma_f32_16x16x32_bf16 v[76:79], v[160:163], v[218:221], 0
	v_mfma_f32_16x16x32_bf16 v[68:71], v[168:171], v[218:221], 0
	v_mfma_f32_16x16x32_bf16 v[124:127], v[164:167], v[198:201], v[124:127]
	v_mfma_f32_16x16x32_bf16 v[116:119], v[172:175], v[198:201], v[116:119]
	v_mfma_f32_16x16x32_bf16 v[108:111], v[164:167], v[206:209], v[108:111]
	v_mfma_f32_16x16x32_bf16 v[100:103], v[172:175], v[206:209], v[100:103]
	v_mfma_f32_16x16x32_bf16 v[92:95], v[164:167], v[214:217], v[92:95]
	v_mfma_f32_16x16x32_bf16 v[84:87], v[172:175], v[214:217], v[84:87]
	v_mfma_f32_16x16x32_bf16 v[76:79], v[164:167], v[222:225], v[76:79]
	v_mfma_f32_16x16x32_bf16 v[68:71], v[172:175], v[222:225], v[68:71]
	s_setprio 0
	s_setprio 1
	v_mfma_f32_16x16x32_bf16 v[120:123], v[176:179], v[194:197], 0
	v_mfma_f32_16x16x32_bf16 v[112:115], v[186:189], v[194:197], 0
	v_mfma_f32_16x16x32_bf16 v[104:107], v[176:179], v[202:205], 0
	v_mfma_f32_16x16x32_bf16 v[96:99], v[186:189], v[202:205], 0
	v_mfma_f32_16x16x32_bf16 v[88:91], v[176:179], v[210:213], 0
	v_mfma_f32_16x16x32_bf16 v[80:83], v[186:189], v[210:213], 0
	v_mfma_f32_16x16x32_bf16 v[72:75], v[176:179], v[218:221], 0
	v_mfma_f32_16x16x32_bf16 v[64:67], v[186:189], v[218:221], 0
	v_mfma_f32_16x16x32_bf16 v[120:123], v[180:183], v[198:201], v[120:123]
	v_mfma_f32_16x16x32_bf16 v[112:115], v[190:193], v[198:201], v[112:115]
	v_mfma_f32_16x16x32_bf16 v[104:107], v[180:183], v[206:209], v[104:107]
	v_mfma_f32_16x16x32_bf16 v[96:99], v[190:193], v[206:209], v[96:99]
	v_mfma_f32_16x16x32_bf16 v[88:91], v[180:183], v[214:217], v[88:91]
	v_mfma_f32_16x16x32_bf16 v[80:83], v[190:193], v[214:217], v[80:83]
	v_mfma_f32_16x16x32_bf16 v[72:75], v[180:183], v[222:225], v[72:75]
	v_mfma_f32_16x16x32_bf16 v[64:67], v[190:193], v[222:225], v[64:67]
	s_setprio 0
	s_barrier
	s_add_i32 s76, s66, s54
	v_lshl_add_u64 v[154:155], s[48:49], 0, v[132:133]
	s_mov_b32 m0, s76
	ds_read_b128 v[194:197], v150 offset:16384
	v_xor_b32_e32 v253, 64, v150
	ds_read_b128 v[198:201], v253 offset:16384
	ds_read_b128 v[202:205], v150 offset:18432
	ds_read_b128 v[206:209], v253 offset:18432
	ds_read_b128 v[210:213], v150 offset:20480
	ds_read_b128 v[214:217], v253 offset:20480
	ds_read_b128 v[218:221], v150 offset:22528
	ds_read_b128 v[222:225], v253 offset:22528
	global_load_lds_dwordx4 v[154:155], off
	s_add_i32 m0, s76, 0x2000
	s_add_u32 s76, s48, 0x40000
	v_lshl_add_u64 v[226:227], s[48:49], 0, v[128:129]
	s_addc_u32 s77, s49, 0
	s_add_i32 s78, s67, s54
	global_load_lds_dwordx4 v[226:227], off
	v_lshl_add_u64 v[228:229], s[76:77], 0, v[132:133]
	s_mov_b32 m0, s78
	v_lshl_add_u64 v[230:231], s[50:51], 0, v[130:131]
	global_load_lds_dwordx4 v[228:229], off
	v_lshl_add_u64 v[228:229], s[76:77], 0, v[128:129]
	s_add_i32 m0, s78, 0x2000
	s_nop 0
	global_load_lds_dwordx4 v[228:229], off
	v_lshl_add_u64 v[228:229], s[50:51], 0, v[134:135]
	s_mov_b32 m0, s57
	s_nop 0
	global_load_lds_dwordx4 v[228:229], off
	s_mov_b32 m0, s58
	s_nop 0
	global_load_lds_dwordx4 v[230:231], off
	s_waitcnt vmcnt(8)
	s_waitcnt lgkmcnt(0)
	s_barrier
	s_setprio 1
	s_waitcnt lgkmcnt(0)
	v_mfma_f32_16x16x32_bf16 v[60:63], v[160:163], v[194:197], 0
	v_mfma_f32_16x16x32_bf16 v[52:55], v[168:171], v[194:197], 0
	v_mfma_f32_16x16x32_bf16 v[44:47], v[160:163], v[202:205], 0
	v_mfma_f32_16x16x32_bf16 v[36:39], v[168:171], v[202:205], 0
	v_mfma_f32_16x16x32_bf16 v[28:31], v[160:163], v[210:213], 0
	v_mfma_f32_16x16x32_bf16 v[20:23], v[168:171], v[210:213], 0
	v_mfma_f32_16x16x32_bf16 v[12:15], v[160:163], v[218:221], 0
	v_mfma_f32_16x16x32_bf16 v[4:7], v[168:171], v[218:221], 0
	v_mfma_f32_16x16x32_bf16 v[60:63], v[164:167], v[198:201], v[60:63]
	v_mfma_f32_16x16x32_bf16 v[52:55], v[172:175], v[198:201], v[52:55]
	v_mfma_f32_16x16x32_bf16 v[44:47], v[164:167], v[206:209], v[44:47]
	v_mfma_f32_16x16x32_bf16 v[36:39], v[172:175], v[206:209], v[36:39]
	v_mfma_f32_16x16x32_bf16 v[28:31], v[164:167], v[214:217], v[28:31]
	v_mfma_f32_16x16x32_bf16 v[20:23], v[172:175], v[214:217], v[20:23]
	v_mfma_f32_16x16x32_bf16 v[12:15], v[164:167], v[222:225], v[12:15]
	v_mfma_f32_16x16x32_bf16 v[4:7], v[172:175], v[222:225], v[4:7]
	s_setprio 0
	s_setprio 1
	v_mfma_f32_16x16x32_bf16 v[56:59], v[176:179], v[194:197], 0
	v_mfma_f32_16x16x32_bf16 v[48:51], v[186:189], v[194:197], 0
	v_mfma_f32_16x16x32_bf16 v[40:43], v[176:179], v[202:205], 0
	v_mfma_f32_16x16x32_bf16 v[32:35], v[186:189], v[202:205], 0
	v_mfma_f32_16x16x32_bf16 v[24:27], v[176:179], v[210:213], 0
	v_mfma_f32_16x16x32_bf16 v[16:19], v[186:189], v[210:213], 0
	v_mfma_f32_16x16x32_bf16 v[8:11], v[176:179], v[218:221], 0
	v_mfma_f32_16x16x32_bf16 v[0:3], v[186:189], v[218:221], 0
	v_mfma_f32_16x16x32_bf16 v[56:59], v[180:183], v[198:201], v[56:59]
	v_mfma_f32_16x16x32_bf16 v[48:51], v[190:193], v[198:201], v[48:51]
	v_mfma_f32_16x16x32_bf16 v[40:43], v[180:183], v[206:209], v[40:43]
	v_mfma_f32_16x16x32_bf16 v[32:35], v[190:193], v[206:209], v[32:35]
	v_mfma_f32_16x16x32_bf16 v[24:27], v[180:183], v[214:217], v[24:27]
	v_mfma_f32_16x16x32_bf16 v[16:19], v[190:193], v[214:217], v[16:19]
	v_mfma_f32_16x16x32_bf16 v[8:11], v[180:183], v[222:225], v[8:11]
	v_mfma_f32_16x16x32_bf16 v[0:3], v[190:193], v[222:225], v[0:3]
	s_setprio 0
	s_barrier
	s_add_i32 s76, 0, 0x18000
	v_add_u32_e32 v153, s76, v147
	s_add_i32 s77, 0, 0x1c000
	ds_read_b128 v[160:163], v153
	v_xor_b32_e32 v253, 64, v153
	ds_read_b128 v[164:167], v253
	ds_read_b128 v[168:171], v153 offset:2048
	ds_read_b128 v[172:175], v253 offset:2048
	v_add_u32_e32 v153, s77, v147
	ds_read_b128 v[176:179], v153
	v_xor_b32_e32 v253, 64, v153
	ds_read_b128 v[180:183], v253
	ds_read_b128 v[186:189], v153 offset:2048
	ds_read_b128 v[190:193], v253 offset:2048
	s_add_u32 s50, s50, 0x40000
	s_addc_u32 s51, s51, 0
	s_mov_b32 m0, s59
	v_lshl_add_u64 v[232:233], s[50:51], 0, v[134:135]
	ds_read_b128 v[194:197], v150 offset:32768
	v_xor_b32_e32 v253, 64, v150
	ds_read_b128 v[198:201], v253 offset:32768
	ds_read_b128 v[202:205], v150 offset:34816
	ds_read_b128 v[206:209], v253 offset:34816
	ds_read_b128 v[210:213], v150 offset:36864
	ds_read_b128 v[214:217], v253 offset:36864
	ds_read_b128 v[218:221], v150 offset:38912
	ds_read_b128 v[222:225], v253 offset:38912
	global_load_lds_dwordx4 v[232:233], off
	v_lshl_add_u64 v[232:233], s[50:51], 0, v[130:131]
	s_mov_b32 m0, s60
	s_nop 0
	global_load_lds_dwordx4 v[232:233], off
	s_waitcnt vmcnt(8)
	s_waitcnt lgkmcnt(0)
	s_barrier
	s_setprio 1
	s_waitcnt lgkmcnt(0)
	v_mfma_f32_16x16x32_bf16 v[124:127], v[160:163], v[194:197], v[124:127]
	v_mfma_f32_16x16x32_bf16 v[116:119], v[168:171], v[194:197], v[116:119]
	v_mfma_f32_16x16x32_bf16 v[108:111], v[160:163], v[202:205], v[108:111]
	v_mfma_f32_16x16x32_bf16 v[100:103], v[168:171], v[202:205], v[100:103]
	v_mfma_f32_16x16x32_bf16 v[92:95], v[160:163], v[210:213], v[92:95]
	v_mfma_f32_16x16x32_bf16 v[84:87], v[168:171], v[210:213], v[84:87]
	v_mfma_f32_16x16x32_bf16 v[76:79], v[160:163], v[218:221], v[76:79]
	v_mfma_f32_16x16x32_bf16 v[68:71], v[168:171], v[218:221], v[68:71]
	v_mfma_f32_16x16x32_bf16 v[124:127], v[164:167], v[198:201], v[124:127]
	v_mfma_f32_16x16x32_bf16 v[116:119], v[172:175], v[198:201], v[116:119]
	v_mfma_f32_16x16x32_bf16 v[108:111], v[164:167], v[206:209], v[108:111]
	v_mfma_f32_16x16x32_bf16 v[100:103], v[172:175], v[206:209], v[100:103]
	v_mfma_f32_16x16x32_bf16 v[92:95], v[164:167], v[214:217], v[92:95]
	v_mfma_f32_16x16x32_bf16 v[84:87], v[172:175], v[214:217], v[84:87]
	v_mfma_f32_16x16x32_bf16 v[76:79], v[164:167], v[222:225], v[76:79]
	v_mfma_f32_16x16x32_bf16 v[68:71], v[172:175], v[222:225], v[68:71]
	s_setprio 0
	s_setprio 1
	v_mfma_f32_16x16x32_bf16 v[120:123], v[176:179], v[194:197], v[120:123]
	v_mfma_f32_16x16x32_bf16 v[112:115], v[186:189], v[194:197], v[112:115]
	v_mfma_f32_16x16x32_bf16 v[104:107], v[176:179], v[202:205], v[104:107]
	v_mfma_f32_16x16x32_bf16 v[96:99], v[186:189], v[202:205], v[96:99]
	v_mfma_f32_16x16x32_bf16 v[88:91], v[176:179], v[210:213], v[88:91]
	v_mfma_f32_16x16x32_bf16 v[80:83], v[186:189], v[210:213], v[80:83]
	v_mfma_f32_16x16x32_bf16 v[72:75], v[176:179], v[218:221], v[72:75]
	v_mfma_f32_16x16x32_bf16 v[64:67], v[186:189], v[218:221], v[64:67]
	v_mfma_f32_16x16x32_bf16 v[120:123], v[180:183], v[198:201], v[120:123]
	v_mfma_f32_16x16x32_bf16 v[112:115], v[190:193], v[198:201], v[112:115]
	v_mfma_f32_16x16x32_bf16 v[104:107], v[180:183], v[206:209], v[104:107]
	v_mfma_f32_16x16x32_bf16 v[96:99], v[190:193], v[206:209], v[96:99]
	v_mfma_f32_16x16x32_bf16 v[88:91], v[180:183], v[214:217], v[88:91]
	v_mfma_f32_16x16x32_bf16 v[80:83], v[190:193], v[214:217], v[80:83]
	v_mfma_f32_16x16x32_bf16 v[72:75], v[180:183], v[222:225], v[72:75]
	v_mfma_f32_16x16x32_bf16 v[64:67], v[190:193], v[222:225], v[64:67]
	s_setprio 0
	s_barrier
	s_add_i32 s50, s76, s54
	v_lshl_add_u64 v[154:155], v[154:155], 0, s[20:21]
	s_mov_b32 m0, s50
	ds_read_b128 v[194:197], v150 offset:49152
	v_xor_b32_e32 v253, 64, v150
	ds_read_b128 v[198:201], v253 offset:49152
	ds_read_b128 v[202:205], v150 offset:51200
	ds_read_b128 v[206:209], v253 offset:51200
	ds_read_b128 v[210:213], v150 offset:53248
	ds_read_b128 v[214:217], v253 offset:53248
	ds_read_b128 v[218:221], v150 offset:55296
	ds_read_b128 v[222:225], v253 offset:55296
	global_load_lds_dwordx4 v[154:155], off
	s_add_i32 m0, s50, 0x2000
	s_add_u32 s48, s48, 0x40080
	v_lshl_add_u64 v[154:155], v[226:227], 0, s[20:21]
	s_addc_u32 s49, s49, 0
	s_add_i32 s50, s77, s54
	global_load_lds_dwordx4 v[154:155], off
	v_lshl_add_u64 v[154:155], s[48:49], 0, v[132:133]
	s_mov_b32 m0, s50
	s_nop 0
	global_load_lds_dwordx4 v[154:155], off
	v_lshl_add_u64 v[154:155], s[48:49], 0, v[128:129]
	s_add_i32 m0, s50, 0x2000
	s_nop 0
	global_load_lds_dwordx4 v[154:155], off
	v_lshl_add_u64 v[154:155], v[228:229], 0, s[20:21]
	s_mov_b32 m0, s62
	s_nop 0
	global_load_lds_dwordx4 v[154:155], off
	v_lshl_add_u64 v[154:155], v[230:231], 0, s[20:21]
	s_mov_b32 m0, s63
	s_nop 0
	global_load_lds_dwordx4 v[154:155], off
	s_waitcnt vmcnt(8)
	s_waitcnt lgkmcnt(0)
	s_barrier
	s_setprio 1
	s_waitcnt lgkmcnt(0)
	v_mfma_f32_16x16x32_bf16 v[60:63], v[160:163], v[194:197], v[60:63]
	v_mfma_f32_16x16x32_bf16 v[52:55], v[168:171], v[194:197], v[52:55]
	v_mfma_f32_16x16x32_bf16 v[44:47], v[160:163], v[202:205], v[44:47]
	v_mfma_f32_16x16x32_bf16 v[36:39], v[168:171], v[202:205], v[36:39]
	v_mfma_f32_16x16x32_bf16 v[28:31], v[160:163], v[210:213], v[28:31]
	v_mfma_f32_16x16x32_bf16 v[20:23], v[168:171], v[210:213], v[20:23]
	v_mfma_f32_16x16x32_bf16 v[12:15], v[160:163], v[218:221], v[12:15]
	v_mfma_f32_16x16x32_bf16 v[4:7], v[168:171], v[218:221], v[4:7]
	v_mfma_f32_16x16x32_bf16 v[60:63], v[164:167], v[198:201], v[60:63]
	v_mfma_f32_16x16x32_bf16 v[52:55], v[172:175], v[198:201], v[52:55]
	v_mfma_f32_16x16x32_bf16 v[44:47], v[164:167], v[206:209], v[44:47]
	v_mfma_f32_16x16x32_bf16 v[36:39], v[172:175], v[206:209], v[36:39]
	v_mfma_f32_16x16x32_bf16 v[28:31], v[164:167], v[214:217], v[28:31]
	v_mfma_f32_16x16x32_bf16 v[20:23], v[172:175], v[214:217], v[20:23]
	v_mfma_f32_16x16x32_bf16 v[12:15], v[164:167], v[222:225], v[12:15]
	v_mfma_f32_16x16x32_bf16 v[4:7], v[172:175], v[222:225], v[4:7]
	s_setprio 0
	s_setprio 1
	v_mfma_f32_16x16x32_bf16 v[56:59], v[176:179], v[194:197], v[56:59]
	v_mfma_f32_16x16x32_bf16 v[48:51], v[186:189], v[194:197], v[48:51]
	v_mfma_f32_16x16x32_bf16 v[40:43], v[176:179], v[202:205], v[40:43]
	v_mfma_f32_16x16x32_bf16 v[32:35], v[186:189], v[202:205], v[32:35]
	v_mfma_f32_16x16x32_bf16 v[24:27], v[176:179], v[210:213], v[24:27]
	v_mfma_f32_16x16x32_bf16 v[16:19], v[186:189], v[210:213], v[16:19]
	v_mfma_f32_16x16x32_bf16 v[8:11], v[176:179], v[218:221], v[8:11]
	v_mfma_f32_16x16x32_bf16 v[0:3], v[186:189], v[218:221], v[0:3]
	v_mfma_f32_16x16x32_bf16 v[56:59], v[180:183], v[198:201], v[56:59]
	v_mfma_f32_16x16x32_bf16 v[48:51], v[190:193], v[198:201], v[48:51]
	v_mfma_f32_16x16x32_bf16 v[40:43], v[180:183], v[206:209], v[40:43]
	v_mfma_f32_16x16x32_bf16 v[32:35], v[190:193], v[206:209], v[32:35]
	v_mfma_f32_16x16x32_bf16 v[24:27], v[180:183], v[214:217], v[24:27]
	v_mfma_f32_16x16x32_bf16 v[16:19], v[190:193], v[214:217], v[16:19]
	v_mfma_f32_16x16x32_bf16 v[8:11], v[180:183], v[222:225], v[8:11]
	v_mfma_f32_16x16x32_bf16 v[0:3], v[190:193], v[222:225], v[0:3]
	s_setprio 0
	s_barrier
	s_add_i32 s75, s75, 2
	s_add_u32 s73, s73, 0x100
	s_addc_u32 s74, s74, 0
	s_add_u32 s46, s46, 0x100
	s_addc_u32 s47, s47, 0
	s_branch .LBB0_527
.LBB0_526:
	v_add_u32_e32 v153, s66, v147
	ds_read_b128 v[160:163], v153
	v_xor_b32_e32 v253, 64, v153
	ds_read_b128 v[164:167], v253
	ds_read_b128 v[168:171], v153 offset:2048
	ds_read_b128 v[172:175], v253 offset:2048
	v_add_u32_e32 v153, s67, v147
	ds_read_b128 v[176:179], v153
	v_xor_b32_e32 v253, 64, v153
	ds_read_b128 v[180:183], v253
	ds_read_b128 v[186:189], v153 offset:2048
	ds_read_b128 v[190:193], v253 offset:2048
	s_add_u32 s50, s46, 0xfffc0080
	s_addc_u32 s51, s47, -1
	s_and_b64 s[48:49], s[48:49], exec
	s_cselect_b32 s51, s29, s51
	s_cselect_b32 s50, s70, s50
	s_cselect_b32 s49, s71, s74
	s_cselect_b32 s48, s72, s73
	v_lshl_add_u64 v[154:155], s[46:47], 0, v[138:139]
	s_add_i32 m0, s57, 0xc000
	ds_read_b128 v[194:197], v150
	v_xor_b32_e32 v253, 64, v150
	ds_read_b128 v[198:201], v253
	ds_read_b128 v[202:205], v150 offset:2048
	ds_read_b128 v[206:209], v253 offset:2048
	ds_read_b128 v[210:213], v150 offset:4096
	ds_read_b128 v[214:217], v253 offset:4096
	ds_read_b128 v[218:221], v150 offset:6144
	ds_read_b128 v[222:225], v253 offset:6144
	global_load_lds_dwordx4 v[154:155], off
	v_lshl_add_u64 v[154:155], s[46:47], 0, v[136:137]
	s_add_i32 m0, s57, 0xe000
	s_nop 0
	global_load_lds_dwordx4 v[154:155], off
	s_waitcnt vmcnt(8)
	s_waitcnt lgkmcnt(0)
	s_barrier
	s_setprio 1
	s_waitcnt lgkmcnt(0)
	v_mfma_f32_16x16x32_bf16 v[124:127], v[160:163], v[194:197], v[124:127]
	v_mfma_f32_16x16x32_bf16 v[116:119], v[168:171], v[194:197], v[116:119]
	v_mfma_f32_16x16x32_bf16 v[108:111], v[160:163], v[202:205], v[108:111]
	v_mfma_f32_16x16x32_bf16 v[100:103], v[168:171], v[202:205], v[100:103]
	v_mfma_f32_16x16x32_bf16 v[92:95], v[160:163], v[210:213], v[92:95]
	v_mfma_f32_16x16x32_bf16 v[84:87], v[168:171], v[210:213], v[84:87]
	v_mfma_f32_16x16x32_bf16 v[76:79], v[160:163], v[218:221], v[76:79]
	v_mfma_f32_16x16x32_bf16 v[68:71], v[168:171], v[218:221], v[68:71]
	v_mfma_f32_16x16x32_bf16 v[124:127], v[164:167], v[198:201], v[124:127]
	v_mfma_f32_16x16x32_bf16 v[116:119], v[172:175], v[198:201], v[116:119]
	v_mfma_f32_16x16x32_bf16 v[108:111], v[164:167], v[206:209], v[108:111]
	v_mfma_f32_16x16x32_bf16 v[100:103], v[172:175], v[206:209], v[100:103]
	v_mfma_f32_16x16x32_bf16 v[92:95], v[164:167], v[214:217], v[92:95]
	v_mfma_f32_16x16x32_bf16 v[84:87], v[172:175], v[214:217], v[84:87]
	v_mfma_f32_16x16x32_bf16 v[76:79], v[164:167], v[222:225], v[76:79]
	v_mfma_f32_16x16x32_bf16 v[68:71], v[172:175], v[222:225], v[68:71]
	s_setprio 0
	s_setprio 1
	v_mfma_f32_16x16x32_bf16 v[120:123], v[176:179], v[194:197], v[120:123]
	v_mfma_f32_16x16x32_bf16 v[112:115], v[186:189], v[194:197], v[112:115]
	v_mfma_f32_16x16x32_bf16 v[104:107], v[176:179], v[202:205], v[104:107]
	v_mfma_f32_16x16x32_bf16 v[96:99], v[186:189], v[202:205], v[96:99]
	v_mfma_f32_16x16x32_bf16 v[88:91], v[176:179], v[210:213], v[88:91]
	v_mfma_f32_16x16x32_bf16 v[80:83], v[186:189], v[210:213], v[80:83]
	v_mfma_f32_16x16x32_bf16 v[72:75], v[176:179], v[218:221], v[72:75]
	v_mfma_f32_16x16x32_bf16 v[64:67], v[186:189], v[218:221], v[64:67]
	v_mfma_f32_16x16x32_bf16 v[120:123], v[180:183], v[198:201], v[120:123]
	v_mfma_f32_16x16x32_bf16 v[112:115], v[190:193], v[198:201], v[112:115]
	v_mfma_f32_16x16x32_bf16 v[104:107], v[180:183], v[206:209], v[104:107]
	v_mfma_f32_16x16x32_bf16 v[96:99], v[190:193], v[206:209], v[96:99]
	v_mfma_f32_16x16x32_bf16 v[88:91], v[180:183], v[214:217], v[88:91]
	v_mfma_f32_16x16x32_bf16 v[80:83], v[190:193], v[214:217], v[80:83]
	v_mfma_f32_16x16x32_bf16 v[72:75], v[180:183], v[222:225], v[72:75]
	v_mfma_f32_16x16x32_bf16 v[64:67], v[190:193], v[222:225], v[64:67]
	s_setprio 0
	s_barrier
	s_add_i32 s76, s66, s54
	v_lshl_add_u64 v[154:155], s[48:49], 0, v[132:133]
	s_mov_b32 m0, s76
	ds_read_b128 v[194:197], v150 offset:16384
	v_xor_b32_e32 v253, 64, v150
	ds_read_b128 v[198:201], v253 offset:16384
	ds_read_b128 v[202:205], v150 offset:18432
	ds_read_b128 v[206:209], v253 offset:18432
	ds_read_b128 v[210:213], v150 offset:20480
	ds_read_b128 v[214:217], v253 offset:20480
	ds_read_b128 v[218:221], v150 offset:22528
	ds_read_b128 v[222:225], v253 offset:22528
	global_load_lds_dwordx4 v[154:155], off
	s_add_i32 m0, s76, 0x2000
	s_add_u32 s76, s48, 0x40000
	v_lshl_add_u64 v[226:227], s[48:49], 0, v[128:129]
	s_addc_u32 s77, s49, 0
	s_add_i32 s78, s67, s54
	global_load_lds_dwordx4 v[226:227], off
	v_lshl_add_u64 v[228:229], s[76:77], 0, v[132:133]
	s_mov_b32 m0, s78
	v_lshl_add_u64 v[230:231], s[50:51], 0, v[130:131]
	global_load_lds_dwordx4 v[228:229], off
	v_lshl_add_u64 v[228:229], s[76:77], 0, v[128:129]
	s_add_i32 m0, s78, 0x2000
	s_nop 0
	global_load_lds_dwordx4 v[228:229], off
	v_lshl_add_u64 v[228:229], s[50:51], 0, v[134:135]
	s_mov_b32 m0, s57
	s_nop 0
	global_load_lds_dwordx4 v[228:229], off
	s_mov_b32 m0, s58
	s_nop 0
	global_load_lds_dwordx4 v[230:231], off
	s_waitcnt vmcnt(8)
	s_waitcnt lgkmcnt(0)
	s_barrier
	s_setprio 1
	s_waitcnt lgkmcnt(0)
	v_mfma_f32_16x16x32_bf16 v[60:63], v[160:163], v[194:197], v[60:63]
	v_mfma_f32_16x16x32_bf16 v[52:55], v[168:171], v[194:197], v[52:55]
	v_mfma_f32_16x16x32_bf16 v[44:47], v[160:163], v[202:205], v[44:47]
	v_mfma_f32_16x16x32_bf16 v[36:39], v[168:171], v[202:205], v[36:39]
	v_mfma_f32_16x16x32_bf16 v[28:31], v[160:163], v[210:213], v[28:31]
	v_mfma_f32_16x16x32_bf16 v[20:23], v[168:171], v[210:213], v[20:23]
	v_mfma_f32_16x16x32_bf16 v[12:15], v[160:163], v[218:221], v[12:15]
	v_mfma_f32_16x16x32_bf16 v[4:7], v[168:171], v[218:221], v[4:7]
	v_mfma_f32_16x16x32_bf16 v[60:63], v[164:167], v[198:201], v[60:63]
	v_mfma_f32_16x16x32_bf16 v[52:55], v[172:175], v[198:201], v[52:55]
	v_mfma_f32_16x16x32_bf16 v[44:47], v[164:167], v[206:209], v[44:47]
	v_mfma_f32_16x16x32_bf16 v[36:39], v[172:175], v[206:209], v[36:39]
	v_mfma_f32_16x16x32_bf16 v[28:31], v[164:167], v[214:217], v[28:31]
	v_mfma_f32_16x16x32_bf16 v[20:23], v[172:175], v[214:217], v[20:23]
	v_mfma_f32_16x16x32_bf16 v[12:15], v[164:167], v[222:225], v[12:15]
	v_mfma_f32_16x16x32_bf16 v[4:7], v[172:175], v[222:225], v[4:7]
	s_setprio 0
	s_setprio 1
	v_mfma_f32_16x16x32_bf16 v[56:59], v[176:179], v[194:197], v[56:59]
	v_mfma_f32_16x16x32_bf16 v[48:51], v[186:189], v[194:197], v[48:51]
	v_mfma_f32_16x16x32_bf16 v[40:43], v[176:179], v[202:205], v[40:43]
	v_mfma_f32_16x16x32_bf16 v[32:35], v[186:189], v[202:205], v[32:35]
	v_mfma_f32_16x16x32_bf16 v[24:27], v[176:179], v[210:213], v[24:27]
	v_mfma_f32_16x16x32_bf16 v[16:19], v[186:189], v[210:213], v[16:19]
	v_mfma_f32_16x16x32_bf16 v[8:11], v[176:179], v[218:221], v[8:11]
	v_mfma_f32_16x16x32_bf16 v[0:3], v[186:189], v[218:221], v[0:3]
	v_mfma_f32_16x16x32_bf16 v[56:59], v[180:183], v[198:201], v[56:59]
	v_mfma_f32_16x16x32_bf16 v[48:51], v[190:193], v[198:201], v[48:51]
	v_mfma_f32_16x16x32_bf16 v[40:43], v[180:183], v[206:209], v[40:43]
	v_mfma_f32_16x16x32_bf16 v[32:35], v[190:193], v[206:209], v[32:35]
	v_mfma_f32_16x16x32_bf16 v[24:27], v[180:183], v[214:217], v[24:27]
	v_mfma_f32_16x16x32_bf16 v[16:19], v[190:193], v[214:217], v[16:19]
	v_mfma_f32_16x16x32_bf16 v[8:11], v[180:183], v[222:225], v[8:11]
	v_mfma_f32_16x16x32_bf16 v[0:3], v[190:193], v[222:225], v[0:3]
	s_setprio 0
	s_barrier
	s_add_i32 s76, 0, 0x18000
	v_add_u32_e32 v153, s76, v147
	s_add_i32 s77, 0, 0x1c000
	ds_read_b128 v[160:163], v153
	v_xor_b32_e32 v253, 64, v153
	ds_read_b128 v[164:167], v253
	ds_read_b128 v[168:171], v153 offset:2048
	ds_read_b128 v[172:175], v253 offset:2048
	v_add_u32_e32 v153, s77, v147
	ds_read_b128 v[176:179], v153
	v_xor_b32_e32 v253, 64, v153
	ds_read_b128 v[180:183], v253
	ds_read_b128 v[186:189], v153 offset:2048
	ds_read_b128 v[190:193], v253 offset:2048
	s_add_u32 s50, s50, 0x40000
	s_addc_u32 s51, s51, 0
	s_mov_b32 m0, s59
	v_lshl_add_u64 v[232:233], s[50:51], 0, v[134:135]
	ds_read_b128 v[194:197], v150 offset:32768
	v_xor_b32_e32 v253, 64, v150
	ds_read_b128 v[198:201], v253 offset:32768
	ds_read_b128 v[202:205], v150 offset:34816
	ds_read_b128 v[206:209], v253 offset:34816
	ds_read_b128 v[210:213], v150 offset:36864
	ds_read_b128 v[214:217], v253 offset:36864
	ds_read_b128 v[218:221], v150 offset:38912
	ds_read_b128 v[222:225], v253 offset:38912
	global_load_lds_dwordx4 v[232:233], off
	v_lshl_add_u64 v[232:233], s[50:51], 0, v[130:131]
	s_mov_b32 m0, s60
	s_nop 0
	global_load_lds_dwordx4 v[232:233], off
	s_waitcnt vmcnt(8)
	s_waitcnt lgkmcnt(0)
	s_barrier
	s_setprio 1
	s_waitcnt lgkmcnt(0)
	v_mfma_f32_16x16x32_bf16 v[124:127], v[160:163], v[194:197], v[124:127]
	v_mfma_f32_16x16x32_bf16 v[116:119], v[168:171], v[194:197], v[116:119]
	v_mfma_f32_16x16x32_bf16 v[108:111], v[160:163], v[202:205], v[108:111]
	v_mfma_f32_16x16x32_bf16 v[100:103], v[168:171], v[202:205], v[100:103]
	v_mfma_f32_16x16x32_bf16 v[92:95], v[160:163], v[210:213], v[92:95]
	v_mfma_f32_16x16x32_bf16 v[84:87], v[168:171], v[210:213], v[84:87]
	v_mfma_f32_16x16x32_bf16 v[76:79], v[160:163], v[218:221], v[76:79]
	v_mfma_f32_16x16x32_bf16 v[68:71], v[168:171], v[218:221], v[68:71]
	v_mfma_f32_16x16x32_bf16 v[124:127], v[164:167], v[198:201], v[124:127]
	v_mfma_f32_16x16x32_bf16 v[116:119], v[172:175], v[198:201], v[116:119]
	v_mfma_f32_16x16x32_bf16 v[108:111], v[164:167], v[206:209], v[108:111]
	v_mfma_f32_16x16x32_bf16 v[100:103], v[172:175], v[206:209], v[100:103]
	v_mfma_f32_16x16x32_bf16 v[92:95], v[164:167], v[214:217], v[92:95]
	v_mfma_f32_16x16x32_bf16 v[84:87], v[172:175], v[214:217], v[84:87]
	v_mfma_f32_16x16x32_bf16 v[76:79], v[164:167], v[222:225], v[76:79]
	v_mfma_f32_16x16x32_bf16 v[68:71], v[172:175], v[222:225], v[68:71]
	s_setprio 0
	s_setprio 1
	v_mfma_f32_16x16x32_bf16 v[120:123], v[176:179], v[194:197], v[120:123]
	v_mfma_f32_16x16x32_bf16 v[112:115], v[186:189], v[194:197], v[112:115]
	v_mfma_f32_16x16x32_bf16 v[104:107], v[176:179], v[202:205], v[104:107]
	v_mfma_f32_16x16x32_bf16 v[96:99], v[186:189], v[202:205], v[96:99]
	v_mfma_f32_16x16x32_bf16 v[88:91], v[176:179], v[210:213], v[88:91]
	v_mfma_f32_16x16x32_bf16 v[80:83], v[186:189], v[210:213], v[80:83]
	v_mfma_f32_16x16x32_bf16 v[72:75], v[176:179], v[218:221], v[72:75]
	v_mfma_f32_16x16x32_bf16 v[64:67], v[186:189], v[218:221], v[64:67]
	v_mfma_f32_16x16x32_bf16 v[120:123], v[180:183], v[198:201], v[120:123]
	v_mfma_f32_16x16x32_bf16 v[112:115], v[190:193], v[198:201], v[112:115]
	v_mfma_f32_16x16x32_bf16 v[104:107], v[180:183], v[206:209], v[104:107]
	v_mfma_f32_16x16x32_bf16 v[96:99], v[190:193], v[206:209], v[96:99]
	v_mfma_f32_16x16x32_bf16 v[88:91], v[180:183], v[214:217], v[88:91]
	v_mfma_f32_16x16x32_bf16 v[80:83], v[190:193], v[214:217], v[80:83]
	v_mfma_f32_16x16x32_bf16 v[72:75], v[180:183], v[222:225], v[72:75]
	v_mfma_f32_16x16x32_bf16 v[64:67], v[190:193], v[222:225], v[64:67]
	s_setprio 0
	s_barrier
	s_add_i32 s50, s76, s54
	v_lshl_add_u64 v[154:155], v[154:155], 0, s[20:21]
	s_mov_b32 m0, s50
	ds_read_b128 v[194:197], v150 offset:49152
	v_xor_b32_e32 v253, 64, v150
	ds_read_b128 v[198:201], v253 offset:49152
	ds_read_b128 v[202:205], v150 offset:51200
	ds_read_b128 v[206:209], v253 offset:51200
	ds_read_b128 v[210:213], v150 offset:53248
	ds_read_b128 v[214:217], v253 offset:53248
	ds_read_b128 v[218:221], v150 offset:55296
	ds_read_b128 v[222:225], v253 offset:55296
	global_load_lds_dwordx4 v[154:155], off
	s_add_i32 m0, s50, 0x2000
	s_add_u32 s48, s48, 0x40080
	v_lshl_add_u64 v[154:155], v[226:227], 0, s[20:21]
	s_addc_u32 s49, s49, 0
	s_add_i32 s50, s77, s54
	global_load_lds_dwordx4 v[154:155], off
	v_lshl_add_u64 v[154:155], s[48:49], 0, v[132:133]
	s_mov_b32 m0, s50
	s_nop 0
	global_load_lds_dwordx4 v[154:155], off
	v_lshl_add_u64 v[154:155], s[48:49], 0, v[128:129]
	s_add_i32 m0, s50, 0x2000
	s_nop 0
	global_load_lds_dwordx4 v[154:155], off
	v_lshl_add_u64 v[154:155], v[228:229], 0, s[20:21]
	s_mov_b32 m0, s62
	s_nop 0
	global_load_lds_dwordx4 v[154:155], off
	v_lshl_add_u64 v[154:155], v[230:231], 0, s[20:21]
	s_mov_b32 m0, s63
	s_nop 0
	global_load_lds_dwordx4 v[154:155], off
	s_waitcnt vmcnt(8)
	s_waitcnt lgkmcnt(0)
	s_barrier
	s_setprio 1
	s_waitcnt lgkmcnt(0)
	v_mfma_f32_16x16x32_bf16 v[60:63], v[160:163], v[194:197], v[60:63]
	v_mfma_f32_16x16x32_bf16 v[52:55], v[168:171], v[194:197], v[52:55]
	v_mfma_f32_16x16x32_bf16 v[44:47], v[160:163], v[202:205], v[44:47]
	v_mfma_f32_16x16x32_bf16 v[36:39], v[168:171], v[202:205], v[36:39]
	v_mfma_f32_16x16x32_bf16 v[28:31], v[160:163], v[210:213], v[28:31]
	v_mfma_f32_16x16x32_bf16 v[20:23], v[168:171], v[210:213], v[20:23]
	v_mfma_f32_16x16x32_bf16 v[12:15], v[160:163], v[218:221], v[12:15]
	v_mfma_f32_16x16x32_bf16 v[4:7], v[168:171], v[218:221], v[4:7]
	v_mfma_f32_16x16x32_bf16 v[60:63], v[164:167], v[198:201], v[60:63]
	v_mfma_f32_16x16x32_bf16 v[52:55], v[172:175], v[198:201], v[52:55]
	v_mfma_f32_16x16x32_bf16 v[44:47], v[164:167], v[206:209], v[44:47]
	v_mfma_f32_16x16x32_bf16 v[36:39], v[172:175], v[206:209], v[36:39]
	v_mfma_f32_16x16x32_bf16 v[28:31], v[164:167], v[214:217], v[28:31]
	v_mfma_f32_16x16x32_bf16 v[20:23], v[172:175], v[214:217], v[20:23]
	v_mfma_f32_16x16x32_bf16 v[12:15], v[164:167], v[222:225], v[12:15]
	v_mfma_f32_16x16x32_bf16 v[4:7], v[172:175], v[222:225], v[4:7]
	s_setprio 0
	s_setprio 1
	v_mfma_f32_16x16x32_bf16 v[56:59], v[176:179], v[194:197], v[56:59]
	v_mfma_f32_16x16x32_bf16 v[48:51], v[186:189], v[194:197], v[48:51]
	v_mfma_f32_16x16x32_bf16 v[40:43], v[176:179], v[202:205], v[40:43]
	v_mfma_f32_16x16x32_bf16 v[32:35], v[186:189], v[202:205], v[32:35]
	v_mfma_f32_16x16x32_bf16 v[24:27], v[176:179], v[210:213], v[24:27]
	v_mfma_f32_16x16x32_bf16 v[16:19], v[186:189], v[210:213], v[16:19]
	v_mfma_f32_16x16x32_bf16 v[8:11], v[176:179], v[218:221], v[8:11]
	v_mfma_f32_16x16x32_bf16 v[0:3], v[186:189], v[218:221], v[0:3]
	v_mfma_f32_16x16x32_bf16 v[56:59], v[180:183], v[198:201], v[56:59]
	v_mfma_f32_16x16x32_bf16 v[48:51], v[190:193], v[198:201], v[48:51]
	v_mfma_f32_16x16x32_bf16 v[40:43], v[180:183], v[206:209], v[40:43]
	v_mfma_f32_16x16x32_bf16 v[32:35], v[190:193], v[206:209], v[32:35]
	v_mfma_f32_16x16x32_bf16 v[24:27], v[180:183], v[214:217], v[24:27]
	v_mfma_f32_16x16x32_bf16 v[16:19], v[190:193], v[214:217], v[16:19]
	v_mfma_f32_16x16x32_bf16 v[8:11], v[180:183], v[222:225], v[8:11]
	v_mfma_f32_16x16x32_bf16 v[0:3], v[190:193], v[222:225], v[0:3]
	s_setprio 0
	s_barrier
	s_add_i32 s75, s75, 2
	s_add_u32 s73, s73, 0x100
	s_addc_u32 s74, s74, 0
	s_add_u32 s46, s46, 0x100
	s_addc_u32 s47, s47, 0
	s_cmp_gt_u32 s75, 13
	s_cbranch_scc1 .LBB0_529

.Llast_4:
	v_add_u32_e32 v153, s66, v147
	ds_read_b128 v[160:163], v153
	v_xor_b32_e32 v253, 64, v153
	ds_read_b128 v[164:167], v253
	ds_read_b128 v[168:171], v153 offset:2048
	ds_read_b128 v[172:175], v253 offset:2048
	v_add_u32_e32 v153, s67, v147
	ds_read_b128 v[176:179], v153
	v_xor_b32_e32 v253, 64, v153
	ds_read_b128 v[180:183], v253
	ds_read_b128 v[186:189], v153 offset:2048
	ds_read_b128 v[190:193], v253 offset:2048
	s_add_u32 s50, s46, 0xfffc0080
	s_addc_u32 s51, s47, -1
	s_and_b64 s[48:49], s[48:49], exec
	s_cselect_b32 s51, s29, s51
	s_cselect_b32 s50, s70, s50
	s_cselect_b32 s49, s71, s74
	s_cselect_b32 s48, s72, s73
	v_lshl_add_u64 v[154:155], s[46:47], 0, v[138:139]
	s_add_i32 m0, s57, 0xc000
	ds_read_b128 v[194:197], v150
	v_xor_b32_e32 v253, 64, v150
	ds_read_b128 v[198:201], v253
	ds_read_b128 v[202:205], v150 offset:2048
	ds_read_b128 v[206:209], v253 offset:2048
	ds_read_b128 v[210:213], v150 offset:4096
	ds_read_b128 v[214:217], v253 offset:4096
	ds_read_b128 v[218:221], v150 offset:6144
	ds_read_b128 v[222:225], v253 offset:6144
	global_load_lds_dwordx4 v[154:155], off
	v_lshl_add_u64 v[154:155], s[46:47], 0, v[136:137]
	s_add_i32 m0, s57, 0xe000
	s_nop 0
	global_load_lds_dwordx4 v[154:155], off
	s_waitcnt vmcnt(8)
	s_waitcnt lgkmcnt(0)
	s_barrier
	s_setprio 1
	s_waitcnt lgkmcnt(0)
	v_mfma_f32_16x16x32_bf16 v[124:127], v[160:163], v[194:197], v[124:127]
	v_mfma_f32_16x16x32_bf16 v[116:119], v[168:171], v[194:197], v[116:119]
	v_mfma_f32_16x16x32_bf16 v[108:111], v[160:163], v[202:205], v[108:111]
	v_mfma_f32_16x16x32_bf16 v[100:103], v[168:171], v[202:205], v[100:103]
	v_mfma_f32_16x16x32_bf16 v[92:95], v[160:163], v[210:213], v[92:95]
	v_mfma_f32_16x16x32_bf16 v[84:87], v[168:171], v[210:213], v[84:87]
	v_mfma_f32_16x16x32_bf16 v[76:79], v[160:163], v[218:221], v[76:79]
	v_mfma_f32_16x16x32_bf16 v[68:71], v[168:171], v[218:221], v[68:71]
	v_mfma_f32_16x16x32_bf16 v[124:127], v[164:167], v[198:201], v[124:127]
	v_mfma_f32_16x16x32_bf16 v[116:119], v[172:175], v[198:201], v[116:119]
	v_mfma_f32_16x16x32_bf16 v[108:111], v[164:167], v[206:209], v[108:111]
	v_mfma_f32_16x16x32_bf16 v[100:103], v[172:175], v[206:209], v[100:103]
	v_mfma_f32_16x16x32_bf16 v[92:95], v[164:167], v[214:217], v[92:95]
	v_mfma_f32_16x16x32_bf16 v[84:87], v[172:175], v[214:217], v[84:87]
	v_mfma_f32_16x16x32_bf16 v[76:79], v[164:167], v[222:225], v[76:79]
	v_mfma_f32_16x16x32_bf16 v[68:71], v[172:175], v[222:225], v[68:71]
	s_setprio 0
	s_setprio 1
	v_mfma_f32_16x16x32_bf16 v[120:123], v[176:179], v[194:197], v[120:123]
	v_mfma_f32_16x16x32_bf16 v[112:115], v[186:189], v[194:197], v[112:115]
	v_mfma_f32_16x16x32_bf16 v[104:107], v[176:179], v[202:205], v[104:107]
	v_mfma_f32_16x16x32_bf16 v[96:99], v[186:189], v[202:205], v[96:99]
	v_mfma_f32_16x16x32_bf16 v[88:91], v[176:179], v[210:213], v[88:91]
	v_mfma_f32_16x16x32_bf16 v[80:83], v[186:189], v[210:213], v[80:83]
	v_mfma_f32_16x16x32_bf16 v[72:75], v[176:179], v[218:221], v[72:75]
	v_mfma_f32_16x16x32_bf16 v[64:67], v[186:189], v[218:221], v[64:67]
	v_mfma_f32_16x16x32_bf16 v[120:123], v[180:183], v[198:201], v[120:123]
	v_mfma_f32_16x16x32_bf16 v[112:115], v[190:193], v[198:201], v[112:115]
	v_mfma_f32_16x16x32_bf16 v[104:107], v[180:183], v[206:209], v[104:107]
	v_mfma_f32_16x16x32_bf16 v[96:99], v[190:193], v[206:209], v[96:99]
	v_mfma_f32_16x16x32_bf16 v[88:91], v[180:183], v[214:217], v[88:91]
	v_mfma_f32_16x16x32_bf16 v[80:83], v[190:193], v[214:217], v[80:83]
	v_mfma_f32_16x16x32_bf16 v[72:75], v[180:183], v[222:225], v[72:75]
	v_mfma_f32_16x16x32_bf16 v[64:67], v[190:193], v[222:225], v[64:67]
	s_setprio 0
	s_barrier
	s_add_i32 s76, s66, s54
	v_lshl_add_u64 v[154:155], s[48:49], 0, v[132:133]
	s_mov_b32 m0, s76
	ds_read_b128 v[194:197], v150 offset:16384
	v_xor_b32_e32 v253, 64, v150
	ds_read_b128 v[198:201], v253 offset:16384
	ds_read_b128 v[202:205], v150 offset:18432
	ds_read_b128 v[206:209], v253 offset:18432
	ds_read_b128 v[210:213], v150 offset:20480
	ds_read_b128 v[214:217], v253 offset:20480
	ds_read_b128 v[218:221], v150 offset:22528
	ds_read_b128 v[222:225], v253 offset:22528
	global_load_lds_dwordx4 v[154:155], off
	s_add_i32 m0, s76, 0x2000
	s_add_u32 s76, s48, 0x40000
	v_lshl_add_u64 v[226:227], s[48:49], 0, v[128:129]
	s_addc_u32 s77, s49, 0
	s_add_i32 s78, s67, s54
	global_load_lds_dwordx4 v[226:227], off
	v_lshl_add_u64 v[228:229], s[76:77], 0, v[132:133]
	s_mov_b32 m0, s78
	v_lshl_add_u64 v[230:231], s[50:51], 0, v[130:131]
	global_load_lds_dwordx4 v[228:229], off
	v_lshl_add_u64 v[228:229], s[76:77], 0, v[128:129]
	s_add_i32 m0, s78, 0x2000
	s_nop 0
	global_load_lds_dwordx4 v[228:229], off
	v_lshl_add_u64 v[228:229], s[50:51], 0, v[134:135]
	s_mov_b32 m0, s57
	s_nop 0
	global_load_lds_dwordx4 v[228:229], off
	s_mov_b32 m0, s58
	s_nop 0
	global_load_lds_dwordx4 v[230:231], off
	s_waitcnt vmcnt(8)
	s_waitcnt lgkmcnt(0)
	s_barrier
	s_setprio 1
	s_waitcnt lgkmcnt(0)
	v_mfma_f32_16x16x32_bf16 v[60:63], v[160:163], v[194:197], v[60:63]
	v_mfma_f32_16x16x32_bf16 v[52:55], v[168:171], v[194:197], v[52:55]
	v_mfma_f32_16x16x32_bf16 v[44:47], v[160:163], v[202:205], v[44:47]
	v_mfma_f32_16x16x32_bf16 v[36:39], v[168:171], v[202:205], v[36:39]
	v_mfma_f32_16x16x32_bf16 v[28:31], v[160:163], v[210:213], v[28:31]
	v_mfma_f32_16x16x32_bf16 v[20:23], v[168:171], v[210:213], v[20:23]
	v_mfma_f32_16x16x32_bf16 v[12:15], v[160:163], v[218:221], v[12:15]
	v_mfma_f32_16x16x32_bf16 v[4:7], v[168:171], v[218:221], v[4:7]
	v_mfma_f32_16x16x32_bf16 v[60:63], v[164:167], v[198:201], v[60:63]
	v_mfma_f32_16x16x32_bf16 v[52:55], v[172:175], v[198:201], v[52:55]
	v_mfma_f32_16x16x32_bf16 v[44:47], v[164:167], v[206:209], v[44:47]
	v_mfma_f32_16x16x32_bf16 v[36:39], v[172:175], v[206:209], v[36:39]
	v_mfma_f32_16x16x32_bf16 v[28:31], v[164:167], v[214:217], v[28:31]
	v_mfma_f32_16x16x32_bf16 v[20:23], v[172:175], v[214:217], v[20:23]
	v_mfma_f32_16x16x32_bf16 v[12:15], v[164:167], v[222:225], v[12:15]
	v_mfma_f32_16x16x32_bf16 v[4:7], v[172:175], v[222:225], v[4:7]
	s_setprio 0
	s_setprio 1
	v_mfma_f32_16x16x32_bf16 v[56:59], v[176:179], v[194:197], v[56:59]
	v_mfma_f32_16x16x32_bf16 v[48:51], v[186:189], v[194:197], v[48:51]
	v_mfma_f32_16x16x32_bf16 v[40:43], v[176:179], v[202:205], v[40:43]
	v_mfma_f32_16x16x32_bf16 v[32:35], v[186:189], v[202:205], v[32:35]
	v_mfma_f32_16x16x32_bf16 v[24:27], v[176:179], v[210:213], v[24:27]
	v_mfma_f32_16x16x32_bf16 v[16:19], v[186:189], v[210:213], v[16:19]
	v_mfma_f32_16x16x32_bf16 v[8:11], v[176:179], v[218:221], v[8:11]
	v_mfma_f32_16x16x32_bf16 v[0:3], v[186:189], v[218:221], v[0:3]
	v_mfma_f32_16x16x32_bf16 v[56:59], v[180:183], v[198:201], v[56:59]
	v_mfma_f32_16x16x32_bf16 v[48:51], v[190:193], v[198:201], v[48:51]
	v_mfma_f32_16x16x32_bf16 v[40:43], v[180:183], v[206:209], v[40:43]
	v_mfma_f32_16x16x32_bf16 v[32:35], v[190:193], v[206:209], v[32:35]
	v_mfma_f32_16x16x32_bf16 v[24:27], v[180:183], v[214:217], v[24:27]
	v_mfma_f32_16x16x32_bf16 v[16:19], v[190:193], v[214:217], v[16:19]
	v_mfma_f32_16x16x32_bf16 v[8:11], v[180:183], v[222:225], v[8:11]
	v_mfma_f32_16x16x32_bf16 v[0:3], v[190:193], v[222:225], v[0:3]
	s_setprio 0
	s_barrier
	s_add_i32 s76, 0, 0x18000
	v_add_u32_e32 v153, s76, v147
	s_add_i32 s77, 0, 0x1c000
	ds_read_b128 v[160:163], v153
	v_xor_b32_e32 v253, 64, v153
	ds_read_b128 v[164:167], v253
	ds_read_b128 v[168:171], v153 offset:2048
	ds_read_b128 v[172:175], v253 offset:2048
	v_add_u32_e32 v153, s77, v147
	ds_read_b128 v[176:179], v153
	v_xor_b32_e32 v253, 64, v153
	ds_read_b128 v[180:183], v253
	ds_read_b128 v[186:189], v153 offset:2048
	ds_read_b128 v[190:193], v253 offset:2048
	s_add_u32 s50, s50, 0x40000
	s_addc_u32 s51, s51, 0
	s_mov_b32 m0, s59
	v_lshl_add_u64 v[232:233], s[50:51], 0, v[134:135]
	ds_read_b128 v[194:197], v150 offset:32768
	v_xor_b32_e32 v253, 64, v150
	ds_read_b128 v[198:201], v253 offset:32768
	ds_read_b128 v[202:205], v150 offset:34816
	ds_read_b128 v[206:209], v253 offset:34816
	ds_read_b128 v[210:213], v150 offset:36864
	ds_read_b128 v[214:217], v253 offset:36864
	ds_read_b128 v[218:221], v150 offset:38912
	ds_read_b128 v[222:225], v253 offset:38912
	global_load_lds_dwordx4 v[232:233], off
	v_lshl_add_u64 v[232:233], s[50:51], 0, v[130:131]
	s_mov_b32 m0, s60
	s_nop 0
	global_load_lds_dwordx4 v[232:233], off
	s_waitcnt vmcnt(8)
	s_waitcnt lgkmcnt(0)
	s_barrier
	s_setprio 1
	s_waitcnt lgkmcnt(0)
	v_mfma_f32_16x16x32_bf16 v[124:127], v[160:163], v[194:197], v[124:127]
	v_mfma_f32_16x16x32_bf16 v[116:119], v[168:171], v[194:197], v[116:119]
	v_mfma_f32_16x16x32_bf16 v[108:111], v[160:163], v[202:205], v[108:111]
	v_mfma_f32_16x16x32_bf16 v[100:103], v[168:171], v[202:205], v[100:103]
	v_mfma_f32_16x16x32_bf16 v[92:95], v[160:163], v[210:213], v[92:95]
	v_mfma_f32_16x16x32_bf16 v[84:87], v[168:171], v[210:213], v[84:87]
	v_mfma_f32_16x16x32_bf16 v[76:79], v[160:163], v[218:221], v[76:79]
	v_mfma_f32_16x16x32_bf16 v[68:71], v[168:171], v[218:221], v[68:71]
	v_mfma_f32_16x16x32_bf16 v[124:127], v[164:167], v[198:201], v[124:127]
	v_mfma_f32_16x16x32_bf16 v[116:119], v[172:175], v[198:201], v[116:119]
	v_mfma_f32_16x16x32_bf16 v[108:111], v[164:167], v[206:209], v[108:111]
	v_mfma_f32_16x16x32_bf16 v[100:103], v[172:175], v[206:209], v[100:103]
	v_mfma_f32_16x16x32_bf16 v[92:95], v[164:167], v[214:217], v[92:95]
	v_mfma_f32_16x16x32_bf16 v[84:87], v[172:175], v[214:217], v[84:87]
	v_mfma_f32_16x16x32_bf16 v[76:79], v[164:167], v[222:225], v[76:79]
	v_mfma_f32_16x16x32_bf16 v[68:71], v[172:175], v[222:225], v[68:71]
	s_setprio 0
	s_setprio 1
	v_mfma_f32_16x16x32_bf16 v[120:123], v[176:179], v[194:197], v[120:123]
	v_mfma_f32_16x16x32_bf16 v[112:115], v[186:189], v[194:197], v[112:115]
	v_mfma_f32_16x16x32_bf16 v[104:107], v[176:179], v[202:205], v[104:107]
	v_mfma_f32_16x16x32_bf16 v[96:99], v[186:189], v[202:205], v[96:99]
	v_mfma_f32_16x16x32_bf16 v[88:91], v[176:179], v[210:213], v[88:91]
	v_mfma_f32_16x16x32_bf16 v[80:83], v[186:189], v[210:213], v[80:83]
	v_mfma_f32_16x16x32_bf16 v[72:75], v[176:179], v[218:221], v[72:75]
	v_mfma_f32_16x16x32_bf16 v[64:67], v[186:189], v[218:221], v[64:67]
	v_mfma_f32_16x16x32_bf16 v[120:123], v[180:183], v[198:201], v[120:123]
	v_mfma_f32_16x16x32_bf16 v[112:115], v[190:193], v[198:201], v[112:115]
	v_mfma_f32_16x16x32_bf16 v[104:107], v[180:183], v[206:209], v[104:107]
	v_mfma_f32_16x16x32_bf16 v[96:99], v[190:193], v[206:209], v[96:99]
	v_mfma_f32_16x16x32_bf16 v[88:91], v[180:183], v[214:217], v[88:91]
	v_mfma_f32_16x16x32_bf16 v[80:83], v[190:193], v[214:217], v[80:83]
	v_mfma_f32_16x16x32_bf16 v[72:75], v[180:183], v[222:225], v[72:75]
	v_mfma_f32_16x16x32_bf16 v[64:67], v[190:193], v[222:225], v[64:67]
	s_setprio 0
	s_barrier
	v_add_u32_e32 v234, 0x21000, v151
	ds_read_b128 v[236:239], v234
	ds_read_b128 v[240:243], v234 offset:256
	ds_read_b128 v[244:247], v234 offset:512
	ds_read_b128 v[248:251], v234 offset:768
	v_add_u32_e32 v235, s27, v146
	v_mul_u32_u24_e32 v235, 0x1600, v235
	v_lshl_or_b32 v234, s69, 7, v149
	v_lshl_add_u32 v235, v234, 1, v235
	s_add_i32 s50, s76, s54
	v_lshl_add_u64 v[154:155], v[154:155], 0, s[20:21]
	s_mov_b32 m0, s50
	ds_read_b128 v[194:197], v150 offset:49152
	v_xor_b32_e32 v253, 64, v150
	ds_read_b128 v[198:201], v253 offset:49152
	ds_read_b128 v[202:205], v150 offset:51200
	ds_read_b128 v[206:209], v253 offset:51200
	ds_read_b128 v[210:213], v150 offset:53248
	ds_read_b128 v[214:217], v253 offset:53248
	ds_read_b128 v[218:221], v150 offset:55296
	ds_read_b128 v[222:225], v253 offset:55296
	global_load_lds_dwordx4 v[154:155], off
	s_add_i32 m0, s50, 0x2000
	s_add_u32 s48, s48, 0x40080
	v_lshl_add_u64 v[154:155], v[226:227], 0, s[20:21]
	s_addc_u32 s49, s49, 0
	s_add_i32 s50, s77, s54
	global_load_lds_dwordx4 v[154:155], off
	v_lshl_add_u64 v[154:155], s[48:49], 0, v[132:133]
	s_mov_b32 m0, s50
	s_nop 0
	global_load_lds_dwordx4 v[154:155], off
	v_lshl_add_u64 v[154:155], s[48:49], 0, v[128:129]
	s_add_i32 m0, s50, 0x2000
	s_nop 0
	global_load_lds_dwordx4 v[154:155], off
	v_lshl_add_u64 v[154:155], v[228:229], 0, s[20:21]
	s_mov_b32 m0, s62
	s_nop 0
	global_load_lds_dwordx4 v[154:155], off
	v_lshl_add_u64 v[154:155], v[230:231], 0, s[20:21]
	s_mov_b32 m0, s63
	s_nop 0
	global_load_lds_dwordx4 v[154:155], off
	s_waitcnt lgkmcnt(8)
	v_add_f32_e32 v236, v236, v237
	v_add_f32_e32 v238, v238, v239
	v_add_f32_e32 v240, v240, v241
	v_add_f32_e32 v242, v242, v243
	v_add_f32_e32 v244, v244, v245
	v_add_f32_e32 v246, v246, v247
	v_add_f32_e32 v248, v248, v249
	v_add_f32_e32 v250, v250, v251
	v_add_f32_e32 v236, v236, v238
	v_add_f32_e32 v240, v240, v242
	v_add_f32_e32 v244, v244, v246
	v_add_f32_e32 v248, v248, v250
	v_fmamk_f32 v236, v236, 0x3a800000, v152
	v_fmamk_f32 v240, v240, 0x3a800000, v152
	v_fmamk_f32 v244, v244, 0x3a800000, v152
	v_fmamk_f32 v248, v248, 0x3a800000, v152
	v_rsq_f32_e32 v236, v236
	v_rsq_f32_e32 v240, v240
	v_rsq_f32_e32 v244, v244
	v_rsq_f32_e32 v248, v248
	v_mul_f32_e32 v252, 0xbfb8aa3b, v236
	v_mul_f32_e32 v254, v236, v236
	v_pk_mul_f32 v[120:121], v[124:125], v[120:121]
	v_pk_mul_f32 v[122:123], v[126:127], v[122:123]
	v_pk_mul_f32 v[112:113], v[116:117], v[112:113]
	v_pk_mul_f32 v[114:115], v[118:119], v[114:115]
	v_pk_mul_f32 v[124:125], v[124:125], v[252:253] op_sel_hi:[1,0]
	v_pk_mul_f32 v[126:127], v[126:127], v[252:253] op_sel_hi:[1,0]
	v_pk_mul_f32 v[116:117], v[116:117], v[252:253] op_sel_hi:[1,0]
	v_pk_mul_f32 v[118:119], v[118:119], v[252:253] op_sel_hi:[1,0]
	v_exp_f32_e32 v124, v124
	v_exp_f32_e32 v125, v125
	v_exp_f32_e32 v126, v126
	v_exp_f32_e32 v127, v127
	v_exp_f32_e32 v116, v116
	v_exp_f32_e32 v117, v117
	v_exp_f32_e32 v118, v118
	v_exp_f32_e32 v119, v119
	v_pk_add_f32 v[124:125], v[124:125], 1.0 op_sel_hi:[1,0]
	v_pk_add_f32 v[126:127], v[126:127], 1.0 op_sel_hi:[1,0]
	v_pk_add_f32 v[116:117], v[116:117], 1.0 op_sel_hi:[1,0]
	v_pk_add_f32 v[118:119], v[118:119], 1.0 op_sel_hi:[1,0]
	v_rcp_f32_e32 v124, v124
	v_rcp_f32_e32 v125, v125
	v_rcp_f32_e32 v126, v126
	v_rcp_f32_e32 v127, v127
	v_rcp_f32_e32 v116, v116
	v_rcp_f32_e32 v117, v117
	v_rcp_f32_e32 v118, v118
	v_rcp_f32_e32 v119, v119
	v_pk_mul_f32 v[120:121], v[120:121], v[254:255] op_sel_hi:[1,0]
	v_pk_mul_f32 v[122:123], v[122:123], v[254:255] op_sel_hi:[1,0]
	v_pk_mul_f32 v[112:113], v[112:113], v[254:255] op_sel_hi:[1,0]
	v_pk_mul_f32 v[114:115], v[114:115], v[254:255] op_sel_hi:[1,0]
	v_pk_mul_f32 v[120:121], v[120:121], v[124:125]
	v_pk_mul_f32 v[122:123], v[122:123], v[126:127]
	v_pk_mul_f32 v[112:113], v[112:113], v[116:117]
	v_pk_mul_f32 v[114:115], v[114:115], v[118:119]
	v_cvt_pk_bf16_f32 v120, v120, v121
	v_cvt_pk_bf16_f32 v121, v122, v123
	v_cvt_pk_bf16_f32 v122, v112, v113
	v_cvt_pk_bf16_f32 v123, v114, v115
	global_store_dwordx4 v235, v[120:123], s[14:15]
	v_add_u32_e32 v234, 0x16000, v235
	v_mul_f32_e32 v252, 0xbfb8aa3b, v240
	v_mul_f32_e32 v254, v240, v240
	v_pk_mul_f32 v[104:105], v[108:109], v[104:105]
	v_pk_mul_f32 v[106:107], v[110:111], v[106:107]
	v_pk_mul_f32 v[96:97], v[100:101], v[96:97]
	v_pk_mul_f32 v[98:99], v[102:103], v[98:99]
	v_pk_mul_f32 v[108:109], v[108:109], v[252:253] op_sel_hi:[1,0]
	v_pk_mul_f32 v[110:111], v[110:111], v[252:253] op_sel_hi:[1,0]
	v_pk_mul_f32 v[100:101], v[100:101], v[252:253] op_sel_hi:[1,0]
	v_pk_mul_f32 v[102:103], v[102:103], v[252:253] op_sel_hi:[1,0]
	v_exp_f32_e32 v108, v108
	v_exp_f32_e32 v109, v109
	v_exp_f32_e32 v110, v110
	v_exp_f32_e32 v111, v111
	v_exp_f32_e32 v100, v100
	v_exp_f32_e32 v101, v101
	v_exp_f32_e32 v102, v102
	v_exp_f32_e32 v103, v103
	v_pk_add_f32 v[108:109], v[108:109], 1.0 op_sel_hi:[1,0]
	v_pk_add_f32 v[110:111], v[110:111], 1.0 op_sel_hi:[1,0]
	v_pk_add_f32 v[100:101], v[100:101], 1.0 op_sel_hi:[1,0]
	v_pk_add_f32 v[102:103], v[102:103], 1.0 op_sel_hi:[1,0]
	v_rcp_f32_e32 v108, v108
	v_rcp_f32_e32 v109, v109
	v_rcp_f32_e32 v110, v110
	v_rcp_f32_e32 v111, v111
	v_rcp_f32_e32 v100, v100
	v_rcp_f32_e32 v101, v101
	v_rcp_f32_e32 v102, v102
	v_rcp_f32_e32 v103, v103
	v_pk_mul_f32 v[104:105], v[104:105], v[254:255] op_sel_hi:[1,0]
	v_pk_mul_f32 v[106:107], v[106:107], v[254:255] op_sel_hi:[1,0]
	v_pk_mul_f32 v[96:97], v[96:97], v[254:255] op_sel_hi:[1,0]
	v_pk_mul_f32 v[98:99], v[98:99], v[254:255] op_sel_hi:[1,0]
	v_pk_mul_f32 v[104:105], v[104:105], v[108:109]
	v_pk_mul_f32 v[106:107], v[106:107], v[110:111]
	v_pk_mul_f32 v[96:97], v[96:97], v[100:101]
	v_pk_mul_f32 v[98:99], v[98:99], v[102:103]
	v_cvt_pk_bf16_f32 v104, v104, v105
	v_cvt_pk_bf16_f32 v105, v106, v107
	v_cvt_pk_bf16_f32 v106, v96, v97
	v_cvt_pk_bf16_f32 v107, v98, v99
	global_store_dwordx4 v234, v[104:107], s[14:15]
	v_add_u32_e32 v235, 0x16000, v234
	v_mul_f32_e32 v252, 0xbfb8aa3b, v244
	v_mul_f32_e32 v254, v244, v244
	v_pk_mul_f32 v[88:89], v[92:93], v[88:89]
	v_pk_mul_f32 v[90:91], v[94:95], v[90:91]
	v_pk_mul_f32 v[80:81], v[84:85], v[80:81]
	v_pk_mul_f32 v[82:83], v[86:87], v[82:83]
	v_pk_mul_f32 v[92:93], v[92:93], v[252:253] op_sel_hi:[1,0]
	v_pk_mul_f32 v[94:95], v[94:95], v[252:253] op_sel_hi:[1,0]
	v_pk_mul_f32 v[84:85], v[84:85], v[252:253] op_sel_hi:[1,0]
	v_pk_mul_f32 v[86:87], v[86:87], v[252:253] op_sel_hi:[1,0]
	v_exp_f32_e32 v92, v92
	v_exp_f32_e32 v93, v93
	v_exp_f32_e32 v94, v94
	v_exp_f32_e32 v95, v95
	v_exp_f32_e32 v84, v84
	v_exp_f32_e32 v85, v85
	v_exp_f32_e32 v86, v86
	v_exp_f32_e32 v87, v87
	v_pk_add_f32 v[92:93], v[92:93], 1.0 op_sel_hi:[1,0]
	v_pk_add_f32 v[94:95], v[94:95], 1.0 op_sel_hi:[1,0]
	v_pk_add_f32 v[84:85], v[84:85], 1.0 op_sel_hi:[1,0]
	v_pk_add_f32 v[86:87], v[86:87], 1.0 op_sel_hi:[1,0]
	v_rcp_f32_e32 v92, v92
	v_rcp_f32_e32 v93, v93
	v_rcp_f32_e32 v94, v94
	v_rcp_f32_e32 v95, v95
	v_rcp_f32_e32 v84, v84
	v_rcp_f32_e32 v85, v85
	v_rcp_f32_e32 v86, v86
	v_rcp_f32_e32 v87, v87
	v_pk_mul_f32 v[88:89], v[88:89], v[254:255] op_sel_hi:[1,0]
	v_pk_mul_f32 v[90:91], v[90:91], v[254:255] op_sel_hi:[1,0]
	v_pk_mul_f32 v[80:81], v[80:81], v[254:255] op_sel_hi:[1,0]
	v_pk_mul_f32 v[82:83], v[82:83], v[254:255] op_sel_hi:[1,0]
	v_pk_mul_f32 v[88:89], v[88:89], v[92:93]
	v_pk_mul_f32 v[90:91], v[90:91], v[94:95]
	v_pk_mul_f32 v[80:81], v[80:81], v[84:85]
	v_pk_mul_f32 v[82:83], v[82:83], v[86:87]
	v_cvt_pk_bf16_f32 v88, v88, v89
	v_cvt_pk_bf16_f32 v89, v90, v91
	v_cvt_pk_bf16_f32 v90, v80, v81
	v_cvt_pk_bf16_f32 v91, v82, v83
	global_store_dwordx4 v235, v[88:91], s[14:15]
	v_add_u32_e32 v234, 0x16000, v235
	v_mul_f32_e32 v252, 0xbfb8aa3b, v248
	v_mul_f32_e32 v254, v248, v248
	v_pk_mul_f32 v[72:73], v[76:77], v[72:73]
	v_pk_mul_f32 v[74:75], v[78:79], v[74:75]
	v_pk_mul_f32 v[64:65], v[68:69], v[64:65]
	v_pk_mul_f32 v[66:67], v[70:71], v[66:67]
	v_pk_mul_f32 v[76:77], v[76:77], v[252:253] op_sel_hi:[1,0]
	v_pk_mul_f32 v[78:79], v[78:79], v[252:253] op_sel_hi:[1,0]
	v_pk_mul_f32 v[68:69], v[68:69], v[252:253] op_sel_hi:[1,0]
	v_pk_mul_f32 v[70:71], v[70:71], v[252:253] op_sel_hi:[1,0]
	v_exp_f32_e32 v76, v76
	v_exp_f32_e32 v77, v77
	v_exp_f32_e32 v78, v78
	v_exp_f32_e32 v79, v79
	v_exp_f32_e32 v68, v68
	v_exp_f32_e32 v69, v69
	v_exp_f32_e32 v70, v70
	v_exp_f32_e32 v71, v71
	v_pk_add_f32 v[76:77], v[76:77], 1.0 op_sel_hi:[1,0]
	v_pk_add_f32 v[78:79], v[78:79], 1.0 op_sel_hi:[1,0]
	v_pk_add_f32 v[68:69], v[68:69], 1.0 op_sel_hi:[1,0]
	v_pk_add_f32 v[70:71], v[70:71], 1.0 op_sel_hi:[1,0]
	v_rcp_f32_e32 v76, v76
	v_rcp_f32_e32 v77, v77
	v_rcp_f32_e32 v78, v78
	v_rcp_f32_e32 v79, v79
	v_rcp_f32_e32 v68, v68
	v_rcp_f32_e32 v69, v69
	v_rcp_f32_e32 v70, v70
	v_rcp_f32_e32 v71, v71
	v_pk_mul_f32 v[72:73], v[72:73], v[254:255] op_sel_hi:[1,0]
	v_pk_mul_f32 v[74:75], v[74:75], v[254:255] op_sel_hi:[1,0]
	v_pk_mul_f32 v[64:65], v[64:65], v[254:255] op_sel_hi:[1,0]
	v_pk_mul_f32 v[66:67], v[66:67], v[254:255] op_sel_hi:[1,0]
	v_pk_mul_f32 v[72:73], v[72:73], v[76:77]
	v_pk_mul_f32 v[74:75], v[74:75], v[78:79]
	v_pk_mul_f32 v[64:65], v[64:65], v[68:69]
	v_pk_mul_f32 v[66:67], v[66:67], v[70:71]
	v_cvt_pk_bf16_f32 v72, v72, v73
	v_cvt_pk_bf16_f32 v73, v74, v75
	v_cvt_pk_bf16_f32 v74, v64, v65
	v_cvt_pk_bf16_f32 v75, v66, v67
	global_store_dwordx4 v234, v[72:75], s[14:15]
	s_waitcnt vmcnt(12)
	s_waitcnt lgkmcnt(0)
	s_barrier
	s_setprio 1
	s_waitcnt lgkmcnt(0)
	v_mfma_f32_16x16x32_bf16 v[60:63], v[160:163], v[194:197], v[60:63]
	v_mfma_f32_16x16x32_bf16 v[52:55], v[168:171], v[194:197], v[52:55]
	v_mfma_f32_16x16x32_bf16 v[44:47], v[160:163], v[202:205], v[44:47]
	v_mfma_f32_16x16x32_bf16 v[36:39], v[168:171], v[202:205], v[36:39]
	v_mfma_f32_16x16x32_bf16 v[28:31], v[160:163], v[210:213], v[28:31]
	v_mfma_f32_16x16x32_bf16 v[20:23], v[168:171], v[210:213], v[20:23]
	v_mfma_f32_16x16x32_bf16 v[12:15], v[160:163], v[218:221], v[12:15]
	v_mfma_f32_16x16x32_bf16 v[4:7], v[168:171], v[218:221], v[4:7]
	v_mfma_f32_16x16x32_bf16 v[60:63], v[164:167], v[198:201], v[60:63]
	v_mfma_f32_16x16x32_bf16 v[52:55], v[172:175], v[198:201], v[52:55]
	v_mfma_f32_16x16x32_bf16 v[44:47], v[164:167], v[206:209], v[44:47]
	v_mfma_f32_16x16x32_bf16 v[36:39], v[172:175], v[206:209], v[36:39]
	v_mfma_f32_16x16x32_bf16 v[28:31], v[164:167], v[214:217], v[28:31]
	v_mfma_f32_16x16x32_bf16 v[20:23], v[172:175], v[214:217], v[20:23]
	v_mfma_f32_16x16x32_bf16 v[12:15], v[164:167], v[222:225], v[12:15]
	v_mfma_f32_16x16x32_bf16 v[4:7], v[172:175], v[222:225], v[4:7]
	s_setprio 0
	s_setprio 1
	v_mfma_f32_16x16x32_bf16 v[56:59], v[176:179], v[194:197], v[56:59]
	v_mfma_f32_16x16x32_bf16 v[48:51], v[186:189], v[194:197], v[48:51]
	v_mfma_f32_16x16x32_bf16 v[40:43], v[176:179], v[202:205], v[40:43]
	v_mfma_f32_16x16x32_bf16 v[32:35], v[186:189], v[202:205], v[32:35]
	v_mfma_f32_16x16x32_bf16 v[24:27], v[176:179], v[210:213], v[24:27]
	v_mfma_f32_16x16x32_bf16 v[16:19], v[186:189], v[210:213], v[16:19]
	v_mfma_f32_16x16x32_bf16 v[8:11], v[176:179], v[218:221], v[8:11]
	v_mfma_f32_16x16x32_bf16 v[0:3], v[186:189], v[218:221], v[0:3]
	v_mfma_f32_16x16x32_bf16 v[56:59], v[180:183], v[198:201], v[56:59]
	v_mfma_f32_16x16x32_bf16 v[48:51], v[190:193], v[198:201], v[48:51]
	v_mfma_f32_16x16x32_bf16 v[40:43], v[180:183], v[206:209], v[40:43]
	v_mfma_f32_16x16x32_bf16 v[32:35], v[190:193], v[206:209], v[32:35]
	v_mfma_f32_16x16x32_bf16 v[24:27], v[180:183], v[214:217], v[24:27]
	v_mfma_f32_16x16x32_bf16 v[16:19], v[190:193], v[214:217], v[16:19]
	v_mfma_f32_16x16x32_bf16 v[8:11], v[180:183], v[222:225], v[8:11]
	v_mfma_f32_16x16x32_bf16 v[0:3], v[190:193], v[222:225], v[0:3]
	s_setprio 0
	s_barrier
	s_add_i32 s75, s75, 2
	s_add_u32 s73, s73, 0x100
	s_addc_u32 s74, s74, 0
	s_add_u32 s46, s46, 0x100
	s_addc_u32 s47, s47, 0

.LBB0_593:
	s_and_b64 vcc, exec, s[4:5]
	s_cbranch_vccnz .LBB0_635
	v_ashrrev_i32_e32 v1, 31, v8
	v_lshrrev_b32_e32 v1, 26, v1
	v_add_u32_e32 v1, v8, v1
	v_ashrrev_i32_e32 v9, 6, v1
	v_bfe_i32 v1, v8, 27, 1
	v_lshlrev_b32_e32 v0, 4, v8
	v_lshrrev_b32_e32 v1, 22, v1
	v_add_u32_e32 v1, v0, v1
	v_and_b32_e32 v1, 0xfffffc00, v1
	v_sub_u32_e32 v1, v0, v1
	v_lshrrev_b32_e32 v2, 4, v1
	v_bitop3_b32 v1, v2, v1, 32 bitop3:0x6c
	v_ashrrev_i32_e32 v3, 31, v1
	v_lshrrev_b32_e32 v3, 26, v3
	v_lshlrev_b32_e32 v2, 3, v9
	v_add_u32_e32 v3, v1, v3
	v_and_b32_e32 v2, -16, v2
	v_ashrrev_i32_e32 v10, 6, v3
	v_and_b32_e32 v3, 0xc0, v3
	v_add_u32_e32 v2, v10, v2
	v_lshlrev_b32_e32 v4, 5, v9
	v_sub_u32_e32 v1, v1, v3
	v_mov_b32_e32 v3, 1
	v_and_b32_e32 v11, 32, v4
	v_ashrrev_i16_sdwa v1, v3, sext(v1) dst_sel:DWORD dst_unused:UNUSED_PAD src0_sel:DWORD src1_sel:BYTE_0
	v_lshlrev_b32_e32 v4, 1, v2
	v_lshrrev_b32_e32 v5, 2, v2
	v_and_b32_e32 v6, 3, v10
	s_mov_b32 s12, 0xffffe0
	v_bfe_i32 v12, v1, 0, 16
	v_and_b32_e32 v4, 24, v4
	v_and_b32_e32 v5, 4, v5
	v_and_or_b32 v6, v2, s12, v6
	s_movk_i32 s15, 0xb00
	v_add_u32_e32 v1, v11, v12
	v_or3_b32 v4, v6, v5, v4
	v_mul_lo_u32 v2, v2, s15
	v_add_lshl_u32 v152, v1, v2, 1
	v_lshrrev_b32_e32 v250, 3, v157
	v_and_b32_e32 v251, 6, v250
	v_and_b32_e32 v252, 7, v157
	v_xor_b32_e32 v251, v251, v252
	v_lshlrev_b32_e32 v251, 4, v251
	v_mul_u32_u24_e32 v250, 0x1600, v250
	v_add_u32_e32 v152, v250, v251
	v_mul_u32_u24_e32 v2, 0xb00, v4
	v_add_u32_e32 v0, 0x2000, v0
	v_add_lshl_u32 v154, v2, v1, 1
	v_lshrrev_b32_e32 v250, 3, v157
	v_and_b32_e32 v251, 6, v250
	v_and_b32_e32 v252, 7, v157
	v_xor_b32_e32 v251, v251, v252
	v_lshlrev_b32_e32 v251, 4, v251
	v_and_b32_e32 v252, 12, v250
	v_lshlrev_b32_e32 v252, 1, v252
	v_and_b32_e32 v253, 16, v250
	v_lshrrev_b32_e32 v253, 2, v253
	v_or_b32_e32 v252, v252, v253
	v_and_b32_e32 v253, 35, v250
	v_or_b32_e32 v250, v252, v253
	v_mul_u32_u24_e32 v250, 0x1600, v250
	v_add_u32_e32 v154, v250, v251
	v_ashrrev_i32_e32 v1, 31, v0
	v_lshrrev_b32_e32 v1, 22, v1
	v_add_u32_e32 v1, v0, v1
	v_ashrrev_i32_e32 v13, 10, v1
	v_mul_i32_i24_e32 v1, 0x400, v13
	v_sub_u32_e32 v0, v0, v1
	v_lshrrev_b32_e32 v1, 4, v0
	v_bitop3_b32 v0, v1, v0, 32 bitop3:0x6c
	v_ashrrev_i32_e32 v2, 31, v0
	s_waitcnt lgkmcnt(0)
	s_add_u32 s35, s10, 0xa000000
	v_lshrrev_b32_e32 v2, 26, v2
	s_addc_u32 s62, s11, 0
	v_lshlrev_b32_e32 v1, 3, v13
	v_add_u32_e32 v2, v0, v2
	s_add_u32 s63, s10, 0x3580000
	v_and_b32_e32 v1, -16, v1
	v_ashrrev_i32_e32 v15, 6, v2
	v_lshlrev_b32_e32 v4, 5, v13
	s_addc_u32 s64, s11, 0
	s_ashr_i32 s3, s14, 6
	v_add_u32_e32 v1, v15, v1
	v_and_b32_e32 v14, 32, v4
	v_and_b32_e32 v2, 0xc0, v2
	v_and_b32_e32 v4, 3, v15
	v_sub_u32_e32 v0, v0, v2
	v_and_or_b32 v4, v1, s12, v4
	s_ashr_i32 s12, s14, 8
	s_lshl_b32 s65, s3, 10
	s_mul_i32 s17, s20, 0x160000
	v_ashrrev_i16_sdwa v0, v3, sext(v0) dst_sel:DWORD dst_unused:UNUSED_PAD src0_sel:DWORD src1_sel:BYTE_0
	v_lshlrev_b32_e32 v2, 1, v1
	v_lshrrev_b32_e32 v3, 2, v1
	s_mul_hi_i32 s16, s20, 0x160000
	s_add_u32 s56, s63, s17
	v_bfe_i32 v16, v0, 0, 16
	v_and_b32_e32 v2, 24, v2
	v_and_b32_e32 v3, 4, v3
	s_addc_u32 s57, s64, s16
	s_add_i32 s66, s65, 0
	v_add_u32_e32 v0, v14, v16
	v_or3_b32 v2, v4, v3, v2
	v_mul_lo_u32 v1, v1, s15
	s_add_i32 m0, s66, 0x10000
	v_add_lshl_u32 v160, v0, v1, 1
	v_lshrrev_b32_e32 v250, 3, v157
	v_and_b32_e32 v251, 6, v250
	v_and_b32_e32 v252, 7, v157
	v_xor_b32_e32 v251, v251, v252
	v_lshlrev_b32_e32 v251, 4, v251
	v_mul_u32_u24_e32 v250, 0x1600, v250
	v_add_u32_e32 v160, v250, v251
	v_add_u32_e32 v160, 0x58000, v160
	v_mul_u32_u24_e32 v1, 0xb00, v2
	global_load_lds_dwordx4 v154, s[56:57]
	s_add_i32 m0, s66, 0x12000
	v_add_lshl_u32 v162, v1, v0, 1
	v_lshrrev_b32_e32 v250, 3, v157
	v_and_b32_e32 v251, 6, v250
	v_and_b32_e32 v252, 7, v157
	v_xor_b32_e32 v251, v251, v252
	v_lshlrev_b32_e32 v251, 4, v251
	v_and_b32_e32 v252, 12, v250
	v_lshlrev_b32_e32 v252, 1, v252
	v_and_b32_e32 v253, 16, v250
	v_lshrrev_b32_e32 v253, 2, v253
	v_or_b32_e32 v252, v252, v253
	v_and_b32_e32 v253, 35, v250
	v_or_b32_e32 v250, v252, v253
	v_mul_u32_u24_e32 v250, 0x1600, v250
	v_add_u32_e32 v162, v250, v251
	v_add_u32_e32 v162, 0x58000, v162
	s_add_u32 s16, s56, 0xb0000
	global_load_lds_dwordx4 v162, s[56:57]
	s_addc_u32 s17, s57, 0
	s_add_i32 m0, s66, 0x14000
	s_mul_i32 s22, s21, 0x160000
	global_load_lds_dwordx4 v154, s[16:17]
	s_add_i32 m0, s66, 0x16000
	s_mul_hi_i32 s13, s21, 0x160000
	s_add_u32 s54, s35, s22
	s_addc_u32 s55, s62, s13
	s_add_i32 s67, s66, 0x2000
	global_load_lds_dwordx4 v162, s[16:17]
	s_mov_b32 m0, s66
	s_add_u32 s16, s54, 0xb0000
	global_load_lds_dwordx4 v152, s[54:55]
	s_mov_b32 m0, s67
	s_addc_u32 s17, s55, 0
	s_add_i32 s68, s66, 0x4000
	global_load_lds_dwordx4 v160, s[54:55]
	s_mov_b32 m0, s68
	s_add_i32 s69, s66, 0x6000
	global_load_lds_dwordx4 v152, s[16:17]
	s_mov_b32 m0, s69
	v_mov_b32_e32 v155, 0
	global_load_lds_dwordx4 v160, s[16:17]
	v_mov_b32_e32 v163, v155
	v_mov_b32_e32 v153, v155
	v_mov_b32_e32 v161, v155
	s_cmp_eq_u32 s12, 1
	s_mov_b32 s70, 0
	v_lshl_add_u64 v[6:7], s[56:57], 0, v[154:155]
	v_lshl_add_u64 v[4:5], s[56:57], 0, v[162:163]
	v_lshl_add_u64 v[0:1], s[54:55], 0, v[152:153]
	s_cselect_b64 s[22:23], -1, 0
	s_cmp_lg_u32 s12, 1
	v_lshl_add_u64 v[2:3], s[54:55], 0, v[160:161]
	s_cbranch_scc1 .LBB0_596
	s_barrier
.LBB0_596:
	s_add_u32 s24, s10, 0x6000000
	s_addc_u32 s25, s11, 0
	s_add_u32 s26, s10, 0x100000
	s_mov_b64 s[28:29], 0x80
	s_addc_u32 s27, s11, 0
	s_and_b32 s44, s3, 3
	s_add_i32 m0, s66, 0x18000
	v_lshl_add_u64 v[6:7], v[6:7], 0, s[28:29]
	s_lshl_b32 s13, s12, 13
	s_lshl_b32 s16, s44, 12
	s_waitcnt vmcnt(2)
	s_barrier
	global_load_lds_dwordx4 v[6:7], off
	v_lshl_add_u64 v[4:5], v[4:5], 0, s[28:29]
	s_add_i32 m0, s66, 0x1a000
	s_add_i32 s3, s66, 0x8000
	s_add_i32 s71, s66, 0xa000
	global_load_lds_dwordx4 v[4:5], off
	v_lshl_add_u64 v[0:1], v[0:1], 0, s[28:29]
	s_mov_b32 m0, s3
	s_add_u32 s10, s56, 0xb0080
	global_load_lds_dwordx4 v[0:1], off
	v_lshl_add_u64 v[0:1], v[2:3], 0, s[28:29]
	s_mov_b32 m0, s71
	s_addc_u32 s11, s57, 0
	global_load_lds_dwordx4 v[0:1], off
	s_add_i32 m0, s66, 0x1c000
	v_lshl_add_u64 v[0:1], s[10:11], 0, v[154:155]
	global_load_lds_dwordx4 v[0:1], off
	v_lshl_add_u64 v[0:1], s[10:11], 0, v[162:163]
	s_add_i32 m0, s66, 0x1e000
	s_cmpk_lt_u32 s14, 0x100
	global_load_lds_dwordx4 v[0:1], off
	v_bfe_u32 v0, v8, 4, 2
	v_and_b32_e32 v1, 15, v8
	v_lshlrev_b32_e32 v3, 4, v0
	s_cselect_b64 s[30:31], -1, 0
	s_lshl_b32 s14, s44, 2
	v_lshl_or_b32 v185, s12, 6, v1
	v_lshl_or_b32 v1, v1, 6, v3
	v_lshlrev_b32_e32 v3, 2, v8
	s_add_i32 s14, s14, 0
	v_and_b32_e32 v3, 32, v3
	s_add_i32 s14, s14, 0x20000
	v_lshlrev_b32_e32 v2, 3, v0
	v_bitop3_b32 v4, v1, s13, v3 bitop3:0xde
	v_bitop3_b32 v186, v1, s16, v3 bitop3:0xde
	v_and_b32_e32 v250, 15, v157
	v_bfe_u32 v251, v157, 4, 2
	v_and_b32_e32 v252, 2, v250
	v_xor_b32_e32 v251, v251, v252
	v_and_b32_e32 v252, 4, v250
	v_lshlrev_b32_e32 v252, 4, v252
	v_lshl_or_b32 v251, v251, 4, v252
	v_lshl_or_b32 v250, v250, 7, v251
	v_bfe_u32 v253, v157, 6, 2
	v_lshl_or_b32 v186, v253, 12, v250
	v_cmp_eq_u32_e64 s[10:11], 0, v0
	v_lshl_add_u32 v188, v185, 4, s14
	v_lshrrev_b32_e32 v1, 1, v13
	v_mul_lo_u32 v0, v15, s15
	s_mov_b32 s14, 0xb000
	v_lshl_or_b32 v187, s44, 5, v2
	v_mad_u64_u32 v[0:1], s[44:45], v1, s14, v[0:1]
	v_or_b32_e32 v0, v0, v14
	s_mov_b64 s[16:17], 0xb0080
	v_add_lshl_u32 v0, v0, v16, 1
	v_mov_b32_e32 v1, v155
	v_lshrrev_b32_e32 v250, 3, v157
	v_and_b32_e32 v251, 6, v250
	v_and_b32_e32 v252, 7, v157
	v_xor_b32_e32 v251, v251, v252
	v_lshlrev_b32_e32 v251, 4, v251
	v_mul_u32_u24_e32 v250, 0x1600, v250
	v_add_u32_e32 v0, v250, v251
	v_add_u32_e32 v0, 0x58000, v0
	v_lshl_add_u64 v[164:165], v[0:1], 0, s[16:17]
	v_lshrrev_b32_e32 v1, 1, v9
	v_mul_lo_u32 v0, v10, s15
	v_mad_u64_u32 v[0:1], s[14:15], v1, s14, v[0:1]
	v_or_b32_e32 v0, v0, v11
	s_waitcnt vmcnt(6)
	v_lshlrev_b32_e32 v2, 4, v157
	v_add_lshl_u32 v0, v0, v12, 1
	v_mov_b32_e32 v1, v155
	s_movk_i32 s12, 0x100
	v_lshrrev_b32_e32 v250, 3, v157
	v_and_b32_e32 v251, 6, v250
	v_and_b32_e32 v252, 7, v157
	v_xor_b32_e32 v251, v251, v252
	v_lshlrev_b32_e32 v251, 4, v251
	v_mul_u32_u24_e32 v250, 0x1600, v250
	v_add_u32_e32 v0, v250, v251
	v_lshl_add_u64 v[166:167], v[0:1], 0, s[16:17]
	s_add_i32 s75, 0, 0x10000
	s_add_i32 s76, 0, 0x14000
	v_add_u32_e32 v0, 0, v2
	v_cmp_gt_u32_e64 s[12:13], s12, v157
	s_ashr_i32 s72, s42, 31
	s_mov_b32 s73, s42
	s_ashr_i32 s74, s2, 31
	v_mov_b64_e32 v[168:169], 0x200
	v_mov_b64_e32 v[170:171], 0x1ff
	v_add_u32_e32 v189, s75, v186
	v_add_u32_e32 v190, s76, v186
	v_add_u32_e32 v191, 0, v4
	v_and_b32_e32 v250, 15, v157
	v_bfe_u32 v251, v157, 4, 2
	v_and_b32_e32 v252, 2, v250
	v_xor_b32_e32 v251, v251, v252
	v_and_b32_e32 v252, 4, v250
	v_lshlrev_b32_e32 v252, 4, v252
	v_lshl_or_b32 v251, v251, 4, v252
	v_lshl_or_b32 v250, v250, 7, v251
	v_lshrrev_b32_e32 v253, 8, v157
	v_lshl_or_b32 v191, v253, 13, v250
	s_mov_b64 s[44:45], 0x40000
	s_mov_b64 s[46:47], 0x48000
	s_mov_b64 s[48:49], 0x50000
	s_mov_b64 s[50:51], 0x58000
	v_add_u32_e32 v192, 0x20000, v0
	s_barrier
	s_branch .LBB0_599

.LBB0_609:
	s_add_u32 s79, s56, 0x100
	s_addc_u32 s80, s57, 0
	s_mov_b32 s81, -2
	s_waitcnt lgkmcnt(0)
	s_cmp_eq_u32 s70, 1
	s_cbranch_scc1 .Lfa_5
	ds_read_b128 v[128:131], v189
	v_xor_b32_e32 v253, 64, v189
	ds_read_b128 v[132:135], v253
	ds_read_b128 v[136:139], v189 offset:2048
	ds_read_b128 v[140:143], v253 offset:2048
	ds_read_b128 v[144:147], v190
	v_xor_b32_e32 v253, 64, v190
	ds_read_b128 v[148:151], v253
	ds_read_b128 v[172:175], v190 offset:2048
	ds_read_b128 v[176:179], v253 offset:2048
	s_add_u32 s56, s54, 0x100
	s_addc_u32 s57, s55, 0
	s_cmp_eq_u32 s81, 40
	s_cselect_b32 s61, s17, s57
	s_cselect_b32 s60, s16, s56
	s_cselect_b32 s59, s53, s80
	s_cselect_b32 s58, s52, s79
	v_lshl_add_u64 v[222:223], s[54:55], 0, v[166:167]
	s_add_i32 m0, s66, 0xc000
	ds_read_b128 v[180:183], v191
	v_xor_b32_e32 v253, 64, v191
	ds_read_b128 v[194:197], v253
	ds_read_b128 v[198:201], v191 offset:2048
	ds_read_b128 v[202:205], v253 offset:2048
	ds_read_b128 v[206:209], v191 offset:4096
	ds_read_b128 v[210:213], v253 offset:4096
	ds_read_b128 v[214:217], v191 offset:6144
	ds_read_b128 v[218:221], v253 offset:6144
	global_load_lds_dwordx4 v[222:223], off
	v_lshl_add_u64 v[222:223], s[54:55], 0, v[164:165]
	s_add_i32 m0, s66, 0xe000
	s_nop 0
	global_load_lds_dwordx4 v[222:223], off
	s_waitcnt vmcnt(24)
	s_waitcnt lgkmcnt(0)
	s_barrier
	s_setprio 1
	s_waitcnt lgkmcnt(0)
	v_mfma_f32_16x16x32_bf16 v[124:127], v[128:131], v[180:183], 0
	v_mfma_f32_16x16x32_bf16 v[120:123], v[136:139], v[180:183], 0
	v_mfma_f32_16x16x32_bf16 v[108:111], v[128:131], v[198:201], 0
	v_mfma_f32_16x16x32_bf16 v[104:107], v[136:139], v[198:201], 0
	v_mfma_f32_16x16x32_bf16 v[92:95], v[128:131], v[206:209], 0
	v_mfma_f32_16x16x32_bf16 v[88:91], v[136:139], v[206:209], 0
	v_mfma_f32_16x16x32_bf16 v[76:79], v[128:131], v[214:217], 0
	v_mfma_f32_16x16x32_bf16 v[72:75], v[136:139], v[214:217], 0
	v_mfma_f32_16x16x32_bf16 v[124:127], v[132:135], v[194:197], v[124:127]
	v_mfma_f32_16x16x32_bf16 v[120:123], v[140:143], v[194:197], v[120:123]
	v_mfma_f32_16x16x32_bf16 v[108:111], v[132:135], v[202:205], v[108:111]
	v_mfma_f32_16x16x32_bf16 v[104:107], v[140:143], v[202:205], v[104:107]
	v_mfma_f32_16x16x32_bf16 v[92:95], v[132:135], v[210:213], v[92:95]
	v_mfma_f32_16x16x32_bf16 v[88:91], v[140:143], v[210:213], v[88:91]
	v_mfma_f32_16x16x32_bf16 v[76:79], v[132:135], v[218:221], v[76:79]
	v_mfma_f32_16x16x32_bf16 v[72:75], v[140:143], v[218:221], v[72:75]
	s_setprio 0
	s_setprio 1
	v_mfma_f32_16x16x32_bf16 v[116:119], v[144:147], v[180:183], 0
	v_mfma_f32_16x16x32_bf16 v[112:115], v[172:175], v[180:183], 0
	v_mfma_f32_16x16x32_bf16 v[100:103], v[144:147], v[198:201], 0
	v_mfma_f32_16x16x32_bf16 v[96:99], v[172:175], v[198:201], 0
	v_mfma_f32_16x16x32_bf16 v[84:87], v[144:147], v[206:209], 0
	v_mfma_f32_16x16x32_bf16 v[80:83], v[172:175], v[206:209], 0
	v_mfma_f32_16x16x32_bf16 v[68:71], v[144:147], v[214:217], 0
	v_mfma_f32_16x16x32_bf16 v[64:67], v[172:175], v[214:217], 0
	v_mfma_f32_16x16x32_bf16 v[116:119], v[148:151], v[194:197], v[116:119]
	v_mfma_f32_16x16x32_bf16 v[112:115], v[176:179], v[194:197], v[112:115]
	v_mfma_f32_16x16x32_bf16 v[100:103], v[148:151], v[202:205], v[100:103]
	v_mfma_f32_16x16x32_bf16 v[96:99], v[176:179], v[202:205], v[96:99]
	v_mfma_f32_16x16x32_bf16 v[84:87], v[148:151], v[210:213], v[84:87]
	v_mfma_f32_16x16x32_bf16 v[80:83], v[176:179], v[210:213], v[80:83]
	v_mfma_f32_16x16x32_bf16 v[68:71], v[148:151], v[218:221], v[68:71]
	v_mfma_f32_16x16x32_bf16 v[64:67], v[176:179], v[218:221], v[64:67]
	s_setprio 0
	s_barrier
	s_add_i32 s54, s75, s65
	v_lshl_add_u64 v[222:223], s[58:59], 0, v[154:155]
	s_mov_b32 m0, s54
	ds_read_b128 v[180:183], v191 offset:16384
	v_xor_b32_e32 v253, 64, v191
	ds_read_b128 v[194:197], v253 offset:16384
	ds_read_b128 v[198:201], v191 offset:18432
	ds_read_b128 v[202:205], v253 offset:18432
	ds_read_b128 v[206:209], v191 offset:20480
	ds_read_b128 v[210:213], v253 offset:20480
	ds_read_b128 v[214:217], v191 offset:22528
	ds_read_b128 v[218:221], v253 offset:22528
	global_load_lds_dwordx4 v[222:223], off
	s_add_i32 m0, s54, 0x2000
	s_add_u32 s54, s58, 0xb0000
	v_lshl_add_u64 v[224:225], s[58:59], 0, v[162:163]
	s_addc_u32 s55, s59, 0
	s_add_i32 s82, s76, s65
	global_load_lds_dwordx4 v[224:225], off
	v_lshl_add_u64 v[226:227], s[54:55], 0, v[154:155]
	s_mov_b32 m0, s82
	v_lshl_add_u64 v[228:229], s[60:61], 0, v[160:161]
	global_load_lds_dwordx4 v[226:227], off
	v_lshl_add_u64 v[226:227], s[54:55], 0, v[162:163]
	s_add_i32 m0, s82, 0x2000
	s_nop 0
	global_load_lds_dwordx4 v[226:227], off
	v_lshl_add_u64 v[226:227], s[60:61], 0, v[152:153]
	s_mov_b32 m0, s66
	s_nop 0
	global_load_lds_dwordx4 v[226:227], off
	s_mov_b32 m0, s67
	s_nop 0
	global_load_lds_dwordx4 v[228:229], off
	s_waitcnt vmcnt(24)
	s_waitcnt lgkmcnt(0)
	s_barrier
	s_setprio 1
	s_waitcnt lgkmcnt(0)
	v_mfma_f32_16x16x32_bf16 v[60:63], v[128:131], v[180:183], 0
	v_mfma_f32_16x16x32_bf16 v[56:59], v[136:139], v[180:183], 0
	v_mfma_f32_16x16x32_bf16 v[44:47], v[128:131], v[198:201], 0
	v_mfma_f32_16x16x32_bf16 v[40:43], v[136:139], v[198:201], 0
	v_mfma_f32_16x16x32_bf16 v[28:31], v[128:131], v[206:209], 0
	v_mfma_f32_16x16x32_bf16 v[24:27], v[136:139], v[206:209], 0
	v_mfma_f32_16x16x32_bf16 v[12:15], v[128:131], v[214:217], 0
	v_mfma_f32_16x16x32_bf16 v[8:11], v[136:139], v[214:217], 0
	v_mfma_f32_16x16x32_bf16 v[60:63], v[132:135], v[194:197], v[60:63]
	v_mfma_f32_16x16x32_bf16 v[56:59], v[140:143], v[194:197], v[56:59]
	v_mfma_f32_16x16x32_bf16 v[44:47], v[132:135], v[202:205], v[44:47]
	v_mfma_f32_16x16x32_bf16 v[40:43], v[140:143], v[202:205], v[40:43]
	v_mfma_f32_16x16x32_bf16 v[28:31], v[132:135], v[210:213], v[28:31]
	v_mfma_f32_16x16x32_bf16 v[24:27], v[140:143], v[210:213], v[24:27]
	v_mfma_f32_16x16x32_bf16 v[12:15], v[132:135], v[218:221], v[12:15]
	v_mfma_f32_16x16x32_bf16 v[8:11], v[140:143], v[218:221], v[8:11]
	s_setprio 0
	s_setprio 1
	v_mfma_f32_16x16x32_bf16 v[52:55], v[144:147], v[180:183], 0
	v_mfma_f32_16x16x32_bf16 v[48:51], v[172:175], v[180:183], 0
	v_mfma_f32_16x16x32_bf16 v[36:39], v[144:147], v[198:201], 0
	v_mfma_f32_16x16x32_bf16 v[32:35], v[172:175], v[198:201], 0
	v_mfma_f32_16x16x32_bf16 v[20:23], v[144:147], v[206:209], 0
	v_mfma_f32_16x16x32_bf16 v[16:19], v[172:175], v[206:209], 0
	v_mfma_f32_16x16x32_bf16 v[4:7], v[144:147], v[214:217], 0
	v_mfma_f32_16x16x32_bf16 v[0:3], v[172:175], v[214:217], 0
	v_mfma_f32_16x16x32_bf16 v[52:55], v[148:151], v[194:197], v[52:55]
	v_mfma_f32_16x16x32_bf16 v[48:51], v[176:179], v[194:197], v[48:51]
	v_mfma_f32_16x16x32_bf16 v[36:39], v[148:151], v[202:205], v[36:39]
	v_mfma_f32_16x16x32_bf16 v[32:35], v[176:179], v[202:205], v[32:35]
	v_mfma_f32_16x16x32_bf16 v[20:23], v[148:151], v[210:213], v[20:23]
	v_mfma_f32_16x16x32_bf16 v[16:19], v[176:179], v[210:213], v[16:19]
	v_mfma_f32_16x16x32_bf16 v[4:7], v[148:151], v[218:221], v[4:7]
	v_mfma_f32_16x16x32_bf16 v[0:3], v[176:179], v[218:221], v[0:3]
	s_setprio 0
	s_barrier
	s_add_i32 s82, 0, 0x18000
	s_add_i32 s83, 0, 0x1c000
	v_add_u32_e32 v140, s82, v186
	v_add_u32_e32 v176, s83, v186
	ds_read_b128 v[128:131], v140
	v_xor_b32_e32 v253, 64, v140
	ds_read_b128 v[132:135], v253
	ds_read_b128 v[136:139], v140 offset:2048
	ds_read_b128 v[140:143], v253 offset:2048
	ds_read_b128 v[144:147], v176
	v_xor_b32_e32 v253, 64, v176
	ds_read_b128 v[148:151], v253
	ds_read_b128 v[172:175], v176 offset:2048
	ds_read_b128 v[176:179], v253 offset:2048
	s_add_u32 s54, s60, 0xb0000
	s_addc_u32 s55, s61, 0
	s_mov_b32 m0, s68
	v_lshl_add_u64 v[230:231], s[54:55], 0, v[152:153]
	ds_read_b128 v[180:183], v191 offset:32768
	v_xor_b32_e32 v253, 64, v191
	ds_read_b128 v[194:197], v253 offset:32768
	ds_read_b128 v[198:201], v191 offset:34816
	ds_read_b128 v[202:205], v253 offset:34816
	ds_read_b128 v[206:209], v191 offset:36864
	ds_read_b128 v[210:213], v253 offset:36864
	ds_read_b128 v[214:217], v191 offset:38912
	ds_read_b128 v[218:221], v253 offset:38912
	global_load_lds_dwordx4 v[230:231], off
	v_lshl_add_u64 v[230:231], s[54:55], 0, v[160:161]
	s_mov_b32 m0, s69
	s_nop 0
	global_load_lds_dwordx4 v[230:231], off
	s_waitcnt vmcnt(8)
	s_waitcnt lgkmcnt(0)
	s_barrier
	s_setprio 1
	s_waitcnt lgkmcnt(0)
	v_mfma_f32_16x16x32_bf16 v[124:127], v[128:131], v[180:183], v[124:127]
	v_mfma_f32_16x16x32_bf16 v[120:123], v[136:139], v[180:183], v[120:123]
	v_mfma_f32_16x16x32_bf16 v[108:111], v[128:131], v[198:201], v[108:111]
	v_mfma_f32_16x16x32_bf16 v[104:107], v[136:139], v[198:201], v[104:107]
	v_mfma_f32_16x16x32_bf16 v[92:95], v[128:131], v[206:209], v[92:95]
	v_mfma_f32_16x16x32_bf16 v[88:91], v[136:139], v[206:209], v[88:91]
	v_mfma_f32_16x16x32_bf16 v[76:79], v[128:131], v[214:217], v[76:79]
	v_mfma_f32_16x16x32_bf16 v[72:75], v[136:139], v[214:217], v[72:75]
	v_mfma_f32_16x16x32_bf16 v[124:127], v[132:135], v[194:197], v[124:127]
	v_mfma_f32_16x16x32_bf16 v[120:123], v[140:143], v[194:197], v[120:123]
	v_mfma_f32_16x16x32_bf16 v[108:111], v[132:135], v[202:205], v[108:111]
	v_mfma_f32_16x16x32_bf16 v[104:107], v[140:143], v[202:205], v[104:107]
	v_mfma_f32_16x16x32_bf16 v[92:95], v[132:135], v[210:213], v[92:95]
	v_mfma_f32_16x16x32_bf16 v[88:91], v[140:143], v[210:213], v[88:91]
	v_mfma_f32_16x16x32_bf16 v[76:79], v[132:135], v[218:221], v[76:79]
	v_mfma_f32_16x16x32_bf16 v[72:75], v[140:143], v[218:221], v[72:75]
	s_setprio 0
	s_setprio 1
	v_mfma_f32_16x16x32_bf16 v[116:119], v[144:147], v[180:183], v[116:119]
	v_mfma_f32_16x16x32_bf16 v[112:115], v[172:175], v[180:183], v[112:115]
	v_mfma_f32_16x16x32_bf16 v[100:103], v[144:147], v[198:201], v[100:103]
	v_mfma_f32_16x16x32_bf16 v[96:99], v[172:175], v[198:201], v[96:99]
	v_mfma_f32_16x16x32_bf16 v[84:87], v[144:147], v[206:209], v[84:87]
	v_mfma_f32_16x16x32_bf16 v[80:83], v[172:175], v[206:209], v[80:83]
	v_mfma_f32_16x16x32_bf16 v[68:71], v[144:147], v[214:217], v[68:71]
	v_mfma_f32_16x16x32_bf16 v[64:67], v[172:175], v[214:217], v[64:67]
	v_mfma_f32_16x16x32_bf16 v[116:119], v[148:151], v[194:197], v[116:119]
	v_mfma_f32_16x16x32_bf16 v[112:115], v[176:179], v[194:197], v[112:115]
	v_mfma_f32_16x16x32_bf16 v[100:103], v[148:151], v[202:205], v[100:103]
	v_mfma_f32_16x16x32_bf16 v[96:99], v[176:179], v[202:205], v[96:99]
	v_mfma_f32_16x16x32_bf16 v[84:87], v[148:151], v[210:213], v[84:87]
	v_mfma_f32_16x16x32_bf16 v[80:83], v[176:179], v[210:213], v[80:83]
	v_mfma_f32_16x16x32_bf16 v[68:71], v[148:151], v[218:221], v[68:71]
	v_mfma_f32_16x16x32_bf16 v[64:67], v[176:179], v[218:221], v[64:67]
	s_setprio 0
	s_barrier
	s_add_i32 s54, s82, s65
	v_lshl_add_u64 v[222:223], v[222:223], 0, s[28:29]
	s_mov_b32 m0, s54
	ds_read_b128 v[180:183], v191 offset:49152
	v_xor_b32_e32 v253, 64, v191
	ds_read_b128 v[194:197], v253 offset:49152
	ds_read_b128 v[198:201], v191 offset:51200
	ds_read_b128 v[202:205], v253 offset:51200
	ds_read_b128 v[206:209], v191 offset:53248
	ds_read_b128 v[210:213], v253 offset:53248
	ds_read_b128 v[214:217], v191 offset:55296
	ds_read_b128 v[218:221], v253 offset:55296
	global_load_lds_dwordx4 v[222:223], off
	s_add_i32 m0, s54, 0x2000
	s_add_u32 s54, s58, 0xb0080
	v_lshl_add_u64 v[222:223], v[224:225], 0, s[28:29]
	s_addc_u32 s55, s59, 0
	s_add_i32 s58, s83, s65
	global_load_lds_dwordx4 v[222:223], off
	v_lshl_add_u64 v[222:223], s[54:55], 0, v[154:155]
	s_mov_b32 m0, s58
	s_nop 0
	global_load_lds_dwordx4 v[222:223], off
	v_lshl_add_u64 v[222:223], s[54:55], 0, v[162:163]
	s_add_i32 m0, s58, 0x2000
	s_nop 0
	global_load_lds_dwordx4 v[222:223], off
	v_lshl_add_u64 v[222:223], v[226:227], 0, s[28:29]
	s_mov_b32 m0, s3
	s_nop 0
	global_load_lds_dwordx4 v[222:223], off
	v_lshl_add_u64 v[222:223], v[228:229], 0, s[28:29]
	s_mov_b32 m0, s71
	s_nop 0
	global_load_lds_dwordx4 v[222:223], off
	s_waitcnt vmcnt(8)
	s_waitcnt lgkmcnt(0)
	s_barrier
	s_setprio 1
	s_waitcnt lgkmcnt(0)
	v_mfma_f32_16x16x32_bf16 v[60:63], v[128:131], v[180:183], v[60:63]
	v_mfma_f32_16x16x32_bf16 v[56:59], v[136:139], v[180:183], v[56:59]
	v_mfma_f32_16x16x32_bf16 v[44:47], v[128:131], v[198:201], v[44:47]
	v_mfma_f32_16x16x32_bf16 v[40:43], v[136:139], v[198:201], v[40:43]
	v_mfma_f32_16x16x32_bf16 v[28:31], v[128:131], v[206:209], v[28:31]
	v_mfma_f32_16x16x32_bf16 v[24:27], v[136:139], v[206:209], v[24:27]
	v_mfma_f32_16x16x32_bf16 v[12:15], v[128:131], v[214:217], v[12:15]
	v_mfma_f32_16x16x32_bf16 v[8:11], v[136:139], v[214:217], v[8:11]
	v_mfma_f32_16x16x32_bf16 v[60:63], v[132:135], v[194:197], v[60:63]
	v_mfma_f32_16x16x32_bf16 v[56:59], v[140:143], v[194:197], v[56:59]
	v_mfma_f32_16x16x32_bf16 v[44:47], v[132:135], v[202:205], v[44:47]
	v_mfma_f32_16x16x32_bf16 v[40:43], v[140:143], v[202:205], v[40:43]
	v_mfma_f32_16x16x32_bf16 v[28:31], v[132:135], v[210:213], v[28:31]
	v_mfma_f32_16x16x32_bf16 v[24:27], v[140:143], v[210:213], v[24:27]
	v_mfma_f32_16x16x32_bf16 v[12:15], v[132:135], v[218:221], v[12:15]
	v_mfma_f32_16x16x32_bf16 v[8:11], v[140:143], v[218:221], v[8:11]
	s_setprio 0
	s_setprio 1
	v_mfma_f32_16x16x32_bf16 v[52:55], v[144:147], v[180:183], v[52:55]
	v_mfma_f32_16x16x32_bf16 v[48:51], v[172:175], v[180:183], v[48:51]
	v_mfma_f32_16x16x32_bf16 v[36:39], v[144:147], v[198:201], v[36:39]
	v_mfma_f32_16x16x32_bf16 v[32:35], v[172:175], v[198:201], v[32:35]
	v_mfma_f32_16x16x32_bf16 v[20:23], v[144:147], v[206:209], v[20:23]
	v_mfma_f32_16x16x32_bf16 v[16:19], v[172:175], v[206:209], v[16:19]
	v_mfma_f32_16x16x32_bf16 v[4:7], v[144:147], v[214:217], v[4:7]
	v_mfma_f32_16x16x32_bf16 v[0:3], v[172:175], v[214:217], v[0:3]
	v_mfma_f32_16x16x32_bf16 v[52:55], v[148:151], v[194:197], v[52:55]
	v_mfma_f32_16x16x32_bf16 v[48:51], v[176:179], v[194:197], v[48:51]
	v_mfma_f32_16x16x32_bf16 v[36:39], v[148:151], v[202:205], v[36:39]
	v_mfma_f32_16x16x32_bf16 v[32:35], v[176:179], v[202:205], v[32:35]
	v_mfma_f32_16x16x32_bf16 v[20:23], v[148:151], v[210:213], v[20:23]
	v_mfma_f32_16x16x32_bf16 v[16:19], v[176:179], v[210:213], v[16:19]
	v_mfma_f32_16x16x32_bf16 v[4:7], v[148:151], v[218:221], v[4:7]
	v_mfma_f32_16x16x32_bf16 v[0:3], v[176:179], v[218:221], v[0:3]
	s_setprio 0
	s_barrier
	s_add_i32 s81, s81, 2
	s_add_u32 s79, s79, 0x100
	s_addc_u32 s80, s80, 0
	s_cmp_gt_u32 s81, 41
	s_mov_b64 s[54:55], s[56:57]
	s_branch .LBB0_610
.Lfa_5:
	ds_read_b128 v[128:131], v189
	v_xor_b32_e32 v253, 64, v189
	ds_read_b128 v[132:135], v253
	ds_read_b128 v[136:139], v189 offset:2048
	ds_read_b128 v[140:143], v253 offset:2048
	ds_read_b128 v[144:147], v190
	v_xor_b32_e32 v253, 64, v190
	ds_read_b128 v[148:151], v253
	ds_read_b128 v[172:175], v190 offset:2048
	ds_read_b128 v[176:179], v253 offset:2048
	s_add_u32 s56, s54, 0x100
	s_addc_u32 s57, s55, 0
	s_cmp_eq_u32 s81, 40
	s_cselect_b32 s61, s17, s57
	s_cselect_b32 s60, s16, s56
	s_cselect_b32 s59, s53, s80
	s_cselect_b32 s58, s52, s79
	v_lshl_add_u64 v[222:223], s[54:55], 0, v[166:167]
	s_add_i32 m0, s66, 0xc000
	ds_read_b128 v[180:183], v191
	v_xor_b32_e32 v253, 64, v191
	ds_read_b128 v[194:197], v253
	ds_read_b128 v[198:201], v191 offset:2048
	ds_read_b128 v[202:205], v253 offset:2048
	ds_read_b128 v[206:209], v191 offset:4096
	ds_read_b128 v[210:213], v253 offset:4096
	ds_read_b128 v[214:217], v191 offset:6144
	ds_read_b128 v[218:221], v253 offset:6144
	global_load_lds_dwordx4 v[222:223], off
	v_lshl_add_u64 v[222:223], s[54:55], 0, v[164:165]
	s_add_i32 m0, s66, 0xe000
	s_nop 0
	global_load_lds_dwordx4 v[222:223], off
	s_waitcnt vmcnt(8)
	s_waitcnt lgkmcnt(0)
	s_barrier
	s_setprio 1
	s_waitcnt lgkmcnt(0)
	v_mfma_f32_16x16x32_bf16 v[124:127], v[128:131], v[180:183], 0
	v_mfma_f32_16x16x32_bf16 v[120:123], v[136:139], v[180:183], 0
	v_mfma_f32_16x16x32_bf16 v[108:111], v[128:131], v[198:201], 0
	v_mfma_f32_16x16x32_bf16 v[104:107], v[136:139], v[198:201], 0
	v_mfma_f32_16x16x32_bf16 v[92:95], v[128:131], v[206:209], 0
	v_mfma_f32_16x16x32_bf16 v[88:91], v[136:139], v[206:209], 0
	v_mfma_f32_16x16x32_bf16 v[76:79], v[128:131], v[214:217], 0
	v_mfma_f32_16x16x32_bf16 v[72:75], v[136:139], v[214:217], 0
	v_mfma_f32_16x16x32_bf16 v[124:127], v[132:135], v[194:197], v[124:127]
	v_mfma_f32_16x16x32_bf16 v[120:123], v[140:143], v[194:197], v[120:123]
	v_mfma_f32_16x16x32_bf16 v[108:111], v[132:135], v[202:205], v[108:111]
	v_mfma_f32_16x16x32_bf16 v[104:107], v[140:143], v[202:205], v[104:107]
	v_mfma_f32_16x16x32_bf16 v[92:95], v[132:135], v[210:213], v[92:95]
	v_mfma_f32_16x16x32_bf16 v[88:91], v[140:143], v[210:213], v[88:91]
	v_mfma_f32_16x16x32_bf16 v[76:79], v[132:135], v[218:221], v[76:79]
	v_mfma_f32_16x16x32_bf16 v[72:75], v[140:143], v[218:221], v[72:75]
	s_setprio 0
	s_setprio 1
	v_mfma_f32_16x16x32_bf16 v[116:119], v[144:147], v[180:183], 0
	v_mfma_f32_16x16x32_bf16 v[112:115], v[172:175], v[180:183], 0
	v_mfma_f32_16x16x32_bf16 v[100:103], v[144:147], v[198:201], 0
	v_mfma_f32_16x16x32_bf16 v[96:99], v[172:175], v[198:201], 0
	v_mfma_f32_16x16x32_bf16 v[84:87], v[144:147], v[206:209], 0
	v_mfma_f32_16x16x32_bf16 v[80:83], v[172:175], v[206:209], 0
	v_mfma_f32_16x16x32_bf16 v[68:71], v[144:147], v[214:217], 0
	v_mfma_f32_16x16x32_bf16 v[64:67], v[172:175], v[214:217], 0
	v_mfma_f32_16x16x32_bf16 v[116:119], v[148:151], v[194:197], v[116:119]
	v_mfma_f32_16x16x32_bf16 v[112:115], v[176:179], v[194:197], v[112:115]
	v_mfma_f32_16x16x32_bf16 v[100:103], v[148:151], v[202:205], v[100:103]
	v_mfma_f32_16x16x32_bf16 v[96:99], v[176:179], v[202:205], v[96:99]
	v_mfma_f32_16x16x32_bf16 v[84:87], v[148:151], v[210:213], v[84:87]
	v_mfma_f32_16x16x32_bf16 v[80:83], v[176:179], v[210:213], v[80:83]
	v_mfma_f32_16x16x32_bf16 v[68:71], v[148:151], v[218:221], v[68:71]
	v_mfma_f32_16x16x32_bf16 v[64:67], v[176:179], v[218:221], v[64:67]
	s_setprio 0
	s_barrier
	s_add_i32 s54, s75, s65
	v_lshl_add_u64 v[222:223], s[58:59], 0, v[154:155]
	s_mov_b32 m0, s54
	ds_read_b128 v[180:183], v191 offset:16384
	v_xor_b32_e32 v253, 64, v191
	ds_read_b128 v[194:197], v253 offset:16384
	ds_read_b128 v[198:201], v191 offset:18432
	ds_read_b128 v[202:205], v253 offset:18432
	ds_read_b128 v[206:209], v191 offset:20480
	ds_read_b128 v[210:213], v253 offset:20480
	ds_read_b128 v[214:217], v191 offset:22528
	ds_read_b128 v[218:221], v253 offset:22528
	global_load_lds_dwordx4 v[222:223], off
	s_add_i32 m0, s54, 0x2000
	s_add_u32 s54, s58, 0xb0000
	v_lshl_add_u64 v[224:225], s[58:59], 0, v[162:163]
	s_addc_u32 s55, s59, 0
	s_add_i32 s82, s76, s65
	global_load_lds_dwordx4 v[224:225], off
	v_lshl_add_u64 v[226:227], s[54:55], 0, v[154:155]
	s_mov_b32 m0, s82
	v_lshl_add_u64 v[228:229], s[60:61], 0, v[160:161]
	global_load_lds_dwordx4 v[226:227], off
	v_lshl_add_u64 v[226:227], s[54:55], 0, v[162:163]
	s_add_i32 m0, s82, 0x2000
	s_nop 0
	global_load_lds_dwordx4 v[226:227], off
	v_lshl_add_u64 v[226:227], s[60:61], 0, v[152:153]
	s_mov_b32 m0, s66
	s_nop 0
	global_load_lds_dwordx4 v[226:227], off
	s_mov_b32 m0, s67
	s_nop 0
	global_load_lds_dwordx4 v[228:229], off
	s_waitcnt vmcnt(8)
	s_waitcnt lgkmcnt(0)
	s_barrier
	s_setprio 1
	s_waitcnt lgkmcnt(0)
	v_mfma_f32_16x16x32_bf16 v[60:63], v[128:131], v[180:183], 0
	v_mfma_f32_16x16x32_bf16 v[56:59], v[136:139], v[180:183], 0
	v_mfma_f32_16x16x32_bf16 v[44:47], v[128:131], v[198:201], 0
	v_mfma_f32_16x16x32_bf16 v[40:43], v[136:139], v[198:201], 0
	v_mfma_f32_16x16x32_bf16 v[28:31], v[128:131], v[206:209], 0
	v_mfma_f32_16x16x32_bf16 v[24:27], v[136:139], v[206:209], 0
	v_mfma_f32_16x16x32_bf16 v[12:15], v[128:131], v[214:217], 0
	v_mfma_f32_16x16x32_bf16 v[8:11], v[136:139], v[214:217], 0
	v_mfma_f32_16x16x32_bf16 v[60:63], v[132:135], v[194:197], v[60:63]
	v_mfma_f32_16x16x32_bf16 v[56:59], v[140:143], v[194:197], v[56:59]
	v_mfma_f32_16x16x32_bf16 v[44:47], v[132:135], v[202:205], v[44:47]
	v_mfma_f32_16x16x32_bf16 v[40:43], v[140:143], v[202:205], v[40:43]
	v_mfma_f32_16x16x32_bf16 v[28:31], v[132:135], v[210:213], v[28:31]
	v_mfma_f32_16x16x32_bf16 v[24:27], v[140:143], v[210:213], v[24:27]
	v_mfma_f32_16x16x32_bf16 v[12:15], v[132:135], v[218:221], v[12:15]
	v_mfma_f32_16x16x32_bf16 v[8:11], v[140:143], v[218:221], v[8:11]
	s_setprio 0
	s_setprio 1
	v_mfma_f32_16x16x32_bf16 v[52:55], v[144:147], v[180:183], 0
	v_mfma_f32_16x16x32_bf16 v[48:51], v[172:175], v[180:183], 0
	v_mfma_f32_16x16x32_bf16 v[36:39], v[144:147], v[198:201], 0
	v_mfma_f32_16x16x32_bf16 v[32:35], v[172:175], v[198:201], 0
	v_mfma_f32_16x16x32_bf16 v[20:23], v[144:147], v[206:209], 0
	v_mfma_f32_16x16x32_bf16 v[16:19], v[172:175], v[206:209], 0
	v_mfma_f32_16x16x32_bf16 v[4:7], v[144:147], v[214:217], 0
	v_mfma_f32_16x16x32_bf16 v[0:3], v[172:175], v[214:217], 0
	v_mfma_f32_16x16x32_bf16 v[52:55], v[148:151], v[194:197], v[52:55]
	v_mfma_f32_16x16x32_bf16 v[48:51], v[176:179], v[194:197], v[48:51]
	v_mfma_f32_16x16x32_bf16 v[36:39], v[148:151], v[202:205], v[36:39]
	v_mfma_f32_16x16x32_bf16 v[32:35], v[176:179], v[202:205], v[32:35]
	v_mfma_f32_16x16x32_bf16 v[20:23], v[148:151], v[210:213], v[20:23]
	v_mfma_f32_16x16x32_bf16 v[16:19], v[176:179], v[210:213], v[16:19]
	v_mfma_f32_16x16x32_bf16 v[4:7], v[148:151], v[218:221], v[4:7]
	v_mfma_f32_16x16x32_bf16 v[0:3], v[176:179], v[218:221], v[0:3]
	s_setprio 0
	s_barrier
	s_add_i32 s82, 0, 0x18000
	s_add_i32 s83, 0, 0x1c000
	v_add_u32_e32 v140, s82, v186
	v_add_u32_e32 v176, s83, v186
	ds_read_b128 v[128:131], v140
	v_xor_b32_e32 v253, 64, v140
	ds_read_b128 v[132:135], v253
	ds_read_b128 v[136:139], v140 offset:2048
	ds_read_b128 v[140:143], v253 offset:2048
	ds_read_b128 v[144:147], v176
	v_xor_b32_e32 v253, 64, v176
	ds_read_b128 v[148:151], v253
	ds_read_b128 v[172:175], v176 offset:2048
	ds_read_b128 v[176:179], v253 offset:2048
	s_add_u32 s54, s60, 0xb0000
	s_addc_u32 s55, s61, 0
	s_mov_b32 m0, s68
	v_lshl_add_u64 v[230:231], s[54:55], 0, v[152:153]
	ds_read_b128 v[180:183], v191 offset:32768
	v_xor_b32_e32 v253, 64, v191
	ds_read_b128 v[194:197], v253 offset:32768
	ds_read_b128 v[198:201], v191 offset:34816
	ds_read_b128 v[202:205], v253 offset:34816
	ds_read_b128 v[206:209], v191 offset:36864
	ds_read_b128 v[210:213], v253 offset:36864
	ds_read_b128 v[214:217], v191 offset:38912
	ds_read_b128 v[218:221], v253 offset:38912
	global_load_lds_dwordx4 v[230:231], off
	v_lshl_add_u64 v[230:231], s[54:55], 0, v[160:161]
	s_mov_b32 m0, s69
	s_nop 0
	global_load_lds_dwordx4 v[230:231], off
	s_waitcnt vmcnt(8)
	s_waitcnt lgkmcnt(0)
	s_barrier
	s_setprio 1
	s_waitcnt lgkmcnt(0)
	v_mfma_f32_16x16x32_bf16 v[124:127], v[128:131], v[180:183], v[124:127]
	v_mfma_f32_16x16x32_bf16 v[120:123], v[136:139], v[180:183], v[120:123]
	v_mfma_f32_16x16x32_bf16 v[108:111], v[128:131], v[198:201], v[108:111]
	v_mfma_f32_16x16x32_bf16 v[104:107], v[136:139], v[198:201], v[104:107]
	v_mfma_f32_16x16x32_bf16 v[92:95], v[128:131], v[206:209], v[92:95]
	v_mfma_f32_16x16x32_bf16 v[88:91], v[136:139], v[206:209], v[88:91]
	v_mfma_f32_16x16x32_bf16 v[76:79], v[128:131], v[214:217], v[76:79]
	v_mfma_f32_16x16x32_bf16 v[72:75], v[136:139], v[214:217], v[72:75]
	v_mfma_f32_16x16x32_bf16 v[124:127], v[132:135], v[194:197], v[124:127]
	v_mfma_f32_16x16x32_bf16 v[120:123], v[140:143], v[194:197], v[120:123]
	v_mfma_f32_16x16x32_bf16 v[108:111], v[132:135], v[202:205], v[108:111]
	v_mfma_f32_16x16x32_bf16 v[104:107], v[140:143], v[202:205], v[104:107]
	v_mfma_f32_16x16x32_bf16 v[92:95], v[132:135], v[210:213], v[92:95]
	v_mfma_f32_16x16x32_bf16 v[88:91], v[140:143], v[210:213], v[88:91]
	v_mfma_f32_16x16x32_bf16 v[76:79], v[132:135], v[218:221], v[76:79]
	v_mfma_f32_16x16x32_bf16 v[72:75], v[140:143], v[218:221], v[72:75]
	s_setprio 0
	s_setprio 1
	v_mfma_f32_16x16x32_bf16 v[116:119], v[144:147], v[180:183], v[116:119]
	v_mfma_f32_16x16x32_bf16 v[112:115], v[172:175], v[180:183], v[112:115]
	v_mfma_f32_16x16x32_bf16 v[100:103], v[144:147], v[198:201], v[100:103]
	v_mfma_f32_16x16x32_bf16 v[96:99], v[172:175], v[198:201], v[96:99]
	v_mfma_f32_16x16x32_bf16 v[84:87], v[144:147], v[206:209], v[84:87]
	v_mfma_f32_16x16x32_bf16 v[80:83], v[172:175], v[206:209], v[80:83]
	v_mfma_f32_16x16x32_bf16 v[68:71], v[144:147], v[214:217], v[68:71]
	v_mfma_f32_16x16x32_bf16 v[64:67], v[172:175], v[214:217], v[64:67]
	v_mfma_f32_16x16x32_bf16 v[116:119], v[148:151], v[194:197], v[116:119]
	v_mfma_f32_16x16x32_bf16 v[112:115], v[176:179], v[194:197], v[112:115]
	v_mfma_f32_16x16x32_bf16 v[100:103], v[148:151], v[202:205], v[100:103]
	v_mfma_f32_16x16x32_bf16 v[96:99], v[176:179], v[202:205], v[96:99]
	v_mfma_f32_16x16x32_bf16 v[84:87], v[148:151], v[210:213], v[84:87]
	v_mfma_f32_16x16x32_bf16 v[80:83], v[176:179], v[210:213], v[80:83]
	v_mfma_f32_16x16x32_bf16 v[68:71], v[148:151], v[218:221], v[68:71]
	v_mfma_f32_16x16x32_bf16 v[64:67], v[176:179], v[218:221], v[64:67]
	s_setprio 0
	s_barrier
	s_add_i32 s54, s82, s65
	v_lshl_add_u64 v[222:223], v[222:223], 0, s[28:29]
	s_mov_b32 m0, s54
	ds_read_b128 v[180:183], v191 offset:49152
	v_xor_b32_e32 v253, 64, v191
	ds_read_b128 v[194:197], v253 offset:49152
	ds_read_b128 v[198:201], v191 offset:51200
	ds_read_b128 v[202:205], v253 offset:51200
	ds_read_b128 v[206:209], v191 offset:53248
	ds_read_b128 v[210:213], v253 offset:53248
	ds_read_b128 v[214:217], v191 offset:55296
	ds_read_b128 v[218:221], v253 offset:55296
	global_load_lds_dwordx4 v[222:223], off
	s_add_i32 m0, s54, 0x2000
	s_add_u32 s54, s58, 0xb0080
	v_lshl_add_u64 v[222:223], v[224:225], 0, s[28:29]
	s_addc_u32 s55, s59, 0
	s_add_i32 s58, s83, s65
	global_load_lds_dwordx4 v[222:223], off
	v_lshl_add_u64 v[222:223], s[54:55], 0, v[154:155]
	s_mov_b32 m0, s58
	s_nop 0
	global_load_lds_dwordx4 v[222:223], off
	v_lshl_add_u64 v[222:223], s[54:55], 0, v[162:163]
	s_add_i32 m0, s58, 0x2000
	s_nop 0
	global_load_lds_dwordx4 v[222:223], off
	v_lshl_add_u64 v[222:223], v[226:227], 0, s[28:29]
	s_mov_b32 m0, s3
	s_nop 0
	global_load_lds_dwordx4 v[222:223], off
	v_lshl_add_u64 v[222:223], v[228:229], 0, s[28:29]
	s_mov_b32 m0, s71
	s_nop 0
	global_load_lds_dwordx4 v[222:223], off
	s_waitcnt vmcnt(8)
	s_waitcnt lgkmcnt(0)
	s_barrier
	s_setprio 1
	s_waitcnt lgkmcnt(0)
	v_mfma_f32_16x16x32_bf16 v[60:63], v[128:131], v[180:183], v[60:63]
	v_mfma_f32_16x16x32_bf16 v[56:59], v[136:139], v[180:183], v[56:59]
	v_mfma_f32_16x16x32_bf16 v[44:47], v[128:131], v[198:201], v[44:47]
	v_mfma_f32_16x16x32_bf16 v[40:43], v[136:139], v[198:201], v[40:43]
	v_mfma_f32_16x16x32_bf16 v[28:31], v[128:131], v[206:209], v[28:31]
	v_mfma_f32_16x16x32_bf16 v[24:27], v[136:139], v[206:209], v[24:27]
	v_mfma_f32_16x16x32_bf16 v[12:15], v[128:131], v[214:217], v[12:15]
	v_mfma_f32_16x16x32_bf16 v[8:11], v[136:139], v[214:217], v[8:11]
	v_mfma_f32_16x16x32_bf16 v[60:63], v[132:135], v[194:197], v[60:63]
	v_mfma_f32_16x16x32_bf16 v[56:59], v[140:143], v[194:197], v[56:59]
	v_mfma_f32_16x16x32_bf16 v[44:47], v[132:135], v[202:205], v[44:47]
	v_mfma_f32_16x16x32_bf16 v[40:43], v[140:143], v[202:205], v[40:43]
	v_mfma_f32_16x16x32_bf16 v[28:31], v[132:135], v[210:213], v[28:31]
	v_mfma_f32_16x16x32_bf16 v[24:27], v[140:143], v[210:213], v[24:27]
	v_mfma_f32_16x16x32_bf16 v[12:15], v[132:135], v[218:221], v[12:15]
	v_mfma_f32_16x16x32_bf16 v[8:11], v[140:143], v[218:221], v[8:11]
	s_setprio 0
	s_setprio 1
	v_mfma_f32_16x16x32_bf16 v[52:55], v[144:147], v[180:183], v[52:55]
	v_mfma_f32_16x16x32_bf16 v[48:51], v[172:175], v[180:183], v[48:51]
	v_mfma_f32_16x16x32_bf16 v[36:39], v[144:147], v[198:201], v[36:39]
	v_mfma_f32_16x16x32_bf16 v[32:35], v[172:175], v[198:201], v[32:35]
	v_mfma_f32_16x16x32_bf16 v[20:23], v[144:147], v[206:209], v[20:23]
	v_mfma_f32_16x16x32_bf16 v[16:19], v[172:175], v[206:209], v[16:19]
	v_mfma_f32_16x16x32_bf16 v[4:7], v[144:147], v[214:217], v[4:7]
	v_mfma_f32_16x16x32_bf16 v[0:3], v[172:175], v[214:217], v[0:3]
	v_mfma_f32_16x16x32_bf16 v[52:55], v[148:151], v[194:197], v[52:55]
	v_mfma_f32_16x16x32_bf16 v[48:51], v[176:179], v[194:197], v[48:51]
	v_mfma_f32_16x16x32_bf16 v[36:39], v[148:151], v[202:205], v[36:39]
	v_mfma_f32_16x16x32_bf16 v[32:35], v[176:179], v[202:205], v[32:35]
	v_mfma_f32_16x16x32_bf16 v[20:23], v[148:151], v[210:213], v[20:23]
	v_mfma_f32_16x16x32_bf16 v[16:19], v[176:179], v[210:213], v[16:19]
	v_mfma_f32_16x16x32_bf16 v[4:7], v[148:151], v[218:221], v[4:7]
	v_mfma_f32_16x16x32_bf16 v[0:3], v[176:179], v[218:221], v[0:3]
	s_setprio 0
	s_barrier
	s_add_i32 s81, s81, 2
	s_add_u32 s79, s79, 0x100
	s_addc_u32 s80, s80, 0
	s_cmp_gt_u32 s81, 41
	s_mov_b64 s[54:55], s[56:57]
.LBB0_610:
	ds_read_b128 v[128:131], v189
	v_xor_b32_e32 v253, 64, v189
	ds_read_b128 v[132:135], v253
	ds_read_b128 v[136:139], v189 offset:2048
	ds_read_b128 v[140:143], v253 offset:2048
	ds_read_b128 v[144:147], v190
	v_xor_b32_e32 v253, 64, v190
	ds_read_b128 v[148:151], v253
	ds_read_b128 v[172:175], v190 offset:2048
	ds_read_b128 v[176:179], v253 offset:2048
	s_add_u32 s56, s54, 0x100
	s_addc_u32 s57, s55, 0
	s_cmp_eq_u32 s81, 40
	s_cselect_b32 s61, s17, s57
	s_cselect_b32 s60, s16, s56
	s_cselect_b32 s59, s53, s80
	s_cselect_b32 s58, s52, s79
	v_lshl_add_u64 v[222:223], s[54:55], 0, v[166:167]
	s_add_i32 m0, s66, 0xc000
	ds_read_b128 v[180:183], v191
	v_xor_b32_e32 v253, 64, v191
	ds_read_b128 v[194:197], v253
	ds_read_b128 v[198:201], v191 offset:2048
	ds_read_b128 v[202:205], v253 offset:2048
	ds_read_b128 v[206:209], v191 offset:4096
	ds_read_b128 v[210:213], v253 offset:4096
	ds_read_b128 v[214:217], v191 offset:6144
	ds_read_b128 v[218:221], v253 offset:6144
	global_load_lds_dwordx4 v[222:223], off
	v_lshl_add_u64 v[222:223], s[54:55], 0, v[164:165]
	s_add_i32 m0, s66, 0xe000
	s_nop 0
	global_load_lds_dwordx4 v[222:223], off
	s_waitcnt vmcnt(8)
	s_waitcnt lgkmcnt(0)
	s_barrier
	s_setprio 1
	s_waitcnt lgkmcnt(0)
	v_mfma_f32_16x16x32_bf16 v[124:127], v[128:131], v[180:183], v[124:127]
	v_mfma_f32_16x16x32_bf16 v[120:123], v[136:139], v[180:183], v[120:123]
	v_mfma_f32_16x16x32_bf16 v[108:111], v[128:131], v[198:201], v[108:111]
	v_mfma_f32_16x16x32_bf16 v[104:107], v[136:139], v[198:201], v[104:107]
	v_mfma_f32_16x16x32_bf16 v[92:95], v[128:131], v[206:209], v[92:95]
	v_mfma_f32_16x16x32_bf16 v[88:91], v[136:139], v[206:209], v[88:91]
	v_mfma_f32_16x16x32_bf16 v[76:79], v[128:131], v[214:217], v[76:79]
	v_mfma_f32_16x16x32_bf16 v[72:75], v[136:139], v[214:217], v[72:75]
	v_mfma_f32_16x16x32_bf16 v[124:127], v[132:135], v[194:197], v[124:127]
	v_mfma_f32_16x16x32_bf16 v[120:123], v[140:143], v[194:197], v[120:123]
	v_mfma_f32_16x16x32_bf16 v[108:111], v[132:135], v[202:205], v[108:111]
	v_mfma_f32_16x16x32_bf16 v[104:107], v[140:143], v[202:205], v[104:107]
	v_mfma_f32_16x16x32_bf16 v[92:95], v[132:135], v[210:213], v[92:95]
	v_mfma_f32_16x16x32_bf16 v[88:91], v[140:143], v[210:213], v[88:91]
	v_mfma_f32_16x16x32_bf16 v[76:79], v[132:135], v[218:221], v[76:79]
	v_mfma_f32_16x16x32_bf16 v[72:75], v[140:143], v[218:221], v[72:75]
	s_setprio 0
	s_setprio 1
	v_mfma_f32_16x16x32_bf16 v[116:119], v[144:147], v[180:183], v[116:119]
	v_mfma_f32_16x16x32_bf16 v[112:115], v[172:175], v[180:183], v[112:115]
	v_mfma_f32_16x16x32_bf16 v[100:103], v[144:147], v[198:201], v[100:103]
	v_mfma_f32_16x16x32_bf16 v[96:99], v[172:175], v[198:201], v[96:99]
	v_mfma_f32_16x16x32_bf16 v[84:87], v[144:147], v[206:209], v[84:87]
	v_mfma_f32_16x16x32_bf16 v[80:83], v[172:175], v[206:209], v[80:83]
	v_mfma_f32_16x16x32_bf16 v[68:71], v[144:147], v[214:217], v[68:71]
	v_mfma_f32_16x16x32_bf16 v[64:67], v[172:175], v[214:217], v[64:67]
	v_mfma_f32_16x16x32_bf16 v[116:119], v[148:151], v[194:197], v[116:119]
	v_mfma_f32_16x16x32_bf16 v[112:115], v[176:179], v[194:197], v[112:115]
	v_mfma_f32_16x16x32_bf16 v[100:103], v[148:151], v[202:205], v[100:103]
	v_mfma_f32_16x16x32_bf16 v[96:99], v[176:179], v[202:205], v[96:99]
	v_mfma_f32_16x16x32_bf16 v[84:87], v[148:151], v[210:213], v[84:87]
	v_mfma_f32_16x16x32_bf16 v[80:83], v[176:179], v[210:213], v[80:83]
	v_mfma_f32_16x16x32_bf16 v[68:71], v[148:151], v[218:221], v[68:71]
	v_mfma_f32_16x16x32_bf16 v[64:67], v[176:179], v[218:221], v[64:67]
	s_setprio 0
	s_barrier
	s_add_i32 s54, s75, s65
	v_lshl_add_u64 v[222:223], s[58:59], 0, v[154:155]
	s_mov_b32 m0, s54
	ds_read_b128 v[180:183], v191 offset:16384
	v_xor_b32_e32 v253, 64, v191
	ds_read_b128 v[194:197], v253 offset:16384
	ds_read_b128 v[198:201], v191 offset:18432
	ds_read_b128 v[202:205], v253 offset:18432
	ds_read_b128 v[206:209], v191 offset:20480
	ds_read_b128 v[210:213], v253 offset:20480
	ds_read_b128 v[214:217], v191 offset:22528
	ds_read_b128 v[218:221], v253 offset:22528
	global_load_lds_dwordx4 v[222:223], off
	s_add_i32 m0, s54, 0x2000
	s_add_u32 s54, s58, 0xb0000
	v_lshl_add_u64 v[224:225], s[58:59], 0, v[162:163]
	s_addc_u32 s55, s59, 0
	s_add_i32 s82, s76, s65
	global_load_lds_dwordx4 v[224:225], off
	v_lshl_add_u64 v[226:227], s[54:55], 0, v[154:155]
	s_mov_b32 m0, s82
	v_lshl_add_u64 v[228:229], s[60:61], 0, v[160:161]
	global_load_lds_dwordx4 v[226:227], off
	v_lshl_add_u64 v[226:227], s[54:55], 0, v[162:163]
	s_add_i32 m0, s82, 0x2000
	s_nop 0
	global_load_lds_dwordx4 v[226:227], off
	v_lshl_add_u64 v[226:227], s[60:61], 0, v[152:153]
	s_mov_b32 m0, s66
	s_nop 0
	global_load_lds_dwordx4 v[226:227], off
	s_mov_b32 m0, s67
	s_nop 0
	global_load_lds_dwordx4 v[228:229], off
	s_waitcnt vmcnt(8)
	s_waitcnt lgkmcnt(0)
	s_barrier
	s_setprio 1
	s_waitcnt lgkmcnt(0)
	v_mfma_f32_16x16x32_bf16 v[60:63], v[128:131], v[180:183], v[60:63]
	v_mfma_f32_16x16x32_bf16 v[56:59], v[136:139], v[180:183], v[56:59]
	v_mfma_f32_16x16x32_bf16 v[44:47], v[128:131], v[198:201], v[44:47]
	v_mfma_f32_16x16x32_bf16 v[40:43], v[136:139], v[198:201], v[40:43]
	v_mfma_f32_16x16x32_bf16 v[28:31], v[128:131], v[206:209], v[28:31]
	v_mfma_f32_16x16x32_bf16 v[24:27], v[136:139], v[206:209], v[24:27]
	v_mfma_f32_16x16x32_bf16 v[12:15], v[128:131], v[214:217], v[12:15]
	v_mfma_f32_16x16x32_bf16 v[8:11], v[136:139], v[214:217], v[8:11]
	v_mfma_f32_16x16x32_bf16 v[60:63], v[132:135], v[194:197], v[60:63]
	v_mfma_f32_16x16x32_bf16 v[56:59], v[140:143], v[194:197], v[56:59]
	v_mfma_f32_16x16x32_bf16 v[44:47], v[132:135], v[202:205], v[44:47]
	v_mfma_f32_16x16x32_bf16 v[40:43], v[140:143], v[202:205], v[40:43]
	v_mfma_f32_16x16x32_bf16 v[28:31], v[132:135], v[210:213], v[28:31]
	v_mfma_f32_16x16x32_bf16 v[24:27], v[140:143], v[210:213], v[24:27]
	v_mfma_f32_16x16x32_bf16 v[12:15], v[132:135], v[218:221], v[12:15]
	v_mfma_f32_16x16x32_bf16 v[8:11], v[140:143], v[218:221], v[8:11]
	s_setprio 0
	s_setprio 1
	v_mfma_f32_16x16x32_bf16 v[52:55], v[144:147], v[180:183], v[52:55]
	v_mfma_f32_16x16x32_bf16 v[48:51], v[172:175], v[180:183], v[48:51]
	v_mfma_f32_16x16x32_bf16 v[36:39], v[144:147], v[198:201], v[36:39]
	v_mfma_f32_16x16x32_bf16 v[32:35], v[172:175], v[198:201], v[32:35]
	v_mfma_f32_16x16x32_bf16 v[20:23], v[144:147], v[206:209], v[20:23]
	v_mfma_f32_16x16x32_bf16 v[16:19], v[172:175], v[206:209], v[16:19]
	v_mfma_f32_16x16x32_bf16 v[4:7], v[144:147], v[214:217], v[4:7]
	v_mfma_f32_16x16x32_bf16 v[0:3], v[172:175], v[214:217], v[0:3]
	v_mfma_f32_16x16x32_bf16 v[52:55], v[148:151], v[194:197], v[52:55]
	v_mfma_f32_16x16x32_bf16 v[48:51], v[176:179], v[194:197], v[48:51]
	v_mfma_f32_16x16x32_bf16 v[36:39], v[148:151], v[202:205], v[36:39]
	v_mfma_f32_16x16x32_bf16 v[32:35], v[176:179], v[202:205], v[32:35]
	v_mfma_f32_16x16x32_bf16 v[20:23], v[148:151], v[210:213], v[20:23]
	v_mfma_f32_16x16x32_bf16 v[16:19], v[176:179], v[210:213], v[16:19]
	v_mfma_f32_16x16x32_bf16 v[4:7], v[148:151], v[218:221], v[4:7]
	v_mfma_f32_16x16x32_bf16 v[0:3], v[176:179], v[218:221], v[0:3]
	s_setprio 0
	s_barrier
	s_add_i32 s82, 0, 0x18000
	s_add_i32 s83, 0, 0x1c000
	v_add_u32_e32 v140, s82, v186
	v_add_u32_e32 v176, s83, v186
	ds_read_b128 v[128:131], v140
	v_xor_b32_e32 v253, 64, v140
	ds_read_b128 v[132:135], v253
	ds_read_b128 v[136:139], v140 offset:2048
	ds_read_b128 v[140:143], v253 offset:2048
	ds_read_b128 v[144:147], v176
	v_xor_b32_e32 v253, 64, v176
	ds_read_b128 v[148:151], v253
	ds_read_b128 v[172:175], v176 offset:2048
	ds_read_b128 v[176:179], v253 offset:2048
	s_add_u32 s54, s60, 0xb0000
	s_addc_u32 s55, s61, 0
	s_mov_b32 m0, s68
	v_lshl_add_u64 v[230:231], s[54:55], 0, v[152:153]
	ds_read_b128 v[180:183], v191 offset:32768
	v_xor_b32_e32 v253, 64, v191
	ds_read_b128 v[194:197], v253 offset:32768
	ds_read_b128 v[198:201], v191 offset:34816
	ds_read_b128 v[202:205], v253 offset:34816
	ds_read_b128 v[206:209], v191 offset:36864
	ds_read_b128 v[210:213], v253 offset:36864
	ds_read_b128 v[214:217], v191 offset:38912
	ds_read_b128 v[218:221], v253 offset:38912
	global_load_lds_dwordx4 v[230:231], off
	v_lshl_add_u64 v[230:231], s[54:55], 0, v[160:161]
	s_mov_b32 m0, s69
	s_nop 0
	global_load_lds_dwordx4 v[230:231], off
	s_waitcnt vmcnt(8)
	s_waitcnt lgkmcnt(0)
	s_barrier
	s_setprio 1
	s_waitcnt lgkmcnt(0)
	v_mfma_f32_16x16x32_bf16 v[124:127], v[128:131], v[180:183], v[124:127]
	v_mfma_f32_16x16x32_bf16 v[120:123], v[136:139], v[180:183], v[120:123]
	v_mfma_f32_16x16x32_bf16 v[108:111], v[128:131], v[198:201], v[108:111]
	v_mfma_f32_16x16x32_bf16 v[104:107], v[136:139], v[198:201], v[104:107]
	v_mfma_f32_16x16x32_bf16 v[92:95], v[128:131], v[206:209], v[92:95]
	v_mfma_f32_16x16x32_bf16 v[88:91], v[136:139], v[206:209], v[88:91]
	v_mfma_f32_16x16x32_bf16 v[76:79], v[128:131], v[214:217], v[76:79]
	v_mfma_f32_16x16x32_bf16 v[72:75], v[136:139], v[214:217], v[72:75]
	v_mfma_f32_16x16x32_bf16 v[124:127], v[132:135], v[194:197], v[124:127]
	v_mfma_f32_16x16x32_bf16 v[120:123], v[140:143], v[194:197], v[120:123]
	v_mfma_f32_16x16x32_bf16 v[108:111], v[132:135], v[202:205], v[108:111]
	v_mfma_f32_16x16x32_bf16 v[104:107], v[140:143], v[202:205], v[104:107]
	v_mfma_f32_16x16x32_bf16 v[92:95], v[132:135], v[210:213], v[92:95]
	v_mfma_f32_16x16x32_bf16 v[88:91], v[140:143], v[210:213], v[88:91]
	v_mfma_f32_16x16x32_bf16 v[76:79], v[132:135], v[218:221], v[76:79]
	v_mfma_f32_16x16x32_bf16 v[72:75], v[140:143], v[218:221], v[72:75]
	s_setprio 0
	s_setprio 1
	v_mfma_f32_16x16x32_bf16 v[116:119], v[144:147], v[180:183], v[116:119]
	v_mfma_f32_16x16x32_bf16 v[112:115], v[172:175], v[180:183], v[112:115]
	v_mfma_f32_16x16x32_bf16 v[100:103], v[144:147], v[198:201], v[100:103]
	v_mfma_f32_16x16x32_bf16 v[96:99], v[172:175], v[198:201], v[96:99]
	v_mfma_f32_16x16x32_bf16 v[84:87], v[144:147], v[206:209], v[84:87]
	v_mfma_f32_16x16x32_bf16 v[80:83], v[172:175], v[206:209], v[80:83]
	v_mfma_f32_16x16x32_bf16 v[68:71], v[144:147], v[214:217], v[68:71]
	v_mfma_f32_16x16x32_bf16 v[64:67], v[172:175], v[214:217], v[64:67]
	v_mfma_f32_16x16x32_bf16 v[116:119], v[148:151], v[194:197], v[116:119]
	v_mfma_f32_16x16x32_bf16 v[112:115], v[176:179], v[194:197], v[112:115]
	v_mfma_f32_16x16x32_bf16 v[100:103], v[148:151], v[202:205], v[100:103]
	v_mfma_f32_16x16x32_bf16 v[96:99], v[176:179], v[202:205], v[96:99]
	v_mfma_f32_16x16x32_bf16 v[84:87], v[148:151], v[210:213], v[84:87]
	v_mfma_f32_16x16x32_bf16 v[80:83], v[176:179], v[210:213], v[80:83]
	v_mfma_f32_16x16x32_bf16 v[68:71], v[148:151], v[218:221], v[68:71]
	v_mfma_f32_16x16x32_bf16 v[64:67], v[176:179], v[218:221], v[64:67]
	s_setprio 0
	s_barrier
	s_add_i32 s54, s82, s65
	v_lshl_add_u64 v[222:223], v[222:223], 0, s[28:29]
	s_mov_b32 m0, s54
	ds_read_b128 v[180:183], v191 offset:49152
	v_xor_b32_e32 v253, 64, v191
	ds_read_b128 v[194:197], v253 offset:49152
	ds_read_b128 v[198:201], v191 offset:51200
	ds_read_b128 v[202:205], v253 offset:51200
	ds_read_b128 v[206:209], v191 offset:53248
	ds_read_b128 v[210:213], v253 offset:53248
	ds_read_b128 v[214:217], v191 offset:55296
	ds_read_b128 v[218:221], v253 offset:55296
	global_load_lds_dwordx4 v[222:223], off
	s_add_i32 m0, s54, 0x2000
	s_add_u32 s54, s58, 0xb0080
	v_lshl_add_u64 v[222:223], v[224:225], 0, s[28:29]
	s_addc_u32 s55, s59, 0
	s_add_i32 s58, s83, s65
	global_load_lds_dwordx4 v[222:223], off
	v_lshl_add_u64 v[222:223], s[54:55], 0, v[154:155]
	s_mov_b32 m0, s58
	s_nop 0
	global_load_lds_dwordx4 v[222:223], off
	v_lshl_add_u64 v[222:223], s[54:55], 0, v[162:163]
	s_add_i32 m0, s58, 0x2000
	s_nop 0
	global_load_lds_dwordx4 v[222:223], off
	v_lshl_add_u64 v[222:223], v[226:227], 0, s[28:29]
	s_mov_b32 m0, s3
	s_nop 0
	global_load_lds_dwordx4 v[222:223], off
	v_lshl_add_u64 v[222:223], v[228:229], 0, s[28:29]
	s_mov_b32 m0, s71
	s_nop 0
	global_load_lds_dwordx4 v[222:223], off
	s_waitcnt vmcnt(8)
	s_waitcnt lgkmcnt(0)
	s_barrier
	s_setprio 1
	s_waitcnt lgkmcnt(0)
	v_mfma_f32_16x16x32_bf16 v[60:63], v[128:131], v[180:183], v[60:63]
	v_mfma_f32_16x16x32_bf16 v[56:59], v[136:139], v[180:183], v[56:59]
	v_mfma_f32_16x16x32_bf16 v[44:47], v[128:131], v[198:201], v[44:47]
	v_mfma_f32_16x16x32_bf16 v[40:43], v[136:139], v[198:201], v[40:43]
	v_mfma_f32_16x16x32_bf16 v[28:31], v[128:131], v[206:209], v[28:31]
	v_mfma_f32_16x16x32_bf16 v[24:27], v[136:139], v[206:209], v[24:27]
	v_mfma_f32_16x16x32_bf16 v[12:15], v[128:131], v[214:217], v[12:15]
	v_mfma_f32_16x16x32_bf16 v[8:11], v[136:139], v[214:217], v[8:11]
	v_mfma_f32_16x16x32_bf16 v[60:63], v[132:135], v[194:197], v[60:63]
	v_mfma_f32_16x16x32_bf16 v[56:59], v[140:143], v[194:197], v[56:59]
	v_mfma_f32_16x16x32_bf16 v[44:47], v[132:135], v[202:205], v[44:47]
	v_mfma_f32_16x16x32_bf16 v[40:43], v[140:143], v[202:205], v[40:43]
	v_mfma_f32_16x16x32_bf16 v[28:31], v[132:135], v[210:213], v[28:31]
	v_mfma_f32_16x16x32_bf16 v[24:27], v[140:143], v[210:213], v[24:27]
	v_mfma_f32_16x16x32_bf16 v[12:15], v[132:135], v[218:221], v[12:15]
	v_mfma_f32_16x16x32_bf16 v[8:11], v[140:143], v[218:221], v[8:11]
	s_setprio 0
	s_setprio 1
	v_mfma_f32_16x16x32_bf16 v[52:55], v[144:147], v[180:183], v[52:55]
	v_mfma_f32_16x16x32_bf16 v[48:51], v[172:175], v[180:183], v[48:51]
	v_mfma_f32_16x16x32_bf16 v[36:39], v[144:147], v[198:201], v[36:39]
	v_mfma_f32_16x16x32_bf16 v[32:35], v[172:175], v[198:201], v[32:35]
	v_mfma_f32_16x16x32_bf16 v[20:23], v[144:147], v[206:209], v[20:23]
	v_mfma_f32_16x16x32_bf16 v[16:19], v[172:175], v[206:209], v[16:19]
	v_mfma_f32_16x16x32_bf16 v[4:7], v[144:147], v[214:217], v[4:7]
	v_mfma_f32_16x16x32_bf16 v[0:3], v[172:175], v[214:217], v[0:3]
	v_mfma_f32_16x16x32_bf16 v[52:55], v[148:151], v[194:197], v[52:55]
	v_mfma_f32_16x16x32_bf16 v[48:51], v[176:179], v[194:197], v[48:51]
	v_mfma_f32_16x16x32_bf16 v[36:39], v[148:151], v[202:205], v[36:39]
	v_mfma_f32_16x16x32_bf16 v[32:35], v[176:179], v[202:205], v[32:35]
	v_mfma_f32_16x16x32_bf16 v[20:23], v[148:151], v[210:213], v[20:23]
	v_mfma_f32_16x16x32_bf16 v[16:19], v[176:179], v[210:213], v[16:19]
	v_mfma_f32_16x16x32_bf16 v[4:7], v[148:151], v[218:221], v[4:7]
	v_mfma_f32_16x16x32_bf16 v[0:3], v[176:179], v[218:221], v[0:3]
	s_setprio 0
	s_barrier
	s_add_i32 s81, s81, 2
	s_add_u32 s79, s79, 0x100
	s_addc_u32 s80, s80, 0
	s_cmp_gt_u32 s81, 41
	s_mov_b64 s[54:55], s[56:57]
	s_cbranch_scc0 .LBB0_610
	s_and_b64 vcc, exec, s[30:31]
	s_cbranch_vccz .LBB0_613
	s_barrier

.LBB0_687:
	s_or_b64 exec, exec, s[10:11]
	s_mov_b64 s[10:11], s[0:1]
	v_mov_b32_e32 v8, v157
	s_waitcnt lgkmcnt(0)
	s_barrier
	s_and_b64 vcc, exec, s[8:9]
	v_readfirstlane_b32 s24, v8
	s_cbranch_vccnz .LBB0_705
	v_lshlrev_b32_e32 v0, 4, v8
	v_add_u32_e32 v1, 0x2000, v0
	v_ashrrev_i32_e32 v2, 31, v1
	v_lshrrev_b32_e32 v2, 22, v2
	v_add_u32_e32 v2, v1, v2
	v_ashrrev_i32_e32 v9, 10, v2
	v_mul_i32_i24_e32 v2, 0x400, v9
	v_sub_u32_e32 v1, v1, v2
	v_lshrrev_b32_e32 v2, 4, v1
	v_bitop3_b32 v1, v2, v1, 32 bitop3:0x6c
	v_ashrrev_i32_e32 v2, 31, v1
	v_lshrrev_b32_e32 v2, 26, v2
	v_add_u32_e32 v2, v1, v2
	v_lshlrev_b32_e32 v3, 3, v9
	v_ashrrev_i32_e32 v10, 6, v2
	v_and_b32_e32 v3, -16, v3
	v_add_u32_e32 v3, v10, v3
	v_and_b32_e32 v4, 3, v10
	s_mov_b32 s12, 0x1fffe0
	v_lshrrev_b32_e32 v5, 2, v3
	v_lshlrev_b32_e32 v6, 1, v3
	v_and_b32_e32 v2, 0xc0, v2
	v_and_or_b32 v4, v3, s12, v4
	v_and_b32_e32 v5, 4, v5
	v_and_b32_e32 v6, 24, v6
	v_sub_u32_e32 v1, v1, v2
	v_mov_b32_e32 v2, 1
	v_or3_b32 v4, v4, v5, v6
	v_lshlrev_b32_e32 v5, 5, v9
	v_ashrrev_i16_sdwa v1, v2, sext(v1) dst_sel:DWORD dst_unused:UNUSED_PAD src0_sel:DWORD src1_sel:BYTE_0
	v_and_b32_e32 v5, 32, v5
	v_bfe_i32 v11, v1, 0, 16
	v_add_lshl_u32 v1, v5, v11, 1
	v_lshl_add_u32 v128, v4, 11, v1
	v_lshrrev_b32_e32 v250, 3, v157
	v_and_b32_e32 v251, 6, v250
	v_and_b32_e32 v252, 7, v157
	v_xor_b32_e32 v251, v251, v252
	v_lshlrev_b32_e32 v251, 4, v251
	v_and_b32_e32 v252, 12, v250
	v_lshlrev_b32_e32 v252, 1, v252
	v_and_b32_e32 v253, 16, v250
	v_lshrrev_b32_e32 v253, 2, v253
	v_or_b32_e32 v252, v252, v253
	v_and_b32_e32 v253, 35, v250
	v_or_b32_e32 v250, v252, v253
	v_mul_u32_u24_e32 v250, 0x800, v250
	v_add_u32_e32 v128, v250, v251
	v_add_u32_e32 v128, 0x20000, v128
	v_lshl_add_u32 v130, v3, 11, v1
	v_lshrrev_b32_e32 v250, 3, v157
	v_and_b32_e32 v251, 6, v250
	v_and_b32_e32 v252, 7, v157
	v_xor_b32_e32 v251, v251, v252
	v_lshlrev_b32_e32 v251, 4, v251
	v_mul_u32_u24_e32 v250, 0x800, v250
	v_add_u32_e32 v130, v250, v251
	v_add_u32_e32 v130, 0x20000, v130
	v_bfe_i32 v1, v8, 27, 1
	v_lshrrev_b32_e32 v1, 22, v1
	v_add_u32_e32 v1, v0, v1
	s_load_dwordx2 s[10:11], s[10:11], 0x80
	v_and_b32_e32 v1, 0xfffffc00, v1
	v_sub_u32_e32 v0, v0, v1
	v_lshrrev_b32_e32 v1, 4, v0
	v_ashrrev_i32_e32 v3, 31, v8
	v_bitop3_b32 v0, v1, v0, 32 bitop3:0x6c
	v_lshrrev_b32_e32 v3, 26, v3
	v_ashrrev_i32_e32 v1, 31, v0
	v_add_u32_e32 v3, v8, v3
	s_waitcnt lgkmcnt(0)
	s_add_u32 s3, s10, 0x6000000
	v_lshrrev_b32_e32 v1, 26, v1
	v_ashrrev_i32_e32 v13, 6, v3
	s_addc_u32 s35, s11, 0
	v_add_u32_e32 v1, v0, v1
	v_lshlrev_b32_e32 v3, 3, v13
	s_add_u32 s52, s10, 0x1a00000
	v_ashrrev_i32_e32 v12, 6, v1
	v_and_b32_e32 v3, -16, v3
	s_addc_u32 s53, s11, 0
	v_add_u32_e32 v3, v12, v3
	v_and_b32_e32 v4, 3, v12
	s_ashr_i32 s55, s2, 31
	v_and_or_b32 v4, v3, s12, v4
	s_lshr_b32 s12, s55, 29
	s_add_i32 s12, s2, s12
	s_ashr_i32 s23, s24, 6
	s_ashr_i32 s13, s12, 3
	s_and_b32 s12, s12, -8
	s_ashr_i32 s25, s24, 8
	s_lshl_b32 s54, s23, 10
	s_sub_i32 s12, s2, s12
	s_cmp_lt_i32 s12, 0
	s_movk_i32 s56, 0x161
	s_cselect_b32 s14, s56, 0x160
	s_mul_i32 s12, s14, s12
	s_add_i32 s12, s12, s13
	s_mul_hi_i32 s13, s12, 0x2e8ba2e9
	s_lshr_b32 s14, s13, 31
	s_ashr_i32 s13, s13, 3
	s_add_i32 s13, s13, s14
	s_lshl_b32 s14, s13, 1
	s_mul_i32 s13, s13, 44
	s_sub_i32 s12, s12, s13
	s_bfe_u32 s13, s12, 0x10007
	s_add_i32 s13, s12, s13
	s_bfe_i32 s15, s13, 0x80000
	s_and_b32 s13, s13, 0xfe
	s_sub_i32 s12, s12, s13
	s_sext_i32_i16 s15, s15
	s_sext_i32_i8 s12, s12
	v_lshrrev_b32_e32 v5, 2, v3
	v_lshlrev_b32_e32 v6, 1, v3
	v_and_b32_e32 v1, 0xc0, v1
	s_lshr_b32 s22, s15, 1
	s_add_i32 s46, s14, s12
	v_and_b32_e32 v5, 4, v5
	v_and_b32_e32 v6, 24, v6
	v_sub_u32_e32 v0, v0, v1
	s_ashr_i32 s47, s46, 31
	s_bfe_i64 s[14:15], s[22:23], 0x100000
	v_or3_b32 v4, v4, v5, v6
	v_lshlrev_b32_e32 v5, 5, v13
	v_ashrrev_i16_sdwa v0, v2, sext(v0) dst_sel:DWORD dst_unused:UNUSED_PAD src0_sel:DWORD src1_sel:BYTE_0
	s_lshl_b64 s[12:13], s[46:47], 19
	s_lshl_b64 s[14:15], s[14:15], 19
	v_and_b32_e32 v5, 32, v5
	v_bfe_i32 v14, v0, 0, 16
	s_add_u32 s48, s52, s14
	v_add_lshl_u32 v0, v5, v14, 1
	s_addc_u32 s49, s53, s15
	s_add_i32 s57, s54, 0
	v_lshl_add_u32 v132, v4, 11, v0
	v_lshrrev_b32_e32 v250, 3, v157
	v_and_b32_e32 v251, 6, v250
	v_and_b32_e32 v252, 7, v157
	v_xor_b32_e32 v251, v251, v252
	v_lshlrev_b32_e32 v251, 4, v251
	v_and_b32_e32 v252, 12, v250
	v_lshlrev_b32_e32 v252, 1, v252
	v_and_b32_e32 v253, 16, v250
	v_lshrrev_b32_e32 v253, 2, v253
	v_or_b32_e32 v252, v252, v253
	v_and_b32_e32 v253, 35, v250
	v_or_b32_e32 v250, v252, v253
	v_mul_u32_u24_e32 v250, 0x800, v250
	v_add_u32_e32 v132, v250, v251
	s_add_i32 m0, s57, 0x10000
	v_lshl_add_u32 v134, v3, 11, v0
	v_lshrrev_b32_e32 v250, 3, v157
	v_and_b32_e32 v251, 6, v250
	v_and_b32_e32 v252, 7, v157
	v_xor_b32_e32 v251, v251, v252
	v_lshlrev_b32_e32 v251, 4, v251
	v_mul_u32_u24_e32 v250, 0x800, v250
	v_add_u32_e32 v134, v250, v251
	global_load_lds_dwordx4 v132, s[48:49]
	s_add_i32 m0, s57, 0x12000
	s_add_u32 s14, s48, 0x40000
	global_load_lds_dwordx4 v128, s[48:49]
	s_addc_u32 s15, s49, 0
	s_add_i32 m0, s57, 0x14000
	v_mov_b32_e32 v133, 0
	global_load_lds_dwordx4 v132, s[14:15]
	s_add_i32 m0, s57, 0x16000
	s_add_u32 s50, s3, s12
	s_addc_u32 s51, s35, s13
	s_add_i32 s58, s57, 0x2000
	global_load_lds_dwordx4 v128, s[14:15]
	s_mov_b32 m0, s57
	s_add_u32 s12, s50, 0x40000
	global_load_lds_dwordx4 v134, s[50:51]
	s_mov_b32 m0, s58
	s_addc_u32 s13, s51, 0
	s_add_i32 s59, s57, 0x4000
	global_load_lds_dwordx4 v130, s[50:51]
	s_mov_b32 m0, s59
	s_add_i32 s60, s57, 0x6000
	global_load_lds_dwordx4 v134, s[12:13]
	s_mov_b32 m0, s60
	v_mov_b32_e32 v129, v133
	global_load_lds_dwordx4 v130, s[12:13]
	v_mov_b32_e32 v135, v133
	v_mov_b32_e32 v131, v133
	s_cmp_eq_u32 s25, 1
	s_mov_b32 s61, 0
	v_lshl_add_u64 v[6:7], s[48:49], 0, v[132:133]
	v_lshl_add_u64 v[4:5], s[48:49], 0, v[128:129]
	v_lshl_add_u64 v[0:1], s[50:51], 0, v[134:135]
	s_cselect_b64 s[12:13], -1, 0
	s_cmp_lg_u32 s25, 1
	v_lshl_add_u64 v[2:3], s[50:51], 0, v[130:131]
	s_cbranch_scc1 .LBB0_690
	s_barrier

.LBB0_763:
	s_and_b64 vcc, exec, s[4:5]
	s_cbranch_vccnz .LBB0_805
	v_ashrrev_i32_e32 v1, 31, v8
	v_lshrrev_b32_e32 v1, 26, v1
	v_add_u32_e32 v1, v8, v1
	v_ashrrev_i32_e32 v9, 6, v1
	v_bfe_i32 v1, v8, 27, 1
	v_lshlrev_b32_e32 v0, 4, v8
	v_lshrrev_b32_e32 v1, 22, v1
	v_add_u32_e32 v1, v0, v1
	v_and_b32_e32 v1, 0xfffffc00, v1
	v_sub_u32_e32 v1, v0, v1
	v_lshrrev_b32_e32 v2, 4, v1
	v_bitop3_b32 v1, v2, v1, 32 bitop3:0x6c
	v_ashrrev_i32_e32 v3, 31, v1
	v_lshrrev_b32_e32 v3, 26, v3
	v_lshlrev_b32_e32 v2, 3, v9
	v_add_u32_e32 v3, v1, v3
	v_and_b32_e32 v2, -16, v2
	v_ashrrev_i32_e32 v10, 6, v3
	v_and_b32_e32 v3, 0xc0, v3
	v_add_u32_e32 v2, v10, v2
	v_lshlrev_b32_e32 v4, 5, v9
	v_sub_u32_e32 v1, v1, v3
	v_mov_b32_e32 v3, 1
	v_and_b32_e32 v11, 32, v4
	v_ashrrev_i16_sdwa v1, v3, sext(v1) dst_sel:DWORD dst_unused:UNUSED_PAD src0_sel:DWORD src1_sel:BYTE_0
	v_lshlrev_b32_e32 v4, 1, v2
	v_lshrrev_b32_e32 v5, 2, v2
	v_and_b32_e32 v6, 3, v10
	s_mov_b32 s12, 0xffffe0
	v_bfe_i32 v12, v1, 0, 16
	v_and_b32_e32 v4, 24, v4
	v_and_b32_e32 v5, 4, v5
	v_and_or_b32 v6, v2, s12, v6
	s_movk_i32 s15, 0xb00
	v_add_u32_e32 v1, v11, v12
	v_or3_b32 v4, v6, v5, v4
	v_mul_lo_u32 v2, v2, s15
	v_add_lshl_u32 v152, v1, v2, 1
	v_lshrrev_b32_e32 v250, 3, v157
	v_and_b32_e32 v251, 6, v250
	v_and_b32_e32 v252, 7, v157
	v_xor_b32_e32 v251, v251, v252
	v_lshlrev_b32_e32 v251, 4, v251
	v_mul_u32_u24_e32 v250, 0x1600, v250
	v_add_u32_e32 v152, v250, v251
	v_mul_u32_u24_e32 v2, 0xb00, v4
	v_add_u32_e32 v0, 0x2000, v0
	v_add_lshl_u32 v154, v2, v1, 1
	v_lshrrev_b32_e32 v250, 3, v157
	v_and_b32_e32 v251, 6, v250
	v_and_b32_e32 v252, 7, v157
	v_xor_b32_e32 v251, v251, v252
	v_lshlrev_b32_e32 v251, 4, v251
	v_and_b32_e32 v252, 12, v250
	v_lshlrev_b32_e32 v252, 1, v252
	v_and_b32_e32 v253, 16, v250
	v_lshrrev_b32_e32 v253, 2, v253
	v_or_b32_e32 v252, v252, v253
	v_and_b32_e32 v253, 35, v250
	v_or_b32_e32 v250, v252, v253
	v_mul_u32_u24_e32 v250, 0x1600, v250
	v_add_u32_e32 v154, v250, v251
	v_ashrrev_i32_e32 v1, 31, v0
	v_lshrrev_b32_e32 v1, 22, v1
	v_add_u32_e32 v1, v0, v1
	v_ashrrev_i32_e32 v13, 10, v1
	v_mul_i32_i24_e32 v1, 0x400, v13
	v_sub_u32_e32 v0, v0, v1
	v_lshrrev_b32_e32 v1, 4, v0
	v_bitop3_b32 v0, v1, v0, 32 bitop3:0x6c
	v_ashrrev_i32_e32 v2, 31, v0
	s_waitcnt lgkmcnt(0)
	s_add_u32 s35, s10, 0xa000000
	v_lshrrev_b32_e32 v2, 26, v2
	s_addc_u32 s62, s11, 0
	v_lshlrev_b32_e32 v1, 3, v13
	v_add_u32_e32 v2, v0, v2
	s_add_u32 s63, s10, 0x3b00000
	v_and_b32_e32 v1, -16, v1
	v_ashrrev_i32_e32 v15, 6, v2
	v_lshlrev_b32_e32 v4, 5, v13
	s_addc_u32 s64, s11, 0
	s_ashr_i32 s3, s14, 6
	v_add_u32_e32 v1, v15, v1
	v_and_b32_e32 v14, 32, v4
	v_and_b32_e32 v2, 0xc0, v2
	v_and_b32_e32 v4, 3, v15
	v_sub_u32_e32 v0, v0, v2
	v_and_or_b32 v4, v1, s12, v4
	s_ashr_i32 s12, s14, 8
	s_lshl_b32 s65, s3, 10
	s_mul_i32 s17, s20, 0x160000
	v_ashrrev_i16_sdwa v0, v3, sext(v0) dst_sel:DWORD dst_unused:UNUSED_PAD src0_sel:DWORD src1_sel:BYTE_0
	v_lshlrev_b32_e32 v2, 1, v1
	v_lshrrev_b32_e32 v3, 2, v1
	s_mul_hi_i32 s16, s20, 0x160000
	s_add_u32 s56, s63, s17
	v_bfe_i32 v16, v0, 0, 16
	v_and_b32_e32 v2, 24, v2
	v_and_b32_e32 v3, 4, v3
	s_addc_u32 s57, s64, s16
	s_add_i32 s66, s65, 0
	v_add_u32_e32 v0, v14, v16
	v_or3_b32 v2, v4, v3, v2
	v_mul_lo_u32 v1, v1, s15
	s_add_i32 m0, s66, 0x10000
	v_add_lshl_u32 v160, v0, v1, 1
	v_lshrrev_b32_e32 v250, 3, v157
	v_and_b32_e32 v251, 6, v250
	v_and_b32_e32 v252, 7, v157
	v_xor_b32_e32 v251, v251, v252
	v_lshlrev_b32_e32 v251, 4, v251
	v_mul_u32_u24_e32 v250, 0x1600, v250
	v_add_u32_e32 v160, v250, v251
	v_add_u32_e32 v160, 0x58000, v160
	v_mul_u32_u24_e32 v1, 0xb00, v2
	global_load_lds_dwordx4 v154, s[56:57]
	s_add_i32 m0, s66, 0x12000
	v_add_lshl_u32 v162, v1, v0, 1
	v_lshrrev_b32_e32 v250, 3, v157
	v_and_b32_e32 v251, 6, v250
	v_and_b32_e32 v252, 7, v157
	v_xor_b32_e32 v251, v251, v252
	v_lshlrev_b32_e32 v251, 4, v251
	v_and_b32_e32 v252, 12, v250
	v_lshlrev_b32_e32 v252, 1, v252
	v_and_b32_e32 v253, 16, v250
	v_lshrrev_b32_e32 v253, 2, v253
	v_or_b32_e32 v252, v252, v253
	v_and_b32_e32 v253, 35, v250
	v_or_b32_e32 v250, v252, v253
	v_mul_u32_u24_e32 v250, 0x1600, v250
	v_add_u32_e32 v162, v250, v251
	v_add_u32_e32 v162, 0x58000, v162
	s_add_u32 s16, s56, 0xb0000
	global_load_lds_dwordx4 v162, s[56:57]
	s_addc_u32 s17, s57, 0
	s_add_i32 m0, s66, 0x14000
	s_mul_i32 s22, s21, 0x160000
	global_load_lds_dwordx4 v154, s[16:17]
	s_add_i32 m0, s66, 0x16000
	s_mul_hi_i32 s13, s21, 0x160000
	s_add_u32 s54, s35, s22
	s_addc_u32 s55, s62, s13
	s_add_i32 s67, s66, 0x2000
	global_load_lds_dwordx4 v162, s[16:17]
	s_mov_b32 m0, s66
	s_add_u32 s16, s54, 0xb0000
	global_load_lds_dwordx4 v152, s[54:55]
	s_mov_b32 m0, s67
	s_addc_u32 s17, s55, 0
	s_add_i32 s68, s66, 0x4000
	global_load_lds_dwordx4 v160, s[54:55]
	s_mov_b32 m0, s68
	s_add_i32 s69, s66, 0x6000
	global_load_lds_dwordx4 v152, s[16:17]
	s_mov_b32 m0, s69
	v_mov_b32_e32 v155, 0
	global_load_lds_dwordx4 v160, s[16:17]
	v_mov_b32_e32 v163, v155
	v_mov_b32_e32 v153, v155
	v_mov_b32_e32 v161, v155
	s_cmp_eq_u32 s12, 1
	s_mov_b32 s70, 0
	v_lshl_add_u64 v[6:7], s[56:57], 0, v[154:155]
	v_lshl_add_u64 v[4:5], s[56:57], 0, v[162:163]
	v_lshl_add_u64 v[0:1], s[54:55], 0, v[152:153]
	s_cselect_b64 s[22:23], -1, 0
	s_cmp_lg_u32 s12, 1
	v_lshl_add_u64 v[2:3], s[54:55], 0, v[160:161]
	s_cbranch_scc1 .LBB0_766
	s_barrier

.LBB0_862:
	v_ashrrev_i32_e32 v1, 31, v8
	v_lshrrev_b32_e32 v1, 26, v1
	v_add_u32_e32 v1, v8, v1
	v_ashrrev_i32_e32 v9, 6, v1
	v_bfe_i32 v1, v8, 27, 1
	v_lshlrev_b32_e32 v0, 4, v8
	v_lshrrev_b32_e32 v1, 22, v1
	v_add_u32_e32 v1, v0, v1
	v_and_b32_e32 v1, 0xfffffc00, v1
	v_sub_u32_e32 v1, v0, v1
	v_lshrrev_b32_e32 v2, 4, v1
	v_bitop3_b32 v1, v2, v1, 32 bitop3:0x6c
	v_ashrrev_i32_e32 v3, 31, v1
	v_lshrrev_b32_e32 v3, 26, v3
	v_add_u32_e32 v3, v1, v3
	v_lshlrev_b32_e32 v2, 3, v9
	v_ashrrev_i32_e32 v10, 6, v3
	v_and_b32_e32 v3, 0xc0, v3
	v_and_b32_e32 v2, -16, v2
	v_sub_u32_e32 v1, v1, v3
	v_mov_b32_e32 v3, 1
	v_add_u32_e32 v2, v10, v2
	v_ashrrev_i16_sdwa v1, v3, sext(v1) dst_sel:DWORD dst_unused:UNUSED_PAD src0_sel:DWORD src1_sel:BYTE_0
	v_lshlrev_b32_e32 v4, 5, v9
	v_bfe_i32 v11, v1, 0, 16
	v_lshlrev_b32_e32 v1, 1, v2
	v_lshrrev_b32_e32 v5, 2, v2
	v_and_b32_e32 v6, 3, v10
	s_mov_b32 s13, 0x1fffe0
	v_and_b32_e32 v4, 32, v4
	v_and_b32_e32 v1, 24, v1
	v_and_b32_e32 v5, 4, v5
	v_and_or_b32 v6, v2, s13, v6
	v_or3_b32 v1, v6, v5, v1
	v_add_lshl_u32 v4, v4, v11, 1
	v_add_u32_e32 v0, 0x2000, v0
	v_lshl_add_u32 v130, v1, 11, v4
	v_lshrrev_b32_e32 v250, 3, v157
	v_and_b32_e32 v251, 6, v250
	v_and_b32_e32 v252, 7, v157
	v_xor_b32_e32 v251, v251, v252
	v_lshlrev_b32_e32 v251, 4, v251
	v_and_b32_e32 v252, 12, v250
	v_lshlrev_b32_e32 v252, 1, v252
	v_and_b32_e32 v253, 16, v250
	v_lshrrev_b32_e32 v253, 2, v253
	v_or_b32_e32 v252, v252, v253
	v_and_b32_e32 v253, 35, v250
	v_or_b32_e32 v250, v252, v253
	v_mul_u32_u24_e32 v250, 0x800, v250
	v_add_u32_e32 v130, v250, v251
	v_ashrrev_i32_e32 v1, 31, v0
	v_lshrrev_b32_e32 v1, 22, v1
	v_add_u32_e32 v1, v0, v1
	v_ashrrev_i32_e32 v12, 10, v1
	v_mul_i32_i24_e32 v1, 0x400, v12
	v_sub_u32_e32 v0, v0, v1
	v_lshrrev_b32_e32 v1, 4, v0
	v_bitop3_b32 v0, v1, v0, 32 bitop3:0x6c
	v_lshl_add_u32 v128, v2, 11, v4
	v_lshrrev_b32_e32 v250, 3, v157
	v_and_b32_e32 v251, 6, v250
	v_and_b32_e32 v252, 7, v157
	v_xor_b32_e32 v251, v251, v252
	v_lshlrev_b32_e32 v251, 4, v251
	v_mul_u32_u24_e32 v250, 0x800, v250
	v_add_u32_e32 v128, v250, v251
	v_ashrrev_i32_e32 v2, 31, v0
	s_ashr_i32 s12, s15, 3
	v_lshrrev_b32_e32 v2, 26, v2
	s_waitcnt lgkmcnt(0)
	s_add_u32 s35, s10, 0x6000000
	v_add_u32_e32 v2, v0, v2
	s_addc_u32 s60, s11, 0
	v_lshlrev_b32_e32 v1, 3, v12
	v_ashrrev_i32_e32 v13, 6, v2
	v_and_b32_e32 v2, 0xc0, v2
	s_add_u32 s61, s10, 0x5200000
	v_and_b32_e32 v1, -16, v1
	v_sub_u32_e32 v0, v0, v2
	s_addc_u32 s62, s11, 0
	v_add_u32_e32 v1, v13, v1
	v_ashrrev_i16_sdwa v0, v3, sext(v0) dst_sel:DWORD dst_unused:UNUSED_PAD src0_sel:DWORD src1_sel:BYTE_0
	v_and_b32_e32 v3, 3, v13
	s_add_i32 s12, s14, s12
	v_and_or_b32 v3, v1, s13, v3
	s_ashr_i32 s13, s12, 31
	s_lshr_b32 s13, s13, 29
	s_add_i32 s13, s12, s13
	s_ashr_i32 s14, s13, 3
	s_and_b32 s13, s13, -8
	s_sub_i32 s12, s12, s13
	s_bfe_u32 s13, s12, 0x10007
	s_add_i32 s13, s12, s13
	s_bfe_i32 s15, s13, 0x80000
	s_and_b32 s13, s13, 0xfe
	s_sub_i32 s12, s12, s13
	s_lshl_b32 s14, s14, 1
	s_sext_i32_i16 s15, s15
	s_sext_i32_i8 s12, s12
	s_ashr_i32 s25, s26, 6
	s_lshr_b32 s24, s15, 1
	s_add_i32 s54, s14, s12
	s_ashr_i32 s55, s54, 31
	s_bfe_i64 s[14:15], s[24:25], 0x100000
	s_ashr_i32 s27, s26, 8
	s_lshl_b32 s63, s25, 10
	s_lshl_b64 s[12:13], s[54:55], 19
	s_lshl_b64 s[14:15], s[14:15], 19
	s_add_u32 s56, s61, s14
	v_lshlrev_b32_e32 v4, 5, v12
	v_bfe_i32 v14, v0, 0, 16
	v_lshlrev_b32_e32 v0, 1, v1
	v_lshrrev_b32_e32 v2, 2, v1
	s_addc_u32 s57, s62, s15
	s_add_i32 s64, s63, 0
	v_and_b32_e32 v4, 32, v4
	v_and_b32_e32 v0, 24, v0
	v_and_b32_e32 v2, 4, v2
	s_add_i32 m0, s64, 0x10000
	v_or3_b32 v0, v3, v2, v0
	v_add_lshl_u32 v2, v4, v14, 1
	global_load_lds_dwordx4 v130, s[56:57]
	s_add_i32 m0, s64, 0x12000
	v_lshl_add_u32 v134, v0, 11, v2
	v_lshrrev_b32_e32 v250, 3, v157
	v_and_b32_e32 v251, 6, v250
	v_and_b32_e32 v252, 7, v157
	v_xor_b32_e32 v251, v251, v252
	v_lshlrev_b32_e32 v251, 4, v251
	v_and_b32_e32 v252, 12, v250
	v_lshlrev_b32_e32 v252, 1, v252
	v_and_b32_e32 v253, 16, v250
	v_lshrrev_b32_e32 v253, 2, v253
	v_or_b32_e32 v252, v252, v253
	v_and_b32_e32 v253, 35, v250
	v_or_b32_e32 v250, v252, v253
	v_mul_u32_u24_e32 v250, 0x800, v250
	v_add_u32_e32 v134, v250, v251
	v_add_u32_e32 v134, 0x20000, v134
	s_add_u32 s14, s56, 0x40000
	global_load_lds_dwordx4 v134, s[56:57]
	s_addc_u32 s15, s57, 0
	s_add_i32 m0, s64, 0x14000
	v_lshl_add_u32 v132, v1, 11, v2
	v_lshrrev_b32_e32 v250, 3, v157
	v_and_b32_e32 v251, 6, v250
	v_and_b32_e32 v252, 7, v157
	v_xor_b32_e32 v251, v251, v252
	v_lshlrev_b32_e32 v251, 4, v251
	v_mul_u32_u24_e32 v250, 0x800, v250
	v_add_u32_e32 v132, v250, v251
	v_add_u32_e32 v132, 0x20000, v132
	global_load_lds_dwordx4 v130, s[14:15]
	s_add_i32 m0, s64, 0x16000
	s_add_u32 s58, s35, s12
	s_addc_u32 s59, s60, s13
	s_add_i32 s65, s64, 0x2000
	global_load_lds_dwordx4 v134, s[14:15]
	s_mov_b32 m0, s64
	s_add_u32 s12, s58, 0x40000
	global_load_lds_dwordx4 v128, s[58:59]
	s_mov_b32 m0, s65
	s_addc_u32 s13, s59, 0
	s_add_i32 s66, s64, 0x4000
	global_load_lds_dwordx4 v132, s[58:59]
	s_mov_b32 m0, s66
	s_add_i32 s67, s64, 0x6000
	global_load_lds_dwordx4 v128, s[12:13]
	s_mov_b32 m0, s67
	v_mov_b32_e32 v131, 0
	global_load_lds_dwordx4 v132, s[12:13]
	v_mov_b32_e32 v135, v131
	v_mov_b32_e32 v129, v131
	v_mov_b32_e32 v133, v131
	s_cmp_eq_u32 s27, 1
	s_mov_b32 s68, 0
	v_lshl_add_u64 v[6:7], s[56:57], 0, v[130:131]
	v_lshl_add_u64 v[2:3], s[56:57], 0, v[134:135]
	s_mov_b64 s[12:13], 0x40000
	v_lshl_add_u64 v[0:1], s[58:59], 0, v[128:129]
	s_cselect_b64 s[14:15], -1, 0
	s_cmp_lg_u32 s27, 1
	v_lshl_add_u64 v[4:5], s[58:59], 0, v[132:133]
	s_cbranch_scc1 .LBB0_864
	s_barrier
.LBB0_864:
	s_add_u32 s16, s10, 0xa000000
	s_addc_u32 s17, s11, 0
	s_add_u32 s20, s10, 0x100000
	s_addc_u32 s21, s11, 0
	s_lshl_b32 s10, s25, 5
	s_mov_b64 s[22:23], 0x80
	s_and_b32 s29, s10, 0x60
	s_add_i32 m0, s64, 0x18000
	v_lshl_add_u64 v[6:7], v[6:7], 0, s[22:23]
	s_lshl_b32 s28, s27, 13
	s_lshl_b32 s30, s29, 7
	s_waitcnt vmcnt(2)
	s_barrier
	global_load_lds_dwordx4 v[6:7], off
	v_lshl_add_u64 v[2:3], v[2:3], 0, s[22:23]
	s_add_i32 m0, s64, 0x1a000
	s_add_i32 s69, s64, 0x8000
	s_add_i32 s70, s64, 0xa000
	global_load_lds_dwordx4 v[2:3], off
	v_lshl_add_u64 v[0:1], v[0:1], 0, s[22:23]
	s_mov_b32 m0, s69
	s_add_u32 s10, s56, 0x40080
	global_load_lds_dwordx4 v[0:1], off
	v_lshl_add_u64 v[0:1], v[4:5], 0, s[22:23]
	s_mov_b32 m0, s70
	s_addc_u32 s11, s57, 0
	global_load_lds_dwordx4 v[0:1], off
	s_add_i32 m0, s64, 0x1c000
	v_lshl_add_u64 v[0:1], s[10:11], 0, v[130:131]
	global_load_lds_dwordx4 v[0:1], off
	v_lshl_add_u64 v[0:1], s[10:11], 0, v[134:135]
	s_add_i32 m0, s64, 0x1e000
	s_cmp_lt_i32 s25, 4
	global_load_lds_dwordx4 v[0:1], off
	v_lshrrev_b32_e32 v1, 1, v8
	v_and_b32_e32 v1, 24, v1
	v_and_b32_e32 v0, 15, v8
	v_lshlrev_b32_e32 v2, 1, v1
	v_lshl_or_b32 v147, s27, 6, v0
	v_lshl_or_b32 v0, v0, 6, v2
	v_lshlrev_b32_e32 v2, 2, v8
	v_or_b32_e32 v153, s29, v1
	v_lshlrev_b32_e32 v1, 14, v12
	v_and_b32_e32 v2, 32, v2
	v_and_b32_e32 v1, 0xffff8000, v1
	v_bitop3_b32 v3, v0, s28, v2 bitop3:0xde
	v_bitop3_b32 v149, v0, s30, v2 bitop3:0xde
	v_and_b32_e32 v250, 15, v157
	v_bfe_u32 v251, v157, 4, 2
	v_and_b32_e32 v252, 2, v250
	v_xor_b32_e32 v251, v251, v252
	v_and_b32_e32 v252, 4, v250
	v_lshlrev_b32_e32 v252, 4, v252
	v_lshl_or_b32 v251, v251, 4, v252
	v_lshl_or_b32 v250, v250, 7, v251
	v_bfe_u32 v253, v157, 6, 2
	v_lshl_or_b32 v149, v253, 12, v250
	v_lshl_add_u32 v1, v13, 11, v1
	v_and_b32_e32 v2, 1, v12
	v_lshl_or_b32 v1, v2, 6, v1
	v_lshl_add_u32 v136, v14, 1, v1
	v_lshrrev_b32_e32 v250, 3, v157
	v_and_b32_e32 v251, 6, v250
	v_and_b32_e32 v252, 7, v157
	v_xor_b32_e32 v251, v251, v252
	v_lshlrev_b32_e32 v251, 4, v251
	v_mul_u32_u24_e32 v250, 0x800, v250
	v_add_u32_e32 v136, v250, v251
	v_add_u32_e32 v136, 0x20000, v136
	v_lshlrev_b32_e32 v1, 14, v9
	v_and_b32_e32 v1, 0xffff8000, v1
	s_waitcnt vmcnt(6)
	s_movk_i32 s10, 0xffc0
	v_mov_b32_e32 v0, s26
	v_lshl_add_u32 v1, v10, 11, v1
	v_and_b32_e32 v2, 1, v9
	s_sext_i32_i8 s79, s24
	s_cselect_b64 s[24:25], -1, 0
	v_bfi_b32 v151, s10, v0, v8
	s_cmpk_lt_u32 s26, 0x100
	v_lshlrev_b32_e32 v0, 4, v147
	v_lshl_or_b32 v1, v2, 6, v1
	s_cselect_b64 s[26:27], -1, 0
	s_ashr_i32 s71, s42, 31
	s_mov_b32 s72, s42
	v_mov_b32_e32 v137, v131
	v_lshl_add_u32 v138, v11, 1, v1
	v_lshrrev_b32_e32 v250, 3, v157
	v_and_b32_e32 v251, 6, v250
	v_and_b32_e32 v252, 7, v157
	v_xor_b32_e32 v251, v251, v252
	v_lshlrev_b32_e32 v251, 4, v251
	v_mul_u32_u24_e32 v250, 0x800, v250
	v_add_u32_e32 v138, v250, v251
	v_mov_b32_e32 v139, v131
	v_mov_b64_e32 v[140:141], 0x200
	v_mov_b64_e32 v[142:143], 0x1ff
	s_add_i32 s73, 0, 0x10000
	s_add_i32 s74, 0, 0x14000
	v_add_u32_e32 v154, 0, v3
	v_and_b32_e32 v250, 15, v157
	v_bfe_u32 v251, v157, 4, 2
	v_and_b32_e32 v252, 2, v250
	v_xor_b32_e32 v251, v251, v252
	v_and_b32_e32 v252, 4, v250
	v_lshlrev_b32_e32 v252, 4, v252
	v_lshl_or_b32 v251, v251, 4, v252
	v_lshl_or_b32 v250, v250, 7, v251
	v_lshrrev_b32_e32 v253, 8, v157
	v_lshl_or_b32 v154, v253, 13, v250
	v_add_u32_e32 v155, 0, v0
	v_mov_b32_e32 v160, 0x358637bd
	s_mov_b32 s75, 0x40000
	s_mov_b64 s[28:29], 0x48000
	s_mov_b32 s76, 0x48000
	s_mov_b64 s[30:31], 0x50000
	s_mov_b32 s77, 0x50000
	s_mov_b64 s[44:45], 0x58000
	s_mov_b32 s78, 0x58000
	s_barrier
	s_branch .LBB0_867

.LBB0_873:
	s_ashr_i32 s49, s48, 31
	s_lshl_b64 s[50:51], s[48:49], 19
	s_add_u32 s50, s35, s50
	s_addc_u32 s51, s60, s51
	s_and_b64 s[52:53], s[10:11], exec
	s_cselect_b32 s49, s51, s59
	s_cselect_b32 s80, s50, s58
	s_ashr_i32 s47, s46, 31
	s_lshl_b64 s[52:53], s[46:47], 19
	s_add_u32 s52, s61, s52
	s_addc_u32 s53, s62, s53
	s_and_b64 s[82:83], s[10:11], exec
	s_cselect_b32 s81, s53, s57
	s_cselect_b32 s82, s52, s56
	s_lshl_b32 s47, s54, 8
	v_add_u32_e32 v0, s47, v151
	s_add_u32 s83, s56, 0x100
	v_ashrrev_i32_e32 v1, 31, v0
	s_addc_u32 s84, s57, 0
	v_lshl_add_u64 v[144:145], v[0:1], 4, s[20:21]
	s_add_u32 s54, s58, 0x40080
	s_addc_u32 s55, s59, 0
	s_mov_b32 s85, -2
	s_mov_b64 s[56:57], 0
	s_cmp_eq_u32 s68, 1
	s_cbranch_scc1 .Lfa_8
	v_add_u32_e32 v146, s73, v149
	ds_read_b128 v[162:165], v146
	v_xor_b32_e32 v253, 64, v146
	ds_read_b128 v[166:169], v253
	ds_read_b128 v[170:173], v146 offset:2048
	ds_read_b128 v[174:177], v253 offset:2048
	v_add_u32_e32 v146, s74, v149
	ds_read_b128 v[178:181], v146
	v_xor_b32_e32 v253, 64, v146
	ds_read_b128 v[186:189], v253
	ds_read_b128 v[190:193], v146 offset:2048
	ds_read_b128 v[194:197], v253 offset:2048
	s_add_u32 s58, s54, 0xfffc0080
	s_addc_u32 s59, s55, -1
	s_and_b64 s[56:57], s[56:57], exec
	s_cselect_b32 s59, s49, s59
	s_cselect_b32 s58, s80, s58
	s_cselect_b32 s57, s81, s84
	s_cselect_b32 s56, s82, s83
	v_lshl_add_u64 v[182:183], s[54:55], 0, v[138:139]
	s_add_i32 m0, s64, 0xc000
	ds_read_b128 v[198:201], v154
	v_xor_b32_e32 v253, 64, v154
	ds_read_b128 v[202:205], v253
	ds_read_b128 v[206:209], v154 offset:2048
	ds_read_b128 v[210:213], v253 offset:2048
	ds_read_b128 v[214:217], v154 offset:4096
	ds_read_b128 v[218:221], v253 offset:4096
	ds_read_b128 v[222:225], v154 offset:6144
	ds_read_b128 v[226:229], v253 offset:6144
	global_load_lds_dwordx4 v[182:183], off
	v_lshl_add_u64 v[182:183], s[54:55], 0, v[136:137]
	s_add_i32 m0, s64, 0xe000
	s_nop 0
	global_load_lds_dwordx4 v[182:183], off
	s_waitcnt vmcnt(24)
	s_waitcnt lgkmcnt(0)
	s_barrier
	s_setprio 1
	s_waitcnt lgkmcnt(0)
	v_mfma_f32_16x16x32_bf16 v[124:127], v[162:165], v[198:201], 0
	v_mfma_f32_16x16x32_bf16 v[120:123], v[170:173], v[198:201], 0
	v_mfma_f32_16x16x32_bf16 v[112:115], v[162:165], v[206:209], 0
	v_mfma_f32_16x16x32_bf16 v[104:107], v[170:173], v[206:209], 0
	v_mfma_f32_16x16x32_bf16 v[96:99], v[162:165], v[214:217], 0
	v_mfma_f32_16x16x32_bf16 v[88:91], v[170:173], v[214:217], 0
	v_mfma_f32_16x16x32_bf16 v[80:83], v[162:165], v[222:225], 0
	v_mfma_f32_16x16x32_bf16 v[72:75], v[170:173], v[222:225], 0
	v_mfma_f32_16x16x32_bf16 v[124:127], v[166:169], v[202:205], v[124:127]
	v_mfma_f32_16x16x32_bf16 v[120:123], v[174:177], v[202:205], v[120:123]
	v_mfma_f32_16x16x32_bf16 v[112:115], v[166:169], v[210:213], v[112:115]
	v_mfma_f32_16x16x32_bf16 v[104:107], v[174:177], v[210:213], v[104:107]
	v_mfma_f32_16x16x32_bf16 v[96:99], v[166:169], v[218:221], v[96:99]
	v_mfma_f32_16x16x32_bf16 v[88:91], v[174:177], v[218:221], v[88:91]
	v_mfma_f32_16x16x32_bf16 v[80:83], v[166:169], v[226:229], v[80:83]
	v_mfma_f32_16x16x32_bf16 v[72:75], v[174:177], v[226:229], v[72:75]
	s_setprio 0
	s_setprio 1
	v_mfma_f32_16x16x32_bf16 v[116:119], v[178:181], v[198:201], 0
	v_mfma_f32_16x16x32_bf16 v[108:111], v[190:193], v[198:201], 0
	v_mfma_f32_16x16x32_bf16 v[100:103], v[178:181], v[206:209], 0
	v_mfma_f32_16x16x32_bf16 v[92:95], v[190:193], v[206:209], 0
	v_mfma_f32_16x16x32_bf16 v[84:87], v[178:181], v[214:217], 0
	v_mfma_f32_16x16x32_bf16 v[76:79], v[190:193], v[214:217], 0
	v_mfma_f32_16x16x32_bf16 v[68:71], v[178:181], v[222:225], 0
	v_mfma_f32_16x16x32_bf16 v[64:67], v[190:193], v[222:225], 0
	v_mfma_f32_16x16x32_bf16 v[116:119], v[186:189], v[202:205], v[116:119]
	v_mfma_f32_16x16x32_bf16 v[108:111], v[194:197], v[202:205], v[108:111]
	v_mfma_f32_16x16x32_bf16 v[100:103], v[186:189], v[210:213], v[100:103]
	v_mfma_f32_16x16x32_bf16 v[92:95], v[194:197], v[210:213], v[92:95]
	v_mfma_f32_16x16x32_bf16 v[84:87], v[186:189], v[218:221], v[84:87]
	v_mfma_f32_16x16x32_bf16 v[76:79], v[194:197], v[218:221], v[76:79]
	v_mfma_f32_16x16x32_bf16 v[68:71], v[186:189], v[226:229], v[68:71]
	v_mfma_f32_16x16x32_bf16 v[64:67], v[194:197], v[226:229], v[64:67]
	s_setprio 0
	s_barrier
	s_add_i32 s86, s73, s63
	v_lshl_add_u64 v[182:183], s[56:57], 0, v[130:131]
	s_mov_b32 m0, s86
	ds_read_b128 v[198:201], v154 offset:16384
	v_xor_b32_e32 v253, 64, v154
	ds_read_b128 v[202:205], v253 offset:16384
	ds_read_b128 v[206:209], v154 offset:18432
	ds_read_b128 v[210:213], v253 offset:18432
	ds_read_b128 v[214:217], v154 offset:20480
	ds_read_b128 v[218:221], v253 offset:20480
	ds_read_b128 v[222:225], v154 offset:22528
	ds_read_b128 v[226:229], v253 offset:22528
	global_load_lds_dwordx4 v[182:183], off
	s_add_i32 m0, s86, 0x2000
	s_add_u32 s86, s56, 0x40000
	v_lshl_add_u64 v[230:231], s[56:57], 0, v[134:135]
	s_addc_u32 s87, s57, 0
	s_add_i32 s88, s74, s63
	global_load_lds_dwordx4 v[230:231], off
	v_lshl_add_u64 v[232:233], s[86:87], 0, v[130:131]
	s_mov_b32 m0, s88
	v_lshl_add_u64 v[234:235], s[58:59], 0, v[132:133]
	global_load_lds_dwordx4 v[232:233], off
	v_lshl_add_u64 v[232:233], s[86:87], 0, v[134:135]
	s_add_i32 m0, s88, 0x2000
	s_nop 0
	global_load_lds_dwordx4 v[232:233], off
	v_lshl_add_u64 v[232:233], s[58:59], 0, v[128:129]
	s_mov_b32 m0, s64
	s_nop 0
	global_load_lds_dwordx4 v[232:233], off
	s_mov_b32 m0, s65
	s_nop 0
	global_load_lds_dwordx4 v[234:235], off
	s_waitcnt vmcnt(24)
	s_waitcnt lgkmcnt(0)
	s_barrier
	s_setprio 1
	s_waitcnt lgkmcnt(0)
	v_mfma_f32_16x16x32_bf16 v[60:63], v[162:165], v[198:201], 0
	v_mfma_f32_16x16x32_bf16 v[56:59], v[170:173], v[198:201], 0
	v_mfma_f32_16x16x32_bf16 v[48:51], v[162:165], v[206:209], 0
	v_mfma_f32_16x16x32_bf16 v[40:43], v[170:173], v[206:209], 0
	v_mfma_f32_16x16x32_bf16 v[32:35], v[162:165], v[214:217], 0
	v_mfma_f32_16x16x32_bf16 v[24:27], v[170:173], v[214:217], 0
	v_mfma_f32_16x16x32_bf16 v[16:19], v[162:165], v[222:225], 0
	v_mfma_f32_16x16x32_bf16 v[8:11], v[170:173], v[222:225], 0
	v_mfma_f32_16x16x32_bf16 v[60:63], v[166:169], v[202:205], v[60:63]
	v_mfma_f32_16x16x32_bf16 v[56:59], v[174:177], v[202:205], v[56:59]
	v_mfma_f32_16x16x32_bf16 v[48:51], v[166:169], v[210:213], v[48:51]
	v_mfma_f32_16x16x32_bf16 v[40:43], v[174:177], v[210:213], v[40:43]
	v_mfma_f32_16x16x32_bf16 v[32:35], v[166:169], v[218:221], v[32:35]
	v_mfma_f32_16x16x32_bf16 v[24:27], v[174:177], v[218:221], v[24:27]
	v_mfma_f32_16x16x32_bf16 v[16:19], v[166:169], v[226:229], v[16:19]
	v_mfma_f32_16x16x32_bf16 v[8:11], v[174:177], v[226:229], v[8:11]
	s_setprio 0
	s_setprio 1
	v_mfma_f32_16x16x32_bf16 v[52:55], v[178:181], v[198:201], 0
	v_mfma_f32_16x16x32_bf16 v[44:47], v[190:193], v[198:201], 0
	v_mfma_f32_16x16x32_bf16 v[36:39], v[178:181], v[206:209], 0
	v_mfma_f32_16x16x32_bf16 v[28:31], v[190:193], v[206:209], 0
	v_mfma_f32_16x16x32_bf16 v[20:23], v[178:181], v[214:217], 0
	v_mfma_f32_16x16x32_bf16 v[12:15], v[190:193], v[214:217], 0
	v_mfma_f32_16x16x32_bf16 v[4:7], v[178:181], v[222:225], 0
	v_mfma_f32_16x16x32_bf16 v[0:3], v[190:193], v[222:225], 0
	v_mfma_f32_16x16x32_bf16 v[52:55], v[186:189], v[202:205], v[52:55]
	v_mfma_f32_16x16x32_bf16 v[44:47], v[194:197], v[202:205], v[44:47]
	v_mfma_f32_16x16x32_bf16 v[36:39], v[186:189], v[210:213], v[36:39]
	v_mfma_f32_16x16x32_bf16 v[28:31], v[194:197], v[210:213], v[28:31]
	v_mfma_f32_16x16x32_bf16 v[20:23], v[186:189], v[218:221], v[20:23]
	v_mfma_f32_16x16x32_bf16 v[12:15], v[194:197], v[218:221], v[12:15]
	v_mfma_f32_16x16x32_bf16 v[4:7], v[186:189], v[226:229], v[4:7]
	v_mfma_f32_16x16x32_bf16 v[0:3], v[194:197], v[226:229], v[0:3]
	s_setprio 0
	s_barrier
	s_add_i32 s86, 0, 0x18000
	v_add_u32_e32 v146, s86, v149
	s_add_i32 s87, 0, 0x1c000
	ds_read_b128 v[162:165], v146
	v_xor_b32_e32 v253, 64, v146
	ds_read_b128 v[166:169], v253
	ds_read_b128 v[170:173], v146 offset:2048
	ds_read_b128 v[174:177], v253 offset:2048
	v_add_u32_e32 v146, s87, v149
	ds_read_b128 v[178:181], v146
	v_xor_b32_e32 v253, 64, v146
	ds_read_b128 v[186:189], v253
	ds_read_b128 v[190:193], v146 offset:2048
	ds_read_b128 v[194:197], v253 offset:2048
	s_add_u32 s58, s58, 0x40000
	s_addc_u32 s59, s59, 0
	s_mov_b32 m0, s66
	v_lshl_add_u64 v[236:237], s[58:59], 0, v[128:129]
	ds_read_b128 v[198:201], v154 offset:32768
	v_xor_b32_e32 v253, 64, v154
	ds_read_b128 v[202:205], v253 offset:32768
	ds_read_b128 v[206:209], v154 offset:34816
	ds_read_b128 v[210:213], v253 offset:34816
	ds_read_b128 v[214:217], v154 offset:36864
	ds_read_b128 v[218:221], v253 offset:36864
	ds_read_b128 v[222:225], v154 offset:38912
	ds_read_b128 v[226:229], v253 offset:38912
	global_load_lds_dwordx4 v[236:237], off
	v_lshl_add_u64 v[236:237], s[58:59], 0, v[132:133]
	s_mov_b32 m0, s67
	s_nop 0
	global_load_lds_dwordx4 v[236:237], off
	s_waitcnt vmcnt(8)
	s_waitcnt lgkmcnt(0)
	s_barrier
	s_setprio 1
	s_waitcnt lgkmcnt(0)
	v_mfma_f32_16x16x32_bf16 v[124:127], v[162:165], v[198:201], v[124:127]
	v_mfma_f32_16x16x32_bf16 v[120:123], v[170:173], v[198:201], v[120:123]
	v_mfma_f32_16x16x32_bf16 v[112:115], v[162:165], v[206:209], v[112:115]
	v_mfma_f32_16x16x32_bf16 v[104:107], v[170:173], v[206:209], v[104:107]
	v_mfma_f32_16x16x32_bf16 v[96:99], v[162:165], v[214:217], v[96:99]
	v_mfma_f32_16x16x32_bf16 v[88:91], v[170:173], v[214:217], v[88:91]
	v_mfma_f32_16x16x32_bf16 v[80:83], v[162:165], v[222:225], v[80:83]
	v_mfma_f32_16x16x32_bf16 v[72:75], v[170:173], v[222:225], v[72:75]
	v_mfma_f32_16x16x32_bf16 v[124:127], v[166:169], v[202:205], v[124:127]
	v_mfma_f32_16x16x32_bf16 v[120:123], v[174:177], v[202:205], v[120:123]
	v_mfma_f32_16x16x32_bf16 v[112:115], v[166:169], v[210:213], v[112:115]
	v_mfma_f32_16x16x32_bf16 v[104:107], v[174:177], v[210:213], v[104:107]
	v_mfma_f32_16x16x32_bf16 v[96:99], v[166:169], v[218:221], v[96:99]
	v_mfma_f32_16x16x32_bf16 v[88:91], v[174:177], v[218:221], v[88:91]
	v_mfma_f32_16x16x32_bf16 v[80:83], v[166:169], v[226:229], v[80:83]
	v_mfma_f32_16x16x32_bf16 v[72:75], v[174:177], v[226:229], v[72:75]
	s_setprio 0
	s_setprio 1
	v_mfma_f32_16x16x32_bf16 v[116:119], v[178:181], v[198:201], v[116:119]
	v_mfma_f32_16x16x32_bf16 v[108:111], v[190:193], v[198:201], v[108:111]
	v_mfma_f32_16x16x32_bf16 v[100:103], v[178:181], v[206:209], v[100:103]
	v_mfma_f32_16x16x32_bf16 v[92:95], v[190:193], v[206:209], v[92:95]
	v_mfma_f32_16x16x32_bf16 v[84:87], v[178:181], v[214:217], v[84:87]
	v_mfma_f32_16x16x32_bf16 v[76:79], v[190:193], v[214:217], v[76:79]
	v_mfma_f32_16x16x32_bf16 v[68:71], v[178:181], v[222:225], v[68:71]
	v_mfma_f32_16x16x32_bf16 v[64:67], v[190:193], v[222:225], v[64:67]
	v_mfma_f32_16x16x32_bf16 v[116:119], v[186:189], v[202:205], v[116:119]
	v_mfma_f32_16x16x32_bf16 v[108:111], v[194:197], v[202:205], v[108:111]
	v_mfma_f32_16x16x32_bf16 v[100:103], v[186:189], v[210:213], v[100:103]
	v_mfma_f32_16x16x32_bf16 v[92:95], v[194:197], v[210:213], v[92:95]
	v_mfma_f32_16x16x32_bf16 v[84:87], v[186:189], v[218:221], v[84:87]
	v_mfma_f32_16x16x32_bf16 v[76:79], v[194:197], v[218:221], v[76:79]
	v_mfma_f32_16x16x32_bf16 v[68:71], v[186:189], v[226:229], v[68:71]
	v_mfma_f32_16x16x32_bf16 v[64:67], v[194:197], v[226:229], v[64:67]
	s_setprio 0
	s_barrier
	s_add_i32 s58, s86, s63
	v_lshl_add_u64 v[182:183], v[182:183], 0, s[22:23]
	s_mov_b32 m0, s58
	ds_read_b128 v[198:201], v154 offset:49152
	v_xor_b32_e32 v253, 64, v154
	ds_read_b128 v[202:205], v253 offset:49152
	ds_read_b128 v[206:209], v154 offset:51200
	ds_read_b128 v[210:213], v253 offset:51200
	ds_read_b128 v[214:217], v154 offset:53248
	ds_read_b128 v[218:221], v253 offset:53248
	ds_read_b128 v[222:225], v154 offset:55296
	ds_read_b128 v[226:229], v253 offset:55296
	global_load_lds_dwordx4 v[182:183], off
	s_add_i32 m0, s58, 0x2000
	s_add_u32 s56, s56, 0x40080
	v_lshl_add_u64 v[182:183], v[230:231], 0, s[22:23]
	s_addc_u32 s57, s57, 0
	s_add_i32 s58, s87, s63
	global_load_lds_dwordx4 v[182:183], off
	v_lshl_add_u64 v[182:183], s[56:57], 0, v[130:131]
	s_mov_b32 m0, s58
	s_nop 0
	global_load_lds_dwordx4 v[182:183], off
	v_lshl_add_u64 v[182:183], s[56:57], 0, v[134:135]
	s_add_i32 m0, s58, 0x2000
	s_nop 0
	global_load_lds_dwordx4 v[182:183], off
	v_lshl_add_u64 v[182:183], v[232:233], 0, s[22:23]
	s_mov_b32 m0, s69
	s_nop 0
	global_load_lds_dwordx4 v[182:183], off
	v_lshl_add_u64 v[182:183], v[234:235], 0, s[22:23]
	s_mov_b32 m0, s70
	s_nop 0
	global_load_lds_dwordx4 v[182:183], off
	s_waitcnt vmcnt(8)
	s_waitcnt lgkmcnt(0)
	s_barrier
	s_setprio 1
	s_waitcnt lgkmcnt(0)
	v_mfma_f32_16x16x32_bf16 v[60:63], v[162:165], v[198:201], v[60:63]
	v_mfma_f32_16x16x32_bf16 v[56:59], v[170:173], v[198:201], v[56:59]
	v_mfma_f32_16x16x32_bf16 v[48:51], v[162:165], v[206:209], v[48:51]
	v_mfma_f32_16x16x32_bf16 v[40:43], v[170:173], v[206:209], v[40:43]
	v_mfma_f32_16x16x32_bf16 v[32:35], v[162:165], v[214:217], v[32:35]
	v_mfma_f32_16x16x32_bf16 v[24:27], v[170:173], v[214:217], v[24:27]
	v_mfma_f32_16x16x32_bf16 v[16:19], v[162:165], v[222:225], v[16:19]
	v_mfma_f32_16x16x32_bf16 v[8:11], v[170:173], v[222:225], v[8:11]
	v_mfma_f32_16x16x32_bf16 v[60:63], v[166:169], v[202:205], v[60:63]
	v_mfma_f32_16x16x32_bf16 v[56:59], v[174:177], v[202:205], v[56:59]
	v_mfma_f32_16x16x32_bf16 v[48:51], v[166:169], v[210:213], v[48:51]
	v_mfma_f32_16x16x32_bf16 v[40:43], v[174:177], v[210:213], v[40:43]
	v_mfma_f32_16x16x32_bf16 v[32:35], v[166:169], v[218:221], v[32:35]
	v_mfma_f32_16x16x32_bf16 v[24:27], v[174:177], v[218:221], v[24:27]
	v_mfma_f32_16x16x32_bf16 v[16:19], v[166:169], v[226:229], v[16:19]
	v_mfma_f32_16x16x32_bf16 v[8:11], v[174:177], v[226:229], v[8:11]
	s_setprio 0
	s_setprio 1
	v_mfma_f32_16x16x32_bf16 v[52:55], v[178:181], v[198:201], v[52:55]
	v_mfma_f32_16x16x32_bf16 v[44:47], v[190:193], v[198:201], v[44:47]
	v_mfma_f32_16x16x32_bf16 v[36:39], v[178:181], v[206:209], v[36:39]
	v_mfma_f32_16x16x32_bf16 v[28:31], v[190:193], v[206:209], v[28:31]
	v_mfma_f32_16x16x32_bf16 v[20:23], v[178:181], v[214:217], v[20:23]
	v_mfma_f32_16x16x32_bf16 v[12:15], v[190:193], v[214:217], v[12:15]
	v_mfma_f32_16x16x32_bf16 v[4:7], v[178:181], v[222:225], v[4:7]
	v_mfma_f32_16x16x32_bf16 v[0:3], v[190:193], v[222:225], v[0:3]
	v_mfma_f32_16x16x32_bf16 v[52:55], v[186:189], v[202:205], v[52:55]
	v_mfma_f32_16x16x32_bf16 v[44:47], v[194:197], v[202:205], v[44:47]
	v_mfma_f32_16x16x32_bf16 v[36:39], v[186:189], v[210:213], v[36:39]
	v_mfma_f32_16x16x32_bf16 v[28:31], v[194:197], v[210:213], v[28:31]
	v_mfma_f32_16x16x32_bf16 v[20:23], v[186:189], v[218:221], v[20:23]
	v_mfma_f32_16x16x32_bf16 v[12:15], v[194:197], v[218:221], v[12:15]
	v_mfma_f32_16x16x32_bf16 v[4:7], v[186:189], v[226:229], v[4:7]
	v_mfma_f32_16x16x32_bf16 v[0:3], v[194:197], v[226:229], v[0:3]
	s_setprio 0
	s_barrier
	s_add_i32 s85, s85, 2
	s_add_u32 s83, s83, 0x100
	s_addc_u32 s84, s84, 0
	s_add_u32 s54, s54, 0x100
	s_addc_u32 s55, s55, 0
	s_branch .LBB0_875
.Lfa_8:
	v_add_u32_e32 v146, s73, v149
	ds_read_b128 v[162:165], v146
	v_xor_b32_e32 v253, 64, v146
	ds_read_b128 v[166:169], v253
	ds_read_b128 v[170:173], v146 offset:2048
	ds_read_b128 v[174:177], v253 offset:2048
	v_add_u32_e32 v146, s74, v149
	ds_read_b128 v[178:181], v146
	v_xor_b32_e32 v253, 64, v146
	ds_read_b128 v[186:189], v253
	ds_read_b128 v[190:193], v146 offset:2048
	ds_read_b128 v[194:197], v253 offset:2048
	s_add_u32 s58, s54, 0xfffc0080
	s_addc_u32 s59, s55, -1
	s_and_b64 s[56:57], s[56:57], exec
	s_cselect_b32 s59, s49, s59
	s_cselect_b32 s58, s80, s58
	s_cselect_b32 s57, s81, s84
	s_cselect_b32 s56, s82, s83
	v_lshl_add_u64 v[182:183], s[54:55], 0, v[138:139]
	s_add_i32 m0, s64, 0xc000
	ds_read_b128 v[198:201], v154
	v_xor_b32_e32 v253, 64, v154
	ds_read_b128 v[202:205], v253
	ds_read_b128 v[206:209], v154 offset:2048
	ds_read_b128 v[210:213], v253 offset:2048
	ds_read_b128 v[214:217], v154 offset:4096
	ds_read_b128 v[218:221], v253 offset:4096
	ds_read_b128 v[222:225], v154 offset:6144
	ds_read_b128 v[226:229], v253 offset:6144
	global_load_lds_dwordx4 v[182:183], off
	v_lshl_add_u64 v[182:183], s[54:55], 0, v[136:137]
	s_add_i32 m0, s64, 0xe000
	s_nop 0
	global_load_lds_dwordx4 v[182:183], off
	s_waitcnt vmcnt(8)
	s_waitcnt lgkmcnt(0)
	s_barrier
	s_setprio 1
	s_waitcnt lgkmcnt(0)
	v_mfma_f32_16x16x32_bf16 v[124:127], v[162:165], v[198:201], 0
	v_mfma_f32_16x16x32_bf16 v[120:123], v[170:173], v[198:201], 0
	v_mfma_f32_16x16x32_bf16 v[112:115], v[162:165], v[206:209], 0
	v_mfma_f32_16x16x32_bf16 v[104:107], v[170:173], v[206:209], 0
	v_mfma_f32_16x16x32_bf16 v[96:99], v[162:165], v[214:217], 0
	v_mfma_f32_16x16x32_bf16 v[88:91], v[170:173], v[214:217], 0
	v_mfma_f32_16x16x32_bf16 v[80:83], v[162:165], v[222:225], 0
	v_mfma_f32_16x16x32_bf16 v[72:75], v[170:173], v[222:225], 0
	v_mfma_f32_16x16x32_bf16 v[124:127], v[166:169], v[202:205], v[124:127]
	v_mfma_f32_16x16x32_bf16 v[120:123], v[174:177], v[202:205], v[120:123]
	v_mfma_f32_16x16x32_bf16 v[112:115], v[166:169], v[210:213], v[112:115]
	v_mfma_f32_16x16x32_bf16 v[104:107], v[174:177], v[210:213], v[104:107]
	v_mfma_f32_16x16x32_bf16 v[96:99], v[166:169], v[218:221], v[96:99]
	v_mfma_f32_16x16x32_bf16 v[88:91], v[174:177], v[218:221], v[88:91]
	v_mfma_f32_16x16x32_bf16 v[80:83], v[166:169], v[226:229], v[80:83]
	v_mfma_f32_16x16x32_bf16 v[72:75], v[174:177], v[226:229], v[72:75]
	s_setprio 0
	s_setprio 1
	v_mfma_f32_16x16x32_bf16 v[116:119], v[178:181], v[198:201], 0
	v_mfma_f32_16x16x32_bf16 v[108:111], v[190:193], v[198:201], 0
	v_mfma_f32_16x16x32_bf16 v[100:103], v[178:181], v[206:209], 0
	v_mfma_f32_16x16x32_bf16 v[92:95], v[190:193], v[206:209], 0
	v_mfma_f32_16x16x32_bf16 v[84:87], v[178:181], v[214:217], 0
	v_mfma_f32_16x16x32_bf16 v[76:79], v[190:193], v[214:217], 0
	v_mfma_f32_16x16x32_bf16 v[68:71], v[178:181], v[222:225], 0
	v_mfma_f32_16x16x32_bf16 v[64:67], v[190:193], v[222:225], 0
	v_mfma_f32_16x16x32_bf16 v[116:119], v[186:189], v[202:205], v[116:119]
	v_mfma_f32_16x16x32_bf16 v[108:111], v[194:197], v[202:205], v[108:111]
	v_mfma_f32_16x16x32_bf16 v[100:103], v[186:189], v[210:213], v[100:103]
	v_mfma_f32_16x16x32_bf16 v[92:95], v[194:197], v[210:213], v[92:95]
	v_mfma_f32_16x16x32_bf16 v[84:87], v[186:189], v[218:221], v[84:87]
	v_mfma_f32_16x16x32_bf16 v[76:79], v[194:197], v[218:221], v[76:79]
	v_mfma_f32_16x16x32_bf16 v[68:71], v[186:189], v[226:229], v[68:71]
	v_mfma_f32_16x16x32_bf16 v[64:67], v[194:197], v[226:229], v[64:67]
	s_setprio 0
	s_barrier
	s_add_i32 s86, s73, s63
	v_lshl_add_u64 v[182:183], s[56:57], 0, v[130:131]
	s_mov_b32 m0, s86
	ds_read_b128 v[198:201], v154 offset:16384
	v_xor_b32_e32 v253, 64, v154
	ds_read_b128 v[202:205], v253 offset:16384
	ds_read_b128 v[206:209], v154 offset:18432
	ds_read_b128 v[210:213], v253 offset:18432
	ds_read_b128 v[214:217], v154 offset:20480
	ds_read_b128 v[218:221], v253 offset:20480
	ds_read_b128 v[222:225], v154 offset:22528
	ds_read_b128 v[226:229], v253 offset:22528
	global_load_lds_dwordx4 v[182:183], off
	s_add_i32 m0, s86, 0x2000
	s_add_u32 s86, s56, 0x40000
	v_lshl_add_u64 v[230:231], s[56:57], 0, v[134:135]
	s_addc_u32 s87, s57, 0
	s_add_i32 s88, s74, s63
	global_load_lds_dwordx4 v[230:231], off
	v_lshl_add_u64 v[232:233], s[86:87], 0, v[130:131]
	s_mov_b32 m0, s88
	v_lshl_add_u64 v[234:235], s[58:59], 0, v[132:133]
	global_load_lds_dwordx4 v[232:233], off
	v_lshl_add_u64 v[232:233], s[86:87], 0, v[134:135]
	s_add_i32 m0, s88, 0x2000
	s_nop 0
	global_load_lds_dwordx4 v[232:233], off
	v_lshl_add_u64 v[232:233], s[58:59], 0, v[128:129]
	s_mov_b32 m0, s64
	s_nop 0
	global_load_lds_dwordx4 v[232:233], off
	s_mov_b32 m0, s65
	s_nop 0
	global_load_lds_dwordx4 v[234:235], off
	s_waitcnt vmcnt(8)
	s_waitcnt lgkmcnt(0)
	s_barrier
	s_setprio 1
	s_waitcnt lgkmcnt(0)
	v_mfma_f32_16x16x32_bf16 v[60:63], v[162:165], v[198:201], 0
	v_mfma_f32_16x16x32_bf16 v[56:59], v[170:173], v[198:201], 0
	v_mfma_f32_16x16x32_bf16 v[48:51], v[162:165], v[206:209], 0
	v_mfma_f32_16x16x32_bf16 v[40:43], v[170:173], v[206:209], 0
	v_mfma_f32_16x16x32_bf16 v[32:35], v[162:165], v[214:217], 0
	v_mfma_f32_16x16x32_bf16 v[24:27], v[170:173], v[214:217], 0
	v_mfma_f32_16x16x32_bf16 v[16:19], v[162:165], v[222:225], 0
	v_mfma_f32_16x16x32_bf16 v[8:11], v[170:173], v[222:225], 0
	v_mfma_f32_16x16x32_bf16 v[60:63], v[166:169], v[202:205], v[60:63]
	v_mfma_f32_16x16x32_bf16 v[56:59], v[174:177], v[202:205], v[56:59]
	v_mfma_f32_16x16x32_bf16 v[48:51], v[166:169], v[210:213], v[48:51]
	v_mfma_f32_16x16x32_bf16 v[40:43], v[174:177], v[210:213], v[40:43]
	v_mfma_f32_16x16x32_bf16 v[32:35], v[166:169], v[218:221], v[32:35]
	v_mfma_f32_16x16x32_bf16 v[24:27], v[174:177], v[218:221], v[24:27]
	v_mfma_f32_16x16x32_bf16 v[16:19], v[166:169], v[226:229], v[16:19]
	v_mfma_f32_16x16x32_bf16 v[8:11], v[174:177], v[226:229], v[8:11]
	s_setprio 0
	s_setprio 1
	v_mfma_f32_16x16x32_bf16 v[52:55], v[178:181], v[198:201], 0
	v_mfma_f32_16x16x32_bf16 v[44:47], v[190:193], v[198:201], 0
	v_mfma_f32_16x16x32_bf16 v[36:39], v[178:181], v[206:209], 0
	v_mfma_f32_16x16x32_bf16 v[28:31], v[190:193], v[206:209], 0
	v_mfma_f32_16x16x32_bf16 v[20:23], v[178:181], v[214:217], 0
	v_mfma_f32_16x16x32_bf16 v[12:15], v[190:193], v[214:217], 0
	v_mfma_f32_16x16x32_bf16 v[4:7], v[178:181], v[222:225], 0
	v_mfma_f32_16x16x32_bf16 v[0:3], v[190:193], v[222:225], 0
	v_mfma_f32_16x16x32_bf16 v[52:55], v[186:189], v[202:205], v[52:55]
	v_mfma_f32_16x16x32_bf16 v[44:47], v[194:197], v[202:205], v[44:47]
	v_mfma_f32_16x16x32_bf16 v[36:39], v[186:189], v[210:213], v[36:39]
	v_mfma_f32_16x16x32_bf16 v[28:31], v[194:197], v[210:213], v[28:31]
	v_mfma_f32_16x16x32_bf16 v[20:23], v[186:189], v[218:221], v[20:23]
	v_mfma_f32_16x16x32_bf16 v[12:15], v[194:197], v[218:221], v[12:15]
	v_mfma_f32_16x16x32_bf16 v[4:7], v[186:189], v[226:229], v[4:7]
	v_mfma_f32_16x16x32_bf16 v[0:3], v[194:197], v[226:229], v[0:3]
	s_setprio 0
	s_barrier
	s_add_i32 s86, 0, 0x18000
	v_add_u32_e32 v146, s86, v149
	s_add_i32 s87, 0, 0x1c000
	ds_read_b128 v[162:165], v146
	v_xor_b32_e32 v253, 64, v146
	ds_read_b128 v[166:169], v253
	ds_read_b128 v[170:173], v146 offset:2048
	ds_read_b128 v[174:177], v253 offset:2048
	v_add_u32_e32 v146, s87, v149
	ds_read_b128 v[178:181], v146
	v_xor_b32_e32 v253, 64, v146
	ds_read_b128 v[186:189], v253
	ds_read_b128 v[190:193], v146 offset:2048
	ds_read_b128 v[194:197], v253 offset:2048
	s_add_u32 s58, s58, 0x40000
	s_addc_u32 s59, s59, 0
	s_mov_b32 m0, s66
	v_lshl_add_u64 v[236:237], s[58:59], 0, v[128:129]
	ds_read_b128 v[198:201], v154 offset:32768
	v_xor_b32_e32 v253, 64, v154
	ds_read_b128 v[202:205], v253 offset:32768
	ds_read_b128 v[206:209], v154 offset:34816
	ds_read_b128 v[210:213], v253 offset:34816
	ds_read_b128 v[214:217], v154 offset:36864
	ds_read_b128 v[218:221], v253 offset:36864
	ds_read_b128 v[222:225], v154 offset:38912
	ds_read_b128 v[226:229], v253 offset:38912
	global_load_lds_dwordx4 v[236:237], off
	v_lshl_add_u64 v[236:237], s[58:59], 0, v[132:133]
	s_mov_b32 m0, s67
	s_nop 0
	global_load_lds_dwordx4 v[236:237], off
	s_waitcnt vmcnt(8)
	s_waitcnt lgkmcnt(0)
	s_barrier
	s_setprio 1
	s_waitcnt lgkmcnt(0)
	v_mfma_f32_16x16x32_bf16 v[124:127], v[162:165], v[198:201], v[124:127]
	v_mfma_f32_16x16x32_bf16 v[120:123], v[170:173], v[198:201], v[120:123]
	v_mfma_f32_16x16x32_bf16 v[112:115], v[162:165], v[206:209], v[112:115]
	v_mfma_f32_16x16x32_bf16 v[104:107], v[170:173], v[206:209], v[104:107]
	v_mfma_f32_16x16x32_bf16 v[96:99], v[162:165], v[214:217], v[96:99]
	v_mfma_f32_16x16x32_bf16 v[88:91], v[170:173], v[214:217], v[88:91]
	v_mfma_f32_16x16x32_bf16 v[80:83], v[162:165], v[222:225], v[80:83]
	v_mfma_f32_16x16x32_bf16 v[72:75], v[170:173], v[222:225], v[72:75]
	v_mfma_f32_16x16x32_bf16 v[124:127], v[166:169], v[202:205], v[124:127]
	v_mfma_f32_16x16x32_bf16 v[120:123], v[174:177], v[202:205], v[120:123]
	v_mfma_f32_16x16x32_bf16 v[112:115], v[166:169], v[210:213], v[112:115]
	v_mfma_f32_16x16x32_bf16 v[104:107], v[174:177], v[210:213], v[104:107]
	v_mfma_f32_16x16x32_bf16 v[96:99], v[166:169], v[218:221], v[96:99]
	v_mfma_f32_16x16x32_bf16 v[88:91], v[174:177], v[218:221], v[88:91]
	v_mfma_f32_16x16x32_bf16 v[80:83], v[166:169], v[226:229], v[80:83]
	v_mfma_f32_16x16x32_bf16 v[72:75], v[174:177], v[226:229], v[72:75]
	s_setprio 0
	s_setprio 1
	v_mfma_f32_16x16x32_bf16 v[116:119], v[178:181], v[198:201], v[116:119]
	v_mfma_f32_16x16x32_bf16 v[108:111], v[190:193], v[198:201], v[108:111]
	v_mfma_f32_16x16x32_bf16 v[100:103], v[178:181], v[206:209], v[100:103]
	v_mfma_f32_16x16x32_bf16 v[92:95], v[190:193], v[206:209], v[92:95]
	v_mfma_f32_16x16x32_bf16 v[84:87], v[178:181], v[214:217], v[84:87]
	v_mfma_f32_16x16x32_bf16 v[76:79], v[190:193], v[214:217], v[76:79]
	v_mfma_f32_16x16x32_bf16 v[68:71], v[178:181], v[222:225], v[68:71]
	v_mfma_f32_16x16x32_bf16 v[64:67], v[190:193], v[222:225], v[64:67]
	v_mfma_f32_16x16x32_bf16 v[116:119], v[186:189], v[202:205], v[116:119]
	v_mfma_f32_16x16x32_bf16 v[108:111], v[194:197], v[202:205], v[108:111]
	v_mfma_f32_16x16x32_bf16 v[100:103], v[186:189], v[210:213], v[100:103]
	v_mfma_f32_16x16x32_bf16 v[92:95], v[194:197], v[210:213], v[92:95]
	v_mfma_f32_16x16x32_bf16 v[84:87], v[186:189], v[218:221], v[84:87]
	v_mfma_f32_16x16x32_bf16 v[76:79], v[194:197], v[218:221], v[76:79]
	v_mfma_f32_16x16x32_bf16 v[68:71], v[186:189], v[226:229], v[68:71]
	v_mfma_f32_16x16x32_bf16 v[64:67], v[194:197], v[226:229], v[64:67]
	s_setprio 0
	s_barrier
	s_add_i32 s58, s86, s63
	v_lshl_add_u64 v[182:183], v[182:183], 0, s[22:23]
	s_mov_b32 m0, s58
	ds_read_b128 v[198:201], v154 offset:49152
	v_xor_b32_e32 v253, 64, v154
	ds_read_b128 v[202:205], v253 offset:49152
	ds_read_b128 v[206:209], v154 offset:51200
	ds_read_b128 v[210:213], v253 offset:51200
	ds_read_b128 v[214:217], v154 offset:53248
	ds_read_b128 v[218:221], v253 offset:53248
	ds_read_b128 v[222:225], v154 offset:55296
	ds_read_b128 v[226:229], v253 offset:55296
	global_load_lds_dwordx4 v[182:183], off
	s_add_i32 m0, s58, 0x2000
	s_add_u32 s56, s56, 0x40080
	v_lshl_add_u64 v[182:183], v[230:231], 0, s[22:23]
	s_addc_u32 s57, s57, 0
	s_add_i32 s58, s87, s63
	global_load_lds_dwordx4 v[182:183], off
	v_lshl_add_u64 v[182:183], s[56:57], 0, v[130:131]
	s_mov_b32 m0, s58
	s_nop 0
	global_load_lds_dwordx4 v[182:183], off
	v_lshl_add_u64 v[182:183], s[56:57], 0, v[134:135]
	s_add_i32 m0, s58, 0x2000
	s_nop 0
	global_load_lds_dwordx4 v[182:183], off
	v_lshl_add_u64 v[182:183], v[232:233], 0, s[22:23]
	s_mov_b32 m0, s69
	s_nop 0
	global_load_lds_dwordx4 v[182:183], off
	v_lshl_add_u64 v[182:183], v[234:235], 0, s[22:23]
	s_mov_b32 m0, s70
	s_nop 0
	global_load_lds_dwordx4 v[182:183], off
	s_waitcnt vmcnt(8)
	s_waitcnt lgkmcnt(0)
	s_barrier
	s_setprio 1
	s_waitcnt lgkmcnt(0)
	v_mfma_f32_16x16x32_bf16 v[60:63], v[162:165], v[198:201], v[60:63]
	v_mfma_f32_16x16x32_bf16 v[56:59], v[170:173], v[198:201], v[56:59]
	v_mfma_f32_16x16x32_bf16 v[48:51], v[162:165], v[206:209], v[48:51]
	v_mfma_f32_16x16x32_bf16 v[40:43], v[170:173], v[206:209], v[40:43]
	v_mfma_f32_16x16x32_bf16 v[32:35], v[162:165], v[214:217], v[32:35]
	v_mfma_f32_16x16x32_bf16 v[24:27], v[170:173], v[214:217], v[24:27]
	v_mfma_f32_16x16x32_bf16 v[16:19], v[162:165], v[222:225], v[16:19]
	v_mfma_f32_16x16x32_bf16 v[8:11], v[170:173], v[222:225], v[8:11]
	v_mfma_f32_16x16x32_bf16 v[60:63], v[166:169], v[202:205], v[60:63]
	v_mfma_f32_16x16x32_bf16 v[56:59], v[174:177], v[202:205], v[56:59]
	v_mfma_f32_16x16x32_bf16 v[48:51], v[166:169], v[210:213], v[48:51]
	v_mfma_f32_16x16x32_bf16 v[40:43], v[174:177], v[210:213], v[40:43]
	v_mfma_f32_16x16x32_bf16 v[32:35], v[166:169], v[218:221], v[32:35]
	v_mfma_f32_16x16x32_bf16 v[24:27], v[174:177], v[218:221], v[24:27]
	v_mfma_f32_16x16x32_bf16 v[16:19], v[166:169], v[226:229], v[16:19]
	v_mfma_f32_16x16x32_bf16 v[8:11], v[174:177], v[226:229], v[8:11]
	s_setprio 0
	s_setprio 1
	v_mfma_f32_16x16x32_bf16 v[52:55], v[178:181], v[198:201], v[52:55]
	v_mfma_f32_16x16x32_bf16 v[44:47], v[190:193], v[198:201], v[44:47]
	v_mfma_f32_16x16x32_bf16 v[36:39], v[178:181], v[206:209], v[36:39]
	v_mfma_f32_16x16x32_bf16 v[28:31], v[190:193], v[206:209], v[28:31]
	v_mfma_f32_16x16x32_bf16 v[20:23], v[178:181], v[214:217], v[20:23]
	v_mfma_f32_16x16x32_bf16 v[12:15], v[190:193], v[214:217], v[12:15]
	v_mfma_f32_16x16x32_bf16 v[4:7], v[178:181], v[222:225], v[4:7]
	v_mfma_f32_16x16x32_bf16 v[0:3], v[190:193], v[222:225], v[0:3]
	v_mfma_f32_16x16x32_bf16 v[52:55], v[186:189], v[202:205], v[52:55]
	v_mfma_f32_16x16x32_bf16 v[44:47], v[194:197], v[202:205], v[44:47]
	v_mfma_f32_16x16x32_bf16 v[36:39], v[186:189], v[210:213], v[36:39]
	v_mfma_f32_16x16x32_bf16 v[28:31], v[194:197], v[210:213], v[28:31]
	v_mfma_f32_16x16x32_bf16 v[20:23], v[186:189], v[218:221], v[20:23]
	v_mfma_f32_16x16x32_bf16 v[12:15], v[194:197], v[218:221], v[12:15]
	v_mfma_f32_16x16x32_bf16 v[4:7], v[186:189], v[226:229], v[4:7]
	v_mfma_f32_16x16x32_bf16 v[0:3], v[194:197], v[226:229], v[0:3]
	s_setprio 0
	s_barrier
	s_add_i32 s85, s85, 2
	s_add_u32 s83, s83, 0x100
	s_addc_u32 s84, s84, 0
	s_add_u32 s54, s54, 0x100
	s_addc_u32 s55, s55, 0
	s_branch .LBB0_875
.LBB0_874:
	v_add_u32_e32 v146, s73, v149
	ds_read_b128 v[162:165], v146
	v_xor_b32_e32 v253, 64, v146
	ds_read_b128 v[166:169], v253
	ds_read_b128 v[170:173], v146 offset:2048
	ds_read_b128 v[174:177], v253 offset:2048
	v_add_u32_e32 v146, s74, v149
	ds_read_b128 v[178:181], v146
	v_xor_b32_e32 v253, 64, v146
	ds_read_b128 v[186:189], v253
	ds_read_b128 v[190:193], v146 offset:2048
	ds_read_b128 v[194:197], v253 offset:2048
	s_add_u32 s58, s54, 0xfffc0080
	s_addc_u32 s59, s55, -1
	s_and_b64 s[56:57], s[56:57], exec
	s_cselect_b32 s59, s49, s59
	s_cselect_b32 s58, s80, s58
	s_cselect_b32 s57, s81, s84
	s_cselect_b32 s56, s82, s83
	v_lshl_add_u64 v[182:183], s[54:55], 0, v[138:139]
	s_add_i32 m0, s64, 0xc000
	ds_read_b128 v[198:201], v154
	v_xor_b32_e32 v253, 64, v154
	ds_read_b128 v[202:205], v253
	ds_read_b128 v[206:209], v154 offset:2048
	ds_read_b128 v[210:213], v253 offset:2048
	ds_read_b128 v[214:217], v154 offset:4096
	ds_read_b128 v[218:221], v253 offset:4096
	ds_read_b128 v[222:225], v154 offset:6144
	ds_read_b128 v[226:229], v253 offset:6144
	global_load_lds_dwordx4 v[182:183], off
	v_lshl_add_u64 v[182:183], s[54:55], 0, v[136:137]
	s_add_i32 m0, s64, 0xe000
	s_nop 0
	global_load_lds_dwordx4 v[182:183], off
	s_waitcnt vmcnt(8)
	s_waitcnt lgkmcnt(0)
	s_barrier
	s_setprio 1
	s_waitcnt lgkmcnt(0)
	v_mfma_f32_16x16x32_bf16 v[124:127], v[162:165], v[198:201], v[124:127]
	v_mfma_f32_16x16x32_bf16 v[120:123], v[170:173], v[198:201], v[120:123]
	v_mfma_f32_16x16x32_bf16 v[112:115], v[162:165], v[206:209], v[112:115]
	v_mfma_f32_16x16x32_bf16 v[104:107], v[170:173], v[206:209], v[104:107]
	v_mfma_f32_16x16x32_bf16 v[96:99], v[162:165], v[214:217], v[96:99]
	v_mfma_f32_16x16x32_bf16 v[88:91], v[170:173], v[214:217], v[88:91]
	v_mfma_f32_16x16x32_bf16 v[80:83], v[162:165], v[222:225], v[80:83]
	v_mfma_f32_16x16x32_bf16 v[72:75], v[170:173], v[222:225], v[72:75]
	v_mfma_f32_16x16x32_bf16 v[124:127], v[166:169], v[202:205], v[124:127]
	v_mfma_f32_16x16x32_bf16 v[120:123], v[174:177], v[202:205], v[120:123]
	v_mfma_f32_16x16x32_bf16 v[112:115], v[166:169], v[210:213], v[112:115]
	v_mfma_f32_16x16x32_bf16 v[104:107], v[174:177], v[210:213], v[104:107]
	v_mfma_f32_16x16x32_bf16 v[96:99], v[166:169], v[218:221], v[96:99]
	v_mfma_f32_16x16x32_bf16 v[88:91], v[174:177], v[218:221], v[88:91]
	v_mfma_f32_16x16x32_bf16 v[80:83], v[166:169], v[226:229], v[80:83]
	v_mfma_f32_16x16x32_bf16 v[72:75], v[174:177], v[226:229], v[72:75]
	s_setprio 0
	s_setprio 1
	v_mfma_f32_16x16x32_bf16 v[116:119], v[178:181], v[198:201], v[116:119]
	v_mfma_f32_16x16x32_bf16 v[108:111], v[190:193], v[198:201], v[108:111]
	v_mfma_f32_16x16x32_bf16 v[100:103], v[178:181], v[206:209], v[100:103]
	v_mfma_f32_16x16x32_bf16 v[92:95], v[190:193], v[206:209], v[92:95]
	v_mfma_f32_16x16x32_bf16 v[84:87], v[178:181], v[214:217], v[84:87]
	v_mfma_f32_16x16x32_bf16 v[76:79], v[190:193], v[214:217], v[76:79]
	v_mfma_f32_16x16x32_bf16 v[68:71], v[178:181], v[222:225], v[68:71]
	v_mfma_f32_16x16x32_bf16 v[64:67], v[190:193], v[222:225], v[64:67]
	v_mfma_f32_16x16x32_bf16 v[116:119], v[186:189], v[202:205], v[116:119]
	v_mfma_f32_16x16x32_bf16 v[108:111], v[194:197], v[202:205], v[108:111]
	v_mfma_f32_16x16x32_bf16 v[100:103], v[186:189], v[210:213], v[100:103]
	v_mfma_f32_16x16x32_bf16 v[92:95], v[194:197], v[210:213], v[92:95]
	v_mfma_f32_16x16x32_bf16 v[84:87], v[186:189], v[218:221], v[84:87]
	v_mfma_f32_16x16x32_bf16 v[76:79], v[194:197], v[218:221], v[76:79]
	v_mfma_f32_16x16x32_bf16 v[68:71], v[186:189], v[226:229], v[68:71]
	v_mfma_f32_16x16x32_bf16 v[64:67], v[194:197], v[226:229], v[64:67]
	s_setprio 0
	s_barrier
	s_add_i32 s86, s73, s63
	v_lshl_add_u64 v[182:183], s[56:57], 0, v[130:131]
	s_mov_b32 m0, s86
	ds_read_b128 v[198:201], v154 offset:16384
	v_xor_b32_e32 v253, 64, v154
	ds_read_b128 v[202:205], v253 offset:16384
	ds_read_b128 v[206:209], v154 offset:18432
	ds_read_b128 v[210:213], v253 offset:18432
	ds_read_b128 v[214:217], v154 offset:20480
	ds_read_b128 v[218:221], v253 offset:20480
	ds_read_b128 v[222:225], v154 offset:22528
	ds_read_b128 v[226:229], v253 offset:22528
	global_load_lds_dwordx4 v[182:183], off
	s_add_i32 m0, s86, 0x2000
	s_add_u32 s86, s56, 0x40000
	v_lshl_add_u64 v[230:231], s[56:57], 0, v[134:135]
	s_addc_u32 s87, s57, 0
	s_add_i32 s88, s74, s63
	global_load_lds_dwordx4 v[230:231], off
	v_lshl_add_u64 v[232:233], s[86:87], 0, v[130:131]
	s_mov_b32 m0, s88
	v_lshl_add_u64 v[234:235], s[58:59], 0, v[132:133]
	global_load_lds_dwordx4 v[232:233], off
	v_lshl_add_u64 v[232:233], s[86:87], 0, v[134:135]
	s_add_i32 m0, s88, 0x2000
	s_nop 0
	global_load_lds_dwordx4 v[232:233], off
	v_lshl_add_u64 v[232:233], s[58:59], 0, v[128:129]
	s_mov_b32 m0, s64
	s_nop 0
	global_load_lds_dwordx4 v[232:233], off
	s_mov_b32 m0, s65
	s_nop 0
	global_load_lds_dwordx4 v[234:235], off
	s_waitcnt vmcnt(8)
	s_waitcnt lgkmcnt(0)
	s_barrier
	s_setprio 1
	s_waitcnt lgkmcnt(0)
	v_mfma_f32_16x16x32_bf16 v[60:63], v[162:165], v[198:201], v[60:63]
	v_mfma_f32_16x16x32_bf16 v[56:59], v[170:173], v[198:201], v[56:59]
	v_mfma_f32_16x16x32_bf16 v[48:51], v[162:165], v[206:209], v[48:51]
	v_mfma_f32_16x16x32_bf16 v[40:43], v[170:173], v[206:209], v[40:43]
	v_mfma_f32_16x16x32_bf16 v[32:35], v[162:165], v[214:217], v[32:35]
	v_mfma_f32_16x16x32_bf16 v[24:27], v[170:173], v[214:217], v[24:27]
	v_mfma_f32_16x16x32_bf16 v[16:19], v[162:165], v[222:225], v[16:19]
	v_mfma_f32_16x16x32_bf16 v[8:11], v[170:173], v[222:225], v[8:11]
	v_mfma_f32_16x16x32_bf16 v[60:63], v[166:169], v[202:205], v[60:63]
	v_mfma_f32_16x16x32_bf16 v[56:59], v[174:177], v[202:205], v[56:59]
	v_mfma_f32_16x16x32_bf16 v[48:51], v[166:169], v[210:213], v[48:51]
	v_mfma_f32_16x16x32_bf16 v[40:43], v[174:177], v[210:213], v[40:43]
	v_mfma_f32_16x16x32_bf16 v[32:35], v[166:169], v[218:221], v[32:35]
	v_mfma_f32_16x16x32_bf16 v[24:27], v[174:177], v[218:221], v[24:27]
	v_mfma_f32_16x16x32_bf16 v[16:19], v[166:169], v[226:229], v[16:19]
	v_mfma_f32_16x16x32_bf16 v[8:11], v[174:177], v[226:229], v[8:11]
	s_setprio 0
	s_setprio 1
	v_mfma_f32_16x16x32_bf16 v[52:55], v[178:181], v[198:201], v[52:55]
	v_mfma_f32_16x16x32_bf16 v[44:47], v[190:193], v[198:201], v[44:47]
	v_mfma_f32_16x16x32_bf16 v[36:39], v[178:181], v[206:209], v[36:39]
	v_mfma_f32_16x16x32_bf16 v[28:31], v[190:193], v[206:209], v[28:31]
	v_mfma_f32_16x16x32_bf16 v[20:23], v[178:181], v[214:217], v[20:23]
	v_mfma_f32_16x16x32_bf16 v[12:15], v[190:193], v[214:217], v[12:15]
	v_mfma_f32_16x16x32_bf16 v[4:7], v[178:181], v[222:225], v[4:7]
	v_mfma_f32_16x16x32_bf16 v[0:3], v[190:193], v[222:225], v[0:3]
	v_mfma_f32_16x16x32_bf16 v[52:55], v[186:189], v[202:205], v[52:55]
	v_mfma_f32_16x16x32_bf16 v[44:47], v[194:197], v[202:205], v[44:47]
	v_mfma_f32_16x16x32_bf16 v[36:39], v[186:189], v[210:213], v[36:39]
	v_mfma_f32_16x16x32_bf16 v[28:31], v[194:197], v[210:213], v[28:31]
	v_mfma_f32_16x16x32_bf16 v[20:23], v[186:189], v[218:221], v[20:23]
	v_mfma_f32_16x16x32_bf16 v[12:15], v[194:197], v[218:221], v[12:15]
	v_mfma_f32_16x16x32_bf16 v[4:7], v[186:189], v[226:229], v[4:7]
	v_mfma_f32_16x16x32_bf16 v[0:3], v[194:197], v[226:229], v[0:3]
	s_setprio 0
	s_barrier
	s_add_i32 s86, 0, 0x18000
	v_add_u32_e32 v146, s86, v149
	s_add_i32 s87, 0, 0x1c000
	ds_read_b128 v[162:165], v146
	v_xor_b32_e32 v253, 64, v146
	ds_read_b128 v[166:169], v253
	ds_read_b128 v[170:173], v146 offset:2048
	ds_read_b128 v[174:177], v253 offset:2048
	v_add_u32_e32 v146, s87, v149
	ds_read_b128 v[178:181], v146
	v_xor_b32_e32 v253, 64, v146
	ds_read_b128 v[186:189], v253
	ds_read_b128 v[190:193], v146 offset:2048
	ds_read_b128 v[194:197], v253 offset:2048
	s_add_u32 s58, s58, 0x40000
	s_addc_u32 s59, s59, 0
	s_mov_b32 m0, s66
	v_lshl_add_u64 v[236:237], s[58:59], 0, v[128:129]
	ds_read_b128 v[198:201], v154 offset:32768
	v_xor_b32_e32 v253, 64, v154
	ds_read_b128 v[202:205], v253 offset:32768
	ds_read_b128 v[206:209], v154 offset:34816
	ds_read_b128 v[210:213], v253 offset:34816
	ds_read_b128 v[214:217], v154 offset:36864
	ds_read_b128 v[218:221], v253 offset:36864
	ds_read_b128 v[222:225], v154 offset:38912
	ds_read_b128 v[226:229], v253 offset:38912
	global_load_lds_dwordx4 v[236:237], off
	v_lshl_add_u64 v[236:237], s[58:59], 0, v[132:133]
	s_mov_b32 m0, s67
	s_nop 0
	global_load_lds_dwordx4 v[236:237], off
	s_waitcnt vmcnt(8)
	s_waitcnt lgkmcnt(0)
	s_barrier
	s_setprio 1
	s_waitcnt lgkmcnt(0)
	v_mfma_f32_16x16x32_bf16 v[124:127], v[162:165], v[198:201], v[124:127]
	v_mfma_f32_16x16x32_bf16 v[120:123], v[170:173], v[198:201], v[120:123]
	v_mfma_f32_16x16x32_bf16 v[112:115], v[162:165], v[206:209], v[112:115]
	v_mfma_f32_16x16x32_bf16 v[104:107], v[170:173], v[206:209], v[104:107]
	v_mfma_f32_16x16x32_bf16 v[96:99], v[162:165], v[214:217], v[96:99]
	v_mfma_f32_16x16x32_bf16 v[88:91], v[170:173], v[214:217], v[88:91]
	v_mfma_f32_16x16x32_bf16 v[80:83], v[162:165], v[222:225], v[80:83]
	v_mfma_f32_16x16x32_bf16 v[72:75], v[170:173], v[222:225], v[72:75]
	v_mfma_f32_16x16x32_bf16 v[124:127], v[166:169], v[202:205], v[124:127]
	v_mfma_f32_16x16x32_bf16 v[120:123], v[174:177], v[202:205], v[120:123]
	v_mfma_f32_16x16x32_bf16 v[112:115], v[166:169], v[210:213], v[112:115]
	v_mfma_f32_16x16x32_bf16 v[104:107], v[174:177], v[210:213], v[104:107]
	v_mfma_f32_16x16x32_bf16 v[96:99], v[166:169], v[218:221], v[96:99]
	v_mfma_f32_16x16x32_bf16 v[88:91], v[174:177], v[218:221], v[88:91]
	v_mfma_f32_16x16x32_bf16 v[80:83], v[166:169], v[226:229], v[80:83]
	v_mfma_f32_16x16x32_bf16 v[72:75], v[174:177], v[226:229], v[72:75]
	s_setprio 0
	s_setprio 1
	v_mfma_f32_16x16x32_bf16 v[116:119], v[178:181], v[198:201], v[116:119]
	v_mfma_f32_16x16x32_bf16 v[108:111], v[190:193], v[198:201], v[108:111]
	v_mfma_f32_16x16x32_bf16 v[100:103], v[178:181], v[206:209], v[100:103]
	v_mfma_f32_16x16x32_bf16 v[92:95], v[190:193], v[206:209], v[92:95]
	v_mfma_f32_16x16x32_bf16 v[84:87], v[178:181], v[214:217], v[84:87]
	v_mfma_f32_16x16x32_bf16 v[76:79], v[190:193], v[214:217], v[76:79]
	v_mfma_f32_16x16x32_bf16 v[68:71], v[178:181], v[222:225], v[68:71]
	v_mfma_f32_16x16x32_bf16 v[64:67], v[190:193], v[222:225], v[64:67]
	v_mfma_f32_16x16x32_bf16 v[116:119], v[186:189], v[202:205], v[116:119]
	v_mfma_f32_16x16x32_bf16 v[108:111], v[194:197], v[202:205], v[108:111]
	v_mfma_f32_16x16x32_bf16 v[100:103], v[186:189], v[210:213], v[100:103]
	v_mfma_f32_16x16x32_bf16 v[92:95], v[194:197], v[210:213], v[92:95]
	v_mfma_f32_16x16x32_bf16 v[84:87], v[186:189], v[218:221], v[84:87]
	v_mfma_f32_16x16x32_bf16 v[76:79], v[194:197], v[218:221], v[76:79]
	v_mfma_f32_16x16x32_bf16 v[68:71], v[186:189], v[226:229], v[68:71]
	v_mfma_f32_16x16x32_bf16 v[64:67], v[194:197], v[226:229], v[64:67]
	s_setprio 0
	s_barrier
	s_add_i32 s58, s86, s63
	v_lshl_add_u64 v[182:183], v[182:183], 0, s[22:23]
	s_mov_b32 m0, s58
	ds_read_b128 v[198:201], v154 offset:49152
	v_xor_b32_e32 v253, 64, v154
	ds_read_b128 v[202:205], v253 offset:49152
	ds_read_b128 v[206:209], v154 offset:51200
	ds_read_b128 v[210:213], v253 offset:51200
	ds_read_b128 v[214:217], v154 offset:53248
	ds_read_b128 v[218:221], v253 offset:53248
	ds_read_b128 v[222:225], v154 offset:55296
	ds_read_b128 v[226:229], v253 offset:55296
	global_load_lds_dwordx4 v[182:183], off
	s_add_i32 m0, s58, 0x2000
	s_add_u32 s56, s56, 0x40080
	v_lshl_add_u64 v[182:183], v[230:231], 0, s[22:23]
	s_addc_u32 s57, s57, 0
	s_add_i32 s58, s87, s63
	global_load_lds_dwordx4 v[182:183], off
	v_lshl_add_u64 v[182:183], s[56:57], 0, v[130:131]
	s_mov_b32 m0, s58
	s_nop 0
	global_load_lds_dwordx4 v[182:183], off
	v_lshl_add_u64 v[182:183], s[56:57], 0, v[134:135]
	s_add_i32 m0, s58, 0x2000
	s_nop 0
	global_load_lds_dwordx4 v[182:183], off
	v_lshl_add_u64 v[182:183], v[232:233], 0, s[22:23]
	s_mov_b32 m0, s69
	s_nop 0
	global_load_lds_dwordx4 v[182:183], off
	v_lshl_add_u64 v[182:183], v[234:235], 0, s[22:23]
	s_mov_b32 m0, s70
	s_nop 0
	global_load_lds_dwordx4 v[182:183], off
	s_waitcnt vmcnt(8)
	s_waitcnt lgkmcnt(0)
	s_barrier
	s_setprio 1
	s_waitcnt lgkmcnt(0)
	v_mfma_f32_16x16x32_bf16 v[60:63], v[162:165], v[198:201], v[60:63]
	v_mfma_f32_16x16x32_bf16 v[56:59], v[170:173], v[198:201], v[56:59]
	v_mfma_f32_16x16x32_bf16 v[48:51], v[162:165], v[206:209], v[48:51]
	v_mfma_f32_16x16x32_bf16 v[40:43], v[170:173], v[206:209], v[40:43]
	v_mfma_f32_16x16x32_bf16 v[32:35], v[162:165], v[214:217], v[32:35]
	v_mfma_f32_16x16x32_bf16 v[24:27], v[170:173], v[214:217], v[24:27]
	v_mfma_f32_16x16x32_bf16 v[16:19], v[162:165], v[222:225], v[16:19]
	v_mfma_f32_16x16x32_bf16 v[8:11], v[170:173], v[222:225], v[8:11]
	v_mfma_f32_16x16x32_bf16 v[60:63], v[166:169], v[202:205], v[60:63]
	v_mfma_f32_16x16x32_bf16 v[56:59], v[174:177], v[202:205], v[56:59]
	v_mfma_f32_16x16x32_bf16 v[48:51], v[166:169], v[210:213], v[48:51]
	v_mfma_f32_16x16x32_bf16 v[40:43], v[174:177], v[210:213], v[40:43]
	v_mfma_f32_16x16x32_bf16 v[32:35], v[166:169], v[218:221], v[32:35]
	v_mfma_f32_16x16x32_bf16 v[24:27], v[174:177], v[218:221], v[24:27]
	v_mfma_f32_16x16x32_bf16 v[16:19], v[166:169], v[226:229], v[16:19]
	v_mfma_f32_16x16x32_bf16 v[8:11], v[174:177], v[226:229], v[8:11]
	s_setprio 0
	s_setprio 1
	v_mfma_f32_16x16x32_bf16 v[52:55], v[178:181], v[198:201], v[52:55]
	v_mfma_f32_16x16x32_bf16 v[44:47], v[190:193], v[198:201], v[44:47]
	v_mfma_f32_16x16x32_bf16 v[36:39], v[178:181], v[206:209], v[36:39]
	v_mfma_f32_16x16x32_bf16 v[28:31], v[190:193], v[206:209], v[28:31]
	v_mfma_f32_16x16x32_bf16 v[20:23], v[178:181], v[214:217], v[20:23]
	v_mfma_f32_16x16x32_bf16 v[12:15], v[190:193], v[214:217], v[12:15]
	v_mfma_f32_16x16x32_bf16 v[4:7], v[178:181], v[222:225], v[4:7]
	v_mfma_f32_16x16x32_bf16 v[0:3], v[190:193], v[222:225], v[0:3]
	v_mfma_f32_16x16x32_bf16 v[52:55], v[186:189], v[202:205], v[52:55]
	v_mfma_f32_16x16x32_bf16 v[44:47], v[194:197], v[202:205], v[44:47]
	v_mfma_f32_16x16x32_bf16 v[36:39], v[186:189], v[210:213], v[36:39]
	v_mfma_f32_16x16x32_bf16 v[28:31], v[194:197], v[210:213], v[28:31]
	v_mfma_f32_16x16x32_bf16 v[20:23], v[186:189], v[218:221], v[20:23]
	v_mfma_f32_16x16x32_bf16 v[12:15], v[194:197], v[218:221], v[12:15]
	v_mfma_f32_16x16x32_bf16 v[4:7], v[186:189], v[226:229], v[4:7]
	v_mfma_f32_16x16x32_bf16 v[0:3], v[194:197], v[226:229], v[0:3]
	s_setprio 0
	s_barrier
	s_add_i32 s85, s85, 2
	s_add_u32 s83, s83, 0x100
	s_addc_u32 s84, s84, 0
	s_add_u32 s54, s54, 0x100
	s_addc_u32 s55, s55, 0
	s_cmp_gt_u32 s85, 13
	s_cbranch_scc1 .LBB0_877

.LBB0_998:
	s_and_b64 vcc, exec, s[4:5]
	s_cbranch_vccnz .LBB0_1036
	v_ashrrev_i32_e32 v1, 31, v8
	v_lshrrev_b32_e32 v1, 26, v1
	v_add_u32_e32 v1, v8, v1
	v_ashrrev_i32_e32 v9, 6, v1
	v_bfe_i32 v1, v8, 27, 1
	v_lshlrev_b32_e32 v0, 4, v8
	v_lshrrev_b32_e32 v1, 22, v1
	v_add_u32_e32 v1, v0, v1
	v_and_b32_e32 v1, 0xfffffc00, v1
	v_sub_u32_e32 v1, v0, v1
	v_lshrrev_b32_e32 v2, 4, v1
	v_bitop3_b32 v1, v2, v1, 32 bitop3:0x6c
	v_ashrrev_i32_e32 v3, 31, v1
	v_lshrrev_b32_e32 v3, 26, v3
	v_add_u32_e32 v3, v1, v3
	v_lshlrev_b32_e32 v2, 3, v9
	v_ashrrev_i32_e32 v10, 6, v3
	v_and_b32_e32 v3, 0xc0, v3
	v_and_b32_e32 v2, -16, v2
	v_sub_u32_e32 v1, v1, v3
	v_mov_b32_e32 v3, 1
	v_add_u32_e32 v2, v10, v2
	v_ashrrev_i16_sdwa v1, v3, sext(v1) dst_sel:DWORD dst_unused:UNUSED_PAD src0_sel:DWORD src1_sel:BYTE_0
	v_lshlrev_b32_e32 v4, 5, v9
	v_bfe_i32 v11, v1, 0, 16
	v_lshlrev_b32_e32 v1, 1, v2
	v_lshrrev_b32_e32 v5, 2, v2
	v_and_b32_e32 v6, 3, v10
	s_mov_b32 s10, 0x1fffe0
	v_and_b32_e32 v4, 32, v4
	v_and_b32_e32 v1, 24, v1
	v_and_b32_e32 v5, 4, v5
	v_and_or_b32 v6, v2, s10, v6
	v_or3_b32 v1, v6, v5, v1
	v_add_lshl_u32 v4, v4, v11, 1
	v_add_u32_e32 v0, 0x2000, v0
	v_lshl_add_u32 v154, v1, 11, v4
	v_lshrrev_b32_e32 v250, 3, v157
	v_and_b32_e32 v251, 6, v250
	v_and_b32_e32 v252, 7, v157
	v_xor_b32_e32 v251, v251, v252
	v_lshlrev_b32_e32 v251, 4, v251
	v_and_b32_e32 v252, 12, v250
	v_lshlrev_b32_e32 v252, 1, v252
	v_and_b32_e32 v253, 16, v250
	v_lshrrev_b32_e32 v253, 2, v253
	v_or_b32_e32 v252, v252, v253
	v_and_b32_e32 v253, 35, v250
	v_or_b32_e32 v250, v252, v253
	v_mul_u32_u24_e32 v250, 0x800, v250
	v_add_u32_e32 v154, v250, v251
	v_ashrrev_i32_e32 v1, 31, v0
	v_lshrrev_b32_e32 v1, 22, v1
	v_add_u32_e32 v1, v0, v1
	v_ashrrev_i32_e32 v12, 10, v1
	v_mul_i32_i24_e32 v1, 0x400, v12
	v_sub_u32_e32 v0, v0, v1
	v_lshrrev_b32_e32 v1, 4, v0
	v_bitop3_b32 v0, v1, v0, 32 bitop3:0x6c
	v_lshl_add_u32 v152, v2, 11, v4
	v_lshrrev_b32_e32 v250, 3, v157
	v_and_b32_e32 v251, 6, v250
	v_and_b32_e32 v252, 7, v157
	v_xor_b32_e32 v251, v251, v252
	v_lshlrev_b32_e32 v251, 4, v251
	v_mul_u32_u24_e32 v250, 0x800, v250
	v_add_u32_e32 v152, v250, v251
	v_ashrrev_i32_e32 v2, 31, v0
	v_lshrrev_b32_e32 v2, 26, v2
	s_waitcnt lgkmcnt(0)
	s_add_u32 s33, s6, 0xe000000
	v_add_u32_e32 v2, v0, v2
	s_addc_u32 s35, s7, 0
	v_lshlrev_b32_e32 v1, 3, v12
	v_ashrrev_i32_e32 v13, 6, v2
	v_and_b32_e32 v2, 0xc0, v2
	s_add_u32 s64, s6, 0x5400000
	v_and_b32_e32 v1, -16, v1
	v_sub_u32_e32 v0, v0, v2
	s_addc_u32 s65, s7, 0
	s_ashr_i32 s3, s12, 6
	v_add_u32_e32 v1, v13, v1
	v_ashrrev_i16_sdwa v0, v3, sext(v0) dst_sel:DWORD dst_unused:UNUSED_PAD src0_sel:DWORD src1_sel:BYTE_0
	v_and_b32_e32 v3, 3, v13
	s_ashr_i32 s57, s56, 31
	s_ashr_i32 s15, s14, 31
	v_and_or_b32 v3, v1, s10, v3
	s_ashr_i32 s10, s12, 8
	s_lshl_b32 s66, s3, 10
	s_lshl_b64 s[16:17], s[56:57], 19
	s_lshl_b64 s[20:21], s[14:15], 19
	s_add_u32 s58, s64, s20
	v_lshlrev_b32_e32 v4, 5, v12
	v_bfe_i32 v14, v0, 0, 16
	v_lshlrev_b32_e32 v0, 1, v1
	v_lshrrev_b32_e32 v2, 2, v1
	s_addc_u32 s59, s65, s21
	s_add_i32 s67, s66, 0
	v_and_b32_e32 v4, 32, v4
	v_and_b32_e32 v0, 24, v0
	v_and_b32_e32 v2, 4, v2
	s_add_i32 m0, s67, 0x10000
	v_or3_b32 v0, v3, v2, v0
	v_add_lshl_u32 v2, v4, v14, 1
	global_load_lds_dwordx4 v154, s[58:59]
	s_add_i32 m0, s67, 0x12000
	v_lshl_add_u32 v162, v0, 11, v2
	v_lshrrev_b32_e32 v250, 3, v157
	v_and_b32_e32 v251, 6, v250
	v_and_b32_e32 v252, 7, v157
	v_xor_b32_e32 v251, v251, v252
	v_lshlrev_b32_e32 v251, 4, v251
	v_and_b32_e32 v252, 12, v250
	v_lshlrev_b32_e32 v252, 1, v252
	v_and_b32_e32 v253, 16, v250
	v_lshrrev_b32_e32 v253, 2, v253
	v_or_b32_e32 v252, v252, v253
	v_and_b32_e32 v253, 35, v250
	v_or_b32_e32 v250, v252, v253
	v_mul_u32_u24_e32 v250, 0x800, v250
	v_add_u32_e32 v162, v250, v251
	v_add_u32_e32 v162, 0x20000, v162
	s_add_u32 s20, s58, 0x40000
	global_load_lds_dwordx4 v162, s[58:59]
	s_addc_u32 s21, s59, 0
	s_add_i32 m0, s67, 0x14000
	v_lshl_add_u32 v160, v1, 11, v2
	v_lshrrev_b32_e32 v250, 3, v157
	v_and_b32_e32 v251, 6, v250
	v_and_b32_e32 v252, 7, v157
	v_xor_b32_e32 v251, v251, v252
	v_lshlrev_b32_e32 v251, 4, v251
	v_mul_u32_u24_e32 v250, 0x800, v250
	v_add_u32_e32 v160, v250, v251
	v_add_u32_e32 v160, 0x20000, v160
	global_load_lds_dwordx4 v154, s[20:21]
	s_add_i32 m0, s67, 0x16000
	s_add_u32 s60, s33, s16
	s_addc_u32 s61, s35, s17
	s_add_i32 s68, s67, 0x2000
	global_load_lds_dwordx4 v162, s[20:21]
	s_mov_b32 m0, s67
	s_add_u32 s16, s60, 0x40000
	global_load_lds_dwordx4 v152, s[60:61]
	s_mov_b32 m0, s68
	s_addc_u32 s17, s61, 0
	s_add_i32 s69, s67, 0x4000
	global_load_lds_dwordx4 v160, s[60:61]
	s_mov_b32 m0, s69
	s_add_i32 s70, s67, 0x6000
	global_load_lds_dwordx4 v152, s[16:17]
	s_mov_b32 m0, s70
	v_mov_b32_e32 v155, 0
	global_load_lds_dwordx4 v160, s[16:17]
	v_mov_b32_e32 v163, v155
	v_mov_b32_e32 v153, v155
	v_mov_b32_e32 v161, v155
	s_cmp_eq_u32 s10, 1
	s_mov_b32 s71, 0
	v_lshl_add_u64 v[6:7], s[58:59], 0, v[154:155]
	v_lshl_add_u64 v[2:3], s[58:59], 0, v[162:163]
	s_mov_b64 s[16:17], 0x40000
	v_lshl_add_u64 v[0:1], s[60:61], 0, v[152:153]
	s_cselect_b64 s[20:21], -1, 0
	s_cmp_lg_u32 s10, 1
	v_lshl_add_u64 v[4:5], s[60:61], 0, v[160:161]
	s_cbranch_scc1 .LBB0_1001
	s_barrier
.LBB0_1001:
	s_add_u32 s22, s6, 0x6000000
	s_addc_u32 s23, s7, 0
	s_add_u32 s24, s6, 0x100000
	s_mov_b64 s[26:27], 0x80
	s_addc_u32 s25, s7, 0
	s_and_b32 s13, s3, 3
	s_add_i32 m0, s67, 0x18000
	v_lshl_add_u64 v[6:7], v[6:7], 0, s[26:27]
	s_lshl_b32 s11, s10, 13
	s_lshl_b32 s15, s13, 12
	s_waitcnt vmcnt(2)
	s_barrier
	global_load_lds_dwordx4 v[6:7], off
	v_lshl_add_u64 v[2:3], v[2:3], 0, s[26:27]
	s_add_i32 m0, s67, 0x1a000
	s_add_i32 s3, s67, 0x8000
	s_add_i32 s72, s67, 0xa000
	global_load_lds_dwordx4 v[2:3], off
	v_lshl_add_u64 v[0:1], v[0:1], 0, s[26:27]
	s_mov_b32 m0, s3
	s_add_u32 s6, s58, 0x40080
	global_load_lds_dwordx4 v[0:1], off
	v_lshl_add_u64 v[0:1], v[4:5], 0, s[26:27]
	s_mov_b32 m0, s72
	s_addc_u32 s7, s59, 0
	global_load_lds_dwordx4 v[0:1], off
	s_add_i32 m0, s67, 0x1c000
	v_lshl_add_u64 v[0:1], s[6:7], 0, v[154:155]
	global_load_lds_dwordx4 v[0:1], off
	v_lshl_add_u64 v[0:1], s[6:7], 0, v[162:163]
	s_add_i32 m0, s67, 0x1e000
	s_cmpk_lt_u32 s12, 0x100
	global_load_lds_dwordx4 v[0:1], off
	v_bfe_u32 v0, v8, 4, 2
	v_and_b32_e32 v1, 15, v8
	v_lshlrev_b32_e32 v3, 4, v0
	v_lshl_or_b32 v184, s10, 6, v1
	v_lshl_or_b32 v1, v1, 6, v3
	v_lshlrev_b32_e32 v3, 2, v8
	v_and_b32_e32 v3, 32, v3
	v_bitop3_b32 v4, v1, s11, v3 bitop3:0xde
	v_bitop3_b32 v185, v1, s15, v3 bitop3:0xde
	v_and_b32_e32 v250, 15, v157
	v_bfe_u32 v251, v157, 4, 2
	v_and_b32_e32 v252, 2, v250
	v_xor_b32_e32 v251, v251, v252
	v_and_b32_e32 v252, 4, v250
	v_lshlrev_b32_e32 v252, 4, v252
	v_lshl_or_b32 v251, v251, 4, v252
	v_lshl_or_b32 v250, v250, 7, v251
	v_bfe_u32 v253, v157, 6, 2
	v_lshl_or_b32 v185, v253, 12, v250
	v_lshlrev_b32_e32 v1, 14, v12
	v_lshlrev_b32_e32 v2, 3, v0
	v_and_b32_e32 v1, 0xffff8000, v1
	v_lshl_or_b32 v186, s13, 5, v2
	v_lshl_add_u32 v1, v13, 11, v1
	v_and_b32_e32 v2, 1, v12
	v_lshl_or_b32 v1, v2, 6, v1
	v_lshl_add_u32 v164, v14, 1, v1
	v_lshrrev_b32_e32 v250, 3, v157
	v_and_b32_e32 v251, 6, v250
	v_and_b32_e32 v252, 7, v157
	v_xor_b32_e32 v251, v251, v252
	v_lshlrev_b32_e32 v251, 4, v251
	v_mul_u32_u24_e32 v250, 0x800, v250
	v_add_u32_e32 v164, v250, v251
	v_add_u32_e32 v164, 0x20000, v164
	v_lshlrev_b32_e32 v1, 14, v9
	s_cselect_b64 s[28:29], -1, 0
	s_lshl_b32 s12, s13, 2
	v_and_b32_e32 v1, 0xffff8000, v1
	s_waitcnt vmcnt(6)
	v_cmp_eq_u32_e64 s[6:7], 0, v0
	v_lshlrev_b32_e32 v0, 4, v157
	s_add_i32 s12, s12, 0
	v_lshl_add_u32 v1, v10, 11, v1
	v_and_b32_e32 v2, 1, v9
	s_movk_i32 s10, 0x100
	s_add_i32 s12, s12, 0x20000
	v_lshl_or_b32 v1, v2, 6, v1
	s_add_i32 s76, 0, 0x10000
	s_add_i32 s77, 0, 0x14000
	v_add_u32_e32 v0, 0, v0
	v_cmp_gt_u32_e64 s[10:11], s10, v157
	s_ashr_i32 s73, s42, 31
	s_mov_b32 s74, s42
	s_ashr_i32 s75, s2, 31
	v_lshl_add_u32 v187, v184, 4, s12
	v_mov_b32_e32 v165, v155
	v_lshl_add_u32 v166, v11, 1, v1
	v_lshrrev_b32_e32 v250, 3, v157
	v_and_b32_e32 v251, 6, v250
	v_and_b32_e32 v252, 7, v157
	v_xor_b32_e32 v251, v251, v252
	v_lshlrev_b32_e32 v251, 4, v251
	v_mul_u32_u24_e32 v250, 0x800, v250
	v_add_u32_e32 v166, v250, v251
	v_mov_b32_e32 v167, v155
	v_mov_b64_e32 v[168:169], 0x200
	v_mov_b64_e32 v[170:171], 0x1ff
	v_add_u32_e32 v188, s76, v185
	v_add_u32_e32 v189, s77, v185
	v_add_u32_e32 v190, 0, v4
	v_and_b32_e32 v250, 15, v157
	v_bfe_u32 v251, v157, 4, 2
	v_and_b32_e32 v252, 2, v250
	v_xor_b32_e32 v251, v251, v252
	v_and_b32_e32 v252, 4, v250
	v_lshlrev_b32_e32 v252, 4, v252
	v_lshl_or_b32 v251, v251, 4, v252
	v_lshl_or_b32 v250, v250, 7, v251
	v_lshrrev_b32_e32 v253, 8, v157
	v_lshl_or_b32 v190, v253, 13, v250
	s_mov_b64 s[30:31], 0x48000
	s_mov_b64 s[44:45], 0x50000
	s_mov_b64 s[46:47], 0x58000
	v_add_u32_e32 v191, 0x20000, v0
	s_barrier
	s_branch .LBB0_1004

.LBB0_1010:
	s_ashr_i32 s51, s50, 31
	s_lshl_b64 s[52:53], s[50:51], 19
	s_add_u32 s52, s33, s52
	s_addc_u32 s53, s35, s53
	s_and_b64 s[54:55], s[12:13], exec
	s_cselect_b32 s15, s53, s61
	s_cselect_b32 s51, s52, s60
	s_ashr_i32 s49, s48, 31
	s_lshl_b64 s[54:55], s[48:49], 19
	s_add_u32 s54, s64, s54
	s_addc_u32 s55, s65, s55
	s_and_b64 s[62:63], s[12:13], exec
	s_cselect_b32 s49, s55, s59
	s_cselect_b32 s57, s54, s58
	s_add_u32 s78, s58, 0x100
	s_addc_u32 s79, s59, 0
	s_add_u32 s58, s60, 0x40080
	s_addc_u32 s59, s61, 0
	s_mov_b32 s80, -2
	s_waitcnt lgkmcnt(0)
	s_cmp_eq_u32 s71, 1
	s_cbranch_scc1 .Lfa_9
	ds_read_b128 v[128:131], v188
	v_xor_b32_e32 v253, 64, v188
	ds_read_b128 v[132:135], v253
	ds_read_b128 v[136:139], v188 offset:2048
	ds_read_b128 v[140:143], v253 offset:2048
	ds_read_b128 v[144:147], v189
	v_xor_b32_e32 v253, 64, v189
	ds_read_b128 v[148:151], v253
	ds_read_b128 v[172:175], v189 offset:2048
	ds_read_b128 v[176:179], v253 offset:2048
	s_add_u32 s60, s58, 0xfffc0080
	s_addc_u32 s61, s59, -1
	s_cmp_eq_u32 s80, 12
	s_cselect_b32 s63, s15, s61
	s_cselect_b32 s62, s51, s60
	s_cselect_b32 s61, s49, s79
	s_cselect_b32 s60, s57, s78
	v_lshl_add_u64 v[220:221], s[58:59], 0, v[166:167]
	s_add_i32 m0, s67, 0xc000
	ds_read_b128 v[180:183], v190
	v_xor_b32_e32 v253, 64, v190
	ds_read_b128 v[192:195], v253
	ds_read_b128 v[196:199], v190 offset:2048
	ds_read_b128 v[200:203], v253 offset:2048
	ds_read_b128 v[204:207], v190 offset:4096
	ds_read_b128 v[208:211], v253 offset:4096
	ds_read_b128 v[212:215], v190 offset:6144
	ds_read_b128 v[216:219], v253 offset:6144
	global_load_lds_dwordx4 v[220:221], off
	v_lshl_add_u64 v[220:221], s[58:59], 0, v[164:165]
	s_add_i32 m0, s67, 0xe000
	s_nop 0
	global_load_lds_dwordx4 v[220:221], off
	s_waitcnt vmcnt(24)
	s_waitcnt lgkmcnt(0)
	s_barrier
	s_setprio 1
	s_waitcnt lgkmcnt(0)
	v_mfma_f32_16x16x32_bf16 v[124:127], v[128:131], v[180:183], 0
	v_mfma_f32_16x16x32_bf16 v[120:123], v[136:139], v[180:183], 0
	v_mfma_f32_16x16x32_bf16 v[108:111], v[128:131], v[196:199], 0
	v_mfma_f32_16x16x32_bf16 v[104:107], v[136:139], v[196:199], 0
	v_mfma_f32_16x16x32_bf16 v[92:95], v[128:131], v[204:207], 0
	v_mfma_f32_16x16x32_bf16 v[88:91], v[136:139], v[204:207], 0
	v_mfma_f32_16x16x32_bf16 v[76:79], v[128:131], v[212:215], 0
	v_mfma_f32_16x16x32_bf16 v[72:75], v[136:139], v[212:215], 0
	v_mfma_f32_16x16x32_bf16 v[124:127], v[132:135], v[192:195], v[124:127]
	v_mfma_f32_16x16x32_bf16 v[120:123], v[140:143], v[192:195], v[120:123]
	v_mfma_f32_16x16x32_bf16 v[108:111], v[132:135], v[200:203], v[108:111]
	v_mfma_f32_16x16x32_bf16 v[104:107], v[140:143], v[200:203], v[104:107]
	v_mfma_f32_16x16x32_bf16 v[92:95], v[132:135], v[208:211], v[92:95]
	v_mfma_f32_16x16x32_bf16 v[88:91], v[140:143], v[208:211], v[88:91]
	v_mfma_f32_16x16x32_bf16 v[76:79], v[132:135], v[216:219], v[76:79]
	v_mfma_f32_16x16x32_bf16 v[72:75], v[140:143], v[216:219], v[72:75]
	s_setprio 0
	s_setprio 1
	v_mfma_f32_16x16x32_bf16 v[116:119], v[144:147], v[180:183], 0
	v_mfma_f32_16x16x32_bf16 v[112:115], v[172:175], v[180:183], 0
	v_mfma_f32_16x16x32_bf16 v[100:103], v[144:147], v[196:199], 0
	v_mfma_f32_16x16x32_bf16 v[96:99], v[172:175], v[196:199], 0
	v_mfma_f32_16x16x32_bf16 v[84:87], v[144:147], v[204:207], 0
	v_mfma_f32_16x16x32_bf16 v[80:83], v[172:175], v[204:207], 0
	v_mfma_f32_16x16x32_bf16 v[68:71], v[144:147], v[212:215], 0
	v_mfma_f32_16x16x32_bf16 v[64:67], v[172:175], v[212:215], 0
	v_mfma_f32_16x16x32_bf16 v[116:119], v[148:151], v[192:195], v[116:119]
	v_mfma_f32_16x16x32_bf16 v[112:115], v[176:179], v[192:195], v[112:115]
	v_mfma_f32_16x16x32_bf16 v[100:103], v[148:151], v[200:203], v[100:103]
	v_mfma_f32_16x16x32_bf16 v[96:99], v[176:179], v[200:203], v[96:99]
	v_mfma_f32_16x16x32_bf16 v[84:87], v[148:151], v[208:211], v[84:87]
	v_mfma_f32_16x16x32_bf16 v[80:83], v[176:179], v[208:211], v[80:83]
	v_mfma_f32_16x16x32_bf16 v[68:71], v[148:151], v[216:219], v[68:71]
	v_mfma_f32_16x16x32_bf16 v[64:67], v[176:179], v[216:219], v[64:67]
	s_setprio 0
	s_barrier
	s_add_i32 s81, s76, s66
	v_lshl_add_u64 v[220:221], s[60:61], 0, v[154:155]
	s_mov_b32 m0, s81
	ds_read_b128 v[180:183], v190 offset:16384
	v_xor_b32_e32 v253, 64, v190
	ds_read_b128 v[192:195], v253 offset:16384
	ds_read_b128 v[196:199], v190 offset:18432
	ds_read_b128 v[200:203], v253 offset:18432
	ds_read_b128 v[204:207], v190 offset:20480
	ds_read_b128 v[208:211], v253 offset:20480
	ds_read_b128 v[212:215], v190 offset:22528
	ds_read_b128 v[216:219], v253 offset:22528
	global_load_lds_dwordx4 v[220:221], off
	s_add_i32 m0, s81, 0x2000
	s_add_u32 s82, s60, 0x40000
	v_lshl_add_u64 v[222:223], s[60:61], 0, v[162:163]
	s_addc_u32 s83, s61, 0
	s_add_i32 s81, s77, s66
	global_load_lds_dwordx4 v[222:223], off
	v_lshl_add_u64 v[224:225], s[82:83], 0, v[154:155]
	s_mov_b32 m0, s81
	v_lshl_add_u64 v[226:227], s[62:63], 0, v[160:161]
	global_load_lds_dwordx4 v[224:225], off
	v_lshl_add_u64 v[224:225], s[82:83], 0, v[162:163]
	s_add_i32 m0, s81, 0x2000
	s_nop 0
	global_load_lds_dwordx4 v[224:225], off
	v_lshl_add_u64 v[224:225], s[62:63], 0, v[152:153]
	s_mov_b32 m0, s67
	s_nop 0
	global_load_lds_dwordx4 v[224:225], off
	s_mov_b32 m0, s68
	s_nop 0
	global_load_lds_dwordx4 v[226:227], off
	s_waitcnt vmcnt(24)
	s_waitcnt lgkmcnt(0)
	s_barrier
	s_setprio 1
	s_waitcnt lgkmcnt(0)
	v_mfma_f32_16x16x32_bf16 v[60:63], v[128:131], v[180:183], 0
	v_mfma_f32_16x16x32_bf16 v[56:59], v[136:139], v[180:183], 0
	v_mfma_f32_16x16x32_bf16 v[44:47], v[128:131], v[196:199], 0
	v_mfma_f32_16x16x32_bf16 v[40:43], v[136:139], v[196:199], 0
	v_mfma_f32_16x16x32_bf16 v[28:31], v[128:131], v[204:207], 0
	v_mfma_f32_16x16x32_bf16 v[24:27], v[136:139], v[204:207], 0
	v_mfma_f32_16x16x32_bf16 v[12:15], v[128:131], v[212:215], 0
	v_mfma_f32_16x16x32_bf16 v[8:11], v[136:139], v[212:215], 0
	v_mfma_f32_16x16x32_bf16 v[60:63], v[132:135], v[192:195], v[60:63]
	v_mfma_f32_16x16x32_bf16 v[56:59], v[140:143], v[192:195], v[56:59]
	v_mfma_f32_16x16x32_bf16 v[44:47], v[132:135], v[200:203], v[44:47]
	v_mfma_f32_16x16x32_bf16 v[40:43], v[140:143], v[200:203], v[40:43]
	v_mfma_f32_16x16x32_bf16 v[28:31], v[132:135], v[208:211], v[28:31]
	v_mfma_f32_16x16x32_bf16 v[24:27], v[140:143], v[208:211], v[24:27]
	v_mfma_f32_16x16x32_bf16 v[12:15], v[132:135], v[216:219], v[12:15]
	v_mfma_f32_16x16x32_bf16 v[8:11], v[140:143], v[216:219], v[8:11]
	s_setprio 0
	s_setprio 1
	v_mfma_f32_16x16x32_bf16 v[52:55], v[144:147], v[180:183], 0
	v_mfma_f32_16x16x32_bf16 v[48:51], v[172:175], v[180:183], 0
	v_mfma_f32_16x16x32_bf16 v[36:39], v[144:147], v[196:199], 0
	v_mfma_f32_16x16x32_bf16 v[32:35], v[172:175], v[196:199], 0
	v_mfma_f32_16x16x32_bf16 v[20:23], v[144:147], v[204:207], 0
	v_mfma_f32_16x16x32_bf16 v[16:19], v[172:175], v[204:207], 0
	v_mfma_f32_16x16x32_bf16 v[4:7], v[144:147], v[212:215], 0
	v_mfma_f32_16x16x32_bf16 v[0:3], v[172:175], v[212:215], 0
	v_mfma_f32_16x16x32_bf16 v[52:55], v[148:151], v[192:195], v[52:55]
	v_mfma_f32_16x16x32_bf16 v[48:51], v[176:179], v[192:195], v[48:51]
	v_mfma_f32_16x16x32_bf16 v[36:39], v[148:151], v[200:203], v[36:39]
	v_mfma_f32_16x16x32_bf16 v[32:35], v[176:179], v[200:203], v[32:35]
	v_mfma_f32_16x16x32_bf16 v[20:23], v[148:151], v[208:211], v[20:23]
	v_mfma_f32_16x16x32_bf16 v[16:19], v[176:179], v[208:211], v[16:19]
	v_mfma_f32_16x16x32_bf16 v[4:7], v[148:151], v[216:219], v[4:7]
	v_mfma_f32_16x16x32_bf16 v[0:3], v[176:179], v[216:219], v[0:3]
	s_setprio 0
	s_barrier
	s_add_i32 s81, 0, 0x18000
	s_add_i32 s82, 0, 0x1c000
	v_add_u32_e32 v140, s81, v185
	v_add_u32_e32 v176, s82, v185
	ds_read_b128 v[128:131], v140
	v_xor_b32_e32 v253, 64, v140
	ds_read_b128 v[132:135], v253
	ds_read_b128 v[136:139], v140 offset:2048
	ds_read_b128 v[140:143], v253 offset:2048
	ds_read_b128 v[144:147], v176
	v_xor_b32_e32 v253, 64, v176
	ds_read_b128 v[148:151], v253
	ds_read_b128 v[172:175], v176 offset:2048
	ds_read_b128 v[176:179], v253 offset:2048
	s_add_u32 s62, s62, 0x40000
	s_addc_u32 s63, s63, 0
	s_mov_b32 m0, s69
	v_lshl_add_u64 v[228:229], s[62:63], 0, v[152:153]
	ds_read_b128 v[180:183], v190 offset:32768
	v_xor_b32_e32 v253, 64, v190
	ds_read_b128 v[192:195], v253 offset:32768
	ds_read_b128 v[196:199], v190 offset:34816
	ds_read_b128 v[200:203], v253 offset:34816
	ds_read_b128 v[204:207], v190 offset:36864
	ds_read_b128 v[208:211], v253 offset:36864
	ds_read_b128 v[212:215], v190 offset:38912
	ds_read_b128 v[216:219], v253 offset:38912
	global_load_lds_dwordx4 v[228:229], off
	v_lshl_add_u64 v[228:229], s[62:63], 0, v[160:161]
	s_mov_b32 m0, s70
	s_nop 0
	global_load_lds_dwordx4 v[228:229], off
	s_waitcnt vmcnt(8)
	s_waitcnt lgkmcnt(0)
	s_barrier
	s_setprio 1
	s_waitcnt lgkmcnt(0)
	v_mfma_f32_16x16x32_bf16 v[124:127], v[128:131], v[180:183], v[124:127]
	v_mfma_f32_16x16x32_bf16 v[120:123], v[136:139], v[180:183], v[120:123]
	v_mfma_f32_16x16x32_bf16 v[108:111], v[128:131], v[196:199], v[108:111]
	v_mfma_f32_16x16x32_bf16 v[104:107], v[136:139], v[196:199], v[104:107]
	v_mfma_f32_16x16x32_bf16 v[92:95], v[128:131], v[204:207], v[92:95]
	v_mfma_f32_16x16x32_bf16 v[88:91], v[136:139], v[204:207], v[88:91]
	v_mfma_f32_16x16x32_bf16 v[76:79], v[128:131], v[212:215], v[76:79]
	v_mfma_f32_16x16x32_bf16 v[72:75], v[136:139], v[212:215], v[72:75]
	v_mfma_f32_16x16x32_bf16 v[124:127], v[132:135], v[192:195], v[124:127]
	v_mfma_f32_16x16x32_bf16 v[120:123], v[140:143], v[192:195], v[120:123]
	v_mfma_f32_16x16x32_bf16 v[108:111], v[132:135], v[200:203], v[108:111]
	v_mfma_f32_16x16x32_bf16 v[104:107], v[140:143], v[200:203], v[104:107]
	v_mfma_f32_16x16x32_bf16 v[92:95], v[132:135], v[208:211], v[92:95]
	v_mfma_f32_16x16x32_bf16 v[88:91], v[140:143], v[208:211], v[88:91]
	v_mfma_f32_16x16x32_bf16 v[76:79], v[132:135], v[216:219], v[76:79]
	v_mfma_f32_16x16x32_bf16 v[72:75], v[140:143], v[216:219], v[72:75]
	s_setprio 0
	s_setprio 1
	v_mfma_f32_16x16x32_bf16 v[116:119], v[144:147], v[180:183], v[116:119]
	v_mfma_f32_16x16x32_bf16 v[112:115], v[172:175], v[180:183], v[112:115]
	v_mfma_f32_16x16x32_bf16 v[100:103], v[144:147], v[196:199], v[100:103]
	v_mfma_f32_16x16x32_bf16 v[96:99], v[172:175], v[196:199], v[96:99]
	v_mfma_f32_16x16x32_bf16 v[84:87], v[144:147], v[204:207], v[84:87]
	v_mfma_f32_16x16x32_bf16 v[80:83], v[172:175], v[204:207], v[80:83]
	v_mfma_f32_16x16x32_bf16 v[68:71], v[144:147], v[212:215], v[68:71]
	v_mfma_f32_16x16x32_bf16 v[64:67], v[172:175], v[212:215], v[64:67]
	v_mfma_f32_16x16x32_bf16 v[116:119], v[148:151], v[192:195], v[116:119]
	v_mfma_f32_16x16x32_bf16 v[112:115], v[176:179], v[192:195], v[112:115]
	v_mfma_f32_16x16x32_bf16 v[100:103], v[148:151], v[200:203], v[100:103]
	v_mfma_f32_16x16x32_bf16 v[96:99], v[176:179], v[200:203], v[96:99]
	v_mfma_f32_16x16x32_bf16 v[84:87], v[148:151], v[208:211], v[84:87]
	v_mfma_f32_16x16x32_bf16 v[80:83], v[176:179], v[208:211], v[80:83]
	v_mfma_f32_16x16x32_bf16 v[68:71], v[148:151], v[216:219], v[68:71]
	v_mfma_f32_16x16x32_bf16 v[64:67], v[176:179], v[216:219], v[64:67]
	s_setprio 0
	s_barrier
	s_add_i32 s62, s81, s66
	v_lshl_add_u64 v[220:221], v[220:221], 0, s[26:27]
	s_mov_b32 m0, s62
	ds_read_b128 v[180:183], v190 offset:49152
	v_xor_b32_e32 v253, 64, v190
	ds_read_b128 v[192:195], v253 offset:49152
	ds_read_b128 v[196:199], v190 offset:51200
	ds_read_b128 v[200:203], v253 offset:51200
	ds_read_b128 v[204:207], v190 offset:53248
	ds_read_b128 v[208:211], v253 offset:53248
	ds_read_b128 v[212:215], v190 offset:55296
	ds_read_b128 v[216:219], v253 offset:55296
	global_load_lds_dwordx4 v[220:221], off
	s_add_i32 m0, s62, 0x2000
	s_add_u32 s60, s60, 0x40080
	v_lshl_add_u64 v[220:221], v[222:223], 0, s[26:27]
	s_addc_u32 s61, s61, 0
	s_add_i32 s62, s82, s66
	global_load_lds_dwordx4 v[220:221], off
	v_lshl_add_u64 v[220:221], s[60:61], 0, v[154:155]
	s_mov_b32 m0, s62
	s_nop 0
	global_load_lds_dwordx4 v[220:221], off
	v_lshl_add_u64 v[220:221], s[60:61], 0, v[162:163]
	s_add_i32 m0, s62, 0x2000
	s_nop 0
	global_load_lds_dwordx4 v[220:221], off
	v_lshl_add_u64 v[220:221], v[224:225], 0, s[26:27]
	s_mov_b32 m0, s3
	s_nop 0
	global_load_lds_dwordx4 v[220:221], off
	v_lshl_add_u64 v[220:221], v[226:227], 0, s[26:27]
	s_mov_b32 m0, s72
	s_nop 0
	global_load_lds_dwordx4 v[220:221], off
	s_waitcnt vmcnt(8)
	s_waitcnt lgkmcnt(0)
	s_barrier
	s_setprio 1
	s_waitcnt lgkmcnt(0)
	v_mfma_f32_16x16x32_bf16 v[60:63], v[128:131], v[180:183], v[60:63]
	v_mfma_f32_16x16x32_bf16 v[56:59], v[136:139], v[180:183], v[56:59]
	v_mfma_f32_16x16x32_bf16 v[44:47], v[128:131], v[196:199], v[44:47]
	v_mfma_f32_16x16x32_bf16 v[40:43], v[136:139], v[196:199], v[40:43]
	v_mfma_f32_16x16x32_bf16 v[28:31], v[128:131], v[204:207], v[28:31]
	v_mfma_f32_16x16x32_bf16 v[24:27], v[136:139], v[204:207], v[24:27]
	v_mfma_f32_16x16x32_bf16 v[12:15], v[128:131], v[212:215], v[12:15]
	v_mfma_f32_16x16x32_bf16 v[8:11], v[136:139], v[212:215], v[8:11]
	v_mfma_f32_16x16x32_bf16 v[60:63], v[132:135], v[192:195], v[60:63]
	v_mfma_f32_16x16x32_bf16 v[56:59], v[140:143], v[192:195], v[56:59]
	v_mfma_f32_16x16x32_bf16 v[44:47], v[132:135], v[200:203], v[44:47]
	v_mfma_f32_16x16x32_bf16 v[40:43], v[140:143], v[200:203], v[40:43]
	v_mfma_f32_16x16x32_bf16 v[28:31], v[132:135], v[208:211], v[28:31]
	v_mfma_f32_16x16x32_bf16 v[24:27], v[140:143], v[208:211], v[24:27]
	v_mfma_f32_16x16x32_bf16 v[12:15], v[132:135], v[216:219], v[12:15]
	v_mfma_f32_16x16x32_bf16 v[8:11], v[140:143], v[216:219], v[8:11]
	s_setprio 0
	s_setprio 1
	v_mfma_f32_16x16x32_bf16 v[52:55], v[144:147], v[180:183], v[52:55]
	v_mfma_f32_16x16x32_bf16 v[48:51], v[172:175], v[180:183], v[48:51]
	v_mfma_f32_16x16x32_bf16 v[36:39], v[144:147], v[196:199], v[36:39]
	v_mfma_f32_16x16x32_bf16 v[32:35], v[172:175], v[196:199], v[32:35]
	v_mfma_f32_16x16x32_bf16 v[20:23], v[144:147], v[204:207], v[20:23]
	v_mfma_f32_16x16x32_bf16 v[16:19], v[172:175], v[204:207], v[16:19]
	v_mfma_f32_16x16x32_bf16 v[4:7], v[144:147], v[212:215], v[4:7]
	v_mfma_f32_16x16x32_bf16 v[0:3], v[172:175], v[212:215], v[0:3]
	v_mfma_f32_16x16x32_bf16 v[52:55], v[148:151], v[192:195], v[52:55]
	v_mfma_f32_16x16x32_bf16 v[48:51], v[176:179], v[192:195], v[48:51]
	v_mfma_f32_16x16x32_bf16 v[36:39], v[148:151], v[200:203], v[36:39]
	v_mfma_f32_16x16x32_bf16 v[32:35], v[176:179], v[200:203], v[32:35]
	v_mfma_f32_16x16x32_bf16 v[20:23], v[148:151], v[208:211], v[20:23]
	v_mfma_f32_16x16x32_bf16 v[16:19], v[176:179], v[208:211], v[16:19]
	v_mfma_f32_16x16x32_bf16 v[4:7], v[148:151], v[216:219], v[4:7]
	v_mfma_f32_16x16x32_bf16 v[0:3], v[176:179], v[216:219], v[0:3]
	s_setprio 0
	s_barrier
	s_add_i32 s80, s80, 2
	s_add_u32 s78, s78, 0x100
	s_addc_u32 s79, s79, 0
	s_add_u32 s58, s58, 0x100
	s_addc_u32 s59, s59, 0
	s_cmp_gt_u32 s80, 13
	s_branch .LBB0_1011
.Lfa_9:
	ds_read_b128 v[128:131], v188
	v_xor_b32_e32 v253, 64, v188
	ds_read_b128 v[132:135], v253
	ds_read_b128 v[136:139], v188 offset:2048
	ds_read_b128 v[140:143], v253 offset:2048
	ds_read_b128 v[144:147], v189
	v_xor_b32_e32 v253, 64, v189
	ds_read_b128 v[148:151], v253
	ds_read_b128 v[172:175], v189 offset:2048
	ds_read_b128 v[176:179], v253 offset:2048
	s_add_u32 s60, s58, 0xfffc0080
	s_addc_u32 s61, s59, -1
	s_cmp_eq_u32 s80, 12
	s_cselect_b32 s63, s15, s61
	s_cselect_b32 s62, s51, s60
	s_cselect_b32 s61, s49, s79
	s_cselect_b32 s60, s57, s78
	v_lshl_add_u64 v[220:221], s[58:59], 0, v[166:167]
	s_add_i32 m0, s67, 0xc000
	ds_read_b128 v[180:183], v190
	v_xor_b32_e32 v253, 64, v190
	ds_read_b128 v[192:195], v253
	ds_read_b128 v[196:199], v190 offset:2048
	ds_read_b128 v[200:203], v253 offset:2048
	ds_read_b128 v[204:207], v190 offset:4096
	ds_read_b128 v[208:211], v253 offset:4096
	ds_read_b128 v[212:215], v190 offset:6144
	ds_read_b128 v[216:219], v253 offset:6144
	global_load_lds_dwordx4 v[220:221], off
	v_lshl_add_u64 v[220:221], s[58:59], 0, v[164:165]
	s_add_i32 m0, s67, 0xe000
	s_nop 0
	global_load_lds_dwordx4 v[220:221], off
	s_waitcnt vmcnt(8)
	s_waitcnt lgkmcnt(0)
	s_barrier
	s_setprio 1
	s_waitcnt lgkmcnt(0)
	v_mfma_f32_16x16x32_bf16 v[124:127], v[128:131], v[180:183], 0
	v_mfma_f32_16x16x32_bf16 v[120:123], v[136:139], v[180:183], 0
	v_mfma_f32_16x16x32_bf16 v[108:111], v[128:131], v[196:199], 0
	v_mfma_f32_16x16x32_bf16 v[104:107], v[136:139], v[196:199], 0
	v_mfma_f32_16x16x32_bf16 v[92:95], v[128:131], v[204:207], 0
	v_mfma_f32_16x16x32_bf16 v[88:91], v[136:139], v[204:207], 0
	v_mfma_f32_16x16x32_bf16 v[76:79], v[128:131], v[212:215], 0
	v_mfma_f32_16x16x32_bf16 v[72:75], v[136:139], v[212:215], 0
	v_mfma_f32_16x16x32_bf16 v[124:127], v[132:135], v[192:195], v[124:127]
	v_mfma_f32_16x16x32_bf16 v[120:123], v[140:143], v[192:195], v[120:123]
	v_mfma_f32_16x16x32_bf16 v[108:111], v[132:135], v[200:203], v[108:111]
	v_mfma_f32_16x16x32_bf16 v[104:107], v[140:143], v[200:203], v[104:107]
	v_mfma_f32_16x16x32_bf16 v[92:95], v[132:135], v[208:211], v[92:95]
	v_mfma_f32_16x16x32_bf16 v[88:91], v[140:143], v[208:211], v[88:91]
	v_mfma_f32_16x16x32_bf16 v[76:79], v[132:135], v[216:219], v[76:79]
	v_mfma_f32_16x16x32_bf16 v[72:75], v[140:143], v[216:219], v[72:75]
	s_setprio 0
	s_setprio 1
	v_mfma_f32_16x16x32_bf16 v[116:119], v[144:147], v[180:183], 0
	v_mfma_f32_16x16x32_bf16 v[112:115], v[172:175], v[180:183], 0
	v_mfma_f32_16x16x32_bf16 v[100:103], v[144:147], v[196:199], 0
	v_mfma_f32_16x16x32_bf16 v[96:99], v[172:175], v[196:199], 0
	v_mfma_f32_16x16x32_bf16 v[84:87], v[144:147], v[204:207], 0
	v_mfma_f32_16x16x32_bf16 v[80:83], v[172:175], v[204:207], 0
	v_mfma_f32_16x16x32_bf16 v[68:71], v[144:147], v[212:215], 0
	v_mfma_f32_16x16x32_bf16 v[64:67], v[172:175], v[212:215], 0
	v_mfma_f32_16x16x32_bf16 v[116:119], v[148:151], v[192:195], v[116:119]
	v_mfma_f32_16x16x32_bf16 v[112:115], v[176:179], v[192:195], v[112:115]
	v_mfma_f32_16x16x32_bf16 v[100:103], v[148:151], v[200:203], v[100:103]
	v_mfma_f32_16x16x32_bf16 v[96:99], v[176:179], v[200:203], v[96:99]
	v_mfma_f32_16x16x32_bf16 v[84:87], v[148:151], v[208:211], v[84:87]
	v_mfma_f32_16x16x32_bf16 v[80:83], v[176:179], v[208:211], v[80:83]
	v_mfma_f32_16x16x32_bf16 v[68:71], v[148:151], v[216:219], v[68:71]
	v_mfma_f32_16x16x32_bf16 v[64:67], v[176:179], v[216:219], v[64:67]
	s_setprio 0
	s_barrier
	s_add_i32 s81, s76, s66
	v_lshl_add_u64 v[220:221], s[60:61], 0, v[154:155]
	s_mov_b32 m0, s81
	ds_read_b128 v[180:183], v190 offset:16384
	v_xor_b32_e32 v253, 64, v190
	ds_read_b128 v[192:195], v253 offset:16384
	ds_read_b128 v[196:199], v190 offset:18432
	ds_read_b128 v[200:203], v253 offset:18432
	ds_read_b128 v[204:207], v190 offset:20480
	ds_read_b128 v[208:211], v253 offset:20480
	ds_read_b128 v[212:215], v190 offset:22528
	ds_read_b128 v[216:219], v253 offset:22528
	global_load_lds_dwordx4 v[220:221], off
	s_add_i32 m0, s81, 0x2000
	s_add_u32 s82, s60, 0x40000
	v_lshl_add_u64 v[222:223], s[60:61], 0, v[162:163]
	s_addc_u32 s83, s61, 0
	s_add_i32 s81, s77, s66
	global_load_lds_dwordx4 v[222:223], off
	v_lshl_add_u64 v[224:225], s[82:83], 0, v[154:155]
	s_mov_b32 m0, s81
	v_lshl_add_u64 v[226:227], s[62:63], 0, v[160:161]
	global_load_lds_dwordx4 v[224:225], off
	v_lshl_add_u64 v[224:225], s[82:83], 0, v[162:163]
	s_add_i32 m0, s81, 0x2000
	s_nop 0
	global_load_lds_dwordx4 v[224:225], off
	v_lshl_add_u64 v[224:225], s[62:63], 0, v[152:153]
	s_mov_b32 m0, s67
	s_nop 0
	global_load_lds_dwordx4 v[224:225], off
	s_mov_b32 m0, s68
	s_nop 0
	global_load_lds_dwordx4 v[226:227], off
	s_waitcnt vmcnt(8)
	s_waitcnt lgkmcnt(0)
	s_barrier
	s_setprio 1
	s_waitcnt lgkmcnt(0)
	v_mfma_f32_16x16x32_bf16 v[60:63], v[128:131], v[180:183], 0
	v_mfma_f32_16x16x32_bf16 v[56:59], v[136:139], v[180:183], 0
	v_mfma_f32_16x16x32_bf16 v[44:47], v[128:131], v[196:199], 0
	v_mfma_f32_16x16x32_bf16 v[40:43], v[136:139], v[196:199], 0
	v_mfma_f32_16x16x32_bf16 v[28:31], v[128:131], v[204:207], 0
	v_mfma_f32_16x16x32_bf16 v[24:27], v[136:139], v[204:207], 0
	v_mfma_f32_16x16x32_bf16 v[12:15], v[128:131], v[212:215], 0
	v_mfma_f32_16x16x32_bf16 v[8:11], v[136:139], v[212:215], 0
	v_mfma_f32_16x16x32_bf16 v[60:63], v[132:135], v[192:195], v[60:63]
	v_mfma_f32_16x16x32_bf16 v[56:59], v[140:143], v[192:195], v[56:59]
	v_mfma_f32_16x16x32_bf16 v[44:47], v[132:135], v[200:203], v[44:47]
	v_mfma_f32_16x16x32_bf16 v[40:43], v[140:143], v[200:203], v[40:43]
	v_mfma_f32_16x16x32_bf16 v[28:31], v[132:135], v[208:211], v[28:31]
	v_mfma_f32_16x16x32_bf16 v[24:27], v[140:143], v[208:211], v[24:27]
	v_mfma_f32_16x16x32_bf16 v[12:15], v[132:135], v[216:219], v[12:15]
	v_mfma_f32_16x16x32_bf16 v[8:11], v[140:143], v[216:219], v[8:11]
	s_setprio 0
	s_setprio 1
	v_mfma_f32_16x16x32_bf16 v[52:55], v[144:147], v[180:183], 0
	v_mfma_f32_16x16x32_bf16 v[48:51], v[172:175], v[180:183], 0
	v_mfma_f32_16x16x32_bf16 v[36:39], v[144:147], v[196:199], 0
	v_mfma_f32_16x16x32_bf16 v[32:35], v[172:175], v[196:199], 0
	v_mfma_f32_16x16x32_bf16 v[20:23], v[144:147], v[204:207], 0
	v_mfma_f32_16x16x32_bf16 v[16:19], v[172:175], v[204:207], 0
	v_mfma_f32_16x16x32_bf16 v[4:7], v[144:147], v[212:215], 0
	v_mfma_f32_16x16x32_bf16 v[0:3], v[172:175], v[212:215], 0
	v_mfma_f32_16x16x32_bf16 v[52:55], v[148:151], v[192:195], v[52:55]
	v_mfma_f32_16x16x32_bf16 v[48:51], v[176:179], v[192:195], v[48:51]
	v_mfma_f32_16x16x32_bf16 v[36:39], v[148:151], v[200:203], v[36:39]
	v_mfma_f32_16x16x32_bf16 v[32:35], v[176:179], v[200:203], v[32:35]
	v_mfma_f32_16x16x32_bf16 v[20:23], v[148:151], v[208:211], v[20:23]
	v_mfma_f32_16x16x32_bf16 v[16:19], v[176:179], v[208:211], v[16:19]
	v_mfma_f32_16x16x32_bf16 v[4:7], v[148:151], v[216:219], v[4:7]
	v_mfma_f32_16x16x32_bf16 v[0:3], v[176:179], v[216:219], v[0:3]
	s_setprio 0
	s_barrier
	s_add_i32 s81, 0, 0x18000
	s_add_i32 s82, 0, 0x1c000
	v_add_u32_e32 v140, s81, v185
	v_add_u32_e32 v176, s82, v185
	ds_read_b128 v[128:131], v140
	v_xor_b32_e32 v253, 64, v140
	ds_read_b128 v[132:135], v253
	ds_read_b128 v[136:139], v140 offset:2048
	ds_read_b128 v[140:143], v253 offset:2048
	ds_read_b128 v[144:147], v176
	v_xor_b32_e32 v253, 64, v176
	ds_read_b128 v[148:151], v253
	ds_read_b128 v[172:175], v176 offset:2048
	ds_read_b128 v[176:179], v253 offset:2048
	s_add_u32 s62, s62, 0x40000
	s_addc_u32 s63, s63, 0
	s_mov_b32 m0, s69
	v_lshl_add_u64 v[228:229], s[62:63], 0, v[152:153]
	ds_read_b128 v[180:183], v190 offset:32768
	v_xor_b32_e32 v253, 64, v190
	ds_read_b128 v[192:195], v253 offset:32768
	ds_read_b128 v[196:199], v190 offset:34816
	ds_read_b128 v[200:203], v253 offset:34816
	ds_read_b128 v[204:207], v190 offset:36864
	ds_read_b128 v[208:211], v253 offset:36864
	ds_read_b128 v[212:215], v190 offset:38912
	ds_read_b128 v[216:219], v253 offset:38912
	global_load_lds_dwordx4 v[228:229], off
	v_lshl_add_u64 v[228:229], s[62:63], 0, v[160:161]
	s_mov_b32 m0, s70
	s_nop 0
	global_load_lds_dwordx4 v[228:229], off
	s_waitcnt vmcnt(8)
	s_waitcnt lgkmcnt(0)
	s_barrier
	s_setprio 1
	s_waitcnt lgkmcnt(0)
	v_mfma_f32_16x16x32_bf16 v[124:127], v[128:131], v[180:183], v[124:127]
	v_mfma_f32_16x16x32_bf16 v[120:123], v[136:139], v[180:183], v[120:123]
	v_mfma_f32_16x16x32_bf16 v[108:111], v[128:131], v[196:199], v[108:111]
	v_mfma_f32_16x16x32_bf16 v[104:107], v[136:139], v[196:199], v[104:107]
	v_mfma_f32_16x16x32_bf16 v[92:95], v[128:131], v[204:207], v[92:95]
	v_mfma_f32_16x16x32_bf16 v[88:91], v[136:139], v[204:207], v[88:91]
	v_mfma_f32_16x16x32_bf16 v[76:79], v[128:131], v[212:215], v[76:79]
	v_mfma_f32_16x16x32_bf16 v[72:75], v[136:139], v[212:215], v[72:75]
	v_mfma_f32_16x16x32_bf16 v[124:127], v[132:135], v[192:195], v[124:127]
	v_mfma_f32_16x16x32_bf16 v[120:123], v[140:143], v[192:195], v[120:123]
	v_mfma_f32_16x16x32_bf16 v[108:111], v[132:135], v[200:203], v[108:111]
	v_mfma_f32_16x16x32_bf16 v[104:107], v[140:143], v[200:203], v[104:107]
	v_mfma_f32_16x16x32_bf16 v[92:95], v[132:135], v[208:211], v[92:95]
	v_mfma_f32_16x16x32_bf16 v[88:91], v[140:143], v[208:211], v[88:91]
	v_mfma_f32_16x16x32_bf16 v[76:79], v[132:135], v[216:219], v[76:79]
	v_mfma_f32_16x16x32_bf16 v[72:75], v[140:143], v[216:219], v[72:75]
	s_setprio 0
	s_setprio 1
	v_mfma_f32_16x16x32_bf16 v[116:119], v[144:147], v[180:183], v[116:119]
	v_mfma_f32_16x16x32_bf16 v[112:115], v[172:175], v[180:183], v[112:115]
	v_mfma_f32_16x16x32_bf16 v[100:103], v[144:147], v[196:199], v[100:103]
	v_mfma_f32_16x16x32_bf16 v[96:99], v[172:175], v[196:199], v[96:99]
	v_mfma_f32_16x16x32_bf16 v[84:87], v[144:147], v[204:207], v[84:87]
	v_mfma_f32_16x16x32_bf16 v[80:83], v[172:175], v[204:207], v[80:83]
	v_mfma_f32_16x16x32_bf16 v[68:71], v[144:147], v[212:215], v[68:71]
	v_mfma_f32_16x16x32_bf16 v[64:67], v[172:175], v[212:215], v[64:67]
	v_mfma_f32_16x16x32_bf16 v[116:119], v[148:151], v[192:195], v[116:119]
	v_mfma_f32_16x16x32_bf16 v[112:115], v[176:179], v[192:195], v[112:115]
	v_mfma_f32_16x16x32_bf16 v[100:103], v[148:151], v[200:203], v[100:103]
	v_mfma_f32_16x16x32_bf16 v[96:99], v[176:179], v[200:203], v[96:99]
	v_mfma_f32_16x16x32_bf16 v[84:87], v[148:151], v[208:211], v[84:87]
	v_mfma_f32_16x16x32_bf16 v[80:83], v[176:179], v[208:211], v[80:83]
	v_mfma_f32_16x16x32_bf16 v[68:71], v[148:151], v[216:219], v[68:71]
	v_mfma_f32_16x16x32_bf16 v[64:67], v[176:179], v[216:219], v[64:67]
	s_setprio 0
	s_barrier
	s_add_i32 s62, s81, s66
	v_lshl_add_u64 v[220:221], v[220:221], 0, s[26:27]
	s_mov_b32 m0, s62
	ds_read_b128 v[180:183], v190 offset:49152
	v_xor_b32_e32 v253, 64, v190
	ds_read_b128 v[192:195], v253 offset:49152
	ds_read_b128 v[196:199], v190 offset:51200
	ds_read_b128 v[200:203], v253 offset:51200
	ds_read_b128 v[204:207], v190 offset:53248
	ds_read_b128 v[208:211], v253 offset:53248
	ds_read_b128 v[212:215], v190 offset:55296
	ds_read_b128 v[216:219], v253 offset:55296
	global_load_lds_dwordx4 v[220:221], off
	s_add_i32 m0, s62, 0x2000
	s_add_u32 s60, s60, 0x40080
	v_lshl_add_u64 v[220:221], v[222:223], 0, s[26:27]
	s_addc_u32 s61, s61, 0
	s_add_i32 s62, s82, s66
	global_load_lds_dwordx4 v[220:221], off
	v_lshl_add_u64 v[220:221], s[60:61], 0, v[154:155]
	s_mov_b32 m0, s62
	s_nop 0
	global_load_lds_dwordx4 v[220:221], off
	v_lshl_add_u64 v[220:221], s[60:61], 0, v[162:163]
	s_add_i32 m0, s62, 0x2000
	s_nop 0
	global_load_lds_dwordx4 v[220:221], off
	v_lshl_add_u64 v[220:221], v[224:225], 0, s[26:27]
	s_mov_b32 m0, s3
	s_nop 0
	global_load_lds_dwordx4 v[220:221], off
	v_lshl_add_u64 v[220:221], v[226:227], 0, s[26:27]
	s_mov_b32 m0, s72
	s_nop 0
	global_load_lds_dwordx4 v[220:221], off
	s_waitcnt vmcnt(8)
	s_waitcnt lgkmcnt(0)
	s_barrier
	s_setprio 1
	s_waitcnt lgkmcnt(0)
	v_mfma_f32_16x16x32_bf16 v[60:63], v[128:131], v[180:183], v[60:63]
	v_mfma_f32_16x16x32_bf16 v[56:59], v[136:139], v[180:183], v[56:59]
	v_mfma_f32_16x16x32_bf16 v[44:47], v[128:131], v[196:199], v[44:47]
	v_mfma_f32_16x16x32_bf16 v[40:43], v[136:139], v[196:199], v[40:43]
	v_mfma_f32_16x16x32_bf16 v[28:31], v[128:131], v[204:207], v[28:31]
	v_mfma_f32_16x16x32_bf16 v[24:27], v[136:139], v[204:207], v[24:27]
	v_mfma_f32_16x16x32_bf16 v[12:15], v[128:131], v[212:215], v[12:15]
	v_mfma_f32_16x16x32_bf16 v[8:11], v[136:139], v[212:215], v[8:11]
	v_mfma_f32_16x16x32_bf16 v[60:63], v[132:135], v[192:195], v[60:63]
	v_mfma_f32_16x16x32_bf16 v[56:59], v[140:143], v[192:195], v[56:59]
	v_mfma_f32_16x16x32_bf16 v[44:47], v[132:135], v[200:203], v[44:47]
	v_mfma_f32_16x16x32_bf16 v[40:43], v[140:143], v[200:203], v[40:43]
	v_mfma_f32_16x16x32_bf16 v[28:31], v[132:135], v[208:211], v[28:31]
	v_mfma_f32_16x16x32_bf16 v[24:27], v[140:143], v[208:211], v[24:27]
	v_mfma_f32_16x16x32_bf16 v[12:15], v[132:135], v[216:219], v[12:15]
	v_mfma_f32_16x16x32_bf16 v[8:11], v[140:143], v[216:219], v[8:11]
	s_setprio 0
	s_setprio 1
	v_mfma_f32_16x16x32_bf16 v[52:55], v[144:147], v[180:183], v[52:55]
	v_mfma_f32_16x16x32_bf16 v[48:51], v[172:175], v[180:183], v[48:51]
	v_mfma_f32_16x16x32_bf16 v[36:39], v[144:147], v[196:199], v[36:39]
	v_mfma_f32_16x16x32_bf16 v[32:35], v[172:175], v[196:199], v[32:35]
	v_mfma_f32_16x16x32_bf16 v[20:23], v[144:147], v[204:207], v[20:23]
	v_mfma_f32_16x16x32_bf16 v[16:19], v[172:175], v[204:207], v[16:19]
	v_mfma_f32_16x16x32_bf16 v[4:7], v[144:147], v[212:215], v[4:7]
	v_mfma_f32_16x16x32_bf16 v[0:3], v[172:175], v[212:215], v[0:3]
	v_mfma_f32_16x16x32_bf16 v[52:55], v[148:151], v[192:195], v[52:55]
	v_mfma_f32_16x16x32_bf16 v[48:51], v[176:179], v[192:195], v[48:51]
	v_mfma_f32_16x16x32_bf16 v[36:39], v[148:151], v[200:203], v[36:39]
	v_mfma_f32_16x16x32_bf16 v[32:35], v[176:179], v[200:203], v[32:35]
	v_mfma_f32_16x16x32_bf16 v[20:23], v[148:151], v[208:211], v[20:23]
	v_mfma_f32_16x16x32_bf16 v[16:19], v[176:179], v[208:211], v[16:19]
	v_mfma_f32_16x16x32_bf16 v[4:7], v[148:151], v[216:219], v[4:7]
	v_mfma_f32_16x16x32_bf16 v[0:3], v[176:179], v[216:219], v[0:3]
	s_setprio 0
	s_barrier
	s_add_i32 s80, s80, 2
	s_add_u32 s78, s78, 0x100
	s_addc_u32 s79, s79, 0
	s_add_u32 s58, s58, 0x100
	s_addc_u32 s59, s59, 0
	s_cmp_gt_u32 s80, 13
.LBB0_1011:
	ds_read_b128 v[128:131], v188
	v_xor_b32_e32 v253, 64, v188
	ds_read_b128 v[132:135], v253
	ds_read_b128 v[136:139], v188 offset:2048
	ds_read_b128 v[140:143], v253 offset:2048
	ds_read_b128 v[144:147], v189
	v_xor_b32_e32 v253, 64, v189
	ds_read_b128 v[148:151], v253
	ds_read_b128 v[172:175], v189 offset:2048
	ds_read_b128 v[176:179], v253 offset:2048
	s_add_u32 s60, s58, 0xfffc0080
	s_addc_u32 s61, s59, -1
	s_cmp_eq_u32 s80, 12
	s_cselect_b32 s63, s15, s61
	s_cselect_b32 s62, s51, s60
	s_cselect_b32 s61, s49, s79
	s_cselect_b32 s60, s57, s78
	v_lshl_add_u64 v[220:221], s[58:59], 0, v[166:167]
	s_add_i32 m0, s67, 0xc000
	ds_read_b128 v[180:183], v190
	v_xor_b32_e32 v253, 64, v190
	ds_read_b128 v[192:195], v253
	ds_read_b128 v[196:199], v190 offset:2048
	ds_read_b128 v[200:203], v253 offset:2048
	ds_read_b128 v[204:207], v190 offset:4096
	ds_read_b128 v[208:211], v253 offset:4096
	ds_read_b128 v[212:215], v190 offset:6144
	ds_read_b128 v[216:219], v253 offset:6144
	global_load_lds_dwordx4 v[220:221], off
	v_lshl_add_u64 v[220:221], s[58:59], 0, v[164:165]
	s_add_i32 m0, s67, 0xe000
	s_nop 0
	global_load_lds_dwordx4 v[220:221], off
	s_waitcnt vmcnt(8)
	s_waitcnt lgkmcnt(0)
	s_barrier
	s_setprio 1
	s_waitcnt lgkmcnt(0)
	v_mfma_f32_16x16x32_bf16 v[124:127], v[128:131], v[180:183], v[124:127]
	v_mfma_f32_16x16x32_bf16 v[120:123], v[136:139], v[180:183], v[120:123]
	v_mfma_f32_16x16x32_bf16 v[108:111], v[128:131], v[196:199], v[108:111]
	v_mfma_f32_16x16x32_bf16 v[104:107], v[136:139], v[196:199], v[104:107]
	v_mfma_f32_16x16x32_bf16 v[92:95], v[128:131], v[204:207], v[92:95]
	v_mfma_f32_16x16x32_bf16 v[88:91], v[136:139], v[204:207], v[88:91]
	v_mfma_f32_16x16x32_bf16 v[76:79], v[128:131], v[212:215], v[76:79]
	v_mfma_f32_16x16x32_bf16 v[72:75], v[136:139], v[212:215], v[72:75]
	v_mfma_f32_16x16x32_bf16 v[124:127], v[132:135], v[192:195], v[124:127]
	v_mfma_f32_16x16x32_bf16 v[120:123], v[140:143], v[192:195], v[120:123]
	v_mfma_f32_16x16x32_bf16 v[108:111], v[132:135], v[200:203], v[108:111]
	v_mfma_f32_16x16x32_bf16 v[104:107], v[140:143], v[200:203], v[104:107]
	v_mfma_f32_16x16x32_bf16 v[92:95], v[132:135], v[208:211], v[92:95]
	v_mfma_f32_16x16x32_bf16 v[88:91], v[140:143], v[208:211], v[88:91]
	v_mfma_f32_16x16x32_bf16 v[76:79], v[132:135], v[216:219], v[76:79]
	v_mfma_f32_16x16x32_bf16 v[72:75], v[140:143], v[216:219], v[72:75]
	s_setprio 0
	s_setprio 1
	v_mfma_f32_16x16x32_bf16 v[116:119], v[144:147], v[180:183], v[116:119]
	v_mfma_f32_16x16x32_bf16 v[112:115], v[172:175], v[180:183], v[112:115]
	v_mfma_f32_16x16x32_bf16 v[100:103], v[144:147], v[196:199], v[100:103]
	v_mfma_f32_16x16x32_bf16 v[96:99], v[172:175], v[196:199], v[96:99]
	v_mfma_f32_16x16x32_bf16 v[84:87], v[144:147], v[204:207], v[84:87]
	v_mfma_f32_16x16x32_bf16 v[80:83], v[172:175], v[204:207], v[80:83]
	v_mfma_f32_16x16x32_bf16 v[68:71], v[144:147], v[212:215], v[68:71]
	v_mfma_f32_16x16x32_bf16 v[64:67], v[172:175], v[212:215], v[64:67]
	v_mfma_f32_16x16x32_bf16 v[116:119], v[148:151], v[192:195], v[116:119]
	v_mfma_f32_16x16x32_bf16 v[112:115], v[176:179], v[192:195], v[112:115]
	v_mfma_f32_16x16x32_bf16 v[100:103], v[148:151], v[200:203], v[100:103]
	v_mfma_f32_16x16x32_bf16 v[96:99], v[176:179], v[200:203], v[96:99]
	v_mfma_f32_16x16x32_bf16 v[84:87], v[148:151], v[208:211], v[84:87]
	v_mfma_f32_16x16x32_bf16 v[80:83], v[176:179], v[208:211], v[80:83]
	v_mfma_f32_16x16x32_bf16 v[68:71], v[148:151], v[216:219], v[68:71]
	v_mfma_f32_16x16x32_bf16 v[64:67], v[176:179], v[216:219], v[64:67]
	s_setprio 0
	s_barrier
	s_add_i32 s81, s76, s66
	v_lshl_add_u64 v[220:221], s[60:61], 0, v[154:155]
	s_mov_b32 m0, s81
	ds_read_b128 v[180:183], v190 offset:16384
	v_xor_b32_e32 v253, 64, v190
	ds_read_b128 v[192:195], v253 offset:16384
	ds_read_b128 v[196:199], v190 offset:18432
	ds_read_b128 v[200:203], v253 offset:18432
	ds_read_b128 v[204:207], v190 offset:20480
	ds_read_b128 v[208:211], v253 offset:20480
	ds_read_b128 v[212:215], v190 offset:22528
	ds_read_b128 v[216:219], v253 offset:22528
	global_load_lds_dwordx4 v[220:221], off
	s_add_i32 m0, s81, 0x2000
	s_add_u32 s82, s60, 0x40000
	v_lshl_add_u64 v[222:223], s[60:61], 0, v[162:163]
	s_addc_u32 s83, s61, 0
	s_add_i32 s81, s77, s66
	global_load_lds_dwordx4 v[222:223], off
	v_lshl_add_u64 v[224:225], s[82:83], 0, v[154:155]
	s_mov_b32 m0, s81
	v_lshl_add_u64 v[226:227], s[62:63], 0, v[160:161]
	global_load_lds_dwordx4 v[224:225], off
	v_lshl_add_u64 v[224:225], s[82:83], 0, v[162:163]
	s_add_i32 m0, s81, 0x2000
	s_nop 0
	global_load_lds_dwordx4 v[224:225], off
	v_lshl_add_u64 v[224:225], s[62:63], 0, v[152:153]
	s_mov_b32 m0, s67
	s_nop 0
	global_load_lds_dwordx4 v[224:225], off
	s_mov_b32 m0, s68
	s_nop 0
	global_load_lds_dwordx4 v[226:227], off
	s_waitcnt vmcnt(8)
	s_waitcnt lgkmcnt(0)
	s_barrier
	s_setprio 1
	s_waitcnt lgkmcnt(0)
	v_mfma_f32_16x16x32_bf16 v[60:63], v[128:131], v[180:183], v[60:63]
	v_mfma_f32_16x16x32_bf16 v[56:59], v[136:139], v[180:183], v[56:59]
	v_mfma_f32_16x16x32_bf16 v[44:47], v[128:131], v[196:199], v[44:47]
	v_mfma_f32_16x16x32_bf16 v[40:43], v[136:139], v[196:199], v[40:43]
	v_mfma_f32_16x16x32_bf16 v[28:31], v[128:131], v[204:207], v[28:31]
	v_mfma_f32_16x16x32_bf16 v[24:27], v[136:139], v[204:207], v[24:27]
	v_mfma_f32_16x16x32_bf16 v[12:15], v[128:131], v[212:215], v[12:15]
	v_mfma_f32_16x16x32_bf16 v[8:11], v[136:139], v[212:215], v[8:11]
	v_mfma_f32_16x16x32_bf16 v[60:63], v[132:135], v[192:195], v[60:63]
	v_mfma_f32_16x16x32_bf16 v[56:59], v[140:143], v[192:195], v[56:59]
	v_mfma_f32_16x16x32_bf16 v[44:47], v[132:135], v[200:203], v[44:47]
	v_mfma_f32_16x16x32_bf16 v[40:43], v[140:143], v[200:203], v[40:43]
	v_mfma_f32_16x16x32_bf16 v[28:31], v[132:135], v[208:211], v[28:31]
	v_mfma_f32_16x16x32_bf16 v[24:27], v[140:143], v[208:211], v[24:27]
	v_mfma_f32_16x16x32_bf16 v[12:15], v[132:135], v[216:219], v[12:15]
	v_mfma_f32_16x16x32_bf16 v[8:11], v[140:143], v[216:219], v[8:11]
	s_setprio 0
	s_setprio 1
	v_mfma_f32_16x16x32_bf16 v[52:55], v[144:147], v[180:183], v[52:55]
	v_mfma_f32_16x16x32_bf16 v[48:51], v[172:175], v[180:183], v[48:51]
	v_mfma_f32_16x16x32_bf16 v[36:39], v[144:147], v[196:199], v[36:39]
	v_mfma_f32_16x16x32_bf16 v[32:35], v[172:175], v[196:199], v[32:35]
	v_mfma_f32_16x16x32_bf16 v[20:23], v[144:147], v[204:207], v[20:23]
	v_mfma_f32_16x16x32_bf16 v[16:19], v[172:175], v[204:207], v[16:19]
	v_mfma_f32_16x16x32_bf16 v[4:7], v[144:147], v[212:215], v[4:7]
	v_mfma_f32_16x16x32_bf16 v[0:3], v[172:175], v[212:215], v[0:3]
	v_mfma_f32_16x16x32_bf16 v[52:55], v[148:151], v[192:195], v[52:55]
	v_mfma_f32_16x16x32_bf16 v[48:51], v[176:179], v[192:195], v[48:51]
	v_mfma_f32_16x16x32_bf16 v[36:39], v[148:151], v[200:203], v[36:39]
	v_mfma_f32_16x16x32_bf16 v[32:35], v[176:179], v[200:203], v[32:35]
	v_mfma_f32_16x16x32_bf16 v[20:23], v[148:151], v[208:211], v[20:23]
	v_mfma_f32_16x16x32_bf16 v[16:19], v[176:179], v[208:211], v[16:19]
	v_mfma_f32_16x16x32_bf16 v[4:7], v[148:151], v[216:219], v[4:7]
	v_mfma_f32_16x16x32_bf16 v[0:3], v[176:179], v[216:219], v[0:3]
	s_setprio 0
	s_barrier
	s_add_i32 s81, 0, 0x18000
	s_add_i32 s82, 0, 0x1c000
	v_add_u32_e32 v140, s81, v185
	v_add_u32_e32 v176, s82, v185
	ds_read_b128 v[128:131], v140
	v_xor_b32_e32 v253, 64, v140
	ds_read_b128 v[132:135], v253
	ds_read_b128 v[136:139], v140 offset:2048
	ds_read_b128 v[140:143], v253 offset:2048
	ds_read_b128 v[144:147], v176
	v_xor_b32_e32 v253, 64, v176
	ds_read_b128 v[148:151], v253
	ds_read_b128 v[172:175], v176 offset:2048
	ds_read_b128 v[176:179], v253 offset:2048
	s_add_u32 s62, s62, 0x40000
	s_addc_u32 s63, s63, 0
	s_mov_b32 m0, s69
	v_lshl_add_u64 v[228:229], s[62:63], 0, v[152:153]
	ds_read_b128 v[180:183], v190 offset:32768
	v_xor_b32_e32 v253, 64, v190
	ds_read_b128 v[192:195], v253 offset:32768
	ds_read_b128 v[196:199], v190 offset:34816
	ds_read_b128 v[200:203], v253 offset:34816
	ds_read_b128 v[204:207], v190 offset:36864
	ds_read_b128 v[208:211], v253 offset:36864
	ds_read_b128 v[212:215], v190 offset:38912
	ds_read_b128 v[216:219], v253 offset:38912
	global_load_lds_dwordx4 v[228:229], off
	v_lshl_add_u64 v[228:229], s[62:63], 0, v[160:161]
	s_mov_b32 m0, s70
	s_nop 0
	global_load_lds_dwordx4 v[228:229], off
	s_waitcnt vmcnt(8)
	s_waitcnt lgkmcnt(0)
	s_barrier
	s_setprio 1
	s_waitcnt lgkmcnt(0)
	v_mfma_f32_16x16x32_bf16 v[124:127], v[128:131], v[180:183], v[124:127]
	v_mfma_f32_16x16x32_bf16 v[120:123], v[136:139], v[180:183], v[120:123]
	v_mfma_f32_16x16x32_bf16 v[108:111], v[128:131], v[196:199], v[108:111]
	v_mfma_f32_16x16x32_bf16 v[104:107], v[136:139], v[196:199], v[104:107]
	v_mfma_f32_16x16x32_bf16 v[92:95], v[128:131], v[204:207], v[92:95]
	v_mfma_f32_16x16x32_bf16 v[88:91], v[136:139], v[204:207], v[88:91]
	v_mfma_f32_16x16x32_bf16 v[76:79], v[128:131], v[212:215], v[76:79]
	v_mfma_f32_16x16x32_bf16 v[72:75], v[136:139], v[212:215], v[72:75]
	v_mfma_f32_16x16x32_bf16 v[124:127], v[132:135], v[192:195], v[124:127]
	v_mfma_f32_16x16x32_bf16 v[120:123], v[140:143], v[192:195], v[120:123]
	v_mfma_f32_16x16x32_bf16 v[108:111], v[132:135], v[200:203], v[108:111]
	v_mfma_f32_16x16x32_bf16 v[104:107], v[140:143], v[200:203], v[104:107]
	v_mfma_f32_16x16x32_bf16 v[92:95], v[132:135], v[208:211], v[92:95]
	v_mfma_f32_16x16x32_bf16 v[88:91], v[140:143], v[208:211], v[88:91]
	v_mfma_f32_16x16x32_bf16 v[76:79], v[132:135], v[216:219], v[76:79]
	v_mfma_f32_16x16x32_bf16 v[72:75], v[140:143], v[216:219], v[72:75]
	s_setprio 0
	s_setprio 1
	v_mfma_f32_16x16x32_bf16 v[116:119], v[144:147], v[180:183], v[116:119]
	v_mfma_f32_16x16x32_bf16 v[112:115], v[172:175], v[180:183], v[112:115]
	v_mfma_f32_16x16x32_bf16 v[100:103], v[144:147], v[196:199], v[100:103]
	v_mfma_f32_16x16x32_bf16 v[96:99], v[172:175], v[196:199], v[96:99]
	v_mfma_f32_16x16x32_bf16 v[84:87], v[144:147], v[204:207], v[84:87]
	v_mfma_f32_16x16x32_bf16 v[80:83], v[172:175], v[204:207], v[80:83]
	v_mfma_f32_16x16x32_bf16 v[68:71], v[144:147], v[212:215], v[68:71]
	v_mfma_f32_16x16x32_bf16 v[64:67], v[172:175], v[212:215], v[64:67]
	v_mfma_f32_16x16x32_bf16 v[116:119], v[148:151], v[192:195], v[116:119]
	v_mfma_f32_16x16x32_bf16 v[112:115], v[176:179], v[192:195], v[112:115]
	v_mfma_f32_16x16x32_bf16 v[100:103], v[148:151], v[200:203], v[100:103]
	v_mfma_f32_16x16x32_bf16 v[96:99], v[176:179], v[200:203], v[96:99]
	v_mfma_f32_16x16x32_bf16 v[84:87], v[148:151], v[208:211], v[84:87]
	v_mfma_f32_16x16x32_bf16 v[80:83], v[176:179], v[208:211], v[80:83]
	v_mfma_f32_16x16x32_bf16 v[68:71], v[148:151], v[216:219], v[68:71]
	v_mfma_f32_16x16x32_bf16 v[64:67], v[176:179], v[216:219], v[64:67]
	s_setprio 0
	s_barrier
	s_add_i32 s62, s81, s66
	v_lshl_add_u64 v[220:221], v[220:221], 0, s[26:27]
	s_mov_b32 m0, s62
	ds_read_b128 v[180:183], v190 offset:49152
	v_xor_b32_e32 v253, 64, v190
	ds_read_b128 v[192:195], v253 offset:49152
	ds_read_b128 v[196:199], v190 offset:51200
	ds_read_b128 v[200:203], v253 offset:51200
	ds_read_b128 v[204:207], v190 offset:53248
	ds_read_b128 v[208:211], v253 offset:53248
	ds_read_b128 v[212:215], v190 offset:55296
	ds_read_b128 v[216:219], v253 offset:55296
	global_load_lds_dwordx4 v[220:221], off
	s_add_i32 m0, s62, 0x2000
	s_add_u32 s60, s60, 0x40080
	v_lshl_add_u64 v[220:221], v[222:223], 0, s[26:27]
	s_addc_u32 s61, s61, 0
	s_add_i32 s62, s82, s66
	global_load_lds_dwordx4 v[220:221], off
	v_lshl_add_u64 v[220:221], s[60:61], 0, v[154:155]
	s_mov_b32 m0, s62
	s_nop 0
	global_load_lds_dwordx4 v[220:221], off
	v_lshl_add_u64 v[220:221], s[60:61], 0, v[162:163]
	s_add_i32 m0, s62, 0x2000
	s_nop 0
	global_load_lds_dwordx4 v[220:221], off
	v_lshl_add_u64 v[220:221], v[224:225], 0, s[26:27]
	s_mov_b32 m0, s3
	s_nop 0
	global_load_lds_dwordx4 v[220:221], off
	v_lshl_add_u64 v[220:221], v[226:227], 0, s[26:27]
	s_mov_b32 m0, s72
	s_nop 0
	global_load_lds_dwordx4 v[220:221], off
	s_waitcnt vmcnt(8)
	s_waitcnt lgkmcnt(0)
	s_barrier
	s_setprio 1
	s_waitcnt lgkmcnt(0)
	v_mfma_f32_16x16x32_bf16 v[60:63], v[128:131], v[180:183], v[60:63]
	v_mfma_f32_16x16x32_bf16 v[56:59], v[136:139], v[180:183], v[56:59]
	v_mfma_f32_16x16x32_bf16 v[44:47], v[128:131], v[196:199], v[44:47]
	v_mfma_f32_16x16x32_bf16 v[40:43], v[136:139], v[196:199], v[40:43]
	v_mfma_f32_16x16x32_bf16 v[28:31], v[128:131], v[204:207], v[28:31]
	v_mfma_f32_16x16x32_bf16 v[24:27], v[136:139], v[204:207], v[24:27]
	v_mfma_f32_16x16x32_bf16 v[12:15], v[128:131], v[212:215], v[12:15]
	v_mfma_f32_16x16x32_bf16 v[8:11], v[136:139], v[212:215], v[8:11]
	v_mfma_f32_16x16x32_bf16 v[60:63], v[132:135], v[192:195], v[60:63]
	v_mfma_f32_16x16x32_bf16 v[56:59], v[140:143], v[192:195], v[56:59]
	v_mfma_f32_16x16x32_bf16 v[44:47], v[132:135], v[200:203], v[44:47]
	v_mfma_f32_16x16x32_bf16 v[40:43], v[140:143], v[200:203], v[40:43]
	v_mfma_f32_16x16x32_bf16 v[28:31], v[132:135], v[208:211], v[28:31]
	v_mfma_f32_16x16x32_bf16 v[24:27], v[140:143], v[208:211], v[24:27]
	v_mfma_f32_16x16x32_bf16 v[12:15], v[132:135], v[216:219], v[12:15]
	v_mfma_f32_16x16x32_bf16 v[8:11], v[140:143], v[216:219], v[8:11]
	s_setprio 0
	s_setprio 1
	v_mfma_f32_16x16x32_bf16 v[52:55], v[144:147], v[180:183], v[52:55]
	v_mfma_f32_16x16x32_bf16 v[48:51], v[172:175], v[180:183], v[48:51]
	v_mfma_f32_16x16x32_bf16 v[36:39], v[144:147], v[196:199], v[36:39]
	v_mfma_f32_16x16x32_bf16 v[32:35], v[172:175], v[196:199], v[32:35]
	v_mfma_f32_16x16x32_bf16 v[20:23], v[144:147], v[204:207], v[20:23]
	v_mfma_f32_16x16x32_bf16 v[16:19], v[172:175], v[204:207], v[16:19]
	v_mfma_f32_16x16x32_bf16 v[4:7], v[144:147], v[212:215], v[4:7]
	v_mfma_f32_16x16x32_bf16 v[0:3], v[172:175], v[212:215], v[0:3]
	v_mfma_f32_16x16x32_bf16 v[52:55], v[148:151], v[192:195], v[52:55]
	v_mfma_f32_16x16x32_bf16 v[48:51], v[176:179], v[192:195], v[48:51]
	v_mfma_f32_16x16x32_bf16 v[36:39], v[148:151], v[200:203], v[36:39]
	v_mfma_f32_16x16x32_bf16 v[32:35], v[176:179], v[200:203], v[32:35]
	v_mfma_f32_16x16x32_bf16 v[20:23], v[148:151], v[208:211], v[20:23]
	v_mfma_f32_16x16x32_bf16 v[16:19], v[176:179], v[208:211], v[16:19]
	v_mfma_f32_16x16x32_bf16 v[4:7], v[148:151], v[216:219], v[4:7]
	v_mfma_f32_16x16x32_bf16 v[0:3], v[176:179], v[216:219], v[0:3]
	s_setprio 0
	s_barrier
	s_add_i32 s80, s80, 2
	s_add_u32 s78, s78, 0x100
	s_addc_u32 s79, s79, 0
	s_add_u32 s58, s58, 0x100
	s_addc_u32 s59, s59, 0
	s_cmp_gt_u32 s80, 13
	s_cbranch_scc0 .LBB0_1011
	s_and_b64 vcc, exec, s[28:29]
	s_cbranch_vccz .LBB0_1014
	s_barrier

.LBB0_1088:
	s_or_b64 exec, exec, s[6:7]
	s_mov_b64 s[6:7], s[0:1]
	v_mov_b32_e32 v8, v157
	s_waitcnt lgkmcnt(0)
	s_barrier
	s_and_b64 vcc, exec, s[8:9]
	v_readfirstlane_b32 s20, v8
	s_cbranch_vccnz .LBB0_1106
	v_lshlrev_b32_e32 v0, 4, v8
	v_add_u32_e32 v1, 0x2000, v0
	v_ashrrev_i32_e32 v2, 31, v1
	v_lshrrev_b32_e32 v2, 22, v2
	v_add_u32_e32 v2, v1, v2
	v_ashrrev_i32_e32 v9, 10, v2
	v_mul_i32_i24_e32 v2, 0x400, v9
	v_sub_u32_e32 v1, v1, v2
	v_lshrrev_b32_e32 v2, 4, v1
	v_bitop3_b32 v1, v2, v1, 32 bitop3:0x6c
	v_ashrrev_i32_e32 v2, 31, v1
	v_lshrrev_b32_e32 v2, 26, v2
	v_add_u32_e32 v2, v1, v2
	v_lshlrev_b32_e32 v3, 3, v9
	v_ashrrev_i32_e32 v10, 6, v2
	v_and_b32_e32 v3, -16, v3
	v_add_u32_e32 v3, v10, v3
	v_and_b32_e32 v4, 3, v10
	s_mov_b32 s8, 0x1fffe0
	v_lshrrev_b32_e32 v5, 2, v3
	v_lshlrev_b32_e32 v6, 1, v3
	v_and_b32_e32 v2, 0xc0, v2
	v_and_or_b32 v4, v3, s8, v4
	v_and_b32_e32 v5, 4, v5
	v_and_b32_e32 v6, 24, v6
	v_sub_u32_e32 v1, v1, v2
	v_mov_b32_e32 v2, 1
	v_or3_b32 v4, v4, v5, v6
	v_lshlrev_b32_e32 v5, 5, v9
	v_ashrrev_i16_sdwa v1, v2, sext(v1) dst_sel:DWORD dst_unused:UNUSED_PAD src0_sel:DWORD src1_sel:BYTE_0
	v_and_b32_e32 v5, 32, v5
	v_bfe_i32 v11, v1, 0, 16
	v_add_lshl_u32 v1, v5, v11, 1
	v_lshl_add_u32 v128, v4, 11, v1
	v_lshrrev_b32_e32 v250, 3, v157
	v_and_b32_e32 v251, 6, v250
	v_and_b32_e32 v252, 7, v157
	v_xor_b32_e32 v251, v251, v252
	v_lshlrev_b32_e32 v251, 4, v251
	v_and_b32_e32 v252, 12, v250
	v_lshlrev_b32_e32 v252, 1, v252
	v_and_b32_e32 v253, 16, v250
	v_lshrrev_b32_e32 v253, 2, v253
	v_or_b32_e32 v252, v252, v253
	v_and_b32_e32 v253, 35, v250
	v_or_b32_e32 v250, v252, v253
	v_mul_u32_u24_e32 v250, 0x800, v250
	v_add_u32_e32 v128, v250, v251
	v_add_u32_e32 v128, 0x20000, v128
	v_lshl_add_u32 v130, v3, 11, v1
	v_lshrrev_b32_e32 v250, 3, v157
	v_and_b32_e32 v251, 6, v250
	v_and_b32_e32 v252, 7, v157
	v_xor_b32_e32 v251, v251, v252
	v_lshlrev_b32_e32 v251, 4, v251
	v_mul_u32_u24_e32 v250, 0x800, v250
	v_add_u32_e32 v130, v250, v251
	v_add_u32_e32 v130, 0x20000, v130
	v_bfe_i32 v1, v8, 27, 1
	v_lshrrev_b32_e32 v1, 22, v1
	v_add_u32_e32 v1, v0, v1
	s_load_dwordx2 s[6:7], s[6:7], 0x80
	v_and_b32_e32 v1, 0xfffffc00, v1
	v_sub_u32_e32 v0, v0, v1
	v_lshrrev_b32_e32 v1, 4, v0
	v_ashrrev_i32_e32 v3, 31, v8
	v_bitop3_b32 v0, v1, v0, 32 bitop3:0x6c
	v_lshrrev_b32_e32 v3, 26, v3
	v_ashrrev_i32_e32 v1, 31, v0
	v_add_u32_e32 v3, v8, v3
	s_waitcnt lgkmcnt(0)
	s_add_u32 s3, s6, 0x6000000
	v_lshrrev_b32_e32 v1, 26, v1
	v_ashrrev_i32_e32 v13, 6, v3
	s_addc_u32 s33, s7, 0
	v_add_u32_e32 v1, v0, v1
	v_lshlrev_b32_e32 v3, 3, v13
	s_add_u32 s35, s6, 0x2500000
	v_ashrrev_i32_e32 v12, 6, v1
	v_and_b32_e32 v3, -16, v3
	s_addc_u32 s48, s7, 0
	v_add_u32_e32 v3, v12, v3
	v_and_b32_e32 v4, 3, v12
	s_ashr_i32 s50, s2, 31
	v_and_or_b32 v4, v3, s8, v4
	s_lshr_b32 s8, s50, 29
	s_add_i32 s8, s2, s8
	s_ashr_i32 s17, s20, 6
	s_ashr_i32 s9, s8, 3
	s_and_b32 s8, s8, -8
	s_ashr_i32 s21, s20, 8
	s_lshl_b32 s49, s17, 10
	s_sub_i32 s8, s2, s8
	s_cmp_lt_i32 s8, 0
	s_movk_i32 s51, 0x161
	s_cselect_b32 s10, s51, 0x160
	s_mul_i32 s8, s10, s8
	s_add_i32 s8, s8, s9
	s_mul_hi_i32 s9, s8, 0x2e8ba2e9
	s_lshr_b32 s10, s9, 31
	s_ashr_i32 s9, s9, 3
	s_add_i32 s9, s9, s10
	s_lshl_b32 s10, s9, 1
	s_mul_i32 s9, s9, 44
	s_sub_i32 s8, s8, s9
	s_bfe_u32 s9, s8, 0x10007
	s_add_i32 s9, s8, s9
	s_bfe_i32 s11, s9, 0x80000
	s_and_b32 s9, s9, 0xfe
	s_sub_i32 s8, s8, s9
	s_sext_i32_i16 s11, s11
	s_sext_i32_i8 s8, s8
	v_lshrrev_b32_e32 v5, 2, v3
	v_lshlrev_b32_e32 v6, 1, v3
	v_and_b32_e32 v1, 0xc0, v1
	s_lshr_b32 s16, s11, 1
	s_add_i32 s30, s10, s8
	v_and_b32_e32 v5, 4, v5
	v_and_b32_e32 v6, 24, v6
	v_sub_u32_e32 v0, v0, v1
	s_ashr_i32 s31, s30, 31
	s_bfe_i64 s[10:11], s[16:17], 0x100000
	v_or3_b32 v4, v4, v5, v6
	v_lshlrev_b32_e32 v5, 5, v13
	v_ashrrev_i16_sdwa v0, v2, sext(v0) dst_sel:DWORD dst_unused:UNUSED_PAD src0_sel:DWORD src1_sel:BYTE_0
	s_lshl_b64 s[8:9], s[30:31], 19
	s_lshl_b64 s[10:11], s[10:11], 19
	v_and_b32_e32 v5, 32, v5
	v_bfe_i32 v14, v0, 0, 16
	s_add_u32 s44, s35, s10
	v_add_lshl_u32 v0, v5, v14, 1
	s_addc_u32 s45, s48, s11
	s_add_i32 s52, s49, 0
	v_lshl_add_u32 v132, v4, 11, v0
	v_lshrrev_b32_e32 v250, 3, v157
	v_and_b32_e32 v251, 6, v250
	v_and_b32_e32 v252, 7, v157
	v_xor_b32_e32 v251, v251, v252
	v_lshlrev_b32_e32 v251, 4, v251
	v_and_b32_e32 v252, 12, v250
	v_lshlrev_b32_e32 v252, 1, v252
	v_and_b32_e32 v253, 16, v250
	v_lshrrev_b32_e32 v253, 2, v253
	v_or_b32_e32 v252, v252, v253
	v_and_b32_e32 v253, 35, v250
	v_or_b32_e32 v250, v252, v253
	v_mul_u32_u24_e32 v250, 0x800, v250
	v_add_u32_e32 v132, v250, v251
	s_add_i32 m0, s52, 0x10000
	v_lshl_add_u32 v134, v3, 11, v0
	v_lshrrev_b32_e32 v250, 3, v157
	v_and_b32_e32 v251, 6, v250
	v_and_b32_e32 v252, 7, v157
	v_xor_b32_e32 v251, v251, v252
	v_lshlrev_b32_e32 v251, 4, v251
	v_mul_u32_u24_e32 v250, 0x800, v250
	v_add_u32_e32 v134, v250, v251
	global_load_lds_dwordx4 v132, s[44:45]
	s_add_i32 m0, s52, 0x12000
	s_add_u32 s10, s44, 0x40000
	global_load_lds_dwordx4 v128, s[44:45]
	s_addc_u32 s11, s45, 0
	s_add_i32 m0, s52, 0x14000
	v_mov_b32_e32 v133, 0
	global_load_lds_dwordx4 v132, s[10:11]
	s_add_i32 m0, s52, 0x16000
	s_add_u32 s46, s3, s8
	s_addc_u32 s47, s33, s9
	s_add_i32 s53, s52, 0x2000
	global_load_lds_dwordx4 v128, s[10:11]
	s_mov_b32 m0, s52
	s_add_u32 s8, s46, 0x40000
	global_load_lds_dwordx4 v134, s[46:47]
	s_mov_b32 m0, s53
	s_addc_u32 s9, s47, 0
	s_add_i32 s54, s52, 0x4000
	global_load_lds_dwordx4 v130, s[46:47]
	s_mov_b32 m0, s54
	s_add_i32 s55, s52, 0x6000
	global_load_lds_dwordx4 v134, s[8:9]
	s_mov_b32 m0, s55
	v_mov_b32_e32 v129, v133
	global_load_lds_dwordx4 v130, s[8:9]
	v_mov_b32_e32 v135, v133
	v_mov_b32_e32 v131, v133
	s_cmp_eq_u32 s21, 1
	s_mov_b32 s56, 0
	v_lshl_add_u64 v[6:7], s[44:45], 0, v[132:133]
	v_lshl_add_u64 v[4:5], s[44:45], 0, v[128:129]
	v_lshl_add_u64 v[0:1], s[46:47], 0, v[134:135]
	s_cselect_b64 s[8:9], -1, 0
	s_cmp_lg_u32 s21, 1
	v_lshl_add_u64 v[2:3], s[46:47], 0, v[130:131]
	s_cbranch_scc1 .LBB0_1091
	s_barrier
.LBB0_1091:
	s_add_u32 s10, s6, 0xa000000
	s_addc_u32 s11, s7, 0
	s_add_u32 s12, s6, 0x100000
	s_addc_u32 s13, s7, 0
	s_lshl_b32 s6, s17, 5
	s_mov_b64 s[14:15], 0x80
	s_and_b32 s23, s6, 0x60
	s_add_i32 m0, s52, 0x18000
	v_lshl_add_u64 v[6:7], v[6:7], 0, s[14:15]
	s_lshl_b32 s22, s21, 13
	s_lshl_b32 s24, s23, 7
	s_waitcnt vmcnt(2)
	s_barrier
	global_load_lds_dwordx4 v[6:7], off
	v_lshl_add_u64 v[4:5], v[4:5], 0, s[14:15]
	s_add_i32 m0, s52, 0x1a000
	s_add_i32 s57, s52, 0x8000
	s_add_i32 s58, s52, 0xa000
	global_load_lds_dwordx4 v[4:5], off
	v_lshl_add_u64 v[0:1], v[0:1], 0, s[14:15]
	s_mov_b32 m0, s57
	s_add_u32 s6, s44, 0x40080
	global_load_lds_dwordx4 v[0:1], off
	v_lshl_add_u64 v[0:1], v[2:3], 0, s[14:15]
	s_mov_b32 m0, s58
	s_addc_u32 s7, s45, 0
	global_load_lds_dwordx4 v[0:1], off
	s_add_i32 m0, s52, 0x1c000
	v_lshl_add_u64 v[0:1], s[6:7], 0, v[132:133]
	global_load_lds_dwordx4 v[0:1], off
	v_lshl_add_u64 v[0:1], s[6:7], 0, v[128:129]
	s_add_i32 m0, s52, 0x1e000
	s_cmp_lt_i32 s17, 4
	global_load_lds_dwordx4 v[0:1], off
	v_lshrrev_b32_e32 v1, 1, v8
	v_and_b32_e32 v1, 24, v1
	v_and_b32_e32 v0, 15, v8
	v_lshlrev_b32_e32 v2, 1, v1
	v_lshl_or_b32 v146, s21, 6, v0
	v_lshl_or_b32 v0, v0, 6, v2
	v_lshlrev_b32_e32 v2, 2, v8
	v_or_b32_e32 v149, s23, v1
	v_lshlrev_b32_e32 v1, 14, v9
	v_and_b32_e32 v2, 32, v2
	v_and_b32_e32 v1, 0xffff8000, v1
	v_bitop3_b32 v3, v0, s22, v2 bitop3:0xde
	v_bitop3_b32 v147, v0, s24, v2 bitop3:0xde
	v_and_b32_e32 v250, 15, v157
	v_bfe_u32 v251, v157, 4, 2
	v_and_b32_e32 v252, 2, v250
	v_xor_b32_e32 v251, v251, v252
	v_and_b32_e32 v252, 4, v250
	v_lshlrev_b32_e32 v252, 4, v252
	v_lshl_or_b32 v251, v251, 4, v252
	v_lshl_or_b32 v250, v250, 7, v251
	v_bfe_u32 v253, v157, 6, 2
	v_lshl_or_b32 v147, v253, 12, v250
	v_lshl_add_u32 v1, v10, 11, v1
	v_and_b32_e32 v2, 1, v9
	v_lshl_or_b32 v1, v2, 6, v1
	v_lshl_add_u32 v136, v11, 1, v1
	v_lshrrev_b32_e32 v250, 3, v157
	v_and_b32_e32 v251, 6, v250
	v_and_b32_e32 v252, 7, v157
	v_xor_b32_e32 v251, v251, v252
	v_lshlrev_b32_e32 v251, 4, v251
	v_mul_u32_u24_e32 v250, 0x800, v250
	v_add_u32_e32 v136, v250, v251
	v_add_u32_e32 v136, 0x20000, v136
	v_lshlrev_b32_e32 v1, 14, v13
	v_and_b32_e32 v1, 0xffff8000, v1
	s_waitcnt vmcnt(6)
	s_movk_i32 s6, 0xffc0
	v_mov_b32_e32 v0, s20
	v_lshl_add_u32 v1, v12, 11, v1
	v_and_b32_e32 v2, 1, v13
	s_sext_i32_i8 s64, s16
	s_cselect_b64 s[16:17], -1, 0
	v_bfi_b32 v148, s6, v0, v8
	s_cmpk_lt_u32 s20, 0x100
	v_lshlrev_b32_e32 v0, 4, v146
	v_lshl_or_b32 v1, v2, 6, v1
	s_cselect_b64 s[20:21], -1, 0
	s_ashr_i32 s59, s42, 31
	s_mov_b32 s60, s42
	v_mov_b32_e32 v137, v133
	v_lshl_add_u32 v138, v14, 1, v1
	v_lshrrev_b32_e32 v250, 3, v157
	v_and_b32_e32 v251, 6, v250
	v_and_b32_e32 v252, 7, v157
	v_xor_b32_e32 v251, v251, v252
	v_lshlrev_b32_e32 v251, 4, v251
	v_mul_u32_u24_e32 v250, 0x800, v250
	v_add_u32_e32 v138, v250, v251
	v_mov_b32_e32 v139, v133
	v_mov_b64_e32 v[140:141], 0xb00
	v_mov_b64_e32 v[142:143], 0xaff
	s_add_i32 s61, 0, 0x10000
	s_add_i32 s62, 0, 0x14000
	v_add_u32_e32 v150, 0, v3
	v_and_b32_e32 v250, 15, v157
	v_bfe_u32 v251, v157, 4, 2
	v_and_b32_e32 v252, 2, v250
	v_xor_b32_e32 v251, v251, v252
	v_and_b32_e32 v252, 4, v250
	v_lshlrev_b32_e32 v252, 4, v252
	v_lshl_or_b32 v251, v251, 4, v252
	v_lshl_or_b32 v250, v250, 7, v251
	v_lshrrev_b32_e32 v253, 8, v157
	v_lshl_or_b32 v150, v253, 13, v250
	v_add_u32_e32 v151, 0, v0
	v_mov_b32_e32 v152, 0x358637bd
	s_movk_i32 s63, 0x1600
	s_barrier
	s_branch .LBB0_1094

.LBB0_1096:
	s_ashr_i32 s25, s24, 31
	s_lshl_b64 s[26:27], s[24:25], 19
	s_add_u32 s26, s3, s26
	s_addc_u32 s27, s33, s27
	s_and_b64 s[28:29], s[6:7], exec
	s_cselect_b32 s25, s27, s47
	s_cselect_b32 s65, s26, s46
	s_ashr_i32 s23, s22, 31
	s_lshl_b64 s[28:29], s[22:23], 19
	s_add_u32 s28, s35, s28
	s_addc_u32 s29, s48, s29
	s_and_b64 s[66:67], s[6:7], exec
	s_cselect_b32 s66, s29, s45
	s_cselect_b32 s67, s28, s44
	s_lshl_b32 s23, s30, 8
	v_add_u32_e32 v0, s23, v148
	s_add_u32 s68, s44, 0x100
	v_ashrrev_i32_e32 v1, 31, v0
	s_addc_u32 s69, s45, 0
	v_lshl_add_u64 v[144:145], v[0:1], 4, s[12:13]
	s_add_u32 s30, s46, 0x40080
	s_addc_u32 s31, s47, 0
	s_mov_b32 s70, -2
	s_mov_b64 s[44:45], 0
	s_cmp_eq_u32 s56, 1
	s_cbranch_scc1 .Lfa_10
	v_add_u32_e32 v153, s61, v147
	ds_read_b128 v[160:163], v153
	v_xor_b32_e32 v253, 64, v153
	ds_read_b128 v[164:167], v253
	ds_read_b128 v[168:171], v153 offset:2048
	ds_read_b128 v[172:175], v253 offset:2048
	v_add_u32_e32 v153, s62, v147
	ds_read_b128 v[176:179], v153
	v_xor_b32_e32 v253, 64, v153
	ds_read_b128 v[180:183], v253
	ds_read_b128 v[184:187], v153 offset:2048
	ds_read_b128 v[188:191], v253 offset:2048
	s_add_u32 s46, s30, 0xfffc0080
	s_addc_u32 s47, s31, -1
	s_and_b64 s[44:45], s[44:45], exec
	s_cselect_b32 s47, s25, s47
	s_cselect_b32 s46, s65, s46
	s_cselect_b32 s45, s66, s69
	s_cselect_b32 s44, s67, s68
	v_lshl_add_u64 v[154:155], s[30:31], 0, v[138:139]
	s_add_i32 m0, s52, 0xc000
	ds_read_b128 v[192:195], v150
	v_xor_b32_e32 v253, 64, v150
	ds_read_b128 v[196:199], v253
	ds_read_b128 v[200:203], v150 offset:2048
	ds_read_b128 v[204:207], v253 offset:2048
	ds_read_b128 v[208:211], v150 offset:4096
	ds_read_b128 v[212:215], v253 offset:4096
	ds_read_b128 v[216:219], v150 offset:6144
	ds_read_b128 v[220:223], v253 offset:6144
	global_load_lds_dwordx4 v[154:155], off
	v_lshl_add_u64 v[154:155], s[30:31], 0, v[136:137]
	s_add_i32 m0, s52, 0xe000
	s_nop 0
	global_load_lds_dwordx4 v[154:155], off
	s_waitcnt vmcnt(16)
	s_waitcnt lgkmcnt(0)
	s_barrier
	s_setprio 1
	s_waitcnt lgkmcnt(0)
	v_mfma_f32_16x16x32_bf16 v[124:127], v[160:163], v[192:195], 0
	v_mfma_f32_16x16x32_bf16 v[116:119], v[168:171], v[192:195], 0
	v_mfma_f32_16x16x32_bf16 v[108:111], v[160:163], v[200:203], 0
	v_mfma_f32_16x16x32_bf16 v[100:103], v[168:171], v[200:203], 0
	v_mfma_f32_16x16x32_bf16 v[92:95], v[160:163], v[208:211], 0
	v_mfma_f32_16x16x32_bf16 v[84:87], v[168:171], v[208:211], 0
	v_mfma_f32_16x16x32_bf16 v[76:79], v[160:163], v[216:219], 0
	v_mfma_f32_16x16x32_bf16 v[68:71], v[168:171], v[216:219], 0
	v_mfma_f32_16x16x32_bf16 v[124:127], v[164:167], v[196:199], v[124:127]
	v_mfma_f32_16x16x32_bf16 v[116:119], v[172:175], v[196:199], v[116:119]
	v_mfma_f32_16x16x32_bf16 v[108:111], v[164:167], v[204:207], v[108:111]
	v_mfma_f32_16x16x32_bf16 v[100:103], v[172:175], v[204:207], v[100:103]
	v_mfma_f32_16x16x32_bf16 v[92:95], v[164:167], v[212:215], v[92:95]
	v_mfma_f32_16x16x32_bf16 v[84:87], v[172:175], v[212:215], v[84:87]
	v_mfma_f32_16x16x32_bf16 v[76:79], v[164:167], v[220:223], v[76:79]
	v_mfma_f32_16x16x32_bf16 v[68:71], v[172:175], v[220:223], v[68:71]
	s_setprio 0
	s_setprio 1
	v_mfma_f32_16x16x32_bf16 v[120:123], v[176:179], v[192:195], 0
	v_mfma_f32_16x16x32_bf16 v[112:115], v[184:187], v[192:195], 0
	v_mfma_f32_16x16x32_bf16 v[104:107], v[176:179], v[200:203], 0
	v_mfma_f32_16x16x32_bf16 v[96:99], v[184:187], v[200:203], 0
	v_mfma_f32_16x16x32_bf16 v[88:91], v[176:179], v[208:211], 0
	v_mfma_f32_16x16x32_bf16 v[80:83], v[184:187], v[208:211], 0
	v_mfma_f32_16x16x32_bf16 v[72:75], v[176:179], v[216:219], 0
	v_mfma_f32_16x16x32_bf16 v[64:67], v[184:187], v[216:219], 0
	v_mfma_f32_16x16x32_bf16 v[120:123], v[180:183], v[196:199], v[120:123]
	v_mfma_f32_16x16x32_bf16 v[112:115], v[188:191], v[196:199], v[112:115]
	v_mfma_f32_16x16x32_bf16 v[104:107], v[180:183], v[204:207], v[104:107]
	v_mfma_f32_16x16x32_bf16 v[96:99], v[188:191], v[204:207], v[96:99]
	v_mfma_f32_16x16x32_bf16 v[88:91], v[180:183], v[212:215], v[88:91]
	v_mfma_f32_16x16x32_bf16 v[80:83], v[188:191], v[212:215], v[80:83]
	v_mfma_f32_16x16x32_bf16 v[72:75], v[180:183], v[220:223], v[72:75]
	v_mfma_f32_16x16x32_bf16 v[64:67], v[188:191], v[220:223], v[64:67]
	s_setprio 0
	s_barrier
	s_add_i32 s71, s61, s49
	v_lshl_add_u64 v[154:155], s[44:45], 0, v[132:133]
	s_mov_b32 m0, s71
	ds_read_b128 v[192:195], v150 offset:16384
	v_xor_b32_e32 v253, 64, v150
	ds_read_b128 v[196:199], v253 offset:16384
	ds_read_b128 v[200:203], v150 offset:18432
	ds_read_b128 v[204:207], v253 offset:18432
	ds_read_b128 v[208:211], v150 offset:20480
	ds_read_b128 v[212:215], v253 offset:20480
	ds_read_b128 v[216:219], v150 offset:22528
	ds_read_b128 v[220:223], v253 offset:22528
	global_load_lds_dwordx4 v[154:155], off
	s_add_i32 m0, s71, 0x2000
	s_add_u32 s72, s44, 0x40000
	v_lshl_add_u64 v[224:225], s[44:45], 0, v[128:129]
	s_addc_u32 s73, s45, 0
	s_add_i32 s71, s62, s49
	global_load_lds_dwordx4 v[224:225], off
	v_lshl_add_u64 v[226:227], s[72:73], 0, v[132:133]
	s_mov_b32 m0, s71
	v_lshl_add_u64 v[228:229], s[46:47], 0, v[130:131]
	global_load_lds_dwordx4 v[226:227], off
	v_lshl_add_u64 v[226:227], s[72:73], 0, v[128:129]
	s_add_i32 m0, s71, 0x2000
	s_nop 0
	global_load_lds_dwordx4 v[226:227], off
	v_lshl_add_u64 v[226:227], s[46:47], 0, v[134:135]
	s_mov_b32 m0, s52
	s_nop 0
	global_load_lds_dwordx4 v[226:227], off
	s_mov_b32 m0, s53
	s_nop 0
	global_load_lds_dwordx4 v[228:229], off
	s_waitcnt vmcnt(16)
	s_waitcnt lgkmcnt(0)
	s_barrier
	s_setprio 1
	s_waitcnt lgkmcnt(0)
	v_mfma_f32_16x16x32_bf16 v[60:63], v[160:163], v[192:195], 0
	v_mfma_f32_16x16x32_bf16 v[52:55], v[168:171], v[192:195], 0
	v_mfma_f32_16x16x32_bf16 v[44:47], v[160:163], v[200:203], 0
	v_mfma_f32_16x16x32_bf16 v[36:39], v[168:171], v[200:203], 0
	v_mfma_f32_16x16x32_bf16 v[28:31], v[160:163], v[208:211], 0
	v_mfma_f32_16x16x32_bf16 v[20:23], v[168:171], v[208:211], 0
	v_mfma_f32_16x16x32_bf16 v[12:15], v[160:163], v[216:219], 0
	v_mfma_f32_16x16x32_bf16 v[4:7], v[168:171], v[216:219], 0
	v_mfma_f32_16x16x32_bf16 v[60:63], v[164:167], v[196:199], v[60:63]
	v_mfma_f32_16x16x32_bf16 v[52:55], v[172:175], v[196:199], v[52:55]
	v_mfma_f32_16x16x32_bf16 v[44:47], v[164:167], v[204:207], v[44:47]
	v_mfma_f32_16x16x32_bf16 v[36:39], v[172:175], v[204:207], v[36:39]
	v_mfma_f32_16x16x32_bf16 v[28:31], v[164:167], v[212:215], v[28:31]
	v_mfma_f32_16x16x32_bf16 v[20:23], v[172:175], v[212:215], v[20:23]
	v_mfma_f32_16x16x32_bf16 v[12:15], v[164:167], v[220:223], v[12:15]
	v_mfma_f32_16x16x32_bf16 v[4:7], v[172:175], v[220:223], v[4:7]
	s_setprio 0
	s_setprio 1
	v_mfma_f32_16x16x32_bf16 v[56:59], v[176:179], v[192:195], 0
	v_mfma_f32_16x16x32_bf16 v[48:51], v[184:187], v[192:195], 0
	v_mfma_f32_16x16x32_bf16 v[40:43], v[176:179], v[200:203], 0
	v_mfma_f32_16x16x32_bf16 v[32:35], v[184:187], v[200:203], 0
	v_mfma_f32_16x16x32_bf16 v[24:27], v[176:179], v[208:211], 0
	v_mfma_f32_16x16x32_bf16 v[16:19], v[184:187], v[208:211], 0
	v_mfma_f32_16x16x32_bf16 v[8:11], v[176:179], v[216:219], 0
	v_mfma_f32_16x16x32_bf16 v[0:3], v[184:187], v[216:219], 0
	v_mfma_f32_16x16x32_bf16 v[56:59], v[180:183], v[196:199], v[56:59]
	v_mfma_f32_16x16x32_bf16 v[48:51], v[188:191], v[196:199], v[48:51]
	v_mfma_f32_16x16x32_bf16 v[40:43], v[180:183], v[204:207], v[40:43]
	v_mfma_f32_16x16x32_bf16 v[32:35], v[188:191], v[204:207], v[32:35]
	v_mfma_f32_16x16x32_bf16 v[24:27], v[180:183], v[212:215], v[24:27]
	v_mfma_f32_16x16x32_bf16 v[16:19], v[188:191], v[212:215], v[16:19]
	v_mfma_f32_16x16x32_bf16 v[8:11], v[180:183], v[220:223], v[8:11]
	v_mfma_f32_16x16x32_bf16 v[0:3], v[188:191], v[220:223], v[0:3]
	s_setprio 0
	s_barrier
	s_add_i32 s71, 0, 0x18000
	v_add_u32_e32 v153, s71, v147
	s_add_i32 s72, 0, 0x1c000
	ds_read_b128 v[160:163], v153
	v_xor_b32_e32 v253, 64, v153
	ds_read_b128 v[164:167], v253
	ds_read_b128 v[168:171], v153 offset:2048
	ds_read_b128 v[172:175], v253 offset:2048
	v_add_u32_e32 v153, s72, v147
	ds_read_b128 v[176:179], v153
	v_xor_b32_e32 v253, 64, v153
	ds_read_b128 v[180:183], v253
	ds_read_b128 v[184:187], v153 offset:2048
	ds_read_b128 v[188:191], v253 offset:2048
	s_add_u32 s46, s46, 0x40000
	s_addc_u32 s47, s47, 0
	s_mov_b32 m0, s54
	v_lshl_add_u64 v[230:231], s[46:47], 0, v[134:135]
	ds_read_b128 v[192:195], v150 offset:32768
	v_xor_b32_e32 v253, 64, v150
	ds_read_b128 v[196:199], v253 offset:32768
	ds_read_b128 v[200:203], v150 offset:34816
	ds_read_b128 v[204:207], v253 offset:34816
	ds_read_b128 v[208:211], v150 offset:36864
	ds_read_b128 v[212:215], v253 offset:36864
	ds_read_b128 v[216:219], v150 offset:38912
	ds_read_b128 v[220:223], v253 offset:38912
	global_load_lds_dwordx4 v[230:231], off
	v_lshl_add_u64 v[230:231], s[46:47], 0, v[130:131]
	s_mov_b32 m0, s55
	s_nop 0
	global_load_lds_dwordx4 v[230:231], off
	s_waitcnt vmcnt(8)
	s_waitcnt lgkmcnt(0)
	s_barrier
	s_setprio 1
	s_waitcnt lgkmcnt(0)
	v_mfma_f32_16x16x32_bf16 v[124:127], v[160:163], v[192:195], v[124:127]
	v_mfma_f32_16x16x32_bf16 v[116:119], v[168:171], v[192:195], v[116:119]
	v_mfma_f32_16x16x32_bf16 v[108:111], v[160:163], v[200:203], v[108:111]
	v_mfma_f32_16x16x32_bf16 v[100:103], v[168:171], v[200:203], v[100:103]
	v_mfma_f32_16x16x32_bf16 v[92:95], v[160:163], v[208:211], v[92:95]
	v_mfma_f32_16x16x32_bf16 v[84:87], v[168:171], v[208:211], v[84:87]
	v_mfma_f32_16x16x32_bf16 v[76:79], v[160:163], v[216:219], v[76:79]
	v_mfma_f32_16x16x32_bf16 v[68:71], v[168:171], v[216:219], v[68:71]
	v_mfma_f32_16x16x32_bf16 v[124:127], v[164:167], v[196:199], v[124:127]
	v_mfma_f32_16x16x32_bf16 v[116:119], v[172:175], v[196:199], v[116:119]
	v_mfma_f32_16x16x32_bf16 v[108:111], v[164:167], v[204:207], v[108:111]
	v_mfma_f32_16x16x32_bf16 v[100:103], v[172:175], v[204:207], v[100:103]
	v_mfma_f32_16x16x32_bf16 v[92:95], v[164:167], v[212:215], v[92:95]
	v_mfma_f32_16x16x32_bf16 v[84:87], v[172:175], v[212:215], v[84:87]
	v_mfma_f32_16x16x32_bf16 v[76:79], v[164:167], v[220:223], v[76:79]
	v_mfma_f32_16x16x32_bf16 v[68:71], v[172:175], v[220:223], v[68:71]
	s_setprio 0
	s_setprio 1
	v_mfma_f32_16x16x32_bf16 v[120:123], v[176:179], v[192:195], v[120:123]
	v_mfma_f32_16x16x32_bf16 v[112:115], v[184:187], v[192:195], v[112:115]
	v_mfma_f32_16x16x32_bf16 v[104:107], v[176:179], v[200:203], v[104:107]
	v_mfma_f32_16x16x32_bf16 v[96:99], v[184:187], v[200:203], v[96:99]
	v_mfma_f32_16x16x32_bf16 v[88:91], v[176:179], v[208:211], v[88:91]
	v_mfma_f32_16x16x32_bf16 v[80:83], v[184:187], v[208:211], v[80:83]
	v_mfma_f32_16x16x32_bf16 v[72:75], v[176:179], v[216:219], v[72:75]
	v_mfma_f32_16x16x32_bf16 v[64:67], v[184:187], v[216:219], v[64:67]
	v_mfma_f32_16x16x32_bf16 v[120:123], v[180:183], v[196:199], v[120:123]
	v_mfma_f32_16x16x32_bf16 v[112:115], v[188:191], v[196:199], v[112:115]
	v_mfma_f32_16x16x32_bf16 v[104:107], v[180:183], v[204:207], v[104:107]
	v_mfma_f32_16x16x32_bf16 v[96:99], v[188:191], v[204:207], v[96:99]
	v_mfma_f32_16x16x32_bf16 v[88:91], v[180:183], v[212:215], v[88:91]
	v_mfma_f32_16x16x32_bf16 v[80:83], v[188:191], v[212:215], v[80:83]
	v_mfma_f32_16x16x32_bf16 v[72:75], v[180:183], v[220:223], v[72:75]
	v_mfma_f32_16x16x32_bf16 v[64:67], v[188:191], v[220:223], v[64:67]
	s_setprio 0
	s_barrier
	s_add_i32 s46, s71, s49
	v_lshl_add_u64 v[154:155], v[154:155], 0, s[14:15]
	s_mov_b32 m0, s46
	ds_read_b128 v[192:195], v150 offset:49152
	v_xor_b32_e32 v253, 64, v150
	ds_read_b128 v[196:199], v253 offset:49152
	ds_read_b128 v[200:203], v150 offset:51200
	ds_read_b128 v[204:207], v253 offset:51200
	ds_read_b128 v[208:211], v150 offset:53248
	ds_read_b128 v[212:215], v253 offset:53248
	ds_read_b128 v[216:219], v150 offset:55296
	ds_read_b128 v[220:223], v253 offset:55296
	global_load_lds_dwordx4 v[154:155], off
	s_add_i32 m0, s46, 0x2000
	s_add_u32 s44, s44, 0x40080
	v_lshl_add_u64 v[154:155], v[224:225], 0, s[14:15]
	s_addc_u32 s45, s45, 0
	s_add_i32 s46, s72, s49
	global_load_lds_dwordx4 v[154:155], off
	v_lshl_add_u64 v[154:155], s[44:45], 0, v[132:133]
	s_mov_b32 m0, s46
	s_nop 0
	global_load_lds_dwordx4 v[154:155], off
	v_lshl_add_u64 v[154:155], s[44:45], 0, v[128:129]
	s_add_i32 m0, s46, 0x2000
	s_nop 0
	global_load_lds_dwordx4 v[154:155], off
	v_lshl_add_u64 v[154:155], v[226:227], 0, s[14:15]
	s_mov_b32 m0, s57
	s_nop 0
	global_load_lds_dwordx4 v[154:155], off
	v_lshl_add_u64 v[154:155], v[228:229], 0, s[14:15]
	s_mov_b32 m0, s58
	s_nop 0
	global_load_lds_dwordx4 v[154:155], off
	s_waitcnt vmcnt(8)
	s_waitcnt lgkmcnt(0)
	s_barrier
	s_setprio 1
	s_waitcnt lgkmcnt(0)
	v_mfma_f32_16x16x32_bf16 v[60:63], v[160:163], v[192:195], v[60:63]
	v_mfma_f32_16x16x32_bf16 v[52:55], v[168:171], v[192:195], v[52:55]
	v_mfma_f32_16x16x32_bf16 v[44:47], v[160:163], v[200:203], v[44:47]
	v_mfma_f32_16x16x32_bf16 v[36:39], v[168:171], v[200:203], v[36:39]
	v_mfma_f32_16x16x32_bf16 v[28:31], v[160:163], v[208:211], v[28:31]
	v_mfma_f32_16x16x32_bf16 v[20:23], v[168:171], v[208:211], v[20:23]
	v_mfma_f32_16x16x32_bf16 v[12:15], v[160:163], v[216:219], v[12:15]
	v_mfma_f32_16x16x32_bf16 v[4:7], v[168:171], v[216:219], v[4:7]
	v_mfma_f32_16x16x32_bf16 v[60:63], v[164:167], v[196:199], v[60:63]
	v_mfma_f32_16x16x32_bf16 v[52:55], v[172:175], v[196:199], v[52:55]
	v_mfma_f32_16x16x32_bf16 v[44:47], v[164:167], v[204:207], v[44:47]
	v_mfma_f32_16x16x32_bf16 v[36:39], v[172:175], v[204:207], v[36:39]
	v_mfma_f32_16x16x32_bf16 v[28:31], v[164:167], v[212:215], v[28:31]
	v_mfma_f32_16x16x32_bf16 v[20:23], v[172:175], v[212:215], v[20:23]
	v_mfma_f32_16x16x32_bf16 v[12:15], v[164:167], v[220:223], v[12:15]
	v_mfma_f32_16x16x32_bf16 v[4:7], v[172:175], v[220:223], v[4:7]
	s_setprio 0
	s_setprio 1
	v_mfma_f32_16x16x32_bf16 v[56:59], v[176:179], v[192:195], v[56:59]
	v_mfma_f32_16x16x32_bf16 v[48:51], v[184:187], v[192:195], v[48:51]
	v_mfma_f32_16x16x32_bf16 v[40:43], v[176:179], v[200:203], v[40:43]
	v_mfma_f32_16x16x32_bf16 v[32:35], v[184:187], v[200:203], v[32:35]
	v_mfma_f32_16x16x32_bf16 v[24:27], v[176:179], v[208:211], v[24:27]
	v_mfma_f32_16x16x32_bf16 v[16:19], v[184:187], v[208:211], v[16:19]
	v_mfma_f32_16x16x32_bf16 v[8:11], v[176:179], v[216:219], v[8:11]
	v_mfma_f32_16x16x32_bf16 v[0:3], v[184:187], v[216:219], v[0:3]
	v_mfma_f32_16x16x32_bf16 v[56:59], v[180:183], v[196:199], v[56:59]
	v_mfma_f32_16x16x32_bf16 v[48:51], v[188:191], v[196:199], v[48:51]
	v_mfma_f32_16x16x32_bf16 v[40:43], v[180:183], v[204:207], v[40:43]
	v_mfma_f32_16x16x32_bf16 v[32:35], v[188:191], v[204:207], v[32:35]
	v_mfma_f32_16x16x32_bf16 v[24:27], v[180:183], v[212:215], v[24:27]
	v_mfma_f32_16x16x32_bf16 v[16:19], v[188:191], v[212:215], v[16:19]
	v_mfma_f32_16x16x32_bf16 v[8:11], v[180:183], v[220:223], v[8:11]
	v_mfma_f32_16x16x32_bf16 v[0:3], v[188:191], v[220:223], v[0:3]
	s_setprio 0
	s_barrier
	s_add_i32 s70, s70, 2
	s_add_u32 s68, s68, 0x100
	s_addc_u32 s69, s69, 0
	s_add_u32 s30, s30, 0x100
	s_addc_u32 s31, s31, 0
	s_branch .LBB0_1098
.Lfa_10:
	v_add_u32_e32 v153, s61, v147
	ds_read_b128 v[160:163], v153
	v_xor_b32_e32 v253, 64, v153
	ds_read_b128 v[164:167], v253
	ds_read_b128 v[168:171], v153 offset:2048
	ds_read_b128 v[172:175], v253 offset:2048
	v_add_u32_e32 v153, s62, v147
	ds_read_b128 v[176:179], v153
	v_xor_b32_e32 v253, 64, v153
	ds_read_b128 v[180:183], v253
	ds_read_b128 v[184:187], v153 offset:2048
	ds_read_b128 v[188:191], v253 offset:2048
	s_add_u32 s46, s30, 0xfffc0080
	s_addc_u32 s47, s31, -1
	s_and_b64 s[44:45], s[44:45], exec
	s_cselect_b32 s47, s25, s47
	s_cselect_b32 s46, s65, s46
	s_cselect_b32 s45, s66, s69
	s_cselect_b32 s44, s67, s68
	v_lshl_add_u64 v[154:155], s[30:31], 0, v[138:139]
	s_add_i32 m0, s52, 0xc000
	ds_read_b128 v[192:195], v150
	v_xor_b32_e32 v253, 64, v150
	ds_read_b128 v[196:199], v253
	ds_read_b128 v[200:203], v150 offset:2048
	ds_read_b128 v[204:207], v253 offset:2048
	ds_read_b128 v[208:211], v150 offset:4096
	ds_read_b128 v[212:215], v253 offset:4096
	ds_read_b128 v[216:219], v150 offset:6144
	ds_read_b128 v[220:223], v253 offset:6144
	global_load_lds_dwordx4 v[154:155], off
	v_lshl_add_u64 v[154:155], s[30:31], 0, v[136:137]
	s_add_i32 m0, s52, 0xe000
	s_nop 0
	global_load_lds_dwordx4 v[154:155], off
	s_waitcnt vmcnt(8)
	s_waitcnt lgkmcnt(0)
	s_barrier
	s_setprio 1
	s_waitcnt lgkmcnt(0)
	v_mfma_f32_16x16x32_bf16 v[124:127], v[160:163], v[192:195], 0
	v_mfma_f32_16x16x32_bf16 v[116:119], v[168:171], v[192:195], 0
	v_mfma_f32_16x16x32_bf16 v[108:111], v[160:163], v[200:203], 0
	v_mfma_f32_16x16x32_bf16 v[100:103], v[168:171], v[200:203], 0
	v_mfma_f32_16x16x32_bf16 v[92:95], v[160:163], v[208:211], 0
	v_mfma_f32_16x16x32_bf16 v[84:87], v[168:171], v[208:211], 0
	v_mfma_f32_16x16x32_bf16 v[76:79], v[160:163], v[216:219], 0
	v_mfma_f32_16x16x32_bf16 v[68:71], v[168:171], v[216:219], 0
	v_mfma_f32_16x16x32_bf16 v[124:127], v[164:167], v[196:199], v[124:127]
	v_mfma_f32_16x16x32_bf16 v[116:119], v[172:175], v[196:199], v[116:119]
	v_mfma_f32_16x16x32_bf16 v[108:111], v[164:167], v[204:207], v[108:111]
	v_mfma_f32_16x16x32_bf16 v[100:103], v[172:175], v[204:207], v[100:103]
	v_mfma_f32_16x16x32_bf16 v[92:95], v[164:167], v[212:215], v[92:95]
	v_mfma_f32_16x16x32_bf16 v[84:87], v[172:175], v[212:215], v[84:87]
	v_mfma_f32_16x16x32_bf16 v[76:79], v[164:167], v[220:223], v[76:79]
	v_mfma_f32_16x16x32_bf16 v[68:71], v[172:175], v[220:223], v[68:71]
	s_setprio 0
	s_setprio 1
	v_mfma_f32_16x16x32_bf16 v[120:123], v[176:179], v[192:195], 0
	v_mfma_f32_16x16x32_bf16 v[112:115], v[184:187], v[192:195], 0
	v_mfma_f32_16x16x32_bf16 v[104:107], v[176:179], v[200:203], 0
	v_mfma_f32_16x16x32_bf16 v[96:99], v[184:187], v[200:203], 0
	v_mfma_f32_16x16x32_bf16 v[88:91], v[176:179], v[208:211], 0
	v_mfma_f32_16x16x32_bf16 v[80:83], v[184:187], v[208:211], 0
	v_mfma_f32_16x16x32_bf16 v[72:75], v[176:179], v[216:219], 0
	v_mfma_f32_16x16x32_bf16 v[64:67], v[184:187], v[216:219], 0
	v_mfma_f32_16x16x32_bf16 v[120:123], v[180:183], v[196:199], v[120:123]
	v_mfma_f32_16x16x32_bf16 v[112:115], v[188:191], v[196:199], v[112:115]
	v_mfma_f32_16x16x32_bf16 v[104:107], v[180:183], v[204:207], v[104:107]
	v_mfma_f32_16x16x32_bf16 v[96:99], v[188:191], v[204:207], v[96:99]
	v_mfma_f32_16x16x32_bf16 v[88:91], v[180:183], v[212:215], v[88:91]
	v_mfma_f32_16x16x32_bf16 v[80:83], v[188:191], v[212:215], v[80:83]
	v_mfma_f32_16x16x32_bf16 v[72:75], v[180:183], v[220:223], v[72:75]
	v_mfma_f32_16x16x32_bf16 v[64:67], v[188:191], v[220:223], v[64:67]
	s_setprio 0
	s_barrier
	s_add_i32 s71, s61, s49
	v_lshl_add_u64 v[154:155], s[44:45], 0, v[132:133]
	s_mov_b32 m0, s71
	ds_read_b128 v[192:195], v150 offset:16384
	v_xor_b32_e32 v253, 64, v150
	ds_read_b128 v[196:199], v253 offset:16384
	ds_read_b128 v[200:203], v150 offset:18432
	ds_read_b128 v[204:207], v253 offset:18432
	ds_read_b128 v[208:211], v150 offset:20480
	ds_read_b128 v[212:215], v253 offset:20480
	ds_read_b128 v[216:219], v150 offset:22528
	ds_read_b128 v[220:223], v253 offset:22528
	global_load_lds_dwordx4 v[154:155], off
	s_add_i32 m0, s71, 0x2000
	s_add_u32 s72, s44, 0x40000
	v_lshl_add_u64 v[224:225], s[44:45], 0, v[128:129]
	s_addc_u32 s73, s45, 0
	s_add_i32 s71, s62, s49
	global_load_lds_dwordx4 v[224:225], off
	v_lshl_add_u64 v[226:227], s[72:73], 0, v[132:133]
	s_mov_b32 m0, s71
	v_lshl_add_u64 v[228:229], s[46:47], 0, v[130:131]
	global_load_lds_dwordx4 v[226:227], off
	v_lshl_add_u64 v[226:227], s[72:73], 0, v[128:129]
	s_add_i32 m0, s71, 0x2000
	s_nop 0
	global_load_lds_dwordx4 v[226:227], off
	v_lshl_add_u64 v[226:227], s[46:47], 0, v[134:135]
	s_mov_b32 m0, s52
	s_nop 0
	global_load_lds_dwordx4 v[226:227], off
	s_mov_b32 m0, s53
	s_nop 0
	global_load_lds_dwordx4 v[228:229], off
	s_waitcnt vmcnt(8)
	s_waitcnt lgkmcnt(0)
	s_barrier
	s_setprio 1
	s_waitcnt lgkmcnt(0)
	v_mfma_f32_16x16x32_bf16 v[60:63], v[160:163], v[192:195], 0
	v_mfma_f32_16x16x32_bf16 v[52:55], v[168:171], v[192:195], 0
	v_mfma_f32_16x16x32_bf16 v[44:47], v[160:163], v[200:203], 0
	v_mfma_f32_16x16x32_bf16 v[36:39], v[168:171], v[200:203], 0
	v_mfma_f32_16x16x32_bf16 v[28:31], v[160:163], v[208:211], 0
	v_mfma_f32_16x16x32_bf16 v[20:23], v[168:171], v[208:211], 0
	v_mfma_f32_16x16x32_bf16 v[12:15], v[160:163], v[216:219], 0
	v_mfma_f32_16x16x32_bf16 v[4:7], v[168:171], v[216:219], 0
	v_mfma_f32_16x16x32_bf16 v[60:63], v[164:167], v[196:199], v[60:63]
	v_mfma_f32_16x16x32_bf16 v[52:55], v[172:175], v[196:199], v[52:55]
	v_mfma_f32_16x16x32_bf16 v[44:47], v[164:167], v[204:207], v[44:47]
	v_mfma_f32_16x16x32_bf16 v[36:39], v[172:175], v[204:207], v[36:39]
	v_mfma_f32_16x16x32_bf16 v[28:31], v[164:167], v[212:215], v[28:31]
	v_mfma_f32_16x16x32_bf16 v[20:23], v[172:175], v[212:215], v[20:23]
	v_mfma_f32_16x16x32_bf16 v[12:15], v[164:167], v[220:223], v[12:15]
	v_mfma_f32_16x16x32_bf16 v[4:7], v[172:175], v[220:223], v[4:7]
	s_setprio 0
	s_setprio 1
	v_mfma_f32_16x16x32_bf16 v[56:59], v[176:179], v[192:195], 0
	v_mfma_f32_16x16x32_bf16 v[48:51], v[184:187], v[192:195], 0
	v_mfma_f32_16x16x32_bf16 v[40:43], v[176:179], v[200:203], 0
	v_mfma_f32_16x16x32_bf16 v[32:35], v[184:187], v[200:203], 0
	v_mfma_f32_16x16x32_bf16 v[24:27], v[176:179], v[208:211], 0
	v_mfma_f32_16x16x32_bf16 v[16:19], v[184:187], v[208:211], 0
	v_mfma_f32_16x16x32_bf16 v[8:11], v[176:179], v[216:219], 0
	v_mfma_f32_16x16x32_bf16 v[0:3], v[184:187], v[216:219], 0
	v_mfma_f32_16x16x32_bf16 v[56:59], v[180:183], v[196:199], v[56:59]
	v_mfma_f32_16x16x32_bf16 v[48:51], v[188:191], v[196:199], v[48:51]
	v_mfma_f32_16x16x32_bf16 v[40:43], v[180:183], v[204:207], v[40:43]
	v_mfma_f32_16x16x32_bf16 v[32:35], v[188:191], v[204:207], v[32:35]
	v_mfma_f32_16x16x32_bf16 v[24:27], v[180:183], v[212:215], v[24:27]
	v_mfma_f32_16x16x32_bf16 v[16:19], v[188:191], v[212:215], v[16:19]
	v_mfma_f32_16x16x32_bf16 v[8:11], v[180:183], v[220:223], v[8:11]
	v_mfma_f32_16x16x32_bf16 v[0:3], v[188:191], v[220:223], v[0:3]
	s_setprio 0
	s_barrier
	s_add_i32 s71, 0, 0x18000
	v_add_u32_e32 v153, s71, v147
	s_add_i32 s72, 0, 0x1c000
	ds_read_b128 v[160:163], v153
	v_xor_b32_e32 v253, 64, v153
	ds_read_b128 v[164:167], v253
	ds_read_b128 v[168:171], v153 offset:2048
	ds_read_b128 v[172:175], v253 offset:2048
	v_add_u32_e32 v153, s72, v147
	ds_read_b128 v[176:179], v153
	v_xor_b32_e32 v253, 64, v153
	ds_read_b128 v[180:183], v253
	ds_read_b128 v[184:187], v153 offset:2048
	ds_read_b128 v[188:191], v253 offset:2048
	s_add_u32 s46, s46, 0x40000
	s_addc_u32 s47, s47, 0
	s_mov_b32 m0, s54
	v_lshl_add_u64 v[230:231], s[46:47], 0, v[134:135]
	ds_read_b128 v[192:195], v150 offset:32768
	v_xor_b32_e32 v253, 64, v150
	ds_read_b128 v[196:199], v253 offset:32768
	ds_read_b128 v[200:203], v150 offset:34816
	ds_read_b128 v[204:207], v253 offset:34816
	ds_read_b128 v[208:211], v150 offset:36864
	ds_read_b128 v[212:215], v253 offset:36864
	ds_read_b128 v[216:219], v150 offset:38912
	ds_read_b128 v[220:223], v253 offset:38912
	global_load_lds_dwordx4 v[230:231], off
	v_lshl_add_u64 v[230:231], s[46:47], 0, v[130:131]
	s_mov_b32 m0, s55
	s_nop 0
	global_load_lds_dwordx4 v[230:231], off
	s_waitcnt vmcnt(8)
	s_waitcnt lgkmcnt(0)
	s_barrier
	s_setprio 1
	s_waitcnt lgkmcnt(0)
	v_mfma_f32_16x16x32_bf16 v[124:127], v[160:163], v[192:195], v[124:127]
	v_mfma_f32_16x16x32_bf16 v[116:119], v[168:171], v[192:195], v[116:119]
	v_mfma_f32_16x16x32_bf16 v[108:111], v[160:163], v[200:203], v[108:111]
	v_mfma_f32_16x16x32_bf16 v[100:103], v[168:171], v[200:203], v[100:103]
	v_mfma_f32_16x16x32_bf16 v[92:95], v[160:163], v[208:211], v[92:95]
	v_mfma_f32_16x16x32_bf16 v[84:87], v[168:171], v[208:211], v[84:87]
	v_mfma_f32_16x16x32_bf16 v[76:79], v[160:163], v[216:219], v[76:79]
	v_mfma_f32_16x16x32_bf16 v[68:71], v[168:171], v[216:219], v[68:71]
	v_mfma_f32_16x16x32_bf16 v[124:127], v[164:167], v[196:199], v[124:127]
	v_mfma_f32_16x16x32_bf16 v[116:119], v[172:175], v[196:199], v[116:119]
	v_mfma_f32_16x16x32_bf16 v[108:111], v[164:167], v[204:207], v[108:111]
	v_mfma_f32_16x16x32_bf16 v[100:103], v[172:175], v[204:207], v[100:103]
	v_mfma_f32_16x16x32_bf16 v[92:95], v[164:167], v[212:215], v[92:95]
	v_mfma_f32_16x16x32_bf16 v[84:87], v[172:175], v[212:215], v[84:87]
	v_mfma_f32_16x16x32_bf16 v[76:79], v[164:167], v[220:223], v[76:79]
	v_mfma_f32_16x16x32_bf16 v[68:71], v[172:175], v[220:223], v[68:71]
	s_setprio 0
	s_setprio 1
	v_mfma_f32_16x16x32_bf16 v[120:123], v[176:179], v[192:195], v[120:123]
	v_mfma_f32_16x16x32_bf16 v[112:115], v[184:187], v[192:195], v[112:115]
	v_mfma_f32_16x16x32_bf16 v[104:107], v[176:179], v[200:203], v[104:107]
	v_mfma_f32_16x16x32_bf16 v[96:99], v[184:187], v[200:203], v[96:99]
	v_mfma_f32_16x16x32_bf16 v[88:91], v[176:179], v[208:211], v[88:91]
	v_mfma_f32_16x16x32_bf16 v[80:83], v[184:187], v[208:211], v[80:83]
	v_mfma_f32_16x16x32_bf16 v[72:75], v[176:179], v[216:219], v[72:75]
	v_mfma_f32_16x16x32_bf16 v[64:67], v[184:187], v[216:219], v[64:67]
	v_mfma_f32_16x16x32_bf16 v[120:123], v[180:183], v[196:199], v[120:123]
	v_mfma_f32_16x16x32_bf16 v[112:115], v[188:191], v[196:199], v[112:115]
	v_mfma_f32_16x16x32_bf16 v[104:107], v[180:183], v[204:207], v[104:107]
	v_mfma_f32_16x16x32_bf16 v[96:99], v[188:191], v[204:207], v[96:99]
	v_mfma_f32_16x16x32_bf16 v[88:91], v[180:183], v[212:215], v[88:91]
	v_mfma_f32_16x16x32_bf16 v[80:83], v[188:191], v[212:215], v[80:83]
	v_mfma_f32_16x16x32_bf16 v[72:75], v[180:183], v[220:223], v[72:75]
	v_mfma_f32_16x16x32_bf16 v[64:67], v[188:191], v[220:223], v[64:67]
	s_setprio 0
	s_barrier
	s_add_i32 s46, s71, s49
	v_lshl_add_u64 v[154:155], v[154:155], 0, s[14:15]
	s_mov_b32 m0, s46
	ds_read_b128 v[192:195], v150 offset:49152
	v_xor_b32_e32 v253, 64, v150
	ds_read_b128 v[196:199], v253 offset:49152
	ds_read_b128 v[200:203], v150 offset:51200
	ds_read_b128 v[204:207], v253 offset:51200
	ds_read_b128 v[208:211], v150 offset:53248
	ds_read_b128 v[212:215], v253 offset:53248
	ds_read_b128 v[216:219], v150 offset:55296
	ds_read_b128 v[220:223], v253 offset:55296
	global_load_lds_dwordx4 v[154:155], off
	s_add_i32 m0, s46, 0x2000
	s_add_u32 s44, s44, 0x40080
	v_lshl_add_u64 v[154:155], v[224:225], 0, s[14:15]
	s_addc_u32 s45, s45, 0
	s_add_i32 s46, s72, s49
	global_load_lds_dwordx4 v[154:155], off
	v_lshl_add_u64 v[154:155], s[44:45], 0, v[132:133]
	s_mov_b32 m0, s46
	s_nop 0
	global_load_lds_dwordx4 v[154:155], off
	v_lshl_add_u64 v[154:155], s[44:45], 0, v[128:129]
	s_add_i32 m0, s46, 0x2000
	s_nop 0
	global_load_lds_dwordx4 v[154:155], off
	v_lshl_add_u64 v[154:155], v[226:227], 0, s[14:15]
	s_mov_b32 m0, s57
	s_nop 0
	global_load_lds_dwordx4 v[154:155], off
	v_lshl_add_u64 v[154:155], v[228:229], 0, s[14:15]
	s_mov_b32 m0, s58
	s_nop 0
	global_load_lds_dwordx4 v[154:155], off
	s_waitcnt vmcnt(8)
	s_waitcnt lgkmcnt(0)
	s_barrier
	s_setprio 1
	s_waitcnt lgkmcnt(0)
	v_mfma_f32_16x16x32_bf16 v[60:63], v[160:163], v[192:195], v[60:63]
	v_mfma_f32_16x16x32_bf16 v[52:55], v[168:171], v[192:195], v[52:55]
	v_mfma_f32_16x16x32_bf16 v[44:47], v[160:163], v[200:203], v[44:47]
	v_mfma_f32_16x16x32_bf16 v[36:39], v[168:171], v[200:203], v[36:39]
	v_mfma_f32_16x16x32_bf16 v[28:31], v[160:163], v[208:211], v[28:31]
	v_mfma_f32_16x16x32_bf16 v[20:23], v[168:171], v[208:211], v[20:23]
	v_mfma_f32_16x16x32_bf16 v[12:15], v[160:163], v[216:219], v[12:15]
	v_mfma_f32_16x16x32_bf16 v[4:7], v[168:171], v[216:219], v[4:7]
	v_mfma_f32_16x16x32_bf16 v[60:63], v[164:167], v[196:199], v[60:63]
	v_mfma_f32_16x16x32_bf16 v[52:55], v[172:175], v[196:199], v[52:55]
	v_mfma_f32_16x16x32_bf16 v[44:47], v[164:167], v[204:207], v[44:47]
	v_mfma_f32_16x16x32_bf16 v[36:39], v[172:175], v[204:207], v[36:39]
	v_mfma_f32_16x16x32_bf16 v[28:31], v[164:167], v[212:215], v[28:31]
	v_mfma_f32_16x16x32_bf16 v[20:23], v[172:175], v[212:215], v[20:23]
	v_mfma_f32_16x16x32_bf16 v[12:15], v[164:167], v[220:223], v[12:15]
	v_mfma_f32_16x16x32_bf16 v[4:7], v[172:175], v[220:223], v[4:7]
	s_setprio 0
	s_setprio 1
	v_mfma_f32_16x16x32_bf16 v[56:59], v[176:179], v[192:195], v[56:59]
	v_mfma_f32_16x16x32_bf16 v[48:51], v[184:187], v[192:195], v[48:51]
	v_mfma_f32_16x16x32_bf16 v[40:43], v[176:179], v[200:203], v[40:43]
	v_mfma_f32_16x16x32_bf16 v[32:35], v[184:187], v[200:203], v[32:35]
	v_mfma_f32_16x16x32_bf16 v[24:27], v[176:179], v[208:211], v[24:27]
	v_mfma_f32_16x16x32_bf16 v[16:19], v[184:187], v[208:211], v[16:19]
	v_mfma_f32_16x16x32_bf16 v[8:11], v[176:179], v[216:219], v[8:11]
	v_mfma_f32_16x16x32_bf16 v[0:3], v[184:187], v[216:219], v[0:3]
	v_mfma_f32_16x16x32_bf16 v[56:59], v[180:183], v[196:199], v[56:59]
	v_mfma_f32_16x16x32_bf16 v[48:51], v[188:191], v[196:199], v[48:51]
	v_mfma_f32_16x16x32_bf16 v[40:43], v[180:183], v[204:207], v[40:43]
	v_mfma_f32_16x16x32_bf16 v[32:35], v[188:191], v[204:207], v[32:35]
	v_mfma_f32_16x16x32_bf16 v[24:27], v[180:183], v[212:215], v[24:27]
	v_mfma_f32_16x16x32_bf16 v[16:19], v[188:191], v[212:215], v[16:19]
	v_mfma_f32_16x16x32_bf16 v[8:11], v[180:183], v[220:223], v[8:11]
	v_mfma_f32_16x16x32_bf16 v[0:3], v[188:191], v[220:223], v[0:3]
	s_setprio 0
	s_barrier
	s_add_i32 s70, s70, 2
	s_add_u32 s68, s68, 0x100
	s_addc_u32 s69, s69, 0
	s_add_u32 s30, s30, 0x100
	s_addc_u32 s31, s31, 0
	s_branch .LBB0_1098
.LBB0_1097:
	v_add_u32_e32 v153, s61, v147
	ds_read_b128 v[160:163], v153
	v_xor_b32_e32 v253, 64, v153
	ds_read_b128 v[164:167], v253
	ds_read_b128 v[168:171], v153 offset:2048
	ds_read_b128 v[172:175], v253 offset:2048
	v_add_u32_e32 v153, s62, v147
	ds_read_b128 v[176:179], v153
	v_xor_b32_e32 v253, 64, v153
	ds_read_b128 v[180:183], v253
	ds_read_b128 v[184:187], v153 offset:2048
	ds_read_b128 v[188:191], v253 offset:2048
	s_add_u32 s46, s30, 0xfffc0080
	s_addc_u32 s47, s31, -1
	s_and_b64 s[44:45], s[44:45], exec
	s_cselect_b32 s47, s25, s47
	s_cselect_b32 s46, s65, s46
	s_cselect_b32 s45, s66, s69
	s_cselect_b32 s44, s67, s68
	v_lshl_add_u64 v[154:155], s[30:31], 0, v[138:139]
	s_add_i32 m0, s52, 0xc000
	ds_read_b128 v[192:195], v150
	v_xor_b32_e32 v253, 64, v150
	ds_read_b128 v[196:199], v253
	ds_read_b128 v[200:203], v150 offset:2048
	ds_read_b128 v[204:207], v253 offset:2048
	ds_read_b128 v[208:211], v150 offset:4096
	ds_read_b128 v[212:215], v253 offset:4096
	ds_read_b128 v[216:219], v150 offset:6144
	ds_read_b128 v[220:223], v253 offset:6144
	global_load_lds_dwordx4 v[154:155], off
	v_lshl_add_u64 v[154:155], s[30:31], 0, v[136:137]
	s_add_i32 m0, s52, 0xe000
	s_nop 0
	global_load_lds_dwordx4 v[154:155], off
	s_waitcnt vmcnt(8)
	s_waitcnt lgkmcnt(0)
	s_barrier
	s_setprio 1
	s_waitcnt lgkmcnt(0)
	v_mfma_f32_16x16x32_bf16 v[124:127], v[160:163], v[192:195], v[124:127]
	v_mfma_f32_16x16x32_bf16 v[116:119], v[168:171], v[192:195], v[116:119]
	v_mfma_f32_16x16x32_bf16 v[108:111], v[160:163], v[200:203], v[108:111]
	v_mfma_f32_16x16x32_bf16 v[100:103], v[168:171], v[200:203], v[100:103]
	v_mfma_f32_16x16x32_bf16 v[92:95], v[160:163], v[208:211], v[92:95]
	v_mfma_f32_16x16x32_bf16 v[84:87], v[168:171], v[208:211], v[84:87]
	v_mfma_f32_16x16x32_bf16 v[76:79], v[160:163], v[216:219], v[76:79]
	v_mfma_f32_16x16x32_bf16 v[68:71], v[168:171], v[216:219], v[68:71]
	v_mfma_f32_16x16x32_bf16 v[124:127], v[164:167], v[196:199], v[124:127]
	v_mfma_f32_16x16x32_bf16 v[116:119], v[172:175], v[196:199], v[116:119]
	v_mfma_f32_16x16x32_bf16 v[108:111], v[164:167], v[204:207], v[108:111]
	v_mfma_f32_16x16x32_bf16 v[100:103], v[172:175], v[204:207], v[100:103]
	v_mfma_f32_16x16x32_bf16 v[92:95], v[164:167], v[212:215], v[92:95]
	v_mfma_f32_16x16x32_bf16 v[84:87], v[172:175], v[212:215], v[84:87]
	v_mfma_f32_16x16x32_bf16 v[76:79], v[164:167], v[220:223], v[76:79]
	v_mfma_f32_16x16x32_bf16 v[68:71], v[172:175], v[220:223], v[68:71]
	s_setprio 0
	s_setprio 1
	v_mfma_f32_16x16x32_bf16 v[120:123], v[176:179], v[192:195], v[120:123]
	v_mfma_f32_16x16x32_bf16 v[112:115], v[184:187], v[192:195], v[112:115]
	v_mfma_f32_16x16x32_bf16 v[104:107], v[176:179], v[200:203], v[104:107]
	v_mfma_f32_16x16x32_bf16 v[96:99], v[184:187], v[200:203], v[96:99]
	v_mfma_f32_16x16x32_bf16 v[88:91], v[176:179], v[208:211], v[88:91]
	v_mfma_f32_16x16x32_bf16 v[80:83], v[184:187], v[208:211], v[80:83]
	v_mfma_f32_16x16x32_bf16 v[72:75], v[176:179], v[216:219], v[72:75]
	v_mfma_f32_16x16x32_bf16 v[64:67], v[184:187], v[216:219], v[64:67]
	v_mfma_f32_16x16x32_bf16 v[120:123], v[180:183], v[196:199], v[120:123]
	v_mfma_f32_16x16x32_bf16 v[112:115], v[188:191], v[196:199], v[112:115]
	v_mfma_f32_16x16x32_bf16 v[104:107], v[180:183], v[204:207], v[104:107]
	v_mfma_f32_16x16x32_bf16 v[96:99], v[188:191], v[204:207], v[96:99]
	v_mfma_f32_16x16x32_bf16 v[88:91], v[180:183], v[212:215], v[88:91]
	v_mfma_f32_16x16x32_bf16 v[80:83], v[188:191], v[212:215], v[80:83]
	v_mfma_f32_16x16x32_bf16 v[72:75], v[180:183], v[220:223], v[72:75]
	v_mfma_f32_16x16x32_bf16 v[64:67], v[188:191], v[220:223], v[64:67]
	s_setprio 0
	s_barrier
	s_add_i32 s71, s61, s49
	v_lshl_add_u64 v[154:155], s[44:45], 0, v[132:133]
	s_mov_b32 m0, s71
	ds_read_b128 v[192:195], v150 offset:16384
	v_xor_b32_e32 v253, 64, v150
	ds_read_b128 v[196:199], v253 offset:16384
	ds_read_b128 v[200:203], v150 offset:18432
	ds_read_b128 v[204:207], v253 offset:18432
	ds_read_b128 v[208:211], v150 offset:20480
	ds_read_b128 v[212:215], v253 offset:20480
	ds_read_b128 v[216:219], v150 offset:22528
	ds_read_b128 v[220:223], v253 offset:22528
	global_load_lds_dwordx4 v[154:155], off
	s_add_i32 m0, s71, 0x2000
	s_add_u32 s72, s44, 0x40000
	v_lshl_add_u64 v[224:225], s[44:45], 0, v[128:129]
	s_addc_u32 s73, s45, 0
	s_add_i32 s71, s62, s49
	global_load_lds_dwordx4 v[224:225], off
	v_lshl_add_u64 v[226:227], s[72:73], 0, v[132:133]
	s_mov_b32 m0, s71
	v_lshl_add_u64 v[228:229], s[46:47], 0, v[130:131]
	global_load_lds_dwordx4 v[226:227], off
	v_lshl_add_u64 v[226:227], s[72:73], 0, v[128:129]
	s_add_i32 m0, s71, 0x2000
	s_nop 0
	global_load_lds_dwordx4 v[226:227], off
	v_lshl_add_u64 v[226:227], s[46:47], 0, v[134:135]
	s_mov_b32 m0, s52
	s_nop 0
	global_load_lds_dwordx4 v[226:227], off
	s_mov_b32 m0, s53
	s_nop 0
	global_load_lds_dwordx4 v[228:229], off
	s_waitcnt vmcnt(8)
	s_waitcnt lgkmcnt(0)
	s_barrier
	s_setprio 1
	s_waitcnt lgkmcnt(0)
	v_mfma_f32_16x16x32_bf16 v[60:63], v[160:163], v[192:195], v[60:63]
	v_mfma_f32_16x16x32_bf16 v[52:55], v[168:171], v[192:195], v[52:55]
	v_mfma_f32_16x16x32_bf16 v[44:47], v[160:163], v[200:203], v[44:47]
	v_mfma_f32_16x16x32_bf16 v[36:39], v[168:171], v[200:203], v[36:39]
	v_mfma_f32_16x16x32_bf16 v[28:31], v[160:163], v[208:211], v[28:31]
	v_mfma_f32_16x16x32_bf16 v[20:23], v[168:171], v[208:211], v[20:23]
	v_mfma_f32_16x16x32_bf16 v[12:15], v[160:163], v[216:219], v[12:15]
	v_mfma_f32_16x16x32_bf16 v[4:7], v[168:171], v[216:219], v[4:7]
	v_mfma_f32_16x16x32_bf16 v[60:63], v[164:167], v[196:199], v[60:63]
	v_mfma_f32_16x16x32_bf16 v[52:55], v[172:175], v[196:199], v[52:55]
	v_mfma_f32_16x16x32_bf16 v[44:47], v[164:167], v[204:207], v[44:47]
	v_mfma_f32_16x16x32_bf16 v[36:39], v[172:175], v[204:207], v[36:39]
	v_mfma_f32_16x16x32_bf16 v[28:31], v[164:167], v[212:215], v[28:31]
	v_mfma_f32_16x16x32_bf16 v[20:23], v[172:175], v[212:215], v[20:23]
	v_mfma_f32_16x16x32_bf16 v[12:15], v[164:167], v[220:223], v[12:15]
	v_mfma_f32_16x16x32_bf16 v[4:7], v[172:175], v[220:223], v[4:7]
	s_setprio 0
	s_setprio 1
	v_mfma_f32_16x16x32_bf16 v[56:59], v[176:179], v[192:195], v[56:59]
	v_mfma_f32_16x16x32_bf16 v[48:51], v[184:187], v[192:195], v[48:51]
	v_mfma_f32_16x16x32_bf16 v[40:43], v[176:179], v[200:203], v[40:43]
	v_mfma_f32_16x16x32_bf16 v[32:35], v[184:187], v[200:203], v[32:35]
	v_mfma_f32_16x16x32_bf16 v[24:27], v[176:179], v[208:211], v[24:27]
	v_mfma_f32_16x16x32_bf16 v[16:19], v[184:187], v[208:211], v[16:19]
	v_mfma_f32_16x16x32_bf16 v[8:11], v[176:179], v[216:219], v[8:11]
	v_mfma_f32_16x16x32_bf16 v[0:3], v[184:187], v[216:219], v[0:3]
	v_mfma_f32_16x16x32_bf16 v[56:59], v[180:183], v[196:199], v[56:59]
	v_mfma_f32_16x16x32_bf16 v[48:51], v[188:191], v[196:199], v[48:51]
	v_mfma_f32_16x16x32_bf16 v[40:43], v[180:183], v[204:207], v[40:43]
	v_mfma_f32_16x16x32_bf16 v[32:35], v[188:191], v[204:207], v[32:35]
	v_mfma_f32_16x16x32_bf16 v[24:27], v[180:183], v[212:215], v[24:27]
	v_mfma_f32_16x16x32_bf16 v[16:19], v[188:191], v[212:215], v[16:19]
	v_mfma_f32_16x16x32_bf16 v[8:11], v[180:183], v[220:223], v[8:11]
	v_mfma_f32_16x16x32_bf16 v[0:3], v[188:191], v[220:223], v[0:3]
	s_setprio 0
	s_barrier
	s_add_i32 s71, 0, 0x18000
	v_add_u32_e32 v153, s71, v147
	s_add_i32 s72, 0, 0x1c000
	ds_read_b128 v[160:163], v153
	v_xor_b32_e32 v253, 64, v153
	ds_read_b128 v[164:167], v253
	ds_read_b128 v[168:171], v153 offset:2048
	ds_read_b128 v[172:175], v253 offset:2048
	v_add_u32_e32 v153, s72, v147
	ds_read_b128 v[176:179], v153
	v_xor_b32_e32 v253, 64, v153
	ds_read_b128 v[180:183], v253
	ds_read_b128 v[184:187], v153 offset:2048
	ds_read_b128 v[188:191], v253 offset:2048
	s_add_u32 s46, s46, 0x40000
	s_addc_u32 s47, s47, 0
	s_mov_b32 m0, s54
	v_lshl_add_u64 v[230:231], s[46:47], 0, v[134:135]
	ds_read_b128 v[192:195], v150 offset:32768
	v_xor_b32_e32 v253, 64, v150
	ds_read_b128 v[196:199], v253 offset:32768
	ds_read_b128 v[200:203], v150 offset:34816
	ds_read_b128 v[204:207], v253 offset:34816
	ds_read_b128 v[208:211], v150 offset:36864
	ds_read_b128 v[212:215], v253 offset:36864
	ds_read_b128 v[216:219], v150 offset:38912
	ds_read_b128 v[220:223], v253 offset:38912
	global_load_lds_dwordx4 v[230:231], off
	v_lshl_add_u64 v[230:231], s[46:47], 0, v[130:131]
	s_mov_b32 m0, s55
	s_nop 0
	global_load_lds_dwordx4 v[230:231], off
	s_waitcnt vmcnt(8)
	s_waitcnt lgkmcnt(0)
	s_barrier
	s_setprio 1
	s_waitcnt lgkmcnt(0)
	v_mfma_f32_16x16x32_bf16 v[124:127], v[160:163], v[192:195], v[124:127]
	v_mfma_f32_16x16x32_bf16 v[116:119], v[168:171], v[192:195], v[116:119]
	v_mfma_f32_16x16x32_bf16 v[108:111], v[160:163], v[200:203], v[108:111]
	v_mfma_f32_16x16x32_bf16 v[100:103], v[168:171], v[200:203], v[100:103]
	v_mfma_f32_16x16x32_bf16 v[92:95], v[160:163], v[208:211], v[92:95]
	v_mfma_f32_16x16x32_bf16 v[84:87], v[168:171], v[208:211], v[84:87]
	v_mfma_f32_16x16x32_bf16 v[76:79], v[160:163], v[216:219], v[76:79]
	v_mfma_f32_16x16x32_bf16 v[68:71], v[168:171], v[216:219], v[68:71]
	v_mfma_f32_16x16x32_bf16 v[124:127], v[164:167], v[196:199], v[124:127]
	v_mfma_f32_16x16x32_bf16 v[116:119], v[172:175], v[196:199], v[116:119]
	v_mfma_f32_16x16x32_bf16 v[108:111], v[164:167], v[204:207], v[108:111]
	v_mfma_f32_16x16x32_bf16 v[100:103], v[172:175], v[204:207], v[100:103]
	v_mfma_f32_16x16x32_bf16 v[92:95], v[164:167], v[212:215], v[92:95]
	v_mfma_f32_16x16x32_bf16 v[84:87], v[172:175], v[212:215], v[84:87]
	v_mfma_f32_16x16x32_bf16 v[76:79], v[164:167], v[220:223], v[76:79]
	v_mfma_f32_16x16x32_bf16 v[68:71], v[172:175], v[220:223], v[68:71]
	s_setprio 0
	s_setprio 1
	v_mfma_f32_16x16x32_bf16 v[120:123], v[176:179], v[192:195], v[120:123]
	v_mfma_f32_16x16x32_bf16 v[112:115], v[184:187], v[192:195], v[112:115]
	v_mfma_f32_16x16x32_bf16 v[104:107], v[176:179], v[200:203], v[104:107]
	v_mfma_f32_16x16x32_bf16 v[96:99], v[184:187], v[200:203], v[96:99]
	v_mfma_f32_16x16x32_bf16 v[88:91], v[176:179], v[208:211], v[88:91]
	v_mfma_f32_16x16x32_bf16 v[80:83], v[184:187], v[208:211], v[80:83]
	v_mfma_f32_16x16x32_bf16 v[72:75], v[176:179], v[216:219], v[72:75]
	v_mfma_f32_16x16x32_bf16 v[64:67], v[184:187], v[216:219], v[64:67]
	v_mfma_f32_16x16x32_bf16 v[120:123], v[180:183], v[196:199], v[120:123]
	v_mfma_f32_16x16x32_bf16 v[112:115], v[188:191], v[196:199], v[112:115]
	v_mfma_f32_16x16x32_bf16 v[104:107], v[180:183], v[204:207], v[104:107]
	v_mfma_f32_16x16x32_bf16 v[96:99], v[188:191], v[204:207], v[96:99]
	v_mfma_f32_16x16x32_bf16 v[88:91], v[180:183], v[212:215], v[88:91]
	v_mfma_f32_16x16x32_bf16 v[80:83], v[188:191], v[212:215], v[80:83]
	v_mfma_f32_16x16x32_bf16 v[72:75], v[180:183], v[220:223], v[72:75]
	v_mfma_f32_16x16x32_bf16 v[64:67], v[188:191], v[220:223], v[64:67]
	s_setprio 0
	s_barrier
	s_add_i32 s46, s71, s49
	v_lshl_add_u64 v[154:155], v[154:155], 0, s[14:15]
	s_mov_b32 m0, s46
	ds_read_b128 v[192:195], v150 offset:49152
	v_xor_b32_e32 v253, 64, v150
	ds_read_b128 v[196:199], v253 offset:49152
	ds_read_b128 v[200:203], v150 offset:51200
	ds_read_b128 v[204:207], v253 offset:51200
	ds_read_b128 v[208:211], v150 offset:53248
	ds_read_b128 v[212:215], v253 offset:53248
	ds_read_b128 v[216:219], v150 offset:55296
	ds_read_b128 v[220:223], v253 offset:55296
	global_load_lds_dwordx4 v[154:155], off
	s_add_i32 m0, s46, 0x2000
	s_add_u32 s44, s44, 0x40080
	v_lshl_add_u64 v[154:155], v[224:225], 0, s[14:15]
	s_addc_u32 s45, s45, 0
	s_add_i32 s46, s72, s49
	global_load_lds_dwordx4 v[154:155], off
	v_lshl_add_u64 v[154:155], s[44:45], 0, v[132:133]
	s_mov_b32 m0, s46
	s_nop 0
	global_load_lds_dwordx4 v[154:155], off
	v_lshl_add_u64 v[154:155], s[44:45], 0, v[128:129]
	s_add_i32 m0, s46, 0x2000
	s_nop 0
	global_load_lds_dwordx4 v[154:155], off
	v_lshl_add_u64 v[154:155], v[226:227], 0, s[14:15]
	s_mov_b32 m0, s57
	s_nop 0
	global_load_lds_dwordx4 v[154:155], off
	v_lshl_add_u64 v[154:155], v[228:229], 0, s[14:15]
	s_mov_b32 m0, s58
	s_nop 0
	global_load_lds_dwordx4 v[154:155], off
	s_waitcnt vmcnt(8)
	s_waitcnt lgkmcnt(0)
	s_barrier
	s_setprio 1
	s_waitcnt lgkmcnt(0)
	v_mfma_f32_16x16x32_bf16 v[60:63], v[160:163], v[192:195], v[60:63]
	v_mfma_f32_16x16x32_bf16 v[52:55], v[168:171], v[192:195], v[52:55]
	v_mfma_f32_16x16x32_bf16 v[44:47], v[160:163], v[200:203], v[44:47]
	v_mfma_f32_16x16x32_bf16 v[36:39], v[168:171], v[200:203], v[36:39]
	v_mfma_f32_16x16x32_bf16 v[28:31], v[160:163], v[208:211], v[28:31]
	v_mfma_f32_16x16x32_bf16 v[20:23], v[168:171], v[208:211], v[20:23]
	v_mfma_f32_16x16x32_bf16 v[12:15], v[160:163], v[216:219], v[12:15]
	v_mfma_f32_16x16x32_bf16 v[4:7], v[168:171], v[216:219], v[4:7]
	v_mfma_f32_16x16x32_bf16 v[60:63], v[164:167], v[196:199], v[60:63]
	v_mfma_f32_16x16x32_bf16 v[52:55], v[172:175], v[196:199], v[52:55]
	v_mfma_f32_16x16x32_bf16 v[44:47], v[164:167], v[204:207], v[44:47]
	v_mfma_f32_16x16x32_bf16 v[36:39], v[172:175], v[204:207], v[36:39]
	v_mfma_f32_16x16x32_bf16 v[28:31], v[164:167], v[212:215], v[28:31]
	v_mfma_f32_16x16x32_bf16 v[20:23], v[172:175], v[212:215], v[20:23]
	v_mfma_f32_16x16x32_bf16 v[12:15], v[164:167], v[220:223], v[12:15]
	v_mfma_f32_16x16x32_bf16 v[4:7], v[172:175], v[220:223], v[4:7]
	s_setprio 0
	s_setprio 1
	v_mfma_f32_16x16x32_bf16 v[56:59], v[176:179], v[192:195], v[56:59]
	v_mfma_f32_16x16x32_bf16 v[48:51], v[184:187], v[192:195], v[48:51]
	v_mfma_f32_16x16x32_bf16 v[40:43], v[176:179], v[200:203], v[40:43]
	v_mfma_f32_16x16x32_bf16 v[32:35], v[184:187], v[200:203], v[32:35]
	v_mfma_f32_16x16x32_bf16 v[24:27], v[176:179], v[208:211], v[24:27]
	v_mfma_f32_16x16x32_bf16 v[16:19], v[184:187], v[208:211], v[16:19]
	v_mfma_f32_16x16x32_bf16 v[8:11], v[176:179], v[216:219], v[8:11]
	v_mfma_f32_16x16x32_bf16 v[0:3], v[184:187], v[216:219], v[0:3]
	v_mfma_f32_16x16x32_bf16 v[56:59], v[180:183], v[196:199], v[56:59]
	v_mfma_f32_16x16x32_bf16 v[48:51], v[188:191], v[196:199], v[48:51]
	v_mfma_f32_16x16x32_bf16 v[40:43], v[180:183], v[204:207], v[40:43]
	v_mfma_f32_16x16x32_bf16 v[32:35], v[188:191], v[204:207], v[32:35]
	v_mfma_f32_16x16x32_bf16 v[24:27], v[180:183], v[212:215], v[24:27]
	v_mfma_f32_16x16x32_bf16 v[16:19], v[188:191], v[212:215], v[16:19]
	v_mfma_f32_16x16x32_bf16 v[8:11], v[180:183], v[220:223], v[8:11]
	v_mfma_f32_16x16x32_bf16 v[0:3], v[188:191], v[220:223], v[0:3]
	s_setprio 0
	s_barrier
	s_add_i32 s70, s70, 2
	s_add_u32 s68, s68, 0x100
	s_addc_u32 s69, s69, 0
	s_add_u32 s30, s30, 0x100
	s_addc_u32 s31, s31, 0
	s_cmp_gt_u32 s70, 13
	s_cbranch_scc1 .LBB0_1100

.Llast_10:
	v_add_u32_e32 v153, s61, v147
	ds_read_b128 v[160:163], v153
	v_xor_b32_e32 v253, 64, v153
	ds_read_b128 v[164:167], v253
	ds_read_b128 v[168:171], v153 offset:2048
	ds_read_b128 v[172:175], v253 offset:2048
	v_add_u32_e32 v153, s62, v147
	ds_read_b128 v[176:179], v153
	v_xor_b32_e32 v253, 64, v153
	ds_read_b128 v[180:183], v253
	ds_read_b128 v[184:187], v153 offset:2048
	ds_read_b128 v[188:191], v253 offset:2048
	s_add_u32 s46, s30, 0xfffc0080
	s_addc_u32 s47, s31, -1
	s_and_b64 s[44:45], s[44:45], exec
	s_cselect_b32 s47, s25, s47
	s_cselect_b32 s46, s65, s46
	s_cselect_b32 s45, s66, s69
	s_cselect_b32 s44, s67, s68
	v_lshl_add_u64 v[154:155], s[30:31], 0, v[138:139]
	s_add_i32 m0, s52, 0xc000
	ds_read_b128 v[192:195], v150
	v_xor_b32_e32 v253, 64, v150
	ds_read_b128 v[196:199], v253
	ds_read_b128 v[200:203], v150 offset:2048
	ds_read_b128 v[204:207], v253 offset:2048
	ds_read_b128 v[208:211], v150 offset:4096
	ds_read_b128 v[212:215], v253 offset:4096
	ds_read_b128 v[216:219], v150 offset:6144
	ds_read_b128 v[220:223], v253 offset:6144
	global_load_lds_dwordx4 v[154:155], off
	v_lshl_add_u64 v[154:155], s[30:31], 0, v[136:137]
	s_add_i32 m0, s52, 0xe000
	s_nop 0
	global_load_lds_dwordx4 v[154:155], off
	s_waitcnt vmcnt(8)
	s_waitcnt lgkmcnt(0)
	s_barrier
	s_setprio 1
	s_waitcnt lgkmcnt(0)
	v_mfma_f32_16x16x32_bf16 v[124:127], v[160:163], v[192:195], v[124:127]
	v_mfma_f32_16x16x32_bf16 v[116:119], v[168:171], v[192:195], v[116:119]
	v_mfma_f32_16x16x32_bf16 v[108:111], v[160:163], v[200:203], v[108:111]
	v_mfma_f32_16x16x32_bf16 v[100:103], v[168:171], v[200:203], v[100:103]
	v_mfma_f32_16x16x32_bf16 v[92:95], v[160:163], v[208:211], v[92:95]
	v_mfma_f32_16x16x32_bf16 v[84:87], v[168:171], v[208:211], v[84:87]
	v_mfma_f32_16x16x32_bf16 v[76:79], v[160:163], v[216:219], v[76:79]
	v_mfma_f32_16x16x32_bf16 v[68:71], v[168:171], v[216:219], v[68:71]
	v_mfma_f32_16x16x32_bf16 v[124:127], v[164:167], v[196:199], v[124:127]
	v_mfma_f32_16x16x32_bf16 v[116:119], v[172:175], v[196:199], v[116:119]
	v_mfma_f32_16x16x32_bf16 v[108:111], v[164:167], v[204:207], v[108:111]
	v_mfma_f32_16x16x32_bf16 v[100:103], v[172:175], v[204:207], v[100:103]
	v_mfma_f32_16x16x32_bf16 v[92:95], v[164:167], v[212:215], v[92:95]
	v_mfma_f32_16x16x32_bf16 v[84:87], v[172:175], v[212:215], v[84:87]
	v_mfma_f32_16x16x32_bf16 v[76:79], v[164:167], v[220:223], v[76:79]
	v_mfma_f32_16x16x32_bf16 v[68:71], v[172:175], v[220:223], v[68:71]
	s_setprio 0
	s_setprio 1
	v_mfma_f32_16x16x32_bf16 v[120:123], v[176:179], v[192:195], v[120:123]
	v_mfma_f32_16x16x32_bf16 v[112:115], v[184:187], v[192:195], v[112:115]
	v_mfma_f32_16x16x32_bf16 v[104:107], v[176:179], v[200:203], v[104:107]
	v_mfma_f32_16x16x32_bf16 v[96:99], v[184:187], v[200:203], v[96:99]
	v_mfma_f32_16x16x32_bf16 v[88:91], v[176:179], v[208:211], v[88:91]
	v_mfma_f32_16x16x32_bf16 v[80:83], v[184:187], v[208:211], v[80:83]
	v_mfma_f32_16x16x32_bf16 v[72:75], v[176:179], v[216:219], v[72:75]
	v_mfma_f32_16x16x32_bf16 v[64:67], v[184:187], v[216:219], v[64:67]
	v_mfma_f32_16x16x32_bf16 v[120:123], v[180:183], v[196:199], v[120:123]
	v_mfma_f32_16x16x32_bf16 v[112:115], v[188:191], v[196:199], v[112:115]
	v_mfma_f32_16x16x32_bf16 v[104:107], v[180:183], v[204:207], v[104:107]
	v_mfma_f32_16x16x32_bf16 v[96:99], v[188:191], v[204:207], v[96:99]
	v_mfma_f32_16x16x32_bf16 v[88:91], v[180:183], v[212:215], v[88:91]
	v_mfma_f32_16x16x32_bf16 v[80:83], v[188:191], v[212:215], v[80:83]
	v_mfma_f32_16x16x32_bf16 v[72:75], v[180:183], v[220:223], v[72:75]
	v_mfma_f32_16x16x32_bf16 v[64:67], v[188:191], v[220:223], v[64:67]
	s_setprio 0
	s_barrier
	s_add_i32 s71, s61, s49
	v_lshl_add_u64 v[154:155], s[44:45], 0, v[132:133]
	s_mov_b32 m0, s71
	ds_read_b128 v[192:195], v150 offset:16384
	v_xor_b32_e32 v253, 64, v150
	ds_read_b128 v[196:199], v253 offset:16384
	ds_read_b128 v[200:203], v150 offset:18432
	ds_read_b128 v[204:207], v253 offset:18432
	ds_read_b128 v[208:211], v150 offset:20480
	ds_read_b128 v[212:215], v253 offset:20480
	ds_read_b128 v[216:219], v150 offset:22528
	ds_read_b128 v[220:223], v253 offset:22528
	global_load_lds_dwordx4 v[154:155], off
	s_add_i32 m0, s71, 0x2000
	s_add_u32 s72, s44, 0x40000
	v_lshl_add_u64 v[224:225], s[44:45], 0, v[128:129]
	s_addc_u32 s73, s45, 0
	s_add_i32 s71, s62, s49
	global_load_lds_dwordx4 v[224:225], off
	v_lshl_add_u64 v[226:227], s[72:73], 0, v[132:133]
	s_mov_b32 m0, s71
	v_lshl_add_u64 v[228:229], s[46:47], 0, v[130:131]
	global_load_lds_dwordx4 v[226:227], off
	v_lshl_add_u64 v[226:227], s[72:73], 0, v[128:129]
	s_add_i32 m0, s71, 0x2000
	s_nop 0
	global_load_lds_dwordx4 v[226:227], off
	v_lshl_add_u64 v[226:227], s[46:47], 0, v[134:135]
	s_mov_b32 m0, s52
	s_nop 0
	global_load_lds_dwordx4 v[226:227], off
	s_mov_b32 m0, s53
	s_nop 0
	global_load_lds_dwordx4 v[228:229], off
	s_waitcnt vmcnt(8)
	s_waitcnt lgkmcnt(0)
	s_barrier
	s_setprio 1
	s_waitcnt lgkmcnt(0)
	v_mfma_f32_16x16x32_bf16 v[60:63], v[160:163], v[192:195], v[60:63]
	v_mfma_f32_16x16x32_bf16 v[52:55], v[168:171], v[192:195], v[52:55]
	v_mfma_f32_16x16x32_bf16 v[44:47], v[160:163], v[200:203], v[44:47]
	v_mfma_f32_16x16x32_bf16 v[36:39], v[168:171], v[200:203], v[36:39]
	v_mfma_f32_16x16x32_bf16 v[28:31], v[160:163], v[208:211], v[28:31]
	v_mfma_f32_16x16x32_bf16 v[20:23], v[168:171], v[208:211], v[20:23]
	v_mfma_f32_16x16x32_bf16 v[12:15], v[160:163], v[216:219], v[12:15]
	v_mfma_f32_16x16x32_bf16 v[4:7], v[168:171], v[216:219], v[4:7]
	v_mfma_f32_16x16x32_bf16 v[60:63], v[164:167], v[196:199], v[60:63]
	v_mfma_f32_16x16x32_bf16 v[52:55], v[172:175], v[196:199], v[52:55]
	v_mfma_f32_16x16x32_bf16 v[44:47], v[164:167], v[204:207], v[44:47]
	v_mfma_f32_16x16x32_bf16 v[36:39], v[172:175], v[204:207], v[36:39]
	v_mfma_f32_16x16x32_bf16 v[28:31], v[164:167], v[212:215], v[28:31]
	v_mfma_f32_16x16x32_bf16 v[20:23], v[172:175], v[212:215], v[20:23]
	v_mfma_f32_16x16x32_bf16 v[12:15], v[164:167], v[220:223], v[12:15]
	v_mfma_f32_16x16x32_bf16 v[4:7], v[172:175], v[220:223], v[4:7]
	s_setprio 0
	s_setprio 1
	v_mfma_f32_16x16x32_bf16 v[56:59], v[176:179], v[192:195], v[56:59]
	v_mfma_f32_16x16x32_bf16 v[48:51], v[184:187], v[192:195], v[48:51]
	v_mfma_f32_16x16x32_bf16 v[40:43], v[176:179], v[200:203], v[40:43]
	v_mfma_f32_16x16x32_bf16 v[32:35], v[184:187], v[200:203], v[32:35]
	v_mfma_f32_16x16x32_bf16 v[24:27], v[176:179], v[208:211], v[24:27]
	v_mfma_f32_16x16x32_bf16 v[16:19], v[184:187], v[208:211], v[16:19]
	v_mfma_f32_16x16x32_bf16 v[8:11], v[176:179], v[216:219], v[8:11]
	v_mfma_f32_16x16x32_bf16 v[0:3], v[184:187], v[216:219], v[0:3]
	v_mfma_f32_16x16x32_bf16 v[56:59], v[180:183], v[196:199], v[56:59]
	v_mfma_f32_16x16x32_bf16 v[48:51], v[188:191], v[196:199], v[48:51]
	v_mfma_f32_16x16x32_bf16 v[40:43], v[180:183], v[204:207], v[40:43]
	v_mfma_f32_16x16x32_bf16 v[32:35], v[188:191], v[204:207], v[32:35]
	v_mfma_f32_16x16x32_bf16 v[24:27], v[180:183], v[212:215], v[24:27]
	v_mfma_f32_16x16x32_bf16 v[16:19], v[188:191], v[212:215], v[16:19]
	v_mfma_f32_16x16x32_bf16 v[8:11], v[180:183], v[220:223], v[8:11]
	v_mfma_f32_16x16x32_bf16 v[0:3], v[188:191], v[220:223], v[0:3]
	s_setprio 0
	s_barrier
	s_add_i32 s71, 0, 0x18000
	v_add_u32_e32 v153, s71, v147
	s_add_i32 s72, 0, 0x1c000
	ds_read_b128 v[160:163], v153
	v_xor_b32_e32 v253, 64, v153
	ds_read_b128 v[164:167], v253
	ds_read_b128 v[168:171], v153 offset:2048
	ds_read_b128 v[172:175], v253 offset:2048
	v_add_u32_e32 v153, s72, v147
	ds_read_b128 v[176:179], v153
	v_xor_b32_e32 v253, 64, v153
	ds_read_b128 v[180:183], v253
	ds_read_b128 v[184:187], v153 offset:2048
	ds_read_b128 v[188:191], v253 offset:2048
	s_add_u32 s46, s46, 0x40000
	s_addc_u32 s47, s47, 0
	s_mov_b32 m0, s54
	v_lshl_add_u64 v[230:231], s[46:47], 0, v[134:135]
	ds_read_b128 v[192:195], v150 offset:32768
	v_xor_b32_e32 v253, 64, v150
	ds_read_b128 v[196:199], v253 offset:32768
	ds_read_b128 v[200:203], v150 offset:34816
	ds_read_b128 v[204:207], v253 offset:34816
	ds_read_b128 v[208:211], v150 offset:36864
	ds_read_b128 v[212:215], v253 offset:36864
	ds_read_b128 v[216:219], v150 offset:38912
	ds_read_b128 v[220:223], v253 offset:38912
	global_load_lds_dwordx4 v[230:231], off
	v_lshl_add_u64 v[230:231], s[46:47], 0, v[130:131]
	s_mov_b32 m0, s55
	s_nop 0
	global_load_lds_dwordx4 v[230:231], off
	s_waitcnt vmcnt(8)
	s_waitcnt lgkmcnt(0)
	s_barrier
	s_setprio 1
	s_waitcnt lgkmcnt(0)
	v_mfma_f32_16x16x32_bf16 v[124:127], v[160:163], v[192:195], v[124:127]
	v_mfma_f32_16x16x32_bf16 v[116:119], v[168:171], v[192:195], v[116:119]
	v_mfma_f32_16x16x32_bf16 v[108:111], v[160:163], v[200:203], v[108:111]
	v_mfma_f32_16x16x32_bf16 v[100:103], v[168:171], v[200:203], v[100:103]
	v_mfma_f32_16x16x32_bf16 v[92:95], v[160:163], v[208:211], v[92:95]
	v_mfma_f32_16x16x32_bf16 v[84:87], v[168:171], v[208:211], v[84:87]
	v_mfma_f32_16x16x32_bf16 v[76:79], v[160:163], v[216:219], v[76:79]
	v_mfma_f32_16x16x32_bf16 v[68:71], v[168:171], v[216:219], v[68:71]
	v_mfma_f32_16x16x32_bf16 v[124:127], v[164:167], v[196:199], v[124:127]
	v_mfma_f32_16x16x32_bf16 v[116:119], v[172:175], v[196:199], v[116:119]
	v_mfma_f32_16x16x32_bf16 v[108:111], v[164:167], v[204:207], v[108:111]
	v_mfma_f32_16x16x32_bf16 v[100:103], v[172:175], v[204:207], v[100:103]
	v_mfma_f32_16x16x32_bf16 v[92:95], v[164:167], v[212:215], v[92:95]
	v_mfma_f32_16x16x32_bf16 v[84:87], v[172:175], v[212:215], v[84:87]
	v_mfma_f32_16x16x32_bf16 v[76:79], v[164:167], v[220:223], v[76:79]
	v_mfma_f32_16x16x32_bf16 v[68:71], v[172:175], v[220:223], v[68:71]
	s_setprio 0
	s_setprio 1
	v_mfma_f32_16x16x32_bf16 v[120:123], v[176:179], v[192:195], v[120:123]
	v_mfma_f32_16x16x32_bf16 v[112:115], v[184:187], v[192:195], v[112:115]
	v_mfma_f32_16x16x32_bf16 v[104:107], v[176:179], v[200:203], v[104:107]
	v_mfma_f32_16x16x32_bf16 v[96:99], v[184:187], v[200:203], v[96:99]
	v_mfma_f32_16x16x32_bf16 v[88:91], v[176:179], v[208:211], v[88:91]
	v_mfma_f32_16x16x32_bf16 v[80:83], v[184:187], v[208:211], v[80:83]
	v_mfma_f32_16x16x32_bf16 v[72:75], v[176:179], v[216:219], v[72:75]
	v_mfma_f32_16x16x32_bf16 v[64:67], v[184:187], v[216:219], v[64:67]
	v_mfma_f32_16x16x32_bf16 v[120:123], v[180:183], v[196:199], v[120:123]
	v_mfma_f32_16x16x32_bf16 v[112:115], v[188:191], v[196:199], v[112:115]
	v_mfma_f32_16x16x32_bf16 v[104:107], v[180:183], v[204:207], v[104:107]
	v_mfma_f32_16x16x32_bf16 v[96:99], v[188:191], v[204:207], v[96:99]
	v_mfma_f32_16x16x32_bf16 v[88:91], v[180:183], v[212:215], v[88:91]
	v_mfma_f32_16x16x32_bf16 v[80:83], v[188:191], v[212:215], v[80:83]
	v_mfma_f32_16x16x32_bf16 v[72:75], v[180:183], v[220:223], v[72:75]
	v_mfma_f32_16x16x32_bf16 v[64:67], v[188:191], v[220:223], v[64:67]
	s_setprio 0
	s_barrier
	v_add_u32_e32 v234, 0x21000, v151
	ds_read_b128 v[236:239], v234
	ds_read_b128 v[240:243], v234 offset:256
	ds_read_b128 v[244:247], v234 offset:512
	ds_read_b128 v[248:251], v234 offset:768
	v_add_u32_e32 v235, s23, v146
	v_mul_u32_u24_e32 v235, 0x1600, v235
	v_lshl_or_b32 v234, s64, 7, v149
	v_lshl_add_u32 v235, v234, 1, v235
	s_add_i32 s46, s71, s49
	v_lshl_add_u64 v[154:155], v[154:155], 0, s[14:15]
	s_mov_b32 m0, s46
	ds_read_b128 v[192:195], v150 offset:49152
	v_xor_b32_e32 v253, 64, v150
	ds_read_b128 v[196:199], v253 offset:49152
	ds_read_b128 v[200:203], v150 offset:51200
	ds_read_b128 v[204:207], v253 offset:51200
	ds_read_b128 v[208:211], v150 offset:53248
	ds_read_b128 v[212:215], v253 offset:53248
	ds_read_b128 v[216:219], v150 offset:55296
	ds_read_b128 v[220:223], v253 offset:55296
	global_load_lds_dwordx4 v[154:155], off
	s_add_i32 m0, s46, 0x2000
	s_add_u32 s44, s44, 0x40080
	v_lshl_add_u64 v[154:155], v[224:225], 0, s[14:15]
	s_addc_u32 s45, s45, 0
	s_add_i32 s46, s72, s49
	global_load_lds_dwordx4 v[154:155], off
	v_lshl_add_u64 v[154:155], s[44:45], 0, v[132:133]
	s_mov_b32 m0, s46
	s_nop 0
	global_load_lds_dwordx4 v[154:155], off
	v_lshl_add_u64 v[154:155], s[44:45], 0, v[128:129]
	s_add_i32 m0, s46, 0x2000
	s_nop 0
	global_load_lds_dwordx4 v[154:155], off
	v_lshl_add_u64 v[154:155], v[226:227], 0, s[14:15]
	s_mov_b32 m0, s57
	s_nop 0
	global_load_lds_dwordx4 v[154:155], off
	v_lshl_add_u64 v[154:155], v[228:229], 0, s[14:15]
	s_mov_b32 m0, s58
	s_nop 0
	global_load_lds_dwordx4 v[154:155], off
	s_waitcnt lgkmcnt(8)
	v_add_f32_e32 v236, v236, v237
	v_add_f32_e32 v238, v238, v239
	v_add_f32_e32 v240, v240, v241
	v_add_f32_e32 v242, v242, v243
	v_add_f32_e32 v244, v244, v245
	v_add_f32_e32 v246, v246, v247
	v_add_f32_e32 v248, v248, v249
	v_add_f32_e32 v250, v250, v251
	v_add_f32_e32 v236, v236, v238
	v_add_f32_e32 v240, v240, v242
	v_add_f32_e32 v244, v244, v246
	v_add_f32_e32 v248, v248, v250
	v_fmamk_f32 v236, v236, 0x3a800000, v152
	v_fmamk_f32 v240, v240, 0x3a800000, v152
	v_fmamk_f32 v244, v244, 0x3a800000, v152
	v_fmamk_f32 v248, v248, 0x3a800000, v152
	v_rsq_f32_e32 v236, v236
	v_rsq_f32_e32 v240, v240
	v_rsq_f32_e32 v244, v244
	v_rsq_f32_e32 v248, v248
	v_mul_f32_e32 v252, 0xbfb8aa3b, v236
	v_mul_f32_e32 v254, v236, v236
	v_pk_mul_f32 v[120:121], v[124:125], v[120:121]
	v_pk_mul_f32 v[122:123], v[126:127], v[122:123]
	v_pk_mul_f32 v[112:113], v[116:117], v[112:113]
	v_pk_mul_f32 v[114:115], v[118:119], v[114:115]
	v_pk_mul_f32 v[124:125], v[124:125], v[252:253] op_sel_hi:[1,0]
	v_pk_mul_f32 v[126:127], v[126:127], v[252:253] op_sel_hi:[1,0]
	v_pk_mul_f32 v[116:117], v[116:117], v[252:253] op_sel_hi:[1,0]
	v_pk_mul_f32 v[118:119], v[118:119], v[252:253] op_sel_hi:[1,0]
	v_exp_f32_e32 v124, v124
	v_exp_f32_e32 v125, v125
	v_exp_f32_e32 v126, v126
	v_exp_f32_e32 v127, v127
	v_exp_f32_e32 v116, v116
	v_exp_f32_e32 v117, v117
	v_exp_f32_e32 v118, v118
	v_exp_f32_e32 v119, v119
	v_pk_add_f32 v[124:125], v[124:125], 1.0 op_sel_hi:[1,0]
	v_pk_add_f32 v[126:127], v[126:127], 1.0 op_sel_hi:[1,0]
	v_pk_add_f32 v[116:117], v[116:117], 1.0 op_sel_hi:[1,0]
	v_pk_add_f32 v[118:119], v[118:119], 1.0 op_sel_hi:[1,0]
	v_rcp_f32_e32 v124, v124
	v_rcp_f32_e32 v125, v125
	v_rcp_f32_e32 v126, v126
	v_rcp_f32_e32 v127, v127
	v_rcp_f32_e32 v116, v116
	v_rcp_f32_e32 v117, v117
	v_rcp_f32_e32 v118, v118
	v_rcp_f32_e32 v119, v119
	v_pk_mul_f32 v[120:121], v[120:121], v[254:255] op_sel_hi:[1,0]
	v_pk_mul_f32 v[122:123], v[122:123], v[254:255] op_sel_hi:[1,0]
	v_pk_mul_f32 v[112:113], v[112:113], v[254:255] op_sel_hi:[1,0]
	v_pk_mul_f32 v[114:115], v[114:115], v[254:255] op_sel_hi:[1,0]
	v_pk_mul_f32 v[120:121], v[120:121], v[124:125]
	v_pk_mul_f32 v[122:123], v[122:123], v[126:127]
	v_pk_mul_f32 v[112:113], v[112:113], v[116:117]
	v_pk_mul_f32 v[114:115], v[114:115], v[118:119]
	v_cvt_pk_bf16_f32 v120, v120, v121
	v_cvt_pk_bf16_f32 v121, v122, v123
	v_cvt_pk_bf16_f32 v122, v112, v113
	v_cvt_pk_bf16_f32 v123, v114, v115
	global_store_dwordx4 v235, v[120:123], s[10:11]
	v_add_u32_e32 v234, 0x16000, v235
	v_mul_f32_e32 v252, 0xbfb8aa3b, v240
	v_mul_f32_e32 v254, v240, v240
	v_pk_mul_f32 v[104:105], v[108:109], v[104:105]
	v_pk_mul_f32 v[106:107], v[110:111], v[106:107]
	v_pk_mul_f32 v[96:97], v[100:101], v[96:97]
	v_pk_mul_f32 v[98:99], v[102:103], v[98:99]
	v_pk_mul_f32 v[108:109], v[108:109], v[252:253] op_sel_hi:[1,0]
	v_pk_mul_f32 v[110:111], v[110:111], v[252:253] op_sel_hi:[1,0]
	v_pk_mul_f32 v[100:101], v[100:101], v[252:253] op_sel_hi:[1,0]
	v_pk_mul_f32 v[102:103], v[102:103], v[252:253] op_sel_hi:[1,0]
	v_exp_f32_e32 v108, v108
	v_exp_f32_e32 v109, v109
	v_exp_f32_e32 v110, v110
	v_exp_f32_e32 v111, v111
	v_exp_f32_e32 v100, v100
	v_exp_f32_e32 v101, v101
	v_exp_f32_e32 v102, v102
	v_exp_f32_e32 v103, v103
	v_pk_add_f32 v[108:109], v[108:109], 1.0 op_sel_hi:[1,0]
	v_pk_add_f32 v[110:111], v[110:111], 1.0 op_sel_hi:[1,0]
	v_pk_add_f32 v[100:101], v[100:101], 1.0 op_sel_hi:[1,0]
	v_pk_add_f32 v[102:103], v[102:103], 1.0 op_sel_hi:[1,0]
	v_rcp_f32_e32 v108, v108
	v_rcp_f32_e32 v109, v109
	v_rcp_f32_e32 v110, v110
	v_rcp_f32_e32 v111, v111
	v_rcp_f32_e32 v100, v100
	v_rcp_f32_e32 v101, v101
	v_rcp_f32_e32 v102, v102
	v_rcp_f32_e32 v103, v103
	v_pk_mul_f32 v[104:105], v[104:105], v[254:255] op_sel_hi:[1,0]
	v_pk_mul_f32 v[106:107], v[106:107], v[254:255] op_sel_hi:[1,0]
	v_pk_mul_f32 v[96:97], v[96:97], v[254:255] op_sel_hi:[1,0]
	v_pk_mul_f32 v[98:99], v[98:99], v[254:255] op_sel_hi:[1,0]
	v_pk_mul_f32 v[104:105], v[104:105], v[108:109]
	v_pk_mul_f32 v[106:107], v[106:107], v[110:111]
	v_pk_mul_f32 v[96:97], v[96:97], v[100:101]
	v_pk_mul_f32 v[98:99], v[98:99], v[102:103]
	v_cvt_pk_bf16_f32 v104, v104, v105
	v_cvt_pk_bf16_f32 v105, v106, v107
	v_cvt_pk_bf16_f32 v106, v96, v97
	v_cvt_pk_bf16_f32 v107, v98, v99
	global_store_dwordx4 v234, v[104:107], s[10:11]
	v_add_u32_e32 v235, 0x16000, v234
	v_mul_f32_e32 v252, 0xbfb8aa3b, v244
	v_mul_f32_e32 v254, v244, v244
	v_pk_mul_f32 v[88:89], v[92:93], v[88:89]
	v_pk_mul_f32 v[90:91], v[94:95], v[90:91]
	v_pk_mul_f32 v[80:81], v[84:85], v[80:81]
	v_pk_mul_f32 v[82:83], v[86:87], v[82:83]
	v_pk_mul_f32 v[92:93], v[92:93], v[252:253] op_sel_hi:[1,0]
	v_pk_mul_f32 v[94:95], v[94:95], v[252:253] op_sel_hi:[1,0]
	v_pk_mul_f32 v[84:85], v[84:85], v[252:253] op_sel_hi:[1,0]
	v_pk_mul_f32 v[86:87], v[86:87], v[252:253] op_sel_hi:[1,0]
	v_exp_f32_e32 v92, v92
	v_exp_f32_e32 v93, v93
	v_exp_f32_e32 v94, v94
	v_exp_f32_e32 v95, v95
	v_exp_f32_e32 v84, v84
	v_exp_f32_e32 v85, v85
	v_exp_f32_e32 v86, v86
	v_exp_f32_e32 v87, v87
	v_pk_add_f32 v[92:93], v[92:93], 1.0 op_sel_hi:[1,0]
	v_pk_add_f32 v[94:95], v[94:95], 1.0 op_sel_hi:[1,0]
	v_pk_add_f32 v[84:85], v[84:85], 1.0 op_sel_hi:[1,0]
	v_pk_add_f32 v[86:87], v[86:87], 1.0 op_sel_hi:[1,0]
	v_rcp_f32_e32 v92, v92
	v_rcp_f32_e32 v93, v93
	v_rcp_f32_e32 v94, v94
	v_rcp_f32_e32 v95, v95
	v_rcp_f32_e32 v84, v84
	v_rcp_f32_e32 v85, v85
	v_rcp_f32_e32 v86, v86
	v_rcp_f32_e32 v87, v87
	v_pk_mul_f32 v[88:89], v[88:89], v[254:255] op_sel_hi:[1,0]
	v_pk_mul_f32 v[90:91], v[90:91], v[254:255] op_sel_hi:[1,0]
	v_pk_mul_f32 v[80:81], v[80:81], v[254:255] op_sel_hi:[1,0]
	v_pk_mul_f32 v[82:83], v[82:83], v[254:255] op_sel_hi:[1,0]
	v_pk_mul_f32 v[88:89], v[88:89], v[92:93]
	v_pk_mul_f32 v[90:91], v[90:91], v[94:95]
	v_pk_mul_f32 v[80:81], v[80:81], v[84:85]
	v_pk_mul_f32 v[82:83], v[82:83], v[86:87]
	v_cvt_pk_bf16_f32 v88, v88, v89
	v_cvt_pk_bf16_f32 v89, v90, v91
	v_cvt_pk_bf16_f32 v90, v80, v81
	v_cvt_pk_bf16_f32 v91, v82, v83
	global_store_dwordx4 v235, v[88:91], s[10:11]
	v_add_u32_e32 v234, 0x16000, v235
	v_mul_f32_e32 v252, 0xbfb8aa3b, v248
	v_mul_f32_e32 v254, v248, v248
	v_pk_mul_f32 v[72:73], v[76:77], v[72:73]
	v_pk_mul_f32 v[74:75], v[78:79], v[74:75]
	v_pk_mul_f32 v[64:65], v[68:69], v[64:65]
	v_pk_mul_f32 v[66:67], v[70:71], v[66:67]
	v_pk_mul_f32 v[76:77], v[76:77], v[252:253] op_sel_hi:[1,0]
	v_pk_mul_f32 v[78:79], v[78:79], v[252:253] op_sel_hi:[1,0]
	v_pk_mul_f32 v[68:69], v[68:69], v[252:253] op_sel_hi:[1,0]
	v_pk_mul_f32 v[70:71], v[70:71], v[252:253] op_sel_hi:[1,0]
	v_exp_f32_e32 v76, v76
	v_exp_f32_e32 v77, v77
	v_exp_f32_e32 v78, v78
	v_exp_f32_e32 v79, v79
	v_exp_f32_e32 v68, v68
	v_exp_f32_e32 v69, v69
	v_exp_f32_e32 v70, v70
	v_exp_f32_e32 v71, v71
	v_pk_add_f32 v[76:77], v[76:77], 1.0 op_sel_hi:[1,0]
	v_pk_add_f32 v[78:79], v[78:79], 1.0 op_sel_hi:[1,0]
	v_pk_add_f32 v[68:69], v[68:69], 1.0 op_sel_hi:[1,0]
	v_pk_add_f32 v[70:71], v[70:71], 1.0 op_sel_hi:[1,0]
	v_rcp_f32_e32 v76, v76
	v_rcp_f32_e32 v77, v77
	v_rcp_f32_e32 v78, v78
	v_rcp_f32_e32 v79, v79
	v_rcp_f32_e32 v68, v68
	v_rcp_f32_e32 v69, v69
	v_rcp_f32_e32 v70, v70
	v_rcp_f32_e32 v71, v71
	v_pk_mul_f32 v[72:73], v[72:73], v[254:255] op_sel_hi:[1,0]
	v_pk_mul_f32 v[74:75], v[74:75], v[254:255] op_sel_hi:[1,0]
	v_pk_mul_f32 v[64:65], v[64:65], v[254:255] op_sel_hi:[1,0]
	v_pk_mul_f32 v[66:67], v[66:67], v[254:255] op_sel_hi:[1,0]
	v_pk_mul_f32 v[72:73], v[72:73], v[76:77]
	v_pk_mul_f32 v[74:75], v[74:75], v[78:79]
	v_pk_mul_f32 v[64:65], v[64:65], v[68:69]
	v_pk_mul_f32 v[66:67], v[66:67], v[70:71]
	v_cvt_pk_bf16_f32 v72, v72, v73
	v_cvt_pk_bf16_f32 v73, v74, v75
	v_cvt_pk_bf16_f32 v74, v64, v65
	v_cvt_pk_bf16_f32 v75, v66, v67
	global_store_dwordx4 v234, v[72:75], s[10:11]
	s_waitcnt vmcnt(12)
	s_waitcnt lgkmcnt(0)
	s_barrier
	s_setprio 1
	s_waitcnt lgkmcnt(0)
	v_mfma_f32_16x16x32_bf16 v[60:63], v[160:163], v[192:195], v[60:63]
	v_mfma_f32_16x16x32_bf16 v[52:55], v[168:171], v[192:195], v[52:55]
	v_mfma_f32_16x16x32_bf16 v[44:47], v[160:163], v[200:203], v[44:47]
	v_mfma_f32_16x16x32_bf16 v[36:39], v[168:171], v[200:203], v[36:39]
	v_mfma_f32_16x16x32_bf16 v[28:31], v[160:163], v[208:211], v[28:31]
	v_mfma_f32_16x16x32_bf16 v[20:23], v[168:171], v[208:211], v[20:23]
	v_mfma_f32_16x16x32_bf16 v[12:15], v[160:163], v[216:219], v[12:15]
	v_mfma_f32_16x16x32_bf16 v[4:7], v[168:171], v[216:219], v[4:7]
	v_mfma_f32_16x16x32_bf16 v[60:63], v[164:167], v[196:199], v[60:63]
	v_mfma_f32_16x16x32_bf16 v[52:55], v[172:175], v[196:199], v[52:55]
	v_mfma_f32_16x16x32_bf16 v[44:47], v[164:167], v[204:207], v[44:47]
	v_mfma_f32_16x16x32_bf16 v[36:39], v[172:175], v[204:207], v[36:39]
	v_mfma_f32_16x16x32_bf16 v[28:31], v[164:167], v[212:215], v[28:31]
	v_mfma_f32_16x16x32_bf16 v[20:23], v[172:175], v[212:215], v[20:23]
	v_mfma_f32_16x16x32_bf16 v[12:15], v[164:167], v[220:223], v[12:15]
	v_mfma_f32_16x16x32_bf16 v[4:7], v[172:175], v[220:223], v[4:7]
	s_setprio 0
	s_setprio 1
	v_mfma_f32_16x16x32_bf16 v[56:59], v[176:179], v[192:195], v[56:59]
	v_mfma_f32_16x16x32_bf16 v[48:51], v[184:187], v[192:195], v[48:51]
	v_mfma_f32_16x16x32_bf16 v[40:43], v[176:179], v[200:203], v[40:43]
	v_mfma_f32_16x16x32_bf16 v[32:35], v[184:187], v[200:203], v[32:35]
	v_mfma_f32_16x16x32_bf16 v[24:27], v[176:179], v[208:211], v[24:27]
	v_mfma_f32_16x16x32_bf16 v[16:19], v[184:187], v[208:211], v[16:19]
	v_mfma_f32_16x16x32_bf16 v[8:11], v[176:179], v[216:219], v[8:11]
	v_mfma_f32_16x16x32_bf16 v[0:3], v[184:187], v[216:219], v[0:3]
	v_mfma_f32_16x16x32_bf16 v[56:59], v[180:183], v[196:199], v[56:59]
	v_mfma_f32_16x16x32_bf16 v[48:51], v[188:191], v[196:199], v[48:51]
	v_mfma_f32_16x16x32_bf16 v[40:43], v[180:183], v[204:207], v[40:43]
	v_mfma_f32_16x16x32_bf16 v[32:35], v[188:191], v[204:207], v[32:35]
	v_mfma_f32_16x16x32_bf16 v[24:27], v[180:183], v[212:215], v[24:27]
	v_mfma_f32_16x16x32_bf16 v[16:19], v[188:191], v[212:215], v[16:19]
	v_mfma_f32_16x16x32_bf16 v[8:11], v[180:183], v[220:223], v[8:11]
	v_mfma_f32_16x16x32_bf16 v[0:3], v[188:191], v[220:223], v[0:3]
	s_setprio 0
	s_barrier
	s_add_i32 s70, s70, 2
	s_add_u32 s68, s68, 0x100
	s_addc_u32 s69, s69, 0
	s_add_u32 s30, s30, 0x100
	s_addc_u32 s31, s31, 0

.LBB0_1164:
	s_and_b64 vcc, exec, s[4:5]
	s_cbranch_vccnz .LBB0_1206
	v_ashrrev_i32_e32 v1, 31, v8
	v_lshrrev_b32_e32 v1, 26, v1
	v_add_u32_e32 v1, v8, v1
	v_ashrrev_i32_e32 v9, 6, v1
	v_bfe_i32 v1, v8, 27, 1
	v_lshlrev_b32_e32 v0, 4, v8
	v_lshrrev_b32_e32 v1, 22, v1
	v_add_u32_e32 v1, v0, v1
	v_and_b32_e32 v1, 0xfffffc00, v1
	v_sub_u32_e32 v1, v0, v1
	v_lshrrev_b32_e32 v2, 4, v1
	v_bitop3_b32 v1, v2, v1, 32 bitop3:0x6c
	v_ashrrev_i32_e32 v3, 31, v1
	v_lshrrev_b32_e32 v3, 26, v3
	v_lshlrev_b32_e32 v2, 3, v9
	v_add_u32_e32 v3, v1, v3
	v_and_b32_e32 v2, -16, v2
	v_ashrrev_i32_e32 v10, 6, v3
	v_and_b32_e32 v3, 0xc0, v3
	v_add_u32_e32 v2, v10, v2
	v_lshlrev_b32_e32 v4, 5, v9
	v_sub_u32_e32 v1, v1, v3
	v_mov_b32_e32 v3, 1
	v_and_b32_e32 v11, 32, v4
	v_ashrrev_i16_sdwa v1, v3, sext(v1) dst_sel:DWORD dst_unused:UNUSED_PAD src0_sel:DWORD src1_sel:BYTE_0
	v_lshlrev_b32_e32 v4, 1, v2
	v_lshrrev_b32_e32 v5, 2, v2
	v_and_b32_e32 v6, 3, v10
	s_mov_b32 s4, 0xffffe0
	v_bfe_i32 v12, v1, 0, 16
	v_and_b32_e32 v4, 24, v4
	v_and_b32_e32 v5, 4, v5
	v_and_or_b32 v6, v2, s4, v6
	s_movk_i32 s8, 0xb00
	v_add_u32_e32 v1, v11, v12
	v_or3_b32 v4, v6, v5, v4
	v_mul_lo_u32 v2, v2, s8
	v_add_lshl_u32 v152, v1, v2, 1
	v_lshrrev_b32_e32 v250, 3, v157
	v_and_b32_e32 v251, 6, v250
	v_and_b32_e32 v252, 7, v157
	v_xor_b32_e32 v251, v251, v252
	v_lshlrev_b32_e32 v251, 4, v251
	v_mul_u32_u24_e32 v250, 0x1600, v250
	v_add_u32_e32 v152, v250, v251
	v_mul_u32_u24_e32 v2, 0xb00, v4
	v_add_u32_e32 v0, 0x2000, v0
	v_add_lshl_u32 v154, v2, v1, 1
	v_lshrrev_b32_e32 v250, 3, v157
	v_and_b32_e32 v251, 6, v250
	v_and_b32_e32 v252, 7, v157
	v_xor_b32_e32 v251, v251, v252
	v_lshlrev_b32_e32 v251, 4, v251
	v_and_b32_e32 v252, 12, v250
	v_lshlrev_b32_e32 v252, 1, v252
	v_and_b32_e32 v253, 16, v250
	v_lshrrev_b32_e32 v253, 2, v253
	v_or_b32_e32 v252, v252, v253
	v_and_b32_e32 v253, 35, v250
	v_or_b32_e32 v250, v252, v253
	v_mul_u32_u24_e32 v250, 0x1600, v250
	v_add_u32_e32 v154, v250, v251
	v_ashrrev_i32_e32 v1, 31, v0
	v_lshrrev_b32_e32 v1, 22, v1
	v_add_u32_e32 v1, v0, v1
	v_ashrrev_i32_e32 v13, 10, v1
	v_mul_i32_i24_e32 v1, 0x400, v13
	v_sub_u32_e32 v0, v0, v1
	v_lshrrev_b32_e32 v1, 4, v0
	v_bitop3_b32 v0, v1, v0, 32 bitop3:0x6c
	v_ashrrev_i32_e32 v2, 31, v0
	s_waitcnt lgkmcnt(0)
	s_add_u32 s33, s6, 0xa000000
	v_lshrrev_b32_e32 v2, 26, v2
	s_addc_u32 s35, s7, 0
	v_lshlrev_b32_e32 v1, 3, v13
	v_add_u32_e32 v2, v0, v2
	s_add_u32 s56, s6, 0x4080000
	v_and_b32_e32 v1, -16, v1
	v_ashrrev_i32_e32 v15, 6, v2
	v_lshlrev_b32_e32 v4, 5, v13
	s_addc_u32 s57, s7, 0
	s_ashr_i32 s3, s10, 6
	v_add_u32_e32 v1, v15, v1
	v_and_b32_e32 v14, 32, v4
	v_and_b32_e32 v2, 0xc0, v2
	v_and_b32_e32 v4, 3, v15
	v_sub_u32_e32 v0, v0, v2
	v_and_or_b32 v4, v1, s4, v4
	s_ashr_i32 s4, s10, 8
	s_lshl_b32 s58, s3, 10
	s_mul_i32 s14, s12, 0x160000
	v_ashrrev_i16_sdwa v0, v3, sext(v0) dst_sel:DWORD dst_unused:UNUSED_PAD src0_sel:DWORD src1_sel:BYTE_0
	v_lshlrev_b32_e32 v2, 1, v1
	v_lshrrev_b32_e32 v3, 2, v1
	s_mul_hi_i32 s11, s12, 0x160000
	s_add_u32 s50, s56, s14
	v_bfe_i32 v16, v0, 0, 16
	v_and_b32_e32 v2, 24, v2
	v_and_b32_e32 v3, 4, v3
	s_addc_u32 s51, s57, s11
	s_add_i32 s59, s58, 0
	v_add_u32_e32 v0, v14, v16
	v_or3_b32 v2, v4, v3, v2
	v_mul_lo_u32 v1, v1, s8
	s_add_i32 m0, s59, 0x10000
	v_add_lshl_u32 v160, v0, v1, 1
	v_lshrrev_b32_e32 v250, 3, v157
	v_and_b32_e32 v251, 6, v250
	v_and_b32_e32 v252, 7, v157
	v_xor_b32_e32 v251, v251, v252
	v_lshlrev_b32_e32 v251, 4, v251
	v_mul_u32_u24_e32 v250, 0x1600, v250
	v_add_u32_e32 v160, v250, v251
	v_add_u32_e32 v160, 0x58000, v160
	v_mul_u32_u24_e32 v1, 0xb00, v2
	global_load_lds_dwordx4 v154, s[50:51]
	s_add_i32 m0, s59, 0x12000
	v_add_lshl_u32 v162, v1, v0, 1
	v_lshrrev_b32_e32 v250, 3, v157
	v_and_b32_e32 v251, 6, v250
	v_and_b32_e32 v252, 7, v157
	v_xor_b32_e32 v251, v251, v252
	v_lshlrev_b32_e32 v251, 4, v251
	v_and_b32_e32 v252, 12, v250
	v_lshlrev_b32_e32 v252, 1, v252
	v_and_b32_e32 v253, 16, v250
	v_lshrrev_b32_e32 v253, 2, v253
	v_or_b32_e32 v252, v252, v253
	v_and_b32_e32 v253, 35, v250
	v_or_b32_e32 v250, v252, v253
	v_mul_u32_u24_e32 v250, 0x1600, v250
	v_add_u32_e32 v162, v250, v251
	v_add_u32_e32 v162, 0x58000, v162
	s_add_u32 s14, s50, 0xb0000
	global_load_lds_dwordx4 v162, s[50:51]
	s_addc_u32 s15, s51, 0
	s_add_i32 m0, s59, 0x14000
	s_mul_i32 s9, s13, 0x160000
	global_load_lds_dwordx4 v154, s[14:15]
	s_add_i32 m0, s59, 0x16000
	s_mul_hi_i32 s5, s13, 0x160000
	s_add_u32 s48, s33, s9
	s_addc_u32 s49, s35, s5
	s_add_i32 s60, s59, 0x2000
	global_load_lds_dwordx4 v162, s[14:15]
	s_mov_b32 m0, s59
	s_add_u32 s14, s48, 0xb0000
	global_load_lds_dwordx4 v152, s[48:49]
	s_mov_b32 m0, s60
	s_addc_u32 s15, s49, 0
	s_add_i32 s61, s59, 0x4000
	global_load_lds_dwordx4 v160, s[48:49]
	s_mov_b32 m0, s61
	s_add_i32 s62, s59, 0x6000
	global_load_lds_dwordx4 v152, s[14:15]
	s_mov_b32 m0, s62
	v_mov_b32_e32 v155, 0
	global_load_lds_dwordx4 v160, s[14:15]
	v_mov_b32_e32 v163, v155
	v_mov_b32_e32 v153, v155
	v_mov_b32_e32 v161, v155
	s_cmp_eq_u32 s4, 1
	s_mov_b32 s63, 0
	v_lshl_add_u64 v[6:7], s[50:51], 0, v[154:155]
	v_lshl_add_u64 v[4:5], s[50:51], 0, v[162:163]
	v_lshl_add_u64 v[0:1], s[48:49], 0, v[152:153]
	s_cselect_b64 s[14:15], -1, 0
	s_cmp_lg_u32 s4, 1
	v_lshl_add_u64 v[2:3], s[48:49], 0, v[160:161]
	s_cbranch_scc1 .LBB0_1167
	s_barrier
.LBB0_1167:
	s_add_u32 s16, s6, 0x6000000
	s_addc_u32 s17, s7, 0
	s_add_u32 s20, s6, 0x100000
	s_mov_b64 s[22:23], 0x80
	s_addc_u32 s21, s7, 0
	s_and_b32 s9, s3, 3
	s_add_i32 m0, s59, 0x18000
	v_lshl_add_u64 v[6:7], v[6:7], 0, s[22:23]
	s_lshl_b32 s5, s4, 13
	s_lshl_b32 s11, s9, 12
	s_waitcnt vmcnt(2)
	s_barrier
	global_load_lds_dwordx4 v[6:7], off
	v_lshl_add_u64 v[4:5], v[4:5], 0, s[22:23]
	s_add_i32 m0, s59, 0x1a000
	s_add_i32 s3, s59, 0x8000
	s_add_i32 s64, s59, 0xa000
	global_load_lds_dwordx4 v[4:5], off
	v_lshl_add_u64 v[0:1], v[0:1], 0, s[22:23]
	s_mov_b32 m0, s3
	s_add_u32 s6, s50, 0xb0080
	global_load_lds_dwordx4 v[0:1], off
	v_lshl_add_u64 v[0:1], v[2:3], 0, s[22:23]
	s_mov_b32 m0, s64
	s_addc_u32 s7, s51, 0
	global_load_lds_dwordx4 v[0:1], off
	s_add_i32 m0, s59, 0x1c000
	v_lshl_add_u64 v[0:1], s[6:7], 0, v[154:155]
	global_load_lds_dwordx4 v[0:1], off
	v_lshl_add_u64 v[0:1], s[6:7], 0, v[162:163]
	s_add_i32 m0, s59, 0x1e000
	s_cmpk_lt_u32 s10, 0x100
	global_load_lds_dwordx4 v[0:1], off
	v_bfe_u32 v0, v8, 4, 2
	v_lshlrev_b32_e32 v2, 3, v0
	v_and_b32_e32 v1, 15, v8
	v_lshlrev_b32_e32 v3, 4, v0
	v_lshl_or_b32 v186, s9, 5, v2
	s_cselect_b64 s[24:25], -1, 0
	s_lshl_b32 s9, s9, 2
	v_lshl_or_b32 v184, s4, 6, v1
	v_lshl_or_b32 v1, v1, 6, v3
	v_lshlrev_b32_e32 v3, 2, v8
	s_add_i32 s9, s9, 0
	v_and_b32_e32 v3, 32, v3
	s_add_i32 s9, s9, 0x20000
	v_bitop3_b32 v4, v1, s5, v3 bitop3:0xde
	v_bitop3_b32 v185, v1, s11, v3 bitop3:0xde
	v_and_b32_e32 v250, 15, v157
	v_bfe_u32 v251, v157, 4, 2
	v_and_b32_e32 v252, 2, v250
	v_xor_b32_e32 v251, v251, v252
	v_and_b32_e32 v252, 4, v250
	v_lshlrev_b32_e32 v252, 4, v252
	v_lshl_or_b32 v251, v251, 4, v252
	v_lshl_or_b32 v250, v250, 7, v251
	v_bfe_u32 v253, v157, 6, 2
	v_lshl_or_b32 v185, v253, 12, v250
	v_cmp_eq_u32_e64 s[4:5], 0, v0
	v_lshl_add_u32 v187, v184, 4, s9
	v_lshrrev_b32_e32 v1, 1, v13
	v_mul_lo_u32 v0, v15, s8
	s_mov_b32 s9, 0xb000
	v_mad_u64_u32 v[0:1], s[10:11], v1, s9, v[0:1]
	v_or_b32_e32 v0, v0, v14
	s_mov_b64 s[26:27], 0xb0080
	v_add_lshl_u32 v0, v0, v16, 1
	v_mov_b32_e32 v1, v155
	v_lshrrev_b32_e32 v250, 3, v157
	v_and_b32_e32 v251, 6, v250
	v_and_b32_e32 v252, 7, v157
	v_xor_b32_e32 v251, v251, v252
	v_lshlrev_b32_e32 v251, 4, v251
	v_mul_u32_u24_e32 v250, 0x1600, v250
	v_add_u32_e32 v0, v250, v251
	v_add_u32_e32 v0, 0x58000, v0
	v_lshl_add_u64 v[164:165], v[0:1], 0, s[26:27]
	v_lshrrev_b32_e32 v1, 1, v9
	v_mul_lo_u32 v0, v10, s8
	v_mad_u64_u32 v[0:1], s[8:9], v1, s9, v[0:1]
	v_or_b32_e32 v0, v0, v11
	s_waitcnt vmcnt(6)
	v_lshlrev_b32_e32 v2, 4, v157
	v_add_lshl_u32 v0, v0, v12, 1
	v_mov_b32_e32 v1, v155
	s_movk_i32 s6, 0x100
	v_lshrrev_b32_e32 v250, 3, v157
	v_and_b32_e32 v251, 6, v250
	v_and_b32_e32 v252, 7, v157
	v_xor_b32_e32 v251, v251, v252
	v_lshlrev_b32_e32 v251, 4, v251
	v_mul_u32_u24_e32 v250, 0x1600, v250
	v_add_u32_e32 v0, v250, v251
	v_lshl_add_u64 v[166:167], v[0:1], 0, s[26:27]
	s_add_i32 s68, 0, 0x10000
	s_add_i32 s69, 0, 0x14000
	v_add_u32_e32 v0, 0, v2
	v_cmp_gt_u32_e64 s[6:7], s6, v157
	s_ashr_i32 s65, s42, 31
	s_mov_b32 s66, s42
	s_ashr_i32 s67, s2, 31
	v_mov_b64_e32 v[168:169], 0x200
	v_mov_b64_e32 v[170:171], 0x1ff
	v_add_u32_e32 v188, s68, v185
	v_add_u32_e32 v189, s69, v185
	v_add_u32_e32 v190, 0, v4
	v_and_b32_e32 v250, 15, v157
	v_bfe_u32 v251, v157, 4, 2
	v_and_b32_e32 v252, 2, v250
	v_xor_b32_e32 v251, v251, v252
	v_and_b32_e32 v252, 4, v250
	v_lshlrev_b32_e32 v252, 4, v252
	v_lshl_or_b32 v251, v251, 4, v252
	v_lshl_or_b32 v250, v250, 7, v251
	v_lshrrev_b32_e32 v253, 8, v157
	v_lshl_or_b32 v190, v253, 13, v250
	s_mov_b64 s[26:27], 0x40000
	s_mov_b64 s[28:29], 0x48000
	s_mov_b64 s[30:31], 0x50000
	s_mov_b64 s[44:45], 0x58000
	v_add_u32_e32 v191, 0x20000, v0
	s_barrier
	s_branch .LBB0_1170

.LBB0_1180:
	s_add_u32 s72, s50, 0x100
	s_addc_u32 s73, s51, 0
	s_mov_b32 s74, -2
	s_waitcnt lgkmcnt(0)
	s_cmp_eq_u32 s63, 1
	s_cbranch_scc1 .Lfa_11
	ds_read_b128 v[128:131], v188
	v_xor_b32_e32 v253, 64, v188
	ds_read_b128 v[132:135], v253
	ds_read_b128 v[136:139], v188 offset:2048
	ds_read_b128 v[140:143], v253 offset:2048
	ds_read_b128 v[144:147], v189
	v_xor_b32_e32 v253, 64, v189
	ds_read_b128 v[148:151], v253
	ds_read_b128 v[172:175], v189 offset:2048
	ds_read_b128 v[176:179], v253 offset:2048
	s_add_u32 s50, s48, 0x100
	s_addc_u32 s51, s49, 0
	s_cmp_eq_u32 s74, 40
	s_cselect_b32 s55, s11, s51
	s_cselect_b32 s54, s10, s50
	s_cselect_b32 s53, s47, s73
	s_cselect_b32 s52, s46, s72
	v_lshl_add_u64 v[220:221], s[48:49], 0, v[166:167]
	s_add_i32 m0, s59, 0xc000
	ds_read_b128 v[180:183], v190
	v_xor_b32_e32 v253, 64, v190
	ds_read_b128 v[192:195], v253
	ds_read_b128 v[196:199], v190 offset:2048
	ds_read_b128 v[200:203], v253 offset:2048
	ds_read_b128 v[204:207], v190 offset:4096
	ds_read_b128 v[208:211], v253 offset:4096
	ds_read_b128 v[212:215], v190 offset:6144
	ds_read_b128 v[216:219], v253 offset:6144
	global_load_lds_dwordx4 v[220:221], off
	v_lshl_add_u64 v[220:221], s[48:49], 0, v[164:165]
	s_add_i32 m0, s59, 0xe000
	s_nop 0
	global_load_lds_dwordx4 v[220:221], off
	s_waitcnt vmcnt(24)
	s_waitcnt lgkmcnt(0)
	s_barrier
	s_setprio 1
	s_waitcnt lgkmcnt(0)
	v_mfma_f32_16x16x32_bf16 v[124:127], v[128:131], v[180:183], 0
	v_mfma_f32_16x16x32_bf16 v[120:123], v[136:139], v[180:183], 0
	v_mfma_f32_16x16x32_bf16 v[108:111], v[128:131], v[196:199], 0
	v_mfma_f32_16x16x32_bf16 v[104:107], v[136:139], v[196:199], 0
	v_mfma_f32_16x16x32_bf16 v[92:95], v[128:131], v[204:207], 0
	v_mfma_f32_16x16x32_bf16 v[88:91], v[136:139], v[204:207], 0
	v_mfma_f32_16x16x32_bf16 v[76:79], v[128:131], v[212:215], 0
	v_mfma_f32_16x16x32_bf16 v[72:75], v[136:139], v[212:215], 0
	v_mfma_f32_16x16x32_bf16 v[124:127], v[132:135], v[192:195], v[124:127]
	v_mfma_f32_16x16x32_bf16 v[120:123], v[140:143], v[192:195], v[120:123]
	v_mfma_f32_16x16x32_bf16 v[108:111], v[132:135], v[200:203], v[108:111]
	v_mfma_f32_16x16x32_bf16 v[104:107], v[140:143], v[200:203], v[104:107]
	v_mfma_f32_16x16x32_bf16 v[92:95], v[132:135], v[208:211], v[92:95]
	v_mfma_f32_16x16x32_bf16 v[88:91], v[140:143], v[208:211], v[88:91]
	v_mfma_f32_16x16x32_bf16 v[76:79], v[132:135], v[216:219], v[76:79]
	v_mfma_f32_16x16x32_bf16 v[72:75], v[140:143], v[216:219], v[72:75]
	s_setprio 0
	s_setprio 1
	v_mfma_f32_16x16x32_bf16 v[116:119], v[144:147], v[180:183], 0
	v_mfma_f32_16x16x32_bf16 v[112:115], v[172:175], v[180:183], 0
	v_mfma_f32_16x16x32_bf16 v[100:103], v[144:147], v[196:199], 0
	v_mfma_f32_16x16x32_bf16 v[96:99], v[172:175], v[196:199], 0
	v_mfma_f32_16x16x32_bf16 v[84:87], v[144:147], v[204:207], 0
	v_mfma_f32_16x16x32_bf16 v[80:83], v[172:175], v[204:207], 0
	v_mfma_f32_16x16x32_bf16 v[68:71], v[144:147], v[212:215], 0
	v_mfma_f32_16x16x32_bf16 v[64:67], v[172:175], v[212:215], 0
	v_mfma_f32_16x16x32_bf16 v[116:119], v[148:151], v[192:195], v[116:119]
	v_mfma_f32_16x16x32_bf16 v[112:115], v[176:179], v[192:195], v[112:115]
	v_mfma_f32_16x16x32_bf16 v[100:103], v[148:151], v[200:203], v[100:103]
	v_mfma_f32_16x16x32_bf16 v[96:99], v[176:179], v[200:203], v[96:99]
	v_mfma_f32_16x16x32_bf16 v[84:87], v[148:151], v[208:211], v[84:87]
	v_mfma_f32_16x16x32_bf16 v[80:83], v[176:179], v[208:211], v[80:83]
	v_mfma_f32_16x16x32_bf16 v[68:71], v[148:151], v[216:219], v[68:71]
	v_mfma_f32_16x16x32_bf16 v[64:67], v[176:179], v[216:219], v[64:67]
	s_setprio 0
	s_barrier
	s_add_i32 s48, s68, s58
	v_lshl_add_u64 v[220:221], s[52:53], 0, v[154:155]
	s_mov_b32 m0, s48
	ds_read_b128 v[180:183], v190 offset:16384
	v_xor_b32_e32 v253, 64, v190
	ds_read_b128 v[192:195], v253 offset:16384
	ds_read_b128 v[196:199], v190 offset:18432
	ds_read_b128 v[200:203], v253 offset:18432
	ds_read_b128 v[204:207], v190 offset:20480
	ds_read_b128 v[208:211], v253 offset:20480
	ds_read_b128 v[212:215], v190 offset:22528
	ds_read_b128 v[216:219], v253 offset:22528
	global_load_lds_dwordx4 v[220:221], off
	s_add_i32 m0, s48, 0x2000
	s_add_u32 s48, s52, 0xb0000
	v_lshl_add_u64 v[222:223], s[52:53], 0, v[162:163]
	s_addc_u32 s49, s53, 0
	s_add_i32 s75, s69, s58
	global_load_lds_dwordx4 v[222:223], off
	v_lshl_add_u64 v[224:225], s[48:49], 0, v[154:155]
	s_mov_b32 m0, s75
	v_lshl_add_u64 v[226:227], s[54:55], 0, v[160:161]
	global_load_lds_dwordx4 v[224:225], off
	v_lshl_add_u64 v[224:225], s[48:49], 0, v[162:163]
	s_add_i32 m0, s75, 0x2000
	s_nop 0
	global_load_lds_dwordx4 v[224:225], off
	v_lshl_add_u64 v[224:225], s[54:55], 0, v[152:153]
	s_mov_b32 m0, s59
	s_nop 0
	global_load_lds_dwordx4 v[224:225], off
	s_mov_b32 m0, s60
	s_nop 0
	global_load_lds_dwordx4 v[226:227], off
	s_waitcnt vmcnt(24)
	s_waitcnt lgkmcnt(0)
	s_barrier
	s_setprio 1
	s_waitcnt lgkmcnt(0)
	v_mfma_f32_16x16x32_bf16 v[60:63], v[128:131], v[180:183], 0
	v_mfma_f32_16x16x32_bf16 v[56:59], v[136:139], v[180:183], 0
	v_mfma_f32_16x16x32_bf16 v[44:47], v[128:131], v[196:199], 0
	v_mfma_f32_16x16x32_bf16 v[40:43], v[136:139], v[196:199], 0
	v_mfma_f32_16x16x32_bf16 v[28:31], v[128:131], v[204:207], 0
	v_mfma_f32_16x16x32_bf16 v[24:27], v[136:139], v[204:207], 0
	v_mfma_f32_16x16x32_bf16 v[12:15], v[128:131], v[212:215], 0
	v_mfma_f32_16x16x32_bf16 v[8:11], v[136:139], v[212:215], 0
	v_mfma_f32_16x16x32_bf16 v[60:63], v[132:135], v[192:195], v[60:63]
	v_mfma_f32_16x16x32_bf16 v[56:59], v[140:143], v[192:195], v[56:59]
	v_mfma_f32_16x16x32_bf16 v[44:47], v[132:135], v[200:203], v[44:47]
	v_mfma_f32_16x16x32_bf16 v[40:43], v[140:143], v[200:203], v[40:43]
	v_mfma_f32_16x16x32_bf16 v[28:31], v[132:135], v[208:211], v[28:31]
	v_mfma_f32_16x16x32_bf16 v[24:27], v[140:143], v[208:211], v[24:27]
	v_mfma_f32_16x16x32_bf16 v[12:15], v[132:135], v[216:219], v[12:15]
	v_mfma_f32_16x16x32_bf16 v[8:11], v[140:143], v[216:219], v[8:11]
	s_setprio 0
	s_setprio 1
	v_mfma_f32_16x16x32_bf16 v[52:55], v[144:147], v[180:183], 0
	v_mfma_f32_16x16x32_bf16 v[48:51], v[172:175], v[180:183], 0
	v_mfma_f32_16x16x32_bf16 v[36:39], v[144:147], v[196:199], 0
	v_mfma_f32_16x16x32_bf16 v[32:35], v[172:175], v[196:199], 0
	v_mfma_f32_16x16x32_bf16 v[20:23], v[144:147], v[204:207], 0
	v_mfma_f32_16x16x32_bf16 v[16:19], v[172:175], v[204:207], 0
	v_mfma_f32_16x16x32_bf16 v[4:7], v[144:147], v[212:215], 0
	v_mfma_f32_16x16x32_bf16 v[0:3], v[172:175], v[212:215], 0
	v_mfma_f32_16x16x32_bf16 v[52:55], v[148:151], v[192:195], v[52:55]
	v_mfma_f32_16x16x32_bf16 v[48:51], v[176:179], v[192:195], v[48:51]
	v_mfma_f32_16x16x32_bf16 v[36:39], v[148:151], v[200:203], v[36:39]
	v_mfma_f32_16x16x32_bf16 v[32:35], v[176:179], v[200:203], v[32:35]
	v_mfma_f32_16x16x32_bf16 v[20:23], v[148:151], v[208:211], v[20:23]
	v_mfma_f32_16x16x32_bf16 v[16:19], v[176:179], v[208:211], v[16:19]
	v_mfma_f32_16x16x32_bf16 v[4:7], v[148:151], v[216:219], v[4:7]
	v_mfma_f32_16x16x32_bf16 v[0:3], v[176:179], v[216:219], v[0:3]
	s_setprio 0
	s_barrier
	s_add_i32 s75, 0, 0x18000
	s_add_i32 s76, 0, 0x1c000
	v_add_u32_e32 v140, s75, v185
	v_add_u32_e32 v176, s76, v185
	ds_read_b128 v[128:131], v140
	v_xor_b32_e32 v253, 64, v140
	ds_read_b128 v[132:135], v253
	ds_read_b128 v[136:139], v140 offset:2048
	ds_read_b128 v[140:143], v253 offset:2048
	ds_read_b128 v[144:147], v176
	v_xor_b32_e32 v253, 64, v176
	ds_read_b128 v[148:151], v253
	ds_read_b128 v[172:175], v176 offset:2048
	ds_read_b128 v[176:179], v253 offset:2048
	s_add_u32 s48, s54, 0xb0000
	s_addc_u32 s49, s55, 0
	s_mov_b32 m0, s61
	v_lshl_add_u64 v[228:229], s[48:49], 0, v[152:153]
	ds_read_b128 v[180:183], v190 offset:32768
	v_xor_b32_e32 v253, 64, v190
	ds_read_b128 v[192:195], v253 offset:32768
	ds_read_b128 v[196:199], v190 offset:34816
	ds_read_b128 v[200:203], v253 offset:34816
	ds_read_b128 v[204:207], v190 offset:36864
	ds_read_b128 v[208:211], v253 offset:36864
	ds_read_b128 v[212:215], v190 offset:38912
	ds_read_b128 v[216:219], v253 offset:38912
	global_load_lds_dwordx4 v[228:229], off
	v_lshl_add_u64 v[228:229], s[48:49], 0, v[160:161]
	s_mov_b32 m0, s62
	s_nop 0
	global_load_lds_dwordx4 v[228:229], off
	s_waitcnt vmcnt(8)
	s_waitcnt lgkmcnt(0)
	s_barrier
	s_setprio 1
	s_waitcnt lgkmcnt(0)
	v_mfma_f32_16x16x32_bf16 v[124:127], v[128:131], v[180:183], v[124:127]
	v_mfma_f32_16x16x32_bf16 v[120:123], v[136:139], v[180:183], v[120:123]
	v_mfma_f32_16x16x32_bf16 v[108:111], v[128:131], v[196:199], v[108:111]
	v_mfma_f32_16x16x32_bf16 v[104:107], v[136:139], v[196:199], v[104:107]
	v_mfma_f32_16x16x32_bf16 v[92:95], v[128:131], v[204:207], v[92:95]
	v_mfma_f32_16x16x32_bf16 v[88:91], v[136:139], v[204:207], v[88:91]
	v_mfma_f32_16x16x32_bf16 v[76:79], v[128:131], v[212:215], v[76:79]
	v_mfma_f32_16x16x32_bf16 v[72:75], v[136:139], v[212:215], v[72:75]
	v_mfma_f32_16x16x32_bf16 v[124:127], v[132:135], v[192:195], v[124:127]
	v_mfma_f32_16x16x32_bf16 v[120:123], v[140:143], v[192:195], v[120:123]
	v_mfma_f32_16x16x32_bf16 v[108:111], v[132:135], v[200:203], v[108:111]
	v_mfma_f32_16x16x32_bf16 v[104:107], v[140:143], v[200:203], v[104:107]
	v_mfma_f32_16x16x32_bf16 v[92:95], v[132:135], v[208:211], v[92:95]
	v_mfma_f32_16x16x32_bf16 v[88:91], v[140:143], v[208:211], v[88:91]
	v_mfma_f32_16x16x32_bf16 v[76:79], v[132:135], v[216:219], v[76:79]
	v_mfma_f32_16x16x32_bf16 v[72:75], v[140:143], v[216:219], v[72:75]
	s_setprio 0
	s_setprio 1
	v_mfma_f32_16x16x32_bf16 v[116:119], v[144:147], v[180:183], v[116:119]
	v_mfma_f32_16x16x32_bf16 v[112:115], v[172:175], v[180:183], v[112:115]
	v_mfma_f32_16x16x32_bf16 v[100:103], v[144:147], v[196:199], v[100:103]
	v_mfma_f32_16x16x32_bf16 v[96:99], v[172:175], v[196:199], v[96:99]
	v_mfma_f32_16x16x32_bf16 v[84:87], v[144:147], v[204:207], v[84:87]
	v_mfma_f32_16x16x32_bf16 v[80:83], v[172:175], v[204:207], v[80:83]
	v_mfma_f32_16x16x32_bf16 v[68:71], v[144:147], v[212:215], v[68:71]
	v_mfma_f32_16x16x32_bf16 v[64:67], v[172:175], v[212:215], v[64:67]
	v_mfma_f32_16x16x32_bf16 v[116:119], v[148:151], v[192:195], v[116:119]
	v_mfma_f32_16x16x32_bf16 v[112:115], v[176:179], v[192:195], v[112:115]
	v_mfma_f32_16x16x32_bf16 v[100:103], v[148:151], v[200:203], v[100:103]
	v_mfma_f32_16x16x32_bf16 v[96:99], v[176:179], v[200:203], v[96:99]
	v_mfma_f32_16x16x32_bf16 v[84:87], v[148:151], v[208:211], v[84:87]
	v_mfma_f32_16x16x32_bf16 v[80:83], v[176:179], v[208:211], v[80:83]
	v_mfma_f32_16x16x32_bf16 v[68:71], v[148:151], v[216:219], v[68:71]
	v_mfma_f32_16x16x32_bf16 v[64:67], v[176:179], v[216:219], v[64:67]
	s_setprio 0
	s_barrier
	s_add_i32 s48, s75, s58
	v_lshl_add_u64 v[220:221], v[220:221], 0, s[22:23]
	s_mov_b32 m0, s48
	ds_read_b128 v[180:183], v190 offset:49152
	v_xor_b32_e32 v253, 64, v190
	ds_read_b128 v[192:195], v253 offset:49152
	ds_read_b128 v[196:199], v190 offset:51200
	ds_read_b128 v[200:203], v253 offset:51200
	ds_read_b128 v[204:207], v190 offset:53248
	ds_read_b128 v[208:211], v253 offset:53248
	ds_read_b128 v[212:215], v190 offset:55296
	ds_read_b128 v[216:219], v253 offset:55296
	global_load_lds_dwordx4 v[220:221], off
	s_add_i32 m0, s48, 0x2000
	s_add_u32 s48, s52, 0xb0080
	v_lshl_add_u64 v[220:221], v[222:223], 0, s[22:23]
	s_addc_u32 s49, s53, 0
	s_add_i32 s52, s76, s58
	global_load_lds_dwordx4 v[220:221], off
	v_lshl_add_u64 v[220:221], s[48:49], 0, v[154:155]
	s_mov_b32 m0, s52
	s_nop 0
	global_load_lds_dwordx4 v[220:221], off
	v_lshl_add_u64 v[220:221], s[48:49], 0, v[162:163]
	s_add_i32 m0, s52, 0x2000
	s_nop 0
	global_load_lds_dwordx4 v[220:221], off
	v_lshl_add_u64 v[220:221], v[224:225], 0, s[22:23]
	s_mov_b32 m0, s3
	s_nop 0
	global_load_lds_dwordx4 v[220:221], off
	v_lshl_add_u64 v[220:221], v[226:227], 0, s[22:23]
	s_mov_b32 m0, s64
	s_nop 0
	global_load_lds_dwordx4 v[220:221], off
	s_waitcnt vmcnt(8)
	s_waitcnt lgkmcnt(0)
	s_barrier
	s_setprio 1
	s_waitcnt lgkmcnt(0)
	v_mfma_f32_16x16x32_bf16 v[60:63], v[128:131], v[180:183], v[60:63]
	v_mfma_f32_16x16x32_bf16 v[56:59], v[136:139], v[180:183], v[56:59]
	v_mfma_f32_16x16x32_bf16 v[44:47], v[128:131], v[196:199], v[44:47]
	v_mfma_f32_16x16x32_bf16 v[40:43], v[136:139], v[196:199], v[40:43]
	v_mfma_f32_16x16x32_bf16 v[28:31], v[128:131], v[204:207], v[28:31]
	v_mfma_f32_16x16x32_bf16 v[24:27], v[136:139], v[204:207], v[24:27]
	v_mfma_f32_16x16x32_bf16 v[12:15], v[128:131], v[212:215], v[12:15]
	v_mfma_f32_16x16x32_bf16 v[8:11], v[136:139], v[212:215], v[8:11]
	v_mfma_f32_16x16x32_bf16 v[60:63], v[132:135], v[192:195], v[60:63]
	v_mfma_f32_16x16x32_bf16 v[56:59], v[140:143], v[192:195], v[56:59]
	v_mfma_f32_16x16x32_bf16 v[44:47], v[132:135], v[200:203], v[44:47]
	v_mfma_f32_16x16x32_bf16 v[40:43], v[140:143], v[200:203], v[40:43]
	v_mfma_f32_16x16x32_bf16 v[28:31], v[132:135], v[208:211], v[28:31]
	v_mfma_f32_16x16x32_bf16 v[24:27], v[140:143], v[208:211], v[24:27]
	v_mfma_f32_16x16x32_bf16 v[12:15], v[132:135], v[216:219], v[12:15]
	v_mfma_f32_16x16x32_bf16 v[8:11], v[140:143], v[216:219], v[8:11]
	s_setprio 0
	s_setprio 1
	v_mfma_f32_16x16x32_bf16 v[52:55], v[144:147], v[180:183], v[52:55]
	v_mfma_f32_16x16x32_bf16 v[48:51], v[172:175], v[180:183], v[48:51]
	v_mfma_f32_16x16x32_bf16 v[36:39], v[144:147], v[196:199], v[36:39]
	v_mfma_f32_16x16x32_bf16 v[32:35], v[172:175], v[196:199], v[32:35]
	v_mfma_f32_16x16x32_bf16 v[20:23], v[144:147], v[204:207], v[20:23]
	v_mfma_f32_16x16x32_bf16 v[16:19], v[172:175], v[204:207], v[16:19]
	v_mfma_f32_16x16x32_bf16 v[4:7], v[144:147], v[212:215], v[4:7]
	v_mfma_f32_16x16x32_bf16 v[0:3], v[172:175], v[212:215], v[0:3]
	v_mfma_f32_16x16x32_bf16 v[52:55], v[148:151], v[192:195], v[52:55]
	v_mfma_f32_16x16x32_bf16 v[48:51], v[176:179], v[192:195], v[48:51]
	v_mfma_f32_16x16x32_bf16 v[36:39], v[148:151], v[200:203], v[36:39]
	v_mfma_f32_16x16x32_bf16 v[32:35], v[176:179], v[200:203], v[32:35]
	v_mfma_f32_16x16x32_bf16 v[20:23], v[148:151], v[208:211], v[20:23]
	v_mfma_f32_16x16x32_bf16 v[16:19], v[176:179], v[208:211], v[16:19]
	v_mfma_f32_16x16x32_bf16 v[4:7], v[148:151], v[216:219], v[4:7]
	v_mfma_f32_16x16x32_bf16 v[0:3], v[176:179], v[216:219], v[0:3]
	s_setprio 0
	s_barrier
	s_add_i32 s74, s74, 2
	s_add_u32 s72, s72, 0x100
	s_addc_u32 s73, s73, 0
	s_cmp_gt_u32 s74, 41
	s_mov_b64 s[48:49], s[50:51]
	s_branch .LBB0_1181
.Lfa_11:
	ds_read_b128 v[128:131], v188
	v_xor_b32_e32 v253, 64, v188
	ds_read_b128 v[132:135], v253
	ds_read_b128 v[136:139], v188 offset:2048
	ds_read_b128 v[140:143], v253 offset:2048
	ds_read_b128 v[144:147], v189
	v_xor_b32_e32 v253, 64, v189
	ds_read_b128 v[148:151], v253
	ds_read_b128 v[172:175], v189 offset:2048
	ds_read_b128 v[176:179], v253 offset:2048
	s_add_u32 s50, s48, 0x100
	s_addc_u32 s51, s49, 0
	s_cmp_eq_u32 s74, 40
	s_cselect_b32 s55, s11, s51
	s_cselect_b32 s54, s10, s50
	s_cselect_b32 s53, s47, s73
	s_cselect_b32 s52, s46, s72
	v_lshl_add_u64 v[220:221], s[48:49], 0, v[166:167]
	s_add_i32 m0, s59, 0xc000
	ds_read_b128 v[180:183], v190
	v_xor_b32_e32 v253, 64, v190
	ds_read_b128 v[192:195], v253
	ds_read_b128 v[196:199], v190 offset:2048
	ds_read_b128 v[200:203], v253 offset:2048
	ds_read_b128 v[204:207], v190 offset:4096
	ds_read_b128 v[208:211], v253 offset:4096
	ds_read_b128 v[212:215], v190 offset:6144
	ds_read_b128 v[216:219], v253 offset:6144
	global_load_lds_dwordx4 v[220:221], off
	v_lshl_add_u64 v[220:221], s[48:49], 0, v[164:165]
	s_add_i32 m0, s59, 0xe000
	s_nop 0
	global_load_lds_dwordx4 v[220:221], off
	s_waitcnt vmcnt(8)
	s_waitcnt lgkmcnt(0)
	s_barrier
	s_setprio 1
	s_waitcnt lgkmcnt(0)
	v_mfma_f32_16x16x32_bf16 v[124:127], v[128:131], v[180:183], 0
	v_mfma_f32_16x16x32_bf16 v[120:123], v[136:139], v[180:183], 0
	v_mfma_f32_16x16x32_bf16 v[108:111], v[128:131], v[196:199], 0
	v_mfma_f32_16x16x32_bf16 v[104:107], v[136:139], v[196:199], 0
	v_mfma_f32_16x16x32_bf16 v[92:95], v[128:131], v[204:207], 0
	v_mfma_f32_16x16x32_bf16 v[88:91], v[136:139], v[204:207], 0
	v_mfma_f32_16x16x32_bf16 v[76:79], v[128:131], v[212:215], 0
	v_mfma_f32_16x16x32_bf16 v[72:75], v[136:139], v[212:215], 0
	v_mfma_f32_16x16x32_bf16 v[124:127], v[132:135], v[192:195], v[124:127]
	v_mfma_f32_16x16x32_bf16 v[120:123], v[140:143], v[192:195], v[120:123]
	v_mfma_f32_16x16x32_bf16 v[108:111], v[132:135], v[200:203], v[108:111]
	v_mfma_f32_16x16x32_bf16 v[104:107], v[140:143], v[200:203], v[104:107]
	v_mfma_f32_16x16x32_bf16 v[92:95], v[132:135], v[208:211], v[92:95]
	v_mfma_f32_16x16x32_bf16 v[88:91], v[140:143], v[208:211], v[88:91]
	v_mfma_f32_16x16x32_bf16 v[76:79], v[132:135], v[216:219], v[76:79]
	v_mfma_f32_16x16x32_bf16 v[72:75], v[140:143], v[216:219], v[72:75]
	s_setprio 0
	s_setprio 1
	v_mfma_f32_16x16x32_bf16 v[116:119], v[144:147], v[180:183], 0
	v_mfma_f32_16x16x32_bf16 v[112:115], v[172:175], v[180:183], 0
	v_mfma_f32_16x16x32_bf16 v[100:103], v[144:147], v[196:199], 0
	v_mfma_f32_16x16x32_bf16 v[96:99], v[172:175], v[196:199], 0
	v_mfma_f32_16x16x32_bf16 v[84:87], v[144:147], v[204:207], 0
	v_mfma_f32_16x16x32_bf16 v[80:83], v[172:175], v[204:207], 0
	v_mfma_f32_16x16x32_bf16 v[68:71], v[144:147], v[212:215], 0
	v_mfma_f32_16x16x32_bf16 v[64:67], v[172:175], v[212:215], 0
	v_mfma_f32_16x16x32_bf16 v[116:119], v[148:151], v[192:195], v[116:119]
	v_mfma_f32_16x16x32_bf16 v[112:115], v[176:179], v[192:195], v[112:115]
	v_mfma_f32_16x16x32_bf16 v[100:103], v[148:151], v[200:203], v[100:103]
	v_mfma_f32_16x16x32_bf16 v[96:99], v[176:179], v[200:203], v[96:99]
	v_mfma_f32_16x16x32_bf16 v[84:87], v[148:151], v[208:211], v[84:87]
	v_mfma_f32_16x16x32_bf16 v[80:83], v[176:179], v[208:211], v[80:83]
	v_mfma_f32_16x16x32_bf16 v[68:71], v[148:151], v[216:219], v[68:71]
	v_mfma_f32_16x16x32_bf16 v[64:67], v[176:179], v[216:219], v[64:67]
	s_setprio 0
	s_barrier
	s_add_i32 s48, s68, s58
	v_lshl_add_u64 v[220:221], s[52:53], 0, v[154:155]
	s_mov_b32 m0, s48
	ds_read_b128 v[180:183], v190 offset:16384
	v_xor_b32_e32 v253, 64, v190
	ds_read_b128 v[192:195], v253 offset:16384
	ds_read_b128 v[196:199], v190 offset:18432
	ds_read_b128 v[200:203], v253 offset:18432
	ds_read_b128 v[204:207], v190 offset:20480
	ds_read_b128 v[208:211], v253 offset:20480
	ds_read_b128 v[212:215], v190 offset:22528
	ds_read_b128 v[216:219], v253 offset:22528
	global_load_lds_dwordx4 v[220:221], off
	s_add_i32 m0, s48, 0x2000
	s_add_u32 s48, s52, 0xb0000
	v_lshl_add_u64 v[222:223], s[52:53], 0, v[162:163]
	s_addc_u32 s49, s53, 0
	s_add_i32 s75, s69, s58
	global_load_lds_dwordx4 v[222:223], off
	v_lshl_add_u64 v[224:225], s[48:49], 0, v[154:155]
	s_mov_b32 m0, s75
	v_lshl_add_u64 v[226:227], s[54:55], 0, v[160:161]
	global_load_lds_dwordx4 v[224:225], off
	v_lshl_add_u64 v[224:225], s[48:49], 0, v[162:163]
	s_add_i32 m0, s75, 0x2000
	s_nop 0
	global_load_lds_dwordx4 v[224:225], off
	v_lshl_add_u64 v[224:225], s[54:55], 0, v[152:153]
	s_mov_b32 m0, s59
	s_nop 0
	global_load_lds_dwordx4 v[224:225], off
	s_mov_b32 m0, s60
	s_nop 0
	global_load_lds_dwordx4 v[226:227], off
	s_waitcnt vmcnt(8)
	s_waitcnt lgkmcnt(0)
	s_barrier
	s_setprio 1
	s_waitcnt lgkmcnt(0)
	v_mfma_f32_16x16x32_bf16 v[60:63], v[128:131], v[180:183], 0
	v_mfma_f32_16x16x32_bf16 v[56:59], v[136:139], v[180:183], 0
	v_mfma_f32_16x16x32_bf16 v[44:47], v[128:131], v[196:199], 0
	v_mfma_f32_16x16x32_bf16 v[40:43], v[136:139], v[196:199], 0
	v_mfma_f32_16x16x32_bf16 v[28:31], v[128:131], v[204:207], 0
	v_mfma_f32_16x16x32_bf16 v[24:27], v[136:139], v[204:207], 0
	v_mfma_f32_16x16x32_bf16 v[12:15], v[128:131], v[212:215], 0
	v_mfma_f32_16x16x32_bf16 v[8:11], v[136:139], v[212:215], 0
	v_mfma_f32_16x16x32_bf16 v[60:63], v[132:135], v[192:195], v[60:63]
	v_mfma_f32_16x16x32_bf16 v[56:59], v[140:143], v[192:195], v[56:59]
	v_mfma_f32_16x16x32_bf16 v[44:47], v[132:135], v[200:203], v[44:47]
	v_mfma_f32_16x16x32_bf16 v[40:43], v[140:143], v[200:203], v[40:43]
	v_mfma_f32_16x16x32_bf16 v[28:31], v[132:135], v[208:211], v[28:31]
	v_mfma_f32_16x16x32_bf16 v[24:27], v[140:143], v[208:211], v[24:27]
	v_mfma_f32_16x16x32_bf16 v[12:15], v[132:135], v[216:219], v[12:15]
	v_mfma_f32_16x16x32_bf16 v[8:11], v[140:143], v[216:219], v[8:11]
	s_setprio 0
	s_setprio 1
	v_mfma_f32_16x16x32_bf16 v[52:55], v[144:147], v[180:183], 0
	v_mfma_f32_16x16x32_bf16 v[48:51], v[172:175], v[180:183], 0
	v_mfma_f32_16x16x32_bf16 v[36:39], v[144:147], v[196:199], 0
	v_mfma_f32_16x16x32_bf16 v[32:35], v[172:175], v[196:199], 0
	v_mfma_f32_16x16x32_bf16 v[20:23], v[144:147], v[204:207], 0
	v_mfma_f32_16x16x32_bf16 v[16:19], v[172:175], v[204:207], 0
	v_mfma_f32_16x16x32_bf16 v[4:7], v[144:147], v[212:215], 0
	v_mfma_f32_16x16x32_bf16 v[0:3], v[172:175], v[212:215], 0
	v_mfma_f32_16x16x32_bf16 v[52:55], v[148:151], v[192:195], v[52:55]
	v_mfma_f32_16x16x32_bf16 v[48:51], v[176:179], v[192:195], v[48:51]
	v_mfma_f32_16x16x32_bf16 v[36:39], v[148:151], v[200:203], v[36:39]
	v_mfma_f32_16x16x32_bf16 v[32:35], v[176:179], v[200:203], v[32:35]
	v_mfma_f32_16x16x32_bf16 v[20:23], v[148:151], v[208:211], v[20:23]
	v_mfma_f32_16x16x32_bf16 v[16:19], v[176:179], v[208:211], v[16:19]
	v_mfma_f32_16x16x32_bf16 v[4:7], v[148:151], v[216:219], v[4:7]
	v_mfma_f32_16x16x32_bf16 v[0:3], v[176:179], v[216:219], v[0:3]
	s_setprio 0
	s_barrier
	s_add_i32 s75, 0, 0x18000
	s_add_i32 s76, 0, 0x1c000
	v_add_u32_e32 v140, s75, v185
	v_add_u32_e32 v176, s76, v185
	ds_read_b128 v[128:131], v140
	v_xor_b32_e32 v253, 64, v140
	ds_read_b128 v[132:135], v253
	ds_read_b128 v[136:139], v140 offset:2048
	ds_read_b128 v[140:143], v253 offset:2048
	ds_read_b128 v[144:147], v176
	v_xor_b32_e32 v253, 64, v176
	ds_read_b128 v[148:151], v253
	ds_read_b128 v[172:175], v176 offset:2048
	ds_read_b128 v[176:179], v253 offset:2048
	s_add_u32 s48, s54, 0xb0000
	s_addc_u32 s49, s55, 0
	s_mov_b32 m0, s61
	v_lshl_add_u64 v[228:229], s[48:49], 0, v[152:153]
	ds_read_b128 v[180:183], v190 offset:32768
	v_xor_b32_e32 v253, 64, v190
	ds_read_b128 v[192:195], v253 offset:32768
	ds_read_b128 v[196:199], v190 offset:34816
	ds_read_b128 v[200:203], v253 offset:34816
	ds_read_b128 v[204:207], v190 offset:36864
	ds_read_b128 v[208:211], v253 offset:36864
	ds_read_b128 v[212:215], v190 offset:38912
	ds_read_b128 v[216:219], v253 offset:38912
	global_load_lds_dwordx4 v[228:229], off
	v_lshl_add_u64 v[228:229], s[48:49], 0, v[160:161]
	s_mov_b32 m0, s62
	s_nop 0
	global_load_lds_dwordx4 v[228:229], off
	s_waitcnt vmcnt(8)
	s_waitcnt lgkmcnt(0)
	s_barrier
	s_setprio 1
	s_waitcnt lgkmcnt(0)
	v_mfma_f32_16x16x32_bf16 v[124:127], v[128:131], v[180:183], v[124:127]
	v_mfma_f32_16x16x32_bf16 v[120:123], v[136:139], v[180:183], v[120:123]
	v_mfma_f32_16x16x32_bf16 v[108:111], v[128:131], v[196:199], v[108:111]
	v_mfma_f32_16x16x32_bf16 v[104:107], v[136:139], v[196:199], v[104:107]
	v_mfma_f32_16x16x32_bf16 v[92:95], v[128:131], v[204:207], v[92:95]
	v_mfma_f32_16x16x32_bf16 v[88:91], v[136:139], v[204:207], v[88:91]
	v_mfma_f32_16x16x32_bf16 v[76:79], v[128:131], v[212:215], v[76:79]
	v_mfma_f32_16x16x32_bf16 v[72:75], v[136:139], v[212:215], v[72:75]
	v_mfma_f32_16x16x32_bf16 v[124:127], v[132:135], v[192:195], v[124:127]
	v_mfma_f32_16x16x32_bf16 v[120:123], v[140:143], v[192:195], v[120:123]
	v_mfma_f32_16x16x32_bf16 v[108:111], v[132:135], v[200:203], v[108:111]
	v_mfma_f32_16x16x32_bf16 v[104:107], v[140:143], v[200:203], v[104:107]
	v_mfma_f32_16x16x32_bf16 v[92:95], v[132:135], v[208:211], v[92:95]
	v_mfma_f32_16x16x32_bf16 v[88:91], v[140:143], v[208:211], v[88:91]
	v_mfma_f32_16x16x32_bf16 v[76:79], v[132:135], v[216:219], v[76:79]
	v_mfma_f32_16x16x32_bf16 v[72:75], v[140:143], v[216:219], v[72:75]
	s_setprio 0
	s_setprio 1
	v_mfma_f32_16x16x32_bf16 v[116:119], v[144:147], v[180:183], v[116:119]
	v_mfma_f32_16x16x32_bf16 v[112:115], v[172:175], v[180:183], v[112:115]
	v_mfma_f32_16x16x32_bf16 v[100:103], v[144:147], v[196:199], v[100:103]
	v_mfma_f32_16x16x32_bf16 v[96:99], v[172:175], v[196:199], v[96:99]
	v_mfma_f32_16x16x32_bf16 v[84:87], v[144:147], v[204:207], v[84:87]
	v_mfma_f32_16x16x32_bf16 v[80:83], v[172:175], v[204:207], v[80:83]
	v_mfma_f32_16x16x32_bf16 v[68:71], v[144:147], v[212:215], v[68:71]
	v_mfma_f32_16x16x32_bf16 v[64:67], v[172:175], v[212:215], v[64:67]
	v_mfma_f32_16x16x32_bf16 v[116:119], v[148:151], v[192:195], v[116:119]
	v_mfma_f32_16x16x32_bf16 v[112:115], v[176:179], v[192:195], v[112:115]
	v_mfma_f32_16x16x32_bf16 v[100:103], v[148:151], v[200:203], v[100:103]
	v_mfma_f32_16x16x32_bf16 v[96:99], v[176:179], v[200:203], v[96:99]
	v_mfma_f32_16x16x32_bf16 v[84:87], v[148:151], v[208:211], v[84:87]
	v_mfma_f32_16x16x32_bf16 v[80:83], v[176:179], v[208:211], v[80:83]
	v_mfma_f32_16x16x32_bf16 v[68:71], v[148:151], v[216:219], v[68:71]
	v_mfma_f32_16x16x32_bf16 v[64:67], v[176:179], v[216:219], v[64:67]
	s_setprio 0
	s_barrier
	s_add_i32 s48, s75, s58
	v_lshl_add_u64 v[220:221], v[220:221], 0, s[22:23]
	s_mov_b32 m0, s48
	ds_read_b128 v[180:183], v190 offset:49152
	v_xor_b32_e32 v253, 64, v190
	ds_read_b128 v[192:195], v253 offset:49152
	ds_read_b128 v[196:199], v190 offset:51200
	ds_read_b128 v[200:203], v253 offset:51200
	ds_read_b128 v[204:207], v190 offset:53248
	ds_read_b128 v[208:211], v253 offset:53248
	ds_read_b128 v[212:215], v190 offset:55296
	ds_read_b128 v[216:219], v253 offset:55296
	global_load_lds_dwordx4 v[220:221], off
	s_add_i32 m0, s48, 0x2000
	s_add_u32 s48, s52, 0xb0080
	v_lshl_add_u64 v[220:221], v[222:223], 0, s[22:23]
	s_addc_u32 s49, s53, 0
	s_add_i32 s52, s76, s58
	global_load_lds_dwordx4 v[220:221], off
	v_lshl_add_u64 v[220:221], s[48:49], 0, v[154:155]
	s_mov_b32 m0, s52
	s_nop 0
	global_load_lds_dwordx4 v[220:221], off
	v_lshl_add_u64 v[220:221], s[48:49], 0, v[162:163]
	s_add_i32 m0, s52, 0x2000
	s_nop 0
	global_load_lds_dwordx4 v[220:221], off
	v_lshl_add_u64 v[220:221], v[224:225], 0, s[22:23]
	s_mov_b32 m0, s3
	s_nop 0
	global_load_lds_dwordx4 v[220:221], off
	v_lshl_add_u64 v[220:221], v[226:227], 0, s[22:23]
	s_mov_b32 m0, s64
	s_nop 0
	global_load_lds_dwordx4 v[220:221], off
	s_waitcnt vmcnt(8)
	s_waitcnt lgkmcnt(0)
	s_barrier
	s_setprio 1
	s_waitcnt lgkmcnt(0)
	v_mfma_f32_16x16x32_bf16 v[60:63], v[128:131], v[180:183], v[60:63]
	v_mfma_f32_16x16x32_bf16 v[56:59], v[136:139], v[180:183], v[56:59]
	v_mfma_f32_16x16x32_bf16 v[44:47], v[128:131], v[196:199], v[44:47]
	v_mfma_f32_16x16x32_bf16 v[40:43], v[136:139], v[196:199], v[40:43]
	v_mfma_f32_16x16x32_bf16 v[28:31], v[128:131], v[204:207], v[28:31]
	v_mfma_f32_16x16x32_bf16 v[24:27], v[136:139], v[204:207], v[24:27]
	v_mfma_f32_16x16x32_bf16 v[12:15], v[128:131], v[212:215], v[12:15]
	v_mfma_f32_16x16x32_bf16 v[8:11], v[136:139], v[212:215], v[8:11]
	v_mfma_f32_16x16x32_bf16 v[60:63], v[132:135], v[192:195], v[60:63]
	v_mfma_f32_16x16x32_bf16 v[56:59], v[140:143], v[192:195], v[56:59]
	v_mfma_f32_16x16x32_bf16 v[44:47], v[132:135], v[200:203], v[44:47]
	v_mfma_f32_16x16x32_bf16 v[40:43], v[140:143], v[200:203], v[40:43]
	v_mfma_f32_16x16x32_bf16 v[28:31], v[132:135], v[208:211], v[28:31]
	v_mfma_f32_16x16x32_bf16 v[24:27], v[140:143], v[208:211], v[24:27]
	v_mfma_f32_16x16x32_bf16 v[12:15], v[132:135], v[216:219], v[12:15]
	v_mfma_f32_16x16x32_bf16 v[8:11], v[140:143], v[216:219], v[8:11]
	s_setprio 0
	s_setprio 1
	v_mfma_f32_16x16x32_bf16 v[52:55], v[144:147], v[180:183], v[52:55]
	v_mfma_f32_16x16x32_bf16 v[48:51], v[172:175], v[180:183], v[48:51]
	v_mfma_f32_16x16x32_bf16 v[36:39], v[144:147], v[196:199], v[36:39]
	v_mfma_f32_16x16x32_bf16 v[32:35], v[172:175], v[196:199], v[32:35]
	v_mfma_f32_16x16x32_bf16 v[20:23], v[144:147], v[204:207], v[20:23]
	v_mfma_f32_16x16x32_bf16 v[16:19], v[172:175], v[204:207], v[16:19]
	v_mfma_f32_16x16x32_bf16 v[4:7], v[144:147], v[212:215], v[4:7]
	v_mfma_f32_16x16x32_bf16 v[0:3], v[172:175], v[212:215], v[0:3]
	v_mfma_f32_16x16x32_bf16 v[52:55], v[148:151], v[192:195], v[52:55]
	v_mfma_f32_16x16x32_bf16 v[48:51], v[176:179], v[192:195], v[48:51]
	v_mfma_f32_16x16x32_bf16 v[36:39], v[148:151], v[200:203], v[36:39]
	v_mfma_f32_16x16x32_bf16 v[32:35], v[176:179], v[200:203], v[32:35]
	v_mfma_f32_16x16x32_bf16 v[20:23], v[148:151], v[208:211], v[20:23]
	v_mfma_f32_16x16x32_bf16 v[16:19], v[176:179], v[208:211], v[16:19]
	v_mfma_f32_16x16x32_bf16 v[4:7], v[148:151], v[216:219], v[4:7]
	v_mfma_f32_16x16x32_bf16 v[0:3], v[176:179], v[216:219], v[0:3]
	s_setprio 0
	s_barrier
	s_add_i32 s74, s74, 2
	s_add_u32 s72, s72, 0x100
	s_addc_u32 s73, s73, 0
	s_cmp_gt_u32 s74, 41
	s_mov_b64 s[48:49], s[50:51]
.LBB0_1181:
	ds_read_b128 v[128:131], v188
	v_xor_b32_e32 v253, 64, v188
	ds_read_b128 v[132:135], v253
	ds_read_b128 v[136:139], v188 offset:2048
	ds_read_b128 v[140:143], v253 offset:2048
	ds_read_b128 v[144:147], v189
	v_xor_b32_e32 v253, 64, v189
	ds_read_b128 v[148:151], v253
	ds_read_b128 v[172:175], v189 offset:2048
	ds_read_b128 v[176:179], v253 offset:2048
	s_add_u32 s50, s48, 0x100
	s_addc_u32 s51, s49, 0
	s_cmp_eq_u32 s74, 40
	s_cselect_b32 s55, s11, s51
	s_cselect_b32 s54, s10, s50
	s_cselect_b32 s53, s47, s73
	s_cselect_b32 s52, s46, s72
	v_lshl_add_u64 v[220:221], s[48:49], 0, v[166:167]
	s_add_i32 m0, s59, 0xc000
	ds_read_b128 v[180:183], v190
	v_xor_b32_e32 v253, 64, v190
	ds_read_b128 v[192:195], v253
	ds_read_b128 v[196:199], v190 offset:2048
	ds_read_b128 v[200:203], v253 offset:2048
	ds_read_b128 v[204:207], v190 offset:4096
	ds_read_b128 v[208:211], v253 offset:4096
	ds_read_b128 v[212:215], v190 offset:6144
	ds_read_b128 v[216:219], v253 offset:6144
	global_load_lds_dwordx4 v[220:221], off
	v_lshl_add_u64 v[220:221], s[48:49], 0, v[164:165]
	s_add_i32 m0, s59, 0xe000
	s_nop 0
	global_load_lds_dwordx4 v[220:221], off
	s_waitcnt vmcnt(8)
	s_waitcnt lgkmcnt(0)
	s_barrier
	s_setprio 1
	s_waitcnt lgkmcnt(0)
	v_mfma_f32_16x16x32_bf16 v[124:127], v[128:131], v[180:183], v[124:127]
	v_mfma_f32_16x16x32_bf16 v[120:123], v[136:139], v[180:183], v[120:123]
	v_mfma_f32_16x16x32_bf16 v[108:111], v[128:131], v[196:199], v[108:111]
	v_mfma_f32_16x16x32_bf16 v[104:107], v[136:139], v[196:199], v[104:107]
	v_mfma_f32_16x16x32_bf16 v[92:95], v[128:131], v[204:207], v[92:95]
	v_mfma_f32_16x16x32_bf16 v[88:91], v[136:139], v[204:207], v[88:91]
	v_mfma_f32_16x16x32_bf16 v[76:79], v[128:131], v[212:215], v[76:79]
	v_mfma_f32_16x16x32_bf16 v[72:75], v[136:139], v[212:215], v[72:75]
	v_mfma_f32_16x16x32_bf16 v[124:127], v[132:135], v[192:195], v[124:127]
	v_mfma_f32_16x16x32_bf16 v[120:123], v[140:143], v[192:195], v[120:123]
	v_mfma_f32_16x16x32_bf16 v[108:111], v[132:135], v[200:203], v[108:111]
	v_mfma_f32_16x16x32_bf16 v[104:107], v[140:143], v[200:203], v[104:107]
	v_mfma_f32_16x16x32_bf16 v[92:95], v[132:135], v[208:211], v[92:95]
	v_mfma_f32_16x16x32_bf16 v[88:91], v[140:143], v[208:211], v[88:91]
	v_mfma_f32_16x16x32_bf16 v[76:79], v[132:135], v[216:219], v[76:79]
	v_mfma_f32_16x16x32_bf16 v[72:75], v[140:143], v[216:219], v[72:75]
	s_setprio 0
	s_setprio 1
	v_mfma_f32_16x16x32_bf16 v[116:119], v[144:147], v[180:183], v[116:119]
	v_mfma_f32_16x16x32_bf16 v[112:115], v[172:175], v[180:183], v[112:115]
	v_mfma_f32_16x16x32_bf16 v[100:103], v[144:147], v[196:199], v[100:103]
	v_mfma_f32_16x16x32_bf16 v[96:99], v[172:175], v[196:199], v[96:99]
	v_mfma_f32_16x16x32_bf16 v[84:87], v[144:147], v[204:207], v[84:87]
	v_mfma_f32_16x16x32_bf16 v[80:83], v[172:175], v[204:207], v[80:83]
	v_mfma_f32_16x16x32_bf16 v[68:71], v[144:147], v[212:215], v[68:71]
	v_mfma_f32_16x16x32_bf16 v[64:67], v[172:175], v[212:215], v[64:67]
	v_mfma_f32_16x16x32_bf16 v[116:119], v[148:151], v[192:195], v[116:119]
	v_mfma_f32_16x16x32_bf16 v[112:115], v[176:179], v[192:195], v[112:115]
	v_mfma_f32_16x16x32_bf16 v[100:103], v[148:151], v[200:203], v[100:103]
	v_mfma_f32_16x16x32_bf16 v[96:99], v[176:179], v[200:203], v[96:99]
	v_mfma_f32_16x16x32_bf16 v[84:87], v[148:151], v[208:211], v[84:87]
	v_mfma_f32_16x16x32_bf16 v[80:83], v[176:179], v[208:211], v[80:83]
	v_mfma_f32_16x16x32_bf16 v[68:71], v[148:151], v[216:219], v[68:71]
	v_mfma_f32_16x16x32_bf16 v[64:67], v[176:179], v[216:219], v[64:67]
	s_setprio 0
	s_barrier
	s_add_i32 s48, s68, s58
	v_lshl_add_u64 v[220:221], s[52:53], 0, v[154:155]
	s_mov_b32 m0, s48
	ds_read_b128 v[180:183], v190 offset:16384
	v_xor_b32_e32 v253, 64, v190
	ds_read_b128 v[192:195], v253 offset:16384
	ds_read_b128 v[196:199], v190 offset:18432
	ds_read_b128 v[200:203], v253 offset:18432
	ds_read_b128 v[204:207], v190 offset:20480
	ds_read_b128 v[208:211], v253 offset:20480
	ds_read_b128 v[212:215], v190 offset:22528
	ds_read_b128 v[216:219], v253 offset:22528
	global_load_lds_dwordx4 v[220:221], off
	s_add_i32 m0, s48, 0x2000
	s_add_u32 s48, s52, 0xb0000
	v_lshl_add_u64 v[222:223], s[52:53], 0, v[162:163]
	s_addc_u32 s49, s53, 0
	s_add_i32 s75, s69, s58
	global_load_lds_dwordx4 v[222:223], off
	v_lshl_add_u64 v[224:225], s[48:49], 0, v[154:155]
	s_mov_b32 m0, s75
	v_lshl_add_u64 v[226:227], s[54:55], 0, v[160:161]
	global_load_lds_dwordx4 v[224:225], off
	v_lshl_add_u64 v[224:225], s[48:49], 0, v[162:163]
	s_add_i32 m0, s75, 0x2000
	s_nop 0
	global_load_lds_dwordx4 v[224:225], off
	v_lshl_add_u64 v[224:225], s[54:55], 0, v[152:153]
	s_mov_b32 m0, s59
	s_nop 0
	global_load_lds_dwordx4 v[224:225], off
	s_mov_b32 m0, s60
	s_nop 0
	global_load_lds_dwordx4 v[226:227], off
	s_waitcnt vmcnt(8)
	s_waitcnt lgkmcnt(0)
	s_barrier
	s_setprio 1
	s_waitcnt lgkmcnt(0)
	v_mfma_f32_16x16x32_bf16 v[60:63], v[128:131], v[180:183], v[60:63]
	v_mfma_f32_16x16x32_bf16 v[56:59], v[136:139], v[180:183], v[56:59]
	v_mfma_f32_16x16x32_bf16 v[44:47], v[128:131], v[196:199], v[44:47]
	v_mfma_f32_16x16x32_bf16 v[40:43], v[136:139], v[196:199], v[40:43]
	v_mfma_f32_16x16x32_bf16 v[28:31], v[128:131], v[204:207], v[28:31]
	v_mfma_f32_16x16x32_bf16 v[24:27], v[136:139], v[204:207], v[24:27]
	v_mfma_f32_16x16x32_bf16 v[12:15], v[128:131], v[212:215], v[12:15]
	v_mfma_f32_16x16x32_bf16 v[8:11], v[136:139], v[212:215], v[8:11]
	v_mfma_f32_16x16x32_bf16 v[60:63], v[132:135], v[192:195], v[60:63]
	v_mfma_f32_16x16x32_bf16 v[56:59], v[140:143], v[192:195], v[56:59]
	v_mfma_f32_16x16x32_bf16 v[44:47], v[132:135], v[200:203], v[44:47]
	v_mfma_f32_16x16x32_bf16 v[40:43], v[140:143], v[200:203], v[40:43]
	v_mfma_f32_16x16x32_bf16 v[28:31], v[132:135], v[208:211], v[28:31]
	v_mfma_f32_16x16x32_bf16 v[24:27], v[140:143], v[208:211], v[24:27]
	v_mfma_f32_16x16x32_bf16 v[12:15], v[132:135], v[216:219], v[12:15]
	v_mfma_f32_16x16x32_bf16 v[8:11], v[140:143], v[216:219], v[8:11]
	s_setprio 0
	s_setprio 1
	v_mfma_f32_16x16x32_bf16 v[52:55], v[144:147], v[180:183], v[52:55]
	v_mfma_f32_16x16x32_bf16 v[48:51], v[172:175], v[180:183], v[48:51]
	v_mfma_f32_16x16x32_bf16 v[36:39], v[144:147], v[196:199], v[36:39]
	v_mfma_f32_16x16x32_bf16 v[32:35], v[172:175], v[196:199], v[32:35]
	v_mfma_f32_16x16x32_bf16 v[20:23], v[144:147], v[204:207], v[20:23]
	v_mfma_f32_16x16x32_bf16 v[16:19], v[172:175], v[204:207], v[16:19]
	v_mfma_f32_16x16x32_bf16 v[4:7], v[144:147], v[212:215], v[4:7]
	v_mfma_f32_16x16x32_bf16 v[0:3], v[172:175], v[212:215], v[0:3]
	v_mfma_f32_16x16x32_bf16 v[52:55], v[148:151], v[192:195], v[52:55]
	v_mfma_f32_16x16x32_bf16 v[48:51], v[176:179], v[192:195], v[48:51]
	v_mfma_f32_16x16x32_bf16 v[36:39], v[148:151], v[200:203], v[36:39]
	v_mfma_f32_16x16x32_bf16 v[32:35], v[176:179], v[200:203], v[32:35]
	v_mfma_f32_16x16x32_bf16 v[20:23], v[148:151], v[208:211], v[20:23]
	v_mfma_f32_16x16x32_bf16 v[16:19], v[176:179], v[208:211], v[16:19]
	v_mfma_f32_16x16x32_bf16 v[4:7], v[148:151], v[216:219], v[4:7]
	v_mfma_f32_16x16x32_bf16 v[0:3], v[176:179], v[216:219], v[0:3]
	s_setprio 0
	s_barrier
	s_add_i32 s75, 0, 0x18000
	s_add_i32 s76, 0, 0x1c000
	v_add_u32_e32 v140, s75, v185
	v_add_u32_e32 v176, s76, v185
	ds_read_b128 v[128:131], v140
	v_xor_b32_e32 v253, 64, v140
	ds_read_b128 v[132:135], v253
	ds_read_b128 v[136:139], v140 offset:2048
	ds_read_b128 v[140:143], v253 offset:2048
	ds_read_b128 v[144:147], v176
	v_xor_b32_e32 v253, 64, v176
	ds_read_b128 v[148:151], v253
	ds_read_b128 v[172:175], v176 offset:2048
	ds_read_b128 v[176:179], v253 offset:2048
	s_add_u32 s48, s54, 0xb0000
	s_addc_u32 s49, s55, 0
	s_mov_b32 m0, s61
	v_lshl_add_u64 v[228:229], s[48:49], 0, v[152:153]
	ds_read_b128 v[180:183], v190 offset:32768
	v_xor_b32_e32 v253, 64, v190
	ds_read_b128 v[192:195], v253 offset:32768
	ds_read_b128 v[196:199], v190 offset:34816
	ds_read_b128 v[200:203], v253 offset:34816
	ds_read_b128 v[204:207], v190 offset:36864
	ds_read_b128 v[208:211], v253 offset:36864
	ds_read_b128 v[212:215], v190 offset:38912
	ds_read_b128 v[216:219], v253 offset:38912
	global_load_lds_dwordx4 v[228:229], off
	v_lshl_add_u64 v[228:229], s[48:49], 0, v[160:161]
	s_mov_b32 m0, s62
	s_nop 0
	global_load_lds_dwordx4 v[228:229], off
	s_waitcnt vmcnt(8)
	s_waitcnt lgkmcnt(0)
	s_barrier
	s_setprio 1
	s_waitcnt lgkmcnt(0)
	v_mfma_f32_16x16x32_bf16 v[124:127], v[128:131], v[180:183], v[124:127]
	v_mfma_f32_16x16x32_bf16 v[120:123], v[136:139], v[180:183], v[120:123]
	v_mfma_f32_16x16x32_bf16 v[108:111], v[128:131], v[196:199], v[108:111]
	v_mfma_f32_16x16x32_bf16 v[104:107], v[136:139], v[196:199], v[104:107]
	v_mfma_f32_16x16x32_bf16 v[92:95], v[128:131], v[204:207], v[92:95]
	v_mfma_f32_16x16x32_bf16 v[88:91], v[136:139], v[204:207], v[88:91]
	v_mfma_f32_16x16x32_bf16 v[76:79], v[128:131], v[212:215], v[76:79]
	v_mfma_f32_16x16x32_bf16 v[72:75], v[136:139], v[212:215], v[72:75]
	v_mfma_f32_16x16x32_bf16 v[124:127], v[132:135], v[192:195], v[124:127]
	v_mfma_f32_16x16x32_bf16 v[120:123], v[140:143], v[192:195], v[120:123]
	v_mfma_f32_16x16x32_bf16 v[108:111], v[132:135], v[200:203], v[108:111]
	v_mfma_f32_16x16x32_bf16 v[104:107], v[140:143], v[200:203], v[104:107]
	v_mfma_f32_16x16x32_bf16 v[92:95], v[132:135], v[208:211], v[92:95]
	v_mfma_f32_16x16x32_bf16 v[88:91], v[140:143], v[208:211], v[88:91]
	v_mfma_f32_16x16x32_bf16 v[76:79], v[132:135], v[216:219], v[76:79]
	v_mfma_f32_16x16x32_bf16 v[72:75], v[140:143], v[216:219], v[72:75]
	s_setprio 0
	s_setprio 1
	v_mfma_f32_16x16x32_bf16 v[116:119], v[144:147], v[180:183], v[116:119]
	v_mfma_f32_16x16x32_bf16 v[112:115], v[172:175], v[180:183], v[112:115]
	v_mfma_f32_16x16x32_bf16 v[100:103], v[144:147], v[196:199], v[100:103]
	v_mfma_f32_16x16x32_bf16 v[96:99], v[172:175], v[196:199], v[96:99]
	v_mfma_f32_16x16x32_bf16 v[84:87], v[144:147], v[204:207], v[84:87]
	v_mfma_f32_16x16x32_bf16 v[80:83], v[172:175], v[204:207], v[80:83]
	v_mfma_f32_16x16x32_bf16 v[68:71], v[144:147], v[212:215], v[68:71]
	v_mfma_f32_16x16x32_bf16 v[64:67], v[172:175], v[212:215], v[64:67]
	v_mfma_f32_16x16x32_bf16 v[116:119], v[148:151], v[192:195], v[116:119]
	v_mfma_f32_16x16x32_bf16 v[112:115], v[176:179], v[192:195], v[112:115]
	v_mfma_f32_16x16x32_bf16 v[100:103], v[148:151], v[200:203], v[100:103]
	v_mfma_f32_16x16x32_bf16 v[96:99], v[176:179], v[200:203], v[96:99]
	v_mfma_f32_16x16x32_bf16 v[84:87], v[148:151], v[208:211], v[84:87]
	v_mfma_f32_16x16x32_bf16 v[80:83], v[176:179], v[208:211], v[80:83]
	v_mfma_f32_16x16x32_bf16 v[68:71], v[148:151], v[216:219], v[68:71]
	v_mfma_f32_16x16x32_bf16 v[64:67], v[176:179], v[216:219], v[64:67]
	s_setprio 0
	s_barrier
	s_add_i32 s48, s75, s58
	v_lshl_add_u64 v[220:221], v[220:221], 0, s[22:23]
	s_mov_b32 m0, s48
	ds_read_b128 v[180:183], v190 offset:49152
	v_xor_b32_e32 v253, 64, v190
	ds_read_b128 v[192:195], v253 offset:49152
	ds_read_b128 v[196:199], v190 offset:51200
	ds_read_b128 v[200:203], v253 offset:51200
	ds_read_b128 v[204:207], v190 offset:53248
	ds_read_b128 v[208:211], v253 offset:53248
	ds_read_b128 v[212:215], v190 offset:55296
	ds_read_b128 v[216:219], v253 offset:55296
	global_load_lds_dwordx4 v[220:221], off
	s_add_i32 m0, s48, 0x2000
	s_add_u32 s48, s52, 0xb0080
	v_lshl_add_u64 v[220:221], v[222:223], 0, s[22:23]
	s_addc_u32 s49, s53, 0
	s_add_i32 s52, s76, s58
	global_load_lds_dwordx4 v[220:221], off
	v_lshl_add_u64 v[220:221], s[48:49], 0, v[154:155]
	s_mov_b32 m0, s52
	s_nop 0
	global_load_lds_dwordx4 v[220:221], off
	v_lshl_add_u64 v[220:221], s[48:49], 0, v[162:163]
	s_add_i32 m0, s52, 0x2000
	s_nop 0
	global_load_lds_dwordx4 v[220:221], off
	v_lshl_add_u64 v[220:221], v[224:225], 0, s[22:23]
	s_mov_b32 m0, s3
	s_nop 0
	global_load_lds_dwordx4 v[220:221], off
	v_lshl_add_u64 v[220:221], v[226:227], 0, s[22:23]
	s_mov_b32 m0, s64
	s_nop 0
	global_load_lds_dwordx4 v[220:221], off
	s_waitcnt vmcnt(8)
	s_waitcnt lgkmcnt(0)
	s_barrier
	s_setprio 1
	s_waitcnt lgkmcnt(0)
	v_mfma_f32_16x16x32_bf16 v[60:63], v[128:131], v[180:183], v[60:63]
	v_mfma_f32_16x16x32_bf16 v[56:59], v[136:139], v[180:183], v[56:59]
	v_mfma_f32_16x16x32_bf16 v[44:47], v[128:131], v[196:199], v[44:47]
	v_mfma_f32_16x16x32_bf16 v[40:43], v[136:139], v[196:199], v[40:43]
	v_mfma_f32_16x16x32_bf16 v[28:31], v[128:131], v[204:207], v[28:31]
	v_mfma_f32_16x16x32_bf16 v[24:27], v[136:139], v[204:207], v[24:27]
	v_mfma_f32_16x16x32_bf16 v[12:15], v[128:131], v[212:215], v[12:15]
	v_mfma_f32_16x16x32_bf16 v[8:11], v[136:139], v[212:215], v[8:11]
	v_mfma_f32_16x16x32_bf16 v[60:63], v[132:135], v[192:195], v[60:63]
	v_mfma_f32_16x16x32_bf16 v[56:59], v[140:143], v[192:195], v[56:59]
	v_mfma_f32_16x16x32_bf16 v[44:47], v[132:135], v[200:203], v[44:47]
	v_mfma_f32_16x16x32_bf16 v[40:43], v[140:143], v[200:203], v[40:43]
	v_mfma_f32_16x16x32_bf16 v[28:31], v[132:135], v[208:211], v[28:31]
	v_mfma_f32_16x16x32_bf16 v[24:27], v[140:143], v[208:211], v[24:27]
	v_mfma_f32_16x16x32_bf16 v[12:15], v[132:135], v[216:219], v[12:15]
	v_mfma_f32_16x16x32_bf16 v[8:11], v[140:143], v[216:219], v[8:11]
	s_setprio 0
	s_setprio 1
	v_mfma_f32_16x16x32_bf16 v[52:55], v[144:147], v[180:183], v[52:55]
	v_mfma_f32_16x16x32_bf16 v[48:51], v[172:175], v[180:183], v[48:51]
	v_mfma_f32_16x16x32_bf16 v[36:39], v[144:147], v[196:199], v[36:39]
	v_mfma_f32_16x16x32_bf16 v[32:35], v[172:175], v[196:199], v[32:35]
	v_mfma_f32_16x16x32_bf16 v[20:23], v[144:147], v[204:207], v[20:23]
	v_mfma_f32_16x16x32_bf16 v[16:19], v[172:175], v[204:207], v[16:19]
	v_mfma_f32_16x16x32_bf16 v[4:7], v[144:147], v[212:215], v[4:7]
	v_mfma_f32_16x16x32_bf16 v[0:3], v[172:175], v[212:215], v[0:3]
	v_mfma_f32_16x16x32_bf16 v[52:55], v[148:151], v[192:195], v[52:55]
	v_mfma_f32_16x16x32_bf16 v[48:51], v[176:179], v[192:195], v[48:51]
	v_mfma_f32_16x16x32_bf16 v[36:39], v[148:151], v[200:203], v[36:39]
	v_mfma_f32_16x16x32_bf16 v[32:35], v[176:179], v[200:203], v[32:35]
	v_mfma_f32_16x16x32_bf16 v[20:23], v[148:151], v[208:211], v[20:23]
	v_mfma_f32_16x16x32_bf16 v[16:19], v[176:179], v[208:211], v[16:19]
	v_mfma_f32_16x16x32_bf16 v[4:7], v[148:151], v[216:219], v[4:7]
	v_mfma_f32_16x16x32_bf16 v[0:3], v[176:179], v[216:219], v[0:3]
	s_setprio 0
	s_barrier
	s_add_i32 s74, s74, 2
	s_add_u32 s72, s72, 0x100
	s_addc_u32 s73, s73, 0
	s_cmp_gt_u32 s74, 41
	s_mov_b64 s[48:49], s[50:51]
	s_cbranch_scc0 .LBB0_1181
	s_and_b64 vcc, exec, s[24:25]
	s_cbranch_vccz .LBB0_1184
	s_barrier
